# speedup vs baseline: 1.0303x; 1.0069x over previous
; __device__ __forceinline__ unsigned pack2(float a, float b) { return (unsigned)f2bf(a) | ((unsigned)f2bf(b) << 16); }
; #define WAIT_V(n) asm volatile("s_waitcnt vmcnt(" #n ")" ::: "memory")
; template <int EPI, bool HS = false>
; __device__ __forceinline__ void gemm_phase(const Params& p, const GemmCfg& g, char* shm, const int wave_s) {
;     ...
;       const float* xin_t = g.xin + (size_t)orow0 * 1024 + pn * 256;
;       float* xout_t = g.xout + (size_t)orow0 * 1024 + pn * 256;
;       u16* xg_t = p.h + (size_t)orow0 * 1024 + pn * 256;
;       float* rss_t = p.rowss + (size_t)orow0 * 16 + pn * 4 + wc;
;       const unsigned tb = (unsigned)((wr * 64 + fq * 4) * 1024 + wc * 32 + 2 * fr);
;       const unsigned ldsb = (unsigned)(size_t)(__attribute__((address_space(3))) char*)shm;
;       const int wv_s = __builtin_amdgcn_readfirstlane(wid);
;       constexpr int XROW = 1040;
;       const char* xl = shm + (wr * 64 + fq * 4) * XROW + (wc * 32 + 2 * fr) * 4;
; #pragma unroll
;       for (int ai = 0; ai < 2; ++ai) {
; #pragma unroll
;         for (int i = 0; i < 16; ++i) {
;           const int r = wv_s * 16 + i;
;           glds_row(xin_t + (size_t)(ai * 128 + r) * 1024, (unsigned)lane * 16u, ldsb + (unsigned)(r * XROW));
;         }
;         WAIT_V(0);
;         __syncthreads();
; #pragma unroll
;         for (int m = 0; m < 4; ++m) {
;           float2 xv[4][2];
; #pragma unroll
;           for (int j = 0; j < 4; ++j)
; #pragma unroll
;             for (int bj = 0; bj < 2; ++bj) xv[j][bj] = *(const float2*)(xl + (m * 16 + j) * XROW + bj * 512);
; #pragma unroll
;           for (int j = 0; j < 4; ++j) {
;             float ss = 0.f;
; #pragma unroll
;             for (int bj = 0; bj < 2; ++bj) {
;               float2 xn;
;               xn.x = xv[j][bj].x + gt[bj][0] * acc[ai][bj][m][0][j];
;               xn.y = xv[j][bj].y + gt[bj][1] * acc[ai][bj][m][1][j];
;               const unsigned o = tb + (unsigned)((ai * 128 + m * 16 + j) * 1024 + bj * 128);
;               *(float2*)(xout_t + o) = xn;
;               if (g.has_next) *(unsigned*)(xg_t + o) = pack2(xn.x * gn[bj][0], xn.y * gn[bj][1]);
;               ss += xn.x * xn.x + xn.y * xn.y;
.LBB0_102:
	s_mov_b32 s85, s43
	s_mov_b32 s77, s41
	s_or_b64 exec, exec, s[2:3]
	s_mov_b32 s2, s82
	s_mov_b32 s3, -1
	v_readlane_b32 s9, v254, 56
	v_mbcnt_lo_u32_b32 v0, s3, 0
	v_mbcnt_hi_u32_b32 v0, s3, v0
	v_lshl_add_u32 v0, s2, 6, v0
	s_lshl_b64 s[2:3], s[4:5], 12
	s_add_u32 s14, s9, s2
	v_readlane_b32 s9, v254, 55
	s_addc_u32 s15, s9, s3
	s_ashr_i32 s9, s8, 31
	s_lshl_b64 s[12:13], s[8:9], 2
	s_add_u32 s71, s14, s12
	v_readlane_b32 s52, v253, 25
	s_addc_u32 s75, s15, s13
	v_readlane_b32 s64, v253, 37
	v_readlane_b32 s65, v253, 38
	s_add_u32 s2, s64, s2
	s_addc_u32 s3, s65, s3
	s_add_u32 s2, s2, s12
	s_addc_u32 s3, s3, s13
	s_add_u32 s10, s88, s10
	s_addc_u32 s11, s89, s11
	v_lshrrev_b32_e32 v132, 2, v0
	s_lshl_b64 s[8:9], s[8:9], 1
	v_ashrrev_i32_e32 v130, 6, v0
	v_ashrrev_i32_e32 v131, 2, v0
	v_and_b32_e32 v132, 12, v132
	s_add_u32 s8, s10, s8
	s_movk_i32 s10, 0xffc0
	v_and_or_b32 v160, v131, s10, v132
	v_readfirstlane_b32 s10, v130
	s_addc_u32 s9, s11, s9
	s_movk_i32 s11, 0x410
	s_lshl_b32 s10, s10, 4
	v_and_b32_e32 v166, 3, v130
	v_mul_lo_u32 v130, v160, s11
	s_ashr_i32 s11, s10, 31
	s_lshl_b64 s[12:13], s[10:11], 12
	v_and_b32_e32 v165, 15, v0
	v_lshlrev_b32_e32 v0, 4, v0
	s_add_u32 s12, s71, s12
	s_mul_i32 s70, s10, 0x410
	v_and_b32_e32 v164, 0x3f0, v0
	s_addc_u32 s13, s75, s13
	s_add_i32 s70, s70, 0
	s_mov_b32 m0, s70
	s_nop 0
	global_load_lds_dwordx4 v164, s[12:13]
	s_or_b32 s12, s10, 1
	s_ashr_i32 s13, s12, 31
	s_lshl_b64 s[14:15], s[12:13], 12
	s_add_u32 s14, s71, s14
	s_mul_i32 s76, s12, 0x410
	s_addc_u32 s15, s75, s15
	s_add_i32 s76, s76, 0
	s_mov_b32 m0, s76
	s_nop 0
	global_load_lds_dwordx4 v164, s[14:15]
	s_or_b32 s12, s10, 2
	s_ashr_i32 s13, s12, 31
	s_lshl_b64 s[14:15], s[12:13], 12
	s_add_u32 s14, s71, s14
	s_mulk_i32 s12, 0x410
	s_addc_u32 s15, s75, s15
	s_add_i32 s12, s12, 0
	s_mov_b32 m0, s12
	s_nop 0
	global_load_lds_dwordx4 v164, s[14:15]
	s_or_b32 s14, s10, 3
	s_ashr_i32 s15, s14, 31
	s_lshl_b64 s[16:17], s[14:15], 12
	s_add_u32 s16, s71, s16
	s_mul_i32 s13, s14, 0x410
	s_addc_u32 s17, s75, s17
	s_add_i32 s13, s13, 0
	s_mov_b32 m0, s13
	s_nop 0
	global_load_lds_dwordx4 v164, s[16:17]
	s_or_b32 s14, s10, 4
	s_ashr_i32 s15, s14, 31
	s_lshl_b64 s[16:17], s[14:15], 12
	s_add_u32 s16, s71, s16
	s_mulk_i32 s14, 0x410
	s_addc_u32 s17, s75, s17
	s_add_i32 s14, s14, 0
	s_mov_b32 m0, s14
	s_nop 0
	global_load_lds_dwordx4 v164, s[16:17]
	s_or_b32 s16, s10, 5
	s_ashr_i32 s17, s16, 31
	s_lshl_b64 s[18:19], s[16:17], 12
	s_add_u32 s18, s71, s18
	s_mul_i32 s15, s16, 0x410
	s_addc_u32 s19, s75, s19
	s_add_i32 s15, s15, 0
	s_mov_b32 m0, s15
	s_nop 0
	global_load_lds_dwordx4 v164, s[18:19]
	s_or_b32 s16, s10, 6
	s_ashr_i32 s17, s16, 31
	s_lshl_b64 s[18:19], s[16:17], 12
	s_add_u32 s18, s71, s18
	s_mulk_i32 s16, 0x410
	s_addc_u32 s19, s75, s19
	s_add_i32 s16, s16, 0
	s_mov_b32 m0, s16
	s_nop 0
	global_load_lds_dwordx4 v164, s[18:19]
	s_or_b32 s18, s10, 7
	s_ashr_i32 s19, s18, 31
	s_lshl_b64 s[20:21], s[18:19], 12
	s_add_u32 s20, s71, s20
	s_mul_i32 s17, s18, 0x410
	s_addc_u32 s21, s75, s21
	s_add_i32 s17, s17, 0
	s_mov_b32 m0, s17
	s_nop 0
	global_load_lds_dwordx4 v164, s[20:21]
	s_or_b32 s18, s10, 8
	s_ashr_i32 s19, s18, 31
	s_lshl_b64 s[20:21], s[18:19], 12
	s_add_u32 s20, s71, s20
	s_mulk_i32 s18, 0x410
	s_addc_u32 s21, s75, s21
	s_add_i32 s18, s18, 0
	s_mov_b32 m0, s18
	s_nop 0
	global_load_lds_dwordx4 v164, s[20:21]
	s_or_b32 s20, s10, 9
	s_ashr_i32 s21, s20, 31
	s_lshl_b64 s[22:23], s[20:21], 12
	s_add_u32 s22, s71, s22
	s_mul_i32 s19, s20, 0x410
	s_addc_u32 s23, s75, s23
	s_add_i32 s19, s19, 0
	s_mov_b32 m0, s19
	s_nop 0
	global_load_lds_dwordx4 v164, s[22:23]
	s_or_b32 s20, s10, 10
	s_ashr_i32 s21, s20, 31
	s_lshl_b64 s[22:23], s[20:21], 12
	s_add_u32 s22, s71, s22
	s_mulk_i32 s20, 0x410
	s_addc_u32 s23, s75, s23
	s_add_i32 s20, s20, 0
	s_mov_b32 m0, s20
	s_nop 0
	global_load_lds_dwordx4 v164, s[22:23]
	s_or_b32 s22, s10, 11
	s_ashr_i32 s23, s22, 31
	s_lshl_b64 s[24:25], s[22:23], 12
	s_add_u32 s24, s71, s24
	s_mul_i32 s21, s22, 0x410
	s_addc_u32 s25, s75, s25
	s_add_i32 s21, s21, 0
	s_mov_b32 m0, s21
	s_nop 0
	global_load_lds_dwordx4 v164, s[24:25]
	s_or_b32 s22, s10, 12
	s_ashr_i32 s23, s22, 31
	s_lshl_b64 s[24:25], s[22:23], 12
	s_add_u32 s24, s71, s24
	s_mulk_i32 s22, 0x410
	s_addc_u32 s25, s75, s25
	s_add_i32 s22, s22, 0
	s_mov_b32 m0, s22
	s_nop 0
	global_load_lds_dwordx4 v164, s[24:25]
	s_or_b32 s24, s10, 13
	s_ashr_i32 s25, s24, 31
	s_lshl_b64 s[26:27], s[24:25], 12
	s_add_u32 s26, s71, s26
	s_mul_i32 s23, s24, 0x410
	s_addc_u32 s27, s75, s27
	s_add_i32 s23, s23, 0
	s_mov_b32 m0, s23
	s_nop 0
	global_load_lds_dwordx4 v164, s[26:27]
	s_or_b32 s24, s10, 14
	s_ashr_i32 s25, s24, 31
	s_lshl_b64 s[26:27], s[24:25], 12
	s_add_u32 s26, s71, s26
	s_mulk_i32 s24, 0x410
	v_lshlrev_b32_e32 v132, 5, v166
	v_lshlrev_b32_e32 v133, 1, v165
	s_addc_u32 s27, s75, s27
	s_add_i32 s24, s24, 0
	s_mov_b32 m0, s24
	s_nop 0
	global_load_lds_dwordx4 v164, s[26:27]
	s_or_b32 s26, s10, 15
	v_or_b32_e32 v134, v132, v133
	s_ashr_i32 s27, s26, 31
	v_add_u32_e32 v130, 0, v130
	v_lshlrev_b32_e32 v134, 2, v134
	s_lshl_b64 s[36:37], s[26:27], 12
	v_add_u32_e32 v161, v130, v134
	s_add_u32 s36, s71, s36
	s_mul_i32 s25, s26, 0x410
	v_lshlrev_b32_e32 v131, 10, v160
	s_addc_u32 s37, s75, s37
	s_add_i32 s25, s25, 0
	s_mov_b32 m0, s25
	s_nop 0
	global_load_lds_dwordx4 v164, s[36:37]
	v_add_u32_e32 v162, 32, v161
	v_add_u32_e32 v163, 48, v161
	v_or3_b32 v0, v131, v133, v132
	s_waitcnt vmcnt(0)
	s_barrier
	ds_read2st64_b64 v[142:145], v161 offset1:1
	ds_read2_b64 v[138:141], v161 offset0:130 offset1:194
	ds_read2st64_b64 v[134:137], v162 offset0:4 offset1:5
	ds_read2st64_b64 v[130:133], v163 offset0:6 offset1:7
	v_readlane_b32 s26, v254, 60
	v_mov_b32_e32 v154, v122
	v_mov_b32_e32 v155, v126
	v_readlane_b32 s27, v254, 61
	s_waitcnt lgkmcnt(3)
	v_pk_fma_f32 v[156:157], v[150:151], v[154:155], v[142:143]
	v_lshl_add_u64 v[158:159], v[0:1], 2, s[2:3]
	s_and_b64 vcc, exec, s[26:27]
	v_lshl_add_u64 v[154:155], v[0:1], 1, s[8:9]
	v_readlane_b32 s53, v253, 26
	v_readlane_b32 s54, v253, 27
	v_readlane_b32 s55, v253, 28
	v_readlane_b32 s56, v253, 29
	v_readlane_b32 s57, v253, 30
	v_readlane_b32 s58, v253, 31
	v_readlane_b32 s59, v253, 32
	v_readlane_b32 s60, v253, 33
	v_readlane_b32 s61, v253, 34
	v_readlane_b32 s62, v253, 35
	v_readlane_b32 s63, v253, 36
	v_readlane_b32 s66, v253, 39
	v_readlane_b32 s67, v253, 40
	global_store_dwordx2 v[158:159], v[156:157], off
	s_cbranch_vccz .LBB0_104
	v_pk_mul_f32 v[142:143], v[148:149], v[156:157]
	s_nop 0
	s_nop 0
	v_and_b32_sdwa v122, v143, v178 dst_sel:DWORD dst_unused:UNUSED_PAD src0_sel:WORD_1 src1_sel:DWORD
	v_cvt_pk_bf16_f32 v126, v142, v142
	v_add3_u32 v122, v143, v122, s81
	v_lshrrev_b32_e32 v126, 16, v126
	v_and_or_b32 v122, v122, s28, v126
	global_store_dword v[154:155], v122, off
; __device__ __forceinline__ unsigned pack2(float a, float b) { return (unsigned)f2bf(a) | ((unsigned)f2bf(b) << 16); }
; template <int EPI, bool HS = false>
; __device__ __forceinline__ void gemm_phase(const Params& p, const GemmCfg& g, char* shm, const int wave_s) {
;     ...
;           for (int j = 0; j < 4; ++j) {
;             float ss = 0.f;
; #pragma unroll
;             for (int bj = 0; bj < 2; ++bj) {
;               float2 xn;
;               xn.x = xv[j][bj].x + gt[bj][0] * acc[ai][bj][m][0][j];
;               xn.y = xv[j][bj].y + gt[bj][1] * acc[ai][bj][m][1][j];
;               const unsigned o = tb + (unsigned)((ai * 128 + m * 16 + j) * 1024 + bj * 128);
;               *(float2*)(xout_t + o) = xn;
;               if (g.has_next) *(unsigned*)(xg_t + o) = pack2(xn.x * gn[bj][0], xn.y * gn[bj][1]);
;               ss += xn.x * xn.x + xn.y * xn.y;
;             }
;             if (g.has_next) {
;               ss = dpp_row_sum16(ss);
;               if (fr == 0) rss_t[(wr * 64 + fq * 4 + ai * 128 + m * 16 + j) * 16] = ss;
;             }
.LBB0_104:
	v_readlane_b32 s36, v252, 0
	s_lshl_b64 s[4:5], s[4:5], 6
	v_readlane_b32 s42, v252, 6
	v_readlane_b32 s43, v252, 7
	s_add_u32 s26, s42, s4
	s_addc_u32 s27, s43, s5
	s_lshl_b32 s4, s68, 2
	s_ashr_i32 s5, s4, 31
	s_lshl_b64 s[4:5], s[4:5], 2
	s_add_u32 s4, s26, s4
	s_addc_u32 s5, s27, s5
	v_lshlrev_b32_e32 v142, 2, v166
	v_mov_b32_e32 v143, v1
	v_mov_b32_e32 v166, v114
	v_mov_b32_e32 v167, v118
	v_lshl_add_u64 v[142:143], s[4:5], 0, v[142:143]
	v_cmp_eq_u32_e64 s[4:5], 0, v165
	v_pk_fma_f32 v[144:145], v[146:147], v[166:167], v[144:145]
	s_and_b64 vcc, exec, s[6:7]
	s_mov_b64 s[68:69], -1
	v_readlane_b32 s37, v252, 1
	v_readlane_b32 s38, v252, 2
	v_readlane_b32 s39, v252, 3
	v_readlane_b32 s40, v252, 4
	v_readlane_b32 s41, v252, 5
	global_store_dwordx2 v[158:159], v[144:145], off offset:512
	s_cbranch_vccnz .LBB0_110
	v_pk_mul_f32 v[158:159], v[152:153], v[144:145]
	v_pk_mul_f32 v[156:157], v[156:157], v[156:157]
	s_nop 0
	v_and_b32_sdwa v114, v159, v178 dst_sel:DWORD dst_unused:UNUSED_PAD src0_sel:WORD_1 src1_sel:DWORD
	v_cvt_pk_bf16_f32 v118, v158, v158
	v_add3_u32 v114, v159, v114, s81
	v_lshrrev_b32_e32 v118, 16, v118
	v_and_or_b32 v114, v114, s28, v118
	v_pk_mul_f32 v[144:145], v[144:145], v[144:145]
	global_store_dword v[154:155], v114, off offset:256
	v_add_f32_e32 v114, v144, v145
	v_add_f32_e32 v118, v156, v157
	v_add_f32_e32 v114, v118, v114
	s_nop 1
	v_add_f32_dpp v114, v114, v114 quad_perm:[1,0,3,2] row_mask:0xf bank_mask:0xf bound_ctrl:1
	s_nop 1
	v_add_f32_dpp v114, v114, v114 quad_perm:[2,3,0,1] row_mask:0xf bank_mask:0xf bound_ctrl:1
	s_nop 1
	v_add_f32_dpp v114, v114, v114 row_half_mirror row_mask:0xf bank_mask:0xf bound_ctrl:1
	s_nop 1
	v_mov_b32_dpp v118, v114 row_mirror row_mask:0xf bank_mask:0xf bound_ctrl:1
	s_and_saveexec_b64 s[68:69], s[4:5]
	s_cbranch_execz .LBB0_107
	v_lshlrev_b32_e32 v144, 4, v160
	v_ashrrev_i32_e32 v145, 31, v144
	v_add_f32_e32 v114, v114, v118
	v_lshl_add_u64 v[144:145], v[144:145], 2, v[142:143]
	global_store_dword v[144:145], v114, off
.LBB0_107:
	s_or_b64 exec, exec, s[68:69]
	v_or_b32_e32 v144, 0x400, v0
	v_mov_b32_e32 v126, v123
	v_mov_b32_e32 v145, v1
	s_waitcnt lgkmcnt(2)
	v_pk_fma_f32 v[156:157], v[150:151], v[126:127], v[138:139]
	v_lshl_add_u64 v[144:145], v[144:145], 2, s[2:3]
	global_store_dwordx2 v[144:145], v[156:157], off
	v_pk_mul_f32 v[144:145], v[148:149], v[156:157]
	v_or_b32_e32 v158, 0x480, v0
	s_nop 0
	v_and_b32_sdwa v114, v145, v178 dst_sel:DWORD dst_unused:UNUSED_PAD src0_sel:WORD_1 src1_sel:DWORD
	v_cvt_pk_bf16_f32 v118, v144, v144
	v_add3_u32 v114, v145, v114, s81
	v_lshrrev_b32_e32 v118, 16, v118
	v_and_or_b32 v114, v114, s28, v118
	v_mov_b32_e32 v118, v115
	v_mov_b32_e32 v159, v1
	v_pk_fma_f32 v[144:145], v[146:147], v[118:119], v[140:141]
	v_lshl_add_u64 v[158:159], v[158:159], 2, s[2:3]
	global_store_dword v[154:155], v114, off offset:2048
	global_store_dwordx2 v[158:159], v[144:145], off
	v_pk_mul_f32 v[158:159], v[152:153], v[144:145]
	v_pk_mul_f32 v[156:157], v[156:157], v[156:157]
	s_nop 0
	v_and_b32_sdwa v114, v159, v178 dst_sel:DWORD dst_unused:UNUSED_PAD src0_sel:WORD_1 src1_sel:DWORD
	v_cvt_pk_bf16_f32 v118, v158, v158
	v_add3_u32 v114, v159, v114, s81
	v_lshrrev_b32_e32 v118, 16, v118
	v_and_or_b32 v114, v114, s28, v118
	v_pk_mul_f32 v[144:145], v[144:145], v[144:145]
	global_store_dword v[154:155], v114, off offset:2304
	v_add_f32_e32 v114, v144, v145
	v_add_f32_e32 v118, v156, v157
	v_add_f32_e32 v114, v118, v114
	s_nop 1
	v_add_f32_dpp v114, v114, v114 quad_perm:[1,0,3,2] row_mask:0xf bank_mask:0xf bound_ctrl:1
	s_nop 1
	v_add_f32_dpp v114, v114, v114 quad_perm:[2,3,0,1] row_mask:0xf bank_mask:0xf bound_ctrl:1
	s_nop 1
	v_add_f32_dpp v114, v114, v114 row_half_mirror row_mask:0xf bank_mask:0xf bound_ctrl:1
	s_nop 1
	v_mov_b32_dpp v118, v114 row_mirror row_mask:0xf bank_mask:0xf bound_ctrl:1
	s_and_saveexec_b64 s[68:69], s[4:5]
	s_cbranch_execz .LBB0_109
	v_lshlrev_b32_e32 v144, 4, v160
	v_ashrrev_i32_e32 v145, 31, v144
	v_add_f32_e32 v114, v114, v118
	v_lshl_add_u64 v[144:145], v[144:145], 2, v[142:143]
	global_store_dword v[144:145], v114, off offset:64

; __device__ __forceinline__ unsigned pack2(float a, float b) { return (unsigned)f2bf(a) | ((unsigned)f2bf(b) << 16); }
; template <int EPI, bool HS = false>
; __device__ __forceinline__ void gemm_phase(const Params& p, const GemmCfg& g, char* shm, const int wave_s) {
;     ...
;           for (int j = 0; j < 4; ++j) {
;             float ss = 0.f;
; #pragma unroll
;             for (int bj = 0; bj < 2; ++bj) {
;               float2 xn;
;               xn.x = xv[j][bj].x + gt[bj][0] * acc[ai][bj][m][0][j];
;               xn.y = xv[j][bj].y + gt[bj][1] * acc[ai][bj][m][1][j];
;               const unsigned o = tb + (unsigned)((ai * 128 + m * 16 + j) * 1024 + bj * 128);
;               *(float2*)(xout_t + o) = xn;
;               if (g.has_next) *(unsigned*)(xg_t + o) = pack2(xn.x * gn[bj][0], xn.y * gn[bj][1]);
;               ss += xn.x * xn.x + xn.y * xn.y;
;             }
;             if (g.has_next) {
;               ss = dpp_row_sum16(ss);
;               if (fr == 0) rss_t[(wr * 64 + fq * 4 + ai * 128 + m * 16 + j) * 16] = ss;
;             }
.LBB0_112:
	v_or_b32_e32 v122, 0x800, v0
	v_mov_b32_e32 v114, v124
	v_mov_b32_e32 v115, v128
	v_mov_b32_e32 v123, v1
	s_waitcnt lgkmcnt(1)
	v_pk_fma_f32 v[118:119], v[150:151], v[114:115], v[134:135]
	v_lshl_add_u64 v[114:115], v[122:123], 2, s[2:3]
	global_store_dwordx2 v[114:115], v[118:119], off
	s_mov_b64 s[68:69], -1
	s_and_b64 vcc, exec, s[6:7]
	v_or_b32_e32 v114, 0x880, v0
	s_mov_b32 s42, 0x800000
	s_mov_b32 s41, s77
	s_mov_b32 s43, s85
	s_cbranch_vccnz .LBB0_116
	v_pk_mul_f32 v[126:127], v[148:149], v[118:119]
	v_lshl_add_u64 v[122:123], v[122:123], 1, s[8:9]
	s_nop 0
	v_and_b32_sdwa v115, v127, v178 dst_sel:DWORD dst_unused:UNUSED_PAD src0_sel:WORD_1 src1_sel:DWORD
	v_cvt_pk_bf16_f32 v124, v126, v126
	v_add3_u32 v115, v127, v115, s81
	v_lshrrev_b32_e32 v124, 16, v124
	v_and_or_b32 v115, v115, s28, v124
	global_store_dword v[122:123], v115, off
	v_mov_b32_e32 v122, v116
	v_mov_b32_e32 v123, v120
	v_mov_b32_e32 v115, v1
	v_pk_fma_f32 v[122:123], v[146:147], v[122:123], v[136:137]
	v_lshl_add_u64 v[126:127], v[114:115], 2, s[2:3]
	global_store_dwordx2 v[126:127], v[122:123], off
	v_pk_mul_f32 v[126:127], v[152:153], v[122:123]
	v_pk_mul_f32 v[118:119], v[118:119], v[118:119]
	v_and_b32_sdwa v128, v126, v178 dst_sel:DWORD dst_unused:UNUSED_PAD src0_sel:WORD_1 src1_sel:DWORD
	v_and_b32_sdwa v124, v127, v178 dst_sel:DWORD dst_unused:UNUSED_PAD src0_sel:WORD_1 src1_sel:DWORD
	v_add3_u32 v126, v126, v128, s81
	v_add3_u32 v124, v127, v124, s81
	v_lshrrev_b32_e32 v126, 16, v126
	v_pk_mul_f32 v[122:123], v[122:123], v[122:123]
	v_and_or_b32 v124, v124, s28, v126
	v_lshl_add_u64 v[126:127], v[114:115], 1, s[8:9]
	v_add_f32_e32 v115, v122, v123
	v_add_f32_e32 v118, v118, v119
	v_add_f32_e32 v115, v118, v115
	global_store_dword v[126:127], v124, off
	s_nop 0
	v_add_f32_dpp v115, v115, v115 quad_perm:[1,0,3,2] row_mask:0xf bank_mask:0xf bound_ctrl:1
	s_nop 1
	v_add_f32_dpp v115, v115, v115 quad_perm:[2,3,0,1] row_mask:0xf bank_mask:0xf bound_ctrl:1
	s_nop 1
	v_add_f32_dpp v115, v115, v115 row_half_mirror row_mask:0xf bank_mask:0xf bound_ctrl:1
	s_nop 1
	v_mov_b32_dpp v118, v115 row_mirror row_mask:0xf bank_mask:0xf bound_ctrl:1
	s_and_saveexec_b64 s[68:69], s[4:5]
	s_cbranch_execz .LBB0_115
	v_add_f32_e32 v115, v115, v118
	v_lshlrev_b32_e32 v118, 4, v160
	v_ashrrev_i32_e32 v119, 31, v118
	v_lshl_add_u64 v[118:119], v[118:119], 2, v[142:143]
	global_store_dword v[118:119], v115, off offset:128

; __device__ __forceinline__ unsigned pack2(float a, float b) { return (unsigned)f2bf(a) | ((unsigned)f2bf(b) << 16); }
; template <int EPI, bool HS = false>
; __device__ __forceinline__ void gemm_phase(const Params& p, const GemmCfg& g, char* shm, const int wave_s) {
;     ...
;           for (int j = 0; j < 4; ++j) {
;             float ss = 0.f;
; #pragma unroll
;             for (int bj = 0; bj < 2; ++bj) {
;               float2 xn;
;               xn.x = xv[j][bj].x + gt[bj][0] * acc[ai][bj][m][0][j];
;               xn.y = xv[j][bj].y + gt[bj][1] * acc[ai][bj][m][1][j];
;               const unsigned o = tb + (unsigned)((ai * 128 + m * 16 + j) * 1024 + bj * 128);
;               *(float2*)(xout_t + o) = xn;
;               if (g.has_next) *(unsigned*)(xg_t + o) = pack2(xn.x * gn[bj][0], xn.y * gn[bj][1]);
;               ss += xn.x * xn.x + xn.y * xn.y;
;             }
;             if (g.has_next) {
;               ss = dpp_row_sum16(ss);
;               if (fr == 0) rss_t[(wr * 64 + fq * 4 + ai * 128 + m * 16 + j) * 16] = ss;
;             }
.LBB0_118:
	v_or_b32_e32 v122, 0xc00, v0
	v_mov_b32_e32 v128, v125
	v_mov_b32_e32 v123, v1
	s_waitcnt lgkmcnt(0)
	v_pk_fma_f32 v[118:119], v[150:151], v[128:129], v[130:131]
	v_lshl_add_u64 v[114:115], v[122:123], 2, s[2:3]
	global_store_dwordx2 v[114:115], v[118:119], off
	s_mov_b64 s[68:69], -1
	s_and_b64 vcc, exec, s[6:7]
	v_or_b32_e32 v114, 0xc80, v0
	s_cbranch_vccnz .LBB0_122
	v_pk_mul_f32 v[124:125], v[148:149], v[118:119]
	v_lshl_add_u64 v[122:123], v[122:123], 1, s[8:9]
	s_nop 0
	v_and_b32_sdwa v115, v125, v178 dst_sel:DWORD dst_unused:UNUSED_PAD src0_sel:WORD_1 src1_sel:DWORD
	v_cvt_pk_bf16_f32 v116, v124, v124
	v_add3_u32 v115, v125, v115, s81
	v_lshrrev_b32_e32 v116, 16, v116
	v_and_or_b32 v115, v115, s28, v116
	global_store_dword v[122:123], v115, off
	v_mov_b32_e32 v120, v117
	v_mov_b32_e32 v115, v1
	v_pk_fma_f32 v[122:123], v[146:147], v[120:121], v[132:133]
	v_lshl_add_u64 v[124:125], v[114:115], 2, s[2:3]
	global_store_dwordx2 v[124:125], v[122:123], off
	v_pk_mul_f32 v[124:125], v[152:153], v[122:123]
	v_pk_mul_f32 v[118:119], v[118:119], v[118:119]
	s_nop 0
	v_and_b32_sdwa v116, v125, v178 dst_sel:DWORD dst_unused:UNUSED_PAD src0_sel:WORD_1 src1_sel:DWORD
	v_cvt_pk_bf16_f32 v120, v124, v124
	v_add3_u32 v116, v125, v116, s81
	v_lshrrev_b32_e32 v120, 16, v120
	v_and_or_b32 v116, v116, s28, v120
	v_lshl_add_u64 v[124:125], v[114:115], 1, s[8:9]
	v_pk_mul_f32 v[122:123], v[122:123], v[122:123]
	global_store_dword v[124:125], v116, off
	v_add_f32_e32 v115, v122, v123
	v_add_f32_e32 v116, v118, v119
	v_add_f32_e32 v115, v116, v115
	s_nop 1
	v_add_f32_dpp v115, v115, v115 quad_perm:[1,0,3,2] row_mask:0xf bank_mask:0xf bound_ctrl:1
	s_nop 1
	v_add_f32_dpp v115, v115, v115 quad_perm:[2,3,0,1] row_mask:0xf bank_mask:0xf bound_ctrl:1
	s_nop 1
	v_add_f32_dpp v115, v115, v115 row_half_mirror row_mask:0xf bank_mask:0xf bound_ctrl:1
	s_nop 1
	v_mov_b32_dpp v116, v115 row_mirror row_mask:0xf bank_mask:0xf bound_ctrl:1
	s_and_saveexec_b64 s[68:69], s[4:5]
	s_cbranch_execz .LBB0_121
	v_lshlrev_b32_e32 v118, 4, v160
	v_ashrrev_i32_e32 v119, 31, v118
	v_add_f32_e32 v115, v115, v116
	v_lshl_add_u64 v[118:119], v[118:119], 2, v[142:143]
	global_store_dword v[118:119], v115, off offset:192

; __device__ __forceinline__ unsigned pack2(float a, float b) { return (unsigned)f2bf(a) | ((unsigned)f2bf(b) << 16); }
; template <int EPI, bool HS = false>
; __device__ __forceinline__ void gemm_phase(const Params& p, const GemmCfg& g, char* shm, const int wave_s) {
;     ...
; #pragma unroll
;         for (int m = 0; m < 4; ++m) {
;           float2 xv[4][2];
; #pragma unroll
;           for (int j = 0; j < 4; ++j)
; #pragma unroll
;             for (int bj = 0; bj < 2; ++bj) xv[j][bj] = *(const float2*)(xl + (m * 16 + j) * XROW + bj * 512);
; #pragma unroll
;           for (int j = 0; j < 4; ++j) {
;             float ss = 0.f;
; #pragma unroll
;             for (int bj = 0; bj < 2; ++bj) {
;               float2 xn;
;               xn.x = xv[j][bj].x + gt[bj][0] * acc[ai][bj][m][0][j];
;               xn.y = xv[j][bj].y + gt[bj][1] * acc[ai][bj][m][1][j];
;               const unsigned o = tb + (unsigned)((ai * 128 + m * 16 + j) * 1024 + bj * 128);
;               *(float2*)(xout_t + o) = xn;
;               if (g.has_next) *(unsigned*)(xg_t + o) = pack2(xn.x * gn[bj][0], xn.y * gn[bj][1]);
;               ss += xn.x * xn.x + xn.y * xn.y;
;             }
;             if (g.has_next) {
;               ss = dpp_row_sum16(ss);
;               if (fr == 0) rss_t[(wr * 64 + fq * 4 + ai * 128 + m * 16 + j) * 16] = ss;
;             }
.LBB0_124:
	v_add_u32_e32 v134, 0x100, v161
	ds_read2st64_b64 v[126:129], v134 offset0:32 offset1:33
	v_add_u32_e32 v135, 0x110, v161
	v_add_u32_e32 v136, 0x120, v161
	v_add_u32_e32 v137, 0x130, v161
	ds_read2st64_b64 v[122:125], v135 offset0:34 offset1:35
	ds_read2st64_b64 v[118:121], v136 offset0:36 offset1:37
	ds_read2st64_b64 v[114:117], v137 offset0:38 offset1:39
	v_or_b32_e32 v132, 0x4000, v0
	v_mov_b32_e32 v130, v106
	v_mov_b32_e32 v131, v110
	v_mov_b32_e32 v133, v1
	s_waitcnt lgkmcnt(3)
	v_pk_fma_f32 v[130:131], v[150:151], v[130:131], v[126:127]
	v_lshl_add_u64 v[126:127], v[132:133], 2, s[2:3]
	global_store_dwordx2 v[126:127], v[130:131], off
	s_mov_b64 s[68:69], -1
	s_and_b64 vcc, exec, s[6:7]
	v_or_b32_e32 v126, 0x4080, v0
	s_cbranch_vccnz .LBB0_128
	v_pk_mul_f32 v[138:139], v[148:149], v[130:131]
	v_lshl_add_u64 v[132:133], v[132:133], 1, s[8:9]
	s_nop 0
	v_and_b32_sdwa v106, v139, v178 dst_sel:DWORD dst_unused:UNUSED_PAD src0_sel:WORD_1 src1_sel:DWORD
	v_cvt_pk_bf16_f32 v110, v138, v138
	v_add3_u32 v106, v139, v106, s81
	v_lshrrev_b32_e32 v110, 16, v110
	v_and_or_b32 v106, v106, s28, v110
	global_store_dword v[132:133], v106, off
	v_mov_b32_e32 v132, v98
	v_mov_b32_e32 v133, v102
	v_mov_b32_e32 v127, v1
	v_pk_fma_f32 v[132:133], v[146:147], v[132:133], v[128:129]
	v_lshl_add_u64 v[138:139], v[126:127], 2, s[2:3]
	global_store_dwordx2 v[138:139], v[132:133], off
	v_pk_mul_f32 v[138:139], v[152:153], v[132:133]
	v_pk_mul_f32 v[130:131], v[130:131], v[130:131]
	s_nop 0
	v_and_b32_sdwa v106, v139, v178 dst_sel:DWORD dst_unused:UNUSED_PAD src0_sel:WORD_1 src1_sel:DWORD
	v_cvt_pk_bf16_f32 v110, v138, v138
	v_add3_u32 v106, v139, v106, s81
	v_lshrrev_b32_e32 v110, 16, v110
	v_and_or_b32 v106, v106, s28, v110
	v_lshl_add_u64 v[138:139], v[126:127], 1, s[8:9]
	v_pk_mul_f32 v[132:133], v[132:133], v[132:133]
	global_store_dword v[138:139], v106, off
	v_add_f32_e32 v106, v132, v133
	v_add_f32_e32 v110, v130, v131
	v_add_f32_e32 v106, v110, v106
	s_nop 1
	v_add_f32_dpp v106, v106, v106 quad_perm:[1,0,3,2] row_mask:0xf bank_mask:0xf bound_ctrl:1
	s_nop 1
	v_add_f32_dpp v106, v106, v106 quad_perm:[2,3,0,1] row_mask:0xf bank_mask:0xf bound_ctrl:1
	s_nop 1
	v_add_f32_dpp v106, v106, v106 row_half_mirror row_mask:0xf bank_mask:0xf bound_ctrl:1
	s_nop 1
	v_mov_b32_dpp v110, v106 row_mirror row_mask:0xf bank_mask:0xf bound_ctrl:1
	s_and_saveexec_b64 s[68:69], s[4:5]
	s_cbranch_execz .LBB0_127
	v_lshlrev_b32_e32 v130, 4, v160
	v_ashrrev_i32_e32 v131, 31, v130
	v_add_f32_e32 v106, v106, v110
	v_lshl_add_u64 v[130:131], v[130:131], 2, v[142:143]
	global_store_dword v[130:131], v106, off offset:1024

; __device__ __forceinline__ unsigned pack2(float a, float b) { return (unsigned)f2bf(a) | ((unsigned)f2bf(b) << 16); }
; template <int EPI, bool HS = false>
; __device__ __forceinline__ void gemm_phase(const Params& p, const GemmCfg& g, char* shm, const int wave_s) {
;     ...
;           for (int j = 0; j < 4; ++j) {
;             float ss = 0.f;
; #pragma unroll
;             for (int bj = 0; bj < 2; ++bj) {
;               float2 xn;
;               xn.x = xv[j][bj].x + gt[bj][0] * acc[ai][bj][m][0][j];
;               xn.y = xv[j][bj].y + gt[bj][1] * acc[ai][bj][m][1][j];
;               const unsigned o = tb + (unsigned)((ai * 128 + m * 16 + j) * 1024 + bj * 128);
;               *(float2*)(xout_t + o) = xn;
;               if (g.has_next) *(unsigned*)(xg_t + o) = pack2(xn.x * gn[bj][0], xn.y * gn[bj][1]);
;               ss += xn.x * xn.x + xn.y * xn.y;
;             }
;             if (g.has_next) {
;               ss = dpp_row_sum16(ss);
;               if (fr == 0) rss_t[(wr * 64 + fq * 4 + ai * 128 + m * 16 + j) * 16] = ss;
;             }
.LBB0_130:
	v_or_b32_e32 v126, 0x4400, v0
	v_mov_b32_e32 v110, v107
	v_mov_b32_e32 v127, v1
	s_waitcnt lgkmcnt(2)
	v_pk_fma_f32 v[110:111], v[150:151], v[110:111], v[122:123]
	v_lshl_add_u64 v[106:107], v[126:127], 2, s[2:3]
	global_store_dwordx2 v[106:107], v[110:111], off
	s_mov_b64 s[68:69], -1
	s_and_b64 vcc, exec, s[6:7]
	v_or_b32_e32 v106, 0x4480, v0
	s_cbranch_vccnz .LBB0_134
	v_pk_mul_f32 v[122:123], v[148:149], v[110:111]
	v_mov_b32_e32 v107, v1
	s_nop 0
	v_and_b32_sdwa v98, v123, v178 dst_sel:DWORD dst_unused:UNUSED_PAD src0_sel:WORD_1 src1_sel:DWORD
	v_cvt_pk_bf16_f32 v102, v122, v122
	v_add3_u32 v98, v123, v98, s81
	v_lshrrev_b32_e32 v102, 16, v102
	v_and_or_b32 v98, v98, s28, v102
	v_lshl_add_u64 v[122:123], v[126:127], 1, s[8:9]
	v_mov_b32_e32 v102, v99
	global_store_dword v[122:123], v98, off
	v_pk_fma_f32 v[122:123], v[146:147], v[102:103], v[124:125]
	v_lshl_add_u64 v[126:127], v[106:107], 2, s[2:3]
	global_store_dwordx2 v[126:127], v[122:123], off
	v_pk_mul_f32 v[126:127], v[152:153], v[122:123]
	v_pk_mul_f32 v[110:111], v[110:111], v[110:111]
	s_nop 0
	v_and_b32_sdwa v98, v127, v178 dst_sel:DWORD dst_unused:UNUSED_PAD src0_sel:WORD_1 src1_sel:DWORD
	v_cvt_pk_bf16_f32 v102, v126, v126
	v_add3_u32 v98, v127, v98, s81
	v_lshrrev_b32_e32 v102, 16, v102
	v_and_or_b32 v98, v98, s28, v102
	v_lshl_add_u64 v[126:127], v[106:107], 1, s[8:9]
	v_pk_mul_f32 v[122:123], v[122:123], v[122:123]
	global_store_dword v[126:127], v98, off
	v_add_f32_e32 v98, v122, v123
	v_add_f32_e32 v102, v110, v111
	v_add_f32_e32 v98, v102, v98
	s_nop 1
	v_add_f32_dpp v98, v98, v98 quad_perm:[1,0,3,2] row_mask:0xf bank_mask:0xf bound_ctrl:1
	s_nop 1
	v_add_f32_dpp v98, v98, v98 quad_perm:[2,3,0,1] row_mask:0xf bank_mask:0xf bound_ctrl:1
	s_nop 1
	v_add_f32_dpp v98, v98, v98 row_half_mirror row_mask:0xf bank_mask:0xf bound_ctrl:1
	s_nop 1
	v_mov_b32_dpp v102, v98 row_mirror row_mask:0xf bank_mask:0xf bound_ctrl:1
	s_and_saveexec_b64 s[68:69], s[4:5]
	s_cbranch_execz .LBB0_133
	v_lshlrev_b32_e32 v110, 4, v160
	v_ashrrev_i32_e32 v111, 31, v110
	v_add_f32_e32 v98, v98, v102
	v_lshl_add_u64 v[110:111], v[110:111], 2, v[142:143]
	global_store_dword v[110:111], v98, off offset:1088

; __device__ __forceinline__ unsigned pack2(float a, float b) { return (unsigned)f2bf(a) | ((unsigned)f2bf(b) << 16); }
; template <int EPI, bool HS = false>
; __device__ __forceinline__ void gemm_phase(const Params& p, const GemmCfg& g, char* shm, const int wave_s) {
;     ...
;           for (int j = 0; j < 4; ++j) {
;             float ss = 0.f;
; #pragma unroll
;             for (int bj = 0; bj < 2; ++bj) {
;               float2 xn;
;               xn.x = xv[j][bj].x + gt[bj][0] * acc[ai][bj][m][0][j];
;               xn.y = xv[j][bj].y + gt[bj][1] * acc[ai][bj][m][1][j];
;               const unsigned o = tb + (unsigned)((ai * 128 + m * 16 + j) * 1024 + bj * 128);
;               *(float2*)(xout_t + o) = xn;
;               if (g.has_next) *(unsigned*)(xg_t + o) = pack2(xn.x * gn[bj][0], xn.y * gn[bj][1]);
;               ss += xn.x * xn.x + xn.y * xn.y;
;             }
;             if (g.has_next) {
;               ss = dpp_row_sum16(ss);
;               if (fr == 0) rss_t[(wr * 64 + fq * 4 + ai * 128 + m * 16 + j) * 16] = ss;
;             }
.LBB0_136:
	v_or_b32_e32 v106, 0x4800, v0
	v_mov_b32_e32 v98, v108
	v_mov_b32_e32 v99, v112
	v_mov_b32_e32 v107, v1
	s_waitcnt lgkmcnt(1)
	v_pk_fma_f32 v[102:103], v[150:151], v[98:99], v[118:119]
	v_lshl_add_u64 v[98:99], v[106:107], 2, s[2:3]
	global_store_dwordx2 v[98:99], v[102:103], off
	s_mov_b64 s[68:69], -1
	s_and_b64 vcc, exec, s[6:7]
	v_or_b32_e32 v98, 0x4880, v0
	s_cbranch_vccnz .LBB0_140
	v_pk_mul_f32 v[110:111], v[148:149], v[102:103]
	v_lshl_add_u64 v[106:107], v[106:107], 1, s[8:9]
	s_nop 0
	v_and_b32_sdwa v99, v111, v178 dst_sel:DWORD dst_unused:UNUSED_PAD src0_sel:WORD_1 src1_sel:DWORD
	v_cvt_pk_bf16_f32 v108, v110, v110
	v_add3_u32 v99, v111, v99, s81
	v_lshrrev_b32_e32 v108, 16, v108
	v_and_or_b32 v99, v99, s28, v108
	global_store_dword v[106:107], v99, off
	v_mov_b32_e32 v106, v100
	v_mov_b32_e32 v107, v104
	v_mov_b32_e32 v99, v1
	v_pk_fma_f32 v[106:107], v[146:147], v[106:107], v[120:121]
	v_lshl_add_u64 v[110:111], v[98:99], 2, s[2:3]
	global_store_dwordx2 v[110:111], v[106:107], off
	v_pk_mul_f32 v[110:111], v[152:153], v[106:107]
	v_pk_mul_f32 v[102:103], v[102:103], v[102:103]
	v_and_b32_sdwa v112, v110, v178 dst_sel:DWORD dst_unused:UNUSED_PAD src0_sel:WORD_1 src1_sel:DWORD
	v_and_b32_sdwa v108, v111, v178 dst_sel:DWORD dst_unused:UNUSED_PAD src0_sel:WORD_1 src1_sel:DWORD
	v_add3_u32 v110, v110, v112, s81
	v_add3_u32 v108, v111, v108, s81
	v_lshrrev_b32_e32 v110, 16, v110
	v_pk_mul_f32 v[106:107], v[106:107], v[106:107]
	v_and_or_b32 v108, v108, s28, v110
	v_lshl_add_u64 v[110:111], v[98:99], 1, s[8:9]
	v_add_f32_e32 v99, v106, v107
	v_add_f32_e32 v102, v102, v103
	v_add_f32_e32 v99, v102, v99
	global_store_dword v[110:111], v108, off
	s_nop 0
	v_add_f32_dpp v99, v99, v99 quad_perm:[1,0,3,2] row_mask:0xf bank_mask:0xf bound_ctrl:1
	s_nop 1
	v_add_f32_dpp v99, v99, v99 quad_perm:[2,3,0,1] row_mask:0xf bank_mask:0xf bound_ctrl:1
	s_nop 1
	v_add_f32_dpp v99, v99, v99 row_half_mirror row_mask:0xf bank_mask:0xf bound_ctrl:1
	s_nop 1
	v_mov_b32_dpp v102, v99 row_mirror row_mask:0xf bank_mask:0xf bound_ctrl:1
	s_and_saveexec_b64 s[68:69], s[4:5]
	s_cbranch_execz .LBB0_139
	v_add_f32_e32 v99, v99, v102
	v_lshlrev_b32_e32 v102, 4, v160
	v_ashrrev_i32_e32 v103, 31, v102
	v_lshl_add_u64 v[102:103], v[102:103], 2, v[142:143]
	global_store_dword v[102:103], v99, off offset:1152

; __device__ __forceinline__ unsigned pack2(float a, float b) { return (unsigned)f2bf(a) | ((unsigned)f2bf(b) << 16); }
; template <int EPI, bool HS = false>
; __device__ __forceinline__ void gemm_phase(const Params& p, const GemmCfg& g, char* shm, const int wave_s) {
;     ...
;           for (int j = 0; j < 4; ++j) {
;             float ss = 0.f;
; #pragma unroll
;             for (int bj = 0; bj < 2; ++bj) {
;               float2 xn;
;               xn.x = xv[j][bj].x + gt[bj][0] * acc[ai][bj][m][0][j];
;               xn.y = xv[j][bj].y + gt[bj][1] * acc[ai][bj][m][1][j];
;               const unsigned o = tb + (unsigned)((ai * 128 + m * 16 + j) * 1024 + bj * 128);
;               *(float2*)(xout_t + o) = xn;
;               if (g.has_next) *(unsigned*)(xg_t + o) = pack2(xn.x * gn[bj][0], xn.y * gn[bj][1]);
;               ss += xn.x * xn.x + xn.y * xn.y;
;             }
;             if (g.has_next) {
;               ss = dpp_row_sum16(ss);
;               if (fr == 0) rss_t[(wr * 64 + fq * 4 + ai * 128 + m * 16 + j) * 16] = ss;
;             }
.LBB0_142:
	v_or_b32_e32 v106, 0x4c00, v0
	v_mov_b32_e32 v112, v109
	v_mov_b32_e32 v107, v1
	s_waitcnt lgkmcnt(0)
	v_pk_fma_f32 v[102:103], v[150:151], v[112:113], v[114:115]
	v_lshl_add_u64 v[98:99], v[106:107], 2, s[2:3]
	global_store_dwordx2 v[98:99], v[102:103], off
	s_mov_b64 s[68:69], -1
	s_and_b64 vcc, exec, s[6:7]
	v_or_b32_e32 v98, 0x4c80, v0
	s_cbranch_vccnz .LBB0_146
	v_pk_mul_f32 v[108:109], v[148:149], v[102:103]
	v_lshl_add_u64 v[106:107], v[106:107], 1, s[8:9]
	s_nop 0
	v_and_b32_sdwa v99, v109, v178 dst_sel:DWORD dst_unused:UNUSED_PAD src0_sel:WORD_1 src1_sel:DWORD
	v_cvt_pk_bf16_f32 v100, v108, v108
	v_add3_u32 v99, v109, v99, s81
	v_lshrrev_b32_e32 v100, 16, v100
	v_and_or_b32 v99, v99, s28, v100
	global_store_dword v[106:107], v99, off
	v_mov_b32_e32 v104, v101
	v_mov_b32_e32 v99, v1
	v_pk_fma_f32 v[106:107], v[146:147], v[104:105], v[116:117]
	v_lshl_add_u64 v[108:109], v[98:99], 2, s[2:3]
	global_store_dwordx2 v[108:109], v[106:107], off
	v_pk_mul_f32 v[108:109], v[152:153], v[106:107]
	v_pk_mul_f32 v[102:103], v[102:103], v[102:103]
	s_nop 0
	v_and_b32_sdwa v100, v109, v178 dst_sel:DWORD dst_unused:UNUSED_PAD src0_sel:WORD_1 src1_sel:DWORD
	v_cvt_pk_bf16_f32 v104, v108, v108
	v_add3_u32 v100, v109, v100, s81
	v_lshrrev_b32_e32 v104, 16, v104
	v_and_or_b32 v100, v100, s28, v104
	v_lshl_add_u64 v[108:109], v[98:99], 1, s[8:9]
	v_pk_mul_f32 v[106:107], v[106:107], v[106:107]
	global_store_dword v[108:109], v100, off
	v_add_f32_e32 v99, v106, v107
	v_add_f32_e32 v100, v102, v103
	v_add_f32_e32 v99, v100, v99
	s_nop 1
	v_add_f32_dpp v99, v99, v99 quad_perm:[1,0,3,2] row_mask:0xf bank_mask:0xf bound_ctrl:1
	s_nop 1
	v_add_f32_dpp v99, v99, v99 quad_perm:[2,3,0,1] row_mask:0xf bank_mask:0xf bound_ctrl:1
	s_nop 1
	v_add_f32_dpp v99, v99, v99 row_half_mirror row_mask:0xf bank_mask:0xf bound_ctrl:1
	s_nop 1
	v_mov_b32_dpp v100, v99 row_mirror row_mask:0xf bank_mask:0xf bound_ctrl:1
	s_and_saveexec_b64 s[68:69], s[4:5]
	s_cbranch_execz .LBB0_145
	v_lshlrev_b32_e32 v102, 4, v160
	v_ashrrev_i32_e32 v103, 31, v102
	v_add_f32_e32 v99, v99, v100
	v_lshl_add_u64 v[102:103], v[102:103], 2, v[142:143]
	global_store_dword v[102:103], v99, off offset:1216

; __device__ __forceinline__ unsigned pack2(float a, float b) { return (unsigned)f2bf(a) | ((unsigned)f2bf(b) << 16); }
; template <int EPI, bool HS = false>
; __device__ __forceinline__ void gemm_phase(const Params& p, const GemmCfg& g, char* shm, const int wave_s) {
;     ...
; #pragma unroll
;         for (int m = 0; m < 4; ++m) {
;           float2 xv[4][2];
; #pragma unroll
;           for (int j = 0; j < 4; ++j)
; #pragma unroll
;             for (int bj = 0; bj < 2; ++bj) xv[j][bj] = *(const float2*)(xl + (m * 16 + j) * XROW + bj * 512);
; #pragma unroll
;           for (int j = 0; j < 4; ++j) {
;             float ss = 0.f;
; #pragma unroll
;             for (int bj = 0; bj < 2; ++bj) {
;               float2 xn;
;               xn.x = xv[j][bj].x + gt[bj][0] * acc[ai][bj][m][0][j];
;               xn.y = xv[j][bj].y + gt[bj][1] * acc[ai][bj][m][1][j];
;               const unsigned o = tb + (unsigned)((ai * 128 + m * 16 + j) * 1024 + bj * 128);
;               *(float2*)(xout_t + o) = xn;
;               if (g.has_next) *(unsigned*)(xg_t + o) = pack2(xn.x * gn[bj][0], xn.y * gn[bj][1]);
;               ss += xn.x * xn.x + xn.y * xn.y;
;             }
;             if (g.has_next) {
;               ss = dpp_row_sum16(ss);
;               if (fr == 0) rss_t[(wr * 64 + fq * 4 + ai * 128 + m * 16 + j) * 16] = ss;
;             }
.LBB0_148:
	ds_read2st64_b64 v[110:113], v161 offset0:65 offset1:66
	v_add_u32_e32 v118, 16, v161
	ds_read2st64_b64 v[106:109], v118 offset0:67 offset1:68
	ds_read2st64_b64 v[102:105], v162 offset0:69 offset1:70
	ds_read2st64_b64 v[98:101], v163 offset0:71 offset1:72
	v_or_b32_e32 v116, 0x8000, v0
	v_mov_b32_e32 v114, v90
	v_mov_b32_e32 v115, v94
	v_mov_b32_e32 v117, v1
	s_waitcnt lgkmcnt(3)
	v_pk_fma_f32 v[114:115], v[150:151], v[114:115], v[110:111]
	v_lshl_add_u64 v[110:111], v[116:117], 2, s[2:3]
	global_store_dwordx2 v[110:111], v[114:115], off
	s_mov_b64 s[68:69], -1
	s_and_b64 vcc, exec, s[6:7]
	v_or_b32_e32 v110, 0x8080, v0
	s_cbranch_vccnz .LBB0_152
	v_pk_mul_f32 v[120:121], v[148:149], v[114:115]
	v_lshl_add_u64 v[116:117], v[116:117], 1, s[8:9]
	s_nop 0
	v_and_b32_sdwa v90, v121, v178 dst_sel:DWORD dst_unused:UNUSED_PAD src0_sel:WORD_1 src1_sel:DWORD
	v_cvt_pk_bf16_f32 v94, v120, v120
	v_add3_u32 v90, v121, v90, s81
	v_lshrrev_b32_e32 v94, 16, v94
	v_and_or_b32 v90, v90, s28, v94
	global_store_dword v[116:117], v90, off
	v_mov_b32_e32 v116, v82
	v_mov_b32_e32 v117, v86
	v_mov_b32_e32 v111, v1
	v_pk_fma_f32 v[116:117], v[146:147], v[116:117], v[112:113]
	v_lshl_add_u64 v[120:121], v[110:111], 2, s[2:3]
	global_store_dwordx2 v[120:121], v[116:117], off
	v_pk_mul_f32 v[120:121], v[152:153], v[116:117]
	v_pk_mul_f32 v[114:115], v[114:115], v[114:115]
	s_nop 0
	v_and_b32_sdwa v90, v121, v178 dst_sel:DWORD dst_unused:UNUSED_PAD src0_sel:WORD_1 src1_sel:DWORD
	v_cvt_pk_bf16_f32 v94, v120, v120
	v_add3_u32 v90, v121, v90, s81
	v_lshrrev_b32_e32 v94, 16, v94
	v_and_or_b32 v90, v90, s28, v94
	v_lshl_add_u64 v[120:121], v[110:111], 1, s[8:9]
	v_pk_mul_f32 v[116:117], v[116:117], v[116:117]
	global_store_dword v[120:121], v90, off
	v_add_f32_e32 v90, v116, v117
	v_add_f32_e32 v94, v114, v115
	v_add_f32_e32 v90, v94, v90
	s_nop 1
	v_add_f32_dpp v90, v90, v90 quad_perm:[1,0,3,2] row_mask:0xf bank_mask:0xf bound_ctrl:1
	s_nop 1
	v_add_f32_dpp v90, v90, v90 quad_perm:[2,3,0,1] row_mask:0xf bank_mask:0xf bound_ctrl:1
	s_nop 1
	v_add_f32_dpp v90, v90, v90 row_half_mirror row_mask:0xf bank_mask:0xf bound_ctrl:1
	s_nop 1
	v_mov_b32_dpp v94, v90 row_mirror row_mask:0xf bank_mask:0xf bound_ctrl:1
	s_and_saveexec_b64 s[68:69], s[4:5]
	s_cbranch_execz .LBB0_151
	v_lshlrev_b32_e32 v114, 4, v160
	v_ashrrev_i32_e32 v115, 31, v114
	v_add_f32_e32 v90, v90, v94
	v_lshl_add_u64 v[114:115], v[114:115], 2, v[142:143]
	global_store_dword v[114:115], v90, off offset:2048

; __device__ __forceinline__ unsigned pack2(float a, float b) { return (unsigned)f2bf(a) | ((unsigned)f2bf(b) << 16); }
; template <int EPI, bool HS = false>
; __device__ __forceinline__ void gemm_phase(const Params& p, const GemmCfg& g, char* shm, const int wave_s) {
;     ...
;           for (int j = 0; j < 4; ++j) {
;             float ss = 0.f;
; #pragma unroll
;             for (int bj = 0; bj < 2; ++bj) {
;               float2 xn;
;               xn.x = xv[j][bj].x + gt[bj][0] * acc[ai][bj][m][0][j];
;               xn.y = xv[j][bj].y + gt[bj][1] * acc[ai][bj][m][1][j];
;               const unsigned o = tb + (unsigned)((ai * 128 + m * 16 + j) * 1024 + bj * 128);
;               *(float2*)(xout_t + o) = xn;
;               if (g.has_next) *(unsigned*)(xg_t + o) = pack2(xn.x * gn[bj][0], xn.y * gn[bj][1]);
;               ss += xn.x * xn.x + xn.y * xn.y;
;             }
;             if (g.has_next) {
;               ss = dpp_row_sum16(ss);
;               if (fr == 0) rss_t[(wr * 64 + fq * 4 + ai * 128 + m * 16 + j) * 16] = ss;
;             }
.LBB0_154:
	v_or_b32_e32 v110, 0x8400, v0
	v_mov_b32_e32 v94, v91
	v_mov_b32_e32 v111, v1
	s_waitcnt lgkmcnt(2)
	v_pk_fma_f32 v[94:95], v[150:151], v[94:95], v[106:107]
	v_lshl_add_u64 v[90:91], v[110:111], 2, s[2:3]
	global_store_dwordx2 v[90:91], v[94:95], off
	s_mov_b64 s[68:69], -1
	s_and_b64 vcc, exec, s[6:7]
	v_or_b32_e32 v90, 0x8480, v0
	s_cbranch_vccnz .LBB0_158
	v_pk_mul_f32 v[106:107], v[148:149], v[94:95]
	v_mov_b32_e32 v91, v1
	s_nop 0
	v_and_b32_sdwa v82, v107, v178 dst_sel:DWORD dst_unused:UNUSED_PAD src0_sel:WORD_1 src1_sel:DWORD
	v_cvt_pk_bf16_f32 v86, v106, v106
	v_add3_u32 v82, v107, v82, s81
	v_lshrrev_b32_e32 v86, 16, v86
	v_and_or_b32 v82, v82, s28, v86
	v_lshl_add_u64 v[106:107], v[110:111], 1, s[8:9]
	v_mov_b32_e32 v86, v83
	global_store_dword v[106:107], v82, off
	v_pk_fma_f32 v[106:107], v[146:147], v[86:87], v[108:109]
	v_lshl_add_u64 v[110:111], v[90:91], 2, s[2:3]
	global_store_dwordx2 v[110:111], v[106:107], off
	v_pk_mul_f32 v[110:111], v[152:153], v[106:107]
	v_pk_mul_f32 v[94:95], v[94:95], v[94:95]
	s_nop 0
	v_and_b32_sdwa v82, v111, v178 dst_sel:DWORD dst_unused:UNUSED_PAD src0_sel:WORD_1 src1_sel:DWORD
	v_cvt_pk_bf16_f32 v86, v110, v110
	v_add3_u32 v82, v111, v82, s81
	v_lshrrev_b32_e32 v86, 16, v86
	v_and_or_b32 v82, v82, s28, v86
	v_lshl_add_u64 v[110:111], v[90:91], 1, s[8:9]
	v_pk_mul_f32 v[106:107], v[106:107], v[106:107]
	global_store_dword v[110:111], v82, off
	v_add_f32_e32 v82, v106, v107
	v_add_f32_e32 v86, v94, v95
	v_add_f32_e32 v82, v86, v82
	s_nop 1
	v_add_f32_dpp v82, v82, v82 quad_perm:[1,0,3,2] row_mask:0xf bank_mask:0xf bound_ctrl:1
	s_nop 1
	v_add_f32_dpp v82, v82, v82 quad_perm:[2,3,0,1] row_mask:0xf bank_mask:0xf bound_ctrl:1
	s_nop 1
	v_add_f32_dpp v82, v82, v82 row_half_mirror row_mask:0xf bank_mask:0xf bound_ctrl:1
	s_nop 1
	v_mov_b32_dpp v86, v82 row_mirror row_mask:0xf bank_mask:0xf bound_ctrl:1
	s_and_saveexec_b64 s[68:69], s[4:5]
	s_cbranch_execz .LBB0_157
	v_lshlrev_b32_e32 v94, 4, v160
	v_ashrrev_i32_e32 v95, 31, v94
	v_add_f32_e32 v82, v82, v86
	v_lshl_add_u64 v[94:95], v[94:95], 2, v[142:143]
	global_store_dword v[94:95], v82, off offset:2112

; __device__ __forceinline__ unsigned pack2(float a, float b) { return (unsigned)f2bf(a) | ((unsigned)f2bf(b) << 16); }
; template <int EPI, bool HS = false>
; __device__ __forceinline__ void gemm_phase(const Params& p, const GemmCfg& g, char* shm, const int wave_s) {
;     ...
;           for (int j = 0; j < 4; ++j) {
;             float ss = 0.f;
; #pragma unroll
;             for (int bj = 0; bj < 2; ++bj) {
;               float2 xn;
;               xn.x = xv[j][bj].x + gt[bj][0] * acc[ai][bj][m][0][j];
;               xn.y = xv[j][bj].y + gt[bj][1] * acc[ai][bj][m][1][j];
;               const unsigned o = tb + (unsigned)((ai * 128 + m * 16 + j) * 1024 + bj * 128);
;               *(float2*)(xout_t + o) = xn;
;               if (g.has_next) *(unsigned*)(xg_t + o) = pack2(xn.x * gn[bj][0], xn.y * gn[bj][1]);
;               ss += xn.x * xn.x + xn.y * xn.y;
;             }
;             if (g.has_next) {
;               ss = dpp_row_sum16(ss);
;               if (fr == 0) rss_t[(wr * 64 + fq * 4 + ai * 128 + m * 16 + j) * 16] = ss;
;             }
.LBB0_160:
	v_or_b32_e32 v90, 0x8800, v0
	v_mov_b32_e32 v82, v92
	v_mov_b32_e32 v83, v96
	v_mov_b32_e32 v91, v1
	s_waitcnt lgkmcnt(1)
	v_pk_fma_f32 v[86:87], v[150:151], v[82:83], v[102:103]
	v_lshl_add_u64 v[82:83], v[90:91], 2, s[2:3]
	global_store_dwordx2 v[82:83], v[86:87], off
	s_mov_b64 s[68:69], -1
	s_and_b64 vcc, exec, s[6:7]
	v_or_b32_e32 v82, 0x8880, v0
	s_cbranch_vccnz .LBB0_164
	v_pk_mul_f32 v[94:95], v[148:149], v[86:87]
	v_lshl_add_u64 v[90:91], v[90:91], 1, s[8:9]
	s_nop 0
	v_and_b32_sdwa v83, v95, v178 dst_sel:DWORD dst_unused:UNUSED_PAD src0_sel:WORD_1 src1_sel:DWORD
	v_cvt_pk_bf16_f32 v92, v94, v94
	v_add3_u32 v83, v95, v83, s81
	v_lshrrev_b32_e32 v92, 16, v92
	v_and_or_b32 v83, v83, s28, v92
	global_store_dword v[90:91], v83, off
	v_mov_b32_e32 v90, v84
	v_mov_b32_e32 v91, v88
	v_mov_b32_e32 v83, v1
	v_pk_fma_f32 v[90:91], v[146:147], v[90:91], v[104:105]
	v_lshl_add_u64 v[94:95], v[82:83], 2, s[2:3]
	global_store_dwordx2 v[94:95], v[90:91], off
	v_pk_mul_f32 v[94:95], v[152:153], v[90:91]
	v_pk_mul_f32 v[86:87], v[86:87], v[86:87]
	v_and_b32_sdwa v96, v94, v178 dst_sel:DWORD dst_unused:UNUSED_PAD src0_sel:WORD_1 src1_sel:DWORD
	v_and_b32_sdwa v92, v95, v178 dst_sel:DWORD dst_unused:UNUSED_PAD src0_sel:WORD_1 src1_sel:DWORD
	v_add3_u32 v94, v94, v96, s81
	v_add3_u32 v92, v95, v92, s81
	v_lshrrev_b32_e32 v94, 16, v94
	v_pk_mul_f32 v[90:91], v[90:91], v[90:91]
	v_and_or_b32 v92, v92, s28, v94
	v_lshl_add_u64 v[94:95], v[82:83], 1, s[8:9]
	v_add_f32_e32 v83, v90, v91
	v_add_f32_e32 v86, v86, v87
	v_add_f32_e32 v83, v86, v83
	global_store_dword v[94:95], v92, off
	s_nop 0
	v_add_f32_dpp v83, v83, v83 quad_perm:[1,0,3,2] row_mask:0xf bank_mask:0xf bound_ctrl:1
	s_nop 1
	v_add_f32_dpp v83, v83, v83 quad_perm:[2,3,0,1] row_mask:0xf bank_mask:0xf bound_ctrl:1
	s_nop 1
	v_add_f32_dpp v83, v83, v83 row_half_mirror row_mask:0xf bank_mask:0xf bound_ctrl:1
	s_nop 1
	v_mov_b32_dpp v86, v83 row_mirror row_mask:0xf bank_mask:0xf bound_ctrl:1
	s_and_saveexec_b64 s[68:69], s[4:5]
	s_cbranch_execz .LBB0_163
	v_add_f32_e32 v83, v83, v86
	v_lshlrev_b32_e32 v86, 4, v160
	v_ashrrev_i32_e32 v87, 31, v86
	v_lshl_add_u64 v[86:87], v[86:87], 2, v[142:143]
	global_store_dword v[86:87], v83, off offset:2176

; __device__ __forceinline__ unsigned pack2(float a, float b) { return (unsigned)f2bf(a) | ((unsigned)f2bf(b) << 16); }
; template <int EPI, bool HS = false>
; __device__ __forceinline__ void gemm_phase(const Params& p, const GemmCfg& g, char* shm, const int wave_s) {
;     ...
;           for (int j = 0; j < 4; ++j) {
;             float ss = 0.f;
; #pragma unroll
;             for (int bj = 0; bj < 2; ++bj) {
;               float2 xn;
;               xn.x = xv[j][bj].x + gt[bj][0] * acc[ai][bj][m][0][j];
;               xn.y = xv[j][bj].y + gt[bj][1] * acc[ai][bj][m][1][j];
;               const unsigned o = tb + (unsigned)((ai * 128 + m * 16 + j) * 1024 + bj * 128);
;               *(float2*)(xout_t + o) = xn;
;               if (g.has_next) *(unsigned*)(xg_t + o) = pack2(xn.x * gn[bj][0], xn.y * gn[bj][1]);
;               ss += xn.x * xn.x + xn.y * xn.y;
;             }
;             if (g.has_next) {
;               ss = dpp_row_sum16(ss);
;               if (fr == 0) rss_t[(wr * 64 + fq * 4 + ai * 128 + m * 16 + j) * 16] = ss;
;             }
.LBB0_166:
	v_or_b32_e32 v90, 0x8c00, v0
	v_mov_b32_e32 v96, v93
	v_mov_b32_e32 v91, v1
	s_waitcnt lgkmcnt(0)
	v_pk_fma_f32 v[86:87], v[150:151], v[96:97], v[98:99]
	v_lshl_add_u64 v[82:83], v[90:91], 2, s[2:3]
	global_store_dwordx2 v[82:83], v[86:87], off
	s_mov_b64 s[68:69], -1
	s_and_b64 vcc, exec, s[6:7]
	v_or_b32_e32 v82, 0x8c80, v0
	s_cbranch_vccnz .LBB0_170
	v_pk_mul_f32 v[92:93], v[148:149], v[86:87]
	v_lshl_add_u64 v[90:91], v[90:91], 1, s[8:9]
	s_nop 0
	v_and_b32_sdwa v83, v93, v178 dst_sel:DWORD dst_unused:UNUSED_PAD src0_sel:WORD_1 src1_sel:DWORD
	v_cvt_pk_bf16_f32 v84, v92, v92
	v_add3_u32 v83, v93, v83, s81
	v_lshrrev_b32_e32 v84, 16, v84
	v_and_or_b32 v83, v83, s28, v84
	global_store_dword v[90:91], v83, off
	v_mov_b32_e32 v88, v85
	v_mov_b32_e32 v83, v1
	v_pk_fma_f32 v[90:91], v[146:147], v[88:89], v[100:101]
	v_lshl_add_u64 v[92:93], v[82:83], 2, s[2:3]
	global_store_dwordx2 v[92:93], v[90:91], off
	v_pk_mul_f32 v[92:93], v[152:153], v[90:91]
	v_pk_mul_f32 v[86:87], v[86:87], v[86:87]
	s_nop 0
	v_and_b32_sdwa v84, v93, v178 dst_sel:DWORD dst_unused:UNUSED_PAD src0_sel:WORD_1 src1_sel:DWORD
	v_cvt_pk_bf16_f32 v88, v92, v92
	v_add3_u32 v84, v93, v84, s81
	v_lshrrev_b32_e32 v88, 16, v88
	v_and_or_b32 v84, v84, s28, v88
	v_lshl_add_u64 v[92:93], v[82:83], 1, s[8:9]
	v_pk_mul_f32 v[90:91], v[90:91], v[90:91]
	global_store_dword v[92:93], v84, off
	v_add_f32_e32 v83, v90, v91
	v_add_f32_e32 v84, v86, v87
	v_add_f32_e32 v83, v84, v83
	s_nop 1
	v_add_f32_dpp v83, v83, v83 quad_perm:[1,0,3,2] row_mask:0xf bank_mask:0xf bound_ctrl:1
	s_nop 1
	v_add_f32_dpp v83, v83, v83 quad_perm:[2,3,0,1] row_mask:0xf bank_mask:0xf bound_ctrl:1
	s_nop 1
	v_add_f32_dpp v83, v83, v83 row_half_mirror row_mask:0xf bank_mask:0xf bound_ctrl:1
	s_nop 1
	v_mov_b32_dpp v84, v83 row_mirror row_mask:0xf bank_mask:0xf bound_ctrl:1
	s_and_saveexec_b64 s[68:69], s[4:5]
	s_cbranch_execz .LBB0_169
	v_lshlrev_b32_e32 v86, 4, v160
	v_ashrrev_i32_e32 v87, 31, v86
	v_add_f32_e32 v83, v83, v84
	v_lshl_add_u64 v[86:87], v[86:87], 2, v[142:143]
	global_store_dword v[86:87], v83, off offset:2240

; __device__ __forceinline__ unsigned pack2(float a, float b) { return (unsigned)f2bf(a) | ((unsigned)f2bf(b) << 16); }
; template <int EPI, bool HS = false>
; __device__ __forceinline__ void gemm_phase(const Params& p, const GemmCfg& g, char* shm, const int wave_s) {
;     ...
; #pragma unroll
;         for (int m = 0; m < 4; ++m) {
;           float2 xv[4][2];
; #pragma unroll
;           for (int j = 0; j < 4; ++j)
; #pragma unroll
;             for (int bj = 0; bj < 2; ++bj) xv[j][bj] = *(const float2*)(xl + (m * 16 + j) * XROW + bj * 512);
; #pragma unroll
;           for (int j = 0; j < 4; ++j) {
;             float ss = 0.f;
; #pragma unroll
;             for (int bj = 0; bj < 2; ++bj) {
;               float2 xn;
;               xn.x = xv[j][bj].x + gt[bj][0] * acc[ai][bj][m][0][j];
;               xn.y = xv[j][bj].y + gt[bj][1] * acc[ai][bj][m][1][j];
;               const unsigned o = tb + (unsigned)((ai * 128 + m * 16 + j) * 1024 + bj * 128);
;               *(float2*)(xout_t + o) = xn;
;               if (g.has_next) *(unsigned*)(xg_t + o) = pack2(xn.x * gn[bj][0], xn.y * gn[bj][1]);
;               ss += xn.x * xn.x + xn.y * xn.y;
;             }
;             if (g.has_next) {
;               ss = dpp_row_sum16(ss);
;               if (fr == 0) rss_t[(wr * 64 + fq * 4 + ai * 128 + m * 16 + j) * 16] = ss;
;             }
.LBB0_172:
	ds_read2st64_b64 v[94:97], v134 offset0:97 offset1:98
	ds_read2st64_b64 v[90:93], v135 offset0:99 offset1:100
	ds_read2st64_b64 v[86:89], v136 offset0:101 offset1:102
	ds_read2st64_b64 v[82:85], v137 offset0:103 offset1:104
	v_or_b32_e32 v100, 0xc000, v0
	v_mov_b32_e32 v98, v74
	v_mov_b32_e32 v99, v78
	v_mov_b32_e32 v101, v1
	s_waitcnt lgkmcnt(3)
	v_pk_fma_f32 v[98:99], v[150:151], v[98:99], v[94:95]
	v_lshl_add_u64 v[94:95], v[100:101], 2, s[2:3]
	global_store_dwordx2 v[94:95], v[98:99], off
	s_mov_b64 s[68:69], -1
	s_and_b64 vcc, exec, s[6:7]
	v_or_b32_e32 v94, 0xc080, v0
	s_cbranch_vccnz .LBB0_176
	v_pk_mul_f32 v[102:103], v[148:149], v[98:99]
	v_lshl_add_u64 v[100:101], v[100:101], 1, s[8:9]
	s_nop 0
	v_and_b32_sdwa v74, v103, v178 dst_sel:DWORD dst_unused:UNUSED_PAD src0_sel:WORD_1 src1_sel:DWORD
	v_cvt_pk_bf16_f32 v78, v102, v102
	v_add3_u32 v74, v103, v74, s81
	v_lshrrev_b32_e32 v78, 16, v78
	v_and_or_b32 v74, v74, s28, v78
	global_store_dword v[100:101], v74, off
	v_mov_b32_e32 v100, v66
	v_mov_b32_e32 v101, v70
	v_mov_b32_e32 v95, v1
	v_pk_fma_f32 v[100:101], v[146:147], v[100:101], v[96:97]
	v_lshl_add_u64 v[102:103], v[94:95], 2, s[2:3]
	global_store_dwordx2 v[102:103], v[100:101], off
	v_pk_mul_f32 v[102:103], v[152:153], v[100:101]
	v_pk_mul_f32 v[98:99], v[98:99], v[98:99]
	s_nop 0
	v_and_b32_sdwa v74, v103, v178 dst_sel:DWORD dst_unused:UNUSED_PAD src0_sel:WORD_1 src1_sel:DWORD
	v_cvt_pk_bf16_f32 v78, v102, v102
	v_add3_u32 v74, v103, v74, s81
	v_lshrrev_b32_e32 v78, 16, v78
	v_and_or_b32 v74, v74, s28, v78
	v_lshl_add_u64 v[102:103], v[94:95], 1, s[8:9]
	v_pk_mul_f32 v[100:101], v[100:101], v[100:101]
	global_store_dword v[102:103], v74, off
	v_add_f32_e32 v74, v100, v101
	v_add_f32_e32 v78, v98, v99
	v_add_f32_e32 v74, v78, v74
	s_nop 1
	v_add_f32_dpp v74, v74, v74 quad_perm:[1,0,3,2] row_mask:0xf bank_mask:0xf bound_ctrl:1
	s_nop 1
	v_add_f32_dpp v74, v74, v74 quad_perm:[2,3,0,1] row_mask:0xf bank_mask:0xf bound_ctrl:1
	s_nop 1
	v_add_f32_dpp v74, v74, v74 row_half_mirror row_mask:0xf bank_mask:0xf bound_ctrl:1
	s_nop 1
	v_mov_b32_dpp v78, v74 row_mirror row_mask:0xf bank_mask:0xf bound_ctrl:1
	s_and_saveexec_b64 s[68:69], s[4:5]
	s_cbranch_execz .LBB0_175
	v_lshlrev_b32_e32 v98, 4, v160
	v_ashrrev_i32_e32 v99, 31, v98
	v_add_f32_e32 v74, v74, v78
	v_lshl_add_u64 v[98:99], v[98:99], 2, v[142:143]
	global_store_dword v[98:99], v74, off offset:3072

; __device__ __forceinline__ unsigned pack2(float a, float b) { return (unsigned)f2bf(a) | ((unsigned)f2bf(b) << 16); }
; template <int EPI, bool HS = false>
; __device__ __forceinline__ void gemm_phase(const Params& p, const GemmCfg& g, char* shm, const int wave_s) {
;     ...
;           for (int j = 0; j < 4; ++j) {
;             float ss = 0.f;
; #pragma unroll
;             for (int bj = 0; bj < 2; ++bj) {
;               float2 xn;
;               xn.x = xv[j][bj].x + gt[bj][0] * acc[ai][bj][m][0][j];
;               xn.y = xv[j][bj].y + gt[bj][1] * acc[ai][bj][m][1][j];
;               const unsigned o = tb + (unsigned)((ai * 128 + m * 16 + j) * 1024 + bj * 128);
;               *(float2*)(xout_t + o) = xn;
;               if (g.has_next) *(unsigned*)(xg_t + o) = pack2(xn.x * gn[bj][0], xn.y * gn[bj][1]);
;               ss += xn.x * xn.x + xn.y * xn.y;
;             }
;             if (g.has_next) {
;               ss = dpp_row_sum16(ss);
;               if (fr == 0) rss_t[(wr * 64 + fq * 4 + ai * 128 + m * 16 + j) * 16] = ss;
;             }
.LBB0_178:
	v_or_b32_e32 v94, 0xc400, v0
	v_mov_b32_e32 v78, v75
	v_mov_b32_e32 v95, v1
	s_waitcnt lgkmcnt(2)
	v_pk_fma_f32 v[78:79], v[150:151], v[78:79], v[90:91]
	v_lshl_add_u64 v[74:75], v[94:95], 2, s[2:3]
	global_store_dwordx2 v[74:75], v[78:79], off
	s_mov_b64 s[68:69], -1
	s_and_b64 vcc, exec, s[6:7]
	v_or_b32_e32 v74, 0xc480, v0
	s_cbranch_vccnz .LBB0_182
	v_pk_mul_f32 v[90:91], v[148:149], v[78:79]
	v_mov_b32_e32 v75, v1
	s_nop 0
	v_and_b32_sdwa v66, v91, v178 dst_sel:DWORD dst_unused:UNUSED_PAD src0_sel:WORD_1 src1_sel:DWORD
	v_cvt_pk_bf16_f32 v70, v90, v90
	v_add3_u32 v66, v91, v66, s81
	v_lshrrev_b32_e32 v70, 16, v70
	v_and_or_b32 v66, v66, s28, v70
	v_lshl_add_u64 v[90:91], v[94:95], 1, s[8:9]
	v_mov_b32_e32 v70, v67
	global_store_dword v[90:91], v66, off
	v_pk_fma_f32 v[90:91], v[146:147], v[70:71], v[92:93]
	v_lshl_add_u64 v[94:95], v[74:75], 2, s[2:3]
	global_store_dwordx2 v[94:95], v[90:91], off
	v_pk_mul_f32 v[94:95], v[152:153], v[90:91]
	v_pk_mul_f32 v[78:79], v[78:79], v[78:79]
	s_nop 0
	v_and_b32_sdwa v66, v95, v178 dst_sel:DWORD dst_unused:UNUSED_PAD src0_sel:WORD_1 src1_sel:DWORD
	v_cvt_pk_bf16_f32 v70, v94, v94
	v_add3_u32 v66, v95, v66, s81
	v_lshrrev_b32_e32 v70, 16, v70
	v_and_or_b32 v66, v66, s28, v70
	v_lshl_add_u64 v[94:95], v[74:75], 1, s[8:9]
	v_pk_mul_f32 v[90:91], v[90:91], v[90:91]
	global_store_dword v[94:95], v66, off
	v_add_f32_e32 v66, v90, v91
	v_add_f32_e32 v70, v78, v79
	v_add_f32_e32 v66, v70, v66
	s_nop 1
	v_add_f32_dpp v66, v66, v66 quad_perm:[1,0,3,2] row_mask:0xf bank_mask:0xf bound_ctrl:1
	s_nop 1
	v_add_f32_dpp v66, v66, v66 quad_perm:[2,3,0,1] row_mask:0xf bank_mask:0xf bound_ctrl:1
	s_nop 1
	v_add_f32_dpp v66, v66, v66 row_half_mirror row_mask:0xf bank_mask:0xf bound_ctrl:1
	s_nop 1
	v_mov_b32_dpp v70, v66 row_mirror row_mask:0xf bank_mask:0xf bound_ctrl:1
	s_and_saveexec_b64 s[68:69], s[4:5]
	s_cbranch_execz .LBB0_181
	v_lshlrev_b32_e32 v78, 4, v160
	v_ashrrev_i32_e32 v79, 31, v78
	v_add_f32_e32 v66, v66, v70
	v_lshl_add_u64 v[78:79], v[78:79], 2, v[142:143]
	global_store_dword v[78:79], v66, off offset:3136

; __device__ __forceinline__ unsigned pack2(float a, float b) { return (unsigned)f2bf(a) | ((unsigned)f2bf(b) << 16); }
; template <int EPI, bool HS = false>
; __device__ __forceinline__ void gemm_phase(const Params& p, const GemmCfg& g, char* shm, const int wave_s) {
;     ...
;           for (int j = 0; j < 4; ++j) {
;             float ss = 0.f;
; #pragma unroll
;             for (int bj = 0; bj < 2; ++bj) {
;               float2 xn;
;               xn.x = xv[j][bj].x + gt[bj][0] * acc[ai][bj][m][0][j];
;               xn.y = xv[j][bj].y + gt[bj][1] * acc[ai][bj][m][1][j];
;               const unsigned o = tb + (unsigned)((ai * 128 + m * 16 + j) * 1024 + bj * 128);
;               *(float2*)(xout_t + o) = xn;
;               if (g.has_next) *(unsigned*)(xg_t + o) = pack2(xn.x * gn[bj][0], xn.y * gn[bj][1]);
;               ss += xn.x * xn.x + xn.y * xn.y;
;             }
;             if (g.has_next) {
;               ss = dpp_row_sum16(ss);
;               if (fr == 0) rss_t[(wr * 64 + fq * 4 + ai * 128 + m * 16 + j) * 16] = ss;
;             }
.LBB0_184:
	v_or_b32_e32 v74, 0xc800, v0
	v_mov_b32_e32 v66, v76
	v_mov_b32_e32 v67, v80
	v_mov_b32_e32 v75, v1
	s_waitcnt lgkmcnt(1)
	v_pk_fma_f32 v[70:71], v[150:151], v[66:67], v[86:87]
	v_lshl_add_u64 v[66:67], v[74:75], 2, s[2:3]
	global_store_dwordx2 v[66:67], v[70:71], off
	s_mov_b64 s[68:69], -1
	s_and_b64 vcc, exec, s[6:7]
	v_or_b32_e32 v66, 0xc880, v0
	s_cbranch_vccnz .LBB0_188
	v_pk_mul_f32 v[78:79], v[148:149], v[70:71]
	v_lshl_add_u64 v[74:75], v[74:75], 1, s[8:9]
	s_nop 0
	v_and_b32_sdwa v67, v79, v178 dst_sel:DWORD dst_unused:UNUSED_PAD src0_sel:WORD_1 src1_sel:DWORD
	v_cvt_pk_bf16_f32 v76, v78, v78
	v_add3_u32 v67, v79, v67, s81
	v_lshrrev_b32_e32 v76, 16, v76
	v_and_or_b32 v67, v67, s28, v76
	global_store_dword v[74:75], v67, off
	v_mov_b32_e32 v74, v68
	v_mov_b32_e32 v75, v72
	v_mov_b32_e32 v67, v1
	v_pk_fma_f32 v[74:75], v[146:147], v[74:75], v[88:89]
	v_lshl_add_u64 v[78:79], v[66:67], 2, s[2:3]
	global_store_dwordx2 v[78:79], v[74:75], off
	v_pk_mul_f32 v[78:79], v[152:153], v[74:75]
	v_pk_mul_f32 v[70:71], v[70:71], v[70:71]
	v_and_b32_sdwa v80, v78, v178 dst_sel:DWORD dst_unused:UNUSED_PAD src0_sel:WORD_1 src1_sel:DWORD
	v_and_b32_sdwa v76, v79, v178 dst_sel:DWORD dst_unused:UNUSED_PAD src0_sel:WORD_1 src1_sel:DWORD
	v_add3_u32 v78, v78, v80, s81
	v_add3_u32 v76, v79, v76, s81
	v_lshrrev_b32_e32 v78, 16, v78
	v_pk_mul_f32 v[74:75], v[74:75], v[74:75]
	v_and_or_b32 v76, v76, s28, v78
	v_lshl_add_u64 v[78:79], v[66:67], 1, s[8:9]
	v_add_f32_e32 v67, v74, v75
	v_add_f32_e32 v70, v70, v71
	v_add_f32_e32 v67, v70, v67
	global_store_dword v[78:79], v76, off
	s_nop 0
	v_add_f32_dpp v67, v67, v67 quad_perm:[1,0,3,2] row_mask:0xf bank_mask:0xf bound_ctrl:1
	s_nop 1
	v_add_f32_dpp v67, v67, v67 quad_perm:[2,3,0,1] row_mask:0xf bank_mask:0xf bound_ctrl:1
	s_nop 1
	v_add_f32_dpp v67, v67, v67 row_half_mirror row_mask:0xf bank_mask:0xf bound_ctrl:1
	s_nop 1
	v_mov_b32_dpp v70, v67 row_mirror row_mask:0xf bank_mask:0xf bound_ctrl:1
	s_and_saveexec_b64 s[68:69], s[4:5]
	s_cbranch_execz .LBB0_187
	v_add_f32_e32 v67, v67, v70
	v_lshlrev_b32_e32 v70, 4, v160
	v_ashrrev_i32_e32 v71, 31, v70
	v_lshl_add_u64 v[70:71], v[70:71], 2, v[142:143]
	global_store_dword v[70:71], v67, off offset:3200

; __device__ __forceinline__ unsigned pack2(float a, float b) { return (unsigned)f2bf(a) | ((unsigned)f2bf(b) << 16); }
; template <int EPI, bool HS = false>
; __device__ __forceinline__ void gemm_phase(const Params& p, const GemmCfg& g, char* shm, const int wave_s) {
;     ...
;           for (int j = 0; j < 4; ++j) {
;             float ss = 0.f;
; #pragma unroll
;             for (int bj = 0; bj < 2; ++bj) {
;               float2 xn;
;               xn.x = xv[j][bj].x + gt[bj][0] * acc[ai][bj][m][0][j];
;               xn.y = xv[j][bj].y + gt[bj][1] * acc[ai][bj][m][1][j];
;               const unsigned o = tb + (unsigned)((ai * 128 + m * 16 + j) * 1024 + bj * 128);
;               *(float2*)(xout_t + o) = xn;
;               if (g.has_next) *(unsigned*)(xg_t + o) = pack2(xn.x * gn[bj][0], xn.y * gn[bj][1]);
;               ss += xn.x * xn.x + xn.y * xn.y;
;             }
;             if (g.has_next) {
;               ss = dpp_row_sum16(ss);
;               if (fr == 0) rss_t[(wr * 64 + fq * 4 + ai * 128 + m * 16 + j) * 16] = ss;
;             }
.LBB0_190:
	v_or_b32_e32 v74, 0xcc00, v0
	v_mov_b32_e32 v80, v77
	v_mov_b32_e32 v75, v1
	s_waitcnt lgkmcnt(0)
	v_pk_fma_f32 v[70:71], v[150:151], v[80:81], v[82:83]
	v_lshl_add_u64 v[66:67], v[74:75], 2, s[2:3]
	global_store_dwordx2 v[66:67], v[70:71], off
	s_mov_b64 s[68:69], -1
	s_and_b64 vcc, exec, s[6:7]
	v_or_b32_e32 v66, 0xcc80, v0
	s_cbranch_vccnz .LBB0_194
	v_pk_mul_f32 v[76:77], v[148:149], v[70:71]
	v_lshl_add_u64 v[74:75], v[74:75], 1, s[8:9]
	s_nop 0
	v_and_b32_sdwa v67, v77, v178 dst_sel:DWORD dst_unused:UNUSED_PAD src0_sel:WORD_1 src1_sel:DWORD
	v_cvt_pk_bf16_f32 v68, v76, v76
	v_add3_u32 v67, v77, v67, s81
	v_lshrrev_b32_e32 v68, 16, v68
	v_and_or_b32 v67, v67, s28, v68
	global_store_dword v[74:75], v67, off
	v_mov_b32_e32 v72, v69
	v_mov_b32_e32 v67, v1
	v_pk_fma_f32 v[74:75], v[146:147], v[72:73], v[84:85]
	v_lshl_add_u64 v[76:77], v[66:67], 2, s[2:3]
	global_store_dwordx2 v[76:77], v[74:75], off
	v_pk_mul_f32 v[76:77], v[152:153], v[74:75]
	v_pk_mul_f32 v[70:71], v[70:71], v[70:71]
	s_nop 0
	v_and_b32_sdwa v68, v77, v178 dst_sel:DWORD dst_unused:UNUSED_PAD src0_sel:WORD_1 src1_sel:DWORD
	v_cvt_pk_bf16_f32 v72, v76, v76
	v_add3_u32 v68, v77, v68, s81
	v_lshrrev_b32_e32 v72, 16, v72
	v_and_or_b32 v68, v68, s28, v72
	v_lshl_add_u64 v[76:77], v[66:67], 1, s[8:9]
	v_pk_mul_f32 v[74:75], v[74:75], v[74:75]
	global_store_dword v[76:77], v68, off
	v_add_f32_e32 v67, v74, v75
	v_add_f32_e32 v68, v70, v71
	v_add_f32_e32 v67, v68, v67
	s_nop 1
	v_add_f32_dpp v67, v67, v67 quad_perm:[1,0,3,2] row_mask:0xf bank_mask:0xf bound_ctrl:1
	s_nop 1
	v_add_f32_dpp v67, v67, v67 quad_perm:[2,3,0,1] row_mask:0xf bank_mask:0xf bound_ctrl:1
	s_nop 1
	v_add_f32_dpp v67, v67, v67 row_half_mirror row_mask:0xf bank_mask:0xf bound_ctrl:1
	s_nop 1
	v_mov_b32_dpp v68, v67 row_mirror row_mask:0xf bank_mask:0xf bound_ctrl:1
	s_and_saveexec_b64 s[68:69], s[4:5]
	s_cbranch_execz .LBB0_193
	v_lshlrev_b32_e32 v70, 4, v160
	v_ashrrev_i32_e32 v71, 31, v70
	v_add_f32_e32 v67, v67, v68
	v_lshl_add_u64 v[70:71], v[70:71], 2, v[142:143]
	global_store_dword v[70:71], v67, off offset:3264

; __device__ __forceinline__ unsigned pack2(float a, float b) { return (unsigned)f2bf(a) | ((unsigned)f2bf(b) << 16); }
; #define WAIT_V(n) asm volatile("s_waitcnt vmcnt(" #n ")" ::: "memory")
; template <int EPI, bool HS = false>
; __device__ __forceinline__ void gemm_phase(const Params& p, const GemmCfg& g, char* shm, const int wave_s) {
;     ...
; #pragma unroll
;       for (int ai = 0; ai < 2; ++ai) {
; #pragma unroll
;         for (int i = 0; i < 16; ++i) {
;           const int r = wv_s * 16 + i;
;           glds_row(xin_t + (size_t)(ai * 128 + r) * 1024, (unsigned)lane * 16u, ldsb + (unsigned)(r * XROW));
;         }
;         WAIT_V(0);
;         __syncthreads();
; #pragma unroll
;         for (int m = 0; m < 4; ++m) {
;           float2 xv[4][2];
; #pragma unroll
;           for (int j = 0; j < 4; ++j)
; #pragma unroll
;             for (int bj = 0; bj < 2; ++bj) xv[j][bj] = *(const float2*)(xl + (m * 16 + j) * XROW + bj * 512);
; #pragma unroll
;           for (int j = 0; j < 4; ++j) {
;             float ss = 0.f;
; #pragma unroll
;             for (int bj = 0; bj < 2; ++bj) {
;               float2 xn;
;               xn.x = xv[j][bj].x + gt[bj][0] * acc[ai][bj][m][0][j];
;               xn.y = xv[j][bj].y + gt[bj][1] * acc[ai][bj][m][1][j];
;               const unsigned o = tb + (unsigned)((ai * 128 + m * 16 + j) * 1024 + bj * 128);
;               *(float2*)(xout_t + o) = xn;
;               if (g.has_next) *(unsigned*)(xg_t + o) = pack2(xn.x * gn[bj][0], xn.y * gn[bj][1]);
;               ss += xn.x * xn.x + xn.y * xn.y;
;             }
;             if (g.has_next) {
;               ss = dpp_row_sum16(ss);
;               if (fr == 0) rss_t[(wr * 64 + fq * 4 + ai * 128 + m * 16 + j) * 16] = ss;
;             }
.LBB0_196:
	s_lshl_b64 s[10:11], s[10:11], 12
	s_add_u32 s26, s71, s10
	s_addc_u32 s27, s75, s11
	s_add_u32 s10, s26, 0x80000
	s_addc_u32 s11, s27, 0
	s_waitcnt vmcnt(63) expcnt(7) lgkmcnt(15)
	s_barrier
	s_mov_b32 m0, s70
	s_nop 0
	global_load_lds_dwordx4 v164, s[10:11]
	s_add_u32 s10, s26, 0x81000
	s_addc_u32 s11, s27, 0
	s_mov_b32 m0, s76
	s_nop 0
	global_load_lds_dwordx4 v164, s[10:11]
	s_add_u32 s10, s26, 0x82000
	s_addc_u32 s11, s27, 0
	s_mov_b32 m0, s12
	s_nop 0
	global_load_lds_dwordx4 v164, s[10:11]
	s_add_u32 s10, s26, 0x83000
	s_addc_u32 s11, s27, 0
	s_mov_b32 m0, s13
	s_nop 0
	global_load_lds_dwordx4 v164, s[10:11]
	s_add_u32 s10, s26, 0x84000
	s_addc_u32 s11, s27, 0
	s_mov_b32 m0, s14
	s_nop 0
	global_load_lds_dwordx4 v164, s[10:11]
	s_add_u32 s10, s26, 0x85000
	s_addc_u32 s11, s27, 0
	s_mov_b32 m0, s15
	s_nop 0
	global_load_lds_dwordx4 v164, s[10:11]
	s_add_u32 s10, s26, 0x86000
	s_addc_u32 s11, s27, 0
	s_mov_b32 m0, s16
	s_nop 0
	global_load_lds_dwordx4 v164, s[10:11]
	s_add_u32 s10, s26, 0x87000
	s_addc_u32 s11, s27, 0
	s_mov_b32 m0, s17
	s_nop 0
	global_load_lds_dwordx4 v164, s[10:11]
	s_add_u32 s10, s26, 0x88000
	s_addc_u32 s11, s27, 0
	s_mov_b32 m0, s18
	s_nop 0
	global_load_lds_dwordx4 v164, s[10:11]
	s_add_u32 s10, s26, 0x89000
	s_addc_u32 s11, s27, 0
	s_mov_b32 m0, s19
	s_nop 0
	global_load_lds_dwordx4 v164, s[10:11]
	s_add_u32 s10, s26, 0x8a000
	s_addc_u32 s11, s27, 0
	s_mov_b32 m0, s20
	s_nop 0
	global_load_lds_dwordx4 v164, s[10:11]
	s_add_u32 s10, s26, 0x8b000
	s_addc_u32 s11, s27, 0
	s_mov_b32 m0, s21
	s_nop 0
	global_load_lds_dwordx4 v164, s[10:11]
	s_add_u32 s10, s26, 0x8c000
	s_addc_u32 s11, s27, 0
	s_mov_b32 m0, s22
	s_nop 0
	global_load_lds_dwordx4 v164, s[10:11]
	s_add_u32 s10, s26, 0x8d000
	s_addc_u32 s11, s27, 0
	s_mov_b32 m0, s23
	s_nop 0
	global_load_lds_dwordx4 v164, s[10:11]
	s_add_u32 s10, s26, 0x8e000
	s_addc_u32 s11, s27, 0
	s_mov_b32 m0, s24
	s_nop 0
	global_load_lds_dwordx4 v164, s[10:11]
	s_add_u32 s10, s26, 0x8f000
	s_addc_u32 s11, s27, 0
	s_mov_b32 m0, s25
	s_nop 0
	global_load_lds_dwordx4 v164, s[10:11]
	s_waitcnt vmcnt(0)
	s_barrier
	ds_read2st64_b64 v[78:81], v161 offset1:1
	ds_read2_b64 v[74:77], v161 offset0:130 offset1:194
	ds_read2st64_b64 v[70:73], v162 offset0:4 offset1:5
	ds_read2st64_b64 v[66:69], v163 offset0:6 offset1:7
	v_add_u32_e32 v84, 0x20000, v0
	v_mov_b32_e32 v82, v58
	v_mov_b32_e32 v83, v62
	v_mov_b32_e32 v85, v1
	s_waitcnt lgkmcnt(3)
	v_pk_fma_f32 v[82:83], v[150:151], v[82:83], v[78:79]
	v_lshl_add_u64 v[78:79], v[84:85], 2, s[2:3]
	global_store_dwordx2 v[78:79], v[82:83], off
	s_mov_b64 s[10:11], -1
	s_and_b64 vcc, exec, s[6:7]
	v_add_u32_e32 v78, 0x20080, v0
	s_cbranch_vccnz .LBB0_200
	v_pk_mul_f32 v[86:87], v[148:149], v[82:83]
	v_lshl_add_u64 v[84:85], v[84:85], 1, s[8:9]
	s_nop 0
	v_and_b32_sdwa v58, v87, v178 dst_sel:DWORD dst_unused:UNUSED_PAD src0_sel:WORD_1 src1_sel:DWORD
	v_cvt_pk_bf16_f32 v62, v86, v86
	v_add3_u32 v58, v87, v58, s81
	v_lshrrev_b32_e32 v62, 16, v62
	v_and_or_b32 v58, v58, s28, v62
	global_store_dword v[84:85], v58, off
	v_mov_b32_e32 v84, v50
	v_mov_b32_e32 v85, v54
	v_mov_b32_e32 v79, v1
	v_pk_fma_f32 v[84:85], v[146:147], v[84:85], v[80:81]
	v_lshl_add_u64 v[86:87], v[78:79], 2, s[2:3]
	global_store_dwordx2 v[86:87], v[84:85], off
	v_pk_mul_f32 v[86:87], v[152:153], v[84:85]
	v_pk_mul_f32 v[82:83], v[82:83], v[82:83]
	s_nop 0
	v_and_b32_sdwa v58, v87, v178 dst_sel:DWORD dst_unused:UNUSED_PAD src0_sel:WORD_1 src1_sel:DWORD
	v_cvt_pk_bf16_f32 v62, v86, v86
	v_add3_u32 v58, v87, v58, s81
	v_lshrrev_b32_e32 v62, 16, v62
	v_and_or_b32 v58, v58, s28, v62
	v_lshl_add_u64 v[86:87], v[78:79], 1, s[8:9]
	v_pk_mul_f32 v[84:85], v[84:85], v[84:85]
	global_store_dword v[86:87], v58, off
	v_add_f32_e32 v58, v84, v85
	v_add_f32_e32 v62, v82, v83
	v_add_f32_e32 v58, v62, v58
	s_nop 1
	v_add_f32_dpp v58, v58, v58 quad_perm:[1,0,3,2] row_mask:0xf bank_mask:0xf bound_ctrl:1
	s_nop 1
	v_add_f32_dpp v58, v58, v58 quad_perm:[2,3,0,1] row_mask:0xf bank_mask:0xf bound_ctrl:1
	s_nop 1
	v_add_f32_dpp v58, v58, v58 row_half_mirror row_mask:0xf bank_mask:0xf bound_ctrl:1
	s_nop 1
	v_mov_b32_dpp v62, v58 row_mirror row_mask:0xf bank_mask:0xf bound_ctrl:1
	s_and_saveexec_b64 s[10:11], s[4:5]
	s_cbranch_execz .LBB0_199
	v_add_f32_e32 v58, v58, v62
	v_mov_b32_e32 v62, 0x800
	v_lshl_add_u32 v82, v160, 4, v62
	v_ashrrev_i32_e32 v83, 31, v82
	v_lshl_add_u64 v[82:83], v[82:83], 2, v[142:143]
	global_store_dword v[82:83], v58, off

; __device__ __forceinline__ unsigned pack2(float a, float b) { return (unsigned)f2bf(a) | ((unsigned)f2bf(b) << 16); }
; template <int EPI, bool HS = false>
; __device__ __forceinline__ void gemm_phase(const Params& p, const GemmCfg& g, char* shm, const int wave_s) {
;     ...
;           for (int j = 0; j < 4; ++j) {
;             float ss = 0.f;
; #pragma unroll
;             for (int bj = 0; bj < 2; ++bj) {
;               float2 xn;
;               xn.x = xv[j][bj].x + gt[bj][0] * acc[ai][bj][m][0][j];
;               xn.y = xv[j][bj].y + gt[bj][1] * acc[ai][bj][m][1][j];
;               const unsigned o = tb + (unsigned)((ai * 128 + m * 16 + j) * 1024 + bj * 128);
;               *(float2*)(xout_t + o) = xn;
;               if (g.has_next) *(unsigned*)(xg_t + o) = pack2(xn.x * gn[bj][0], xn.y * gn[bj][1]);
;               ss += xn.x * xn.x + xn.y * xn.y;
;             }
;             if (g.has_next) {
;               ss = dpp_row_sum16(ss);
;               if (fr == 0) rss_t[(wr * 64 + fq * 4 + ai * 128 + m * 16 + j) * 16] = ss;
;             }
.LBB0_202:
	v_add_u32_e32 v78, 0x20400, v0
	v_mov_b32_e32 v62, v59
	v_mov_b32_e32 v79, v1
	s_waitcnt lgkmcnt(2)
	v_pk_fma_f32 v[62:63], v[150:151], v[62:63], v[74:75]
	v_lshl_add_u64 v[58:59], v[78:79], 2, s[2:3]
	global_store_dwordx2 v[58:59], v[62:63], off
	s_mov_b64 s[10:11], -1
	s_and_b64 vcc, exec, s[6:7]
	v_add_u32_e32 v58, 0x20480, v0
	s_cbranch_vccnz .LBB0_206
	v_pk_mul_f32 v[74:75], v[148:149], v[62:63]
	v_mov_b32_e32 v59, v1
	s_nop 0
	v_and_b32_sdwa v50, v75, v178 dst_sel:DWORD dst_unused:UNUSED_PAD src0_sel:WORD_1 src1_sel:DWORD
	v_cvt_pk_bf16_f32 v54, v74, v74
	v_add3_u32 v50, v75, v50, s81
	v_lshrrev_b32_e32 v54, 16, v54
	v_and_or_b32 v50, v50, s28, v54
	v_lshl_add_u64 v[74:75], v[78:79], 1, s[8:9]
	v_mov_b32_e32 v54, v51
	global_store_dword v[74:75], v50, off
	v_pk_fma_f32 v[74:75], v[146:147], v[54:55], v[76:77]
	v_lshl_add_u64 v[78:79], v[58:59], 2, s[2:3]
	global_store_dwordx2 v[78:79], v[74:75], off
	v_pk_mul_f32 v[78:79], v[152:153], v[74:75]
	v_pk_mul_f32 v[62:63], v[62:63], v[62:63]
	s_nop 0
	v_and_b32_sdwa v50, v79, v178 dst_sel:DWORD dst_unused:UNUSED_PAD src0_sel:WORD_1 src1_sel:DWORD
	v_cvt_pk_bf16_f32 v54, v78, v78
	v_add3_u32 v50, v79, v50, s81
	v_lshrrev_b32_e32 v54, 16, v54
	v_and_or_b32 v50, v50, s28, v54
	v_lshl_add_u64 v[78:79], v[58:59], 1, s[8:9]
	v_pk_mul_f32 v[74:75], v[74:75], v[74:75]
	global_store_dword v[78:79], v50, off
	v_add_f32_e32 v50, v74, v75
	v_add_f32_e32 v54, v62, v63
	v_add_f32_e32 v50, v54, v50
	s_nop 1
	v_add_f32_dpp v50, v50, v50 quad_perm:[1,0,3,2] row_mask:0xf bank_mask:0xf bound_ctrl:1
	s_nop 1
	v_add_f32_dpp v50, v50, v50 quad_perm:[2,3,0,1] row_mask:0xf bank_mask:0xf bound_ctrl:1
	s_nop 1
	v_add_f32_dpp v50, v50, v50 row_half_mirror row_mask:0xf bank_mask:0xf bound_ctrl:1
	s_nop 1
	v_mov_b32_dpp v54, v50 row_mirror row_mask:0xf bank_mask:0xf bound_ctrl:1
	s_and_saveexec_b64 s[10:11], s[4:5]
	s_cbranch_execz .LBB0_205
	v_add_f32_e32 v50, v50, v54
	v_mov_b32_e32 v54, 0x810
	v_lshl_add_u32 v62, v160, 4, v54
	v_ashrrev_i32_e32 v63, 31, v62
	v_lshl_add_u64 v[62:63], v[62:63], 2, v[142:143]
	global_store_dword v[62:63], v50, off

; __device__ __forceinline__ unsigned pack2(float a, float b) { return (unsigned)f2bf(a) | ((unsigned)f2bf(b) << 16); }
; template <int EPI, bool HS = false>
; __device__ __forceinline__ void gemm_phase(const Params& p, const GemmCfg& g, char* shm, const int wave_s) {
;     ...
;           for (int j = 0; j < 4; ++j) {
;             float ss = 0.f;
; #pragma unroll
;             for (int bj = 0; bj < 2; ++bj) {
;               float2 xn;
;               xn.x = xv[j][bj].x + gt[bj][0] * acc[ai][bj][m][0][j];
;               xn.y = xv[j][bj].y + gt[bj][1] * acc[ai][bj][m][1][j];
;               const unsigned o = tb + (unsigned)((ai * 128 + m * 16 + j) * 1024 + bj * 128);
;               *(float2*)(xout_t + o) = xn;
;               if (g.has_next) *(unsigned*)(xg_t + o) = pack2(xn.x * gn[bj][0], xn.y * gn[bj][1]);
;               ss += xn.x * xn.x + xn.y * xn.y;
;             }
;             if (g.has_next) {
;               ss = dpp_row_sum16(ss);
;               if (fr == 0) rss_t[(wr * 64 + fq * 4 + ai * 128 + m * 16 + j) * 16] = ss;
;             }
.LBB0_208:
	v_add_u32_e32 v58, 0x20800, v0
	v_mov_b32_e32 v50, v60
	v_mov_b32_e32 v51, v64
	v_mov_b32_e32 v59, v1
	s_waitcnt lgkmcnt(1)
	v_pk_fma_f32 v[54:55], v[150:151], v[50:51], v[70:71]
	v_lshl_add_u64 v[50:51], v[58:59], 2, s[2:3]
	global_store_dwordx2 v[50:51], v[54:55], off
	s_mov_b64 s[10:11], -1
	s_and_b64 vcc, exec, s[6:7]
	v_add_u32_e32 v50, 0x20880, v0
	s_cbranch_vccnz .LBB0_212
	v_pk_mul_f32 v[62:63], v[148:149], v[54:55]
	v_lshl_add_u64 v[58:59], v[58:59], 1, s[8:9]
	s_nop 0
	v_and_b32_sdwa v51, v63, v178 dst_sel:DWORD dst_unused:UNUSED_PAD src0_sel:WORD_1 src1_sel:DWORD
	v_cvt_pk_bf16_f32 v60, v62, v62
	v_add3_u32 v51, v63, v51, s81
	v_lshrrev_b32_e32 v60, 16, v60
	v_and_or_b32 v51, v51, s28, v60
	global_store_dword v[58:59], v51, off
	v_mov_b32_e32 v58, v52
	v_mov_b32_e32 v59, v56
	v_mov_b32_e32 v51, v1
	v_pk_fma_f32 v[58:59], v[146:147], v[58:59], v[72:73]
	v_lshl_add_u64 v[62:63], v[50:51], 2, s[2:3]
	global_store_dwordx2 v[62:63], v[58:59], off
	v_pk_mul_f32 v[62:63], v[152:153], v[58:59]
	v_pk_mul_f32 v[54:55], v[54:55], v[54:55]
	v_and_b32_sdwa v64, v62, v178 dst_sel:DWORD dst_unused:UNUSED_PAD src0_sel:WORD_1 src1_sel:DWORD
	v_and_b32_sdwa v60, v63, v178 dst_sel:DWORD dst_unused:UNUSED_PAD src0_sel:WORD_1 src1_sel:DWORD
	v_add3_u32 v62, v62, v64, s81
	v_add3_u32 v60, v63, v60, s81
	v_lshrrev_b32_e32 v62, 16, v62
	v_pk_mul_f32 v[58:59], v[58:59], v[58:59]
	v_and_or_b32 v60, v60, s28, v62
	v_lshl_add_u64 v[62:63], v[50:51], 1, s[8:9]
	v_add_f32_e32 v51, v58, v59
	v_add_f32_e32 v54, v54, v55
	v_add_f32_e32 v51, v54, v51
	global_store_dword v[62:63], v60, off
	s_nop 0
	v_add_f32_dpp v51, v51, v51 quad_perm:[1,0,3,2] row_mask:0xf bank_mask:0xf bound_ctrl:1
	s_nop 1
	v_add_f32_dpp v51, v51, v51 quad_perm:[2,3,0,1] row_mask:0xf bank_mask:0xf bound_ctrl:1
	s_nop 1
	v_add_f32_dpp v51, v51, v51 row_half_mirror row_mask:0xf bank_mask:0xf bound_ctrl:1
	s_nop 1
	v_mov_b32_dpp v54, v51 row_mirror row_mask:0xf bank_mask:0xf bound_ctrl:1
	s_and_saveexec_b64 s[10:11], s[4:5]
	s_cbranch_execz .LBB0_211
	v_add_f32_e32 v51, v51, v54
	v_mov_b32_e32 v54, 0x820
	v_lshl_add_u32 v54, v160, 4, v54
	v_ashrrev_i32_e32 v55, 31, v54
	v_lshl_add_u64 v[54:55], v[54:55], 2, v[142:143]
	global_store_dword v[54:55], v51, off

; __device__ __forceinline__ unsigned pack2(float a, float b) { return (unsigned)f2bf(a) | ((unsigned)f2bf(b) << 16); }
; template <int EPI, bool HS = false>
; __device__ __forceinline__ void gemm_phase(const Params& p, const GemmCfg& g, char* shm, const int wave_s) {
;     ...
;           for (int j = 0; j < 4; ++j) {
;             float ss = 0.f;
; #pragma unroll
;             for (int bj = 0; bj < 2; ++bj) {
;               float2 xn;
;               xn.x = xv[j][bj].x + gt[bj][0] * acc[ai][bj][m][0][j];
;               xn.y = xv[j][bj].y + gt[bj][1] * acc[ai][bj][m][1][j];
;               const unsigned o = tb + (unsigned)((ai * 128 + m * 16 + j) * 1024 + bj * 128);
;               *(float2*)(xout_t + o) = xn;
;               if (g.has_next) *(unsigned*)(xg_t + o) = pack2(xn.x * gn[bj][0], xn.y * gn[bj][1]);
;               ss += xn.x * xn.x + xn.y * xn.y;
;             }
;             if (g.has_next) {
;               ss = dpp_row_sum16(ss);
;               if (fr == 0) rss_t[(wr * 64 + fq * 4 + ai * 128 + m * 16 + j) * 16] = ss;
;             }
.LBB0_214:
	v_add_u32_e32 v58, 0x20c00, v0
	v_mov_b32_e32 v64, v61
	v_mov_b32_e32 v59, v1
	s_waitcnt lgkmcnt(0)
	v_pk_fma_f32 v[54:55], v[150:151], v[64:65], v[66:67]
	v_lshl_add_u64 v[50:51], v[58:59], 2, s[2:3]
	global_store_dwordx2 v[50:51], v[54:55], off
	s_mov_b64 s[10:11], -1
	s_and_b64 vcc, exec, s[6:7]
	v_add_u32_e32 v50, 0x20c80, v0
	s_cbranch_vccnz .LBB0_218
	v_pk_mul_f32 v[60:61], v[148:149], v[54:55]
	v_lshl_add_u64 v[58:59], v[58:59], 1, s[8:9]
	s_nop 0
	v_and_b32_sdwa v51, v61, v178 dst_sel:DWORD dst_unused:UNUSED_PAD src0_sel:WORD_1 src1_sel:DWORD
	v_cvt_pk_bf16_f32 v52, v60, v60
	v_add3_u32 v51, v61, v51, s81
	v_lshrrev_b32_e32 v52, 16, v52
	v_and_or_b32 v51, v51, s28, v52
	global_store_dword v[58:59], v51, off
	v_mov_b32_e32 v56, v53
	v_mov_b32_e32 v51, v1
	v_pk_fma_f32 v[58:59], v[146:147], v[56:57], v[68:69]
	v_lshl_add_u64 v[60:61], v[50:51], 2, s[2:3]
	global_store_dwordx2 v[60:61], v[58:59], off
	v_pk_mul_f32 v[60:61], v[152:153], v[58:59]
	v_pk_mul_f32 v[54:55], v[54:55], v[54:55]
	s_nop 0
	v_and_b32_sdwa v52, v61, v178 dst_sel:DWORD dst_unused:UNUSED_PAD src0_sel:WORD_1 src1_sel:DWORD
	v_cvt_pk_bf16_f32 v56, v60, v60
	v_add3_u32 v52, v61, v52, s81
	v_lshrrev_b32_e32 v56, 16, v56
	v_and_or_b32 v52, v52, s28, v56
	v_lshl_add_u64 v[60:61], v[50:51], 1, s[8:9]
	v_pk_mul_f32 v[58:59], v[58:59], v[58:59]
	global_store_dword v[60:61], v52, off
	v_add_f32_e32 v51, v58, v59
	v_add_f32_e32 v52, v54, v55
	v_add_f32_e32 v51, v52, v51
	s_nop 1
	v_add_f32_dpp v51, v51, v51 quad_perm:[1,0,3,2] row_mask:0xf bank_mask:0xf bound_ctrl:1
	s_nop 1
	v_add_f32_dpp v51, v51, v51 quad_perm:[2,3,0,1] row_mask:0xf bank_mask:0xf bound_ctrl:1
	s_nop 1
	v_add_f32_dpp v51, v51, v51 row_half_mirror row_mask:0xf bank_mask:0xf bound_ctrl:1
	s_nop 1
	v_mov_b32_dpp v52, v51 row_mirror row_mask:0xf bank_mask:0xf bound_ctrl:1
	s_and_saveexec_b64 s[10:11], s[4:5]
	s_cbranch_execz .LBB0_217
	v_add_f32_e32 v51, v51, v52
	v_mov_b32_e32 v52, 0x830
	v_lshl_add_u32 v54, v160, 4, v52
	v_ashrrev_i32_e32 v55, 31, v54
	v_lshl_add_u64 v[54:55], v[54:55], 2, v[142:143]
	global_store_dword v[54:55], v51, off

; __device__ __forceinline__ unsigned pack2(float a, float b) { return (unsigned)f2bf(a) | ((unsigned)f2bf(b) << 16); }
; template <int EPI, bool HS = false>
; __device__ __forceinline__ void gemm_phase(const Params& p, const GemmCfg& g, char* shm, const int wave_s) {
;     ...
; #pragma unroll
;         for (int m = 0; m < 4; ++m) {
;           float2 xv[4][2];
; #pragma unroll
;           for (int j = 0; j < 4; ++j)
; #pragma unroll
;             for (int bj = 0; bj < 2; ++bj) xv[j][bj] = *(const float2*)(xl + (m * 16 + j) * XROW + bj * 512);
; #pragma unroll
;           for (int j = 0; j < 4; ++j) {
;             float ss = 0.f;
; #pragma unroll
;             for (int bj = 0; bj < 2; ++bj) {
;               float2 xn;
;               xn.x = xv[j][bj].x + gt[bj][0] * acc[ai][bj][m][0][j];
;               xn.y = xv[j][bj].y + gt[bj][1] * acc[ai][bj][m][1][j];
;               const unsigned o = tb + (unsigned)((ai * 128 + m * 16 + j) * 1024 + bj * 128);
;               *(float2*)(xout_t + o) = xn;
;               if (g.has_next) *(unsigned*)(xg_t + o) = pack2(xn.x * gn[bj][0], xn.y * gn[bj][1]);
;               ss += xn.x * xn.x + xn.y * xn.y;
;             }
;             if (g.has_next) {
;               ss = dpp_row_sum16(ss);
;               if (fr == 0) rss_t[(wr * 64 + fq * 4 + ai * 128 + m * 16 + j) * 16] = ss;
;             }
.LBB0_220:
	ds_read2st64_b64 v[62:65], v134 offset0:32 offset1:33
	ds_read2st64_b64 v[58:61], v135 offset0:34 offset1:35
	ds_read2st64_b64 v[54:57], v136 offset0:36 offset1:37
	ds_read2st64_b64 v[50:53], v137 offset0:38 offset1:39
	v_add_u32_e32 v68, 0x24000, v0
	v_mov_b32_e32 v66, v42
	v_mov_b32_e32 v67, v46
	v_mov_b32_e32 v69, v1
	s_waitcnt lgkmcnt(3)
	v_pk_fma_f32 v[66:67], v[150:151], v[66:67], v[62:63]
	v_lshl_add_u64 v[62:63], v[68:69], 2, s[2:3]
	global_store_dwordx2 v[62:63], v[66:67], off
	s_mov_b64 s[10:11], -1
	s_and_b64 vcc, exec, s[6:7]
	v_add_u32_e32 v62, 0x24080, v0
	s_cbranch_vccnz .LBB0_224
	v_pk_mul_f32 v[70:71], v[148:149], v[66:67]
	v_lshl_add_u64 v[68:69], v[68:69], 1, s[8:9]
	s_nop 0
	v_and_b32_sdwa v42, v71, v178 dst_sel:DWORD dst_unused:UNUSED_PAD src0_sel:WORD_1 src1_sel:DWORD
	v_cvt_pk_bf16_f32 v46, v70, v70
	v_add3_u32 v42, v71, v42, s81
	v_lshrrev_b32_e32 v46, 16, v46
	v_and_or_b32 v42, v42, s28, v46
	global_store_dword v[68:69], v42, off
	v_mov_b32_e32 v68, v34
	v_mov_b32_e32 v69, v38
	v_mov_b32_e32 v63, v1
	v_pk_fma_f32 v[68:69], v[146:147], v[68:69], v[64:65]
	v_lshl_add_u64 v[70:71], v[62:63], 2, s[2:3]
	global_store_dwordx2 v[70:71], v[68:69], off
	v_pk_mul_f32 v[70:71], v[152:153], v[68:69]
	v_pk_mul_f32 v[66:67], v[66:67], v[66:67]
	s_nop 0
	v_and_b32_sdwa v42, v71, v178 dst_sel:DWORD dst_unused:UNUSED_PAD src0_sel:WORD_1 src1_sel:DWORD
	v_cvt_pk_bf16_f32 v46, v70, v70
	v_add3_u32 v42, v71, v42, s81
	v_lshrrev_b32_e32 v46, 16, v46
	v_and_or_b32 v42, v42, s28, v46
	v_lshl_add_u64 v[70:71], v[62:63], 1, s[8:9]
	v_pk_mul_f32 v[68:69], v[68:69], v[68:69]
	global_store_dword v[70:71], v42, off
	v_add_f32_e32 v42, v68, v69
	v_add_f32_e32 v46, v66, v67
	v_add_f32_e32 v42, v46, v42
	s_nop 1
	v_add_f32_dpp v42, v42, v42 quad_perm:[1,0,3,2] row_mask:0xf bank_mask:0xf bound_ctrl:1
	s_nop 1
	v_add_f32_dpp v42, v42, v42 quad_perm:[2,3,0,1] row_mask:0xf bank_mask:0xf bound_ctrl:1
	s_nop 1
	v_add_f32_dpp v42, v42, v42 row_half_mirror row_mask:0xf bank_mask:0xf bound_ctrl:1
	s_nop 1
	v_mov_b32_dpp v46, v42 row_mirror row_mask:0xf bank_mask:0xf bound_ctrl:1
	s_and_saveexec_b64 s[10:11], s[4:5]
	s_cbranch_execz .LBB0_223
	v_add_f32_e32 v42, v42, v46
	v_mov_b32_e32 v46, 0x900
	v_lshl_add_u32 v66, v160, 4, v46
	v_ashrrev_i32_e32 v67, 31, v66
	v_lshl_add_u64 v[66:67], v[66:67], 2, v[142:143]
	global_store_dword v[66:67], v42, off

; __device__ __forceinline__ unsigned pack2(float a, float b) { return (unsigned)f2bf(a) | ((unsigned)f2bf(b) << 16); }
; template <int EPI, bool HS = false>
; __device__ __forceinline__ void gemm_phase(const Params& p, const GemmCfg& g, char* shm, const int wave_s) {
;     ...
;           for (int j = 0; j < 4; ++j) {
;             float ss = 0.f;
; #pragma unroll
;             for (int bj = 0; bj < 2; ++bj) {
;               float2 xn;
;               xn.x = xv[j][bj].x + gt[bj][0] * acc[ai][bj][m][0][j];
;               xn.y = xv[j][bj].y + gt[bj][1] * acc[ai][bj][m][1][j];
;               const unsigned o = tb + (unsigned)((ai * 128 + m * 16 + j) * 1024 + bj * 128);
;               *(float2*)(xout_t + o) = xn;
;               if (g.has_next) *(unsigned*)(xg_t + o) = pack2(xn.x * gn[bj][0], xn.y * gn[bj][1]);
;               ss += xn.x * xn.x + xn.y * xn.y;
;             }
;             if (g.has_next) {
;               ss = dpp_row_sum16(ss);
;               if (fr == 0) rss_t[(wr * 64 + fq * 4 + ai * 128 + m * 16 + j) * 16] = ss;
;             }
.LBB0_226:
	v_add_u32_e32 v62, 0x24400, v0
	v_mov_b32_e32 v46, v43
	v_mov_b32_e32 v63, v1
	s_waitcnt lgkmcnt(2)
	v_pk_fma_f32 v[46:47], v[150:151], v[46:47], v[58:59]
	v_lshl_add_u64 v[42:43], v[62:63], 2, s[2:3]
	global_store_dwordx2 v[42:43], v[46:47], off
	s_mov_b64 s[10:11], -1
	s_and_b64 vcc, exec, s[6:7]
	v_add_u32_e32 v42, 0x24480, v0
	s_cbranch_vccnz .LBB0_230
	v_pk_mul_f32 v[58:59], v[148:149], v[46:47]
	v_mov_b32_e32 v43, v1
	s_nop 0
	v_and_b32_sdwa v34, v59, v178 dst_sel:DWORD dst_unused:UNUSED_PAD src0_sel:WORD_1 src1_sel:DWORD
	v_cvt_pk_bf16_f32 v38, v58, v58
	v_add3_u32 v34, v59, v34, s81
	v_lshrrev_b32_e32 v38, 16, v38
	v_and_or_b32 v34, v34, s28, v38
	v_lshl_add_u64 v[58:59], v[62:63], 1, s[8:9]
	v_mov_b32_e32 v38, v35
	global_store_dword v[58:59], v34, off
	v_pk_fma_f32 v[58:59], v[146:147], v[38:39], v[60:61]
	v_lshl_add_u64 v[62:63], v[42:43], 2, s[2:3]
	global_store_dwordx2 v[62:63], v[58:59], off
	v_pk_mul_f32 v[62:63], v[152:153], v[58:59]
	v_pk_mul_f32 v[46:47], v[46:47], v[46:47]
	s_nop 0
	v_and_b32_sdwa v34, v63, v178 dst_sel:DWORD dst_unused:UNUSED_PAD src0_sel:WORD_1 src1_sel:DWORD
	v_cvt_pk_bf16_f32 v38, v62, v62
	v_add3_u32 v34, v63, v34, s81
	v_lshrrev_b32_e32 v38, 16, v38
	v_and_or_b32 v34, v34, s28, v38
	v_lshl_add_u64 v[62:63], v[42:43], 1, s[8:9]
	v_pk_mul_f32 v[58:59], v[58:59], v[58:59]
	global_store_dword v[62:63], v34, off
	v_add_f32_e32 v34, v58, v59
	v_add_f32_e32 v38, v46, v47
	v_add_f32_e32 v34, v38, v34
	s_nop 1
	v_add_f32_dpp v34, v34, v34 quad_perm:[1,0,3,2] row_mask:0xf bank_mask:0xf bound_ctrl:1
	s_nop 1
	v_add_f32_dpp v34, v34, v34 quad_perm:[2,3,0,1] row_mask:0xf bank_mask:0xf bound_ctrl:1
	s_nop 1
	v_add_f32_dpp v34, v34, v34 row_half_mirror row_mask:0xf bank_mask:0xf bound_ctrl:1
	s_nop 1
	v_mov_b32_dpp v38, v34 row_mirror row_mask:0xf bank_mask:0xf bound_ctrl:1
	s_and_saveexec_b64 s[10:11], s[4:5]
	s_cbranch_execz .LBB0_229
	v_add_f32_e32 v34, v34, v38
	v_mov_b32_e32 v38, 0x910
	v_lshl_add_u32 v46, v160, 4, v38
	v_ashrrev_i32_e32 v47, 31, v46
	v_lshl_add_u64 v[46:47], v[46:47], 2, v[142:143]
	global_store_dword v[46:47], v34, off

; __device__ __forceinline__ unsigned pack2(float a, float b) { return (unsigned)f2bf(a) | ((unsigned)f2bf(b) << 16); }
; template <int EPI, bool HS = false>
; __device__ __forceinline__ void gemm_phase(const Params& p, const GemmCfg& g, char* shm, const int wave_s) {
;     ...
;           for (int j = 0; j < 4; ++j) {
;             float ss = 0.f;
; #pragma unroll
;             for (int bj = 0; bj < 2; ++bj) {
;               float2 xn;
;               xn.x = xv[j][bj].x + gt[bj][0] * acc[ai][bj][m][0][j];
;               xn.y = xv[j][bj].y + gt[bj][1] * acc[ai][bj][m][1][j];
;               const unsigned o = tb + (unsigned)((ai * 128 + m * 16 + j) * 1024 + bj * 128);
;               *(float2*)(xout_t + o) = xn;
;               if (g.has_next) *(unsigned*)(xg_t + o) = pack2(xn.x * gn[bj][0], xn.y * gn[bj][1]);
;               ss += xn.x * xn.x + xn.y * xn.y;
;             }
;             if (g.has_next) {
;               ss = dpp_row_sum16(ss);
;               if (fr == 0) rss_t[(wr * 64 + fq * 4 + ai * 128 + m * 16 + j) * 16] = ss;
;             }
.LBB0_232:
	v_add_u32_e32 v42, 0x24800, v0
	v_mov_b32_e32 v34, v44
	v_mov_b32_e32 v35, v48
	v_mov_b32_e32 v43, v1
	s_waitcnt lgkmcnt(1)
	v_pk_fma_f32 v[38:39], v[150:151], v[34:35], v[54:55]
	v_lshl_add_u64 v[34:35], v[42:43], 2, s[2:3]
	global_store_dwordx2 v[34:35], v[38:39], off
	s_mov_b64 s[10:11], -1
	s_and_b64 vcc, exec, s[6:7]
	v_add_u32_e32 v34, 0x24880, v0
	s_cbranch_vccnz .LBB0_236
	v_pk_mul_f32 v[46:47], v[148:149], v[38:39]
	v_lshl_add_u64 v[42:43], v[42:43], 1, s[8:9]
	s_nop 0
	v_and_b32_sdwa v35, v47, v178 dst_sel:DWORD dst_unused:UNUSED_PAD src0_sel:WORD_1 src1_sel:DWORD
	v_cvt_pk_bf16_f32 v44, v46, v46
	v_add3_u32 v35, v47, v35, s81
	v_lshrrev_b32_e32 v44, 16, v44
	v_and_or_b32 v35, v35, s28, v44
	global_store_dword v[42:43], v35, off
	v_mov_b32_e32 v42, v36
	v_mov_b32_e32 v43, v40
	v_mov_b32_e32 v35, v1
	v_pk_fma_f32 v[42:43], v[146:147], v[42:43], v[56:57]
	v_lshl_add_u64 v[46:47], v[34:35], 2, s[2:3]
	global_store_dwordx2 v[46:47], v[42:43], off
	v_pk_mul_f32 v[46:47], v[152:153], v[42:43]
	v_pk_mul_f32 v[38:39], v[38:39], v[38:39]
	v_and_b32_sdwa v48, v46, v178 dst_sel:DWORD dst_unused:UNUSED_PAD src0_sel:WORD_1 src1_sel:DWORD
	v_and_b32_sdwa v44, v47, v178 dst_sel:DWORD dst_unused:UNUSED_PAD src0_sel:WORD_1 src1_sel:DWORD
	v_add3_u32 v46, v46, v48, s81
	v_add3_u32 v44, v47, v44, s81
	v_lshrrev_b32_e32 v46, 16, v46
	v_pk_mul_f32 v[42:43], v[42:43], v[42:43]
	v_and_or_b32 v44, v44, s28, v46
	v_lshl_add_u64 v[46:47], v[34:35], 1, s[8:9]
	v_add_f32_e32 v35, v42, v43
	v_add_f32_e32 v38, v38, v39
	v_add_f32_e32 v35, v38, v35
	global_store_dword v[46:47], v44, off
	s_nop 0
	v_add_f32_dpp v35, v35, v35 quad_perm:[1,0,3,2] row_mask:0xf bank_mask:0xf bound_ctrl:1
	s_nop 1
	v_add_f32_dpp v35, v35, v35 quad_perm:[2,3,0,1] row_mask:0xf bank_mask:0xf bound_ctrl:1
	s_nop 1
	v_add_f32_dpp v35, v35, v35 row_half_mirror row_mask:0xf bank_mask:0xf bound_ctrl:1
	s_nop 1
	v_mov_b32_dpp v38, v35 row_mirror row_mask:0xf bank_mask:0xf bound_ctrl:1
	s_and_saveexec_b64 s[10:11], s[4:5]
	s_cbranch_execz .LBB0_235
	v_add_f32_e32 v35, v35, v38
	v_mov_b32_e32 v38, 0x920
	v_lshl_add_u32 v38, v160, 4, v38
	v_ashrrev_i32_e32 v39, 31, v38
	v_lshl_add_u64 v[38:39], v[38:39], 2, v[142:143]
	global_store_dword v[38:39], v35, off

; __device__ __forceinline__ unsigned pack2(float a, float b) { return (unsigned)f2bf(a) | ((unsigned)f2bf(b) << 16); }
; template <int EPI, bool HS = false>
; __device__ __forceinline__ void gemm_phase(const Params& p, const GemmCfg& g, char* shm, const int wave_s) {
;     ...
;           for (int j = 0; j < 4; ++j) {
;             float ss = 0.f;
; #pragma unroll
;             for (int bj = 0; bj < 2; ++bj) {
;               float2 xn;
;               xn.x = xv[j][bj].x + gt[bj][0] * acc[ai][bj][m][0][j];
;               xn.y = xv[j][bj].y + gt[bj][1] * acc[ai][bj][m][1][j];
;               const unsigned o = tb + (unsigned)((ai * 128 + m * 16 + j) * 1024 + bj * 128);
;               *(float2*)(xout_t + o) = xn;
;               if (g.has_next) *(unsigned*)(xg_t + o) = pack2(xn.x * gn[bj][0], xn.y * gn[bj][1]);
;               ss += xn.x * xn.x + xn.y * xn.y;
;             }
;             if (g.has_next) {
;               ss = dpp_row_sum16(ss);
;               if (fr == 0) rss_t[(wr * 64 + fq * 4 + ai * 128 + m * 16 + j) * 16] = ss;
;             }
.LBB0_238:
	v_add_u32_e32 v42, 0x24c00, v0
	v_mov_b32_e32 v48, v45
	v_mov_b32_e32 v43, v1
	s_waitcnt lgkmcnt(0)
	v_pk_fma_f32 v[38:39], v[150:151], v[48:49], v[50:51]
	v_lshl_add_u64 v[34:35], v[42:43], 2, s[2:3]
	global_store_dwordx2 v[34:35], v[38:39], off
	s_mov_b64 s[10:11], -1
	s_and_b64 vcc, exec, s[6:7]
	v_add_u32_e32 v34, 0x24c80, v0
	s_cbranch_vccnz .LBB0_242
	v_pk_mul_f32 v[44:45], v[148:149], v[38:39]
	v_lshl_add_u64 v[42:43], v[42:43], 1, s[8:9]
	s_nop 0
	v_and_b32_sdwa v35, v45, v178 dst_sel:DWORD dst_unused:UNUSED_PAD src0_sel:WORD_1 src1_sel:DWORD
	v_cvt_pk_bf16_f32 v36, v44, v44
	v_add3_u32 v35, v45, v35, s81
	v_lshrrev_b32_e32 v36, 16, v36
	v_and_or_b32 v35, v35, s28, v36
	global_store_dword v[42:43], v35, off
	v_mov_b32_e32 v40, v37
	v_mov_b32_e32 v35, v1
	v_pk_fma_f32 v[42:43], v[146:147], v[40:41], v[52:53]
	v_lshl_add_u64 v[44:45], v[34:35], 2, s[2:3]
	global_store_dwordx2 v[44:45], v[42:43], off
	v_pk_mul_f32 v[44:45], v[152:153], v[42:43]
	v_pk_mul_f32 v[38:39], v[38:39], v[38:39]
	s_nop 0
	v_and_b32_sdwa v36, v45, v178 dst_sel:DWORD dst_unused:UNUSED_PAD src0_sel:WORD_1 src1_sel:DWORD
	v_cvt_pk_bf16_f32 v40, v44, v44
	v_add3_u32 v36, v45, v36, s81
	v_lshrrev_b32_e32 v40, 16, v40
	v_and_or_b32 v36, v36, s28, v40
	v_lshl_add_u64 v[44:45], v[34:35], 1, s[8:9]
	v_pk_mul_f32 v[42:43], v[42:43], v[42:43]
	global_store_dword v[44:45], v36, off
	v_add_f32_e32 v35, v42, v43
	v_add_f32_e32 v36, v38, v39
	v_add_f32_e32 v35, v36, v35
	s_nop 1
	v_add_f32_dpp v35, v35, v35 quad_perm:[1,0,3,2] row_mask:0xf bank_mask:0xf bound_ctrl:1
	s_nop 1
	v_add_f32_dpp v35, v35, v35 quad_perm:[2,3,0,1] row_mask:0xf bank_mask:0xf bound_ctrl:1
	s_nop 1
	v_add_f32_dpp v35, v35, v35 row_half_mirror row_mask:0xf bank_mask:0xf bound_ctrl:1
	s_nop 1
	v_mov_b32_dpp v36, v35 row_mirror row_mask:0xf bank_mask:0xf bound_ctrl:1
	s_and_saveexec_b64 s[10:11], s[4:5]
	s_cbranch_execz .LBB0_241
	v_add_f32_e32 v35, v35, v36
	v_mov_b32_e32 v36, 0x930
	v_lshl_add_u32 v38, v160, 4, v36
	v_ashrrev_i32_e32 v39, 31, v38
	v_lshl_add_u64 v[38:39], v[38:39], 2, v[142:143]
	global_store_dword v[38:39], v35, off

; __device__ __forceinline__ unsigned pack2(float a, float b) { return (unsigned)f2bf(a) | ((unsigned)f2bf(b) << 16); }
; template <int EPI, bool HS = false>
; __device__ __forceinline__ void gemm_phase(const Params& p, const GemmCfg& g, char* shm, const int wave_s) {
;     ...
;             for (int bj = 0; bj < 2; ++bj) xv[j][bj] = *(const float2*)(xl + (m * 16 + j) * XROW + bj * 512);
; #pragma unroll
;           for (int j = 0; j < 4; ++j) {
;             float ss = 0.f;
; #pragma unroll
;             for (int bj = 0; bj < 2; ++bj) {
;               float2 xn;
;               xn.x = xv[j][bj].x + gt[bj][0] * acc[ai][bj][m][0][j];
;               xn.y = xv[j][bj].y + gt[bj][1] * acc[ai][bj][m][1][j];
;               const unsigned o = tb + (unsigned)((ai * 128 + m * 16 + j) * 1024 + bj * 128);
;               *(float2*)(xout_t + o) = xn;
;               if (g.has_next) *(unsigned*)(xg_t + o) = pack2(xn.x * gn[bj][0], xn.y * gn[bj][1]);
;               ss += xn.x * xn.x + xn.y * xn.y;
;             }
;             if (g.has_next) {
;               ss = dpp_row_sum16(ss);
;               if (fr == 0) rss_t[(wr * 64 + fq * 4 + ai * 128 + m * 16 + j) * 16] = ss;
;             }
.LBB0_244:
	ds_read2st64_b64 v[46:49], v161 offset0:65 offset1:66
	ds_read2st64_b64 v[42:45], v118 offset0:67 offset1:68
	ds_read2st64_b64 v[38:41], v162 offset0:69 offset1:70
	ds_read2st64_b64 v[34:37], v163 offset0:71 offset1:72
	v_add_u32_e32 v52, 0x28000, v0
	v_mov_b32_e32 v50, v26
	v_mov_b32_e32 v51, v30
	v_mov_b32_e32 v53, v1
	s_waitcnt lgkmcnt(3)
	v_pk_fma_f32 v[50:51], v[150:151], v[50:51], v[46:47]
	v_lshl_add_u64 v[46:47], v[52:53], 2, s[2:3]
	global_store_dwordx2 v[46:47], v[50:51], off
	s_mov_b64 s[10:11], -1
	s_and_b64 vcc, exec, s[6:7]
	v_add_u32_e32 v46, 0x28080, v0
	s_cbranch_vccnz .LBB0_248
	v_pk_mul_f32 v[54:55], v[148:149], v[50:51]
	v_lshl_add_u64 v[52:53], v[52:53], 1, s[8:9]
	s_nop 0
	v_and_b32_sdwa v26, v55, v178 dst_sel:DWORD dst_unused:UNUSED_PAD src0_sel:WORD_1 src1_sel:DWORD
	v_cvt_pk_bf16_f32 v30, v54, v54
	v_add3_u32 v26, v55, v26, s81
	v_lshrrev_b32_e32 v30, 16, v30
	v_and_or_b32 v26, v26, s28, v30
	global_store_dword v[52:53], v26, off
	v_mov_b32_e32 v52, v18
	v_mov_b32_e32 v53, v22
	v_mov_b32_e32 v47, v1
	v_pk_fma_f32 v[52:53], v[146:147], v[52:53], v[48:49]
	v_lshl_add_u64 v[54:55], v[46:47], 2, s[2:3]
	global_store_dwordx2 v[54:55], v[52:53], off
	v_pk_mul_f32 v[54:55], v[152:153], v[52:53]
	v_pk_mul_f32 v[50:51], v[50:51], v[50:51]
	s_nop 0
	v_and_b32_sdwa v26, v55, v178 dst_sel:DWORD dst_unused:UNUSED_PAD src0_sel:WORD_1 src1_sel:DWORD
	v_cvt_pk_bf16_f32 v30, v54, v54
	v_add3_u32 v26, v55, v26, s81
	v_lshrrev_b32_e32 v30, 16, v30
	v_and_or_b32 v26, v26, s28, v30
	v_lshl_add_u64 v[54:55], v[46:47], 1, s[8:9]
	v_pk_mul_f32 v[52:53], v[52:53], v[52:53]
	global_store_dword v[54:55], v26, off
	v_add_f32_e32 v26, v52, v53
	v_add_f32_e32 v30, v50, v51
	v_add_f32_e32 v26, v30, v26
	s_nop 1
	v_add_f32_dpp v26, v26, v26 quad_perm:[1,0,3,2] row_mask:0xf bank_mask:0xf bound_ctrl:1
	s_nop 1
	v_add_f32_dpp v26, v26, v26 quad_perm:[2,3,0,1] row_mask:0xf bank_mask:0xf bound_ctrl:1
	s_nop 1
	v_add_f32_dpp v26, v26, v26 row_half_mirror row_mask:0xf bank_mask:0xf bound_ctrl:1
	s_nop 1
	v_mov_b32_dpp v30, v26 row_mirror row_mask:0xf bank_mask:0xf bound_ctrl:1
	s_and_saveexec_b64 s[10:11], s[4:5]
	s_cbranch_execz .LBB0_247
	v_add_f32_e32 v26, v26, v30
	v_mov_b32_e32 v30, 0xa00
	v_lshl_add_u32 v50, v160, 4, v30
	v_ashrrev_i32_e32 v51, 31, v50
	v_lshl_add_u64 v[50:51], v[50:51], 2, v[142:143]
	global_store_dword v[50:51], v26, off

; __device__ __forceinline__ unsigned pack2(float a, float b) { return (unsigned)f2bf(a) | ((unsigned)f2bf(b) << 16); }
; template <int EPI, bool HS = false>
; __device__ __forceinline__ void gemm_phase(const Params& p, const GemmCfg& g, char* shm, const int wave_s) {
;     ...
;           for (int j = 0; j < 4; ++j) {
;             float ss = 0.f;
; #pragma unroll
;             for (int bj = 0; bj < 2; ++bj) {
;               float2 xn;
;               xn.x = xv[j][bj].x + gt[bj][0] * acc[ai][bj][m][0][j];
;               xn.y = xv[j][bj].y + gt[bj][1] * acc[ai][bj][m][1][j];
;               const unsigned o = tb + (unsigned)((ai * 128 + m * 16 + j) * 1024 + bj * 128);
;               *(float2*)(xout_t + o) = xn;
;               if (g.has_next) *(unsigned*)(xg_t + o) = pack2(xn.x * gn[bj][0], xn.y * gn[bj][1]);
;               ss += xn.x * xn.x + xn.y * xn.y;
;             }
;             if (g.has_next) {
;               ss = dpp_row_sum16(ss);
;               if (fr == 0) rss_t[(wr * 64 + fq * 4 + ai * 128 + m * 16 + j) * 16] = ss;
;             }
.LBB0_250:
	v_add_u32_e32 v46, 0x28400, v0
	v_mov_b32_e32 v30, v27
	v_mov_b32_e32 v47, v1
	s_waitcnt lgkmcnt(2)
	v_pk_fma_f32 v[30:31], v[150:151], v[30:31], v[42:43]
	v_lshl_add_u64 v[26:27], v[46:47], 2, s[2:3]
	global_store_dwordx2 v[26:27], v[30:31], off
	s_mov_b64 s[10:11], -1
	s_and_b64 vcc, exec, s[6:7]
	v_add_u32_e32 v26, 0x28480, v0
	s_cbranch_vccnz .LBB0_254
	v_pk_mul_f32 v[42:43], v[148:149], v[30:31]
	v_mov_b32_e32 v27, v1
	s_nop 0
	v_and_b32_sdwa v18, v43, v178 dst_sel:DWORD dst_unused:UNUSED_PAD src0_sel:WORD_1 src1_sel:DWORD
	v_cvt_pk_bf16_f32 v22, v42, v42
	v_add3_u32 v18, v43, v18, s81
	v_lshrrev_b32_e32 v22, 16, v22
	v_and_or_b32 v18, v18, s28, v22
	v_lshl_add_u64 v[42:43], v[46:47], 1, s[8:9]
	v_mov_b32_e32 v22, v19
	global_store_dword v[42:43], v18, off
	v_pk_fma_f32 v[42:43], v[146:147], v[22:23], v[44:45]
	v_lshl_add_u64 v[46:47], v[26:27], 2, s[2:3]
	global_store_dwordx2 v[46:47], v[42:43], off
	v_pk_mul_f32 v[46:47], v[152:153], v[42:43]
	v_pk_mul_f32 v[30:31], v[30:31], v[30:31]
	s_nop 0
	v_and_b32_sdwa v18, v47, v178 dst_sel:DWORD dst_unused:UNUSED_PAD src0_sel:WORD_1 src1_sel:DWORD
	v_cvt_pk_bf16_f32 v22, v46, v46
	v_add3_u32 v18, v47, v18, s81
	v_lshrrev_b32_e32 v22, 16, v22
	v_and_or_b32 v18, v18, s28, v22
	v_lshl_add_u64 v[46:47], v[26:27], 1, s[8:9]
	v_pk_mul_f32 v[42:43], v[42:43], v[42:43]
	global_store_dword v[46:47], v18, off
	v_add_f32_e32 v18, v42, v43
	v_add_f32_e32 v22, v30, v31
	v_add_f32_e32 v18, v22, v18
	s_nop 1
	v_add_f32_dpp v18, v18, v18 quad_perm:[1,0,3,2] row_mask:0xf bank_mask:0xf bound_ctrl:1
	s_nop 1
	v_add_f32_dpp v18, v18, v18 quad_perm:[2,3,0,1] row_mask:0xf bank_mask:0xf bound_ctrl:1
	s_nop 1
	v_add_f32_dpp v18, v18, v18 row_half_mirror row_mask:0xf bank_mask:0xf bound_ctrl:1
	s_nop 1
	v_mov_b32_dpp v22, v18 row_mirror row_mask:0xf bank_mask:0xf bound_ctrl:1
	s_and_saveexec_b64 s[10:11], s[4:5]
	s_cbranch_execz .LBB0_253
	v_add_f32_e32 v18, v18, v22
	v_mov_b32_e32 v22, 0xa10
	v_lshl_add_u32 v30, v160, 4, v22
	v_ashrrev_i32_e32 v31, 31, v30
	v_lshl_add_u64 v[30:31], v[30:31], 2, v[142:143]
	global_store_dword v[30:31], v18, off

; __device__ __forceinline__ unsigned pack2(float a, float b) { return (unsigned)f2bf(a) | ((unsigned)f2bf(b) << 16); }
; template <int EPI, bool HS = false>
; __device__ __forceinline__ void gemm_phase(const Params& p, const GemmCfg& g, char* shm, const int wave_s) {
;     ...
;           for (int j = 0; j < 4; ++j) {
;             float ss = 0.f;
; #pragma unroll
;             for (int bj = 0; bj < 2; ++bj) {
;               float2 xn;
;               xn.x = xv[j][bj].x + gt[bj][0] * acc[ai][bj][m][0][j];
;               xn.y = xv[j][bj].y + gt[bj][1] * acc[ai][bj][m][1][j];
;               const unsigned o = tb + (unsigned)((ai * 128 + m * 16 + j) * 1024 + bj * 128);
;               *(float2*)(xout_t + o) = xn;
;               if (g.has_next) *(unsigned*)(xg_t + o) = pack2(xn.x * gn[bj][0], xn.y * gn[bj][1]);
;               ss += xn.x * xn.x + xn.y * xn.y;
;             }
;             if (g.has_next) {
;               ss = dpp_row_sum16(ss);
;               if (fr == 0) rss_t[(wr * 64 + fq * 4 + ai * 128 + m * 16 + j) * 16] = ss;
;             }
.LBB0_256:
	v_add_u32_e32 v26, 0x28800, v0
	v_mov_b32_e32 v18, v28
	v_mov_b32_e32 v19, v32
	v_mov_b32_e32 v27, v1
	s_waitcnt lgkmcnt(1)
	v_pk_fma_f32 v[22:23], v[150:151], v[18:19], v[38:39]
	v_lshl_add_u64 v[18:19], v[26:27], 2, s[2:3]
	global_store_dwordx2 v[18:19], v[22:23], off
	s_mov_b64 s[10:11], -1
	s_and_b64 vcc, exec, s[6:7]
	v_add_u32_e32 v18, 0x28880, v0
	s_cbranch_vccnz .LBB0_260
	v_pk_mul_f32 v[30:31], v[148:149], v[22:23]
	v_lshl_add_u64 v[26:27], v[26:27], 1, s[8:9]
	s_nop 0
	v_and_b32_sdwa v19, v31, v178 dst_sel:DWORD dst_unused:UNUSED_PAD src0_sel:WORD_1 src1_sel:DWORD
	v_cvt_pk_bf16_f32 v28, v30, v30
	v_add3_u32 v19, v31, v19, s81
	v_lshrrev_b32_e32 v28, 16, v28
	v_and_or_b32 v19, v19, s28, v28
	global_store_dword v[26:27], v19, off
	v_mov_b32_e32 v26, v20
	v_mov_b32_e32 v27, v24
	v_mov_b32_e32 v19, v1
	v_pk_fma_f32 v[26:27], v[146:147], v[26:27], v[40:41]
	v_lshl_add_u64 v[30:31], v[18:19], 2, s[2:3]
	global_store_dwordx2 v[30:31], v[26:27], off
	v_pk_mul_f32 v[30:31], v[152:153], v[26:27]
	v_pk_mul_f32 v[22:23], v[22:23], v[22:23]
	v_and_b32_sdwa v32, v30, v178 dst_sel:DWORD dst_unused:UNUSED_PAD src0_sel:WORD_1 src1_sel:DWORD
	v_and_b32_sdwa v28, v31, v178 dst_sel:DWORD dst_unused:UNUSED_PAD src0_sel:WORD_1 src1_sel:DWORD
	v_add3_u32 v30, v30, v32, s81
	v_add3_u32 v28, v31, v28, s81
	v_lshrrev_b32_e32 v30, 16, v30
	v_pk_mul_f32 v[26:27], v[26:27], v[26:27]
	v_and_or_b32 v28, v28, s28, v30
	v_lshl_add_u64 v[30:31], v[18:19], 1, s[8:9]
	v_add_f32_e32 v19, v26, v27
	v_add_f32_e32 v22, v22, v23
	v_add_f32_e32 v19, v22, v19
	global_store_dword v[30:31], v28, off
	s_nop 0
	v_add_f32_dpp v19, v19, v19 quad_perm:[1,0,3,2] row_mask:0xf bank_mask:0xf bound_ctrl:1
	s_nop 1
	v_add_f32_dpp v19, v19, v19 quad_perm:[2,3,0,1] row_mask:0xf bank_mask:0xf bound_ctrl:1
	s_nop 1
	v_add_f32_dpp v19, v19, v19 row_half_mirror row_mask:0xf bank_mask:0xf bound_ctrl:1
	s_nop 1
	v_mov_b32_dpp v22, v19 row_mirror row_mask:0xf bank_mask:0xf bound_ctrl:1
	s_and_saveexec_b64 s[10:11], s[4:5]
	s_cbranch_execz .LBB0_259
	v_add_f32_e32 v19, v19, v22
	v_mov_b32_e32 v22, 0xa20
	v_lshl_add_u32 v22, v160, 4, v22
	v_ashrrev_i32_e32 v23, 31, v22
	v_lshl_add_u64 v[22:23], v[22:23], 2, v[142:143]
	global_store_dword v[22:23], v19, off

; __device__ __forceinline__ unsigned pack2(float a, float b) { return (unsigned)f2bf(a) | ((unsigned)f2bf(b) << 16); }
; template <int EPI, bool HS = false>
; __device__ __forceinline__ void gemm_phase(const Params& p, const GemmCfg& g, char* shm, const int wave_s) {
;     ...
;           for (int j = 0; j < 4; ++j) {
;             float ss = 0.f;
; #pragma unroll
;             for (int bj = 0; bj < 2; ++bj) {
;               float2 xn;
;               xn.x = xv[j][bj].x + gt[bj][0] * acc[ai][bj][m][0][j];
;               xn.y = xv[j][bj].y + gt[bj][1] * acc[ai][bj][m][1][j];
;               const unsigned o = tb + (unsigned)((ai * 128 + m * 16 + j) * 1024 + bj * 128);
;               *(float2*)(xout_t + o) = xn;
;               if (g.has_next) *(unsigned*)(xg_t + o) = pack2(xn.x * gn[bj][0], xn.y * gn[bj][1]);
;               ss += xn.x * xn.x + xn.y * xn.y;
;             }
;             if (g.has_next) {
;               ss = dpp_row_sum16(ss);
;               if (fr == 0) rss_t[(wr * 64 + fq * 4 + ai * 128 + m * 16 + j) * 16] = ss;
;             }
.LBB0_262:
	v_add_u32_e32 v26, 0x28c00, v0
	v_mov_b32_e32 v32, v29
	v_mov_b32_e32 v27, v1
	s_waitcnt lgkmcnt(0)
	v_pk_fma_f32 v[22:23], v[150:151], v[32:33], v[34:35]
	v_lshl_add_u64 v[18:19], v[26:27], 2, s[2:3]
	global_store_dwordx2 v[18:19], v[22:23], off
	s_mov_b64 s[10:11], -1
	s_and_b64 vcc, exec, s[6:7]
	v_add_u32_e32 v18, 0x28c80, v0
	s_cbranch_vccnz .LBB0_266
	v_pk_mul_f32 v[28:29], v[148:149], v[22:23]
	v_lshl_add_u64 v[26:27], v[26:27], 1, s[8:9]
	s_nop 0
	v_and_b32_sdwa v19, v29, v178 dst_sel:DWORD dst_unused:UNUSED_PAD src0_sel:WORD_1 src1_sel:DWORD
	v_cvt_pk_bf16_f32 v20, v28, v28
	v_add3_u32 v19, v29, v19, s81
	v_lshrrev_b32_e32 v20, 16, v20
	v_and_or_b32 v19, v19, s28, v20
	global_store_dword v[26:27], v19, off
	v_mov_b32_e32 v24, v21
	v_mov_b32_e32 v19, v1
	v_pk_fma_f32 v[26:27], v[146:147], v[24:25], v[36:37]
	v_lshl_add_u64 v[28:29], v[18:19], 2, s[2:3]
	global_store_dwordx2 v[28:29], v[26:27], off
	v_pk_mul_f32 v[28:29], v[152:153], v[26:27]
	v_pk_mul_f32 v[22:23], v[22:23], v[22:23]
	s_nop 0
	v_and_b32_sdwa v20, v29, v178 dst_sel:DWORD dst_unused:UNUSED_PAD src0_sel:WORD_1 src1_sel:DWORD
	v_cvt_pk_bf16_f32 v24, v28, v28
	v_add3_u32 v20, v29, v20, s81
	v_lshrrev_b32_e32 v24, 16, v24
	v_and_or_b32 v20, v20, s28, v24
	v_lshl_add_u64 v[28:29], v[18:19], 1, s[8:9]
	v_pk_mul_f32 v[26:27], v[26:27], v[26:27]
	global_store_dword v[28:29], v20, off
	v_add_f32_e32 v19, v26, v27
	v_add_f32_e32 v20, v22, v23
	v_add_f32_e32 v19, v20, v19
	s_nop 1
	v_add_f32_dpp v19, v19, v19 quad_perm:[1,0,3,2] row_mask:0xf bank_mask:0xf bound_ctrl:1
	s_nop 1
	v_add_f32_dpp v19, v19, v19 quad_perm:[2,3,0,1] row_mask:0xf bank_mask:0xf bound_ctrl:1
	s_nop 1
	v_add_f32_dpp v19, v19, v19 row_half_mirror row_mask:0xf bank_mask:0xf bound_ctrl:1
	s_nop 1
	v_mov_b32_dpp v20, v19 row_mirror row_mask:0xf bank_mask:0xf bound_ctrl:1
	s_and_saveexec_b64 s[10:11], s[4:5]
	s_cbranch_execz .LBB0_265
	v_add_f32_e32 v19, v19, v20
	v_mov_b32_e32 v20, 0xa30
	v_lshl_add_u32 v22, v160, 4, v20
	v_ashrrev_i32_e32 v23, 31, v22
	v_lshl_add_u64 v[22:23], v[22:23], 2, v[142:143]
	global_store_dword v[22:23], v19, off

; __device__ __forceinline__ unsigned pack2(float a, float b) { return (unsigned)f2bf(a) | ((unsigned)f2bf(b) << 16); }
; template <int EPI, bool HS = false>
; __device__ __forceinline__ void gemm_phase(const Params& p, const GemmCfg& g, char* shm, const int wave_s) {
;     ...
;             for (int bj = 0; bj < 2; ++bj) xv[j][bj] = *(const float2*)(xl + (m * 16 + j) * XROW + bj * 512);
; #pragma unroll
;           for (int j = 0; j < 4; ++j) {
;             float ss = 0.f;
; #pragma unroll
;             for (int bj = 0; bj < 2; ++bj) {
;               float2 xn;
;               xn.x = xv[j][bj].x + gt[bj][0] * acc[ai][bj][m][0][j];
;               xn.y = xv[j][bj].y + gt[bj][1] * acc[ai][bj][m][1][j];
;               const unsigned o = tb + (unsigned)((ai * 128 + m * 16 + j) * 1024 + bj * 128);
;               *(float2*)(xout_t + o) = xn;
;               if (g.has_next) *(unsigned*)(xg_t + o) = pack2(xn.x * gn[bj][0], xn.y * gn[bj][1]);
;               ss += xn.x * xn.x + xn.y * xn.y;
;             }
;             if (g.has_next) {
;               ss = dpp_row_sum16(ss);
;               if (fr == 0) rss_t[(wr * 64 + fq * 4 + ai * 128 + m * 16 + j) * 16] = ss;
;             }
.LBB0_268:
	ds_read2st64_b64 v[30:33], v134 offset0:97 offset1:98
	ds_read2st64_b64 v[26:29], v135 offset0:99 offset1:100
	ds_read2st64_b64 v[22:25], v136 offset0:101 offset1:102
	ds_read2st64_b64 v[18:21], v137 offset0:103 offset1:104
	v_add_u32_e32 v36, 0x2c000, v0
	v_mov_b32_e32 v34, v10
	v_mov_b32_e32 v35, v14
	v_mov_b32_e32 v37, v1
	s_waitcnt lgkmcnt(3)
	v_pk_fma_f32 v[34:35], v[150:151], v[34:35], v[30:31]
	v_lshl_add_u64 v[30:31], v[36:37], 2, s[2:3]
	global_store_dwordx2 v[30:31], v[34:35], off
	s_mov_b64 s[10:11], -1
	s_and_b64 vcc, exec, s[6:7]
	v_add_u32_e32 v30, 0x2c080, v0
	s_cbranch_vccnz .LBB0_272
	v_pk_mul_f32 v[38:39], v[148:149], v[34:35]
	v_lshl_add_u64 v[36:37], v[36:37], 1, s[8:9]
	s_nop 0
	v_and_b32_sdwa v10, v39, v178 dst_sel:DWORD dst_unused:UNUSED_PAD src0_sel:WORD_1 src1_sel:DWORD
	v_cvt_pk_bf16_f32 v14, v38, v38
	v_add3_u32 v10, v39, v10, s81
	v_lshrrev_b32_e32 v14, 16, v14
	v_and_or_b32 v10, v10, s28, v14
	global_store_dword v[36:37], v10, off
	v_mov_b32_e32 v36, v2
	v_mov_b32_e32 v37, v6
	v_mov_b32_e32 v31, v1
	v_pk_fma_f32 v[36:37], v[146:147], v[36:37], v[32:33]
	v_lshl_add_u64 v[38:39], v[30:31], 2, s[2:3]
	global_store_dwordx2 v[38:39], v[36:37], off
	v_pk_mul_f32 v[38:39], v[152:153], v[36:37]
	v_pk_mul_f32 v[34:35], v[34:35], v[34:35]
	s_nop 0
	v_and_b32_sdwa v10, v39, v178 dst_sel:DWORD dst_unused:UNUSED_PAD src0_sel:WORD_1 src1_sel:DWORD
	v_cvt_pk_bf16_f32 v14, v38, v38
	v_add3_u32 v10, v39, v10, s81
	v_lshrrev_b32_e32 v14, 16, v14
	v_and_or_b32 v10, v10, s28, v14
	v_lshl_add_u64 v[38:39], v[30:31], 1, s[8:9]
	v_pk_mul_f32 v[36:37], v[36:37], v[36:37]
	global_store_dword v[38:39], v10, off
	v_add_f32_e32 v10, v36, v37
	v_add_f32_e32 v14, v34, v35
	v_add_f32_e32 v10, v14, v10
	s_nop 1
	v_add_f32_dpp v10, v10, v10 quad_perm:[1,0,3,2] row_mask:0xf bank_mask:0xf bound_ctrl:1
	s_nop 1
	v_add_f32_dpp v10, v10, v10 quad_perm:[2,3,0,1] row_mask:0xf bank_mask:0xf bound_ctrl:1
	s_nop 1
	v_add_f32_dpp v10, v10, v10 row_half_mirror row_mask:0xf bank_mask:0xf bound_ctrl:1
	s_nop 1
	v_mov_b32_dpp v14, v10 row_mirror row_mask:0xf bank_mask:0xf bound_ctrl:1
	s_and_saveexec_b64 s[10:11], s[4:5]
	s_cbranch_execz .LBB0_271
	v_add_f32_e32 v10, v10, v14
	v_mov_b32_e32 v14, 0xb00
	v_lshl_add_u32 v34, v160, 4, v14
	v_ashrrev_i32_e32 v35, 31, v34
	v_lshl_add_u64 v[34:35], v[34:35], 2, v[142:143]
	global_store_dword v[34:35], v10, off

; __device__ __forceinline__ unsigned pack2(float a, float b) { return (unsigned)f2bf(a) | ((unsigned)f2bf(b) << 16); }
; template <int EPI, bool HS = false>
; __device__ __forceinline__ void gemm_phase(const Params& p, const GemmCfg& g, char* shm, const int wave_s) {
;     ...
;           for (int j = 0; j < 4; ++j) {
;             float ss = 0.f;
; #pragma unroll
;             for (int bj = 0; bj < 2; ++bj) {
;               float2 xn;
;               xn.x = xv[j][bj].x + gt[bj][0] * acc[ai][bj][m][0][j];
;               xn.y = xv[j][bj].y + gt[bj][1] * acc[ai][bj][m][1][j];
;               const unsigned o = tb + (unsigned)((ai * 128 + m * 16 + j) * 1024 + bj * 128);
;               *(float2*)(xout_t + o) = xn;
;               if (g.has_next) *(unsigned*)(xg_t + o) = pack2(xn.x * gn[bj][0], xn.y * gn[bj][1]);
;               ss += xn.x * xn.x + xn.y * xn.y;
;             }
;             if (g.has_next) {
;               ss = dpp_row_sum16(ss);
;               if (fr == 0) rss_t[(wr * 64 + fq * 4 + ai * 128 + m * 16 + j) * 16] = ss;
;             }
.LBB0_274:
	v_add_u32_e32 v30, 0x2c400, v0
	v_mov_b32_e32 v14, v11
	v_mov_b32_e32 v31, v1
	s_waitcnt lgkmcnt(2)
	v_pk_fma_f32 v[14:15], v[150:151], v[14:15], v[26:27]
	v_lshl_add_u64 v[10:11], v[30:31], 2, s[2:3]
	global_store_dwordx2 v[10:11], v[14:15], off
	s_mov_b64 s[10:11], -1
	s_and_b64 vcc, exec, s[6:7]
	v_add_u32_e32 v10, 0x2c480, v0
	s_cbranch_vccnz .LBB0_278
	v_pk_mul_f32 v[26:27], v[148:149], v[14:15]
	v_mov_b32_e32 v11, v1
	s_nop 0
	v_and_b32_sdwa v2, v27, v178 dst_sel:DWORD dst_unused:UNUSED_PAD src0_sel:WORD_1 src1_sel:DWORD
	v_cvt_pk_bf16_f32 v6, v26, v26
	v_add3_u32 v2, v27, v2, s81
	v_lshrrev_b32_e32 v6, 16, v6
	v_and_or_b32 v2, v2, s28, v6
	v_lshl_add_u64 v[26:27], v[30:31], 1, s[8:9]
	v_mov_b32_e32 v6, v3
	global_store_dword v[26:27], v2, off
	v_pk_fma_f32 v[26:27], v[146:147], v[6:7], v[28:29]
	v_lshl_add_u64 v[30:31], v[10:11], 2, s[2:3]
	global_store_dwordx2 v[30:31], v[26:27], off
	v_pk_mul_f32 v[30:31], v[152:153], v[26:27]
	v_pk_mul_f32 v[14:15], v[14:15], v[14:15]
	s_nop 0
	v_and_b32_sdwa v2, v31, v178 dst_sel:DWORD dst_unused:UNUSED_PAD src0_sel:WORD_1 src1_sel:DWORD
	v_cvt_pk_bf16_f32 v6, v30, v30
	v_add3_u32 v2, v31, v2, s81
	v_lshrrev_b32_e32 v6, 16, v6
	v_and_or_b32 v2, v2, s28, v6
	v_lshl_add_u64 v[30:31], v[10:11], 1, s[8:9]
	v_pk_mul_f32 v[26:27], v[26:27], v[26:27]
	global_store_dword v[30:31], v2, off
	v_add_f32_e32 v2, v26, v27
	v_add_f32_e32 v6, v14, v15
	v_add_f32_e32 v2, v6, v2
	s_nop 1
	v_add_f32_dpp v2, v2, v2 quad_perm:[1,0,3,2] row_mask:0xf bank_mask:0xf bound_ctrl:1
	s_nop 1
	v_add_f32_dpp v2, v2, v2 quad_perm:[2,3,0,1] row_mask:0xf bank_mask:0xf bound_ctrl:1
	s_nop 1
	v_add_f32_dpp v2, v2, v2 row_half_mirror row_mask:0xf bank_mask:0xf bound_ctrl:1
	s_nop 1
	v_mov_b32_dpp v6, v2 row_mirror row_mask:0xf bank_mask:0xf bound_ctrl:1
	s_and_saveexec_b64 s[10:11], s[4:5]
	s_cbranch_execz .LBB0_277
	v_add_f32_e32 v2, v2, v6
	v_mov_b32_e32 v6, 0xb10
	v_lshl_add_u32 v14, v160, 4, v6
	v_ashrrev_i32_e32 v15, 31, v14
	v_lshl_add_u64 v[14:15], v[14:15], 2, v[142:143]
	global_store_dword v[14:15], v2, off

; __device__ __forceinline__ unsigned pack2(float a, float b) { return (unsigned)f2bf(a) | ((unsigned)f2bf(b) << 16); }
; template <int EPI, bool HS = false>
; __device__ __forceinline__ void gemm_phase(const Params& p, const GemmCfg& g, char* shm, const int wave_s) {
;     ...
;           for (int j = 0; j < 4; ++j) {
;             float ss = 0.f;
; #pragma unroll
;             for (int bj = 0; bj < 2; ++bj) {
;               float2 xn;
;               xn.x = xv[j][bj].x + gt[bj][0] * acc[ai][bj][m][0][j];
;               xn.y = xv[j][bj].y + gt[bj][1] * acc[ai][bj][m][1][j];
;               const unsigned o = tb + (unsigned)((ai * 128 + m * 16 + j) * 1024 + bj * 128);
;               *(float2*)(xout_t + o) = xn;
;               if (g.has_next) *(unsigned*)(xg_t + o) = pack2(xn.x * gn[bj][0], xn.y * gn[bj][1]);
;               ss += xn.x * xn.x + xn.y * xn.y;
;             }
;             if (g.has_next) {
;               ss = dpp_row_sum16(ss);
;               if (fr == 0) rss_t[(wr * 64 + fq * 4 + ai * 128 + m * 16 + j) * 16] = ss;
;             }
.LBB0_280:
	v_add_u32_e32 v10, 0x2c800, v0
	v_mov_b32_e32 v2, v12
	v_mov_b32_e32 v3, v16
	v_mov_b32_e32 v11, v1
	s_waitcnt lgkmcnt(1)
	v_pk_fma_f32 v[6:7], v[150:151], v[2:3], v[22:23]
	v_lshl_add_u64 v[2:3], v[10:11], 2, s[2:3]
	global_store_dwordx2 v[2:3], v[6:7], off
	s_mov_b64 s[10:11], -1
	s_and_b64 vcc, exec, s[6:7]
	v_add_u32_e32 v2, 0x2c880, v0
	s_cbranch_vccnz .LBB0_284
	v_pk_mul_f32 v[14:15], v[148:149], v[6:7]
	v_lshl_add_u64 v[10:11], v[10:11], 1, s[8:9]
	s_nop 0
	v_and_b32_sdwa v3, v15, v178 dst_sel:DWORD dst_unused:UNUSED_PAD src0_sel:WORD_1 src1_sel:DWORD
	v_cvt_pk_bf16_f32 v12, v14, v14
	v_add3_u32 v3, v15, v3, s81
	v_lshrrev_b32_e32 v12, 16, v12
	v_and_or_b32 v3, v3, s28, v12
	global_store_dword v[10:11], v3, off
	v_mov_b32_e32 v10, v4
	v_mov_b32_e32 v11, v8
	v_mov_b32_e32 v3, v1
	v_pk_fma_f32 v[10:11], v[146:147], v[10:11], v[24:25]
	v_lshl_add_u64 v[14:15], v[2:3], 2, s[2:3]
	global_store_dwordx2 v[14:15], v[10:11], off
	v_pk_mul_f32 v[14:15], v[152:153], v[10:11]
	v_pk_mul_f32 v[6:7], v[6:7], v[6:7]
	v_and_b32_sdwa v16, v14, v178 dst_sel:DWORD dst_unused:UNUSED_PAD src0_sel:WORD_1 src1_sel:DWORD
	v_and_b32_sdwa v12, v15, v178 dst_sel:DWORD dst_unused:UNUSED_PAD src0_sel:WORD_1 src1_sel:DWORD
	v_add3_u32 v14, v14, v16, s81
	v_add3_u32 v12, v15, v12, s81
	v_lshrrev_b32_e32 v14, 16, v14
	v_pk_mul_f32 v[10:11], v[10:11], v[10:11]
	v_and_or_b32 v12, v12, s28, v14
	v_lshl_add_u64 v[14:15], v[2:3], 1, s[8:9]
	v_add_f32_e32 v3, v10, v11
	v_add_f32_e32 v6, v6, v7
	v_add_f32_e32 v3, v6, v3
	global_store_dword v[14:15], v12, off
	s_nop 0
	v_add_f32_dpp v3, v3, v3 quad_perm:[1,0,3,2] row_mask:0xf bank_mask:0xf bound_ctrl:1
	s_nop 1
	v_add_f32_dpp v3, v3, v3 quad_perm:[2,3,0,1] row_mask:0xf bank_mask:0xf bound_ctrl:1
	s_nop 1
	v_add_f32_dpp v3, v3, v3 row_half_mirror row_mask:0xf bank_mask:0xf bound_ctrl:1
	s_nop 1
	v_mov_b32_dpp v6, v3 row_mirror row_mask:0xf bank_mask:0xf bound_ctrl:1
	s_and_saveexec_b64 s[10:11], s[4:5]
	s_cbranch_execz .LBB0_283
	v_add_f32_e32 v3, v3, v6
	v_mov_b32_e32 v6, 0xb20
	v_lshl_add_u32 v6, v160, 4, v6
	v_ashrrev_i32_e32 v7, 31, v6
	v_lshl_add_u64 v[6:7], v[6:7], 2, v[142:143]
	global_store_dword v[6:7], v3, off

; __device__ __forceinline__ unsigned pack2(float a, float b) { return (unsigned)f2bf(a) | ((unsigned)f2bf(b) << 16); }
; template <int EPI, bool HS = false>
; __device__ __forceinline__ void gemm_phase(const Params& p, const GemmCfg& g, char* shm, const int wave_s) {
;     ...
;           for (int j = 0; j < 4; ++j) {
;             float ss = 0.f;
; #pragma unroll
;             for (int bj = 0; bj < 2; ++bj) {
;               float2 xn;
;               xn.x = xv[j][bj].x + gt[bj][0] * acc[ai][bj][m][0][j];
;               xn.y = xv[j][bj].y + gt[bj][1] * acc[ai][bj][m][1][j];
;               const unsigned o = tb + (unsigned)((ai * 128 + m * 16 + j) * 1024 + bj * 128);
;               *(float2*)(xout_t + o) = xn;
;               if (g.has_next) *(unsigned*)(xg_t + o) = pack2(xn.x * gn[bj][0], xn.y * gn[bj][1]);
;               ss += xn.x * xn.x + xn.y * xn.y;
;             }
;             if (g.has_next) {
;               ss = dpp_row_sum16(ss);
;               if (fr == 0) rss_t[(wr * 64 + fq * 4 + ai * 128 + m * 16 + j) * 16] = ss;
;             }
.LBB0_286:
	v_add_u32_e32 v6, 0x2cc00, v0
	v_mov_b32_e32 v16, v13
	v_mov_b32_e32 v7, v1
	s_waitcnt lgkmcnt(0)
	v_pk_fma_f32 v[2:3], v[150:151], v[16:17], v[18:19]
	v_lshl_add_u64 v[10:11], v[6:7], 2, s[2:3]
	s_mov_b64 s[10:11], -1
	s_and_b64 vcc, exec, s[6:7]
	v_add_u32_e32 v0, 0x2cc80, v0
	global_store_dwordx2 v[10:11], v[2:3], off
	s_cbranch_vccnz .LBB0_290
	v_pk_mul_f32 v[10:11], v[148:149], v[2:3]
	v_lshl_add_u64 v[6:7], v[6:7], 1, s[8:9]
	s_nop 0
	v_and_b32_sdwa v4, v11, v178 dst_sel:DWORD dst_unused:UNUSED_PAD src0_sel:WORD_1 src1_sel:DWORD
	v_cvt_pk_bf16_f32 v8, v10, v10
	v_add3_u32 v4, v11, v4, s81
	v_lshrrev_b32_e32 v8, 16, v8
	v_and_or_b32 v4, v4, s28, v8
	v_mov_b32_e32 v8, v5
	global_store_dword v[6:7], v4, off
	v_pk_fma_f32 v[6:7], v[146:147], v[8:9], v[20:21]
	v_lshl_add_u64 v[10:11], v[0:1], 2, s[2:3]
	global_store_dwordx2 v[10:11], v[6:7], off
	v_pk_mul_f32 v[10:11], v[152:153], v[6:7]
	v_pk_mul_f32 v[2:3], v[2:3], v[2:3]
	s_nop 0
	v_and_b32_sdwa v4, v11, v178 dst_sel:DWORD dst_unused:UNUSED_PAD src0_sel:WORD_1 src1_sel:DWORD
	v_cvt_pk_bf16_f32 v8, v10, v10
	v_add3_u32 v4, v11, v4, s81
	v_lshrrev_b32_e32 v8, 16, v8
	v_and_or_b32 v4, v4, s28, v8
	v_lshl_add_u64 v[10:11], v[0:1], 1, s[8:9]
	v_pk_mul_f32 v[6:7], v[6:7], v[6:7]
	global_store_dword v[10:11], v4, off
	v_add_f32_e32 v4, v6, v7
	v_add_f32_e32 v2, v2, v3
	v_add_f32_e32 v2, v2, v4
	s_nop 1
	v_add_f32_dpp v2, v2, v2 quad_perm:[1,0,3,2] row_mask:0xf bank_mask:0xf bound_ctrl:1
	s_nop 1
	v_add_f32_dpp v2, v2, v2 quad_perm:[2,3,0,1] row_mask:0xf bank_mask:0xf bound_ctrl:1
	s_nop 1
	v_add_f32_dpp v2, v2, v2 row_half_mirror row_mask:0xf bank_mask:0xf bound_ctrl:1
	s_nop 1
	v_mov_b32_dpp v3, v2 row_mirror row_mask:0xf bank_mask:0xf bound_ctrl:1
	s_and_saveexec_b64 s[6:7], s[4:5]
	s_cbranch_execz .LBB0_289
	v_add_f32_e32 v4, v2, v3
	v_mov_b32_e32 v2, 0xb30
	v_lshl_add_u32 v2, v160, 4, v2
	v_ashrrev_i32_e32 v3, 31, v2
	v_lshl_add_u64 v[2:3], v[2:3], 2, v[142:143]
	global_store_dword v[2:3], v4, off

; #define SCHED __builtin_amdgcn_sched_barrier(0)
; template <int EPI, bool HS = false>
; __device__ __forceinline__ void gemm_phase(const Params& p, const GemmCfg& g, char* shm, const int wave_s) {
;     ...
;         u16* ot = g.o16 + (size_t)TOK * 1024 + (size_t)orow0 * 1024 + (pn - 4) * 128;
;         const unsigned tb = (unsigned)((wr * 64 + fq * 4) * 1024 + wc * 16 + fr);
; #pragma unroll
;         for (int ai = 0; ai < 2; ++ai)
; #pragma unroll
;           for (int m = 0; m < 4; ++m) {
;             const f32x4 r4 = *(const f32x4*)(rsw + ai * 128 + m * 16);
; #pragma unroll
;             for (int j = 0; j < 4; ++j)
; #pragma unroll
;               for (int bj = 0; bj < 2; ++bj)
;                 ot[tb + (ai * 128 + m * 16 + j) * 1024 + bj * 64] =
;                     f2bf((r4[j] * acc[ai][bj][m][0][j] + swv[bj][0]) * (r4[j] * acc[ai][bj][m][1][j] + swv[bj][1]));
;             SCHED;
;           }
.LBB0_325:
	ds_read_b128 v[138:141], v130
	s_add_u32 s3, s8, s2
	s_addc_u32 s7, s9, 0
	s_add_u32 s6, s3, 0x7fffc00
	v_lshlrev_b32_e32 v0, 4, v131
	s_waitcnt lgkmcnt(0)
	v_fma_f32 v142, v118, v138, v137
	v_fma_f32 v143, v114, v138, v136
	v_mul_f32_e32 v142, v142, v143
	s_addc_u32 s7, s7, 0
	v_or3_b32 v0, v133, v0, v132
	s_nop 0
	v_cvt_pk_bf16_f32 v144, v142, v142
	v_lshl_add_u64 v[142:143], v[0:1], 1, s[6:7]
	global_store_short_d16_hi v[142:143], v144, off
	v_fma_f32 v142, v126, v138, v135
	v_fma_f32 v138, v122, v138, v134
	v_mul_f32_e32 v138, v142, v138
	s_nop 0
	v_cvt_pk_bf16_f32 v138, v138, v138
	v_or_b32_e32 v142, 64, v0
	v_mov_b32_e32 v143, v1
	v_lshl_add_u64 v[142:143], v[142:143], 1, s[6:7]
	global_store_short_d16_hi v[142:143], v138, off
	v_fma_f32 v138, v119, v139, v137
	v_fma_f32 v143, v115, v139, v136
	v_mul_f32_e32 v138, v138, v143
	s_nop 0
	v_or_b32_e32 v142, 0x400, v0
	v_cvt_pk_bf16_f32 v138, v138, v138
	v_mov_b32_e32 v143, v1
	v_lshl_add_u64 v[142:143], v[142:143], 1, s[6:7]
	global_store_short_d16_hi v[142:143], v138, off
	v_fma_f32 v138, v127, v139, v135
	v_fma_f32 v139, v123, v139, v134
	v_mul_f32_e32 v138, v138, v139
	s_nop 0
	v_cvt_pk_bf16_f32 v142, v138, v138
	v_or_b32_e32 v138, 0x440, v0
	v_mov_b32_e32 v139, v1
	v_lshl_add_u64 v[138:139], v[138:139], 1, s[6:7]
	global_store_short_d16_hi v[138:139], v142, off
	v_fma_f32 v139, v120, v140, v137
	v_fma_f32 v142, v116, v140, v136
	v_mul_f32_e32 v139, v139, v142
	s_nop 0
	v_or_b32_e32 v138, 0x800, v0
	v_cvt_pk_bf16_f32 v142, v139, v139
	v_mov_b32_e32 v139, v1
	v_lshl_add_u64 v[138:139], v[138:139], 1, s[6:7]
	global_store_short_d16_hi v[138:139], v142, off
	v_fma_f32 v138, v128, v140, v135
	v_fma_f32 v139, v124, v140, v134
	v_mul_f32_e32 v138, v138, v139
	s_nop 0
	v_cvt_pk_bf16_f32 v140, v138, v138
	v_or_b32_e32 v138, 0x840, v0
	v_mov_b32_e32 v139, v1
	v_lshl_add_u64 v[138:139], v[138:139], 1, s[6:7]
	global_store_short_d16_hi v[138:139], v140, off
	v_fma_f32 v139, v121, v141, v137
	v_fma_f32 v140, v117, v141, v136
	v_mul_f32_e32 v139, v139, v140
	s_nop 0
	v_or_b32_e32 v138, 0xc00, v0
	v_cvt_pk_bf16_f32 v140, v139, v139
	v_mov_b32_e32 v139, v1
	v_lshl_add_u64 v[138:139], v[138:139], 1, s[6:7]
	global_store_short_d16_hi v[138:139], v140, off
	v_fma_f32 v138, v129, v141, v135
	v_fma_f32 v139, v125, v141, v134
	v_mul_f32_e32 v138, v138, v139
	s_nop 0
	v_cvt_pk_bf16_f32 v140, v138, v138
	v_or_b32_e32 v138, 0xc40, v0
	v_mov_b32_e32 v139, v1
	v_lshl_add_u64 v[138:139], v[138:139], 1, s[6:7]
	global_store_short_d16_hi v[138:139], v140, off
	ds_read_b128 v[138:141], v130 offset:64
	v_or_b32_e32 v142, 0x4000, v0
	v_mov_b32_e32 v143, v1
	v_lshl_add_u64 v[142:143], v[142:143], 1, s[6:7]
	s_waitcnt lgkmcnt(0)
	v_fma_f32 v144, v102, v138, v137
	v_fma_f32 v145, v98, v138, v136
	v_mul_f32_e32 v144, v144, v145
	s_nop 0
	v_cvt_pk_bf16_f32 v144, v144, v144
	global_store_short_d16_hi v[142:143], v144, off
	v_fma_f32 v142, v110, v138, v135
	v_fma_f32 v138, v106, v138, v134
	v_mul_f32_e32 v138, v142, v138
	s_nop 0
	v_cvt_pk_bf16_f32 v138, v138, v138
	v_or_b32_e32 v142, 0x4040, v0
	v_mov_b32_e32 v143, v1
	v_lshl_add_u64 v[142:143], v[142:143], 1, s[6:7]
	global_store_short_d16_hi v[142:143], v138, off
	v_fma_f32 v138, v103, v139, v137
	v_fma_f32 v143, v99, v139, v136
	v_mul_f32_e32 v138, v138, v143
	s_nop 0
	v_or_b32_e32 v142, 0x4400, v0
	v_cvt_pk_bf16_f32 v138, v138, v138
	v_mov_b32_e32 v143, v1
	v_lshl_add_u64 v[142:143], v[142:143], 1, s[6:7]
	global_store_short_d16_hi v[142:143], v138, off
	v_fma_f32 v138, v111, v139, v135
	v_fma_f32 v139, v107, v139, v134
	v_mul_f32_e32 v138, v138, v139
	s_nop 0
	v_cvt_pk_bf16_f32 v142, v138, v138
	v_or_b32_e32 v138, 0x4440, v0
	v_mov_b32_e32 v139, v1
	v_lshl_add_u64 v[138:139], v[138:139], 1, s[6:7]
	global_store_short_d16_hi v[138:139], v142, off
	v_fma_f32 v139, v104, v140, v137
	v_fma_f32 v142, v100, v140, v136
	v_mul_f32_e32 v139, v139, v142
	s_nop 0
	v_or_b32_e32 v138, 0x4800, v0
	v_cvt_pk_bf16_f32 v142, v139, v139
	v_mov_b32_e32 v139, v1
	v_lshl_add_u64 v[138:139], v[138:139], 1, s[6:7]
	global_store_short_d16_hi v[138:139], v142, off
	v_fma_f32 v138, v112, v140, v135
	v_fma_f32 v139, v108, v140, v134
	v_mul_f32_e32 v138, v138, v139
	s_nop 0
	v_cvt_pk_bf16_f32 v140, v138, v138
	v_or_b32_e32 v138, 0x4840, v0
	v_mov_b32_e32 v139, v1
	v_lshl_add_u64 v[138:139], v[138:139], 1, s[6:7]
	global_store_short_d16_hi v[138:139], v140, off
	v_fma_f32 v139, v105, v141, v137
	v_fma_f32 v140, v101, v141, v136
	v_mul_f32_e32 v139, v139, v140
	s_nop 0
	v_or_b32_e32 v138, 0x4c00, v0
	v_cvt_pk_bf16_f32 v140, v139, v139
	v_mov_b32_e32 v139, v1
	v_lshl_add_u64 v[138:139], v[138:139], 1, s[6:7]
	global_store_short_d16_hi v[138:139], v140, off
	v_fma_f32 v138, v113, v141, v135
	v_fma_f32 v139, v109, v141, v134
	v_mul_f32_e32 v138, v138, v139
	s_nop 0
	v_cvt_pk_bf16_f32 v140, v138, v138
	v_or_b32_e32 v138, 0x4c40, v0
	v_mov_b32_e32 v139, v1
	v_lshl_add_u64 v[138:139], v[138:139], 1, s[6:7]
	global_store_short_d16_hi v[138:139], v140, off
	ds_read_b128 v[138:141], v130 offset:128
	v_or_b32_e32 v142, 0x8000, v0
	v_mov_b32_e32 v143, v1
	v_lshl_add_u64 v[142:143], v[142:143], 1, s[6:7]
	s_waitcnt lgkmcnt(0)
; #define SCHED __builtin_amdgcn_sched_barrier(0)
; template <int EPI, bool HS = false>
; __device__ __forceinline__ void gemm_phase(const Params& p, const GemmCfg& g, char* shm, const int wave_s) {
;     ...
;         u16* ot = g.o16 + (size_t)TOK * 1024 + (size_t)orow0 * 1024 + (pn - 4) * 128;
;         const unsigned tb = (unsigned)((wr * 64 + fq * 4) * 1024 + wc * 16 + fr);
; #pragma unroll
;         for (int ai = 0; ai < 2; ++ai)
; #pragma unroll
;           for (int m = 0; m < 4; ++m) {
;             const f32x4 r4 = *(const f32x4*)(rsw + ai * 128 + m * 16);
; #pragma unroll
;             for (int j = 0; j < 4; ++j)
; #pragma unroll
;               for (int bj = 0; bj < 2; ++bj)
;                 ot[tb + (ai * 128 + m * 16 + j) * 1024 + bj * 64] =
;                     f2bf((r4[j] * acc[ai][bj][m][0][j] + swv[bj][0]) * (r4[j] * acc[ai][bj][m][1][j] + swv[bj][1]));
;             SCHED;
;           }
	v_fma_f32 v144, v86, v138, v137
	v_fma_f32 v145, v82, v138, v136
	v_mul_f32_e32 v144, v144, v145
	s_nop 0
	v_cvt_pk_bf16_f32 v144, v144, v144
	global_store_short_d16_hi v[142:143], v144, off
	v_fma_f32 v142, v94, v138, v135
	v_fma_f32 v138, v90, v138, v134
	v_mul_f32_e32 v138, v142, v138
	s_nop 0
	v_cvt_pk_bf16_f32 v138, v138, v138
	v_or_b32_e32 v142, 0x8040, v0
	v_mov_b32_e32 v143, v1
	v_lshl_add_u64 v[142:143], v[142:143], 1, s[6:7]
	global_store_short_d16_hi v[142:143], v138, off
	v_fma_f32 v138, v87, v139, v137
	v_fma_f32 v143, v83, v139, v136
	v_mul_f32_e32 v138, v138, v143
	s_nop 0
	v_or_b32_e32 v142, 0x8400, v0
	v_cvt_pk_bf16_f32 v138, v138, v138
	v_mov_b32_e32 v143, v1
	v_lshl_add_u64 v[142:143], v[142:143], 1, s[6:7]
	global_store_short_d16_hi v[142:143], v138, off
	v_fma_f32 v138, v95, v139, v135
	v_fma_f32 v139, v91, v139, v134
	v_mul_f32_e32 v138, v138, v139
	s_nop 0
	v_cvt_pk_bf16_f32 v142, v138, v138
	v_or_b32_e32 v138, 0x8440, v0
	v_mov_b32_e32 v139, v1
	v_lshl_add_u64 v[138:139], v[138:139], 1, s[6:7]
	global_store_short_d16_hi v[138:139], v142, off
	v_fma_f32 v139, v88, v140, v137
	v_fma_f32 v142, v84, v140, v136
	v_mul_f32_e32 v139, v139, v142
	s_nop 0
	v_or_b32_e32 v138, 0x8800, v0
	v_cvt_pk_bf16_f32 v142, v139, v139
	v_mov_b32_e32 v139, v1
	v_lshl_add_u64 v[138:139], v[138:139], 1, s[6:7]
	global_store_short_d16_hi v[138:139], v142, off
	v_fma_f32 v138, v96, v140, v135
	v_fma_f32 v139, v92, v140, v134
	v_mul_f32_e32 v138, v138, v139
	s_nop 0
	v_cvt_pk_bf16_f32 v140, v138, v138
	v_or_b32_e32 v138, 0x8840, v0
	v_mov_b32_e32 v139, v1
	v_lshl_add_u64 v[138:139], v[138:139], 1, s[6:7]
	global_store_short_d16_hi v[138:139], v140, off
	v_fma_f32 v139, v89, v141, v137
	v_fma_f32 v140, v85, v141, v136
	v_mul_f32_e32 v139, v139, v140
	s_nop 0
	v_or_b32_e32 v138, 0x8c00, v0
	v_cvt_pk_bf16_f32 v140, v139, v139
	v_mov_b32_e32 v139, v1
	v_lshl_add_u64 v[138:139], v[138:139], 1, s[6:7]
	global_store_short_d16_hi v[138:139], v140, off
	v_fma_f32 v138, v97, v141, v135
	v_fma_f32 v139, v93, v141, v134
	v_mul_f32_e32 v138, v138, v139
	s_nop 0
	v_cvt_pk_bf16_f32 v140, v138, v138
	v_or_b32_e32 v138, 0x8c40, v0
	v_mov_b32_e32 v139, v1
	v_lshl_add_u64 v[138:139], v[138:139], 1, s[6:7]
	global_store_short_d16_hi v[138:139], v140, off
	ds_read_b128 v[138:141], v130 offset:192
	v_or_b32_e32 v142, 0xc000, v0
	v_mov_b32_e32 v143, v1
	v_lshl_add_u64 v[142:143], v[142:143], 1, s[6:7]
	s_waitcnt lgkmcnt(0)
	v_fma_f32 v144, v70, v138, v137
	v_fma_f32 v145, v66, v138, v136
	v_mul_f32_e32 v144, v144, v145
	s_nop 0
	v_cvt_pk_bf16_f32 v144, v144, v144
	global_store_short_d16_hi v[142:143], v144, off
	v_fma_f32 v142, v78, v138, v135
	v_fma_f32 v138, v74, v138, v134
	v_mul_f32_e32 v138, v142, v138
	s_nop 0
	v_cvt_pk_bf16_f32 v138, v138, v138
	v_or_b32_e32 v142, 0xc040, v0
	v_mov_b32_e32 v143, v1
	v_lshl_add_u64 v[142:143], v[142:143], 1, s[6:7]
	global_store_short_d16_hi v[142:143], v138, off
	v_fma_f32 v138, v71, v139, v137
	v_fma_f32 v143, v67, v139, v136
	v_mul_f32_e32 v138, v138, v143
	s_nop 0
	v_or_b32_e32 v142, 0xc400, v0
	v_cvt_pk_bf16_f32 v138, v138, v138
	v_mov_b32_e32 v143, v1
	v_lshl_add_u64 v[142:143], v[142:143], 1, s[6:7]
	global_store_short_d16_hi v[142:143], v138, off
	v_fma_f32 v138, v79, v139, v135
	v_fma_f32 v139, v75, v139, v134
	v_mul_f32_e32 v138, v138, v139
	s_nop 0
	v_cvt_pk_bf16_f32 v142, v138, v138
	v_or_b32_e32 v138, 0xc440, v0
	v_mov_b32_e32 v139, v1
	v_lshl_add_u64 v[138:139], v[138:139], 1, s[6:7]
	global_store_short_d16_hi v[138:139], v142, off
	v_fma_f32 v139, v72, v140, v137
	v_fma_f32 v142, v68, v140, v136
	v_mul_f32_e32 v139, v139, v142
	s_nop 0
	v_or_b32_e32 v138, 0xc800, v0
	v_cvt_pk_bf16_f32 v142, v139, v139
	v_mov_b32_e32 v139, v1
	v_lshl_add_u64 v[138:139], v[138:139], 1, s[6:7]
	global_store_short_d16_hi v[138:139], v142, off
	v_fma_f32 v138, v80, v140, v135
	v_fma_f32 v139, v76, v140, v134
	v_mul_f32_e32 v138, v138, v139
	s_nop 0
	v_cvt_pk_bf16_f32 v140, v138, v138
	v_or_b32_e32 v138, 0xc840, v0
	v_mov_b32_e32 v139, v1
	v_lshl_add_u64 v[138:139], v[138:139], 1, s[6:7]
	global_store_short_d16_hi v[138:139], v140, off
	v_fma_f32 v139, v73, v141, v137
	v_fma_f32 v140, v69, v141, v136
	v_mul_f32_e32 v139, v139, v140
	s_nop 0
	v_or_b32_e32 v138, 0xcc00, v0
	v_cvt_pk_bf16_f32 v140, v139, v139
	v_mov_b32_e32 v139, v1
	v_lshl_add_u64 v[138:139], v[138:139], 1, s[6:7]
	global_store_short_d16_hi v[138:139], v140, off
	v_fma_f32 v138, v81, v141, v135
	v_fma_f32 v139, v77, v141, v134
	v_mul_f32_e32 v138, v138, v139
	s_nop 0
	v_cvt_pk_bf16_f32 v140, v138, v138
	v_or_b32_e32 v138, 0xcc40, v0
	v_mov_b32_e32 v139, v1
	v_lshl_add_u64 v[138:139], v[138:139], 1, s[6:7]
	global_store_short_d16_hi v[138:139], v140, off
	ds_read_b128 v[138:141], v130 offset:512
	v_add_u32_e32 v142, 0x20000, v0
	v_mov_b32_e32 v143, v1
	v_lshl_add_u64 v[142:143], v[142:143], 1, s[6:7]
	s_waitcnt lgkmcnt(0)
; #define SCHED __builtin_amdgcn_sched_barrier(0)
; template <int EPI, bool HS = false>
; __device__ __forceinline__ void gemm_phase(const Params& p, const GemmCfg& g, char* shm, const int wave_s) {
;     ...
;         u16* ot = g.o16 + (size_t)TOK * 1024 + (size_t)orow0 * 1024 + (pn - 4) * 128;
;         const unsigned tb = (unsigned)((wr * 64 + fq * 4) * 1024 + wc * 16 + fr);
; #pragma unroll
;         for (int ai = 0; ai < 2; ++ai)
; #pragma unroll
;           for (int m = 0; m < 4; ++m) {
;             const f32x4 r4 = *(const f32x4*)(rsw + ai * 128 + m * 16);
; #pragma unroll
;             for (int j = 0; j < 4; ++j)
; #pragma unroll
;               for (int bj = 0; bj < 2; ++bj)
;                 ot[tb + (ai * 128 + m * 16 + j) * 1024 + bj * 64] =
;                     f2bf((r4[j] * acc[ai][bj][m][0][j] + swv[bj][0]) * (r4[j] * acc[ai][bj][m][1][j] + swv[bj][1]));
;             SCHED;
;           }
	v_fma_f32 v144, v58, v138, v137
	v_fma_f32 v145, v50, v138, v136
	v_mul_f32_e32 v144, v144, v145
	s_nop 0
	v_cvt_pk_bf16_f32 v144, v144, v144
	global_store_short_d16_hi v[142:143], v144, off
	v_fma_f32 v142, v62, v138, v135
	v_fma_f32 v138, v54, v138, v134
	v_mul_f32_e32 v138, v142, v138
	s_nop 0
	v_cvt_pk_bf16_f32 v138, v138, v138
	v_add_u32_e32 v142, 0x20040, v0
	v_mov_b32_e32 v143, v1
	v_lshl_add_u64 v[142:143], v[142:143], 1, s[6:7]
	global_store_short_d16_hi v[142:143], v138, off
	v_fma_f32 v138, v59, v139, v137
	v_fma_f32 v143, v51, v139, v136
	v_mul_f32_e32 v138, v138, v143
	s_nop 0
	v_add_u32_e32 v142, 0x20400, v0
	v_cvt_pk_bf16_f32 v138, v138, v138
	v_mov_b32_e32 v143, v1
	v_lshl_add_u64 v[142:143], v[142:143], 1, s[6:7]
	global_store_short_d16_hi v[142:143], v138, off
	v_fma_f32 v138, v63, v139, v135
	v_fma_f32 v139, v55, v139, v134
	v_mul_f32_e32 v138, v138, v139
	s_nop 0
	v_cvt_pk_bf16_f32 v142, v138, v138
	v_add_u32_e32 v138, 0x20440, v0
	v_mov_b32_e32 v139, v1
	v_lshl_add_u64 v[138:139], v[138:139], 1, s[6:7]
	global_store_short_d16_hi v[138:139], v142, off
	v_fma_f32 v139, v60, v140, v137
	v_fma_f32 v142, v52, v140, v136
	v_mul_f32_e32 v139, v139, v142
	s_nop 0
	v_add_u32_e32 v138, 0x20800, v0
	v_cvt_pk_bf16_f32 v142, v139, v139
	v_mov_b32_e32 v139, v1
	v_lshl_add_u64 v[138:139], v[138:139], 1, s[6:7]
	global_store_short_d16_hi v[138:139], v142, off
	v_fma_f32 v138, v64, v140, v135
	v_fma_f32 v139, v56, v140, v134
	v_mul_f32_e32 v138, v138, v139
	s_nop 0
	v_cvt_pk_bf16_f32 v140, v138, v138
	v_add_u32_e32 v138, 0x20840, v0
	v_mov_b32_e32 v139, v1
	v_lshl_add_u64 v[138:139], v[138:139], 1, s[6:7]
	global_store_short_d16_hi v[138:139], v140, off
	v_fma_f32 v139, v61, v141, v137
	v_fma_f32 v140, v53, v141, v136
	v_mul_f32_e32 v139, v139, v140
	s_nop 0
	v_add_u32_e32 v138, 0x20c00, v0
	v_cvt_pk_bf16_f32 v140, v139, v139
	v_mov_b32_e32 v139, v1
	v_lshl_add_u64 v[138:139], v[138:139], 1, s[6:7]
	global_store_short_d16_hi v[138:139], v140, off
	v_fma_f32 v138, v65, v141, v135
	v_fma_f32 v139, v57, v141, v134
	v_mul_f32_e32 v138, v138, v139
	s_nop 0
	v_cvt_pk_bf16_f32 v140, v138, v138
	v_add_u32_e32 v138, 0x20c40, v0
	v_mov_b32_e32 v139, v1
	v_lshl_add_u64 v[138:139], v[138:139], 1, s[6:7]
	global_store_short_d16_hi v[138:139], v140, off
	ds_read_b128 v[138:141], v130 offset:576
	v_add_u32_e32 v142, 0x24000, v0
	v_mov_b32_e32 v143, v1
	v_lshl_add_u64 v[142:143], v[142:143], 1, s[6:7]
	s_waitcnt lgkmcnt(0)
	v_fma_f32 v144, v42, v138, v137
	v_fma_f32 v145, v34, v138, v136
	v_mul_f32_e32 v144, v144, v145
	s_nop 0
	v_cvt_pk_bf16_f32 v144, v144, v144
	global_store_short_d16_hi v[142:143], v144, off
	v_fma_f32 v142, v46, v138, v135
	v_fma_f32 v138, v38, v138, v134
	v_mul_f32_e32 v138, v142, v138
	s_nop 0
	v_cvt_pk_bf16_f32 v138, v138, v138
	v_add_u32_e32 v142, 0x24040, v0
	v_mov_b32_e32 v143, v1
	v_lshl_add_u64 v[142:143], v[142:143], 1, s[6:7]
	global_store_short_d16_hi v[142:143], v138, off
	v_fma_f32 v138, v43, v139, v137
	v_fma_f32 v143, v35, v139, v136
	v_mul_f32_e32 v138, v138, v143
	s_nop 0
	v_add_u32_e32 v142, 0x24400, v0
	v_cvt_pk_bf16_f32 v138, v138, v138
	v_mov_b32_e32 v143, v1
	v_lshl_add_u64 v[142:143], v[142:143], 1, s[6:7]
	global_store_short_d16_hi v[142:143], v138, off
	v_fma_f32 v138, v47, v139, v135
	v_fma_f32 v139, v39, v139, v134
	v_mul_f32_e32 v138, v138, v139
	s_nop 0
	v_cvt_pk_bf16_f32 v142, v138, v138
	v_add_u32_e32 v138, 0x24440, v0
	v_mov_b32_e32 v139, v1
	v_lshl_add_u64 v[138:139], v[138:139], 1, s[6:7]
	global_store_short_d16_hi v[138:139], v142, off
	v_fma_f32 v139, v44, v140, v137
	v_fma_f32 v142, v36, v140, v136
	v_mul_f32_e32 v139, v139, v142
	s_nop 0
	v_add_u32_e32 v138, 0x24800, v0
	v_cvt_pk_bf16_f32 v142, v139, v139
	v_mov_b32_e32 v139, v1
	v_lshl_add_u64 v[138:139], v[138:139], 1, s[6:7]
	global_store_short_d16_hi v[138:139], v142, off
	v_fma_f32 v138, v48, v140, v135
	v_fma_f32 v139, v40, v140, v134
	v_mul_f32_e32 v138, v138, v139
	s_nop 0
	v_cvt_pk_bf16_f32 v140, v138, v138
	v_add_u32_e32 v138, 0x24840, v0
	v_mov_b32_e32 v139, v1
	v_lshl_add_u64 v[138:139], v[138:139], 1, s[6:7]
	global_store_short_d16_hi v[138:139], v140, off
	v_fma_f32 v139, v45, v141, v137
	v_fma_f32 v140, v37, v141, v136
	v_mul_f32_e32 v139, v139, v140
	s_nop 0
	v_add_u32_e32 v138, 0x24c00, v0
	v_cvt_pk_bf16_f32 v140, v139, v139
	v_mov_b32_e32 v139, v1
	v_lshl_add_u64 v[138:139], v[138:139], 1, s[6:7]
	global_store_short_d16_hi v[138:139], v140, off
	v_fma_f32 v138, v49, v141, v135
	v_fma_f32 v139, v41, v141, v134
	v_mul_f32_e32 v138, v138, v139
	s_nop 0
	v_cvt_pk_bf16_f32 v140, v138, v138
	v_add_u32_e32 v138, 0x24c40, v0
	v_mov_b32_e32 v139, v1
	v_lshl_add_u64 v[138:139], v[138:139], 1, s[6:7]
	global_store_short_d16_hi v[138:139], v140, off
	ds_read_b128 v[138:141], v130 offset:640
	v_add_u32_e32 v142, 0x28000, v0
	v_mov_b32_e32 v143, v1
	v_lshl_add_u64 v[142:143], v[142:143], 1, s[6:7]
	s_waitcnt lgkmcnt(0)
; #define SCHED __builtin_amdgcn_sched_barrier(0)
; template <int EPI, bool HS = false>
; __device__ __forceinline__ void gemm_phase(const Params& p, const GemmCfg& g, char* shm, const int wave_s) {
;     ...
;         u16* ot = g.o16 + (size_t)TOK * 1024 + (size_t)orow0 * 1024 + (pn - 4) * 128;
;         const unsigned tb = (unsigned)((wr * 64 + fq * 4) * 1024 + wc * 16 + fr);
; #pragma unroll
;         for (int ai = 0; ai < 2; ++ai)
; #pragma unroll
;           for (int m = 0; m < 4; ++m) {
;             const f32x4 r4 = *(const f32x4*)(rsw + ai * 128 + m * 16);
; #pragma unroll
;             for (int j = 0; j < 4; ++j)
; #pragma unroll
;               for (int bj = 0; bj < 2; ++bj)
;                 ot[tb + (ai * 128 + m * 16 + j) * 1024 + bj * 64] =
;                     f2bf((r4[j] * acc[ai][bj][m][0][j] + swv[bj][0]) * (r4[j] * acc[ai][bj][m][1][j] + swv[bj][1]));
;             SCHED;
;           }
	v_fma_f32 v144, v26, v138, v137
	v_fma_f32 v145, v18, v138, v136
	v_mul_f32_e32 v144, v144, v145
	s_nop 0
	v_cvt_pk_bf16_f32 v144, v144, v144
	global_store_short_d16_hi v[142:143], v144, off
	v_fma_f32 v142, v30, v138, v135
	v_fma_f32 v138, v22, v138, v134
	v_mul_f32_e32 v138, v142, v138
	s_nop 0
	v_cvt_pk_bf16_f32 v138, v138, v138
	v_add_u32_e32 v142, 0x28040, v0
	v_mov_b32_e32 v143, v1
	v_lshl_add_u64 v[142:143], v[142:143], 1, s[6:7]
	global_store_short_d16_hi v[142:143], v138, off
	v_fma_f32 v138, v27, v139, v137
	v_fma_f32 v143, v19, v139, v136
	v_mul_f32_e32 v138, v138, v143
	s_nop 0
	v_add_u32_e32 v142, 0x28400, v0
	v_cvt_pk_bf16_f32 v138, v138, v138
	v_mov_b32_e32 v143, v1
	v_lshl_add_u64 v[142:143], v[142:143], 1, s[6:7]
	global_store_short_d16_hi v[142:143], v138, off
	v_fma_f32 v138, v31, v139, v135
	v_fma_f32 v139, v23, v139, v134
	v_mul_f32_e32 v138, v138, v139
	s_nop 0
	v_cvt_pk_bf16_f32 v142, v138, v138
	v_add_u32_e32 v138, 0x28440, v0
	v_mov_b32_e32 v139, v1
	v_lshl_add_u64 v[138:139], v[138:139], 1, s[6:7]
	global_store_short_d16_hi v[138:139], v142, off
	v_fma_f32 v139, v28, v140, v137
	v_fma_f32 v142, v20, v140, v136
	v_mul_f32_e32 v139, v139, v142
	s_nop 0
	v_add_u32_e32 v138, 0x28800, v0
	v_cvt_pk_bf16_f32 v142, v139, v139
	v_mov_b32_e32 v139, v1
	v_lshl_add_u64 v[138:139], v[138:139], 1, s[6:7]
	global_store_short_d16_hi v[138:139], v142, off
	v_fma_f32 v138, v32, v140, v135
	v_fma_f32 v139, v24, v140, v134
	v_mul_f32_e32 v138, v138, v139
	s_nop 0
	v_cvt_pk_bf16_f32 v140, v138, v138
	v_add_u32_e32 v138, 0x28840, v0
	v_mov_b32_e32 v139, v1
	v_lshl_add_u64 v[138:139], v[138:139], 1, s[6:7]
	global_store_short_d16_hi v[138:139], v140, off
	v_fma_f32 v139, v29, v141, v137
	v_fma_f32 v140, v21, v141, v136
	v_mul_f32_e32 v139, v139, v140
	s_nop 0
	v_add_u32_e32 v138, 0x28c00, v0
	v_cvt_pk_bf16_f32 v140, v139, v139
	v_mov_b32_e32 v139, v1
	v_lshl_add_u64 v[138:139], v[138:139], 1, s[6:7]
	global_store_short_d16_hi v[138:139], v140, off
	v_fma_f32 v138, v33, v141, v135
	v_fma_f32 v139, v25, v141, v134
	v_mul_f32_e32 v138, v138, v139
	s_nop 0
	v_cvt_pk_bf16_f32 v140, v138, v138
	v_add_u32_e32 v138, 0x28c40, v0
	v_mov_b32_e32 v139, v1
	v_lshl_add_u64 v[138:139], v[138:139], 1, s[6:7]
	global_store_short_d16_hi v[138:139], v140, off
	ds_read_b128 v[138:141], v130 offset:704
	v_add_u32_e32 v142, 0x2c000, v0
	v_mov_b32_e32 v143, v1
	v_lshl_add_u64 v[142:143], v[142:143], 1, s[6:7]
	s_waitcnt lgkmcnt(0)
	v_fma_f32 v144, v10, v138, v137
	v_fma_f32 v145, v2, v138, v136
	v_mul_f32_e32 v144, v144, v145
	v_bfe_u32 v145, v144, 16, 1
	v_add3_u32 v144, v144, v145, s81
	global_store_short_d16_hi v[142:143], v144, off
	v_fma_f32 v142, v14, v138, v135
	v_fma_f32 v138, v6, v138, v134
	v_mul_f32_e32 v138, v142, v138
	s_nop 0
	v_cvt_pk_bf16_f32 v138, v138, v138
	v_add_u32_e32 v142, 0x2c040, v0
	v_mov_b32_e32 v143, v1
	v_lshl_add_u64 v[142:143], v[142:143], 1, s[6:7]
	global_store_short_d16_hi v[142:143], v138, off
	v_fma_f32 v138, v11, v139, v137
	v_fma_f32 v143, v3, v139, v136
	v_mul_f32_e32 v138, v138, v143
	s_nop 0
	v_add_u32_e32 v142, 0x2c400, v0
	v_cvt_pk_bf16_f32 v138, v138, v138
	v_mov_b32_e32 v143, v1
	v_lshl_add_u64 v[142:143], v[142:143], 1, s[6:7]
	global_store_short_d16_hi v[142:143], v138, off
	v_fma_f32 v138, v15, v139, v135
	v_fma_f32 v139, v7, v139, v134
	v_mul_f32_e32 v138, v138, v139
	s_nop 0
	v_cvt_pk_bf16_f32 v142, v138, v138
	v_add_u32_e32 v138, 0x2c440, v0
	v_mov_b32_e32 v139, v1
	v_lshl_add_u64 v[138:139], v[138:139], 1, s[6:7]
	global_store_short_d16_hi v[138:139], v142, off
	v_fma_f32 v139, v12, v140, v137
	v_fma_f32 v142, v4, v140, v136
	v_mul_f32_e32 v139, v139, v142
	v_bfe_u32 v142, v139, 16, 1
	v_add_u32_e32 v138, 0x2c800, v0
	v_add3_u32 v142, v139, v142, s81
	v_mov_b32_e32 v139, v1
	v_lshl_add_u64 v[138:139], v[138:139], 1, s[6:7]
	global_store_short_d16_hi v[138:139], v142, off
	v_fma_f32 v138, v16, v140, v135
	v_fma_f32 v139, v8, v140, v134
	v_mul_f32_e32 v138, v138, v139
	s_nop 0
	v_cvt_pk_bf16_f32 v140, v138, v138
	v_add_u32_e32 v138, 0x2c840, v0
	v_mov_b32_e32 v139, v1
	v_lshl_add_u64 v[138:139], v[138:139], 1, s[6:7]
	global_store_short_d16_hi v[138:139], v140, off
	v_fma_f32 v139, v13, v141, v137
	v_fma_f32 v140, v5, v141, v136
	v_mul_f32_e32 v139, v139, v140
	s_nop 0
	v_add_u32_e32 v138, 0x2cc00, v0
	v_cvt_pk_bf16_f32 v140, v139, v139
	v_mov_b32_e32 v139, v1
	v_lshl_add_u64 v[138:139], v[138:139], 1, s[6:7]
	global_store_short_d16_hi v[138:139], v140, off
	v_fma_f32 v138, v17, v141, v135
	v_fma_f32 v139, v9, v141, v134
	v_mul_f32_e32 v138, v138, v139
	v_bfe_u32 v139, v138, 16, 1
	v_add_u32_e32 v0, 0x2cc40, v0
	v_add3_u32 v140, v138, v139, s81
	v_lshl_add_u64 v[138:139], v[0:1], 1, s[6:7]
	global_store_short_d16_hi v[138:139], v140, off
	s_cbranch_execnz .LBB0_312
; #define SCHED __builtin_amdgcn_sched_barrier(0)
; template <int EPI, bool HS = false>
; __device__ __forceinline__ void gemm_phase(const Params& p, const GemmCfg& g, char* shm, const int wave_s) {
;     ...
;       if (pn < 4) {
;         u16* ot = g.o16 + (size_t)orow0 * 1024 + pn * 256;
;         const unsigned tb = (unsigned)((wr * 64 + fq * 4) * 1024 + wc * 32 + fr);
; #pragma unroll
;         for (int ai = 0; ai < 2; ++ai)
; #pragma unroll
;           for (int m = 0; m < 4; ++m) {
;             const f32x4 r4 = *(const f32x4*)(rsw + ai * 128 + m * 16);
; #pragma unroll
;             for (int j = 0; j < 4; ++j)
; #pragma unroll
;               for (int bj = 0; bj < 2; ++bj)
; #pragma unroll
;                 for (int n = 0; n < 2; ++n)
;                   ot[tb + (ai * 128 + m * 16 + j) * 1024 + bj * 128 + n * 16] = f2bf(r4[j] * acc[ai][bj][m][n][j] + swv[bj][n]);
;             SCHED;
;           }
.LBB0_326:
	ds_read_b128 v[138:141], v130
	s_ashr_i32 s3, s2, 31
	s_lshl_b64 s[2:3], s[2:3], 1
	s_add_u32 s2, s8, s2
	v_lshlrev_b32_e32 v0, 5, v131
	s_waitcnt lgkmcnt(0)
	v_fma_f32 v118, v118, v138, v137
	s_addc_u32 s3, s9, s3
	v_or3_b32 v0, v133, v0, v132
	v_bfe_u32 v131, v118, 16, 1
	v_add3_u32 v118, v118, v131, s81
	v_lshl_add_u64 v[132:133], v[0:1], 1, s[2:3]
	v_fma_f32 v114, v114, v138, v136
	global_store_short_d16_hi v[132:133], v118, off
	s_nop 0
	v_cvt_pk_bf16_f32 v114, v114, v114
	global_store_short_d16_hi v[132:133], v114, off offset:32
	v_fma_f32 v114, v126, v138, v135
	s_nop 0
	v_cvt_pk_bf16_f32 v114, v114, v114
	global_store_short_d16_hi v[132:133], v114, off offset:256
	v_fma_f32 v114, v122, v138, v134
	s_nop 0
	v_cvt_pk_bf16_f32 v114, v114, v114
	global_store_short_d16_hi v[132:133], v114, off offset:288
	v_fma_f32 v114, v119, v139, v137
	s_nop 0
	v_cvt_pk_bf16_f32 v114, v114, v114
	global_store_short_d16_hi v[132:133], v114, off offset:2048
	v_fma_f32 v114, v115, v139, v136
	s_nop 0
	v_cvt_pk_bf16_f32 v114, v114, v114
	global_store_short_d16_hi v[132:133], v114, off offset:2080
	v_fma_f32 v114, v127, v139, v135
	s_nop 0
	v_cvt_pk_bf16_f32 v114, v114, v114
	global_store_short_d16_hi v[132:133], v114, off offset:2304
	v_fma_f32 v114, v123, v139, v134
	s_nop 0
	v_cvt_pk_bf16_f32 v114, v114, v114
	v_fma_f32 v115, v120, v140, v137
	s_nop 0
	global_store_short_d16_hi v[132:133], v114, off offset:2336
	v_or_b32_e32 v114, 0x800, v0
	v_cvt_pk_bf16_f32 v118, v115, v115
	v_mov_b32_e32 v115, v1
	v_lshl_add_u64 v[114:115], v[114:115], 1, s[2:3]
	global_store_short_d16_hi v[114:115], v118, off
	v_fma_f32 v114, v116, v140, v136
	s_nop 0
	v_cvt_pk_bf16_f32 v116, v114, v114
	v_or_b32_e32 v114, 0x810, v0
	v_mov_b32_e32 v115, v1
	v_lshl_add_u64 v[114:115], v[114:115], 1, s[2:3]
	global_store_short_d16_hi v[114:115], v116, off
	v_fma_f32 v115, v128, v140, v135
	s_nop 0
	v_or_b32_e32 v114, 0x880, v0
	v_cvt_pk_bf16_f32 v116, v115, v115
	v_mov_b32_e32 v115, v1
	v_lshl_add_u64 v[114:115], v[114:115], 1, s[2:3]
	global_store_short_d16_hi v[114:115], v116, off
	v_fma_f32 v114, v124, v140, v134
	s_nop 0
	v_cvt_pk_bf16_f32 v116, v114, v114
	v_or_b32_e32 v114, 0x890, v0
	v_mov_b32_e32 v115, v1
	v_lshl_add_u64 v[114:115], v[114:115], 1, s[2:3]
	global_store_short_d16_hi v[114:115], v116, off
	v_fma_f32 v115, v121, v141, v137
	s_nop 0
	v_or_b32_e32 v114, 0xc00, v0
	v_cvt_pk_bf16_f32 v116, v115, v115
	v_mov_b32_e32 v115, v1
	v_lshl_add_u64 v[114:115], v[114:115], 1, s[2:3]
	global_store_short_d16_hi v[114:115], v116, off
	v_fma_f32 v114, v117, v141, v136
	s_nop 0
	v_cvt_pk_bf16_f32 v116, v114, v114
	v_or_b32_e32 v114, 0xc10, v0
	v_mov_b32_e32 v115, v1
	v_lshl_add_u64 v[114:115], v[114:115], 1, s[2:3]
	global_store_short_d16_hi v[114:115], v116, off
	v_fma_f32 v115, v129, v141, v135
	s_nop 0
	v_or_b32_e32 v114, 0xc80, v0
	v_cvt_pk_bf16_f32 v116, v115, v115
	v_mov_b32_e32 v115, v1
	v_lshl_add_u64 v[114:115], v[114:115], 1, s[2:3]
	global_store_short_d16_hi v[114:115], v116, off
	v_fma_f32 v114, v125, v141, v134
	s_nop 0
	v_cvt_pk_bf16_f32 v116, v114, v114
	v_or_b32_e32 v114, 0xc90, v0
	v_mov_b32_e32 v115, v1
	v_lshl_add_u64 v[114:115], v[114:115], 1, s[2:3]
	global_store_short_d16_hi v[114:115], v116, off
	ds_read_b128 v[114:117], v130 offset:64
	v_or_b32_e32 v118, 0x4000, v0
	v_mov_b32_e32 v119, v1
	v_lshl_add_u64 v[118:119], v[118:119], 1, s[2:3]
	s_waitcnt lgkmcnt(0)
	v_fma_f32 v102, v102, v114, v137
	v_bfe_u32 v120, v102, 16, 1
	v_fma_f32 v98, v98, v114, v136
	v_add3_u32 v102, v102, v120, s81
	global_store_short_d16_hi v[118:119], v102, off
	s_nop 0
	v_or_b32_e32 v118, 0x4010, v0
	v_mov_b32_e32 v119, v1
	v_cvt_pk_bf16_f32 v98, v98, v98
	v_lshl_add_u64 v[118:119], v[118:119], 1, s[2:3]
	global_store_short_d16_hi v[118:119], v98, off
	v_fma_f32 v98, v110, v114, v135
	v_or_b32_e32 v118, 0x4080, v0
	s_nop 0
	v_mov_b32_e32 v119, v1
	v_cvt_pk_bf16_f32 v98, v98, v98
	v_lshl_add_u64 v[118:119], v[118:119], 1, s[2:3]
	global_store_short_d16_hi v[118:119], v98, off
	v_fma_f32 v98, v106, v114, v134
	s_nop 0
	v_or_b32_e32 v118, 0x4090, v0
	v_mov_b32_e32 v119, v1
	v_cvt_pk_bf16_f32 v98, v98, v98
	v_lshl_add_u64 v[118:119], v[118:119], 1, s[2:3]
	global_store_short_d16_hi v[118:119], v98, off
	v_fma_f32 v98, v103, v115, v137
	s_nop 0
	v_or_b32_e32 v102, 0x4400, v0
	v_cvt_pk_bf16_f32 v98, v98, v98
	v_mov_b32_e32 v103, v1
	v_lshl_add_u64 v[102:103], v[102:103], 1, s[2:3]
	global_store_short_d16_hi v[102:103], v98, off
	v_fma_f32 v98, v99, v115, v136
	s_nop 0
	v_cvt_pk_bf16_f32 v102, v98, v98
	v_or_b32_e32 v98, 0x4410, v0
	v_mov_b32_e32 v99, v1
	v_lshl_add_u64 v[98:99], v[98:99], 1, s[2:3]
	global_store_short_d16_hi v[98:99], v102, off
	v_fma_f32 v99, v111, v115, v135
	s_nop 0
	v_or_b32_e32 v98, 0x4480, v0
	v_cvt_pk_bf16_f32 v102, v99, v99
	v_mov_b32_e32 v99, v1
	v_lshl_add_u64 v[98:99], v[98:99], 1, s[2:3]
	global_store_short_d16_hi v[98:99], v102, off
	v_fma_f32 v98, v107, v115, v134
	s_nop 0
	v_cvt_pk_bf16_f32 v102, v98, v98
	v_or_b32_e32 v98, 0x4490, v0
	v_mov_b32_e32 v99, v1
	v_lshl_add_u64 v[98:99], v[98:99], 1, s[2:3]
	global_store_short_d16_hi v[98:99], v102, off
	v_fma_f32 v99, v104, v116, v137
	s_nop 0
	v_or_b32_e32 v98, 0x4800, v0
	v_cvt_pk_bf16_f32 v102, v99, v99
	v_mov_b32_e32 v99, v1
	v_lshl_add_u64 v[98:99], v[98:99], 1, s[2:3]
	global_store_short_d16_hi v[98:99], v102, off
	v_fma_f32 v98, v100, v116, v136
	s_nop 0
	v_cvt_pk_bf16_f32 v100, v98, v98
	v_or_b32_e32 v98, 0x4810, v0
	v_mov_b32_e32 v99, v1
	v_lshl_add_u64 v[98:99], v[98:99], 1, s[2:3]
	global_store_short_d16_hi v[98:99], v100, off
	v_fma_f32 v99, v112, v116, v135
	s_nop 0
	v_or_b32_e32 v98, 0x4880, v0
; #define SCHED __builtin_amdgcn_sched_barrier(0)
; template <int EPI, bool HS = false>
; __device__ __forceinline__ void gemm_phase(const Params& p, const GemmCfg& g, char* shm, const int wave_s) {
;     ...
;       if (pn < 4) {
;         u16* ot = g.o16 + (size_t)orow0 * 1024 + pn * 256;
;         const unsigned tb = (unsigned)((wr * 64 + fq * 4) * 1024 + wc * 32 + fr);
; #pragma unroll
;         for (int ai = 0; ai < 2; ++ai)
; #pragma unroll
;           for (int m = 0; m < 4; ++m) {
;             const f32x4 r4 = *(const f32x4*)(rsw + ai * 128 + m * 16);
; #pragma unroll
;             for (int j = 0; j < 4; ++j)
; #pragma unroll
;               for (int bj = 0; bj < 2; ++bj)
; #pragma unroll
;                 for (int n = 0; n < 2; ++n)
;                   ot[tb + (ai * 128 + m * 16 + j) * 1024 + bj * 128 + n * 16] = f2bf(r4[j] * acc[ai][bj][m][n][j] + swv[bj][n]);
;             SCHED;
;           }
	v_cvt_pk_bf16_f32 v100, v99, v99
	v_mov_b32_e32 v99, v1
	v_lshl_add_u64 v[98:99], v[98:99], 1, s[2:3]
	global_store_short_d16_hi v[98:99], v100, off
	v_fma_f32 v98, v108, v116, v134
	s_nop 0
	v_cvt_pk_bf16_f32 v100, v98, v98
	v_or_b32_e32 v98, 0x4890, v0
	v_mov_b32_e32 v99, v1
	v_lshl_add_u64 v[98:99], v[98:99], 1, s[2:3]
	global_store_short_d16_hi v[98:99], v100, off
	v_fma_f32 v99, v105, v117, v137
	s_nop 0
	v_or_b32_e32 v98, 0x4c00, v0
	v_cvt_pk_bf16_f32 v100, v99, v99
	v_mov_b32_e32 v99, v1
	v_lshl_add_u64 v[98:99], v[98:99], 1, s[2:3]
	global_store_short_d16_hi v[98:99], v100, off
	v_fma_f32 v98, v101, v117, v136
	s_nop 0
	v_cvt_pk_bf16_f32 v100, v98, v98
	v_or_b32_e32 v98, 0x4c10, v0
	v_mov_b32_e32 v99, v1
	v_lshl_add_u64 v[98:99], v[98:99], 1, s[2:3]
	global_store_short_d16_hi v[98:99], v100, off
	v_fma_f32 v99, v113, v117, v135
	s_nop 0
	v_or_b32_e32 v98, 0x4c80, v0
	v_cvt_pk_bf16_f32 v100, v99, v99
	v_mov_b32_e32 v99, v1
	v_lshl_add_u64 v[98:99], v[98:99], 1, s[2:3]
	global_store_short_d16_hi v[98:99], v100, off
	v_fma_f32 v98, v109, v117, v134
	s_nop 0
	v_cvt_pk_bf16_f32 v100, v98, v98
	v_or_b32_e32 v98, 0x4c90, v0
	v_mov_b32_e32 v99, v1
	v_lshl_add_u64 v[98:99], v[98:99], 1, s[2:3]
	global_store_short_d16_hi v[98:99], v100, off
	ds_read_b128 v[98:101], v130 offset:128
	v_or_b32_e32 v102, 0x8000, v0
	v_mov_b32_e32 v103, v1
	v_lshl_add_u64 v[102:103], v[102:103], 1, s[2:3]
	s_waitcnt lgkmcnt(0)
	v_fma_f32 v86, v86, v98, v137
	v_bfe_u32 v104, v86, 16, 1
	v_fma_f32 v82, v82, v98, v136
	v_add3_u32 v86, v86, v104, s81
	global_store_short_d16_hi v[102:103], v86, off
	s_nop 0
	v_or_b32_e32 v102, 0x8010, v0
	v_mov_b32_e32 v103, v1
	v_cvt_pk_bf16_f32 v82, v82, v82
	v_lshl_add_u64 v[102:103], v[102:103], 1, s[2:3]
	global_store_short_d16_hi v[102:103], v82, off
	v_fma_f32 v82, v94, v98, v135
	v_or_b32_e32 v102, 0x8080, v0
	s_nop 0
	v_mov_b32_e32 v103, v1
	v_cvt_pk_bf16_f32 v82, v82, v82
	v_lshl_add_u64 v[102:103], v[102:103], 1, s[2:3]
	global_store_short_d16_hi v[102:103], v82, off
	v_fma_f32 v82, v90, v98, v134
	s_nop 0
	v_or_b32_e32 v102, 0x8090, v0
	v_mov_b32_e32 v103, v1
	v_cvt_pk_bf16_f32 v82, v82, v82
	v_lshl_add_u64 v[102:103], v[102:103], 1, s[2:3]
	global_store_short_d16_hi v[102:103], v82, off
	v_fma_f32 v82, v87, v99, v137
	s_nop 0
	v_or_b32_e32 v86, 0x8400, v0
	v_cvt_pk_bf16_f32 v82, v82, v82
	v_mov_b32_e32 v87, v1
	v_lshl_add_u64 v[86:87], v[86:87], 1, s[2:3]
	global_store_short_d16_hi v[86:87], v82, off
	v_fma_f32 v82, v83, v99, v136
	s_nop 0
	v_cvt_pk_bf16_f32 v86, v82, v82
	v_or_b32_e32 v82, 0x8410, v0
	v_mov_b32_e32 v83, v1
	v_lshl_add_u64 v[82:83], v[82:83], 1, s[2:3]
	global_store_short_d16_hi v[82:83], v86, off
	v_fma_f32 v83, v95, v99, v135
	s_nop 0
	v_or_b32_e32 v82, 0x8480, v0
	v_cvt_pk_bf16_f32 v86, v83, v83
	v_mov_b32_e32 v83, v1
	v_lshl_add_u64 v[82:83], v[82:83], 1, s[2:3]
	global_store_short_d16_hi v[82:83], v86, off
	v_fma_f32 v82, v91, v99, v134
	s_nop 0
	v_cvt_pk_bf16_f32 v86, v82, v82
	v_or_b32_e32 v82, 0x8490, v0
	v_mov_b32_e32 v83, v1
	v_lshl_add_u64 v[82:83], v[82:83], 1, s[2:3]
	global_store_short_d16_hi v[82:83], v86, off
	v_fma_f32 v83, v88, v100, v137
	s_nop 0
	v_or_b32_e32 v82, 0x8800, v0
	v_cvt_pk_bf16_f32 v86, v83, v83
	v_mov_b32_e32 v83, v1
	v_lshl_add_u64 v[82:83], v[82:83], 1, s[2:3]
	global_store_short_d16_hi v[82:83], v86, off
	v_fma_f32 v82, v84, v100, v136
	s_nop 0
	v_cvt_pk_bf16_f32 v84, v82, v82
	v_or_b32_e32 v82, 0x8810, v0
	v_mov_b32_e32 v83, v1
	v_lshl_add_u64 v[82:83], v[82:83], 1, s[2:3]
	global_store_short_d16_hi v[82:83], v84, off
	v_fma_f32 v83, v96, v100, v135
	s_nop 0
	v_or_b32_e32 v82, 0x8880, v0
	v_cvt_pk_bf16_f32 v84, v83, v83
	v_mov_b32_e32 v83, v1
	v_lshl_add_u64 v[82:83], v[82:83], 1, s[2:3]
	global_store_short_d16_hi v[82:83], v84, off
	v_fma_f32 v82, v92, v100, v134
	s_nop 0
	v_cvt_pk_bf16_f32 v84, v82, v82
	v_or_b32_e32 v82, 0x8890, v0
	v_mov_b32_e32 v83, v1
	v_lshl_add_u64 v[82:83], v[82:83], 1, s[2:3]
	global_store_short_d16_hi v[82:83], v84, off
	v_fma_f32 v83, v89, v101, v137
	s_nop 0
	v_or_b32_e32 v82, 0x8c00, v0
	v_cvt_pk_bf16_f32 v84, v83, v83
	v_mov_b32_e32 v83, v1
	v_lshl_add_u64 v[82:83], v[82:83], 1, s[2:3]
	global_store_short_d16_hi v[82:83], v84, off
	v_fma_f32 v82, v85, v101, v136
	s_nop 0
	v_cvt_pk_bf16_f32 v84, v82, v82
	v_or_b32_e32 v82, 0x8c10, v0
	v_mov_b32_e32 v83, v1
	v_lshl_add_u64 v[82:83], v[82:83], 1, s[2:3]
	global_store_short_d16_hi v[82:83], v84, off
	v_fma_f32 v83, v97, v101, v135
	s_nop 0
	v_or_b32_e32 v82, 0x8c80, v0
	v_cvt_pk_bf16_f32 v84, v83, v83
	v_mov_b32_e32 v83, v1
	v_lshl_add_u64 v[82:83], v[82:83], 1, s[2:3]
	global_store_short_d16_hi v[82:83], v84, off
	v_fma_f32 v82, v93, v101, v134
	s_nop 0
	v_cvt_pk_bf16_f32 v84, v82, v82
	v_or_b32_e32 v82, 0x8c90, v0
	v_mov_b32_e32 v83, v1
	v_lshl_add_u64 v[82:83], v[82:83], 1, s[2:3]
	global_store_short_d16_hi v[82:83], v84, off
	ds_read_b128 v[82:85], v130 offset:192
	v_or_b32_e32 v86, 0xc000, v0
	v_mov_b32_e32 v87, v1
	v_lshl_add_u64 v[86:87], v[86:87], 1, s[2:3]
	s_waitcnt lgkmcnt(0)
; #define SCHED __builtin_amdgcn_sched_barrier(0)
; template <int EPI, bool HS = false>
; __device__ __forceinline__ void gemm_phase(const Params& p, const GemmCfg& g, char* shm, const int wave_s) {
;     ...
;       if (pn < 4) {
;         u16* ot = g.o16 + (size_t)orow0 * 1024 + pn * 256;
;         const unsigned tb = (unsigned)((wr * 64 + fq * 4) * 1024 + wc * 32 + fr);
; #pragma unroll
;         for (int ai = 0; ai < 2; ++ai)
; #pragma unroll
;           for (int m = 0; m < 4; ++m) {
;             const f32x4 r4 = *(const f32x4*)(rsw + ai * 128 + m * 16);
; #pragma unroll
;             for (int j = 0; j < 4; ++j)
; #pragma unroll
;               for (int bj = 0; bj < 2; ++bj)
; #pragma unroll
;                 for (int n = 0; n < 2; ++n)
;                   ot[tb + (ai * 128 + m * 16 + j) * 1024 + bj * 128 + n * 16] = f2bf(r4[j] * acc[ai][bj][m][n][j] + swv[bj][n]);
;             SCHED;
;           }
	v_fma_f32 v70, v70, v82, v137
	v_bfe_u32 v88, v70, 16, 1
	v_fma_f32 v66, v66, v82, v136
	v_add3_u32 v70, v70, v88, s81
	global_store_short_d16_hi v[86:87], v70, off
	s_nop 0
	v_or_b32_e32 v86, 0xc010, v0
	v_mov_b32_e32 v87, v1
	v_cvt_pk_bf16_f32 v66, v66, v66
	v_lshl_add_u64 v[86:87], v[86:87], 1, s[2:3]
	global_store_short_d16_hi v[86:87], v66, off
	v_fma_f32 v66, v78, v82, v135
	v_or_b32_e32 v86, 0xc080, v0
	s_nop 0
	v_mov_b32_e32 v87, v1
	v_cvt_pk_bf16_f32 v66, v66, v66
	v_lshl_add_u64 v[86:87], v[86:87], 1, s[2:3]
	global_store_short_d16_hi v[86:87], v66, off
	v_fma_f32 v66, v74, v82, v134
	s_nop 0
	v_or_b32_e32 v86, 0xc090, v0
	v_mov_b32_e32 v87, v1
	v_cvt_pk_bf16_f32 v66, v66, v66
	v_lshl_add_u64 v[86:87], v[86:87], 1, s[2:3]
	global_store_short_d16_hi v[86:87], v66, off
	v_fma_f32 v66, v71, v83, v137
	s_nop 0
	v_or_b32_e32 v70, 0xc400, v0
	v_cvt_pk_bf16_f32 v66, v66, v66
	v_mov_b32_e32 v71, v1
	v_lshl_add_u64 v[70:71], v[70:71], 1, s[2:3]
	global_store_short_d16_hi v[70:71], v66, off
	v_fma_f32 v66, v67, v83, v136
	s_nop 0
	v_cvt_pk_bf16_f32 v70, v66, v66
	v_or_b32_e32 v66, 0xc410, v0
	v_mov_b32_e32 v67, v1
	v_lshl_add_u64 v[66:67], v[66:67], 1, s[2:3]
	global_store_short_d16_hi v[66:67], v70, off
	v_fma_f32 v67, v79, v83, v135
	s_nop 0
	v_or_b32_e32 v66, 0xc480, v0
	v_cvt_pk_bf16_f32 v70, v67, v67
	v_mov_b32_e32 v67, v1
	v_lshl_add_u64 v[66:67], v[66:67], 1, s[2:3]
	global_store_short_d16_hi v[66:67], v70, off
	v_fma_f32 v66, v75, v83, v134
	s_nop 0
	v_cvt_pk_bf16_f32 v70, v66, v66
	v_or_b32_e32 v66, 0xc490, v0
	v_mov_b32_e32 v67, v1
	v_lshl_add_u64 v[66:67], v[66:67], 1, s[2:3]
	global_store_short_d16_hi v[66:67], v70, off
	v_fma_f32 v67, v72, v84, v137
	s_nop 0
	v_or_b32_e32 v66, 0xc800, v0
	v_cvt_pk_bf16_f32 v70, v67, v67
	v_mov_b32_e32 v67, v1
	v_lshl_add_u64 v[66:67], v[66:67], 1, s[2:3]
	global_store_short_d16_hi v[66:67], v70, off
	v_fma_f32 v66, v68, v84, v136
	s_nop 0
	v_cvt_pk_bf16_f32 v68, v66, v66
	v_or_b32_e32 v66, 0xc810, v0
	v_mov_b32_e32 v67, v1
	v_lshl_add_u64 v[66:67], v[66:67], 1, s[2:3]
	global_store_short_d16_hi v[66:67], v68, off
	v_fma_f32 v67, v80, v84, v135
	s_nop 0
	v_or_b32_e32 v66, 0xc880, v0
	v_cvt_pk_bf16_f32 v68, v67, v67
	v_mov_b32_e32 v67, v1
	v_lshl_add_u64 v[66:67], v[66:67], 1, s[2:3]
	global_store_short_d16_hi v[66:67], v68, off
	v_fma_f32 v66, v76, v84, v134
	s_nop 0
	v_cvt_pk_bf16_f32 v68, v66, v66
	v_or_b32_e32 v66, 0xc890, v0
	v_mov_b32_e32 v67, v1
	v_lshl_add_u64 v[66:67], v[66:67], 1, s[2:3]
	global_store_short_d16_hi v[66:67], v68, off
	v_fma_f32 v67, v73, v85, v137
	s_nop 0
	v_or_b32_e32 v66, 0xcc00, v0
	v_cvt_pk_bf16_f32 v68, v67, v67
	v_mov_b32_e32 v67, v1
	v_lshl_add_u64 v[66:67], v[66:67], 1, s[2:3]
	global_store_short_d16_hi v[66:67], v68, off
	v_fma_f32 v66, v69, v85, v136
	s_nop 0
	v_cvt_pk_bf16_f32 v68, v66, v66
	v_or_b32_e32 v66, 0xcc10, v0
	v_mov_b32_e32 v67, v1
	v_lshl_add_u64 v[66:67], v[66:67], 1, s[2:3]
	global_store_short_d16_hi v[66:67], v68, off
	v_fma_f32 v67, v81, v85, v135
	s_nop 0
	v_or_b32_e32 v66, 0xcc80, v0
	v_cvt_pk_bf16_f32 v68, v67, v67
	v_mov_b32_e32 v67, v1
	v_lshl_add_u64 v[66:67], v[66:67], 1, s[2:3]
	global_store_short_d16_hi v[66:67], v68, off
	v_fma_f32 v66, v77, v85, v134
	s_nop 0
	v_cvt_pk_bf16_f32 v68, v66, v66
	v_or_b32_e32 v66, 0xcc90, v0
	v_mov_b32_e32 v67, v1
	v_lshl_add_u64 v[66:67], v[66:67], 1, s[2:3]
	global_store_short_d16_hi v[66:67], v68, off
	ds_read_b128 v[66:69], v130 offset:512
	v_add_u32_e32 v70, 0x20000, v0
	v_mov_b32_e32 v71, v1
	v_lshl_add_u64 v[70:71], v[70:71], 1, s[2:3]
	s_waitcnt lgkmcnt(0)
	v_fma_f32 v58, v58, v66, v137
	v_bfe_u32 v72, v58, 16, 1
	v_fma_f32 v50, v50, v66, v136
	v_add3_u32 v58, v58, v72, s81
	global_store_short_d16_hi v[70:71], v58, off
	s_nop 0
	v_add_u32_e32 v70, 0x20010, v0
	v_mov_b32_e32 v71, v1
	v_cvt_pk_bf16_f32 v50, v50, v50
	v_lshl_add_u64 v[70:71], v[70:71], 1, s[2:3]
	global_store_short_d16_hi v[70:71], v50, off
	v_fma_f32 v50, v62, v66, v135
	v_add_u32_e32 v70, 0x20080, v0
	s_nop 0
	v_mov_b32_e32 v71, v1
	v_cvt_pk_bf16_f32 v50, v50, v50
	v_lshl_add_u64 v[70:71], v[70:71], 1, s[2:3]
	global_store_short_d16_hi v[70:71], v50, off
	v_fma_f32 v50, v54, v66, v134
	s_nop 0
	v_add_u32_e32 v70, 0x20090, v0
	v_mov_b32_e32 v71, v1
	v_cvt_pk_bf16_f32 v50, v50, v50
	v_lshl_add_u64 v[70:71], v[70:71], 1, s[2:3]
	global_store_short_d16_hi v[70:71], v50, off
	v_fma_f32 v50, v59, v67, v137
	v_add_u32_e32 v58, 0x20400, v0
	s_nop 0
	v_mov_b32_e32 v59, v1
	v_cvt_pk_bf16_f32 v50, v50, v50
	v_lshl_add_u64 v[58:59], v[58:59], 1, s[2:3]
	global_store_short_d16_hi v[58:59], v50, off
	v_fma_f32 v50, v51, v67, v136
	s_nop 0
	v_cvt_pk_bf16_f32 v54, v50, v50
	v_add_u32_e32 v50, 0x20410, v0
	v_mov_b32_e32 v51, v1
	v_lshl_add_u64 v[50:51], v[50:51], 1, s[2:3]
	global_store_short_d16_hi v[50:51], v54, off
	v_fma_f32 v51, v63, v67, v135
	s_nop 0
	v_add_u32_e32 v50, 0x20480, v0
	v_cvt_pk_bf16_f32 v54, v51, v51
	v_mov_b32_e32 v51, v1
	v_lshl_add_u64 v[50:51], v[50:51], 1, s[2:3]
	global_store_short_d16_hi v[50:51], v54, off
	v_fma_f32 v50, v55, v67, v134
	s_nop 0
	v_cvt_pk_bf16_f32 v54, v50, v50
	v_add_u32_e32 v50, 0x20490, v0
	v_mov_b32_e32 v51, v1
	v_lshl_add_u64 v[50:51], v[50:51], 1, s[2:3]
	global_store_short_d16_hi v[50:51], v54, off
	v_fma_f32 v51, v60, v68, v137
	s_nop 0
	v_add_u32_e32 v50, 0x20800, v0
	v_cvt_pk_bf16_f32 v54, v51, v51
	v_mov_b32_e32 v51, v1
	v_lshl_add_u64 v[50:51], v[50:51], 1, s[2:3]
	global_store_short_d16_hi v[50:51], v54, off
	v_fma_f32 v50, v52, v68, v136
	s_nop 0
	v_cvt_pk_bf16_f32 v52, v50, v50
	v_add_u32_e32 v50, 0x20810, v0
	v_mov_b32_e32 v51, v1
	v_lshl_add_u64 v[50:51], v[50:51], 1, s[2:3]
; #define SCHED __builtin_amdgcn_sched_barrier(0)
; template <int EPI, bool HS = false>
; __device__ __forceinline__ void gemm_phase(const Params& p, const GemmCfg& g, char* shm, const int wave_s) {
;     ...
;       if (pn < 4) {
;         u16* ot = g.o16 + (size_t)orow0 * 1024 + pn * 256;
;         const unsigned tb = (unsigned)((wr * 64 + fq * 4) * 1024 + wc * 32 + fr);
; #pragma unroll
;         for (int ai = 0; ai < 2; ++ai)
; #pragma unroll
;           for (int m = 0; m < 4; ++m) {
;             const f32x4 r4 = *(const f32x4*)(rsw + ai * 128 + m * 16);
; #pragma unroll
;             for (int j = 0; j < 4; ++j)
; #pragma unroll
;               for (int bj = 0; bj < 2; ++bj)
; #pragma unroll
;                 for (int n = 0; n < 2; ++n)
;                   ot[tb + (ai * 128 + m * 16 + j) * 1024 + bj * 128 + n * 16] = f2bf(r4[j] * acc[ai][bj][m][n][j] + swv[bj][n]);
;             SCHED;
;           }
	global_store_short_d16_hi v[50:51], v52, off
	v_fma_f32 v51, v64, v68, v135
	s_nop 0
	v_add_u32_e32 v50, 0x20880, v0
	v_cvt_pk_bf16_f32 v52, v51, v51
	v_mov_b32_e32 v51, v1
	v_lshl_add_u64 v[50:51], v[50:51], 1, s[2:3]
	global_store_short_d16_hi v[50:51], v52, off
	v_fma_f32 v50, v56, v68, v134
	s_nop 0
	v_cvt_pk_bf16_f32 v52, v50, v50
	v_add_u32_e32 v50, 0x20890, v0
	v_mov_b32_e32 v51, v1
	v_lshl_add_u64 v[50:51], v[50:51], 1, s[2:3]
	global_store_short_d16_hi v[50:51], v52, off
	v_fma_f32 v51, v61, v69, v137
	s_nop 0
	v_add_u32_e32 v50, 0x20c00, v0
	v_cvt_pk_bf16_f32 v52, v51, v51
	v_mov_b32_e32 v51, v1
	v_lshl_add_u64 v[50:51], v[50:51], 1, s[2:3]
	global_store_short_d16_hi v[50:51], v52, off
	v_fma_f32 v50, v53, v69, v136
	s_nop 0
	v_cvt_pk_bf16_f32 v52, v50, v50
	v_add_u32_e32 v50, 0x20c10, v0
	v_mov_b32_e32 v51, v1
	v_lshl_add_u64 v[50:51], v[50:51], 1, s[2:3]
	global_store_short_d16_hi v[50:51], v52, off
	v_fma_f32 v51, v65, v69, v135
	s_nop 0
	v_add_u32_e32 v50, 0x20c80, v0
	v_cvt_pk_bf16_f32 v52, v51, v51
	v_mov_b32_e32 v51, v1
	v_lshl_add_u64 v[50:51], v[50:51], 1, s[2:3]
	global_store_short_d16_hi v[50:51], v52, off
	v_fma_f32 v50, v57, v69, v134
	s_nop 0
	v_cvt_pk_bf16_f32 v52, v50, v50
	v_add_u32_e32 v50, 0x20c90, v0
	v_mov_b32_e32 v51, v1
	v_lshl_add_u64 v[50:51], v[50:51], 1, s[2:3]
	global_store_short_d16_hi v[50:51], v52, off
	ds_read_b128 v[50:53], v130 offset:576
	v_add_u32_e32 v54, 0x24000, v0
	v_mov_b32_e32 v55, v1
	v_lshl_add_u64 v[54:55], v[54:55], 1, s[2:3]
	s_waitcnt lgkmcnt(0)
	v_fma_f32 v42, v42, v50, v137
	v_bfe_u32 v56, v42, 16, 1
	v_fma_f32 v34, v34, v50, v136
	v_add3_u32 v42, v42, v56, s81
	global_store_short_d16_hi v[54:55], v42, off
	s_nop 0
	v_add_u32_e32 v54, 0x24010, v0
	v_mov_b32_e32 v55, v1
	v_cvt_pk_bf16_f32 v34, v34, v34
	v_lshl_add_u64 v[54:55], v[54:55], 1, s[2:3]
	global_store_short_d16_hi v[54:55], v34, off
	v_fma_f32 v34, v46, v50, v135
	v_add_u32_e32 v54, 0x24080, v0
	s_nop 0
	v_mov_b32_e32 v55, v1
	v_cvt_pk_bf16_f32 v34, v34, v34
	v_lshl_add_u64 v[54:55], v[54:55], 1, s[2:3]
	global_store_short_d16_hi v[54:55], v34, off
	v_fma_f32 v34, v38, v50, v134
	s_nop 0
	v_add_u32_e32 v54, 0x24090, v0
	v_mov_b32_e32 v55, v1
	v_cvt_pk_bf16_f32 v34, v34, v34
	v_lshl_add_u64 v[54:55], v[54:55], 1, s[2:3]
	global_store_short_d16_hi v[54:55], v34, off
	v_fma_f32 v34, v43, v51, v137
	v_add_u32_e32 v42, 0x24400, v0
	s_nop 0
	v_mov_b32_e32 v43, v1
	v_cvt_pk_bf16_f32 v34, v34, v34
	v_lshl_add_u64 v[42:43], v[42:43], 1, s[2:3]
	global_store_short_d16_hi v[42:43], v34, off
	v_fma_f32 v34, v35, v51, v136
	s_nop 0
	v_cvt_pk_bf16_f32 v38, v34, v34
	v_add_u32_e32 v34, 0x24410, v0
	v_mov_b32_e32 v35, v1
	v_lshl_add_u64 v[34:35], v[34:35], 1, s[2:3]
	global_store_short_d16_hi v[34:35], v38, off
	v_fma_f32 v35, v47, v51, v135
	s_nop 0
	v_add_u32_e32 v34, 0x24480, v0
	v_cvt_pk_bf16_f32 v38, v35, v35
	v_mov_b32_e32 v35, v1
	v_lshl_add_u64 v[34:35], v[34:35], 1, s[2:3]
	global_store_short_d16_hi v[34:35], v38, off
	v_fma_f32 v34, v39, v51, v134
	s_nop 0
	v_cvt_pk_bf16_f32 v38, v34, v34
	v_add_u32_e32 v34, 0x24490, v0
	v_mov_b32_e32 v35, v1
	v_lshl_add_u64 v[34:35], v[34:35], 1, s[2:3]
	global_store_short_d16_hi v[34:35], v38, off
	v_fma_f32 v35, v44, v52, v137
	s_nop 0
	v_add_u32_e32 v34, 0x24800, v0
	v_cvt_pk_bf16_f32 v38, v35, v35
	v_mov_b32_e32 v35, v1
	v_lshl_add_u64 v[34:35], v[34:35], 1, s[2:3]
	global_store_short_d16_hi v[34:35], v38, off
	v_fma_f32 v34, v36, v52, v136
	s_nop 0
	v_cvt_pk_bf16_f32 v36, v34, v34
	v_add_u32_e32 v34, 0x24810, v0
	v_mov_b32_e32 v35, v1
	v_lshl_add_u64 v[34:35], v[34:35], 1, s[2:3]
	global_store_short_d16_hi v[34:35], v36, off
	v_fma_f32 v35, v48, v52, v135
	s_nop 0
	v_add_u32_e32 v34, 0x24880, v0
	v_cvt_pk_bf16_f32 v36, v35, v35
	v_mov_b32_e32 v35, v1
	v_lshl_add_u64 v[34:35], v[34:35], 1, s[2:3]
	global_store_short_d16_hi v[34:35], v36, off
	v_fma_f32 v34, v40, v52, v134
	s_nop 0
	v_cvt_pk_bf16_f32 v36, v34, v34
	v_add_u32_e32 v34, 0x24890, v0
	v_mov_b32_e32 v35, v1
	v_lshl_add_u64 v[34:35], v[34:35], 1, s[2:3]
	global_store_short_d16_hi v[34:35], v36, off
	v_fma_f32 v35, v45, v53, v137
	s_nop 0
	v_add_u32_e32 v34, 0x24c00, v0
	v_cvt_pk_bf16_f32 v36, v35, v35
	v_mov_b32_e32 v35, v1
	v_lshl_add_u64 v[34:35], v[34:35], 1, s[2:3]
	global_store_short_d16_hi v[34:35], v36, off
	v_fma_f32 v34, v37, v53, v136
	s_nop 0
	v_cvt_pk_bf16_f32 v36, v34, v34
	v_add_u32_e32 v34, 0x24c10, v0
	v_mov_b32_e32 v35, v1
	v_lshl_add_u64 v[34:35], v[34:35], 1, s[2:3]
	global_store_short_d16_hi v[34:35], v36, off
	v_fma_f32 v35, v49, v53, v135
	s_nop 0
	v_add_u32_e32 v34, 0x24c80, v0
	v_cvt_pk_bf16_f32 v36, v35, v35
	v_mov_b32_e32 v35, v1
	v_lshl_add_u64 v[34:35], v[34:35], 1, s[2:3]
	global_store_short_d16_hi v[34:35], v36, off
	v_fma_f32 v34, v41, v53, v134
	s_nop 0
	v_cvt_pk_bf16_f32 v36, v34, v34
	v_add_u32_e32 v34, 0x24c90, v0
	v_mov_b32_e32 v35, v1
	v_lshl_add_u64 v[34:35], v[34:35], 1, s[2:3]
	global_store_short_d16_hi v[34:35], v36, off
	ds_read_b128 v[34:37], v130 offset:640
	v_add_u32_e32 v38, 0x28000, v0
	v_mov_b32_e32 v39, v1
	v_lshl_add_u64 v[38:39], v[38:39], 1, s[2:3]
	s_waitcnt lgkmcnt(0)
; #define SCHED __builtin_amdgcn_sched_barrier(0)
; template <int EPI, bool HS = false>
; __device__ __forceinline__ void gemm_phase(const Params& p, const GemmCfg& g, char* shm, const int wave_s) {
;     ...
;       if (pn < 4) {
;         u16* ot = g.o16 + (size_t)orow0 * 1024 + pn * 256;
;         const unsigned tb = (unsigned)((wr * 64 + fq * 4) * 1024 + wc * 32 + fr);
; #pragma unroll
;         for (int ai = 0; ai < 2; ++ai)
; #pragma unroll
;           for (int m = 0; m < 4; ++m) {
;             const f32x4 r4 = *(const f32x4*)(rsw + ai * 128 + m * 16);
; #pragma unroll
;             for (int j = 0; j < 4; ++j)
; #pragma unroll
;               for (int bj = 0; bj < 2; ++bj)
; #pragma unroll
;                 for (int n = 0; n < 2; ++n)
;                   ot[tb + (ai * 128 + m * 16 + j) * 1024 + bj * 128 + n * 16] = f2bf(r4[j] * acc[ai][bj][m][n][j] + swv[bj][n]);
;             SCHED;
;           }
	v_fma_f32 v26, v26, v34, v137
	v_bfe_u32 v40, v26, 16, 1
	v_fma_f32 v18, v18, v34, v136
	v_add3_u32 v26, v26, v40, s81
	global_store_short_d16_hi v[38:39], v26, off
	s_nop 0
	v_add_u32_e32 v38, 0x28010, v0
	v_mov_b32_e32 v39, v1
	v_cvt_pk_bf16_f32 v18, v18, v18
	v_lshl_add_u64 v[38:39], v[38:39], 1, s[2:3]
	global_store_short_d16_hi v[38:39], v18, off
	v_fma_f32 v18, v30, v34, v135
	v_add_u32_e32 v38, 0x28080, v0
	s_nop 0
	v_mov_b32_e32 v39, v1
	v_cvt_pk_bf16_f32 v18, v18, v18
	v_lshl_add_u64 v[38:39], v[38:39], 1, s[2:3]
	global_store_short_d16_hi v[38:39], v18, off
	v_fma_f32 v18, v22, v34, v134
	s_nop 0
	v_add_u32_e32 v38, 0x28090, v0
	v_mov_b32_e32 v39, v1
	v_cvt_pk_bf16_f32 v18, v18, v18
	v_lshl_add_u64 v[38:39], v[38:39], 1, s[2:3]
	global_store_short_d16_hi v[38:39], v18, off
	v_fma_f32 v18, v27, v35, v137
	v_add_u32_e32 v26, 0x28400, v0
	s_nop 0
	v_mov_b32_e32 v27, v1
	v_cvt_pk_bf16_f32 v18, v18, v18
	v_lshl_add_u64 v[26:27], v[26:27], 1, s[2:3]
	global_store_short_d16_hi v[26:27], v18, off
	v_fma_f32 v18, v19, v35, v136
	s_nop 0
	v_cvt_pk_bf16_f32 v22, v18, v18
	v_add_u32_e32 v18, 0x28410, v0
	v_mov_b32_e32 v19, v1
	v_lshl_add_u64 v[18:19], v[18:19], 1, s[2:3]
	global_store_short_d16_hi v[18:19], v22, off
	v_fma_f32 v19, v31, v35, v135
	s_nop 0
	v_add_u32_e32 v18, 0x28480, v0
	v_cvt_pk_bf16_f32 v22, v19, v19
	v_mov_b32_e32 v19, v1
	v_lshl_add_u64 v[18:19], v[18:19], 1, s[2:3]
	global_store_short_d16_hi v[18:19], v22, off
	v_fma_f32 v18, v23, v35, v134
	s_nop 0
	v_cvt_pk_bf16_f32 v22, v18, v18
	v_add_u32_e32 v18, 0x28490, v0
	v_mov_b32_e32 v19, v1
	v_lshl_add_u64 v[18:19], v[18:19], 1, s[2:3]
	global_store_short_d16_hi v[18:19], v22, off
	v_fma_f32 v19, v28, v36, v137
	s_nop 0
	v_add_u32_e32 v18, 0x28800, v0
	v_cvt_pk_bf16_f32 v22, v19, v19
	v_mov_b32_e32 v19, v1
	v_lshl_add_u64 v[18:19], v[18:19], 1, s[2:3]
	global_store_short_d16_hi v[18:19], v22, off
	v_fma_f32 v18, v20, v36, v136
	s_nop 0
	v_cvt_pk_bf16_f32 v20, v18, v18
	v_add_u32_e32 v18, 0x28810, v0
	v_mov_b32_e32 v19, v1
	v_lshl_add_u64 v[18:19], v[18:19], 1, s[2:3]
	global_store_short_d16_hi v[18:19], v20, off
	v_fma_f32 v19, v32, v36, v135
	s_nop 0
	v_add_u32_e32 v18, 0x28880, v0
	v_cvt_pk_bf16_f32 v20, v19, v19
	v_mov_b32_e32 v19, v1
	v_lshl_add_u64 v[18:19], v[18:19], 1, s[2:3]
	global_store_short_d16_hi v[18:19], v20, off
	v_fma_f32 v18, v24, v36, v134
	s_nop 0
	v_cvt_pk_bf16_f32 v20, v18, v18
	v_add_u32_e32 v18, 0x28890, v0
	v_mov_b32_e32 v19, v1
	v_lshl_add_u64 v[18:19], v[18:19], 1, s[2:3]
	global_store_short_d16_hi v[18:19], v20, off
	v_fma_f32 v19, v29, v37, v137
	s_nop 0
	v_add_u32_e32 v18, 0x28c00, v0
	v_cvt_pk_bf16_f32 v20, v19, v19
	v_mov_b32_e32 v19, v1
	v_lshl_add_u64 v[18:19], v[18:19], 1, s[2:3]
	global_store_short_d16_hi v[18:19], v20, off
	v_fma_f32 v18, v21, v37, v136
	s_nop 0
	v_cvt_pk_bf16_f32 v20, v18, v18
	v_add_u32_e32 v18, 0x28c10, v0
	v_mov_b32_e32 v19, v1
	v_lshl_add_u64 v[18:19], v[18:19], 1, s[2:3]
	global_store_short_d16_hi v[18:19], v20, off
	v_fma_f32 v19, v33, v37, v135
	s_nop 0
	v_add_u32_e32 v18, 0x28c80, v0
	v_cvt_pk_bf16_f32 v20, v19, v19
	v_mov_b32_e32 v19, v1
	v_lshl_add_u64 v[18:19], v[18:19], 1, s[2:3]
	global_store_short_d16_hi v[18:19], v20, off
	v_fma_f32 v18, v25, v37, v134
	s_nop 0
	v_cvt_pk_bf16_f32 v20, v18, v18
	v_add_u32_e32 v18, 0x28c90, v0
	v_mov_b32_e32 v19, v1
	v_lshl_add_u64 v[18:19], v[18:19], 1, s[2:3]
	global_store_short_d16_hi v[18:19], v20, off
	ds_read_b128 v[18:21], v130 offset:704
	v_add_u32_e32 v22, 0x2c000, v0
	v_mov_b32_e32 v23, v1
	v_lshl_add_u64 v[22:23], v[22:23], 1, s[2:3]
	s_waitcnt lgkmcnt(0)
	v_fma_f32 v10, v10, v18, v137
	v_bfe_u32 v24, v10, 16, 1
	v_fma_f32 v2, v2, v18, v136
	v_add3_u32 v10, v10, v24, s81
	global_store_short_d16_hi v[22:23], v10, off
	s_nop 0
	v_add_u32_e32 v22, 0x2c010, v0
	v_mov_b32_e32 v23, v1
	v_cvt_pk_bf16_f32 v2, v2, v2
	v_lshl_add_u64 v[22:23], v[22:23], 1, s[2:3]
	global_store_short_d16_hi v[22:23], v2, off
	v_fma_f32 v2, v14, v18, v135
	v_add_u32_e32 v22, 0x2c080, v0
	s_nop 0
	v_mov_b32_e32 v23, v1
	v_cvt_pk_bf16_f32 v2, v2, v2
	v_lshl_add_u64 v[22:23], v[22:23], 1, s[2:3]
	global_store_short_d16_hi v[22:23], v2, off
	v_fma_f32 v2, v6, v18, v134
	s_nop 0
	v_add_u32_e32 v22, 0x2c090, v0
	v_mov_b32_e32 v23, v1
	v_cvt_pk_bf16_f32 v2, v2, v2
	v_lshl_add_u64 v[22:23], v[22:23], 1, s[2:3]
	global_store_short_d16_hi v[22:23], v2, off
	v_fma_f32 v2, v11, v19, v137
	v_add_u32_e32 v10, 0x2c400, v0
	s_nop 0
	v_mov_b32_e32 v11, v1
	v_cvt_pk_bf16_f32 v2, v2, v2
	v_lshl_add_u64 v[10:11], v[10:11], 1, s[2:3]
	global_store_short_d16_hi v[10:11], v2, off
	v_fma_f32 v2, v3, v19, v136
	s_nop 0
	v_cvt_pk_bf16_f32 v6, v2, v2
	v_add_u32_e32 v2, 0x2c410, v0
	v_mov_b32_e32 v3, v1
	v_lshl_add_u64 v[2:3], v[2:3], 1, s[2:3]
	global_store_short_d16_hi v[2:3], v6, off
	v_fma_f32 v3, v15, v19, v135
	s_nop 0
	v_add_u32_e32 v2, 0x2c480, v0
	v_cvt_pk_bf16_f32 v6, v3, v3
	v_mov_b32_e32 v3, v1
	v_lshl_add_u64 v[2:3], v[2:3], 1, s[2:3]
	global_store_short_d16_hi v[2:3], v6, off
	v_fma_f32 v2, v7, v19, v134
	s_nop 0
	v_cvt_pk_bf16_f32 v6, v2, v2
	v_add_u32_e32 v2, 0x2c490, v0
	v_mov_b32_e32 v3, v1
	v_lshl_add_u64 v[2:3], v[2:3], 1, s[2:3]
	global_store_short_d16_hi v[2:3], v6, off
	v_fma_f32 v3, v12, v20, v137
	v_bfe_u32 v6, v3, 16, 1
	v_add_u32_e32 v2, 0x2c800, v0
	v_add3_u32 v6, v3, v6, s81
	v_mov_b32_e32 v3, v1
	v_lshl_add_u64 v[2:3], v[2:3], 1, s[2:3]
	global_store_short_d16_hi v[2:3], v6, off
	v_fma_f32 v2, v4, v20, v136
	s_nop 0
	v_cvt_pk_bf16_f32 v4, v2, v2
	v_add_u32_e32 v2, 0x2c810, v0
	v_mov_b32_e32 v3, v1
	v_lshl_add_u64 v[2:3], v[2:3], 1, s[2:3]
	global_store_short_d16_hi v[2:3], v4, off
	v_fma_f32 v3, v16, v20, v135
	s_nop 0
	v_add_u32_e32 v2, 0x2c880, v0
	v_cvt_pk_bf16_f32 v4, v3, v3
	v_mov_b32_e32 v3, v1
	v_lshl_add_u64 v[2:3], v[2:3], 1, s[2:3]
	global_store_short_d16_hi v[2:3], v4, off
	v_fma_f32 v2, v8, v20, v134
	s_nop 0
	v_cvt_pk_bf16_f32 v4, v2, v2
	v_add_u32_e32 v2, 0x2c890, v0
	v_mov_b32_e32 v3, v1
	v_lshl_add_u64 v[2:3], v[2:3], 1, s[2:3]
	v_fmac_f32_e32 v137, v13, v21
	global_store_short_d16_hi v[2:3], v4, off
	s_nop 0
	v_add_u32_e32 v2, 0x2cc00, v0
	v_cvt_pk_bf16_f32 v4, v137, v137
	v_mov_b32_e32 v3, v1
	v_lshl_add_u64 v[2:3], v[2:3], 1, s[2:3]
	v_fmac_f32_e32 v136, v5, v21
	global_store_short_d16_hi v[2:3], v4, off
	s_nop 0
	v_cvt_pk_bf16_f32 v4, v136, v136
	v_add_u32_e32 v2, 0x2cc10, v0
	v_mov_b32_e32 v3, v1
	v_lshl_add_u64 v[2:3], v[2:3], 1, s[2:3]
	v_fmac_f32_e32 v135, v17, v21
	global_store_short_d16_hi v[2:3], v4, off
	s_nop 0
	v_add_u32_e32 v2, 0x2cc80, v0
	v_cvt_pk_bf16_f32 v4, v135, v135
	v_mov_b32_e32 v3, v1
	v_lshl_add_u64 v[2:3], v[2:3], 1, s[2:3]
	v_fmac_f32_e32 v134, v9, v21
	global_store_short_d16_hi v[2:3], v4, off
	v_bfe_u32 v2, v134, 16, 1
	v_add_u32_e32 v0, 0x2cc90, v0
	v_add3_u32 v4, v134, v2, s81
	v_lshl_add_u64 v[2:3], v[0:1], 1, s[2:3]
	global_store_short_d16_hi v[2:3], v4, off
	s_branch .LBB0_312

; __device__ __forceinline__ unsigned pack2(float a, float b) { return (unsigned)f2bf(a) | ((unsigned)f2bf(b) << 16); }
; #define SCHED __builtin_amdgcn_sched_barrier(0)
; template <bool HS>
; __device__ __forceinline__ void gemm_tile8(const u16* __restrict__ Ap, const u16* __restrict__ Bp, int K,
;                                            f32x4 (&acc)[2][2][4][2], char* shm, const int tid, const float* hsr = nullptr) {
;     ...
; #pragma unroll
;     for (int ai = 0; ai < 2; ++ai)
; #pragma unroll
;       for (int m = 0; m < 4; ++m) {
;         const f32x4 q4 = *(const f32x4*)(rt + ai * 128 + m * 16);
; #pragma unroll
;         for (int bj = 0; bj < 2; ++bj)
; #pragma unroll
;           for (int n = 0; n < 2; ++n) acc[ai][bj][m][n] *= q4;
;         SCHED;
;       }
; template <int EPI, bool HS = false>
; __device__ __forceinline__ void gemm_phase(const Params& p, const GemmCfg& g, char* shm, const int wave_s) {
;     ...
;           for (int j = 0; j < 4; ++j) {
;             float ss = 0.f;
; #pragma unroll
;             for (int bj = 0; bj < 2; ++bj) {
;               float2 xn;
;               xn.x = xv[j][bj].x + gt[bj][0] * acc[ai][bj][m][0][j];
;               xn.y = xv[j][bj].y + gt[bj][1] * acc[ai][bj][m][1][j];
;               const unsigned o = tb + (unsigned)((ai * 128 + m * 16 + j) * 1024 + bj * 128);
;               *(float2*)(xout_t + o) = xn;
;               if (g.has_next) *(unsigned*)(xg_t + o) = pack2(xn.x * gn[bj][0], xn.y * gn[bj][1]);
;               ss += xn.x * xn.x + xn.y * xn.y;
;             }
;             if (g.has_next) {
;               ss = dpp_row_sum16(ss);
;               if (fr == 0) rss_t[(wr * 64 + fq * 4 + ai * 128 + m * 16 + j) * 16] = ss;
;             }
.LBB0_357:
	v_readlane_b32 s16, v252, 0
	s_lshl_b64 s[4:5], s[4:5], 6
	v_readlane_b32 s22, v252, 6
	v_readlane_b32 s23, v252, 7
	s_add_u32 s14, s22, s4
	s_addc_u32 s15, s23, s5
	s_lshl_b32 s4, s13, 2
	s_ashr_i32 s5, s4, 31
	s_lshl_b64 s[4:5], s[4:5], 2
	s_add_u32 s4, s14, s4
	v_pk_mul_f32 v[146:147], v[146:147], v[158:159]
	v_pk_mul_f32 v[142:143], v[142:143], v[158:159]
	s_addc_u32 s5, s15, s5
	v_lshlrev_b32_e32 v150, 2, v200
	v_mov_b32_e32 v151, v1
	v_mov_b32_e32 v158, v146
	v_mov_b32_e32 v159, v142
	v_pk_mul_f32 v[156:157], v[156:157], v[160:161]
	v_pk_mul_f32 v[152:153], v[152:153], v[160:161]
	v_lshl_add_u64 v[150:151], s[4:5], 0, v[150:151]
	v_cmp_eq_u32_e64 s[4:5], 0, v199
	v_pk_mul_f32 v[148:149], v[148:149], v[160:161]
	v_pk_mul_f32 v[144:145], v[144:145], v[160:161]
	s_waitcnt vmcnt(1)
	v_pk_fma_f32 v[158:159], v[158:159], v[180:181], v[176:177]
	s_and_b64 vcc, exec, s[6:7]
	s_mov_b64 s[68:69], -1
	v_readlane_b32 s17, v252, 1
	v_readlane_b32 s18, v252, 2
	v_readlane_b32 s19, v252, 3
	v_readlane_b32 s20, v252, 4
	v_readlane_b32 s21, v252, 5
	global_store_dwordx2 v[192:193], v[158:159], off offset:512
	s_cbranch_vccnz .LBB0_363
	v_pk_mul_f32 v[176:177], v[186:187], v[158:159]
	v_pk_mul_f32 v[160:161], v[190:191], v[190:191]
	s_nop 0
	v_and_b32_sdwa v142, v177, v178 dst_sel:DWORD dst_unused:UNUSED_PAD src0_sel:WORD_1 src1_sel:DWORD
	v_cvt_pk_bf16_f32 v146, v176, v176
	v_add3_u32 v142, v177, v142, s81
	v_lshrrev_b32_e32 v146, 16, v146
	v_and_or_b32 v142, v142, s28, v146
	v_pk_mul_f32 v[158:159], v[158:159], v[158:159]
	global_store_dword v[174:175], v142, off offset:256
	v_add_f32_e32 v142, v158, v159
	v_add_f32_e32 v146, v160, v161
	v_add_f32_e32 v142, v146, v142
	s_nop 1
	v_add_f32_dpp v142, v142, v142 quad_perm:[1,0,3,2] row_mask:0xf bank_mask:0xf bound_ctrl:1
	s_nop 1
	v_add_f32_dpp v142, v142, v142 quad_perm:[2,3,0,1] row_mask:0xf bank_mask:0xf bound_ctrl:1
	s_nop 1
	v_add_f32_dpp v142, v142, v142 row_half_mirror row_mask:0xf bank_mask:0xf bound_ctrl:1
	s_nop 1
	v_mov_b32_dpp v146, v142 row_mirror row_mask:0xf bank_mask:0xf bound_ctrl:1
	s_and_saveexec_b64 s[68:69], s[4:5]
	s_cbranch_execz .LBB0_360
	v_lshlrev_b32_e32 v158, 4, v194
	v_ashrrev_i32_e32 v159, 31, v158
	v_add_f32_e32 v142, v142, v146
	v_lshl_add_u64 v[158:159], v[158:159], 2, v[150:151]
	global_store_dword v[158:159], v142, off
.LBB0_360:
	s_or_b64 exec, exec, s[68:69]
	v_or_b32_e32 v158, 0x400, v0
	v_mov_b32_e32 v154, v189
	v_mov_b32_e32 v159, v1
	s_waitcnt lgkmcnt(2)
	v_pk_fma_f32 v[160:161], v[154:155], v[184:185], v[170:171]
	v_lshl_add_u64 v[158:159], v[158:159], 2, s[2:3]
	global_store_dwordx2 v[158:159], v[160:161], off
	v_pk_mul_f32 v[158:159], v[182:183], v[160:161]
	v_or_b32_e32 v176, 0x480, v0
	s_nop 0
	v_and_b32_sdwa v142, v159, v178 dst_sel:DWORD dst_unused:UNUSED_PAD src0_sel:WORD_1 src1_sel:DWORD
	v_cvt_pk_bf16_f32 v146, v158, v158
	v_add3_u32 v142, v159, v142, s81
	v_lshrrev_b32_e32 v146, 16, v146
	v_and_or_b32 v142, v142, s28, v146
	global_store_dword v[174:175], v142, off offset:2048
	v_mov_b32_e32 v142, v147
	v_mov_b32_e32 v177, v1
	v_pk_fma_f32 v[158:159], v[142:143], v[180:181], v[172:173]
	v_lshl_add_u64 v[176:177], v[176:177], 2, s[2:3]
	global_store_dwordx2 v[176:177], v[158:159], off
	v_pk_mul_f32 v[176:177], v[186:187], v[158:159]
	v_pk_mul_f32 v[160:161], v[160:161], v[160:161]
	s_nop 0
	v_and_b32_sdwa v142, v177, v178 dst_sel:DWORD dst_unused:UNUSED_PAD src0_sel:WORD_1 src1_sel:DWORD
	v_cvt_pk_bf16_f32 v146, v176, v176
	v_add3_u32 v142, v177, v142, s81
	v_lshrrev_b32_e32 v146, 16, v146
	v_and_or_b32 v142, v142, s28, v146
	v_pk_mul_f32 v[158:159], v[158:159], v[158:159]
	global_store_dword v[174:175], v142, off offset:2304
	v_add_f32_e32 v142, v158, v159
	v_add_f32_e32 v146, v160, v161
	v_add_f32_e32 v142, v146, v142
	s_nop 1
	v_add_f32_dpp v142, v142, v142 quad_perm:[1,0,3,2] row_mask:0xf bank_mask:0xf bound_ctrl:1
	s_nop 1
	v_add_f32_dpp v142, v142, v142 quad_perm:[2,3,0,1] row_mask:0xf bank_mask:0xf bound_ctrl:1
	s_nop 1
	v_add_f32_dpp v142, v142, v142 row_half_mirror row_mask:0xf bank_mask:0xf bound_ctrl:1
	s_nop 1
	v_mov_b32_dpp v146, v142 row_mirror row_mask:0xf bank_mask:0xf bound_ctrl:1
	s_and_saveexec_b64 s[68:69], s[4:5]
	s_cbranch_execz .LBB0_362
	v_lshlrev_b32_e32 v158, 4, v194
	v_ashrrev_i32_e32 v159, 31, v158
	v_add_f32_e32 v142, v142, v146
	v_lshl_add_u64 v[158:159], v[158:159], 2, v[150:151]
	global_store_dword v[158:159], v142, off offset:64

; __device__ __forceinline__ unsigned pack2(float a, float b) { return (unsigned)f2bf(a) | ((unsigned)f2bf(b) << 16); }
; template <int EPI, bool HS = false>
; __device__ __forceinline__ void gemm_phase(const Params& p, const GemmCfg& g, char* shm, const int wave_s) {
;     ...
;           for (int j = 0; j < 4; ++j) {
;             float ss = 0.f;
; #pragma unroll
;             for (int bj = 0; bj < 2; ++bj) {
;               float2 xn;
;               xn.x = xv[j][bj].x + gt[bj][0] * acc[ai][bj][m][0][j];
;               xn.y = xv[j][bj].y + gt[bj][1] * acc[ai][bj][m][1][j];
;               const unsigned o = tb + (unsigned)((ai * 128 + m * 16 + j) * 1024 + bj * 128);
;               *(float2*)(xout_t + o) = xn;
;               if (g.has_next) *(unsigned*)(xg_t + o) = pack2(xn.x * gn[bj][0], xn.y * gn[bj][1]);
;               ss += xn.x * xn.x + xn.y * xn.y;
;             }
;             if (g.has_next) {
;               ss = dpp_row_sum16(ss);
;               if (fr == 0) rss_t[(wr * 64 + fq * 4 + ai * 128 + m * 16 + j) * 16] = ss;
;             }
.LBB0_365:
	v_or_b32_e32 v154, 0x800, v0
	v_mov_b32_e32 v142, v156
	v_mov_b32_e32 v143, v152
	v_mov_b32_e32 v155, v1
	s_waitcnt lgkmcnt(1)
	v_pk_fma_f32 v[146:147], v[142:143], v[184:185], v[166:167]
	v_lshl_add_u64 v[142:143], v[154:155], 2, s[2:3]
	global_store_dwordx2 v[142:143], v[146:147], off
	s_mov_b64 s[68:69], -1
	s_and_b64 vcc, exec, s[6:7]
	v_or_b32_e32 v142, 0x880, v0
	s_cbranch_vccnz .LBB0_369
	v_pk_mul_f32 v[158:159], v[182:183], v[146:147]
	v_lshl_add_u64 v[154:155], v[154:155], 1, s[8:9]
	s_nop 0
	v_and_b32_sdwa v143, v159, v178 dst_sel:DWORD dst_unused:UNUSED_PAD src0_sel:WORD_1 src1_sel:DWORD
	v_cvt_pk_bf16_f32 v152, v158, v158
	v_add3_u32 v143, v159, v143, s81
	v_lshrrev_b32_e32 v152, 16, v152
	v_and_or_b32 v143, v143, s28, v152
	global_store_dword v[154:155], v143, off
	v_mov_b32_e32 v154, v148
	v_mov_b32_e32 v155, v144
	v_mov_b32_e32 v143, v1
	v_pk_fma_f32 v[154:155], v[154:155], v[180:181], v[168:169]
	v_lshl_add_u64 v[158:159], v[142:143], 2, s[2:3]
	global_store_dwordx2 v[158:159], v[154:155], off
	v_pk_mul_f32 v[158:159], v[186:187], v[154:155]
	v_pk_mul_f32 v[146:147], v[146:147], v[146:147]
	v_and_b32_sdwa v152, v159, v178 dst_sel:DWORD dst_unused:UNUSED_PAD src0_sel:WORD_1 src1_sel:DWORD
	s_nop 0
	v_pk_mul_f32 v[154:155], v[154:155], v[154:155]
	v_add3_u32 v152, v159, v152, s81
	v_cvt_pk_bf16_f32 v156, v158, v158
	v_lshl_add_u64 v[158:159], v[142:143], 1, s[8:9]
	v_add_f32_e32 v143, v154, v155
	v_add_f32_e32 v146, v146, v147
	v_add_f32_e32 v143, v146, v143
	v_lshrrev_b32_e32 v156, 16, v156
	v_and_or_b32 v152, v152, s28, v156
	v_add_f32_dpp v143, v143, v143 quad_perm:[1,0,3,2] row_mask:0xf bank_mask:0xf bound_ctrl:1
	global_store_dword v[158:159], v152, off
	s_nop 0
	v_add_f32_dpp v143, v143, v143 quad_perm:[2,3,0,1] row_mask:0xf bank_mask:0xf bound_ctrl:1
	s_nop 1
	v_add_f32_dpp v143, v143, v143 row_half_mirror row_mask:0xf bank_mask:0xf bound_ctrl:1
	s_nop 1
	v_mov_b32_dpp v146, v143 row_mirror row_mask:0xf bank_mask:0xf bound_ctrl:1
	s_and_saveexec_b64 s[68:69], s[4:5]
	s_cbranch_execz .LBB0_368
	v_add_f32_e32 v143, v143, v146
	v_lshlrev_b32_e32 v146, 4, v194
	v_ashrrev_i32_e32 v147, 31, v146
	v_lshl_add_u64 v[146:147], v[146:147], 2, v[150:151]
	global_store_dword v[146:147], v143, off offset:128

; __device__ __forceinline__ unsigned pack2(float a, float b) { return (unsigned)f2bf(a) | ((unsigned)f2bf(b) << 16); }
; template <int EPI, bool HS = false>
; __device__ __forceinline__ void gemm_phase(const Params& p, const GemmCfg& g, char* shm, const int wave_s) {
;     ...
;           for (int j = 0; j < 4; ++j) {
;             float ss = 0.f;
; #pragma unroll
;             for (int bj = 0; bj < 2; ++bj) {
;               float2 xn;
;               xn.x = xv[j][bj].x + gt[bj][0] * acc[ai][bj][m][0][j];
;               xn.y = xv[j][bj].y + gt[bj][1] * acc[ai][bj][m][1][j];
;               const unsigned o = tb + (unsigned)((ai * 128 + m * 16 + j) * 1024 + bj * 128);
;               *(float2*)(xout_t + o) = xn;
;               if (g.has_next) *(unsigned*)(xg_t + o) = pack2(xn.x * gn[bj][0], xn.y * gn[bj][1]);
;               ss += xn.x * xn.x + xn.y * xn.y;
;             }
;             if (g.has_next) {
;               ss = dpp_row_sum16(ss);
;               if (fr == 0) rss_t[(wr * 64 + fq * 4 + ai * 128 + m * 16 + j) * 16] = ss;
;             }
.LBB0_371:
	v_or_b32_e32 v154, 0xc00, v0
	v_mov_b32_e32 v152, v157
	v_mov_b32_e32 v155, v1
	s_waitcnt lgkmcnt(0)
	v_pk_fma_f32 v[146:147], v[152:153], v[184:185], v[162:163]
	v_lshl_add_u64 v[142:143], v[154:155], 2, s[2:3]
	global_store_dwordx2 v[142:143], v[146:147], off
	s_mov_b64 s[68:69], -1
	s_and_b64 vcc, exec, s[6:7]
	v_or_b32_e32 v142, 0xc80, v0
	s_cbranch_vccnz .LBB0_375
	v_pk_mul_f32 v[152:153], v[182:183], v[146:147]
	v_pk_mul_f32 v[146:147], v[146:147], v[146:147]
	s_nop 0
	v_and_b32_sdwa v143, v153, v178 dst_sel:DWORD dst_unused:UNUSED_PAD src0_sel:WORD_1 src1_sel:DWORD
	v_cvt_pk_bf16_f32 v144, v152, v152
	v_add3_u32 v143, v153, v143, s81
	v_lshrrev_b32_e32 v144, 16, v144
	v_and_or_b32 v143, v143, s28, v144
	v_lshl_add_u64 v[152:153], v[154:155], 1, s[8:9]
	global_store_dword v[152:153], v143, off
	v_mov_b32_e32 v144, v149
	v_mov_b32_e32 v143, v1
	v_pk_fma_f32 v[152:153], v[144:145], v[180:181], v[164:165]
	v_lshl_add_u64 v[154:155], v[142:143], 2, s[2:3]
	global_store_dwordx2 v[154:155], v[152:153], off
	v_pk_mul_f32 v[154:155], v[186:187], v[152:153]
	v_pk_mul_f32 v[152:153], v[152:153], v[152:153]
	s_nop 0
	v_and_b32_sdwa v144, v155, v178 dst_sel:DWORD dst_unused:UNUSED_PAD src0_sel:WORD_1 src1_sel:DWORD
	v_cvt_pk_bf16_f32 v148, v154, v154
	v_add3_u32 v144, v155, v144, s81
	v_lshrrev_b32_e32 v148, 16, v148
	v_and_or_b32 v144, v144, s28, v148
	v_lshl_add_u64 v[154:155], v[142:143], 1, s[8:9]
	global_store_dword v[154:155], v144, off
	v_add_f32_e32 v143, v152, v153
	v_add_f32_e32 v144, v146, v147
	v_add_f32_e32 v143, v144, v143
	s_nop 1
	v_add_f32_dpp v143, v143, v143 quad_perm:[1,0,3,2] row_mask:0xf bank_mask:0xf bound_ctrl:1
	s_nop 1
	v_add_f32_dpp v143, v143, v143 quad_perm:[2,3,0,1] row_mask:0xf bank_mask:0xf bound_ctrl:1
	s_nop 1
	v_add_f32_dpp v143, v143, v143 row_half_mirror row_mask:0xf bank_mask:0xf bound_ctrl:1
	s_nop 1
	v_mov_b32_dpp v144, v143 row_mirror row_mask:0xf bank_mask:0xf bound_ctrl:1
	s_and_saveexec_b64 s[68:69], s[4:5]
	s_cbranch_execz .LBB0_374
	v_lshlrev_b32_e32 v146, 4, v194
	v_ashrrev_i32_e32 v147, 31, v146
	v_add_f32_e32 v143, v143, v144
	v_lshl_add_u64 v[146:147], v[146:147], 2, v[150:151]
	global_store_dword v[146:147], v143, off offset:192

; __device__ __forceinline__ unsigned pack2(float a, float b) { return (unsigned)f2bf(a) | ((unsigned)f2bf(b) << 16); }
; #define SCHED __builtin_amdgcn_sched_barrier(0)
; template <bool HS>
; __device__ __forceinline__ void gemm_tile8(const u16* __restrict__ Ap, const u16* __restrict__ Bp, int K,
;                                            f32x4 (&acc)[2][2][4][2], char* shm, const int tid, const float* hsr = nullptr) {
;     ...
;       for (int m = 0; m < 4; ++m) {
;         const f32x4 q4 = *(const f32x4*)(rt + ai * 128 + m * 16);
; #pragma unroll
;         for (int bj = 0; bj < 2; ++bj)
; #pragma unroll
;           for (int n = 0; n < 2; ++n) acc[ai][bj][m][n] *= q4;
;         SCHED;
;       }
; template <int EPI, bool HS = false>
; __device__ __forceinline__ void gemm_phase(const Params& p, const GemmCfg& g, char* shm, const int wave_s) {
;     ...
;             for (int bj = 0; bj < 2; ++bj) xv[j][bj] = *(const float2*)(xl + (m * 16 + j) * XROW + bj * 512);
; #pragma unroll
;           for (int j = 0; j < 4; ++j) {
;             float ss = 0.f;
; #pragma unroll
;             for (int bj = 0; bj < 2; ++bj) {
;               float2 xn;
;               xn.x = xv[j][bj].x + gt[bj][0] * acc[ai][bj][m][0][j];
;               xn.y = xv[j][bj].y + gt[bj][1] * acc[ai][bj][m][1][j];
;               const unsigned o = tb + (unsigned)((ai * 128 + m * 16 + j) * 1024 + bj * 128);
;               *(float2*)(xout_t + o) = xn;
;               if (g.has_next) *(unsigned*)(xg_t + o) = pack2(xn.x * gn[bj][0], xn.y * gn[bj][1]);
;               ss += xn.x * xn.x + xn.y * xn.y;
;             }
;             if (g.has_next) {
;               ss = dpp_row_sum16(ss);
;               if (fr == 0) rss_t[(wr * 64 + fq * 4 + ai * 128 + m * 16 + j) * 16] = ss;
;             }
.LBB0_377:
	v_pk_mul_f32 v[156:157], v[126:127], v[130:131]
	v_pk_mul_f32 v[154:155], v[122:123], v[130:131]
	v_pk_mul_f32 v[122:123], v[140:141], v[132:133]
	v_pk_mul_f32 v[152:153], v[138:139], v[130:131]
	v_pk_mul_f32 v[126:127], v[136:137], v[132:133]
	v_pk_mul_f32 v[130:131], v[134:135], v[130:131]
	v_add_u32_e32 v162, 0x100, v195
	ds_read2st64_b64 v[146:149], v162 offset0:32 offset1:33
	v_add_u32_e32 v163, 0x110, v195
	v_add_u32_e32 v164, 0x120, v195
	v_add_u32_e32 v165, 0x130, v195
	ds_read2st64_b64 v[142:145], v163 offset0:34 offset1:35
	ds_read2st64_b64 v[138:141], v164 offset0:36 offset1:37
	ds_read2st64_b64 v[134:137], v165 offset0:38 offset1:39
	v_or_b32_e32 v160, 0x4000, v0
	v_mov_b32_e32 v158, v156
	v_mov_b32_e32 v159, v154
	v_mov_b32_e32 v161, v1
	s_waitcnt lgkmcnt(3)
	v_pk_fma_f32 v[158:159], v[158:159], v[184:185], v[146:147]
	v_lshl_add_u64 v[146:147], v[160:161], 2, s[2:3]
	global_store_dwordx2 v[146:147], v[158:159], off
	s_mov_b64 s[68:69], -1
	s_and_b64 vcc, exec, s[6:7]
	v_or_b32_e32 v146, 0x4080, v0
	s_cbranch_vccnz .LBB0_381
	v_pk_mul_f32 v[166:167], v[182:183], v[158:159]
	v_lshl_add_u64 v[160:161], v[160:161], 1, s[8:9]
	s_nop 0
	v_and_b32_sdwa v147, v167, v178 dst_sel:DWORD dst_unused:UNUSED_PAD src0_sel:WORD_1 src1_sel:DWORD
	v_cvt_pk_bf16_f32 v154, v166, v166
	v_add3_u32 v147, v167, v147, s81
	v_lshrrev_b32_e32 v154, 16, v154
	v_and_or_b32 v147, v147, s28, v154
	global_store_dword v[160:161], v147, off
	v_mov_b32_e32 v160, v152
	v_mov_b32_e32 v161, v130
	v_mov_b32_e32 v147, v1
	v_pk_fma_f32 v[160:161], v[160:161], v[180:181], v[148:149]
	v_lshl_add_u64 v[166:167], v[146:147], 2, s[2:3]
	global_store_dwordx2 v[166:167], v[160:161], off
	v_pk_mul_f32 v[166:167], v[186:187], v[160:161]
	v_pk_mul_f32 v[158:159], v[158:159], v[158:159]
	s_nop 0
	v_and_b32_sdwa v154, v167, v178 dst_sel:DWORD dst_unused:UNUSED_PAD src0_sel:WORD_1 src1_sel:DWORD
	v_cvt_pk_bf16_f32 v156, v166, v166
	v_add3_u32 v154, v167, v154, s81
	v_lshrrev_b32_e32 v156, 16, v156
	v_and_or_b32 v154, v154, s28, v156
	v_lshl_add_u64 v[166:167], v[146:147], 1, s[8:9]
	v_pk_mul_f32 v[160:161], v[160:161], v[160:161]
	global_store_dword v[166:167], v154, off
	v_add_f32_e32 v147, v160, v161
	v_add_f32_e32 v154, v158, v159
	v_add_f32_e32 v147, v154, v147
	s_nop 1
	v_add_f32_dpp v147, v147, v147 quad_perm:[1,0,3,2] row_mask:0xf bank_mask:0xf bound_ctrl:1
	s_nop 1
	v_add_f32_dpp v147, v147, v147 quad_perm:[2,3,0,1] row_mask:0xf bank_mask:0xf bound_ctrl:1
	s_nop 1
	v_add_f32_dpp v147, v147, v147 row_half_mirror row_mask:0xf bank_mask:0xf bound_ctrl:1
	s_nop 1
	v_mov_b32_dpp v154, v147 row_mirror row_mask:0xf bank_mask:0xf bound_ctrl:1
	s_and_saveexec_b64 s[68:69], s[4:5]
	s_cbranch_execz .LBB0_380
	v_lshlrev_b32_e32 v158, 4, v194
	v_ashrrev_i32_e32 v159, 31, v158
	v_add_f32_e32 v147, v147, v154
	v_lshl_add_u64 v[158:159], v[158:159], 2, v[150:151]
	global_store_dword v[158:159], v147, off offset:1024

; __device__ __forceinline__ unsigned pack2(float a, float b) { return (unsigned)f2bf(a) | ((unsigned)f2bf(b) << 16); }
; template <int EPI, bool HS = false>
; __device__ __forceinline__ void gemm_phase(const Params& p, const GemmCfg& g, char* shm, const int wave_s) {
;     ...
;           for (int j = 0; j < 4; ++j) {
;             float ss = 0.f;
; #pragma unroll
;             for (int bj = 0; bj < 2; ++bj) {
;               float2 xn;
;               xn.x = xv[j][bj].x + gt[bj][0] * acc[ai][bj][m][0][j];
;               xn.y = xv[j][bj].y + gt[bj][1] * acc[ai][bj][m][1][j];
;               const unsigned o = tb + (unsigned)((ai * 128 + m * 16 + j) * 1024 + bj * 128);
;               *(float2*)(xout_t + o) = xn;
;               if (g.has_next) *(unsigned*)(xg_t + o) = pack2(xn.x * gn[bj][0], xn.y * gn[bj][1]);
;               ss += xn.x * xn.x + xn.y * xn.y;
;             }
;             if (g.has_next) {
;               ss = dpp_row_sum16(ss);
;               if (fr == 0) rss_t[(wr * 64 + fq * 4 + ai * 128 + m * 16 + j) * 16] = ss;
;             }
.LBB0_383:
	v_or_b32_e32 v146, 0x4400, v0
	v_mov_b32_e32 v154, v157
	v_mov_b32_e32 v147, v1
	v_pk_mul_f32 v[128:129], v[128:129], v[132:133]
	v_pk_mul_f32 v[124:125], v[124:125], v[132:133]
	s_waitcnt lgkmcnt(2)
	v_pk_fma_f32 v[142:143], v[154:155], v[184:185], v[142:143]
	v_lshl_add_u64 v[132:133], v[146:147], 2, s[2:3]
	global_store_dwordx2 v[132:133], v[142:143], off
	s_mov_b64 s[68:69], -1
	s_and_b64 vcc, exec, s[6:7]
	v_or_b32_e32 v132, 0x4480, v0
	s_cbranch_vccnz .LBB0_387
	v_pk_mul_f32 v[148:149], v[182:183], v[142:143]
	v_lshl_add_u64 v[146:147], v[146:147], 1, s[8:9]
	s_nop 0
	v_and_b32_sdwa v130, v149, v178 dst_sel:DWORD dst_unused:UNUSED_PAD src0_sel:WORD_1 src1_sel:DWORD
	v_cvt_pk_bf16_f32 v133, v148, v148
	v_add3_u32 v130, v149, v130, s81
	v_lshrrev_b32_e32 v133, 16, v133
	v_and_or_b32 v130, v130, s28, v133
	global_store_dword v[146:147], v130, off
	v_mov_b32_e32 v130, v153
	v_mov_b32_e32 v133, v1
	v_pk_fma_f32 v[146:147], v[130:131], v[180:181], v[144:145]
	v_lshl_add_u64 v[148:149], v[132:133], 2, s[2:3]
	global_store_dwordx2 v[148:149], v[146:147], off
	v_pk_mul_f32 v[148:149], v[186:187], v[146:147]
	v_pk_mul_f32 v[142:143], v[142:143], v[142:143]
	v_and_b32_sdwa v152, v148, v178 dst_sel:DWORD dst_unused:UNUSED_PAD src0_sel:WORD_1 src1_sel:DWORD
	v_and_b32_sdwa v130, v149, v178 dst_sel:DWORD dst_unused:UNUSED_PAD src0_sel:WORD_1 src1_sel:DWORD
	v_add3_u32 v148, v148, v152, s81
	v_add3_u32 v130, v149, v130, s81
	v_lshrrev_b32_e32 v148, 16, v148
	v_and_or_b32 v130, v130, s28, v148
	v_lshl_add_u64 v[148:149], v[132:133], 1, s[8:9]
	v_pk_mul_f32 v[146:147], v[146:147], v[146:147]
	global_store_dword v[148:149], v130, off
	v_add_f32_e32 v130, v146, v147
	v_add_f32_e32 v133, v142, v143
	v_add_f32_e32 v130, v133, v130
	s_nop 1
	v_add_f32_dpp v130, v130, v130 quad_perm:[1,0,3,2] row_mask:0xf bank_mask:0xf bound_ctrl:1
	s_nop 1
	v_add_f32_dpp v130, v130, v130 quad_perm:[2,3,0,1] row_mask:0xf bank_mask:0xf bound_ctrl:1
	s_nop 1
	v_add_f32_dpp v130, v130, v130 row_half_mirror row_mask:0xf bank_mask:0xf bound_ctrl:1
	s_nop 1
	v_mov_b32_dpp v133, v130 row_mirror row_mask:0xf bank_mask:0xf bound_ctrl:1
	s_and_saveexec_b64 s[68:69], s[4:5]
	s_cbranch_execz .LBB0_386
	v_lshlrev_b32_e32 v142, 4, v194
	v_ashrrev_i32_e32 v143, 31, v142
	v_add_f32_e32 v130, v130, v133
	v_lshl_add_u64 v[142:143], v[142:143], 2, v[150:151]
	global_store_dword v[142:143], v130, off offset:1088

; __device__ __forceinline__ unsigned pack2(float a, float b) { return (unsigned)f2bf(a) | ((unsigned)f2bf(b) << 16); }
; template <int EPI, bool HS = false>
; __device__ __forceinline__ void gemm_phase(const Params& p, const GemmCfg& g, char* shm, const int wave_s) {
;     ...
;           for (int j = 0; j < 4; ++j) {
;             float ss = 0.f;
; #pragma unroll
;             for (int bj = 0; bj < 2; ++bj) {
;               float2 xn;
;               xn.x = xv[j][bj].x + gt[bj][0] * acc[ai][bj][m][0][j];
;               xn.y = xv[j][bj].y + gt[bj][1] * acc[ai][bj][m][1][j];
;               const unsigned o = tb + (unsigned)((ai * 128 + m * 16 + j) * 1024 + bj * 128);
;               *(float2*)(xout_t + o) = xn;
;               if (g.has_next) *(unsigned*)(xg_t + o) = pack2(xn.x * gn[bj][0], xn.y * gn[bj][1]);
;               ss += xn.x * xn.x + xn.y * xn.y;
;             }
;             if (g.has_next) {
;               ss = dpp_row_sum16(ss);
;               if (fr == 0) rss_t[(wr * 64 + fq * 4 + ai * 128 + m * 16 + j) * 16] = ss;
;             }
.LBB0_389:
	v_or_b32_e32 v142, 0x4800, v0
	v_mov_b32_e32 v130, v128
	v_mov_b32_e32 v131, v124
	v_mov_b32_e32 v143, v1
	s_waitcnt lgkmcnt(1)
	v_pk_fma_f32 v[132:133], v[130:131], v[184:185], v[138:139]
	v_lshl_add_u64 v[130:131], v[142:143], 2, s[2:3]
	global_store_dwordx2 v[130:131], v[132:133], off
	s_mov_b64 s[68:69], -1
	s_and_b64 vcc, exec, s[6:7]
	v_or_b32_e32 v130, 0x4880, v0
	s_cbranch_vccnz .LBB0_393
	v_pk_mul_f32 v[138:139], v[182:183], v[132:133]
	v_mov_b32_e32 v131, v1
	s_nop 0
	v_and_b32_sdwa v124, v139, v178 dst_sel:DWORD dst_unused:UNUSED_PAD src0_sel:WORD_1 src1_sel:DWORD
	v_cvt_pk_bf16_f32 v128, v138, v138
	v_add3_u32 v124, v139, v124, s81
	v_lshrrev_b32_e32 v128, 16, v128
	v_and_or_b32 v124, v124, s28, v128
	v_lshl_add_u64 v[138:139], v[142:143], 1, s[8:9]
	global_store_dword v[138:139], v124, off
	v_mov_b32_e32 v138, v122
	v_mov_b32_e32 v139, v126
	v_pk_fma_f32 v[138:139], v[138:139], v[180:181], v[140:141]
	v_lshl_add_u64 v[142:143], v[130:131], 2, s[2:3]
	global_store_dwordx2 v[142:143], v[138:139], off
	v_pk_mul_f32 v[142:143], v[186:187], v[138:139]
	v_pk_mul_f32 v[132:133], v[132:133], v[132:133]
	s_nop 0
	v_and_b32_sdwa v124, v143, v178 dst_sel:DWORD dst_unused:UNUSED_PAD src0_sel:WORD_1 src1_sel:DWORD
	v_cvt_pk_bf16_f32 v128, v142, v142
	v_add3_u32 v124, v143, v124, s81
	v_lshrrev_b32_e32 v128, 16, v128
	v_and_or_b32 v124, v124, s28, v128
	v_lshl_add_u64 v[142:143], v[130:131], 1, s[8:9]
	v_pk_mul_f32 v[138:139], v[138:139], v[138:139]
	global_store_dword v[142:143], v124, off
	v_add_f32_e32 v124, v138, v139
	v_add_f32_e32 v128, v132, v133
	v_add_f32_e32 v124, v128, v124
	s_nop 1
	v_add_f32_dpp v124, v124, v124 quad_perm:[1,0,3,2] row_mask:0xf bank_mask:0xf bound_ctrl:1
	s_nop 1
	v_add_f32_dpp v124, v124, v124 quad_perm:[2,3,0,1] row_mask:0xf bank_mask:0xf bound_ctrl:1
	s_nop 1
	v_add_f32_dpp v124, v124, v124 row_half_mirror row_mask:0xf bank_mask:0xf bound_ctrl:1
	s_nop 1
	v_mov_b32_dpp v128, v124 row_mirror row_mask:0xf bank_mask:0xf bound_ctrl:1
	s_and_saveexec_b64 s[68:69], s[4:5]
	s_cbranch_execz .LBB0_392
	v_lshlrev_b32_e32 v132, 4, v194
	v_ashrrev_i32_e32 v133, 31, v132
	v_add_f32_e32 v124, v124, v128
	v_lshl_add_u64 v[132:133], v[132:133], 2, v[150:151]
	global_store_dword v[132:133], v124, off offset:1152

; __device__ __forceinline__ unsigned pack2(float a, float b) { return (unsigned)f2bf(a) | ((unsigned)f2bf(b) << 16); }
; template <int EPI, bool HS = false>
; __device__ __forceinline__ void gemm_phase(const Params& p, const GemmCfg& g, char* shm, const int wave_s) {
;     ...
;           for (int j = 0; j < 4; ++j) {
;             float ss = 0.f;
; #pragma unroll
;             for (int bj = 0; bj < 2; ++bj) {
;               float2 xn;
;               xn.x = xv[j][bj].x + gt[bj][0] * acc[ai][bj][m][0][j];
;               xn.y = xv[j][bj].y + gt[bj][1] * acc[ai][bj][m][1][j];
;               const unsigned o = tb + (unsigned)((ai * 128 + m * 16 + j) * 1024 + bj * 128);
;               *(float2*)(xout_t + o) = xn;
;               if (g.has_next) *(unsigned*)(xg_t + o) = pack2(xn.x * gn[bj][0], xn.y * gn[bj][1]);
;               ss += xn.x * xn.x + xn.y * xn.y;
;             }
;             if (g.has_next) {
;               ss = dpp_row_sum16(ss);
;               if (fr == 0) rss_t[(wr * 64 + fq * 4 + ai * 128 + m * 16 + j) * 16] = ss;
;             }
.LBB0_395:
	v_or_b32_e32 v130, 0x4c00, v0
	v_mov_b32_e32 v124, v129
	v_mov_b32_e32 v131, v1
	s_waitcnt lgkmcnt(0)
	v_pk_fma_f32 v[128:129], v[124:125], v[184:185], v[134:135]
	v_lshl_add_u64 v[124:125], v[130:131], 2, s[2:3]
	global_store_dwordx2 v[124:125], v[128:129], off
	s_mov_b64 s[68:69], -1
	s_and_b64 vcc, exec, s[6:7]
	v_or_b32_e32 v124, 0x4c80, v0
	s_cbranch_vccnz .LBB0_399
	v_pk_mul_f32 v[132:133], v[182:183], v[128:129]
	v_lshl_add_u64 v[130:131], v[130:131], 1, s[8:9]
	s_nop 0
	v_and_b32_sdwa v122, v133, v178 dst_sel:DWORD dst_unused:UNUSED_PAD src0_sel:WORD_1 src1_sel:DWORD
	v_cvt_pk_bf16_f32 v125, v132, v132
	v_add3_u32 v122, v133, v122, s81
	v_lshrrev_b32_e32 v125, 16, v125
	v_and_or_b32 v122, v122, s28, v125
	v_mov_b32_e32 v126, v123
	v_mov_b32_e32 v125, v1
	global_store_dword v[130:131], v122, off
	v_pk_fma_f32 v[130:131], v[126:127], v[180:181], v[136:137]
	v_lshl_add_u64 v[132:133], v[124:125], 2, s[2:3]
	global_store_dwordx2 v[132:133], v[130:131], off
	v_pk_mul_f32 v[132:133], v[186:187], v[130:131]
	v_pk_mul_f32 v[128:129], v[128:129], v[128:129]
	s_nop 0
	v_and_b32_sdwa v122, v133, v178 dst_sel:DWORD dst_unused:UNUSED_PAD src0_sel:WORD_1 src1_sel:DWORD
	v_cvt_pk_bf16_f32 v126, v132, v132
	v_add3_u32 v122, v133, v122, s81
	v_lshrrev_b32_e32 v126, 16, v126
	v_and_or_b32 v122, v122, s28, v126
	v_lshl_add_u64 v[132:133], v[124:125], 1, s[8:9]
	v_pk_mul_f32 v[130:131], v[130:131], v[130:131]
	global_store_dword v[132:133], v122, off
	v_add_f32_e32 v122, v130, v131
	v_add_f32_e32 v125, v128, v129
	v_add_f32_e32 v122, v125, v122
	s_nop 1
	v_add_f32_dpp v122, v122, v122 quad_perm:[1,0,3,2] row_mask:0xf bank_mask:0xf bound_ctrl:1
	s_nop 1
	v_add_f32_dpp v122, v122, v122 quad_perm:[2,3,0,1] row_mask:0xf bank_mask:0xf bound_ctrl:1
	s_nop 1
	v_add_f32_dpp v122, v122, v122 row_half_mirror row_mask:0xf bank_mask:0xf bound_ctrl:1
	s_nop 1
	v_mov_b32_dpp v125, v122 row_mirror row_mask:0xf bank_mask:0xf bound_ctrl:1
	s_and_saveexec_b64 s[68:69], s[4:5]
	s_cbranch_execz .LBB0_398
	v_lshlrev_b32_e32 v128, 4, v194
	v_ashrrev_i32_e32 v129, 31, v128
	v_add_f32_e32 v122, v122, v125
	v_lshl_add_u64 v[128:129], v[128:129], 2, v[150:151]
	global_store_dword v[128:129], v122, off offset:1216

; __device__ __forceinline__ unsigned pack2(float a, float b) { return (unsigned)f2bf(a) | ((unsigned)f2bf(b) << 16); }
; #define SCHED __builtin_amdgcn_sched_barrier(0)
; template <bool HS>
; __device__ __forceinline__ void gemm_tile8(const u16* __restrict__ Ap, const u16* __restrict__ Bp, int K,
;                                            f32x4 (&acc)[2][2][4][2], char* shm, const int tid, const float* hsr = nullptr) {
;     ...
;       for (int m = 0; m < 4; ++m) {
;         const f32x4 q4 = *(const f32x4*)(rt + ai * 128 + m * 16);
; #pragma unroll
;         for (int bj = 0; bj < 2; ++bj)
; #pragma unroll
;           for (int n = 0; n < 2; ++n) acc[ai][bj][m][n] *= q4;
;         SCHED;
;       }
; template <int EPI, bool HS = false>
; __device__ __forceinline__ void gemm_phase(const Params& p, const GemmCfg& g, char* shm, const int wave_s) {
;     ...
;             for (int bj = 0; bj < 2; ++bj) xv[j][bj] = *(const float2*)(xl + (m * 16 + j) * XROW + bj * 512);
; #pragma unroll
;           for (int j = 0; j < 4; ++j) {
;             float ss = 0.f;
; #pragma unroll
;             for (int bj = 0; bj < 2; ++bj) {
;               float2 xn;
;               xn.x = xv[j][bj].x + gt[bj][0] * acc[ai][bj][m][0][j];
;               xn.y = xv[j][bj].y + gt[bj][1] * acc[ai][bj][m][1][j];
;               const unsigned o = tb + (unsigned)((ai * 128 + m * 16 + j) * 1024 + bj * 128);
;               *(float2*)(xout_t + o) = xn;
;               if (g.has_next) *(unsigned*)(xg_t + o) = pack2(xn.x * gn[bj][0], xn.y * gn[bj][1]);
;               ss += xn.x * xn.x + xn.y * xn.y;
;             }
;             if (g.has_next) {
;               ss = dpp_row_sum16(ss);
;               if (fr == 0) rss_t[(wr * 64 + fq * 4 + ai * 128 + m * 16 + j) * 16] = ss;
;             }
.LBB0_401:
	v_pk_mul_f32 v[134:135], v[106:107], v[110:111]
	v_pk_mul_f32 v[132:133], v[102:103], v[110:111]
	v_pk_mul_f32 v[102:103], v[120:121], v[112:113]
	v_pk_mul_f32 v[130:131], v[118:119], v[110:111]
	v_pk_mul_f32 v[106:107], v[116:117], v[112:113]
	v_pk_mul_f32 v[110:111], v[114:115], v[110:111]
	ds_read2st64_b64 v[126:129], v195 offset0:65 offset1:66
	v_add_u32_e32 v140, 16, v195
	ds_read2st64_b64 v[122:125], v140 offset0:67 offset1:68
	ds_read2st64_b64 v[118:121], v196 offset0:69 offset1:70
	ds_read2st64_b64 v[114:117], v197 offset0:71 offset1:72
	v_or_b32_e32 v138, 0x8000, v0
	v_mov_b32_e32 v136, v134
	v_mov_b32_e32 v137, v132
	v_mov_b32_e32 v139, v1
	s_waitcnt lgkmcnt(3)
	v_pk_fma_f32 v[136:137], v[136:137], v[184:185], v[126:127]
	v_lshl_add_u64 v[126:127], v[138:139], 2, s[2:3]
	global_store_dwordx2 v[126:127], v[136:137], off
	s_mov_b64 s[68:69], -1
	s_and_b64 vcc, exec, s[6:7]
	v_or_b32_e32 v126, 0x8080, v0
	s_cbranch_vccnz .LBB0_405
	v_pk_mul_f32 v[142:143], v[182:183], v[136:137]
	v_lshl_add_u64 v[138:139], v[138:139], 1, s[8:9]
	s_nop 0
	v_and_b32_sdwa v127, v143, v178 dst_sel:DWORD dst_unused:UNUSED_PAD src0_sel:WORD_1 src1_sel:DWORD
	v_cvt_pk_bf16_f32 v132, v142, v142
	v_add3_u32 v127, v143, v127, s81
	v_lshrrev_b32_e32 v132, 16, v132
	v_and_or_b32 v127, v127, s28, v132
	global_store_dword v[138:139], v127, off
	v_mov_b32_e32 v138, v130
	v_mov_b32_e32 v139, v110
	v_mov_b32_e32 v127, v1
	v_pk_fma_f32 v[138:139], v[138:139], v[180:181], v[128:129]
	v_lshl_add_u64 v[142:143], v[126:127], 2, s[2:3]
	global_store_dwordx2 v[142:143], v[138:139], off
	v_pk_mul_f32 v[142:143], v[186:187], v[138:139]
	v_pk_mul_f32 v[136:137], v[136:137], v[136:137]
	s_nop 0
	v_and_b32_sdwa v132, v143, v178 dst_sel:DWORD dst_unused:UNUSED_PAD src0_sel:WORD_1 src1_sel:DWORD
	v_cvt_pk_bf16_f32 v134, v142, v142
	v_add3_u32 v132, v143, v132, s81
	v_lshrrev_b32_e32 v134, 16, v134
	v_and_or_b32 v132, v132, s28, v134
	v_lshl_add_u64 v[142:143], v[126:127], 1, s[8:9]
	v_pk_mul_f32 v[138:139], v[138:139], v[138:139]
	global_store_dword v[142:143], v132, off
	v_add_f32_e32 v127, v138, v139
	v_add_f32_e32 v132, v136, v137
	v_add_f32_e32 v127, v132, v127
	s_nop 1
	v_add_f32_dpp v127, v127, v127 quad_perm:[1,0,3,2] row_mask:0xf bank_mask:0xf bound_ctrl:1
	s_nop 1
	v_add_f32_dpp v127, v127, v127 quad_perm:[2,3,0,1] row_mask:0xf bank_mask:0xf bound_ctrl:1
	s_nop 1
	v_add_f32_dpp v127, v127, v127 row_half_mirror row_mask:0xf bank_mask:0xf bound_ctrl:1
	s_nop 1
	v_mov_b32_dpp v132, v127 row_mirror row_mask:0xf bank_mask:0xf bound_ctrl:1
	s_and_saveexec_b64 s[68:69], s[4:5]
	s_cbranch_execz .LBB0_404
	v_lshlrev_b32_e32 v136, 4, v194
	v_ashrrev_i32_e32 v137, 31, v136
	v_add_f32_e32 v127, v127, v132
	v_lshl_add_u64 v[136:137], v[136:137], 2, v[150:151]
	global_store_dword v[136:137], v127, off offset:2048

; __device__ __forceinline__ unsigned pack2(float a, float b) { return (unsigned)f2bf(a) | ((unsigned)f2bf(b) << 16); }
; template <int EPI, bool HS = false>
; __device__ __forceinline__ void gemm_phase(const Params& p, const GemmCfg& g, char* shm, const int wave_s) {
;     ...
;           for (int j = 0; j < 4; ++j) {
;             float ss = 0.f;
; #pragma unroll
;             for (int bj = 0; bj < 2; ++bj) {
;               float2 xn;
;               xn.x = xv[j][bj].x + gt[bj][0] * acc[ai][bj][m][0][j];
;               xn.y = xv[j][bj].y + gt[bj][1] * acc[ai][bj][m][1][j];
;               const unsigned o = tb + (unsigned)((ai * 128 + m * 16 + j) * 1024 + bj * 128);
;               *(float2*)(xout_t + o) = xn;
;               if (g.has_next) *(unsigned*)(xg_t + o) = pack2(xn.x * gn[bj][0], xn.y * gn[bj][1]);
;               ss += xn.x * xn.x + xn.y * xn.y;
;             }
;             if (g.has_next) {
;               ss = dpp_row_sum16(ss);
;               if (fr == 0) rss_t[(wr * 64 + fq * 4 + ai * 128 + m * 16 + j) * 16] = ss;
;             }
.LBB0_407:
	v_or_b32_e32 v126, 0x8400, v0
	v_mov_b32_e32 v132, v135
	v_mov_b32_e32 v127, v1
	v_pk_mul_f32 v[108:109], v[108:109], v[112:113]
	v_pk_mul_f32 v[104:105], v[104:105], v[112:113]
	s_waitcnt lgkmcnt(2)
	v_pk_fma_f32 v[122:123], v[132:133], v[184:185], v[122:123]
	v_lshl_add_u64 v[112:113], v[126:127], 2, s[2:3]
	global_store_dwordx2 v[112:113], v[122:123], off
	s_mov_b64 s[68:69], -1
	s_and_b64 vcc, exec, s[6:7]
	v_or_b32_e32 v112, 0x8480, v0
	s_cbranch_vccnz .LBB0_411
	v_pk_mul_f32 v[128:129], v[182:183], v[122:123]
	v_lshl_add_u64 v[126:127], v[126:127], 1, s[8:9]
	s_nop 0
	v_and_b32_sdwa v110, v129, v178 dst_sel:DWORD dst_unused:UNUSED_PAD src0_sel:WORD_1 src1_sel:DWORD
	v_cvt_pk_bf16_f32 v113, v128, v128
	v_add3_u32 v110, v129, v110, s81
	v_lshrrev_b32_e32 v113, 16, v113
	v_and_or_b32 v110, v110, s28, v113
	global_store_dword v[126:127], v110, off
	v_mov_b32_e32 v110, v131
	v_mov_b32_e32 v113, v1
	v_pk_fma_f32 v[126:127], v[110:111], v[180:181], v[124:125]
	v_lshl_add_u64 v[128:129], v[112:113], 2, s[2:3]
	global_store_dwordx2 v[128:129], v[126:127], off
	v_pk_mul_f32 v[128:129], v[186:187], v[126:127]
	v_pk_mul_f32 v[122:123], v[122:123], v[122:123]
	v_and_b32_sdwa v130, v128, v178 dst_sel:DWORD dst_unused:UNUSED_PAD src0_sel:WORD_1 src1_sel:DWORD
	v_and_b32_sdwa v110, v129, v178 dst_sel:DWORD dst_unused:UNUSED_PAD src0_sel:WORD_1 src1_sel:DWORD
	v_add3_u32 v128, v128, v130, s81
	v_add3_u32 v110, v129, v110, s81
	v_lshrrev_b32_e32 v128, 16, v128
	v_and_or_b32 v110, v110, s28, v128
	v_lshl_add_u64 v[128:129], v[112:113], 1, s[8:9]
	v_pk_mul_f32 v[126:127], v[126:127], v[126:127]
	global_store_dword v[128:129], v110, off
	v_add_f32_e32 v110, v126, v127
	v_add_f32_e32 v113, v122, v123
	v_add_f32_e32 v110, v113, v110
	s_nop 1
	v_add_f32_dpp v110, v110, v110 quad_perm:[1,0,3,2] row_mask:0xf bank_mask:0xf bound_ctrl:1
	s_nop 1
	v_add_f32_dpp v110, v110, v110 quad_perm:[2,3,0,1] row_mask:0xf bank_mask:0xf bound_ctrl:1
	s_nop 1
	v_add_f32_dpp v110, v110, v110 row_half_mirror row_mask:0xf bank_mask:0xf bound_ctrl:1
	s_nop 1
	v_mov_b32_dpp v113, v110 row_mirror row_mask:0xf bank_mask:0xf bound_ctrl:1
	s_and_saveexec_b64 s[68:69], s[4:5]
	s_cbranch_execz .LBB0_410
	v_lshlrev_b32_e32 v122, 4, v194
	v_ashrrev_i32_e32 v123, 31, v122
	v_add_f32_e32 v110, v110, v113
	v_lshl_add_u64 v[122:123], v[122:123], 2, v[150:151]
	global_store_dword v[122:123], v110, off offset:2112

; __device__ __forceinline__ unsigned pack2(float a, float b) { return (unsigned)f2bf(a) | ((unsigned)f2bf(b) << 16); }
; template <int EPI, bool HS = false>
; __device__ __forceinline__ void gemm_phase(const Params& p, const GemmCfg& g, char* shm, const int wave_s) {
;     ...
;           for (int j = 0; j < 4; ++j) {
;             float ss = 0.f;
; #pragma unroll
;             for (int bj = 0; bj < 2; ++bj) {
;               float2 xn;
;               xn.x = xv[j][bj].x + gt[bj][0] * acc[ai][bj][m][0][j];
;               xn.y = xv[j][bj].y + gt[bj][1] * acc[ai][bj][m][1][j];
;               const unsigned o = tb + (unsigned)((ai * 128 + m * 16 + j) * 1024 + bj * 128);
;               *(float2*)(xout_t + o) = xn;
;               if (g.has_next) *(unsigned*)(xg_t + o) = pack2(xn.x * gn[bj][0], xn.y * gn[bj][1]);
;               ss += xn.x * xn.x + xn.y * xn.y;
;             }
;             if (g.has_next) {
;               ss = dpp_row_sum16(ss);
;               if (fr == 0) rss_t[(wr * 64 + fq * 4 + ai * 128 + m * 16 + j) * 16] = ss;
;             }
.LBB0_413:
	v_or_b32_e32 v122, 0x8800, v0
	v_mov_b32_e32 v110, v108
	v_mov_b32_e32 v111, v104
	v_mov_b32_e32 v123, v1
	s_waitcnt lgkmcnt(1)
	v_pk_fma_f32 v[112:113], v[110:111], v[184:185], v[118:119]
	v_lshl_add_u64 v[110:111], v[122:123], 2, s[2:3]
	global_store_dwordx2 v[110:111], v[112:113], off
	s_mov_b64 s[68:69], -1
	s_and_b64 vcc, exec, s[6:7]
	v_or_b32_e32 v110, 0x8880, v0
	s_cbranch_vccnz .LBB0_417
	v_pk_mul_f32 v[118:119], v[182:183], v[112:113]
	v_mov_b32_e32 v111, v1
	s_nop 0
	v_and_b32_sdwa v104, v119, v178 dst_sel:DWORD dst_unused:UNUSED_PAD src0_sel:WORD_1 src1_sel:DWORD
	v_cvt_pk_bf16_f32 v108, v118, v118
	v_add3_u32 v104, v119, v104, s81
	v_lshrrev_b32_e32 v108, 16, v108
	v_and_or_b32 v104, v104, s28, v108
	v_lshl_add_u64 v[118:119], v[122:123], 1, s[8:9]
	global_store_dword v[118:119], v104, off
	v_mov_b32_e32 v118, v102
	v_mov_b32_e32 v119, v106
	v_pk_fma_f32 v[118:119], v[118:119], v[180:181], v[120:121]
	v_lshl_add_u64 v[122:123], v[110:111], 2, s[2:3]
	global_store_dwordx2 v[122:123], v[118:119], off
	v_pk_mul_f32 v[122:123], v[186:187], v[118:119]
	v_pk_mul_f32 v[112:113], v[112:113], v[112:113]
	s_nop 0
	v_and_b32_sdwa v104, v123, v178 dst_sel:DWORD dst_unused:UNUSED_PAD src0_sel:WORD_1 src1_sel:DWORD
	v_cvt_pk_bf16_f32 v108, v122, v122
	v_add3_u32 v104, v123, v104, s81
	v_lshrrev_b32_e32 v108, 16, v108
	v_and_or_b32 v104, v104, s28, v108
	v_lshl_add_u64 v[122:123], v[110:111], 1, s[8:9]
	v_pk_mul_f32 v[118:119], v[118:119], v[118:119]
	global_store_dword v[122:123], v104, off
	v_add_f32_e32 v104, v118, v119
	v_add_f32_e32 v108, v112, v113
	v_add_f32_e32 v104, v108, v104
	s_nop 1
	v_add_f32_dpp v104, v104, v104 quad_perm:[1,0,3,2] row_mask:0xf bank_mask:0xf bound_ctrl:1
	s_nop 1
	v_add_f32_dpp v104, v104, v104 quad_perm:[2,3,0,1] row_mask:0xf bank_mask:0xf bound_ctrl:1
	s_nop 1
	v_add_f32_dpp v104, v104, v104 row_half_mirror row_mask:0xf bank_mask:0xf bound_ctrl:1
	s_nop 1
	v_mov_b32_dpp v108, v104 row_mirror row_mask:0xf bank_mask:0xf bound_ctrl:1
	s_and_saveexec_b64 s[68:69], s[4:5]
	s_cbranch_execz .LBB0_416
	v_lshlrev_b32_e32 v112, 4, v194
	v_ashrrev_i32_e32 v113, 31, v112
	v_add_f32_e32 v104, v104, v108
	v_lshl_add_u64 v[112:113], v[112:113], 2, v[150:151]
	global_store_dword v[112:113], v104, off offset:2176

; __device__ __forceinline__ unsigned pack2(float a, float b) { return (unsigned)f2bf(a) | ((unsigned)f2bf(b) << 16); }
; template <int EPI, bool HS = false>
; __device__ __forceinline__ void gemm_phase(const Params& p, const GemmCfg& g, char* shm, const int wave_s) {
;     ...
;           for (int j = 0; j < 4; ++j) {
;             float ss = 0.f;
; #pragma unroll
;             for (int bj = 0; bj < 2; ++bj) {
;               float2 xn;
;               xn.x = xv[j][bj].x + gt[bj][0] * acc[ai][bj][m][0][j];
;               xn.y = xv[j][bj].y + gt[bj][1] * acc[ai][bj][m][1][j];
;               const unsigned o = tb + (unsigned)((ai * 128 + m * 16 + j) * 1024 + bj * 128);
;               *(float2*)(xout_t + o) = xn;
;               if (g.has_next) *(unsigned*)(xg_t + o) = pack2(xn.x * gn[bj][0], xn.y * gn[bj][1]);
;               ss += xn.x * xn.x + xn.y * xn.y;
;             }
;             if (g.has_next) {
;               ss = dpp_row_sum16(ss);
;               if (fr == 0) rss_t[(wr * 64 + fq * 4 + ai * 128 + m * 16 + j) * 16] = ss;
;             }
.LBB0_419:
	v_or_b32_e32 v110, 0x8c00, v0
	v_mov_b32_e32 v104, v109
	v_mov_b32_e32 v111, v1
	s_waitcnt lgkmcnt(0)
	v_pk_fma_f32 v[108:109], v[104:105], v[184:185], v[114:115]
	v_lshl_add_u64 v[104:105], v[110:111], 2, s[2:3]
	global_store_dwordx2 v[104:105], v[108:109], off
	s_mov_b64 s[68:69], -1
	s_and_b64 vcc, exec, s[6:7]
	v_or_b32_e32 v104, 0x8c80, v0
	s_cbranch_vccnz .LBB0_423
	v_pk_mul_f32 v[112:113], v[182:183], v[108:109]
	v_lshl_add_u64 v[110:111], v[110:111], 1, s[8:9]
	s_nop 0
	v_and_b32_sdwa v102, v113, v178 dst_sel:DWORD dst_unused:UNUSED_PAD src0_sel:WORD_1 src1_sel:DWORD
	v_cvt_pk_bf16_f32 v105, v112, v112
	v_add3_u32 v102, v113, v102, s81
	v_lshrrev_b32_e32 v105, 16, v105
	v_and_or_b32 v102, v102, s28, v105
	v_mov_b32_e32 v106, v103
	v_mov_b32_e32 v105, v1
	global_store_dword v[110:111], v102, off
	v_pk_fma_f32 v[110:111], v[106:107], v[180:181], v[116:117]
	v_lshl_add_u64 v[112:113], v[104:105], 2, s[2:3]
	global_store_dwordx2 v[112:113], v[110:111], off
	v_pk_mul_f32 v[112:113], v[186:187], v[110:111]
	v_pk_mul_f32 v[108:109], v[108:109], v[108:109]
	s_nop 0
	v_and_b32_sdwa v102, v113, v178 dst_sel:DWORD dst_unused:UNUSED_PAD src0_sel:WORD_1 src1_sel:DWORD
	v_cvt_pk_bf16_f32 v106, v112, v112
	v_add3_u32 v102, v113, v102, s81
	v_lshrrev_b32_e32 v106, 16, v106
	v_and_or_b32 v102, v102, s28, v106
	v_lshl_add_u64 v[112:113], v[104:105], 1, s[8:9]
	v_pk_mul_f32 v[110:111], v[110:111], v[110:111]
	global_store_dword v[112:113], v102, off
	v_add_f32_e32 v102, v110, v111
	v_add_f32_e32 v105, v108, v109
	v_add_f32_e32 v102, v105, v102
	s_nop 1
	v_add_f32_dpp v102, v102, v102 quad_perm:[1,0,3,2] row_mask:0xf bank_mask:0xf bound_ctrl:1
	s_nop 1
	v_add_f32_dpp v102, v102, v102 quad_perm:[2,3,0,1] row_mask:0xf bank_mask:0xf bound_ctrl:1
	s_nop 1
	v_add_f32_dpp v102, v102, v102 row_half_mirror row_mask:0xf bank_mask:0xf bound_ctrl:1
	s_nop 1
	v_mov_b32_dpp v105, v102 row_mirror row_mask:0xf bank_mask:0xf bound_ctrl:1
	s_and_saveexec_b64 s[68:69], s[4:5]
	s_cbranch_execz .LBB0_422
	v_lshlrev_b32_e32 v108, 4, v194
	v_ashrrev_i32_e32 v109, 31, v108
	v_add_f32_e32 v102, v102, v105
	v_lshl_add_u64 v[108:109], v[108:109], 2, v[150:151]
	global_store_dword v[108:109], v102, off offset:2240

; __device__ __forceinline__ unsigned pack2(float a, float b) { return (unsigned)f2bf(a) | ((unsigned)f2bf(b) << 16); }
; #define SCHED __builtin_amdgcn_sched_barrier(0)
; template <bool HS>
; __device__ __forceinline__ void gemm_tile8(const u16* __restrict__ Ap, const u16* __restrict__ Bp, int K,
;                                            f32x4 (&acc)[2][2][4][2], char* shm, const int tid, const float* hsr = nullptr) {
;     ...
;       for (int m = 0; m < 4; ++m) {
;         const f32x4 q4 = *(const f32x4*)(rt + ai * 128 + m * 16);
; #pragma unroll
;         for (int bj = 0; bj < 2; ++bj)
; #pragma unroll
;           for (int n = 0; n < 2; ++n) acc[ai][bj][m][n] *= q4;
;         SCHED;
;       }
; template <int EPI, bool HS = false>
; __device__ __forceinline__ void gemm_phase(const Params& p, const GemmCfg& g, char* shm, const int wave_s) {
;     ...
;             for (int bj = 0; bj < 2; ++bj) xv[j][bj] = *(const float2*)(xl + (m * 16 + j) * XROW + bj * 512);
; #pragma unroll
;           for (int j = 0; j < 4; ++j) {
;             float ss = 0.f;
; #pragma unroll
;             for (int bj = 0; bj < 2; ++bj) {
;               float2 xn;
;               xn.x = xv[j][bj].x + gt[bj][0] * acc[ai][bj][m][0][j];
;               xn.y = xv[j][bj].y + gt[bj][1] * acc[ai][bj][m][1][j];
;               const unsigned o = tb + (unsigned)((ai * 128 + m * 16 + j) * 1024 + bj * 128);
;               *(float2*)(xout_t + o) = xn;
;               if (g.has_next) *(unsigned*)(xg_t + o) = pack2(xn.x * gn[bj][0], xn.y * gn[bj][1]);
;               ss += xn.x * xn.x + xn.y * xn.y;
;             }
;             if (g.has_next) {
;               ss = dpp_row_sum16(ss);
;               if (fr == 0) rss_t[(wr * 64 + fq * 4 + ai * 128 + m * 16 + j) * 16] = ss;
;             }
.LBB0_425:
	v_pk_mul_f32 v[114:115], v[86:87], v[90:91]
	v_pk_mul_f32 v[112:113], v[82:83], v[90:91]
	v_pk_mul_f32 v[82:83], v[100:101], v[92:93]
	v_pk_mul_f32 v[110:111], v[98:99], v[90:91]
	v_pk_mul_f32 v[86:87], v[96:97], v[92:93]
	v_pk_mul_f32 v[90:91], v[94:95], v[90:91]
	ds_read2st64_b64 v[106:109], v162 offset0:97 offset1:98
	ds_read2st64_b64 v[102:105], v163 offset0:99 offset1:100
	ds_read2st64_b64 v[98:101], v164 offset0:101 offset1:102
	ds_read2st64_b64 v[94:97], v165 offset0:103 offset1:104
	v_or_b32_e32 v118, 0xc000, v0
	v_mov_b32_e32 v116, v114
	v_mov_b32_e32 v117, v112
	v_mov_b32_e32 v119, v1
	s_waitcnt lgkmcnt(3)
	v_pk_fma_f32 v[116:117], v[116:117], v[184:185], v[106:107]
	v_lshl_add_u64 v[106:107], v[118:119], 2, s[2:3]
	global_store_dwordx2 v[106:107], v[116:117], off
	s_mov_b64 s[68:69], -1
	s_and_b64 vcc, exec, s[6:7]
	v_or_b32_e32 v106, 0xc080, v0
	s_cbranch_vccnz .LBB0_429
	v_pk_mul_f32 v[120:121], v[182:183], v[116:117]
	v_lshl_add_u64 v[118:119], v[118:119], 1, s[8:9]
	s_nop 0
	v_and_b32_sdwa v107, v121, v178 dst_sel:DWORD dst_unused:UNUSED_PAD src0_sel:WORD_1 src1_sel:DWORD
	v_cvt_pk_bf16_f32 v112, v120, v120
	v_add3_u32 v107, v121, v107, s81
	v_lshrrev_b32_e32 v112, 16, v112
	v_and_or_b32 v107, v107, s28, v112
	global_store_dword v[118:119], v107, off
	v_mov_b32_e32 v118, v110
	v_mov_b32_e32 v119, v90
	v_mov_b32_e32 v107, v1
	v_pk_fma_f32 v[118:119], v[118:119], v[180:181], v[108:109]
	v_lshl_add_u64 v[120:121], v[106:107], 2, s[2:3]
	global_store_dwordx2 v[120:121], v[118:119], off
	v_pk_mul_f32 v[120:121], v[186:187], v[118:119]
	v_pk_mul_f32 v[116:117], v[116:117], v[116:117]
	s_nop 0
	v_and_b32_sdwa v112, v121, v178 dst_sel:DWORD dst_unused:UNUSED_PAD src0_sel:WORD_1 src1_sel:DWORD
	v_cvt_pk_bf16_f32 v114, v120, v120
	v_add3_u32 v112, v121, v112, s81
	v_lshrrev_b32_e32 v114, 16, v114
	v_and_or_b32 v112, v112, s28, v114
	v_lshl_add_u64 v[120:121], v[106:107], 1, s[8:9]
	v_pk_mul_f32 v[118:119], v[118:119], v[118:119]
	global_store_dword v[120:121], v112, off
	v_add_f32_e32 v107, v118, v119
	v_add_f32_e32 v112, v116, v117
	v_add_f32_e32 v107, v112, v107
	s_nop 1
	v_add_f32_dpp v107, v107, v107 quad_perm:[1,0,3,2] row_mask:0xf bank_mask:0xf bound_ctrl:1
	s_nop 1
	v_add_f32_dpp v107, v107, v107 quad_perm:[2,3,0,1] row_mask:0xf bank_mask:0xf bound_ctrl:1
	s_nop 1
	v_add_f32_dpp v107, v107, v107 row_half_mirror row_mask:0xf bank_mask:0xf bound_ctrl:1
	s_nop 1
	v_mov_b32_dpp v112, v107 row_mirror row_mask:0xf bank_mask:0xf bound_ctrl:1
	s_and_saveexec_b64 s[68:69], s[4:5]
	s_cbranch_execz .LBB0_428
	v_lshlrev_b32_e32 v116, 4, v194
	v_ashrrev_i32_e32 v117, 31, v116
	v_add_f32_e32 v107, v107, v112
	v_lshl_add_u64 v[116:117], v[116:117], 2, v[150:151]
	global_store_dword v[116:117], v107, off offset:3072

; __device__ __forceinline__ unsigned pack2(float a, float b) { return (unsigned)f2bf(a) | ((unsigned)f2bf(b) << 16); }
; template <int EPI, bool HS = false>
; __device__ __forceinline__ void gemm_phase(const Params& p, const GemmCfg& g, char* shm, const int wave_s) {
;     ...
;           for (int j = 0; j < 4; ++j) {
;             float ss = 0.f;
; #pragma unroll
;             for (int bj = 0; bj < 2; ++bj) {
;               float2 xn;
;               xn.x = xv[j][bj].x + gt[bj][0] * acc[ai][bj][m][0][j];
;               xn.y = xv[j][bj].y + gt[bj][1] * acc[ai][bj][m][1][j];
;               const unsigned o = tb + (unsigned)((ai * 128 + m * 16 + j) * 1024 + bj * 128);
;               *(float2*)(xout_t + o) = xn;
;               if (g.has_next) *(unsigned*)(xg_t + o) = pack2(xn.x * gn[bj][0], xn.y * gn[bj][1]);
;               ss += xn.x * xn.x + xn.y * xn.y;
;             }
;             if (g.has_next) {
;               ss = dpp_row_sum16(ss);
;               if (fr == 0) rss_t[(wr * 64 + fq * 4 + ai * 128 + m * 16 + j) * 16] = ss;
;             }
.LBB0_431:
	v_or_b32_e32 v106, 0xc400, v0
	v_mov_b32_e32 v112, v115
	v_mov_b32_e32 v107, v1
	v_pk_mul_f32 v[88:89], v[88:89], v[92:93]
	v_pk_mul_f32 v[84:85], v[84:85], v[92:93]
	s_waitcnt lgkmcnt(2)
	v_pk_fma_f32 v[102:103], v[112:113], v[184:185], v[102:103]
	v_lshl_add_u64 v[92:93], v[106:107], 2, s[2:3]
	global_store_dwordx2 v[92:93], v[102:103], off
	s_mov_b64 s[68:69], -1
	s_and_b64 vcc, exec, s[6:7]
	v_or_b32_e32 v92, 0xc480, v0
	s_cbranch_vccnz .LBB0_435
	v_pk_mul_f32 v[108:109], v[182:183], v[102:103]
	v_lshl_add_u64 v[106:107], v[106:107], 1, s[8:9]
	s_nop 0
	v_and_b32_sdwa v90, v109, v178 dst_sel:DWORD dst_unused:UNUSED_PAD src0_sel:WORD_1 src1_sel:DWORD
	v_cvt_pk_bf16_f32 v93, v108, v108
	v_add3_u32 v90, v109, v90, s81
	v_lshrrev_b32_e32 v93, 16, v93
	v_and_or_b32 v90, v90, s28, v93
	global_store_dword v[106:107], v90, off
	v_mov_b32_e32 v90, v111
	v_mov_b32_e32 v93, v1
	v_pk_fma_f32 v[106:107], v[90:91], v[180:181], v[104:105]
	v_lshl_add_u64 v[108:109], v[92:93], 2, s[2:3]
	global_store_dwordx2 v[108:109], v[106:107], off
	v_pk_mul_f32 v[108:109], v[186:187], v[106:107]
	v_pk_mul_f32 v[102:103], v[102:103], v[102:103]
	v_and_b32_sdwa v110, v108, v178 dst_sel:DWORD dst_unused:UNUSED_PAD src0_sel:WORD_1 src1_sel:DWORD
	v_and_b32_sdwa v90, v109, v178 dst_sel:DWORD dst_unused:UNUSED_PAD src0_sel:WORD_1 src1_sel:DWORD
	v_add3_u32 v108, v108, v110, s81
	v_add3_u32 v90, v109, v90, s81
	v_lshrrev_b32_e32 v108, 16, v108
	v_and_or_b32 v90, v90, s28, v108
	v_lshl_add_u64 v[108:109], v[92:93], 1, s[8:9]
	v_pk_mul_f32 v[106:107], v[106:107], v[106:107]
	global_store_dword v[108:109], v90, off
	v_add_f32_e32 v90, v106, v107
	v_add_f32_e32 v93, v102, v103
	v_add_f32_e32 v90, v93, v90
	s_nop 1
	v_add_f32_dpp v90, v90, v90 quad_perm:[1,0,3,2] row_mask:0xf bank_mask:0xf bound_ctrl:1
	s_nop 1
	v_add_f32_dpp v90, v90, v90 quad_perm:[2,3,0,1] row_mask:0xf bank_mask:0xf bound_ctrl:1
	s_nop 1
	v_add_f32_dpp v90, v90, v90 row_half_mirror row_mask:0xf bank_mask:0xf bound_ctrl:1
	s_nop 1
	v_mov_b32_dpp v93, v90 row_mirror row_mask:0xf bank_mask:0xf bound_ctrl:1
	s_and_saveexec_b64 s[68:69], s[4:5]
	s_cbranch_execz .LBB0_434
	v_lshlrev_b32_e32 v102, 4, v194
	v_ashrrev_i32_e32 v103, 31, v102
	v_add_f32_e32 v90, v90, v93
	v_lshl_add_u64 v[102:103], v[102:103], 2, v[150:151]
	global_store_dword v[102:103], v90, off offset:3136

; __device__ __forceinline__ unsigned pack2(float a, float b) { return (unsigned)f2bf(a) | ((unsigned)f2bf(b) << 16); }
; template <int EPI, bool HS = false>
; __device__ __forceinline__ void gemm_phase(const Params& p, const GemmCfg& g, char* shm, const int wave_s) {
;     ...
;             for (int bj = 0; bj < 2; ++bj) xv[j][bj] = *(const float2*)(xl + (m * 16 + j) * XROW + bj * 512);
; #pragma unroll
;           for (int j = 0; j < 4; ++j) {
;             float ss = 0.f;
; #pragma unroll
;             for (int bj = 0; bj < 2; ++bj) {
;               float2 xn;
;               xn.x = xv[j][bj].x + gt[bj][0] * acc[ai][bj][m][0][j];
;               xn.y = xv[j][bj].y + gt[bj][1] * acc[ai][bj][m][1][j];
;               const unsigned o = tb + (unsigned)((ai * 128 + m * 16 + j) * 1024 + bj * 128);
;               *(float2*)(xout_t + o) = xn;
;               if (g.has_next) *(unsigned*)(xg_t + o) = pack2(xn.x * gn[bj][0], xn.y * gn[bj][1]);
;               ss += xn.x * xn.x + xn.y * xn.y;
;             }
;             if (g.has_next) {
;               ss = dpp_row_sum16(ss);
;               if (fr == 0) rss_t[(wr * 64 + fq * 4 + ai * 128 + m * 16 + j) * 16] = ss;
;             }
.LBB0_437:
	v_or_b32_e32 v102, 0xc800, v0
	v_mov_b32_e32 v90, v88
	v_mov_b32_e32 v91, v84
	v_mov_b32_e32 v103, v1
	s_waitcnt lgkmcnt(1)
	v_pk_fma_f32 v[92:93], v[90:91], v[184:185], v[98:99]
	v_lshl_add_u64 v[90:91], v[102:103], 2, s[2:3]
	global_store_dwordx2 v[90:91], v[92:93], off
	s_mov_b64 s[68:69], -1
	s_and_b64 vcc, exec, s[6:7]
	v_or_b32_e32 v90, 0xc880, v0
	s_cbranch_vccnz .LBB0_441
	v_pk_mul_f32 v[98:99], v[182:183], v[92:93]
	v_mov_b32_e32 v91, v1
	s_nop 0
	v_and_b32_sdwa v84, v99, v178 dst_sel:DWORD dst_unused:UNUSED_PAD src0_sel:WORD_1 src1_sel:DWORD
	v_cvt_pk_bf16_f32 v88, v98, v98
	v_add3_u32 v84, v99, v84, s81
	v_lshrrev_b32_e32 v88, 16, v88
	v_and_or_b32 v84, v84, s28, v88
	v_lshl_add_u64 v[98:99], v[102:103], 1, s[8:9]
	global_store_dword v[98:99], v84, off
	v_mov_b32_e32 v98, v82
	v_mov_b32_e32 v99, v86
	v_pk_fma_f32 v[98:99], v[98:99], v[180:181], v[100:101]
	v_lshl_add_u64 v[102:103], v[90:91], 2, s[2:3]
	global_store_dwordx2 v[102:103], v[98:99], off
	v_pk_mul_f32 v[102:103], v[186:187], v[98:99]
	v_pk_mul_f32 v[92:93], v[92:93], v[92:93]
	s_nop 0
	v_and_b32_sdwa v84, v103, v178 dst_sel:DWORD dst_unused:UNUSED_PAD src0_sel:WORD_1 src1_sel:DWORD
	v_cvt_pk_bf16_f32 v88, v102, v102
	v_add3_u32 v84, v103, v84, s81
	v_lshrrev_b32_e32 v88, 16, v88
	v_and_or_b32 v84, v84, s28, v88
	v_lshl_add_u64 v[102:103], v[90:91], 1, s[8:9]
	v_pk_mul_f32 v[98:99], v[98:99], v[98:99]
	global_store_dword v[102:103], v84, off
	v_add_f32_e32 v84, v98, v99
	v_add_f32_e32 v88, v92, v93
	v_add_f32_e32 v84, v88, v84
	s_nop 1
	v_add_f32_dpp v84, v84, v84 quad_perm:[1,0,3,2] row_mask:0xf bank_mask:0xf bound_ctrl:1
	s_nop 1
	v_add_f32_dpp v84, v84, v84 quad_perm:[2,3,0,1] row_mask:0xf bank_mask:0xf bound_ctrl:1
	s_nop 1
	v_add_f32_dpp v84, v84, v84 row_half_mirror row_mask:0xf bank_mask:0xf bound_ctrl:1
	s_nop 1
	v_mov_b32_dpp v88, v84 row_mirror row_mask:0xf bank_mask:0xf bound_ctrl:1
	s_and_saveexec_b64 s[68:69], s[4:5]
	s_cbranch_execz .LBB0_440
	v_lshlrev_b32_e32 v92, 4, v194
	v_ashrrev_i32_e32 v93, 31, v92
	v_add_f32_e32 v84, v84, v88
	v_lshl_add_u64 v[92:93], v[92:93], 2, v[150:151]
	global_store_dword v[92:93], v84, off offset:3200

; __device__ __forceinline__ unsigned pack2(float a, float b) { return (unsigned)f2bf(a) | ((unsigned)f2bf(b) << 16); }
; template <int EPI, bool HS = false>
; __device__ __forceinline__ void gemm_phase(const Params& p, const GemmCfg& g, char* shm, const int wave_s) {
;     ...
;             for (int bj = 0; bj < 2; ++bj) xv[j][bj] = *(const float2*)(xl + (m * 16 + j) * XROW + bj * 512);
; #pragma unroll
;           for (int j = 0; j < 4; ++j) {
;             float ss = 0.f;
; #pragma unroll
;             for (int bj = 0; bj < 2; ++bj) {
;               float2 xn;
;               xn.x = xv[j][bj].x + gt[bj][0] * acc[ai][bj][m][0][j];
;               xn.y = xv[j][bj].y + gt[bj][1] * acc[ai][bj][m][1][j];
;               const unsigned o = tb + (unsigned)((ai * 128 + m * 16 + j) * 1024 + bj * 128);
;               *(float2*)(xout_t + o) = xn;
;               if (g.has_next) *(unsigned*)(xg_t + o) = pack2(xn.x * gn[bj][0], xn.y * gn[bj][1]);
;               ss += xn.x * xn.x + xn.y * xn.y;
;             }
;             if (g.has_next) {
;               ss = dpp_row_sum16(ss);
;               if (fr == 0) rss_t[(wr * 64 + fq * 4 + ai * 128 + m * 16 + j) * 16] = ss;
;             }
.LBB0_443:
	v_or_b32_e32 v90, 0xcc00, v0
	v_mov_b32_e32 v84, v89
	v_mov_b32_e32 v91, v1
	s_waitcnt lgkmcnt(0)
	v_pk_fma_f32 v[88:89], v[84:85], v[184:185], v[94:95]
	v_lshl_add_u64 v[84:85], v[90:91], 2, s[2:3]
	global_store_dwordx2 v[84:85], v[88:89], off
	s_mov_b64 s[68:69], -1
	s_and_b64 vcc, exec, s[6:7]
	v_or_b32_e32 v84, 0xcc80, v0
	s_cbranch_vccnz .LBB0_447
	v_pk_mul_f32 v[92:93], v[182:183], v[88:89]
	v_lshl_add_u64 v[90:91], v[90:91], 1, s[8:9]
	s_nop 0
	v_and_b32_sdwa v82, v93, v178 dst_sel:DWORD dst_unused:UNUSED_PAD src0_sel:WORD_1 src1_sel:DWORD
	v_cvt_pk_bf16_f32 v85, v92, v92
	v_add3_u32 v82, v93, v82, s81
	v_lshrrev_b32_e32 v85, 16, v85
	v_and_or_b32 v82, v82, s28, v85
	v_mov_b32_e32 v86, v83
	v_mov_b32_e32 v85, v1
	global_store_dword v[90:91], v82, off
	v_pk_fma_f32 v[90:91], v[86:87], v[180:181], v[96:97]
	v_lshl_add_u64 v[92:93], v[84:85], 2, s[2:3]
	global_store_dwordx2 v[92:93], v[90:91], off
	v_pk_mul_f32 v[92:93], v[186:187], v[90:91]
	v_pk_mul_f32 v[88:89], v[88:89], v[88:89]
	s_nop 0
	v_and_b32_sdwa v82, v93, v178 dst_sel:DWORD dst_unused:UNUSED_PAD src0_sel:WORD_1 src1_sel:DWORD
	v_cvt_pk_bf16_f32 v86, v92, v92
	v_add3_u32 v82, v93, v82, s81
	v_lshrrev_b32_e32 v86, 16, v86
	v_and_or_b32 v82, v82, s28, v86
	v_lshl_add_u64 v[92:93], v[84:85], 1, s[8:9]
	v_pk_mul_f32 v[90:91], v[90:91], v[90:91]
	global_store_dword v[92:93], v82, off
	v_add_f32_e32 v82, v90, v91
	v_add_f32_e32 v85, v88, v89
	v_add_f32_e32 v82, v85, v82
	s_nop 1
	v_add_f32_dpp v82, v82, v82 quad_perm:[1,0,3,2] row_mask:0xf bank_mask:0xf bound_ctrl:1
	s_nop 1
	v_add_f32_dpp v82, v82, v82 quad_perm:[2,3,0,1] row_mask:0xf bank_mask:0xf bound_ctrl:1
	s_nop 1
	v_add_f32_dpp v82, v82, v82 row_half_mirror row_mask:0xf bank_mask:0xf bound_ctrl:1
	s_nop 1
	v_mov_b32_dpp v85, v82 row_mirror row_mask:0xf bank_mask:0xf bound_ctrl:1
	s_and_saveexec_b64 s[68:69], s[4:5]
	s_cbranch_execz .LBB0_446
	v_lshlrev_b32_e32 v88, 4, v194
	v_ashrrev_i32_e32 v89, 31, v88
	v_add_f32_e32 v82, v82, v85
	v_lshl_add_u64 v[88:89], v[88:89], 2, v[150:151]
	global_store_dword v[88:89], v82, off offset:3264

; __device__ __forceinline__ unsigned pack2(float a, float b) { return (unsigned)f2bf(a) | ((unsigned)f2bf(b) << 16); }
; #define WAIT_V(n) asm volatile("s_waitcnt vmcnt(" #n ")" ::: "memory")
; template <int EPI, bool HS = false>
; __device__ __forceinline__ void gemm_phase(const Params& p, const GemmCfg& g, char* shm, const int wave_s) {
;     ...
;         for (int i = 0; i < 16; ++i) {
;           const int r = wv_s * 16 + i;
;           glds_row(xin_t + (size_t)(ai * 128 + r) * 1024, (unsigned)lane * 16u, ldsb + (unsigned)(r * XROW));
;         }
;         WAIT_V(0);
;         __syncthreads();
; #pragma unroll
;         for (int m = 0; m < 4; ++m) {
;           float2 xv[4][2];
; #pragma unroll
;           for (int j = 0; j < 4; ++j)
; #pragma unroll
;             for (int bj = 0; bj < 2; ++bj) xv[j][bj] = *(const float2*)(xl + (m * 16 + j) * XROW + bj * 512);
; #pragma unroll
;           for (int j = 0; j < 4; ++j) {
;             float ss = 0.f;
; #pragma unroll
;             for (int bj = 0; bj < 2; ++bj) {
;               float2 xn;
;               xn.x = xv[j][bj].x + gt[bj][0] * acc[ai][bj][m][0][j];
;               xn.y = xv[j][bj].y + gt[bj][1] * acc[ai][bj][m][1][j];
;               const unsigned o = tb + (unsigned)((ai * 128 + m * 16 + j) * 1024 + bj * 128);
;               *(float2*)(xout_t + o) = xn;
;               if (g.has_next) *(unsigned*)(xg_t + o) = pack2(xn.x * gn[bj][0], xn.y * gn[bj][1]);
;               ss += xn.x * xn.x + xn.y * xn.y;
;             }
;             if (g.has_next) {
;               ss = dpp_row_sum16(ss);
;               if (fr == 0) rss_t[(wr * 64 + fq * 4 + ai * 128 + m * 16 + j) * 16] = ss;
;             }
.LBB0_449:
	v_pk_mul_f32 v[94:95], v[66:67], v[70:71]
	v_pk_mul_f32 v[92:93], v[62:63], v[70:71]
	v_pk_mul_f32 v[62:63], v[80:81], v[72:73]
	v_pk_mul_f32 v[90:91], v[78:79], v[70:71]
	v_pk_mul_f32 v[66:67], v[76:77], v[72:73]
	v_pk_mul_f32 v[70:71], v[74:75], v[70:71]
	s_lshl_b64 s[10:11], s[10:11], 12
	s_add_u32 s13, s76, s10
	s_addc_u32 s14, s77, s11
	s_add_u32 s10, s13, 0x80000
	s_addc_u32 s11, s14, 0
	s_waitcnt vmcnt(63) expcnt(7) lgkmcnt(15)
	s_barrier
	s_mov_b32 m0, s84
	s_nop 0
	global_load_lds_dwordx4 v198, s[10:11]
	s_add_u32 s10, s13, 0x81000
	s_addc_u32 s11, s14, 0
	s_mov_b32 m0, s85
	s_nop 0
	global_load_lds_dwordx4 v198, s[10:11]
	s_add_u32 s10, s13, 0x82000
	s_addc_u32 s11, s14, 0
	s_mov_b32 m0, s88
	s_nop 0
	global_load_lds_dwordx4 v198, s[10:11]
	s_add_u32 s10, s13, 0x83000
	s_addc_u32 s11, s14, 0
	s_mov_b32 m0, s89
	s_nop 0
	global_load_lds_dwordx4 v198, s[10:11]
	s_add_u32 s10, s13, 0x84000
	s_addc_u32 s11, s14, 0
	s_mov_b32 m0, s90
	s_nop 0
	global_load_lds_dwordx4 v198, s[10:11]
	s_add_u32 s10, s13, 0x85000
	s_addc_u32 s11, s14, 0
	s_mov_b32 m0, s91
	s_nop 0
	global_load_lds_dwordx4 v198, s[10:11]
	s_add_u32 s10, s13, 0x86000
	s_addc_u32 s11, s14, 0
	s_mov_b32 m0, s92
	s_nop 0
	global_load_lds_dwordx4 v198, s[10:11]
	s_add_u32 s10, s13, 0x87000
	s_addc_u32 s11, s14, 0
	s_mov_b32 m0, s93
	s_nop 0
	global_load_lds_dwordx4 v198, s[10:11]
	s_add_u32 s10, s13, 0x88000
	s_addc_u32 s11, s14, 0
	s_mov_b32 m0, s71
	s_nop 0
	global_load_lds_dwordx4 v198, s[10:11]
	s_add_u32 s10, s13, 0x89000
	s_addc_u32 s11, s14, 0
	s_mov_b32 m0, s70
	s_nop 0
	global_load_lds_dwordx4 v198, s[10:11]
	s_add_u32 s10, s13, 0x8a000
	s_addc_u32 s11, s14, 0
	s_mov_b32 m0, s72
	s_nop 0
	global_load_lds_dwordx4 v198, s[10:11]
	s_add_u32 s10, s13, 0x8b000
	s_addc_u32 s11, s14, 0
	s_mov_b32 m0, s73
	s_nop 0
	global_load_lds_dwordx4 v198, s[10:11]
	s_add_u32 s10, s13, 0x8c000
	s_addc_u32 s11, s14, 0
	s_mov_b32 m0, s74
	s_nop 0
	global_load_lds_dwordx4 v198, s[10:11]
	s_add_u32 s10, s13, 0x8d000
	s_addc_u32 s11, s14, 0
	s_mov_b32 m0, s0
	s_nop 0
	global_load_lds_dwordx4 v198, s[10:11]
	s_add_u32 s10, s13, 0x8e000
	s_addc_u32 s11, s14, 0
	s_mov_b32 m0, s1
	s_nop 0
	global_load_lds_dwordx4 v198, s[10:11]
	s_add_u32 s0, s13, 0x8f000
	s_addc_u32 s1, s14, 0
	s_mov_b32 m0, s12
	s_nop 0
	global_load_lds_dwordx4 v198, s[0:1]
	s_waitcnt vmcnt(0)
	s_barrier
	ds_read2st64_b64 v[86:89], v195 offset1:1
	ds_read2_b64 v[82:85], v195 offset0:130 offset1:194
	ds_read2st64_b64 v[78:81], v196 offset0:4 offset1:5
	ds_read2st64_b64 v[74:77], v197 offset0:6 offset1:7
	v_add_u32_e32 v98, 0x20000, v0
	v_mov_b32_e32 v96, v94
	v_mov_b32_e32 v97, v92
	v_mov_b32_e32 v99, v1
	s_waitcnt lgkmcnt(3)
	v_pk_fma_f32 v[96:97], v[96:97], v[184:185], v[86:87]
	v_lshl_add_u64 v[86:87], v[98:99], 2, s[2:3]
	v_readlane_b32 s88, v254, 47
	global_store_dwordx2 v[86:87], v[96:97], off
	s_mov_b64 s[10:11], -1
	s_and_b64 vcc, exec, s[6:7]
	v_add_u32_e32 v86, 0x20080, v0
	s_mov_b32 s84, 0x8000
	v_readlane_b32 s89, v254, 48
	v_readlane_b32 s90, v254, 49
	v_readlane_b32 s91, v254, 50
	s_cbranch_vccnz .LBB0_453
	v_pk_mul_f32 v[100:101], v[182:183], v[96:97]
	v_lshl_add_u64 v[98:99], v[98:99], 1, s[8:9]
	s_nop 0
	v_and_b32_sdwa v87, v101, v178 dst_sel:DWORD dst_unused:UNUSED_PAD src0_sel:WORD_1 src1_sel:DWORD
	v_cvt_pk_bf16_f32 v92, v100, v100
	v_add3_u32 v87, v101, v87, s81
	v_lshrrev_b32_e32 v92, 16, v92
	v_and_or_b32 v87, v87, s28, v92
	global_store_dword v[98:99], v87, off
	v_mov_b32_e32 v98, v90
	v_mov_b32_e32 v99, v70
	v_mov_b32_e32 v87, v1
	v_pk_fma_f32 v[98:99], v[98:99], v[180:181], v[88:89]
	v_lshl_add_u64 v[100:101], v[86:87], 2, s[2:3]
	global_store_dwordx2 v[100:101], v[98:99], off
	v_pk_mul_f32 v[100:101], v[186:187], v[98:99]
	v_pk_mul_f32 v[96:97], v[96:97], v[96:97]
	s_nop 0
	v_and_b32_sdwa v92, v101, v178 dst_sel:DWORD dst_unused:UNUSED_PAD src0_sel:WORD_1 src1_sel:DWORD
	v_cvt_pk_bf16_f32 v94, v100, v100
	v_add3_u32 v92, v101, v92, s81
	v_lshrrev_b32_e32 v94, 16, v94
	v_and_or_b32 v92, v92, s28, v94
	v_lshl_add_u64 v[100:101], v[86:87], 1, s[8:9]
	v_pk_mul_f32 v[98:99], v[98:99], v[98:99]
	global_store_dword v[100:101], v92, off
	v_add_f32_e32 v87, v98, v99
	v_add_f32_e32 v92, v96, v97
	v_add_f32_e32 v87, v92, v87
	s_nop 1
	v_add_f32_dpp v87, v87, v87 quad_perm:[1,0,3,2] row_mask:0xf bank_mask:0xf bound_ctrl:1
	s_nop 1
	v_add_f32_dpp v87, v87, v87 quad_perm:[2,3,0,1] row_mask:0xf bank_mask:0xf bound_ctrl:1
	s_nop 1
	v_add_f32_dpp v87, v87, v87 row_half_mirror row_mask:0xf bank_mask:0xf bound_ctrl:1
	s_nop 1
	v_mov_b32_dpp v92, v87 row_mirror row_mask:0xf bank_mask:0xf bound_ctrl:1
	s_and_saveexec_b64 s[10:11], s[4:5]
	s_cbranch_execz .LBB0_452
	v_add_f32_e32 v87, v87, v92
	v_mov_b32_e32 v92, 0x800
	v_lshl_add_u32 v96, v194, 4, v92
	v_ashrrev_i32_e32 v97, 31, v96
	v_lshl_add_u64 v[96:97], v[96:97], 2, v[150:151]
	global_store_dword v[96:97], v87, off

; __device__ __forceinline__ unsigned pack2(float a, float b) { return (unsigned)f2bf(a) | ((unsigned)f2bf(b) << 16); }
; template <int EPI, bool HS = false>
; __device__ __forceinline__ void gemm_phase(const Params& p, const GemmCfg& g, char* shm, const int wave_s) {
;     ...
;             for (int bj = 0; bj < 2; ++bj) xv[j][bj] = *(const float2*)(xl + (m * 16 + j) * XROW + bj * 512);
; #pragma unroll
;           for (int j = 0; j < 4; ++j) {
;             float ss = 0.f;
; #pragma unroll
;             for (int bj = 0; bj < 2; ++bj) {
;               float2 xn;
;               xn.x = xv[j][bj].x + gt[bj][0] * acc[ai][bj][m][0][j];
;               xn.y = xv[j][bj].y + gt[bj][1] * acc[ai][bj][m][1][j];
;               const unsigned o = tb + (unsigned)((ai * 128 + m * 16 + j) * 1024 + bj * 128);
;               *(float2*)(xout_t + o) = xn;
;               if (g.has_next) *(unsigned*)(xg_t + o) = pack2(xn.x * gn[bj][0], xn.y * gn[bj][1]);
;               ss += xn.x * xn.x + xn.y * xn.y;
;             }
;             if (g.has_next) {
;               ss = dpp_row_sum16(ss);
;               if (fr == 0) rss_t[(wr * 64 + fq * 4 + ai * 128 + m * 16 + j) * 16] = ss;
;             }
.LBB0_455:
	v_add_u32_e32 v86, 0x20400, v0
	v_mov_b32_e32 v92, v95
	v_mov_b32_e32 v87, v1
	v_pk_mul_f32 v[68:69], v[68:69], v[72:73]
	v_pk_mul_f32 v[64:65], v[64:65], v[72:73]
	s_waitcnt lgkmcnt(2)
	v_pk_fma_f32 v[82:83], v[92:93], v[184:185], v[82:83]
	v_lshl_add_u64 v[72:73], v[86:87], 2, s[2:3]
	global_store_dwordx2 v[72:73], v[82:83], off
	s_mov_b64 s[10:11], -1
	s_and_b64 vcc, exec, s[6:7]
	v_add_u32_e32 v72, 0x20480, v0
	s_cbranch_vccnz .LBB0_459
	v_pk_mul_f32 v[88:89], v[182:183], v[82:83]
	v_lshl_add_u64 v[86:87], v[86:87], 1, s[8:9]
	s_nop 0
	v_and_b32_sdwa v70, v89, v178 dst_sel:DWORD dst_unused:UNUSED_PAD src0_sel:WORD_1 src1_sel:DWORD
	v_cvt_pk_bf16_f32 v73, v88, v88
	v_add3_u32 v70, v89, v70, s81
	v_lshrrev_b32_e32 v73, 16, v73
	v_and_or_b32 v70, v70, s28, v73
	global_store_dword v[86:87], v70, off
	v_mov_b32_e32 v70, v91
	v_mov_b32_e32 v73, v1
	v_pk_fma_f32 v[86:87], v[70:71], v[180:181], v[84:85]
	v_lshl_add_u64 v[88:89], v[72:73], 2, s[2:3]
	global_store_dwordx2 v[88:89], v[86:87], off
	v_pk_mul_f32 v[88:89], v[186:187], v[86:87]
	v_pk_mul_f32 v[82:83], v[82:83], v[82:83]
	v_and_b32_sdwa v90, v88, v178 dst_sel:DWORD dst_unused:UNUSED_PAD src0_sel:WORD_1 src1_sel:DWORD
	v_and_b32_sdwa v70, v89, v178 dst_sel:DWORD dst_unused:UNUSED_PAD src0_sel:WORD_1 src1_sel:DWORD
	v_add3_u32 v88, v88, v90, s81
	v_add3_u32 v70, v89, v70, s81
	v_lshrrev_b32_e32 v88, 16, v88
	v_and_or_b32 v70, v70, s28, v88
	v_lshl_add_u64 v[88:89], v[72:73], 1, s[8:9]
	v_pk_mul_f32 v[86:87], v[86:87], v[86:87]
	global_store_dword v[88:89], v70, off
	v_add_f32_e32 v70, v86, v87
	v_add_f32_e32 v73, v82, v83
	v_add_f32_e32 v70, v73, v70
	s_nop 1
	v_add_f32_dpp v70, v70, v70 quad_perm:[1,0,3,2] row_mask:0xf bank_mask:0xf bound_ctrl:1
	s_nop 1
	v_add_f32_dpp v70, v70, v70 quad_perm:[2,3,0,1] row_mask:0xf bank_mask:0xf bound_ctrl:1
	s_nop 1
	v_add_f32_dpp v70, v70, v70 row_half_mirror row_mask:0xf bank_mask:0xf bound_ctrl:1
	s_nop 1
	v_mov_b32_dpp v73, v70 row_mirror row_mask:0xf bank_mask:0xf bound_ctrl:1
	s_and_saveexec_b64 s[10:11], s[4:5]
	s_cbranch_execz .LBB0_458
	v_add_f32_e32 v70, v70, v73
	v_mov_b32_e32 v73, 0x810
	v_lshl_add_u32 v82, v194, 4, v73
	v_ashrrev_i32_e32 v83, 31, v82
	v_lshl_add_u64 v[82:83], v[82:83], 2, v[150:151]
	global_store_dword v[82:83], v70, off

; __device__ __forceinline__ unsigned pack2(float a, float b) { return (unsigned)f2bf(a) | ((unsigned)f2bf(b) << 16); }
; template <int EPI, bool HS = false>
; __device__ __forceinline__ void gemm_phase(const Params& p, const GemmCfg& g, char* shm, const int wave_s) {
;     ...
;             for (int bj = 0; bj < 2; ++bj) xv[j][bj] = *(const float2*)(xl + (m * 16 + j) * XROW + bj * 512);
; #pragma unroll
;           for (int j = 0; j < 4; ++j) {
;             float ss = 0.f;
; #pragma unroll
;             for (int bj = 0; bj < 2; ++bj) {
;               float2 xn;
;               xn.x = xv[j][bj].x + gt[bj][0] * acc[ai][bj][m][0][j];
;               xn.y = xv[j][bj].y + gt[bj][1] * acc[ai][bj][m][1][j];
;               const unsigned o = tb + (unsigned)((ai * 128 + m * 16 + j) * 1024 + bj * 128);
;               *(float2*)(xout_t + o) = xn;
;               if (g.has_next) *(unsigned*)(xg_t + o) = pack2(xn.x * gn[bj][0], xn.y * gn[bj][1]);
;               ss += xn.x * xn.x + xn.y * xn.y;
;             }
;             if (g.has_next) {
;               ss = dpp_row_sum16(ss);
;               if (fr == 0) rss_t[(wr * 64 + fq * 4 + ai * 128 + m * 16 + j) * 16] = ss;
;             }
.LBB0_461:
	v_add_u32_e32 v82, 0x20800, v0
	v_mov_b32_e32 v70, v68
	v_mov_b32_e32 v71, v64
	v_mov_b32_e32 v83, v1
	s_waitcnt lgkmcnt(1)
	v_pk_fma_f32 v[72:73], v[70:71], v[184:185], v[78:79]
	v_lshl_add_u64 v[70:71], v[82:83], 2, s[2:3]
	global_store_dwordx2 v[70:71], v[72:73], off
	s_mov_b64 s[10:11], -1
	s_and_b64 vcc, exec, s[6:7]
	v_add_u32_e32 v70, 0x20880, v0
	s_cbranch_vccnz .LBB0_465
	v_pk_mul_f32 v[78:79], v[182:183], v[72:73]
	v_mov_b32_e32 v71, v1
	s_nop 0
	v_and_b32_sdwa v64, v79, v178 dst_sel:DWORD dst_unused:UNUSED_PAD src0_sel:WORD_1 src1_sel:DWORD
	v_cvt_pk_bf16_f32 v68, v78, v78
	v_add3_u32 v64, v79, v64, s81
	v_lshrrev_b32_e32 v68, 16, v68
	v_and_or_b32 v64, v64, s28, v68
	v_lshl_add_u64 v[78:79], v[82:83], 1, s[8:9]
	global_store_dword v[78:79], v64, off
	v_mov_b32_e32 v78, v62
	v_mov_b32_e32 v79, v66
	v_pk_fma_f32 v[78:79], v[78:79], v[180:181], v[80:81]
	v_lshl_add_u64 v[82:83], v[70:71], 2, s[2:3]
	global_store_dwordx2 v[82:83], v[78:79], off
	v_pk_mul_f32 v[82:83], v[186:187], v[78:79]
	v_pk_mul_f32 v[72:73], v[72:73], v[72:73]
	s_nop 0
	v_and_b32_sdwa v64, v83, v178 dst_sel:DWORD dst_unused:UNUSED_PAD src0_sel:WORD_1 src1_sel:DWORD
	v_cvt_pk_bf16_f32 v68, v82, v82
	v_add3_u32 v64, v83, v64, s81
	v_lshrrev_b32_e32 v68, 16, v68
	v_and_or_b32 v64, v64, s28, v68
	v_lshl_add_u64 v[82:83], v[70:71], 1, s[8:9]
	v_pk_mul_f32 v[78:79], v[78:79], v[78:79]
	global_store_dword v[82:83], v64, off
	v_add_f32_e32 v64, v78, v79
	v_add_f32_e32 v68, v72, v73
	v_add_f32_e32 v64, v68, v64
	s_nop 1
	v_add_f32_dpp v64, v64, v64 quad_perm:[1,0,3,2] row_mask:0xf bank_mask:0xf bound_ctrl:1
	s_nop 1
	v_add_f32_dpp v64, v64, v64 quad_perm:[2,3,0,1] row_mask:0xf bank_mask:0xf bound_ctrl:1
	s_nop 1
	v_add_f32_dpp v64, v64, v64 row_half_mirror row_mask:0xf bank_mask:0xf bound_ctrl:1
	s_nop 1
	v_mov_b32_dpp v68, v64 row_mirror row_mask:0xf bank_mask:0xf bound_ctrl:1
	s_and_saveexec_b64 s[10:11], s[4:5]
	s_cbranch_execz .LBB0_464
	v_add_f32_e32 v64, v64, v68
	v_mov_b32_e32 v68, 0x820
	v_lshl_add_u32 v72, v194, 4, v68
	v_ashrrev_i32_e32 v73, 31, v72
	v_lshl_add_u64 v[72:73], v[72:73], 2, v[150:151]
	global_store_dword v[72:73], v64, off

; __device__ __forceinline__ unsigned pack2(float a, float b) { return (unsigned)f2bf(a) | ((unsigned)f2bf(b) << 16); }
; template <int EPI, bool HS = false>
; __device__ __forceinline__ void gemm_phase(const Params& p, const GemmCfg& g, char* shm, const int wave_s) {
;     ...
;             for (int bj = 0; bj < 2; ++bj) xv[j][bj] = *(const float2*)(xl + (m * 16 + j) * XROW + bj * 512);
; #pragma unroll
;           for (int j = 0; j < 4; ++j) {
;             float ss = 0.f;
; #pragma unroll
;             for (int bj = 0; bj < 2; ++bj) {
;               float2 xn;
;               xn.x = xv[j][bj].x + gt[bj][0] * acc[ai][bj][m][0][j];
;               xn.y = xv[j][bj].y + gt[bj][1] * acc[ai][bj][m][1][j];
;               const unsigned o = tb + (unsigned)((ai * 128 + m * 16 + j) * 1024 + bj * 128);
;               *(float2*)(xout_t + o) = xn;
;               if (g.has_next) *(unsigned*)(xg_t + o) = pack2(xn.x * gn[bj][0], xn.y * gn[bj][1]);
;               ss += xn.x * xn.x + xn.y * xn.y;
;             }
;             if (g.has_next) {
;               ss = dpp_row_sum16(ss);
;               if (fr == 0) rss_t[(wr * 64 + fq * 4 + ai * 128 + m * 16 + j) * 16] = ss;
;             }
.LBB0_467:
	v_add_u32_e32 v70, 0x20c00, v0
	v_mov_b32_e32 v64, v69
	v_mov_b32_e32 v71, v1
	s_waitcnt lgkmcnt(0)
	v_pk_fma_f32 v[68:69], v[64:65], v[184:185], v[74:75]
	v_lshl_add_u64 v[64:65], v[70:71], 2, s[2:3]
	global_store_dwordx2 v[64:65], v[68:69], off
	s_mov_b64 s[10:11], -1
	s_and_b64 vcc, exec, s[6:7]
	v_add_u32_e32 v64, 0x20c80, v0
	s_cbranch_vccnz .LBB0_471
	v_pk_mul_f32 v[72:73], v[182:183], v[68:69]
	v_lshl_add_u64 v[70:71], v[70:71], 1, s[8:9]
	s_nop 0
	v_and_b32_sdwa v62, v73, v178 dst_sel:DWORD dst_unused:UNUSED_PAD src0_sel:WORD_1 src1_sel:DWORD
	v_cvt_pk_bf16_f32 v65, v72, v72
	v_add3_u32 v62, v73, v62, s81
	v_lshrrev_b32_e32 v65, 16, v65
	v_and_or_b32 v62, v62, s28, v65
	v_mov_b32_e32 v66, v63
	v_mov_b32_e32 v65, v1
	global_store_dword v[70:71], v62, off
	v_pk_fma_f32 v[70:71], v[66:67], v[180:181], v[76:77]
	v_lshl_add_u64 v[72:73], v[64:65], 2, s[2:3]
	global_store_dwordx2 v[72:73], v[70:71], off
	v_pk_mul_f32 v[72:73], v[186:187], v[70:71]
	v_pk_mul_f32 v[68:69], v[68:69], v[68:69]
	s_nop 0
	v_and_b32_sdwa v62, v73, v178 dst_sel:DWORD dst_unused:UNUSED_PAD src0_sel:WORD_1 src1_sel:DWORD
	v_cvt_pk_bf16_f32 v66, v72, v72
	v_add3_u32 v62, v73, v62, s81
	v_lshrrev_b32_e32 v66, 16, v66
	v_and_or_b32 v62, v62, s28, v66
	v_lshl_add_u64 v[72:73], v[64:65], 1, s[8:9]
	v_pk_mul_f32 v[70:71], v[70:71], v[70:71]
	global_store_dword v[72:73], v62, off
	v_add_f32_e32 v62, v70, v71
	v_add_f32_e32 v65, v68, v69
	v_add_f32_e32 v62, v65, v62
	s_nop 1
	v_add_f32_dpp v62, v62, v62 quad_perm:[1,0,3,2] row_mask:0xf bank_mask:0xf bound_ctrl:1
	s_nop 1
	v_add_f32_dpp v62, v62, v62 quad_perm:[2,3,0,1] row_mask:0xf bank_mask:0xf bound_ctrl:1
	s_nop 1
	v_add_f32_dpp v62, v62, v62 row_half_mirror row_mask:0xf bank_mask:0xf bound_ctrl:1
	s_nop 1
	v_mov_b32_dpp v65, v62 row_mirror row_mask:0xf bank_mask:0xf bound_ctrl:1
	s_and_saveexec_b64 s[10:11], s[4:5]
	s_cbranch_execz .LBB0_470
	v_add_f32_e32 v62, v62, v65
	v_mov_b32_e32 v65, 0x830
	v_lshl_add_u32 v68, v194, 4, v65
	v_ashrrev_i32_e32 v69, 31, v68
	v_lshl_add_u64 v[68:69], v[68:69], 2, v[150:151]
	global_store_dword v[68:69], v62, off

; __device__ __forceinline__ unsigned pack2(float a, float b) { return (unsigned)f2bf(a) | ((unsigned)f2bf(b) << 16); }
; template <int EPI, bool HS = false>
; __device__ __forceinline__ void gemm_phase(const Params& p, const GemmCfg& g, char* shm, const int wave_s) {
;     ...
;         for (int m = 0; m < 4; ++m) {
;           float2 xv[4][2];
; #pragma unroll
;           for (int j = 0; j < 4; ++j)
; #pragma unroll
;             for (int bj = 0; bj < 2; ++bj) xv[j][bj] = *(const float2*)(xl + (m * 16 + j) * XROW + bj * 512);
; #pragma unroll
;           for (int j = 0; j < 4; ++j) {
;             float ss = 0.f;
; #pragma unroll
;             for (int bj = 0; bj < 2; ++bj) {
;               float2 xn;
;               xn.x = xv[j][bj].x + gt[bj][0] * acc[ai][bj][m][0][j];
;               xn.y = xv[j][bj].y + gt[bj][1] * acc[ai][bj][m][1][j];
;               const unsigned o = tb + (unsigned)((ai * 128 + m * 16 + j) * 1024 + bj * 128);
;               *(float2*)(xout_t + o) = xn;
;               if (g.has_next) *(unsigned*)(xg_t + o) = pack2(xn.x * gn[bj][0], xn.y * gn[bj][1]);
;               ss += xn.x * xn.x + xn.y * xn.y;
;             }
;             if (g.has_next) {
;               ss = dpp_row_sum16(ss);
;               if (fr == 0) rss_t[(wr * 64 + fq * 4 + ai * 128 + m * 16 + j) * 16] = ss;
;             }
.LBB0_473:
	v_pk_mul_f32 v[74:75], v[46:47], v[50:51]
	v_pk_mul_f32 v[72:73], v[42:43], v[50:51]
	v_pk_mul_f32 v[42:43], v[60:61], v[52:53]
	v_pk_mul_f32 v[70:71], v[58:59], v[50:51]
	v_pk_mul_f32 v[46:47], v[56:57], v[52:53]
	v_pk_mul_f32 v[50:51], v[54:55], v[50:51]
	ds_read2st64_b64 v[66:69], v162 offset0:32 offset1:33
	ds_read2st64_b64 v[62:65], v163 offset0:34 offset1:35
	ds_read2st64_b64 v[58:61], v164 offset0:36 offset1:37
	ds_read2st64_b64 v[54:57], v165 offset0:38 offset1:39
	v_add_u32_e32 v78, 0x24000, v0
	v_mov_b32_e32 v76, v74
	v_mov_b32_e32 v77, v72
	v_mov_b32_e32 v79, v1
	s_waitcnt lgkmcnt(3)
	v_pk_fma_f32 v[76:77], v[76:77], v[184:185], v[66:67]
	v_lshl_add_u64 v[66:67], v[78:79], 2, s[2:3]
	global_store_dwordx2 v[66:67], v[76:77], off
	s_mov_b64 s[10:11], -1
	s_and_b64 vcc, exec, s[6:7]
	v_add_u32_e32 v66, 0x24080, v0
	s_cbranch_vccnz .LBB0_477
	v_pk_mul_f32 v[80:81], v[182:183], v[76:77]
	v_lshl_add_u64 v[78:79], v[78:79], 1, s[8:9]
	s_nop 0
	v_and_b32_sdwa v67, v81, v178 dst_sel:DWORD dst_unused:UNUSED_PAD src0_sel:WORD_1 src1_sel:DWORD
	v_cvt_pk_bf16_f32 v72, v80, v80
	v_add3_u32 v67, v81, v67, s81
	v_lshrrev_b32_e32 v72, 16, v72
	v_and_or_b32 v67, v67, s28, v72
	global_store_dword v[78:79], v67, off
	v_mov_b32_e32 v78, v70
	v_mov_b32_e32 v79, v50
	v_mov_b32_e32 v67, v1
	v_pk_fma_f32 v[78:79], v[78:79], v[180:181], v[68:69]
	v_lshl_add_u64 v[80:81], v[66:67], 2, s[2:3]
	global_store_dwordx2 v[80:81], v[78:79], off
	v_pk_mul_f32 v[80:81], v[186:187], v[78:79]
	v_pk_mul_f32 v[76:77], v[76:77], v[76:77]
	s_nop 0
	v_and_b32_sdwa v72, v81, v178 dst_sel:DWORD dst_unused:UNUSED_PAD src0_sel:WORD_1 src1_sel:DWORD
	v_cvt_pk_bf16_f32 v74, v80, v80
	v_add3_u32 v72, v81, v72, s81
	v_lshrrev_b32_e32 v74, 16, v74
	v_and_or_b32 v72, v72, s28, v74
	v_lshl_add_u64 v[80:81], v[66:67], 1, s[8:9]
	v_pk_mul_f32 v[78:79], v[78:79], v[78:79]
	global_store_dword v[80:81], v72, off
	v_add_f32_e32 v67, v78, v79
	v_add_f32_e32 v72, v76, v77
	v_add_f32_e32 v67, v72, v67
	s_nop 1
	v_add_f32_dpp v67, v67, v67 quad_perm:[1,0,3,2] row_mask:0xf bank_mask:0xf bound_ctrl:1
	s_nop 1
	v_add_f32_dpp v67, v67, v67 quad_perm:[2,3,0,1] row_mask:0xf bank_mask:0xf bound_ctrl:1
	s_nop 1
	v_add_f32_dpp v67, v67, v67 row_half_mirror row_mask:0xf bank_mask:0xf bound_ctrl:1
	s_nop 1
	v_mov_b32_dpp v72, v67 row_mirror row_mask:0xf bank_mask:0xf bound_ctrl:1
	s_and_saveexec_b64 s[10:11], s[4:5]
	s_cbranch_execz .LBB0_476
	v_add_f32_e32 v67, v67, v72
	v_mov_b32_e32 v72, 0x900
	v_lshl_add_u32 v76, v194, 4, v72
	v_ashrrev_i32_e32 v77, 31, v76
	v_lshl_add_u64 v[76:77], v[76:77], 2, v[150:151]
	global_store_dword v[76:77], v67, off

; __device__ __forceinline__ unsigned pack2(float a, float b) { return (unsigned)f2bf(a) | ((unsigned)f2bf(b) << 16); }
; template <int EPI, bool HS = false>
; __device__ __forceinline__ void gemm_phase(const Params& p, const GemmCfg& g, char* shm, const int wave_s) {
;     ...
;             for (int bj = 0; bj < 2; ++bj) xv[j][bj] = *(const float2*)(xl + (m * 16 + j) * XROW + bj * 512);
; #pragma unroll
;           for (int j = 0; j < 4; ++j) {
;             float ss = 0.f;
; #pragma unroll
;             for (int bj = 0; bj < 2; ++bj) {
;               float2 xn;
;               xn.x = xv[j][bj].x + gt[bj][0] * acc[ai][bj][m][0][j];
;               xn.y = xv[j][bj].y + gt[bj][1] * acc[ai][bj][m][1][j];
;               const unsigned o = tb + (unsigned)((ai * 128 + m * 16 + j) * 1024 + bj * 128);
;               *(float2*)(xout_t + o) = xn;
;               if (g.has_next) *(unsigned*)(xg_t + o) = pack2(xn.x * gn[bj][0], xn.y * gn[bj][1]);
;               ss += xn.x * xn.x + xn.y * xn.y;
;             }
;             if (g.has_next) {
;               ss = dpp_row_sum16(ss);
;               if (fr == 0) rss_t[(wr * 64 + fq * 4 + ai * 128 + m * 16 + j) * 16] = ss;
;             }
.LBB0_479:
	v_add_u32_e32 v66, 0x24400, v0
	v_mov_b32_e32 v72, v75
	v_mov_b32_e32 v67, v1
	v_pk_mul_f32 v[48:49], v[48:49], v[52:53]
	v_pk_mul_f32 v[44:45], v[44:45], v[52:53]
	s_waitcnt lgkmcnt(2)
	v_pk_fma_f32 v[62:63], v[72:73], v[184:185], v[62:63]
	v_lshl_add_u64 v[52:53], v[66:67], 2, s[2:3]
	global_store_dwordx2 v[52:53], v[62:63], off
	s_mov_b64 s[10:11], -1
	s_and_b64 vcc, exec, s[6:7]
	v_add_u32_e32 v52, 0x24480, v0
	s_cbranch_vccnz .LBB0_483
	v_pk_mul_f32 v[68:69], v[182:183], v[62:63]
	v_lshl_add_u64 v[66:67], v[66:67], 1, s[8:9]
	s_nop 0
	v_and_b32_sdwa v50, v69, v178 dst_sel:DWORD dst_unused:UNUSED_PAD src0_sel:WORD_1 src1_sel:DWORD
	v_cvt_pk_bf16_f32 v53, v68, v68
	v_add3_u32 v50, v69, v50, s81
	v_lshrrev_b32_e32 v53, 16, v53
	v_and_or_b32 v50, v50, s28, v53
	global_store_dword v[66:67], v50, off
	v_mov_b32_e32 v50, v71
	v_mov_b32_e32 v53, v1
	v_pk_fma_f32 v[66:67], v[50:51], v[180:181], v[64:65]
	v_lshl_add_u64 v[68:69], v[52:53], 2, s[2:3]
	global_store_dwordx2 v[68:69], v[66:67], off
	v_pk_mul_f32 v[68:69], v[186:187], v[66:67]
	v_pk_mul_f32 v[62:63], v[62:63], v[62:63]
	v_and_b32_sdwa v70, v68, v178 dst_sel:DWORD dst_unused:UNUSED_PAD src0_sel:WORD_1 src1_sel:DWORD
	v_and_b32_sdwa v50, v69, v178 dst_sel:DWORD dst_unused:UNUSED_PAD src0_sel:WORD_1 src1_sel:DWORD
	v_add3_u32 v68, v68, v70, s81
	v_add3_u32 v50, v69, v50, s81
	v_lshrrev_b32_e32 v68, 16, v68
	v_and_or_b32 v50, v50, s28, v68
	v_lshl_add_u64 v[68:69], v[52:53], 1, s[8:9]
	v_pk_mul_f32 v[66:67], v[66:67], v[66:67]
	global_store_dword v[68:69], v50, off
	v_add_f32_e32 v50, v66, v67
	v_add_f32_e32 v53, v62, v63
	v_add_f32_e32 v50, v53, v50
	s_nop 1
	v_add_f32_dpp v50, v50, v50 quad_perm:[1,0,3,2] row_mask:0xf bank_mask:0xf bound_ctrl:1
	s_nop 1
	v_add_f32_dpp v50, v50, v50 quad_perm:[2,3,0,1] row_mask:0xf bank_mask:0xf bound_ctrl:1
	s_nop 1
	v_add_f32_dpp v50, v50, v50 row_half_mirror row_mask:0xf bank_mask:0xf bound_ctrl:1
	s_nop 1
	v_mov_b32_dpp v53, v50 row_mirror row_mask:0xf bank_mask:0xf bound_ctrl:1
	s_and_saveexec_b64 s[10:11], s[4:5]
	s_cbranch_execz .LBB0_482
	v_add_f32_e32 v50, v50, v53
	v_mov_b32_e32 v53, 0x910
	v_lshl_add_u32 v62, v194, 4, v53
	v_ashrrev_i32_e32 v63, 31, v62
	v_lshl_add_u64 v[62:63], v[62:63], 2, v[150:151]
	global_store_dword v[62:63], v50, off

; __device__ __forceinline__ unsigned pack2(float a, float b) { return (unsigned)f2bf(a) | ((unsigned)f2bf(b) << 16); }
; template <int EPI, bool HS = false>
; __device__ __forceinline__ void gemm_phase(const Params& p, const GemmCfg& g, char* shm, const int wave_s) {
;     ...
;             for (int bj = 0; bj < 2; ++bj) xv[j][bj] = *(const float2*)(xl + (m * 16 + j) * XROW + bj * 512);
; #pragma unroll
;           for (int j = 0; j < 4; ++j) {
;             float ss = 0.f;
; #pragma unroll
;             for (int bj = 0; bj < 2; ++bj) {
;               float2 xn;
;               xn.x = xv[j][bj].x + gt[bj][0] * acc[ai][bj][m][0][j];
;               xn.y = xv[j][bj].y + gt[bj][1] * acc[ai][bj][m][1][j];
;               const unsigned o = tb + (unsigned)((ai * 128 + m * 16 + j) * 1024 + bj * 128);
;               *(float2*)(xout_t + o) = xn;
;               if (g.has_next) *(unsigned*)(xg_t + o) = pack2(xn.x * gn[bj][0], xn.y * gn[bj][1]);
;               ss += xn.x * xn.x + xn.y * xn.y;
;             }
;             if (g.has_next) {
;               ss = dpp_row_sum16(ss);
;               if (fr == 0) rss_t[(wr * 64 + fq * 4 + ai * 128 + m * 16 + j) * 16] = ss;
;             }
.LBB0_485:
	v_add_u32_e32 v62, 0x24800, v0
	v_mov_b32_e32 v50, v48
	v_mov_b32_e32 v51, v44
	v_mov_b32_e32 v63, v1
	s_waitcnt lgkmcnt(1)
	v_pk_fma_f32 v[52:53], v[50:51], v[184:185], v[58:59]
	v_lshl_add_u64 v[50:51], v[62:63], 2, s[2:3]
	global_store_dwordx2 v[50:51], v[52:53], off
	s_mov_b64 s[10:11], -1
	s_and_b64 vcc, exec, s[6:7]
	v_add_u32_e32 v50, 0x24880, v0
	s_cbranch_vccnz .LBB0_489
	v_pk_mul_f32 v[58:59], v[182:183], v[52:53]
	v_mov_b32_e32 v51, v1
	s_nop 0
	v_and_b32_sdwa v44, v59, v178 dst_sel:DWORD dst_unused:UNUSED_PAD src0_sel:WORD_1 src1_sel:DWORD
	v_cvt_pk_bf16_f32 v48, v58, v58
	v_add3_u32 v44, v59, v44, s81
	v_lshrrev_b32_e32 v48, 16, v48
	v_and_or_b32 v44, v44, s28, v48
	v_lshl_add_u64 v[58:59], v[62:63], 1, s[8:9]
	global_store_dword v[58:59], v44, off
	v_mov_b32_e32 v58, v42
	v_mov_b32_e32 v59, v46
	v_pk_fma_f32 v[58:59], v[58:59], v[180:181], v[60:61]
	v_lshl_add_u64 v[62:63], v[50:51], 2, s[2:3]
	global_store_dwordx2 v[62:63], v[58:59], off
	v_pk_mul_f32 v[62:63], v[186:187], v[58:59]
	v_pk_mul_f32 v[52:53], v[52:53], v[52:53]
	s_nop 0
	v_and_b32_sdwa v44, v63, v178 dst_sel:DWORD dst_unused:UNUSED_PAD src0_sel:WORD_1 src1_sel:DWORD
	v_cvt_pk_bf16_f32 v48, v62, v62
	v_add3_u32 v44, v63, v44, s81
	v_lshrrev_b32_e32 v48, 16, v48
	v_and_or_b32 v44, v44, s28, v48
	v_lshl_add_u64 v[62:63], v[50:51], 1, s[8:9]
	v_pk_mul_f32 v[58:59], v[58:59], v[58:59]
	global_store_dword v[62:63], v44, off
	v_add_f32_e32 v44, v58, v59
	v_add_f32_e32 v48, v52, v53
	v_add_f32_e32 v44, v48, v44
	s_nop 1
	v_add_f32_dpp v44, v44, v44 quad_perm:[1,0,3,2] row_mask:0xf bank_mask:0xf bound_ctrl:1
	s_nop 1
	v_add_f32_dpp v44, v44, v44 quad_perm:[2,3,0,1] row_mask:0xf bank_mask:0xf bound_ctrl:1
	s_nop 1
	v_add_f32_dpp v44, v44, v44 row_half_mirror row_mask:0xf bank_mask:0xf bound_ctrl:1
	s_nop 1
	v_mov_b32_dpp v48, v44 row_mirror row_mask:0xf bank_mask:0xf bound_ctrl:1
	s_and_saveexec_b64 s[10:11], s[4:5]
	s_cbranch_execz .LBB0_488
	v_add_f32_e32 v44, v44, v48
	v_mov_b32_e32 v48, 0x920
	v_lshl_add_u32 v52, v194, 4, v48
	v_ashrrev_i32_e32 v53, 31, v52
	v_lshl_add_u64 v[52:53], v[52:53], 2, v[150:151]
	global_store_dword v[52:53], v44, off

; __device__ __forceinline__ unsigned pack2(float a, float b) { return (unsigned)f2bf(a) | ((unsigned)f2bf(b) << 16); }
; template <int EPI, bool HS = false>
; __device__ __forceinline__ void gemm_phase(const Params& p, const GemmCfg& g, char* shm, const int wave_s) {
;     ...
;             for (int bj = 0; bj < 2; ++bj) xv[j][bj] = *(const float2*)(xl + (m * 16 + j) * XROW + bj * 512);
; #pragma unroll
;           for (int j = 0; j < 4; ++j) {
;             float ss = 0.f;
; #pragma unroll
;             for (int bj = 0; bj < 2; ++bj) {
;               float2 xn;
;               xn.x = xv[j][bj].x + gt[bj][0] * acc[ai][bj][m][0][j];
;               xn.y = xv[j][bj].y + gt[bj][1] * acc[ai][bj][m][1][j];
;               const unsigned o = tb + (unsigned)((ai * 128 + m * 16 + j) * 1024 + bj * 128);
;               *(float2*)(xout_t + o) = xn;
;               if (g.has_next) *(unsigned*)(xg_t + o) = pack2(xn.x * gn[bj][0], xn.y * gn[bj][1]);
;               ss += xn.x * xn.x + xn.y * xn.y;
;             }
;             if (g.has_next) {
;               ss = dpp_row_sum16(ss);
;               if (fr == 0) rss_t[(wr * 64 + fq * 4 + ai * 128 + m * 16 + j) * 16] = ss;
;             }
.LBB0_491:
	v_add_u32_e32 v50, 0x24c00, v0
	v_mov_b32_e32 v44, v49
	v_mov_b32_e32 v51, v1
	s_waitcnt lgkmcnt(0)
	v_pk_fma_f32 v[48:49], v[44:45], v[184:185], v[54:55]
	v_lshl_add_u64 v[44:45], v[50:51], 2, s[2:3]
	global_store_dwordx2 v[44:45], v[48:49], off
	s_mov_b64 s[10:11], -1
	s_and_b64 vcc, exec, s[6:7]
	v_add_u32_e32 v44, 0x24c80, v0
	s_cbranch_vccnz .LBB0_495
	v_pk_mul_f32 v[52:53], v[182:183], v[48:49]
	v_lshl_add_u64 v[50:51], v[50:51], 1, s[8:9]
	s_nop 0
	v_and_b32_sdwa v42, v53, v178 dst_sel:DWORD dst_unused:UNUSED_PAD src0_sel:WORD_1 src1_sel:DWORD
	v_cvt_pk_bf16_f32 v45, v52, v52
	v_add3_u32 v42, v53, v42, s81
	v_lshrrev_b32_e32 v45, 16, v45
	v_and_or_b32 v42, v42, s28, v45
	v_mov_b32_e32 v46, v43
	v_mov_b32_e32 v45, v1
	global_store_dword v[50:51], v42, off
	v_pk_fma_f32 v[50:51], v[46:47], v[180:181], v[56:57]
	v_lshl_add_u64 v[52:53], v[44:45], 2, s[2:3]
	global_store_dwordx2 v[52:53], v[50:51], off
	v_pk_mul_f32 v[52:53], v[186:187], v[50:51]
	v_pk_mul_f32 v[48:49], v[48:49], v[48:49]
	s_nop 0
	v_and_b32_sdwa v42, v53, v178 dst_sel:DWORD dst_unused:UNUSED_PAD src0_sel:WORD_1 src1_sel:DWORD
	v_cvt_pk_bf16_f32 v46, v52, v52
	v_add3_u32 v42, v53, v42, s81
	v_lshrrev_b32_e32 v46, 16, v46
	v_and_or_b32 v42, v42, s28, v46
	v_lshl_add_u64 v[52:53], v[44:45], 1, s[8:9]
	v_pk_mul_f32 v[50:51], v[50:51], v[50:51]
	global_store_dword v[52:53], v42, off
	v_add_f32_e32 v42, v50, v51
	v_add_f32_e32 v45, v48, v49
	v_add_f32_e32 v42, v45, v42
	s_nop 1
	v_add_f32_dpp v42, v42, v42 quad_perm:[1,0,3,2] row_mask:0xf bank_mask:0xf bound_ctrl:1
	s_nop 1
	v_add_f32_dpp v42, v42, v42 quad_perm:[2,3,0,1] row_mask:0xf bank_mask:0xf bound_ctrl:1
	s_nop 1
	v_add_f32_dpp v42, v42, v42 row_half_mirror row_mask:0xf bank_mask:0xf bound_ctrl:1
	s_nop 1
	v_mov_b32_dpp v45, v42 row_mirror row_mask:0xf bank_mask:0xf bound_ctrl:1
	s_and_saveexec_b64 s[10:11], s[4:5]
	s_cbranch_execz .LBB0_494
	v_add_f32_e32 v42, v42, v45
	v_mov_b32_e32 v45, 0x930
	v_lshl_add_u32 v48, v194, 4, v45
	v_ashrrev_i32_e32 v49, 31, v48
	v_lshl_add_u64 v[48:49], v[48:49], 2, v[150:151]
	global_store_dword v[48:49], v42, off

; __device__ __forceinline__ unsigned pack2(float a, float b) { return (unsigned)f2bf(a) | ((unsigned)f2bf(b) << 16); }
; template <int EPI, bool HS = false>
; __device__ __forceinline__ void gemm_phase(const Params& p, const GemmCfg& g, char* shm, const int wave_s) {
;     ...
;         for (int m = 0; m < 4; ++m) {
;           float2 xv[4][2];
; #pragma unroll
;           for (int j = 0; j < 4; ++j)
; #pragma unroll
;             for (int bj = 0; bj < 2; ++bj) xv[j][bj] = *(const float2*)(xl + (m * 16 + j) * XROW + bj * 512);
; #pragma unroll
;           for (int j = 0; j < 4; ++j) {
;             float ss = 0.f;
; #pragma unroll
;             for (int bj = 0; bj < 2; ++bj) {
;               float2 xn;
;               xn.x = xv[j][bj].x + gt[bj][0] * acc[ai][bj][m][0][j];
;               xn.y = xv[j][bj].y + gt[bj][1] * acc[ai][bj][m][1][j];
;               const unsigned o = tb + (unsigned)((ai * 128 + m * 16 + j) * 1024 + bj * 128);
;               *(float2*)(xout_t + o) = xn;
;               if (g.has_next) *(unsigned*)(xg_t + o) = pack2(xn.x * gn[bj][0], xn.y * gn[bj][1]);
;               ss += xn.x * xn.x + xn.y * xn.y;
;             }
;             if (g.has_next) {
;               ss = dpp_row_sum16(ss);
;               if (fr == 0) rss_t[(wr * 64 + fq * 4 + ai * 128 + m * 16 + j) * 16] = ss;
;             }
.LBB0_497:
	v_pk_mul_f32 v[54:55], v[26:27], v[30:31]
	v_pk_mul_f32 v[52:53], v[22:23], v[30:31]
	v_pk_mul_f32 v[22:23], v[40:41], v[32:33]
	v_pk_mul_f32 v[50:51], v[38:39], v[30:31]
	v_pk_mul_f32 v[26:27], v[36:37], v[32:33]
	v_pk_mul_f32 v[30:31], v[34:35], v[30:31]
	ds_read2st64_b64 v[46:49], v195 offset0:65 offset1:66
	ds_read2st64_b64 v[42:45], v140 offset0:67 offset1:68
	ds_read2st64_b64 v[38:41], v196 offset0:69 offset1:70
	ds_read2st64_b64 v[34:37], v197 offset0:71 offset1:72
	v_add_u32_e32 v58, 0x28000, v0
	v_mov_b32_e32 v56, v54
	v_mov_b32_e32 v57, v52
	v_mov_b32_e32 v59, v1
	s_waitcnt lgkmcnt(3)
	v_pk_fma_f32 v[56:57], v[56:57], v[184:185], v[46:47]
	v_lshl_add_u64 v[46:47], v[58:59], 2, s[2:3]
	global_store_dwordx2 v[46:47], v[56:57], off
	s_mov_b64 s[10:11], -1
	s_and_b64 vcc, exec, s[6:7]
	v_add_u32_e32 v46, 0x28080, v0
	s_cbranch_vccnz .LBB0_501
	v_pk_mul_f32 v[60:61], v[182:183], v[56:57]
	v_lshl_add_u64 v[58:59], v[58:59], 1, s[8:9]
	s_nop 0
	v_and_b32_sdwa v47, v61, v178 dst_sel:DWORD dst_unused:UNUSED_PAD src0_sel:WORD_1 src1_sel:DWORD
	v_cvt_pk_bf16_f32 v52, v60, v60
	v_add3_u32 v47, v61, v47, s81
	v_lshrrev_b32_e32 v52, 16, v52
	v_and_or_b32 v47, v47, s28, v52
	global_store_dword v[58:59], v47, off
	v_mov_b32_e32 v58, v50
	v_mov_b32_e32 v59, v30
	v_mov_b32_e32 v47, v1
	v_pk_fma_f32 v[58:59], v[58:59], v[180:181], v[48:49]
	v_lshl_add_u64 v[60:61], v[46:47], 2, s[2:3]
	global_store_dwordx2 v[60:61], v[58:59], off
	v_pk_mul_f32 v[60:61], v[186:187], v[58:59]
	v_pk_mul_f32 v[56:57], v[56:57], v[56:57]
	s_nop 0
	v_and_b32_sdwa v52, v61, v178 dst_sel:DWORD dst_unused:UNUSED_PAD src0_sel:WORD_1 src1_sel:DWORD
	v_cvt_pk_bf16_f32 v54, v60, v60
	v_add3_u32 v52, v61, v52, s81
	v_lshrrev_b32_e32 v54, 16, v54
	v_and_or_b32 v52, v52, s28, v54
	v_lshl_add_u64 v[60:61], v[46:47], 1, s[8:9]
	v_pk_mul_f32 v[58:59], v[58:59], v[58:59]
	global_store_dword v[60:61], v52, off
	v_add_f32_e32 v47, v58, v59
	v_add_f32_e32 v52, v56, v57
	v_add_f32_e32 v47, v52, v47
	s_nop 1
	v_add_f32_dpp v47, v47, v47 quad_perm:[1,0,3,2] row_mask:0xf bank_mask:0xf bound_ctrl:1
	s_nop 1
	v_add_f32_dpp v47, v47, v47 quad_perm:[2,3,0,1] row_mask:0xf bank_mask:0xf bound_ctrl:1
	s_nop 1
	v_add_f32_dpp v47, v47, v47 row_half_mirror row_mask:0xf bank_mask:0xf bound_ctrl:1
	s_nop 1
	v_mov_b32_dpp v52, v47 row_mirror row_mask:0xf bank_mask:0xf bound_ctrl:1
	s_and_saveexec_b64 s[10:11], s[4:5]
	s_cbranch_execz .LBB0_500
	v_add_f32_e32 v47, v47, v52
	v_mov_b32_e32 v52, 0xa00
	v_lshl_add_u32 v56, v194, 4, v52
	v_ashrrev_i32_e32 v57, 31, v56
	v_lshl_add_u64 v[56:57], v[56:57], 2, v[150:151]
	global_store_dword v[56:57], v47, off

; __device__ __forceinline__ unsigned pack2(float a, float b) { return (unsigned)f2bf(a) | ((unsigned)f2bf(b) << 16); }
; template <int EPI, bool HS = false>
; __device__ __forceinline__ void gemm_phase(const Params& p, const GemmCfg& g, char* shm, const int wave_s) {
;     ...
;             for (int bj = 0; bj < 2; ++bj) xv[j][bj] = *(const float2*)(xl + (m * 16 + j) * XROW + bj * 512);
; #pragma unroll
;           for (int j = 0; j < 4; ++j) {
;             float ss = 0.f;
; #pragma unroll
;             for (int bj = 0; bj < 2; ++bj) {
;               float2 xn;
;               xn.x = xv[j][bj].x + gt[bj][0] * acc[ai][bj][m][0][j];
;               xn.y = xv[j][bj].y + gt[bj][1] * acc[ai][bj][m][1][j];
;               const unsigned o = tb + (unsigned)((ai * 128 + m * 16 + j) * 1024 + bj * 128);
;               *(float2*)(xout_t + o) = xn;
;               if (g.has_next) *(unsigned*)(xg_t + o) = pack2(xn.x * gn[bj][0], xn.y * gn[bj][1]);
;               ss += xn.x * xn.x + xn.y * xn.y;
;             }
;             if (g.has_next) {
;               ss = dpp_row_sum16(ss);
;               if (fr == 0) rss_t[(wr * 64 + fq * 4 + ai * 128 + m * 16 + j) * 16] = ss;
;             }
.LBB0_503:
	v_add_u32_e32 v46, 0x28400, v0
	v_mov_b32_e32 v52, v55
	v_mov_b32_e32 v47, v1
	v_pk_mul_f32 v[28:29], v[28:29], v[32:33]
	v_pk_mul_f32 v[24:25], v[24:25], v[32:33]
	s_waitcnt lgkmcnt(2)
	v_pk_fma_f32 v[42:43], v[52:53], v[184:185], v[42:43]
	v_lshl_add_u64 v[32:33], v[46:47], 2, s[2:3]
	global_store_dwordx2 v[32:33], v[42:43], off
	s_mov_b64 s[10:11], -1
	s_and_b64 vcc, exec, s[6:7]
	v_add_u32_e32 v32, 0x28480, v0
	s_cbranch_vccnz .LBB0_507
	v_pk_mul_f32 v[48:49], v[182:183], v[42:43]
	v_lshl_add_u64 v[46:47], v[46:47], 1, s[8:9]
	s_nop 0
	v_and_b32_sdwa v30, v49, v178 dst_sel:DWORD dst_unused:UNUSED_PAD src0_sel:WORD_1 src1_sel:DWORD
	v_cvt_pk_bf16_f32 v33, v48, v48
	v_add3_u32 v30, v49, v30, s81
	v_lshrrev_b32_e32 v33, 16, v33
	v_and_or_b32 v30, v30, s28, v33
	global_store_dword v[46:47], v30, off
	v_mov_b32_e32 v30, v51
	v_mov_b32_e32 v33, v1
	v_pk_fma_f32 v[46:47], v[30:31], v[180:181], v[44:45]
	v_lshl_add_u64 v[48:49], v[32:33], 2, s[2:3]
	global_store_dwordx2 v[48:49], v[46:47], off
	v_pk_mul_f32 v[48:49], v[186:187], v[46:47]
	v_pk_mul_f32 v[42:43], v[42:43], v[42:43]
	v_and_b32_sdwa v50, v48, v178 dst_sel:DWORD dst_unused:UNUSED_PAD src0_sel:WORD_1 src1_sel:DWORD
	v_and_b32_sdwa v30, v49, v178 dst_sel:DWORD dst_unused:UNUSED_PAD src0_sel:WORD_1 src1_sel:DWORD
	v_add3_u32 v48, v48, v50, s81
	v_add3_u32 v30, v49, v30, s81
	v_lshrrev_b32_e32 v48, 16, v48
	v_and_or_b32 v30, v30, s28, v48
	v_lshl_add_u64 v[48:49], v[32:33], 1, s[8:9]
	v_pk_mul_f32 v[46:47], v[46:47], v[46:47]
	global_store_dword v[48:49], v30, off
	v_add_f32_e32 v30, v46, v47
	v_add_f32_e32 v33, v42, v43
	v_add_f32_e32 v30, v33, v30
	s_nop 1
	v_add_f32_dpp v30, v30, v30 quad_perm:[1,0,3,2] row_mask:0xf bank_mask:0xf bound_ctrl:1
	s_nop 1
	v_add_f32_dpp v30, v30, v30 quad_perm:[2,3,0,1] row_mask:0xf bank_mask:0xf bound_ctrl:1
	s_nop 1
	v_add_f32_dpp v30, v30, v30 row_half_mirror row_mask:0xf bank_mask:0xf bound_ctrl:1
	s_nop 1
	v_mov_b32_dpp v33, v30 row_mirror row_mask:0xf bank_mask:0xf bound_ctrl:1
	s_and_saveexec_b64 s[10:11], s[4:5]
	s_cbranch_execz .LBB0_506
	v_add_f32_e32 v30, v30, v33
	v_mov_b32_e32 v33, 0xa10
	v_lshl_add_u32 v42, v194, 4, v33
	v_ashrrev_i32_e32 v43, 31, v42
	v_lshl_add_u64 v[42:43], v[42:43], 2, v[150:151]
	global_store_dword v[42:43], v30, off

; __device__ __forceinline__ unsigned pack2(float a, float b) { return (unsigned)f2bf(a) | ((unsigned)f2bf(b) << 16); }
; template <int EPI, bool HS = false>
; __device__ __forceinline__ void gemm_phase(const Params& p, const GemmCfg& g, char* shm, const int wave_s) {
;     ...
;             for (int bj = 0; bj < 2; ++bj) xv[j][bj] = *(const float2*)(xl + (m * 16 + j) * XROW + bj * 512);
; #pragma unroll
;           for (int j = 0; j < 4; ++j) {
;             float ss = 0.f;
; #pragma unroll
;             for (int bj = 0; bj < 2; ++bj) {
;               float2 xn;
;               xn.x = xv[j][bj].x + gt[bj][0] * acc[ai][bj][m][0][j];
;               xn.y = xv[j][bj].y + gt[bj][1] * acc[ai][bj][m][1][j];
;               const unsigned o = tb + (unsigned)((ai * 128 + m * 16 + j) * 1024 + bj * 128);
;               *(float2*)(xout_t + o) = xn;
;               if (g.has_next) *(unsigned*)(xg_t + o) = pack2(xn.x * gn[bj][0], xn.y * gn[bj][1]);
;               ss += xn.x * xn.x + xn.y * xn.y;
;             }
;             if (g.has_next) {
;               ss = dpp_row_sum16(ss);
;               if (fr == 0) rss_t[(wr * 64 + fq * 4 + ai * 128 + m * 16 + j) * 16] = ss;
;             }
.LBB0_509:
	v_add_u32_e32 v42, 0x28800, v0
	v_mov_b32_e32 v30, v28
	v_mov_b32_e32 v31, v24
	v_mov_b32_e32 v43, v1
	s_waitcnt lgkmcnt(1)
	v_pk_fma_f32 v[32:33], v[30:31], v[184:185], v[38:39]
	v_lshl_add_u64 v[30:31], v[42:43], 2, s[2:3]
	global_store_dwordx2 v[30:31], v[32:33], off
	s_mov_b64 s[10:11], -1
	s_and_b64 vcc, exec, s[6:7]
	v_add_u32_e32 v30, 0x28880, v0
	s_cbranch_vccnz .LBB0_513
	v_pk_mul_f32 v[38:39], v[182:183], v[32:33]
	v_mov_b32_e32 v31, v1
	s_nop 0
	v_and_b32_sdwa v24, v39, v178 dst_sel:DWORD dst_unused:UNUSED_PAD src0_sel:WORD_1 src1_sel:DWORD
	v_cvt_pk_bf16_f32 v28, v38, v38
	v_add3_u32 v24, v39, v24, s81
	v_lshrrev_b32_e32 v28, 16, v28
	v_and_or_b32 v24, v24, s28, v28
	v_lshl_add_u64 v[38:39], v[42:43], 1, s[8:9]
	global_store_dword v[38:39], v24, off
	v_mov_b32_e32 v38, v22
	v_mov_b32_e32 v39, v26
	v_pk_fma_f32 v[38:39], v[38:39], v[180:181], v[40:41]
	v_lshl_add_u64 v[42:43], v[30:31], 2, s[2:3]
	global_store_dwordx2 v[42:43], v[38:39], off
	v_pk_mul_f32 v[42:43], v[186:187], v[38:39]
	v_pk_mul_f32 v[32:33], v[32:33], v[32:33]
	s_nop 0
	v_and_b32_sdwa v24, v43, v178 dst_sel:DWORD dst_unused:UNUSED_PAD src0_sel:WORD_1 src1_sel:DWORD
	v_cvt_pk_bf16_f32 v28, v42, v42
	v_add3_u32 v24, v43, v24, s81
	v_lshrrev_b32_e32 v28, 16, v28
	v_and_or_b32 v24, v24, s28, v28
	v_lshl_add_u64 v[42:43], v[30:31], 1, s[8:9]
	v_pk_mul_f32 v[38:39], v[38:39], v[38:39]
	global_store_dword v[42:43], v24, off
	v_add_f32_e32 v24, v38, v39
	v_add_f32_e32 v28, v32, v33
	v_add_f32_e32 v24, v28, v24
	s_nop 1
	v_add_f32_dpp v24, v24, v24 quad_perm:[1,0,3,2] row_mask:0xf bank_mask:0xf bound_ctrl:1
	s_nop 1
	v_add_f32_dpp v24, v24, v24 quad_perm:[2,3,0,1] row_mask:0xf bank_mask:0xf bound_ctrl:1
	s_nop 1
	v_add_f32_dpp v24, v24, v24 row_half_mirror row_mask:0xf bank_mask:0xf bound_ctrl:1
	s_nop 1
	v_mov_b32_dpp v28, v24 row_mirror row_mask:0xf bank_mask:0xf bound_ctrl:1
	s_and_saveexec_b64 s[10:11], s[4:5]
	s_cbranch_execz .LBB0_512
	v_add_f32_e32 v24, v24, v28
	v_mov_b32_e32 v28, 0xa20
	v_lshl_add_u32 v32, v194, 4, v28
	v_ashrrev_i32_e32 v33, 31, v32
	v_lshl_add_u64 v[32:33], v[32:33], 2, v[150:151]
	global_store_dword v[32:33], v24, off

; __device__ __forceinline__ unsigned pack2(float a, float b) { return (unsigned)f2bf(a) | ((unsigned)f2bf(b) << 16); }
; template <int EPI, bool HS = false>
; __device__ __forceinline__ void gemm_phase(const Params& p, const GemmCfg& g, char* shm, const int wave_s) {
;     ...
;             for (int bj = 0; bj < 2; ++bj) xv[j][bj] = *(const float2*)(xl + (m * 16 + j) * XROW + bj * 512);
; #pragma unroll
;           for (int j = 0; j < 4; ++j) {
;             float ss = 0.f;
; #pragma unroll
;             for (int bj = 0; bj < 2; ++bj) {
;               float2 xn;
;               xn.x = xv[j][bj].x + gt[bj][0] * acc[ai][bj][m][0][j];
;               xn.y = xv[j][bj].y + gt[bj][1] * acc[ai][bj][m][1][j];
;               const unsigned o = tb + (unsigned)((ai * 128 + m * 16 + j) * 1024 + bj * 128);
;               *(float2*)(xout_t + o) = xn;
;               if (g.has_next) *(unsigned*)(xg_t + o) = pack2(xn.x * gn[bj][0], xn.y * gn[bj][1]);
;               ss += xn.x * xn.x + xn.y * xn.y;
;             }
;             if (g.has_next) {
;               ss = dpp_row_sum16(ss);
;               if (fr == 0) rss_t[(wr * 64 + fq * 4 + ai * 128 + m * 16 + j) * 16] = ss;
;             }
.LBB0_515:
	v_add_u32_e32 v30, 0x28c00, v0
	v_mov_b32_e32 v24, v29
	v_mov_b32_e32 v31, v1
	s_waitcnt lgkmcnt(0)
	v_pk_fma_f32 v[28:29], v[24:25], v[184:185], v[34:35]
	v_lshl_add_u64 v[24:25], v[30:31], 2, s[2:3]
	global_store_dwordx2 v[24:25], v[28:29], off
	s_mov_b64 s[10:11], -1
	s_and_b64 vcc, exec, s[6:7]
	v_add_u32_e32 v24, 0x28c80, v0
	s_cbranch_vccnz .LBB0_519
	v_pk_mul_f32 v[32:33], v[182:183], v[28:29]
	v_lshl_add_u64 v[30:31], v[30:31], 1, s[8:9]
	s_nop 0
	v_and_b32_sdwa v22, v33, v178 dst_sel:DWORD dst_unused:UNUSED_PAD src0_sel:WORD_1 src1_sel:DWORD
	v_cvt_pk_bf16_f32 v25, v32, v32
	v_add3_u32 v22, v33, v22, s81
	v_lshrrev_b32_e32 v25, 16, v25
	v_and_or_b32 v22, v22, s28, v25
	v_mov_b32_e32 v26, v23
	v_mov_b32_e32 v25, v1
	global_store_dword v[30:31], v22, off
	v_pk_fma_f32 v[30:31], v[26:27], v[180:181], v[36:37]
	v_lshl_add_u64 v[32:33], v[24:25], 2, s[2:3]
	global_store_dwordx2 v[32:33], v[30:31], off
	v_pk_mul_f32 v[32:33], v[186:187], v[30:31]
	v_pk_mul_f32 v[28:29], v[28:29], v[28:29]
	s_nop 0
	v_and_b32_sdwa v22, v33, v178 dst_sel:DWORD dst_unused:UNUSED_PAD src0_sel:WORD_1 src1_sel:DWORD
	v_cvt_pk_bf16_f32 v26, v32, v32
	v_add3_u32 v22, v33, v22, s81
	v_lshrrev_b32_e32 v26, 16, v26
	v_and_or_b32 v22, v22, s28, v26
	v_lshl_add_u64 v[32:33], v[24:25], 1, s[8:9]
	v_pk_mul_f32 v[30:31], v[30:31], v[30:31]
	global_store_dword v[32:33], v22, off
	v_add_f32_e32 v22, v30, v31
	v_add_f32_e32 v25, v28, v29
	v_add_f32_e32 v22, v25, v22
	s_nop 1
	v_add_f32_dpp v22, v22, v22 quad_perm:[1,0,3,2] row_mask:0xf bank_mask:0xf bound_ctrl:1
	s_nop 1
	v_add_f32_dpp v22, v22, v22 quad_perm:[2,3,0,1] row_mask:0xf bank_mask:0xf bound_ctrl:1
	s_nop 1
	v_add_f32_dpp v22, v22, v22 row_half_mirror row_mask:0xf bank_mask:0xf bound_ctrl:1
	s_nop 1
	v_mov_b32_dpp v25, v22 row_mirror row_mask:0xf bank_mask:0xf bound_ctrl:1
	s_and_saveexec_b64 s[10:11], s[4:5]
	s_cbranch_execz .LBB0_518
	v_add_f32_e32 v22, v22, v25
	v_mov_b32_e32 v25, 0xa30
	v_lshl_add_u32 v28, v194, 4, v25
	v_ashrrev_i32_e32 v29, 31, v28
	v_lshl_add_u64 v[28:29], v[28:29], 2, v[150:151]
	global_store_dword v[28:29], v22, off

; __device__ __forceinline__ unsigned pack2(float a, float b) { return (unsigned)f2bf(a) | ((unsigned)f2bf(b) << 16); }
; template <int EPI, bool HS = false>
; __device__ __forceinline__ void gemm_phase(const Params& p, const GemmCfg& g, char* shm, const int wave_s) {
;     ...
;         for (int m = 0; m < 4; ++m) {
;           float2 xv[4][2];
; #pragma unroll
;           for (int j = 0; j < 4; ++j)
; #pragma unroll
;             for (int bj = 0; bj < 2; ++bj) xv[j][bj] = *(const float2*)(xl + (m * 16 + j) * XROW + bj * 512);
; #pragma unroll
;           for (int j = 0; j < 4; ++j) {
;             float ss = 0.f;
; #pragma unroll
;             for (int bj = 0; bj < 2; ++bj) {
;               float2 xn;
;               xn.x = xv[j][bj].x + gt[bj][0] * acc[ai][bj][m][0][j];
;               xn.y = xv[j][bj].y + gt[bj][1] * acc[ai][bj][m][1][j];
;               const unsigned o = tb + (unsigned)((ai * 128 + m * 16 + j) * 1024 + bj * 128);
;               *(float2*)(xout_t + o) = xn;
;               if (g.has_next) *(unsigned*)(xg_t + o) = pack2(xn.x * gn[bj][0], xn.y * gn[bj][1]);
;               ss += xn.x * xn.x + xn.y * xn.y;
;             }
;             if (g.has_next) {
;               ss = dpp_row_sum16(ss);
;               if (fr == 0) rss_t[(wr * 64 + fq * 4 + ai * 128 + m * 16 + j) * 16] = ss;
;             }
.LBB0_521:
	v_pk_mul_f32 v[34:35], v[6:7], v[10:11]
	v_pk_mul_f32 v[32:33], v[2:3], v[10:11]
	v_pk_mul_f32 v[2:3], v[20:21], v[12:13]
	v_pk_mul_f32 v[30:31], v[18:19], v[10:11]
	v_pk_mul_f32 v[6:7], v[16:17], v[12:13]
	v_pk_mul_f32 v[10:11], v[14:15], v[10:11]
	ds_read2st64_b64 v[26:29], v162 offset0:97 offset1:98
	ds_read2st64_b64 v[22:25], v163 offset0:99 offset1:100
	ds_read2st64_b64 v[18:21], v164 offset0:101 offset1:102
	ds_read2st64_b64 v[14:17], v165 offset0:103 offset1:104
	v_add_u32_e32 v38, 0x2c000, v0
	v_mov_b32_e32 v36, v34
	v_mov_b32_e32 v37, v32
	v_mov_b32_e32 v39, v1
	s_waitcnt lgkmcnt(3)
	v_pk_fma_f32 v[36:37], v[36:37], v[184:185], v[26:27]
	v_lshl_add_u64 v[26:27], v[38:39], 2, s[2:3]
	global_store_dwordx2 v[26:27], v[36:37], off
	s_mov_b64 s[10:11], -1
	s_and_b64 vcc, exec, s[6:7]
	v_add_u32_e32 v26, 0x2c080, v0
	s_cbranch_vccnz .LBB0_525
	v_pk_mul_f32 v[40:41], v[182:183], v[36:37]
	v_lshl_add_u64 v[38:39], v[38:39], 1, s[8:9]
	s_nop 0
	v_and_b32_sdwa v27, v41, v178 dst_sel:DWORD dst_unused:UNUSED_PAD src0_sel:WORD_1 src1_sel:DWORD
	v_cvt_pk_bf16_f32 v32, v40, v40
	v_add3_u32 v27, v41, v27, s81
	v_lshrrev_b32_e32 v32, 16, v32
	v_and_or_b32 v27, v27, s28, v32
	global_store_dword v[38:39], v27, off
	v_mov_b32_e32 v38, v30
	v_mov_b32_e32 v39, v10
	v_mov_b32_e32 v27, v1
	v_pk_fma_f32 v[38:39], v[38:39], v[180:181], v[28:29]
	v_lshl_add_u64 v[40:41], v[26:27], 2, s[2:3]
	global_store_dwordx2 v[40:41], v[38:39], off
	v_pk_mul_f32 v[40:41], v[186:187], v[38:39]
	v_pk_mul_f32 v[36:37], v[36:37], v[36:37]
	s_nop 0
	v_and_b32_sdwa v32, v41, v178 dst_sel:DWORD dst_unused:UNUSED_PAD src0_sel:WORD_1 src1_sel:DWORD
	v_cvt_pk_bf16_f32 v34, v40, v40
	v_add3_u32 v32, v41, v32, s81
	v_lshrrev_b32_e32 v34, 16, v34
	v_and_or_b32 v32, v32, s28, v34
	v_lshl_add_u64 v[40:41], v[26:27], 1, s[8:9]
	v_pk_mul_f32 v[38:39], v[38:39], v[38:39]
	global_store_dword v[40:41], v32, off
	v_add_f32_e32 v27, v38, v39
	v_add_f32_e32 v32, v36, v37
	v_add_f32_e32 v27, v32, v27
	s_nop 1
	v_add_f32_dpp v27, v27, v27 quad_perm:[1,0,3,2] row_mask:0xf bank_mask:0xf bound_ctrl:1
	s_nop 1
	v_add_f32_dpp v27, v27, v27 quad_perm:[2,3,0,1] row_mask:0xf bank_mask:0xf bound_ctrl:1
	s_nop 1
	v_add_f32_dpp v27, v27, v27 row_half_mirror row_mask:0xf bank_mask:0xf bound_ctrl:1
	s_nop 1
	v_mov_b32_dpp v32, v27 row_mirror row_mask:0xf bank_mask:0xf bound_ctrl:1
	s_and_saveexec_b64 s[10:11], s[4:5]
	s_cbranch_execz .LBB0_524
	v_add_f32_e32 v27, v27, v32
	v_mov_b32_e32 v32, 0xb00
	v_lshl_add_u32 v36, v194, 4, v32
	v_ashrrev_i32_e32 v37, 31, v36
	v_lshl_add_u64 v[36:37], v[36:37], 2, v[150:151]
	global_store_dword v[36:37], v27, off

; __device__ __forceinline__ unsigned pack2(float a, float b) { return (unsigned)f2bf(a) | ((unsigned)f2bf(b) << 16); }
; template <int EPI, bool HS = false>
; __device__ __forceinline__ void gemm_phase(const Params& p, const GemmCfg& g, char* shm, const int wave_s) {
;     ...
;             for (int bj = 0; bj < 2; ++bj) xv[j][bj] = *(const float2*)(xl + (m * 16 + j) * XROW + bj * 512);
; #pragma unroll
;           for (int j = 0; j < 4; ++j) {
;             float ss = 0.f;
; #pragma unroll
;             for (int bj = 0; bj < 2; ++bj) {
;               float2 xn;
;               xn.x = xv[j][bj].x + gt[bj][0] * acc[ai][bj][m][0][j];
;               xn.y = xv[j][bj].y + gt[bj][1] * acc[ai][bj][m][1][j];
;               const unsigned o = tb + (unsigned)((ai * 128 + m * 16 + j) * 1024 + bj * 128);
;               *(float2*)(xout_t + o) = xn;
;               if (g.has_next) *(unsigned*)(xg_t + o) = pack2(xn.x * gn[bj][0], xn.y * gn[bj][1]);
;               ss += xn.x * xn.x + xn.y * xn.y;
;             }
;             if (g.has_next) {
;               ss = dpp_row_sum16(ss);
;               if (fr == 0) rss_t[(wr * 64 + fq * 4 + ai * 128 + m * 16 + j) * 16] = ss;
;             }
.LBB0_527:
	v_add_u32_e32 v26, 0x2c400, v0
	v_mov_b32_e32 v32, v35
	v_mov_b32_e32 v27, v1
	v_pk_mul_f32 v[8:9], v[8:9], v[12:13]
	v_pk_mul_f32 v[4:5], v[4:5], v[12:13]
	s_waitcnt lgkmcnt(2)
	v_pk_fma_f32 v[22:23], v[32:33], v[184:185], v[22:23]
	v_lshl_add_u64 v[12:13], v[26:27], 2, s[2:3]
	global_store_dwordx2 v[12:13], v[22:23], off
	s_mov_b64 s[10:11], -1
	s_and_b64 vcc, exec, s[6:7]
	v_add_u32_e32 v12, 0x2c480, v0
	s_cbranch_vccnz .LBB0_531
	v_pk_mul_f32 v[28:29], v[182:183], v[22:23]
	v_lshl_add_u64 v[26:27], v[26:27], 1, s[8:9]
	s_nop 0
	v_and_b32_sdwa v10, v29, v178 dst_sel:DWORD dst_unused:UNUSED_PAD src0_sel:WORD_1 src1_sel:DWORD
	v_cvt_pk_bf16_f32 v13, v28, v28
	v_add3_u32 v10, v29, v10, s81
	v_lshrrev_b32_e32 v13, 16, v13
	v_and_or_b32 v10, v10, s28, v13
	global_store_dword v[26:27], v10, off
	v_mov_b32_e32 v10, v31
	v_mov_b32_e32 v13, v1
	v_pk_fma_f32 v[26:27], v[10:11], v[180:181], v[24:25]
	v_lshl_add_u64 v[28:29], v[12:13], 2, s[2:3]
	global_store_dwordx2 v[28:29], v[26:27], off
	v_pk_mul_f32 v[28:29], v[186:187], v[26:27]
	v_pk_mul_f32 v[22:23], v[22:23], v[22:23]
	v_and_b32_sdwa v30, v28, v178 dst_sel:DWORD dst_unused:UNUSED_PAD src0_sel:WORD_1 src1_sel:DWORD
	v_and_b32_sdwa v10, v29, v178 dst_sel:DWORD dst_unused:UNUSED_PAD src0_sel:WORD_1 src1_sel:DWORD
	v_add3_u32 v28, v28, v30, s81
	v_add3_u32 v10, v29, v10, s81
	v_lshrrev_b32_e32 v28, 16, v28
	v_and_or_b32 v10, v10, s28, v28
	v_lshl_add_u64 v[28:29], v[12:13], 1, s[8:9]
	v_pk_mul_f32 v[26:27], v[26:27], v[26:27]
	global_store_dword v[28:29], v10, off
	v_add_f32_e32 v10, v26, v27
	v_add_f32_e32 v13, v22, v23
	v_add_f32_e32 v10, v13, v10
	s_nop 1
	v_add_f32_dpp v10, v10, v10 quad_perm:[1,0,3,2] row_mask:0xf bank_mask:0xf bound_ctrl:1
	s_nop 1
	v_add_f32_dpp v10, v10, v10 quad_perm:[2,3,0,1] row_mask:0xf bank_mask:0xf bound_ctrl:1
	s_nop 1
	v_add_f32_dpp v10, v10, v10 row_half_mirror row_mask:0xf bank_mask:0xf bound_ctrl:1
	s_nop 1
	v_mov_b32_dpp v13, v10 row_mirror row_mask:0xf bank_mask:0xf bound_ctrl:1
	s_and_saveexec_b64 s[10:11], s[4:5]
	s_cbranch_execz .LBB0_530
	v_add_f32_e32 v10, v10, v13
	v_mov_b32_e32 v13, 0xb10
	v_lshl_add_u32 v22, v194, 4, v13
	v_ashrrev_i32_e32 v23, 31, v22
	v_lshl_add_u64 v[22:23], v[22:23], 2, v[150:151]
	global_store_dword v[22:23], v10, off

; __device__ __forceinline__ unsigned pack2(float a, float b) { return (unsigned)f2bf(a) | ((unsigned)f2bf(b) << 16); }
; template <int EPI, bool HS = false>
; __device__ __forceinline__ void gemm_phase(const Params& p, const GemmCfg& g, char* shm, const int wave_s) {
;     ...
;             for (int bj = 0; bj < 2; ++bj) xv[j][bj] = *(const float2*)(xl + (m * 16 + j) * XROW + bj * 512);
; #pragma unroll
;           for (int j = 0; j < 4; ++j) {
;             float ss = 0.f;
; #pragma unroll
;             for (int bj = 0; bj < 2; ++bj) {
;               float2 xn;
;               xn.x = xv[j][bj].x + gt[bj][0] * acc[ai][bj][m][0][j];
;               xn.y = xv[j][bj].y + gt[bj][1] * acc[ai][bj][m][1][j];
;               const unsigned o = tb + (unsigned)((ai * 128 + m * 16 + j) * 1024 + bj * 128);
;               *(float2*)(xout_t + o) = xn;
;               if (g.has_next) *(unsigned*)(xg_t + o) = pack2(xn.x * gn[bj][0], xn.y * gn[bj][1]);
;               ss += xn.x * xn.x + xn.y * xn.y;
;             }
;             if (g.has_next) {
;               ss = dpp_row_sum16(ss);
;               if (fr == 0) rss_t[(wr * 64 + fq * 4 + ai * 128 + m * 16 + j) * 16] = ss;
;             }
.LBB0_533:
	v_add_u32_e32 v22, 0x2c800, v0
	v_mov_b32_e32 v10, v8
	v_mov_b32_e32 v11, v4
	v_mov_b32_e32 v23, v1
	s_waitcnt lgkmcnt(1)
	v_pk_fma_f32 v[12:13], v[10:11], v[184:185], v[18:19]
	v_lshl_add_u64 v[10:11], v[22:23], 2, s[2:3]
	global_store_dwordx2 v[10:11], v[12:13], off
	s_mov_b64 s[10:11], -1
	s_and_b64 vcc, exec, s[6:7]
	v_add_u32_e32 v10, 0x2c880, v0
	s_cbranch_vccnz .LBB0_537
	v_pk_mul_f32 v[18:19], v[182:183], v[12:13]
	v_mov_b32_e32 v11, v1
	s_nop 0
	v_and_b32_sdwa v4, v19, v178 dst_sel:DWORD dst_unused:UNUSED_PAD src0_sel:WORD_1 src1_sel:DWORD
	v_cvt_pk_bf16_f32 v8, v18, v18
	v_add3_u32 v4, v19, v4, s81
	v_lshrrev_b32_e32 v8, 16, v8
	v_and_or_b32 v4, v4, s28, v8
	v_lshl_add_u64 v[18:19], v[22:23], 1, s[8:9]
	global_store_dword v[18:19], v4, off
	v_mov_b32_e32 v18, v2
	v_mov_b32_e32 v19, v6
	v_pk_fma_f32 v[18:19], v[18:19], v[180:181], v[20:21]
	v_lshl_add_u64 v[22:23], v[10:11], 2, s[2:3]
	global_store_dwordx2 v[22:23], v[18:19], off
	v_pk_mul_f32 v[22:23], v[186:187], v[18:19]
	v_pk_mul_f32 v[12:13], v[12:13], v[12:13]
	s_nop 0
	v_and_b32_sdwa v4, v23, v178 dst_sel:DWORD dst_unused:UNUSED_PAD src0_sel:WORD_1 src1_sel:DWORD
	v_cvt_pk_bf16_f32 v8, v22, v22
	v_add3_u32 v4, v23, v4, s81
	v_lshrrev_b32_e32 v8, 16, v8
	v_and_or_b32 v4, v4, s28, v8
	v_lshl_add_u64 v[22:23], v[10:11], 1, s[8:9]
	v_pk_mul_f32 v[18:19], v[18:19], v[18:19]
	global_store_dword v[22:23], v4, off
	v_add_f32_e32 v4, v18, v19
	v_add_f32_e32 v8, v12, v13
	v_add_f32_e32 v4, v8, v4
	s_nop 1
	v_add_f32_dpp v4, v4, v4 quad_perm:[1,0,3,2] row_mask:0xf bank_mask:0xf bound_ctrl:1
	s_nop 1
	v_add_f32_dpp v4, v4, v4 quad_perm:[2,3,0,1] row_mask:0xf bank_mask:0xf bound_ctrl:1
	s_nop 1
	v_add_f32_dpp v4, v4, v4 row_half_mirror row_mask:0xf bank_mask:0xf bound_ctrl:1
	s_nop 1
	v_mov_b32_dpp v8, v4 row_mirror row_mask:0xf bank_mask:0xf bound_ctrl:1
	s_and_saveexec_b64 s[10:11], s[4:5]
	s_cbranch_execz .LBB0_536
	v_add_f32_e32 v4, v4, v8
	v_mov_b32_e32 v8, 0xb20
	v_lshl_add_u32 v12, v194, 4, v8
	v_ashrrev_i32_e32 v13, 31, v12
	v_lshl_add_u64 v[12:13], v[12:13], 2, v[150:151]
	global_store_dword v[12:13], v4, off

; __device__ __forceinline__ unsigned pack2(float a, float b) { return (unsigned)f2bf(a) | ((unsigned)f2bf(b) << 16); }
; template <int EPI, bool HS = false>
; __device__ __forceinline__ void gemm_phase(const Params& p, const GemmCfg& g, char* shm, const int wave_s) {
;     ...
;             for (int bj = 0; bj < 2; ++bj) xv[j][bj] = *(const float2*)(xl + (m * 16 + j) * XROW + bj * 512);
; #pragma unroll
;           for (int j = 0; j < 4; ++j) {
;             float ss = 0.f;
; #pragma unroll
;             for (int bj = 0; bj < 2; ++bj) {
;               float2 xn;
;               xn.x = xv[j][bj].x + gt[bj][0] * acc[ai][bj][m][0][j];
;               xn.y = xv[j][bj].y + gt[bj][1] * acc[ai][bj][m][1][j];
;               const unsigned o = tb + (unsigned)((ai * 128 + m * 16 + j) * 1024 + bj * 128);
;               *(float2*)(xout_t + o) = xn;
;               if (g.has_next) *(unsigned*)(xg_t + o) = pack2(xn.x * gn[bj][0], xn.y * gn[bj][1]);
;               ss += xn.x * xn.x + xn.y * xn.y;
;             }
;             if (g.has_next) {
;               ss = dpp_row_sum16(ss);
;               if (fr == 0) rss_t[(wr * 64 + fq * 4 + ai * 128 + m * 16 + j) * 16] = ss;
;             }
.LBB0_539:
	v_add_u32_e32 v8, 0x2cc00, v0
	v_mov_b32_e32 v4, v9
	v_mov_b32_e32 v9, v1
	s_waitcnt lgkmcnt(0)
	v_pk_fma_f32 v[4:5], v[4:5], v[184:185], v[14:15]
	v_lshl_add_u64 v[10:11], v[8:9], 2, s[2:3]
	s_mov_b64 s[10:11], -1
	s_and_b64 vcc, exec, s[6:7]
	v_add_u32_e32 v0, 0x2cc80, v0
	global_store_dwordx2 v[10:11], v[4:5], off
	s_cbranch_vccnz .LBB0_543
	v_pk_mul_f32 v[10:11], v[182:183], v[4:5]
	v_lshl_add_u64 v[8:9], v[8:9], 1, s[8:9]
	s_nop 0
	v_and_b32_sdwa v2, v11, v178 dst_sel:DWORD dst_unused:UNUSED_PAD src0_sel:WORD_1 src1_sel:DWORD
	v_cvt_pk_bf16_f32 v6, v10, v10
	v_add3_u32 v2, v11, v2, s81
	v_lshrrev_b32_e32 v6, 16, v6
	v_and_or_b32 v2, v2, s28, v6
	v_mov_b32_e32 v6, v3
	global_store_dword v[8:9], v2, off
	v_pk_fma_f32 v[8:9], v[6:7], v[180:181], v[16:17]
	v_lshl_add_u64 v[10:11], v[0:1], 2, s[2:3]
	global_store_dwordx2 v[10:11], v[8:9], off
	v_pk_mul_f32 v[10:11], v[186:187], v[8:9]
	v_pk_mul_f32 v[4:5], v[4:5], v[4:5]
	s_nop 0
	v_and_b32_sdwa v2, v11, v178 dst_sel:DWORD dst_unused:UNUSED_PAD src0_sel:WORD_1 src1_sel:DWORD
	v_cvt_pk_bf16_f32 v6, v10, v10
	v_add3_u32 v2, v11, v2, s81
	v_lshrrev_b32_e32 v6, 16, v6
	v_and_or_b32 v2, v2, s28, v6
	v_lshl_add_u64 v[10:11], v[0:1], 1, s[8:9]
	v_pk_mul_f32 v[8:9], v[8:9], v[8:9]
	global_store_dword v[10:11], v2, off
	v_add_f32_e32 v2, v8, v9
	v_add_f32_e32 v4, v4, v5
	v_add_f32_e32 v2, v4, v2
	s_nop 1
	v_add_f32_dpp v2, v2, v2 quad_perm:[1,0,3,2] row_mask:0xf bank_mask:0xf bound_ctrl:1
	s_nop 1
	v_add_f32_dpp v2, v2, v2 quad_perm:[2,3,0,1] row_mask:0xf bank_mask:0xf bound_ctrl:1
	s_nop 1
	v_add_f32_dpp v2, v2, v2 row_half_mirror row_mask:0xf bank_mask:0xf bound_ctrl:1
	s_nop 1
	v_mov_b32_dpp v4, v2 row_mirror row_mask:0xf bank_mask:0xf bound_ctrl:1
	s_and_saveexec_b64 s[6:7], s[4:5]
	s_cbranch_execz .LBB0_542
	v_add_f32_e32 v2, v2, v4
	v_mov_b32_e32 v4, 0xb30
	v_lshl_add_u32 v4, v194, 4, v4
	v_ashrrev_i32_e32 v5, 31, v4
	v_lshl_add_u64 v[4:5], v[4:5], 2, v[150:151]
	global_store_dword v[4:5], v2, off

; __device__ __forceinline__ unsigned pack2(float a, float b) { return (unsigned)f2bf(a) | ((unsigned)f2bf(b) << 16); }
; __device__ __forceinline__ void ret_core_phase(const Params& p, const PD& d, char* shm, const int wave_s) {
;     ...
;           for (int r = 0; r < 4; ++r) S[df][vf][r] = st[((df * 4 + vf) * 4 + r) * 512 + tid];
;     }
;     __syncthreads();
; #pragma unroll
;     for (int df = 0; df < 4; ++df)
; #pragma unroll
;       for (int vf = 0; vf < 4; ++vf) {
;         uint2 pk; pk.x = pack2(S[df][vf][0], S[df][vf][1]); pk.y = pack2(S[df][vf][2], S[df][vf][3]);
;         *(uint2*)(R2 + (64 * wj + 16 * vf + fr) * 528 + (64 * wi + 16 * df + 4 * fq) * 2) = pk;
.LBB0_561:
	v_bfe_u32 v164, v68, 6, 1
	v_and_b32_e32 v70, 15, v68
	v_lshlrev_b32_e32 v241, 6, v164
	v_lshrrev_b32_e32 v3, 1, v68
	v_or_b32_e32 v0, v241, v70
	v_and_b32_e32 v2, 0xffffff80, v68
	v_and_b32_e32 v71, 24, v3
	s_add_i32 s73, 0, 0x11000
	s_waitcnt vmcnt(62)
	s_nop 0
	v_add_u32_e32 v2, s73, v2
	v_mul_u32_u24_e32 v0, 0x210, v0
	v_cvt_pk_bf16_f32 v72, v4, v4
	s_waitcnt vmcnt(60)
	s_nop 0
	s_nop 0
	v_add3_u32 v0, v2, v71, v0
	s_nop 0
	v_cvt_pk_bf16_f32 v3, v7, v7
	v_cvt_pk_bf16_f32 v73, v5, v5
	v_cvt_pk_bf16_f32 v2, v6, v6
	v_and_b32_e32 v3, 0xffff0000, v3
	v_and_b32_e32 v73, 0xffff0000, v73
	v_or_b32_sdwa v3, v3, v2 dst_sel:DWORD dst_unused:UNUSED_PAD src0_sel:DWORD src1_sel:WORD_1
	v_or_b32_sdwa v2, v73, v72 dst_sel:DWORD dst_unused:UNUSED_PAD src0_sel:DWORD src1_sel:WORD_1
	s_waitcnt vmcnt(59)
	s_nop 0
	v_cvt_pk_bf16_f32 v74, v8, v8
	s_waitcnt vmcnt(56)
	s_nop 0
	s_nop 0
	s_nop 0
	v_cvt_pk_bf16_f32 v73, v11, v11
	v_cvt_pk_bf16_f32 v75, v9, v9
	v_cvt_pk_bf16_f32 v72, v10, v10
	v_and_b32_e32 v73, 0xffff0000, v73
	v_and_b32_e32 v75, 0xffff0000, v75
	v_or_b32_sdwa v73, v73, v72 dst_sel:DWORD dst_unused:UNUSED_PAD src0_sel:DWORD src1_sel:WORD_1
	v_or_b32_sdwa v72, v75, v74 dst_sel:DWORD dst_unused:UNUSED_PAD src0_sel:DWORD src1_sel:WORD_1
	s_waitcnt vmcnt(55)
	s_nop 0
	v_cvt_pk_bf16_f32 v76, v12, v12
	s_waitcnt vmcnt(52)
	s_nop 0
	s_nop 0
	s_nop 0
	v_cvt_pk_bf16_f32 v75, v15, v15
	v_cvt_pk_bf16_f32 v83, v13, v13
	v_cvt_pk_bf16_f32 v74, v14, v14
	v_and_b32_e32 v75, 0xffff0000, v75
	v_and_b32_e32 v83, 0xffff0000, v83
	s_waitcnt vmcnt(48)
	s_nop 0
	s_nop 0
	v_or_b32_sdwa v75, v75, v74 dst_sel:DWORD dst_unused:UNUSED_PAD src0_sel:DWORD src1_sel:WORD_1
	v_or_b32_sdwa v74, v83, v76 dst_sel:DWORD dst_unused:UNUSED_PAD src0_sel:DWORD src1_sel:WORD_1
	s_nop 0
	s_nop 0
	v_cvt_pk_bf16_f32 v84, v19, v19
	v_cvt_pk_bf16_f32 v85, v17, v17
	v_cvt_pk_bf16_f32 v83, v16, v16
	v_cvt_pk_bf16_f32 v76, v18, v18
	v_and_b32_e32 v84, 0xffff0000, v84
	v_and_b32_e32 v86, 0xffff0000, v85
	v_or_b32_sdwa v85, v84, v76 dst_sel:DWORD dst_unused:UNUSED_PAD src0_sel:DWORD src1_sel:WORD_1
	v_or_b32_sdwa v84, v86, v83 dst_sel:DWORD dst_unused:UNUSED_PAD src0_sel:DWORD src1_sel:WORD_1
	s_waitcnt vmcnt(44)
	s_nop 0
	s_nop 0
	s_nop 0
	s_nop 0
	v_cvt_pk_bf16_f32 v86, v23, v23
	v_cvt_pk_bf16_f32 v87, v21, v21
	v_cvt_pk_bf16_f32 v83, v20, v20
	v_cvt_pk_bf16_f32 v76, v22, v22
	v_and_b32_e32 v86, 0xffff0000, v86
	v_and_b32_e32 v88, 0xffff0000, v87
	v_or_b32_sdwa v87, v86, v76 dst_sel:DWORD dst_unused:UNUSED_PAD src0_sel:DWORD src1_sel:WORD_1
	v_or_b32_sdwa v86, v88, v83 dst_sel:DWORD dst_unused:UNUSED_PAD src0_sel:DWORD src1_sel:WORD_1
	s_barrier
	ds_write2_b64 v0, v[2:3], v[86:87] offset1:4
	s_waitcnt vmcnt(43)
	s_nop 0
	v_cvt_pk_bf16_f32 v76, v24, v24
	s_waitcnt vmcnt(40)
	s_nop 0
	s_nop 0
	s_nop 0
	v_cvt_pk_bf16_f32 v3, v27, v27
	v_cvt_pk_bf16_f32 v83, v25, v25
	v_cvt_pk_bf16_f32 v2, v26, v26
	v_and_b32_e32 v3, 0xffff0000, v3
	v_and_b32_e32 v83, 0xffff0000, v83
	v_or_b32_sdwa v3, v3, v2 dst_sel:DWORD dst_unused:UNUSED_PAD src0_sel:DWORD src1_sel:WORD_1
	v_or_b32_sdwa v2, v83, v76 dst_sel:DWORD dst_unused:UNUSED_PAD src0_sel:DWORD src1_sel:WORD_1
	v_add_u32_e32 v76, 0x2000, v0
	ds_write2_b64 v76, v[72:73], v[2:3] offset0:32 offset1:36
	s_waitcnt vmcnt(39)
	s_nop 0
	v_cvt_pk_bf16_f32 v72, v28, v28
	s_waitcnt vmcnt(36)
	s_nop 0
	s_waitcnt lgkmcnt(2)
	s_nop 0
	s_nop 0
	v_cvt_pk_bf16_f32 v3, v31, v31
	v_cvt_pk_bf16_f32 v73, v29, v29
	v_cvt_pk_bf16_f32 v2, v30, v30
	v_and_b32_e32 v3, 0xffff0000, v3
	v_and_b32_e32 v73, 0xffff0000, v73
	v_or_b32_sdwa v3, v3, v2 dst_sel:DWORD dst_unused:UNUSED_PAD src0_sel:DWORD src1_sel:WORD_1
	v_or_b32_sdwa v2, v73, v72 dst_sel:DWORD dst_unused:UNUSED_PAD src0_sel:DWORD src1_sel:WORD_1
	v_add_u32_e32 v83, 0x4000, v0
	ds_write2_b64 v83, v[74:75], v[2:3] offset0:64 offset1:68
	s_waitcnt vmcnt(35)
	s_nop 0
	v_cvt_pk_bf16_f32 v72, v32, v32
	s_waitcnt vmcnt(32)
	s_nop 0
	s_nop 0
	s_nop 0
	v_cvt_pk_bf16_f32 v3, v35, v35
	v_cvt_pk_bf16_f32 v73, v33, v33
	v_cvt_pk_bf16_f32 v2, v34, v34
	v_and_b32_e32 v3, 0xffff0000, v3
	v_and_b32_e32 v73, 0xffff0000, v73
	v_or_b32_sdwa v3, v3, v2 dst_sel:DWORD dst_unused:UNUSED_PAD src0_sel:DWORD src1_sel:WORD_1
	v_or_b32_sdwa v2, v73, v72 dst_sel:DWORD dst_unused:UNUSED_PAD src0_sel:DWORD src1_sel:WORD_1
	v_add_u32_e32 v88, 0x6000, v0
	ds_write2_b64 v88, v[84:85], v[2:3] offset0:96 offset1:100
	s_waitcnt vmcnt(31)
	s_nop 0
	v_cvt_pk_bf16_f32 v72, v36, v36
	s_waitcnt vmcnt(28)
	s_nop 0
	s_nop 0
	s_nop 0
	v_cvt_pk_bf16_f32 v3, v39, v39
	v_cvt_pk_bf16_f32 v73, v37, v37
	v_cvt_pk_bf16_f32 v2, v38, v38
	v_and_b32_e32 v3, 0xffff0000, v3
	v_and_b32_e32 v73, 0xffff0000, v73
	v_or_b32_sdwa v3, v3, v2 dst_sel:DWORD dst_unused:UNUSED_PAD src0_sel:DWORD src1_sel:WORD_1
	v_or_b32_sdwa v2, v73, v72 dst_sel:DWORD dst_unused:UNUSED_PAD src0_sel:DWORD src1_sel:WORD_1
	s_waitcnt vmcnt(27)
	s_nop 0
	v_cvt_pk_bf16_f32 v74, v40, v40
	s_waitcnt vmcnt(24)
	s_nop 0
	s_nop 0
	s_nop 0
	v_cvt_pk_bf16_f32 v73, v43, v43
	v_cvt_pk_bf16_f32 v75, v41, v41
	v_cvt_pk_bf16_f32 v72, v42, v42
	v_and_b32_e32 v73, 0xffff0000, v73
	v_and_b32_e32 v75, 0xffff0000, v75
	v_or_b32_sdwa v73, v73, v72 dst_sel:DWORD dst_unused:UNUSED_PAD src0_sel:DWORD src1_sel:WORD_1
	v_or_b32_sdwa v72, v75, v74 dst_sel:DWORD dst_unused:UNUSED_PAD src0_sel:DWORD src1_sel:WORD_1
	s_waitcnt vmcnt(23)
	s_nop 0
	v_cvt_pk_bf16_f32 v84, v44, v44
	s_waitcnt vmcnt(20)
	s_nop 0
	s_nop 0
	s_nop 0
	v_cvt_pk_bf16_f32 v75, v47, v47
	v_cvt_pk_bf16_f32 v85, v45, v45
	v_cvt_pk_bf16_f32 v74, v46, v46
	v_and_b32_e32 v75, 0xffff0000, v75
	v_and_b32_e32 v85, 0xffff0000, v85
	v_or_b32_sdwa v75, v75, v74 dst_sel:DWORD dst_unused:UNUSED_PAD src0_sel:DWORD src1_sel:WORD_1
	v_or_b32_sdwa v74, v85, v84 dst_sel:DWORD dst_unused:UNUSED_PAD src0_sel:DWORD src1_sel:WORD_1
	s_waitcnt vmcnt(19)
; __device__ __forceinline__ unsigned pack2(float a, float b) { return (unsigned)f2bf(a) | ((unsigned)f2bf(b) << 16); }
; __device__ __forceinline__ void ret_core_phase(const Params& p, const PD& d, char* shm, const int wave_s) {
;     ...
;     for (int df = 0; df < 4; ++df)
; #pragma unroll
;       for (int vf = 0; vf < 4; ++vf) {
;         uint2 pk; pk.x = pack2(S[df][vf][0], S[df][vf][1]); pk.y = pack2(S[df][vf][2], S[df][vf][3]);
;         *(uint2*)(R2 + (64 * wj + 16 * vf + fr) * 528 + (64 * wi + 16 * df + 4 * fq) * 2) = pk;
;     ...
;     {
;       const size_t lt0 = (size_t)b * 2048;
; #pragma unroll
;       for (int i = 0; i < 8; ++i) {
;         int c = i * 512 + tid, row = c >> 5, cc = c & 31;
;         kpre[i] = *(const bf16x8*)(Kb + (lt0 + row) * 1024 + hh * 256 + cc * 8);
;       }
;       const u16* Qw = Qb + (lt0 + 32 * wi + fr) * 1024 + hh * 256 + fq * 8;
; #pragma unroll
;       for (int f = 0; f < 2; ++f)
; #pragma unroll
;         for (int ks = 0; ks < 8; ++ks) Qf[f][ks] = *(const bf16x8*)(Qw + f * 16 * 1024 + ks * 32);
	s_nop 0
	v_cvt_pk_bf16_f32 v86, v48, v48
	s_waitcnt vmcnt(16)
	s_nop 0
	s_nop 0
	s_nop 0
	v_cvt_pk_bf16_f32 v85, v51, v51
	v_cvt_pk_bf16_f32 v87, v49, v49
	v_cvt_pk_bf16_f32 v84, v50, v50
	v_and_b32_e32 v85, 0xffff0000, v85
	v_and_b32_e32 v87, 0xffff0000, v87
	v_or_b32_sdwa v85, v85, v84 dst_sel:DWORD dst_unused:UNUSED_PAD src0_sel:DWORD src1_sel:WORD_1
	v_or_b32_sdwa v84, v87, v86 dst_sel:DWORD dst_unused:UNUSED_PAD src0_sel:DWORD src1_sel:WORD_1
	s_waitcnt vmcnt(15)
	s_nop 0
	v_cvt_pk_bf16_f32 v89, v52, v52
	s_waitcnt vmcnt(12)
	s_nop 0
	s_nop 0
	s_nop 0
	v_cvt_pk_bf16_f32 v87, v55, v55
	v_cvt_pk_bf16_f32 v90, v53, v53
	v_cvt_pk_bf16_f32 v86, v54, v54
	v_and_b32_e32 v87, 0xffff0000, v87
	v_and_b32_e32 v90, 0xffff0000, v90
	v_or_b32_sdwa v87, v87, v86 dst_sel:DWORD dst_unused:UNUSED_PAD src0_sel:DWORD src1_sel:WORD_1
	v_or_b32_sdwa v86, v90, v89 dst_sel:DWORD dst_unused:UNUSED_PAD src0_sel:DWORD src1_sel:WORD_1
	ds_write2_b64 v0, v[2:3], v[86:87] offset0:8 offset1:12
	s_waitcnt vmcnt(8)
	s_nop 0
	s_nop 0
	s_nop 0
	s_nop 0
	v_cvt_pk_bf16_f32 v3, v59, v59
	v_cvt_pk_bf16_f32 v86, v57, v57
	v_cvt_pk_bf16_f32 v2, v56, v56
	v_cvt_pk_bf16_f32 v0, v58, v58
	v_and_b32_e32 v3, 0xffff0000, v3
	v_and_b32_e32 v86, 0xffff0000, v86
	v_or_b32_sdwa v3, v3, v0 dst_sel:DWORD dst_unused:UNUSED_PAD src0_sel:DWORD src1_sel:WORD_1
	v_or_b32_sdwa v2, v86, v2 dst_sel:DWORD dst_unused:UNUSED_PAD src0_sel:DWORD src1_sel:WORD_1
	s_lshl_b32 s2, s72, 4
	ds_write2_b64 v76, v[72:73], v[2:3] offset0:40 offset1:44
	s_waitcnt vmcnt(4)
	s_nop 0
	s_nop 0
	s_and_b32 s7, s2, 0x380
	s_lshl_b32 s2, s90, 3
	s_nop 0
	s_nop 0
	v_cvt_pk_bf16_f32 v3, v63, v63
	v_cvt_pk_bf16_f32 v72, v61, v61
	s_and_b32 s2, s2, 56
	v_cvt_pk_bf16_f32 v2, v60, v60
	v_cvt_pk_bf16_f32 v0, v62, v62
	v_and_b32_e32 v3, 0xffff0000, v3
	v_and_b32_e32 v72, 0xffff0000, v72
	s_add_i32 s2, s2, s4
	v_or_b32_sdwa v3, v3, v0 dst_sel:DWORD dst_unused:UNUSED_PAD src0_sel:DWORD src1_sel:WORD_1
	v_or_b32_sdwa v2, v72, v2 dst_sel:DWORD dst_unused:UNUSED_PAD src0_sel:DWORD src1_sel:WORD_1
	s_waitcnt vmcnt(2)
	s_nop 0
	s_ashr_i32 s2, s2, 2
	ds_write2_b64 v83, v[74:75], v[2:3] offset0:72 offset1:76
	s_nop 0
	s_waitcnt vmcnt(0)
	s_nop 0
	v_cvt_pk_bf16_f32 v72, v65, v65
	s_nop 0
	v_cvt_pk_bf16_f32 v2, v64, v64
	v_cvt_pk_bf16_f32 v3, v67, v67
	v_and_b32_e32 v72, 0xffff0000, v72
	s_ashr_i32 s3, s2, 31
	v_readlane_b32 s12, v253, 53
	s_bfe_u32 s8, s90, 0x20003
	v_cvt_pk_bf16_f32 v0, v66, v66
	v_and_b32_e32 v3, 0xffff0000, v3
	v_or_b32_sdwa v2, v72, v2 dst_sel:DWORD dst_unused:UNUSED_PAD src0_sel:DWORD src1_sel:WORD_1
	s_lshl_b64 s[92:93], s[2:3], 11
	s_lshl_b32 s12, s5, 9
	v_readlane_b32 s2, v252, 59
	v_ashrrev_i32_e32 v72, 5, v68
	v_or_b32_sdwa v3, v3, v0 dst_sel:DWORD dst_unused:UNUSED_PAD src0_sel:DWORD src1_sel:WORD_1
	s_add_u32 s88, s2, s12
	v_readlane_b32 s2, v252, 60
	v_lshlrev_b32_e32 v0, 4, v68
	v_ashrrev_i32_e32 v73, 31, v72
	s_addc_u32 s89, s2, 0
	v_and_b32_e32 v0, 0x1f0, v0
	v_lshl_add_u64 v[72:73], s[92:93], 0, v[72:73]
	ds_write2_b64 v88, v[84:85], v[2:3] offset0:104 offset1:108
	v_lshl_add_u64 v[2:3], s[88:89], 0, v[0:1]
	v_lshlrev_b64 v[72:73], 11, v[72:73]
	v_lshl_add_u64 v[72:73], v[2:3], 0, v[72:73]
	global_load_dwordx4 v[100:103], v[72:73], off
	v_ashrrev_i32_e32 v72, 5, v82
	v_ashrrev_i32_e32 v73, 31, v72
	v_lshl_add_u64 v[72:73], s[92:93], 0, v[72:73]
	v_lshlrev_b64 v[72:73], 11, v[72:73]
	v_lshl_add_u64 v[72:73], v[2:3], 0, v[72:73]
	global_load_dwordx4 v[104:107], v[72:73], off
	v_ashrrev_i32_e32 v72, 5, v81
	v_ashrrev_i32_e32 v73, 31, v72
	v_lshl_add_u64 v[72:73], s[92:93], 0, v[72:73]
	v_lshlrev_b64 v[72:73], 11, v[72:73]
	v_lshl_add_u64 v[72:73], v[2:3], 0, v[72:73]
	global_load_dwordx4 v[108:111], v[72:73], off
	v_ashrrev_i32_e32 v72, 5, v80
	v_ashrrev_i32_e32 v73, 31, v72
	v_lshl_add_u64 v[72:73], s[92:93], 0, v[72:73]
	v_lshlrev_b64 v[72:73], 11, v[72:73]
	v_lshl_add_u64 v[72:73], v[2:3], 0, v[72:73]
	global_load_dwordx4 v[116:119], v[72:73], off
	v_ashrrev_i32_e32 v72, 5, v79
	v_ashrrev_i32_e32 v73, 31, v72
	v_lshl_add_u64 v[72:73], s[92:93], 0, v[72:73]
	v_lshlrev_b64 v[72:73], 11, v[72:73]
	v_lshl_add_u64 v[72:73], v[2:3], 0, v[72:73]
	global_load_dwordx4 v[124:127], v[72:73], off
	v_ashrrev_i32_e32 v72, 5, v78
	v_ashrrev_i32_e32 v73, 31, v72
	v_lshl_add_u64 v[72:73], s[92:93], 0, v[72:73]
	v_lshlrev_b64 v[72:73], 11, v[72:73]
	v_lshl_add_u64 v[72:73], v[2:3], 0, v[72:73]
	v_ashrrev_i32_e32 v165, 7, v68
	global_load_dwordx4 v[128:131], v[72:73], off
	v_ashrrev_i32_e32 v72, 5, v77
	v_ashrrev_i32_e32 v68, 5, v69
	v_ashrrev_i32_e32 v73, 31, v72
	v_ashrrev_i32_e32 v69, 31, v68
	v_lshl_add_u64 v[72:73], s[92:93], 0, v[72:73]
	v_lshl_add_u64 v[68:69], s[92:93], 0, v[68:69]
	v_lshlrev_b64 v[72:73], 11, v[72:73]
	v_lshlrev_b64 v[68:69], 11, v[68:69]
	v_lshl_add_u64 v[72:73], v[2:3], 0, v[72:73]
	v_lshl_add_u64 v[2:3], v[2:3], 0, v[68:69]
	global_load_dwordx4 v[132:135], v[72:73], off
	global_load_dwordx4 v[136:139], v[2:3], off
	v_lshlrev_b32_e32 v2, 5, v165
	v_ashrrev_i32_e32 v3, 31, v2
	v_lshl_add_u64 v[176:177], s[92:93], 0, v[2:3]
	v_or_b32_e32 v68, v176, v70
	v_mov_b32_e32 v69, v177
	v_readlane_b32 s16, v254, 47
	v_lshlrev_b64 v[68:69], 11, v[68:69]
	v_readlane_b32 s18, v254, 49
	v_readlane_b32 s19, v254, 50
	v_readlane_b32 s13, v253, 54
	v_lshlrev_b32_e32 v0, 1, v71
	v_lshl_add_u64 v[68:69], s[18:19], 0, v[68:69]
	v_lshl_add_u64 v[68:69], v[68:69], 0, s[12:13]
	v_lshl_add_u64 v[72:73], v[68:69], 0, v[0:1]
	global_load_dwordx4 v[156:159], v[72:73], off
	global_load_dwordx4 v[144:147], v[72:73], off offset:64
	global_load_dwordx4 v[140:143], v[72:73], off offset:128
	global_load_dwordx4 v[96:99], v[72:73], off offset:192
; __device__ __forceinline__ unsigned pack2(float a, float b) { return (unsigned)f2bf(a) | ((unsigned)f2bf(b) << 16); }
; __device__ __forceinline__ void ret_core_phase(const Params& p, const PD& d, char* shm, const int wave_s) {
;     ...
;       for (int i = 0; i < 8; ++i) {
;         int c = i * 512 + tid, row = c >> 5, cc = c & 31;
;         kpre[i] = *(const bf16x8*)(Kb + (lt0 + row) * 1024 + hh * 256 + cc * 8);
;       }
;       const u16* Qw = Qb + (lt0 + 32 * wi + fr) * 1024 + hh * 256 + fq * 8;
; #pragma unroll
;       for (int f = 0; f < 2; ++f)
; #pragma unroll
;         for (int ks = 0; ks < 8; ++ks) Qf[f][ks] = *(const bf16x8*)(Qw + f * 16 * 1024 + ks * 32);
;     ...
;         for (int f = 0; f < 2; ++f) {
;           float ss = 0.f;
; #pragma unroll
;           for (int vf = 0; vf < 4; ++vf)
; #pragma unroll
;             for (int r = 0; r < 4; ++r) ss += OT[vf][f][r] * OT[vf][f][r];
;           ss += shfl_xor_l(ss, 16, fqv * 16 + frv); ss += shfl_xor_l(ss, 32, fqv * 16 + frv);
;           if (fqv == 0) sst[(16 * f) * 32] = ss;
; #pragma unroll
;           for (int vf = 0; vf < 4; ++vf) {
;             uint2 gq = gpre[vf][f];
;             float g0 = __uint_as_float(gq.x << 16), g1 = __uint_as_float(gq.x & 0xffff0000u);
;             float g2 = __uint_as_float(gq.y << 16), g3 = __uint_as_float(gq.y & 0xffff0000u);
;             uint2 o;
;             o.x = pack2(silu_f(g0) * OT[vf][f][0], silu_f(g1) * OT[vf][f][1]);
;             o.y = pack2(silu_f(g2) * OT[vf][f][2], silu_f(g3) * OT[vf][f][3]);
;             *(uint2*)(got + f * 16 * 2048 + vf * 16) = o;
	global_load_dwordx4 v[92:95], v[72:73], off offset:256
	global_load_dwordx4 v[80:83], v[72:73], off offset:320
	global_load_dwordx4 v[76:79], v[72:73], off offset:384
	global_load_dwordx4 v[68:71], v[72:73], off offset:448
	v_add_co_u32_e32 v72, vcc, s20, v72
	v_writelane_b32 v253, s12, 53
	s_nop 0
	v_addc_co_u32_e32 v73, vcc, 0, v73, vcc
	global_load_dwordx4 v[160:163], v[72:73], off
	global_load_dwordx4 v[152:155], v[72:73], off offset:64
	global_load_dwordx4 v[148:151], v[72:73], off offset:128
	global_load_dwordx4 v[120:123], v[72:73], off offset:192
	global_load_dwordx4 v[112:115], v[72:73], off offset:256
	global_load_dwordx4 v[88:91], v[72:73], off offset:320
	global_load_dwordx4 v[84:87], v[72:73], off offset:384
	s_nop 0
	global_load_dwordx4 v[72:75], v[72:73], off offset:448
	s_add_u32 s84, s18, s12
	s_addc_u32 s85, s19, 0
	s_lshl_b32 s9, s8, 7
	s_lshl_b32 s2, s5, 10
	v_readlane_b32 s3, v254, 9
	s_add_u32 s2, s3, s2
	v_readlane_b32 s3, v254, 10
	s_addc_u32 s3, s3, 0
	s_lshl_b32 s11, s8, 8
	s_add_u32 s2, s2, s11
	v_readlane_b32 s17, v254, 48
	v_lshlrev_b32_e32 v0, 7, v164
	s_addc_u32 s3, s3, 0
	v_writelane_b32 v253, s13, 54
	v_lshl_add_u64 v[180:181], s[2:3], 0, v[0:1]
	s_lshl_b32 s2, s5, 5
	v_readlane_b32 s12, v252, 0
	v_readlane_b32 s13, v252, 1
	s_add_u32 s2, s12, s2
	s_addc_u32 s3, s13, 0
	s_lshl_b32 s5, s8, 3
	s_add_u32 s2, s2, s5
	v_add_u32_e32 v242, 0, v0
	s_addc_u32 s3, s3, 0
	v_lshlrev_b32_e32 v0, 2, v164
	v_lshl_add_u64 v[184:185], s[2:3], 0, v[0:1]
	s_lshl_b32 s2, s4, 4
	s_add_i32 s2, s7, s2
	v_lshlrev_b32_e32 v182, 6, v165
	s_ashr_i32 s3, s2, 31
	v_ashrrev_i32_e32 v183, 31, v182
	s_lshl_b64 s[4:5], s[2:3], 8
	s_lshl_b64 s[2:3], s[2:3], 9
	s_mov_b32 s11, s10
	s_mov_b32 s76, s10
	s_mov_b32 s77, s10
	v_lshl_add_u64 v[186:187], s[4:5], 0, v[182:183]
	s_or_b32 s2, s2, s9
	s_mov_b64 s[8:9], 0
	v_mov_b32_e32 v183, s6
	s_mov_b64 s[68:69], 0
	v_readlane_b32 s14, v252, 2
	v_readlane_b32 s15, v252, 3
	v_readlane_b32 s16, v252, 4
	v_readlane_b32 s17, v252, 5
	v_readlane_b32 s18, v252, 6
	v_readlane_b32 s19, v252, 7
	s_branch .LBB0_563
.LBB0_562:
	s_or_b64 exec, exec, s[4:5]
	s_waitcnt vmcnt(15)
	v_lshlrev_b32_e32 v126, 16, v146
	v_mul_f32_e32 v125, 0xbfb8aa3b, v126
	v_exp_f32_e32 v125, v125
	v_and_b32_e32 v128, 0xffff0000, v146
	v_lshlrev_b32_e32 v127, 16, v147
	v_and_b32_e32 v129, 0xffff0000, v147
	v_add_f32_e32 v125, 1.0, v125
	v_rcp_f32_e32 v130, v125
	v_mul_f32_e32 v125, 0xbfb8aa3b, v128
	v_exp_f32_e32 v125, v125
	s_mov_b64 s[4:5], 0x10000
	v_lshl_add_u64 v[122:123], v[148:149], 0, s[4:5]
	s_mov_b64 s[4:5], 0x10020
	v_add_f32_e32 v125, 1.0, v125
	v_rcp_f32_e32 v146, v125
	v_mul_f32_e32 v125, 0xbfb8aa3b, v127
	v_exp_f32_e32 v125, v125
	v_lshl_add_u64 v[120:121], v[148:149], 0, s[4:5]
	s_mov_b64 s[4:5], 0x10040
	v_lshl_add_u64 v[118:119], v[148:149], 0, s[4:5]
	v_add_f32_e32 v125, 1.0, v125
	v_rcp_f32_e32 v131, v125
	s_add_u32 s8, s8, 0x80
	s_addc_u32 s9, s9, 0
	s_mov_b64 s[4:5], 0x10060
	v_pk_mul_f32 v[126:127], v[130:131], v[126:127]
	v_mov_b32_e32 v130, v112
	v_mul_f32_e32 v112, 0xbfb8aa3b, v129
	v_exp_f32_e32 v112, v112
	v_mov_b32_e32 v131, v114
	v_pk_mul_f32 v[126:127], v[126:127], v[130:131]
	v_mov_b32_e32 v114, v113
	v_add_f32_e32 v112, 1.0, v112
	v_rcp_f32_e32 v147, v112
	s_cmpk_lg_i32 s68, 0x1e00
	s_waitcnt lgkmcnt(0)
	v_lshl_add_u64 v[116:117], v[148:149], 0, s[4:5]
	s_cselect_b32 s4, s8, 0x780
	v_pk_mul_f32 v[128:129], v[146:147], v[128:129]
	v_lshlrev_b32_e32 v124, 3, v191
	v_pk_mul_f32 v[112:113], v[128:129], v[114:115]
	s_nop 0
	v_cvt_pk_bf16_f32 v115, v126, v126
	s_nop 0
	s_nop 0
	s_nop 0
	v_cvt_pk_bf16_f32 v113, v113, v113
	v_cvt_pk_bf16_f32 v112, v112, v112
	v_cvt_pk_bf16_f32 v114, v127, v127
	v_and_b32_e32 v113, 0xffff0000, v113
	v_and_b32_e32 v112, 0xffff0000, v112
	v_or_b32_sdwa v113, v113, v114 dst_sel:DWORD dst_unused:UNUSED_PAD src0_sel:DWORD src1_sel:WORD_1
	v_or_b32_sdwa v112, v112, v115 dst_sel:DWORD dst_unused:UNUSED_PAD src0_sel:DWORD src1_sel:WORD_1
	s_waitcnt vmcnt(14)
	v_and_b32_e32 v114, 0xffff0000, v144
	global_store_dwordx2 v[122:123], v[112:113], off
	v_mul_f32_e32 v123, 0xbfb8aa3b, v114
	v_exp_f32_e32 v123, v123
	v_lshlrev_b32_e32 v113, 16, v145
	v_lshlrev_b32_e32 v112, 16, v144
	v_mul_f32_e32 v122, 0xbfb8aa3b, v112
	v_add_f32_e32 v123, 1.0, v123
	v_rcp_f32_e32 v126, v123
	v_mul_f32_e32 v123, 0xbfb8aa3b, v113
	v_exp_f32_e32 v122, v122
	v_exp_f32_e32 v123, v123
	v_and_b32_e32 v115, 0xffff0000, v145
	s_add_u32 s4, s92, s4
	v_add_f32_e32 v122, 1.0, v122
	v_add_f32_e32 v123, 1.0, v123
	v_rcp_f32_e32 v122, v122
	v_rcp_f32_e32 v123, v123
	v_mul_u32_u24_e32 v164, 0x210, v193
	v_lshlrev_b32_e32 v165, 2, v195
	v_mul_u32_u24_e32 v166, 0x110, v193
	v_pk_mul_f32 v[112:113], v[122:123], v[112:113]
	v_mov_b32_e32 v122, v108
	v_mul_f32_e32 v108, 0xbfb8aa3b, v115
	v_exp_f32_e32 v108, v108
	v_mov_b32_e32 v123, v110
	v_pk_mul_f32 v[112:113], v[112:113], v[122:123]
	v_mov_b32_e32 v110, v109
	v_add_f32_e32 v108, 1.0, v108
	v_rcp_f32_e32 v127, v108
	s_addc_u32 s5, s93, 0
	v_pk_mul_f32 v[114:115], v[126:127], v[114:115]
	s_nop 0
	v_pk_mul_f32 v[108:109], v[114:115], v[110:111]
	s_nop 0
	v_cvt_pk_bf16_f32 v111, v112, v112
	s_nop 0
	s_nop 0
	v_cvt_pk_bf16_f32 v109, v109, v109
	v_cvt_pk_bf16_f32 v110, v113, v113
	v_and_b32_e32 v109, 0xffff0000, v109
	s_nop 0
	v_or_b32_sdwa v109, v109, v110 dst_sel:DWORD dst_unused:UNUSED_PAD src0_sel:DWORD src1_sel:WORD_1
	s_waitcnt vmcnt(14)
; __device__ __forceinline__ unsigned pack2(float a, float b) { return (unsigned)f2bf(a) | ((unsigned)f2bf(b) << 16); }
; #define SCHED __builtin_amdgcn_sched_barrier(0)
; __device__ __forceinline__ void ret_core_phase(const Params& p, const PD& d, char* shm, const int wave_s) {
;     ...
;           for (int vf = 0; vf < 4; ++vf) {
;             uint2 gq = gpre[vf][f];
;             float g0 = __uint_as_float(gq.x << 16), g1 = __uint_as_float(gq.x & 0xffff0000u);
;             float g2 = __uint_as_float(gq.y << 16), g3 = __uint_as_float(gq.y & 0xffff0000u);
;             uint2 o;
;             o.x = pack2(silu_f(g0) * OT[vf][f][0], silu_f(g1) * OT[vf][f][1]);
;             o.y = pack2(silu_f(g2) * OT[vf][f][2], silu_f(g3) * OT[vf][f][3]);
;             *(uint2*)(got + f * 16 * 2048 + vf * 16) = o;
;           }
;         }
;       }
;       SCHED;
; #pragma unroll
;       for (int ks = 2; ks < 4; ++ks)
; #pragma unroll
;         for (int df = 0; df < 4; ++df) ktf[ks][df] = *(const bf16x8*)(KTw + df * 16 * 128 + ks * 32);
; #pragma unroll
;       for (int i = 0; i < 8; ++i) {
;         int c = i * 512 + tidv, row = c >> 5, cc = c & 31;
;         kpre[i] = *(const bf16x8*)(Kb + (lt1 + row) * 1024 + hh * 256 + cc * 8);
;       }
	v_and_b32_e32 v110, 0xffff0000, v142
	v_cvt_pk_bf16_f32 v108, v108, v108
	v_mul_f32_e32 v113, 0xbfb8aa3b, v110
	v_exp_f32_e32 v113, v113
	v_and_b32_e32 v108, 0xffff0000, v108
	v_or_b32_sdwa v108, v108, v111 dst_sel:DWORD dst_unused:UNUSED_PAD src0_sel:DWORD src1_sel:WORD_1
	global_store_dwordx2 v[120:121], v[108:109], off
	v_lshlrev_b32_e32 v109, 16, v143
	v_lshlrev_b32_e32 v108, 16, v142
	v_add_f32_e32 v113, 1.0, v113
	v_mul_f32_e32 v112, 0xbfb8aa3b, v108
	v_rcp_f32_e32 v114, v113
	v_mul_f32_e32 v113, 0xbfb8aa3b, v109
	v_exp_f32_e32 v112, v112
	v_exp_f32_e32 v113, v113
	v_and_b32_e32 v111, 0xffff0000, v143
	v_add_f32_e32 v112, 1.0, v112
	v_add_f32_e32 v113, 1.0, v113
	v_rcp_f32_e32 v112, v112
	v_rcp_f32_e32 v113, v113
	s_nop 0
	v_pk_mul_f32 v[108:109], v[112:113], v[108:109]
	v_mov_b32_e32 v112, v104
	v_mul_f32_e32 v104, 0xbfb8aa3b, v111
	v_exp_f32_e32 v104, v104
	v_mov_b32_e32 v113, v106
	v_pk_mul_f32 v[108:109], v[108:109], v[112:113]
	v_mov_b32_e32 v106, v105
	v_add_f32_e32 v104, 1.0, v104
	v_rcp_f32_e32 v115, v104
	s_nop 0
	v_pk_mul_f32 v[110:111], v[114:115], v[110:111]
	s_nop 0
	v_pk_mul_f32 v[104:105], v[110:111], v[106:107]
	s_nop 0
	v_cvt_pk_bf16_f32 v107, v108, v108
	s_nop 0
	s_nop 0
	v_cvt_pk_bf16_f32 v105, v105, v105
	v_cvt_pk_bf16_f32 v106, v109, v109
	v_and_b32_e32 v105, 0xffff0000, v105
	s_nop 0
	v_or_b32_sdwa v105, v105, v106 dst_sel:DWORD dst_unused:UNUSED_PAD src0_sel:DWORD src1_sel:WORD_1
	s_waitcnt vmcnt(14)
	v_and_b32_e32 v106, 0xffff0000, v140
	v_cvt_pk_bf16_f32 v104, v104, v104
	v_mul_f32_e32 v109, 0xbfb8aa3b, v106
	v_exp_f32_e32 v109, v109
	v_and_b32_e32 v104, 0xffff0000, v104
	v_or_b32_sdwa v104, v104, v107 dst_sel:DWORD dst_unused:UNUSED_PAD src0_sel:DWORD src1_sel:WORD_1
	global_store_dwordx2 v[118:119], v[104:105], off
	v_lshlrev_b32_e32 v105, 16, v141
	v_lshlrev_b32_e32 v104, 16, v140
	v_add_f32_e32 v109, 1.0, v109
	v_mul_f32_e32 v108, 0xbfb8aa3b, v104
	v_rcp_f32_e32 v110, v109
	v_mul_f32_e32 v109, 0xbfb8aa3b, v105
	v_exp_f32_e32 v108, v108
	v_exp_f32_e32 v109, v109
	v_and_b32_e32 v107, 0xffff0000, v141
	v_add_f32_e32 v108, 1.0, v108
	v_add_f32_e32 v109, 1.0, v109
	v_rcp_f32_e32 v108, v108
	v_rcp_f32_e32 v109, v109
	s_nop 0
	v_pk_mul_f32 v[104:105], v[108:109], v[104:105]
	v_mov_b32_e32 v108, v100
	v_mul_f32_e32 v100, 0xbfb8aa3b, v107
	v_exp_f32_e32 v100, v100
	v_mov_b32_e32 v109, v102
	v_pk_mul_f32 v[104:105], v[104:105], v[108:109]
	v_mov_b32_e32 v102, v101
	v_add_f32_e32 v100, 1.0, v100
	v_rcp_f32_e32 v111, v100
	s_nop 0
	v_pk_mul_f32 v[106:107], v[110:111], v[106:107]
	s_nop 0
	v_pk_mul_f32 v[100:101], v[106:107], v[102:103]
	s_nop 0
	s_nop 0
	v_cvt_pk_bf16_f32 v103, v104, v104
	v_cvt_pk_bf16_f32 v102, v105, v105
	s_nop 0
	s_nop 0
	v_cvt_pk_bf16_f32 v101, v101, v101
	v_cvt_pk_bf16_f32 v100, v100, v100
	v_and_b32_e32 v101, 0xffff0000, v101
	v_and_b32_e32 v100, 0xffff0000, v100
	v_or_b32_sdwa v101, v101, v102 dst_sel:DWORD dst_unused:UNUSED_PAD src0_sel:DWORD src1_sel:WORD_1
	v_or_b32_sdwa v100, v100, v103 dst_sel:DWORD dst_unused:UNUSED_PAD src0_sel:DWORD src1_sel:WORD_1
	global_store_dwordx2 v[116:117], v[100:101], off
	global_load_dwordx4 v[148:151], v[132:133], off offset:128
	global_load_dwordx4 v[144:147], v[132:133], off offset:192
	global_load_dwordx4 v[160:163], v[134:135], off offset:128
	global_load_dwordx4 v[140:143], v[134:135], off offset:192
	global_load_dwordx4 v[156:159], v[136:137], off offset:128
	global_load_dwordx4 v[120:123], v[136:137], off offset:192
	global_load_dwordx4 v[152:155], v[138:139], off offset:128
	global_load_dwordx4 v[112:115], v[138:139], off offset:192
	v_and_b32_e32 v100, 0xf8, v124
	v_lshlrev_b32_e32 v100, 1, v100
	v_mov_b32_e32 v101, v1
	v_ashrrev_i32_e32 v205, 31, v204
	v_ashrrev_i32_e32 v203, 31, v202
	v_ashrrev_i32_e32 v201, 31, v200
	v_ashrrev_i32_e32 v199, 31, v198
	v_ashrrev_i32_e32 v197, 31, v196
	v_ashrrev_i32_e32 v195, 31, v194
	v_ashrrev_i32_e32 v193, 31, v192
	v_ashrrev_i32_e32 v191, 31, v190
	v_lshl_add_u64 v[132:133], s[88:89], 0, v[100:101]
	v_lshl_add_u64 v[100:101], s[4:5], 0, v[204:205]
	v_lshl_add_u64 v[102:103], s[4:5], 0, v[202:203]
	v_lshl_add_u64 v[108:109], s[4:5], 0, v[200:201]
	v_lshl_add_u64 v[110:111], s[4:5], 0, v[198:199]
	v_lshl_add_u64 v[124:125], s[4:5], 0, v[196:197]
	v_lshl_add_u64 v[126:127], s[4:5], 0, v[194:195]
	v_lshl_add_u64 v[134:135], s[4:5], 0, v[192:193]
	v_lshl_add_u64 v[136:137], s[4:5], 0, v[190:191]
	v_lshlrev_b64 v[100:101], 11, v[100:101]
	v_lshlrev_b64 v[102:103], 11, v[102:103]
	v_lshlrev_b64 v[108:109], 11, v[108:109]
	v_lshlrev_b64 v[110:111], 11, v[110:111]
	v_lshlrev_b64 v[124:125], 11, v[124:125]
	v_lshlrev_b64 v[126:127], 11, v[126:127]
	v_lshlrev_b64 v[134:135], 11, v[134:135]
	v_lshlrev_b64 v[136:137], 11, v[136:137]
	v_lshl_add_u64 v[100:101], v[132:133], 0, v[100:101]
	v_lshl_add_u64 v[104:105], v[132:133], 0, v[102:103]
	v_lshl_add_u64 v[108:109], v[132:133], 0, v[108:109]
	v_lshl_add_u64 v[116:117], v[132:133], 0, v[110:111]
	v_lshl_add_u64 v[124:125], v[132:133], 0, v[124:125]
	v_lshl_add_u64 v[128:129], v[132:133], 0, v[126:127]
	v_lshl_add_u64 v[134:135], v[132:133], 0, v[134:135]
	v_lshl_add_u64 v[136:137], v[132:133], 0, v[136:137]
	global_load_dwordx4 v[100:103], v[100:101], off
	s_nop 0
	global_load_dwordx4 v[104:107], v[104:105], off
	s_nop 0
	global_load_dwordx4 v[108:111], v[108:109], off
	s_nop 0
	global_load_dwordx4 v[116:119], v[116:117], off
	s_nop 0
	global_load_dwordx4 v[124:127], v[124:125], off
	s_nop 0
	global_load_dwordx4 v[128:131], v[128:129], off
	s_nop 0
	global_load_dwordx4 v[132:135], v[134:135], off
	s_nop 0
	global_load_dwordx4 v[136:139], v[136:137], off
; __device__ __forceinline__ void ret_core_phase(const Params& p, const PD& d, char* shm, const int wave_s) {
;     ...
; #pragma unroll
;       for (int df = 0; df < 4; ++df)
; #pragma unroll
;         for (int vf = 0; vf < 4; ++vf) S[df][vf] *= cdec;
; #pragma unroll
;       for (int ks = 0; ks < 4; ++ks) {
;         bf16x8 Vf[4];
; #pragma unroll
;         for (int vf = 0; vf < 4; ++vf) Vf[vf] = *(const bf16x8*)(Vl + (64 * wj + 16 * vf + frv) * 272 + (ks * 32 + fqv * 8) * 2);
; #pragma unroll
;         for (int df = 0; df < 4; ++df)
; #pragma unroll
;           for (int vf = 0; vf < 4; ++vf) S[df][vf] = __builtin_amdgcn_mfma_f32_16x16x32_bf16(ktf[ks][df], Vf[vf], S[df][vf], 0, 0, 0);
;       }
	v_add_u32_e32 v174, v209, v166
	ds_read_b128 v[166:169], v174 offset:34816
	ds_read_b128 v[170:173], v174 offset:39168
	ds_read_b128 v[190:193], v174 offset:43520
	ds_read_b128 v[194:197], v174 offset:47872
	v_pk_mul_f32 v[6:7], s[76:77], v[6:7]
	v_pk_mul_f32 v[4:5], s[10:11], v[4:5]
	v_pk_mul_f32 v[10:11], s[76:77], v[10:11]
	v_pk_mul_f32 v[8:9], s[10:11], v[8:9]
	v_pk_mul_f32 v[14:15], s[76:77], v[14:15]
	v_pk_mul_f32 v[12:13], s[10:11], v[12:13]
	v_pk_mul_f32 v[18:19], s[76:77], v[18:19]
	v_pk_mul_f32 v[16:17], s[10:11], v[16:17]
	v_pk_mul_f32 v[22:23], s[76:77], v[22:23]
	v_pk_mul_f32 v[20:21], s[10:11], v[20:21]
	v_pk_mul_f32 v[26:27], s[76:77], v[26:27]
	v_pk_mul_f32 v[24:25], s[10:11], v[24:25]
	v_pk_mul_f32 v[30:31], s[76:77], v[30:31]
	v_pk_mul_f32 v[28:29], s[10:11], v[28:29]
	v_pk_mul_f32 v[34:35], s[76:77], v[34:35]
	v_pk_mul_f32 v[32:33], s[10:11], v[32:33]
	v_pk_mul_f32 v[38:39], s[76:77], v[38:39]
	v_pk_mul_f32 v[36:37], s[10:11], v[36:37]
	v_pk_mul_f32 v[42:43], s[76:77], v[42:43]
	v_pk_mul_f32 v[40:41], s[10:11], v[40:41]
	v_pk_mul_f32 v[46:47], s[76:77], v[46:47]
	v_pk_mul_f32 v[44:45], s[10:11], v[44:45]
	v_pk_mul_f32 v[50:51], s[76:77], v[50:51]
	v_pk_mul_f32 v[48:49], s[10:11], v[48:49]
	v_pk_mul_f32 v[54:55], s[76:77], v[54:55]
	v_pk_mul_f32 v[52:53], s[10:11], v[52:53]
	v_pk_mul_f32 v[58:59], s[76:77], v[58:59]
	v_pk_mul_f32 v[56:57], s[10:11], v[56:57]
	v_pk_mul_f32 v[62:63], s[76:77], v[62:63]
	v_pk_mul_f32 v[60:61], s[10:11], v[60:61]
	v_pk_mul_f32 v[66:67], s[76:77], v[66:67]
	v_pk_mul_f32 v[64:65], s[10:11], v[64:65]
	s_waitcnt vmcnt(31) lgkmcnt(3)
	v_mfma_f32_16x16x32_bf16 v[4:7], v[92:95], v[166:169], v[4:7]
	v_readlane_b32 s6, v254, 41
	s_waitcnt lgkmcnt(2)
	v_mfma_f32_16x16x32_bf16 v[8:11], v[92:95], v[170:173], v[8:11]
	s_waitcnt lgkmcnt(1)
	v_mfma_f32_16x16x32_bf16 v[12:15], v[92:95], v[190:193], v[12:15]
	s_waitcnt lgkmcnt(0)
	v_mfma_f32_16x16x32_bf16 v[16:19], v[92:95], v[194:197], v[16:19]
	s_waitcnt vmcnt(29)
	v_mfma_f32_16x16x32_bf16 v[20:23], v[96:99], v[166:169], v[20:23]
	v_mfma_f32_16x16x32_bf16 v[24:27], v[96:99], v[170:173], v[24:27]
	v_mfma_f32_16x16x32_bf16 v[28:31], v[96:99], v[190:193], v[28:31]
	v_mfma_f32_16x16x32_bf16 v[32:35], v[96:99], v[194:197], v[32:35]
	s_waitcnt vmcnt(27)
	v_mfma_f32_16x16x32_bf16 v[36:39], v[88:91], v[166:169], v[36:39]
	v_mfma_f32_16x16x32_bf16 v[40:43], v[88:91], v[170:173], v[40:43]
	v_mfma_f32_16x16x32_bf16 v[44:47], v[88:91], v[190:193], v[44:47]
	v_mfma_f32_16x16x32_bf16 v[48:51], v[88:91], v[194:197], v[48:51]
	s_waitcnt vmcnt(25)
	v_mfma_f32_16x16x32_bf16 v[52:55], v[84:87], v[166:169], v[52:55]
	v_mfma_f32_16x16x32_bf16 v[56:59], v[84:87], v[170:173], v[56:59]
	v_mfma_f32_16x16x32_bf16 v[60:63], v[84:87], v[190:193], v[60:63]
	v_mfma_f32_16x16x32_bf16 v[64:67], v[84:87], v[194:197], v[64:67]
	ds_read_b128 v[84:87], v174 offset:34880
	ds_read_b128 v[88:91], v174 offset:39232
	ds_read_b128 v[92:95], v174 offset:43584
	ds_read_b128 v[96:99], v174 offset:47936
	s_waitcnt lgkmcnt(3)
	v_mfma_f32_16x16x32_bf16 v[4:7], v[80:83], v[84:87], v[4:7]
	s_waitcnt lgkmcnt(2)
	v_mfma_f32_16x16x32_bf16 v[8:11], v[80:83], v[88:91], v[8:11]
	s_waitcnt lgkmcnt(1)
	v_mfma_f32_16x16x32_bf16 v[12:15], v[80:83], v[92:95], v[12:15]
	s_waitcnt lgkmcnt(0)
	v_mfma_f32_16x16x32_bf16 v[16:19], v[80:83], v[96:99], v[16:19]
	v_mfma_f32_16x16x32_bf16 v[20:23], v[76:79], v[84:87], v[20:23]
	v_mfma_f32_16x16x32_bf16 v[24:27], v[76:79], v[88:91], v[24:27]
	v_mfma_f32_16x16x32_bf16 v[28:31], v[76:79], v[92:95], v[28:31]
	v_mfma_f32_16x16x32_bf16 v[32:35], v[76:79], v[96:99], v[32:35]
	v_mfma_f32_16x16x32_bf16 v[36:39], v[72:75], v[84:87], v[36:39]
	v_mfma_f32_16x16x32_bf16 v[40:43], v[72:75], v[88:91], v[40:43]
	v_mfma_f32_16x16x32_bf16 v[44:47], v[72:75], v[92:95], v[44:47]
	v_mfma_f32_16x16x32_bf16 v[48:51], v[72:75], v[96:99], v[48:51]
	s_waitcnt vmcnt(24)
	v_mfma_f32_16x16x32_bf16 v[52:55], v[68:71], v[84:87], v[52:55]
	v_mfma_f32_16x16x32_bf16 v[56:59], v[68:71], v[88:91], v[56:59]
	v_mfma_f32_16x16x32_bf16 v[60:63], v[68:71], v[92:95], v[60:63]
	v_mfma_f32_16x16x32_bf16 v[64:67], v[68:71], v[96:99], v[64:67]
	ds_read_b128 v[68:71], v174 offset:34944
	ds_read_b128 v[72:75], v174 offset:39296
	ds_read_b128 v[76:79], v174 offset:43648
	ds_read_b128 v[80:83], v174 offset:48000
	s_waitcnt vmcnt(15) lgkmcnt(3)
	v_mfma_f32_16x16x32_bf16 v[4:7], v[148:151], v[68:71], v[4:7]
	s_waitcnt lgkmcnt(2)
	v_mfma_f32_16x16x32_bf16 v[8:11], v[148:151], v[72:75], v[8:11]
	s_waitcnt lgkmcnt(1)
	v_mfma_f32_16x16x32_bf16 v[12:15], v[148:151], v[76:79], v[12:15]
	s_waitcnt lgkmcnt(0)
	v_mfma_f32_16x16x32_bf16 v[16:19], v[148:151], v[80:83], v[16:19]
	s_waitcnt vmcnt(13)
	v_mfma_f32_16x16x32_bf16 v[20:23], v[160:163], v[68:71], v[20:23]
	v_mfma_f32_16x16x32_bf16 v[24:27], v[160:163], v[72:75], v[24:27]
	v_mfma_f32_16x16x32_bf16 v[28:31], v[160:163], v[76:79], v[28:31]
	v_mfma_f32_16x16x32_bf16 v[32:35], v[160:163], v[80:83], v[32:35]
	s_waitcnt vmcnt(11)
	v_mfma_f32_16x16x32_bf16 v[36:39], v[156:159], v[68:71], v[36:39]
	v_mfma_f32_16x16x32_bf16 v[40:43], v[156:159], v[72:75], v[40:43]
	v_mfma_f32_16x16x32_bf16 v[44:47], v[156:159], v[76:79], v[44:47]
	v_mfma_f32_16x16x32_bf16 v[48:51], v[156:159], v[80:83], v[48:51]
	s_waitcnt vmcnt(9)
	v_mfma_f32_16x16x32_bf16 v[52:55], v[152:155], v[68:71], v[52:55]
	v_mfma_f32_16x16x32_bf16 v[56:59], v[152:155], v[72:75], v[56:59]
	v_mfma_f32_16x16x32_bf16 v[60:63], v[152:155], v[76:79], v[60:63]
	v_mfma_f32_16x16x32_bf16 v[64:67], v[152:155], v[80:83], v[64:67]
	ds_read_b128 v[68:71], v174 offset:35008
	ds_read_b128 v[72:75], v174 offset:39360
	ds_read_b128 v[76:79], v174 offset:43712
	ds_read_b128 v[80:83], v174 offset:48064
	s_waitcnt lgkmcnt(3)
; __device__ __forceinline__ unsigned pack2(float a, float b) { return (unsigned)f2bf(a) | ((unsigned)f2bf(b) << 16); }
; __device__ __forceinline__ void ret_core_phase(const Params& p, const PD& d, char* shm, const int wave_s) {
;     ...
;       for (int ks = 0; ks < 4; ++ks) {
;         bf16x8 Vf[4];
; #pragma unroll
;         for (int vf = 0; vf < 4; ++vf) Vf[vf] = *(const bf16x8*)(Vl + (64 * wj + 16 * vf + frv) * 272 + (ks * 32 + fqv * 8) * 2);
; #pragma unroll
;         for (int df = 0; df < 4; ++df)
; #pragma unroll
;           for (int vf = 0; vf < 4; ++vf) S[df][vf] = __builtin_amdgcn_mfma_f32_16x16x32_bf16(ktf[ks][df], Vf[vf], S[df][vf], 0, 0, 0);
;       }
; #pragma unroll
;       for (int df = 0; df < 4; ++df)
; #pragma unroll
;         for (int vf = 0; vf < 4; ++vf) {
;           uint2 pk; pk.x = pack2(S[df][vf][0], S[df][vf][1]); pk.y = pack2(S[df][vf][2], S[df][vf][3]);
;           *(uint2*)(R2 + (64 * wj + 16 * vf + frv) * 528 + (64 * wi + 16 * df + 4 * fqv) * 2) = pk;
;         }
	v_mfma_f32_16x16x32_bf16 v[4:7], v[144:147], v[68:71], v[4:7]
	v_mfma_f32_16x16x32_bf16 v[20:23], v[140:143], v[68:71], v[20:23]
	v_mfma_f32_16x16x32_bf16 v[36:39], v[120:123], v[68:71], v[36:39]
	s_waitcnt vmcnt(8)
	v_mfma_f32_16x16x32_bf16 v[52:55], v[112:115], v[68:71], v[52:55]
	s_nop 3
	s_nop 0
	v_or_b32_e32 v68, v165, v182
	v_lshlrev_b32_e32 v70, 1, v68
	s_waitcnt lgkmcnt(2)
	v_mfma_f32_16x16x32_bf16 v[8:11], v[144:147], v[72:75], v[8:11]
	s_nop 0
	v_cvt_pk_bf16_f32 v68, v6, v6
	v_add3_u32 v71, s73, v70, v164
	v_mfma_f32_16x16x32_bf16 v[24:27], v[140:143], v[72:75], v[24:27]
	v_mfma_f32_16x16x32_bf16 v[40:43], v[120:123], v[72:75], v[40:43]
	v_mfma_f32_16x16x32_bf16 v[56:59], v[112:115], v[72:75], v[56:59]
	v_cvt_pk_bf16_f32 v72, v4, v4
	s_nop 0
	s_nop 0
	v_cvt_pk_bf16_f32 v69, v7, v7
	v_cvt_pk_bf16_f32 v73, v5, v5
	v_and_b32_e32 v69, 0xffff0000, v69
	v_and_b32_e32 v73, 0xffff0000, v73
	v_or_b32_sdwa v69, v69, v68 dst_sel:DWORD dst_unused:UNUSED_PAD src0_sel:DWORD src1_sel:WORD_1
	v_or_b32_sdwa v68, v73, v72 dst_sel:DWORD dst_unused:UNUSED_PAD src0_sel:DWORD src1_sel:WORD_1
	ds_write_b64 v71, v[68:69]
	s_nop 0
	s_waitcnt lgkmcnt(2)
	v_mfma_f32_16x16x32_bf16 v[12:15], v[144:147], v[76:79], v[12:15]
	v_cvt_pk_bf16_f32 v72, v8, v8
	s_nop 0
	s_nop 0
	s_nop 0
	v_cvt_pk_bf16_f32 v69, v11, v11
	v_cvt_pk_bf16_f32 v73, v9, v9
	v_cvt_pk_bf16_f32 v68, v10, v10
	v_and_b32_e32 v69, 0xffff0000, v69
	v_and_b32_e32 v73, 0xffff0000, v73
	v_or_b32_sdwa v69, v69, v68 dst_sel:DWORD dst_unused:UNUSED_PAD src0_sel:DWORD src1_sel:WORD_1
	v_or_b32_sdwa v68, v73, v72 dst_sel:DWORD dst_unused:UNUSED_PAD src0_sel:DWORD src1_sel:WORD_1
	ds_write_b64 v71, v[68:69] offset:8448
	s_nop 0
	s_waitcnt lgkmcnt(2)
	v_mfma_f32_16x16x32_bf16 v[16:19], v[144:147], v[80:83], v[16:19]
	v_cvt_pk_bf16_f32 v72, v12, v12
	s_nop 0
	s_nop 0
	s_nop 0
	v_cvt_pk_bf16_f32 v69, v15, v15
	v_cvt_pk_bf16_f32 v73, v13, v13
	v_cvt_pk_bf16_f32 v68, v14, v14
	v_and_b32_e32 v69, 0xffff0000, v69
	v_and_b32_e32 v73, 0xffff0000, v73
	v_or_b32_sdwa v69, v69, v68 dst_sel:DWORD dst_unused:UNUSED_PAD src0_sel:DWORD src1_sel:WORD_1
	v_or_b32_sdwa v68, v73, v72 dst_sel:DWORD dst_unused:UNUSED_PAD src0_sel:DWORD src1_sel:WORD_1
	ds_write_b64 v71, v[68:69] offset:16896
	s_nop 0
	v_cvt_pk_bf16_f32 v72, v16, v16
	s_nop 0
	s_nop 0
	s_nop 0
	v_cvt_pk_bf16_f32 v69, v19, v19
	v_cvt_pk_bf16_f32 v73, v17, v17
	v_cvt_pk_bf16_f32 v68, v18, v18
	v_and_b32_e32 v69, 0xffff0000, v69
	v_and_b32_e32 v73, 0xffff0000, v73
	v_or_b32_sdwa v69, v69, v68 dst_sel:DWORD dst_unused:UNUSED_PAD src0_sel:DWORD src1_sel:WORD_1
	v_or_b32_sdwa v68, v73, v72 dst_sel:DWORD dst_unused:UNUSED_PAD src0_sel:DWORD src1_sel:WORD_1
	ds_write_b64 v71, v[68:69] offset:25344
	s_nop 0
	v_cvt_pk_bf16_f32 v72, v20, v20
	s_nop 0
	s_nop 0
	s_nop 0
	v_cvt_pk_bf16_f32 v69, v23, v23
	v_cvt_pk_bf16_f32 v73, v21, v21
	v_cvt_pk_bf16_f32 v68, v22, v22
	v_and_b32_e32 v69, 0xffff0000, v69
	v_and_b32_e32 v73, 0xffff0000, v73
	v_add3_u32 v71, s6, v70, v164
	v_or_b32_sdwa v69, v69, v68 dst_sel:DWORD dst_unused:UNUSED_PAD src0_sel:DWORD src1_sel:WORD_1
	v_or_b32_sdwa v68, v73, v72 dst_sel:DWORD dst_unused:UNUSED_PAD src0_sel:DWORD src1_sel:WORD_1
	ds_write_b64 v71, v[68:69]
	s_nop 0
	v_mfma_f32_16x16x32_bf16 v[28:31], v[140:143], v[76:79], v[28:31]
	v_cvt_pk_bf16_f32 v72, v24, v24
	s_nop 0
	s_nop 0
	s_nop 0
	v_cvt_pk_bf16_f32 v69, v27, v27
	v_cvt_pk_bf16_f32 v73, v25, v25
	v_cvt_pk_bf16_f32 v68, v26, v26
	v_and_b32_e32 v69, 0xffff0000, v69
	v_and_b32_e32 v73, 0xffff0000, v73
	v_or_b32_sdwa v69, v69, v68 dst_sel:DWORD dst_unused:UNUSED_PAD src0_sel:DWORD src1_sel:WORD_1
	v_or_b32_sdwa v68, v73, v72 dst_sel:DWORD dst_unused:UNUSED_PAD src0_sel:DWORD src1_sel:WORD_1
	ds_write_b64 v71, v[68:69] offset:8448
	s_nop 0
	v_mfma_f32_16x16x32_bf16 v[32:35], v[140:143], v[80:83], v[32:35]
	v_cvt_pk_bf16_f32 v72, v28, v28
	s_nop 0
	s_nop 0
	s_nop 0
	v_cvt_pk_bf16_f32 v69, v31, v31
	v_cvt_pk_bf16_f32 v73, v29, v29
	v_cvt_pk_bf16_f32 v68, v30, v30
	v_and_b32_e32 v69, 0xffff0000, v69
	v_and_b32_e32 v73, 0xffff0000, v73
	v_or_b32_sdwa v69, v69, v68 dst_sel:DWORD dst_unused:UNUSED_PAD src0_sel:DWORD src1_sel:WORD_1
	v_or_b32_sdwa v68, v73, v72 dst_sel:DWORD dst_unused:UNUSED_PAD src0_sel:DWORD src1_sel:WORD_1
	ds_write_b64 v71, v[68:69] offset:16896
	s_nop 0
	v_cvt_pk_bf16_f32 v72, v32, v32
	s_nop 0
	s_nop 0
	s_nop 0
	v_cvt_pk_bf16_f32 v69, v35, v35
	v_cvt_pk_bf16_f32 v73, v33, v33
	v_cvt_pk_bf16_f32 v68, v34, v34
	v_and_b32_e32 v69, 0xffff0000, v69
	v_and_b32_e32 v73, 0xffff0000, v73
	v_or_b32_sdwa v69, v69, v68 dst_sel:DWORD dst_unused:UNUSED_PAD src0_sel:DWORD src1_sel:WORD_1
	v_or_b32_sdwa v68, v73, v72 dst_sel:DWORD dst_unused:UNUSED_PAD src0_sel:DWORD src1_sel:WORD_1
	ds_write_b64 v71, v[68:69] offset:25344
	s_nop 0
	v_cvt_pk_bf16_f32 v72, v36, v36
	s_nop 0
	s_nop 0
	s_nop 0
	v_cvt_pk_bf16_f32 v69, v39, v39
	v_cvt_pk_bf16_f32 v73, v37, v37
	v_readlane_b32 s6, v254, 42
	v_cvt_pk_bf16_f32 v68, v38, v38
	v_and_b32_e32 v69, 0xffff0000, v69
	v_and_b32_e32 v73, 0xffff0000, v73
	v_add3_u32 v71, s6, v70, v164
	v_or_b32_sdwa v69, v69, v68 dst_sel:DWORD dst_unused:UNUSED_PAD src0_sel:DWORD src1_sel:WORD_1
	v_or_b32_sdwa v68, v73, v72 dst_sel:DWORD dst_unused:UNUSED_PAD src0_sel:DWORD src1_sel:WORD_1
	ds_write_b64 v71, v[68:69]
	s_nop 0
	v_mfma_f32_16x16x32_bf16 v[44:47], v[120:123], v[76:79], v[44:47]
	v_cvt_pk_bf16_f32 v72, v40, v40
	s_nop 0
	s_nop 0
	s_nop 0
	v_cvt_pk_bf16_f32 v69, v43, v43
	v_cvt_pk_bf16_f32 v73, v41, v41
	v_cvt_pk_bf16_f32 v68, v42, v42
	v_and_b32_e32 v69, 0xffff0000, v69
	v_and_b32_e32 v73, 0xffff0000, v73
	v_or_b32_sdwa v69, v69, v68 dst_sel:DWORD dst_unused:UNUSED_PAD src0_sel:DWORD src1_sel:WORD_1
; __device__ __forceinline__ unsigned pack2(float a, float b) { return (unsigned)f2bf(a) | ((unsigned)f2bf(b) << 16); }
; #define SCHED __builtin_amdgcn_sched_barrier(0)
; __device__ __forceinline__ void ret_core_phase(const Params& p, const PD& d, char* shm, const int wave_s) {
;     ...
; #pragma unroll
;       for (int df = 0; df < 4; ++df)
; #pragma unroll
;         for (int vf = 0; vf < 4; ++vf) {
;           uint2 pk; pk.x = pack2(S[df][vf][0], S[df][vf][1]); pk.y = pack2(S[df][vf][2], S[df][vf][3]);
;           *(uint2*)(R2 + (64 * wj + 16 * vf + frv) * 528 + (64 * wi + 16 * df + 4 * fqv) * 2) = pk;
;         }
;       SCHED;
;       {
;         const u16* Qw = Qb + (lt1 + 32 * wi + frv) * 1024 + hh * 256 + fqv * 8;
; #pragma unroll
;         for (int f = 0; f < 2; ++f)
; #pragma unroll
;           for (int ks = 0; ks < 8; ++ks) Qf[f][ks] = *(const bf16x8*)(Qw + f * 16 * 1024 + ks * 32);
;       }
;       __syncthreads();
	v_or_b32_sdwa v68, v73, v72 dst_sel:DWORD dst_unused:UNUSED_PAD src0_sel:DWORD src1_sel:WORD_1
	ds_write_b64 v71, v[68:69] offset:8448
	s_nop 0
	v_mfma_f32_16x16x32_bf16 v[48:51], v[120:123], v[80:83], v[48:51]
	v_cvt_pk_bf16_f32 v72, v44, v44
	s_nop 0
	s_nop 0
	s_nop 0
	v_cvt_pk_bf16_f32 v69, v47, v47
	v_cvt_pk_bf16_f32 v73, v45, v45
	v_cvt_pk_bf16_f32 v68, v46, v46
	v_and_b32_e32 v69, 0xffff0000, v69
	v_and_b32_e32 v73, 0xffff0000, v73
	v_or_b32_sdwa v69, v69, v68 dst_sel:DWORD dst_unused:UNUSED_PAD src0_sel:DWORD src1_sel:WORD_1
	v_or_b32_sdwa v68, v73, v72 dst_sel:DWORD dst_unused:UNUSED_PAD src0_sel:DWORD src1_sel:WORD_1
	ds_write_b64 v71, v[68:69] offset:16896
	s_nop 0
	v_cvt_pk_bf16_f32 v72, v48, v48
	s_nop 0
	s_nop 0
	s_nop 0
	v_cvt_pk_bf16_f32 v69, v51, v51
	v_cvt_pk_bf16_f32 v73, v49, v49
	v_cvt_pk_bf16_f32 v68, v50, v50
	v_and_b32_e32 v69, 0xffff0000, v69
	v_and_b32_e32 v73, 0xffff0000, v73
	v_or_b32_sdwa v69, v69, v68 dst_sel:DWORD dst_unused:UNUSED_PAD src0_sel:DWORD src1_sel:WORD_1
	v_or_b32_sdwa v68, v73, v72 dst_sel:DWORD dst_unused:UNUSED_PAD src0_sel:DWORD src1_sel:WORD_1
	ds_write_b64 v71, v[68:69] offset:25344
	s_nop 0
	v_cvt_pk_bf16_f32 v71, v52, v52
	s_nop 0
	s_nop 0
	s_nop 0
	v_cvt_pk_bf16_f32 v69, v55, v55
	v_cvt_pk_bf16_f32 v72, v53, v53
	v_readlane_b32 s6, v254, 43
	v_cvt_pk_bf16_f32 v68, v54, v54
	v_and_b32_e32 v69, 0xffff0000, v69
	v_and_b32_e32 v72, 0xffff0000, v72
	v_add3_u32 v70, s6, v70, v164
	v_or_b32_sdwa v69, v69, v68 dst_sel:DWORD dst_unused:UNUSED_PAD src0_sel:DWORD src1_sel:WORD_1
	v_or_b32_sdwa v68, v72, v71 dst_sel:DWORD dst_unused:UNUSED_PAD src0_sel:DWORD src1_sel:WORD_1
	ds_write_b64 v70, v[68:69]
	s_nop 0
	v_mfma_f32_16x16x32_bf16 v[60:63], v[112:115], v[76:79], v[60:63]
	v_cvt_pk_bf16_f32 v71, v56, v56
	s_nop 0
	s_nop 0
	s_nop 0
	v_cvt_pk_bf16_f32 v69, v59, v59
	v_cvt_pk_bf16_f32 v72, v57, v57
	v_cvt_pk_bf16_f32 v68, v58, v58
	v_and_b32_e32 v69, 0xffff0000, v69
	v_and_b32_e32 v72, 0xffff0000, v72
	v_or_b32_sdwa v69, v69, v68 dst_sel:DWORD dst_unused:UNUSED_PAD src0_sel:DWORD src1_sel:WORD_1
	v_or_b32_sdwa v68, v72, v71 dst_sel:DWORD dst_unused:UNUSED_PAD src0_sel:DWORD src1_sel:WORD_1
	ds_write_b64 v70, v[68:69] offset:8448
	s_nop 0
	v_mfma_f32_16x16x32_bf16 v[64:67], v[112:115], v[80:83], v[64:67]
	v_cvt_pk_bf16_f32 v71, v60, v60
	s_nop 0
	s_nop 0
	s_nop 0
	v_cvt_pk_bf16_f32 v69, v63, v63
	v_cvt_pk_bf16_f32 v72, v61, v61
	v_cvt_pk_bf16_f32 v68, v62, v62
	v_and_b32_e32 v69, 0xffff0000, v69
	v_and_b32_e32 v72, 0xffff0000, v72
	v_or_b32_sdwa v69, v69, v68 dst_sel:DWORD dst_unused:UNUSED_PAD src0_sel:DWORD src1_sel:WORD_1
	v_or_b32_sdwa v68, v72, v71 dst_sel:DWORD dst_unused:UNUSED_PAD src0_sel:DWORD src1_sel:WORD_1
	ds_write_b64 v70, v[68:69] offset:16896
	s_nop 0
	v_cvt_pk_bf16_f32 v71, v64, v64
	s_nop 0
	s_nop 0
	s_nop 0
	v_cvt_pk_bf16_f32 v69, v67, v67
	v_cvt_pk_bf16_f32 v72, v65, v65
	v_cvt_pk_bf16_f32 v68, v66, v66
	v_and_b32_e32 v69, 0xffff0000, v69
	v_and_b32_e32 v72, 0xffff0000, v72
	v_or_b32_sdwa v69, v69, v68 dst_sel:DWORD dst_unused:UNUSED_PAD src0_sel:DWORD src1_sel:WORD_1
	v_or_b32_sdwa v68, v72, v71 dst_sel:DWORD dst_unused:UNUSED_PAD src0_sel:DWORD src1_sel:WORD_1
	ds_write_b64 v70, v[68:69] offset:25344
	v_lshl_add_u64 v[68:69], s[4:5], 0, v[2:3]
	v_or_b32_e32 v68, v68, v0
	v_lshlrev_b64 v[68:69], 11, v[68:69]
	v_lshl_add_u64 v[68:69], s[84:85], 0, v[68:69]
	v_lshlrev_b32_e32 v0, 1, v188
	v_lshl_add_u64 v[72:73], v[68:69], 0, v[0:1]
	global_load_dwordx4 v[156:159], v[72:73], off
	global_load_dwordx4 v[144:147], v[72:73], off offset:64
	global_load_dwordx4 v[140:143], v[72:73], off offset:128
	global_load_dwordx4 v[96:99], v[72:73], off offset:192
	global_load_dwordx4 v[92:95], v[72:73], off offset:256
	global_load_dwordx4 v[80:83], v[72:73], off offset:320
	global_load_dwordx4 v[76:79], v[72:73], off offset:384
	global_load_dwordx4 v[68:71], v[72:73], off offset:448
	v_add_co_u32_e32 v72, vcc, s20, v72
	s_add_u32 s68, s68, 0x200
	s_nop 0
	v_addc_co_u32_e32 v73, vcc, 0, v73, vcc
	global_load_dwordx4 v[160:163], v[72:73], off
	global_load_dwordx4 v[152:155], v[72:73], off offset:64
	global_load_dwordx4 v[148:151], v[72:73], off offset:128
	global_load_dwordx4 v[120:123], v[72:73], off offset:192
	global_load_dwordx4 v[112:115], v[72:73], off offset:256
	global_load_dwordx4 v[88:91], v[72:73], off offset:320
	global_load_dwordx4 v[84:87], v[72:73], off offset:384
	s_nop 0
	global_load_dwordx4 v[72:75], v[72:73], off offset:448
	s_addc_u32 s69, s69, 0
	s_cmpk_eq_i32 s68, 0x2000
	v_lshl_add_u64 v[186:187], v[186:187], 0, s[78:79]
	s_waitcnt lgkmcnt(0)
	s_barrier
	s_cbranch_scc1 .LBB0_555
; __device__ __forceinline__ void ret_core_phase(const Params& p, const PD& d, char* shm, const int wave_s) {
;     ...
;       const int tidv = fresh_tid(wave_s);
;       const int frv = tidv & 15, fqv = (tidv >> 4) & 3;
;       float lg2v = lg2;
;       asm volatile("" : "+v"(lg2v));
; #pragma unroll
;       for (int i = 0; i < 8; ++i) {
;         int c = i * 512 + tidv, row = c >> 5, cc = c & 31;
;         *(bf16x8*)(R1 + row * 528 + cc * 16) = kpre[i];
;       }
;       bf16x8 vpre[4];
; #pragma unroll
;       for (int i = 0; i < 4; ++i) {
;         int c = i * 512 + tidv, row = c >> 4, cc = c & 15;
;         vpre[i] = *(const bf16x8*)(VTb + ((size_t)(bh * 16 + lc) * 512 + vs * 128 + row) * 128 + cc * 8);
;       }
;       __syncthreads();
;       f32x4 PT[4][2];
; #pragma unroll
;       for (int a = 0; a < 4; ++a)
; #pragma unroll
;         for (int c = 0; c < 2; ++c) PT[a][c] = f32x4{0.f, 0.f, 0.f, 0.f};
; #pragma unroll
;       for (int ks = 0; ks < 8; ++ks) {
; #pragma unroll
;         for (int jf = 0; jf < 4; ++jf) {
;           bf16x8 Kf = *(const bf16x8*)(R1 + (64 * wj + 16 * jf + frv) * 528 + (ks * 32 + fqv * 8) * 2);
; #pragma unroll
;           for (int f = 0; f < 2; ++f) PT[jf][f] = __builtin_amdgcn_mfma_f32_16x16x32_bf16(Kf, Qf[f][ks], PT[jf][f], 0, 0, 0);
;         }
;       }
.LBB0_563:
	s_mov_b32 s4, s82
	s_mov_b32 s5, -1
	v_mov_b32_e32 v197, v183
	v_mbcnt_lo_u32_b32 v0, s5, 0
	v_mbcnt_hi_u32_b32 v0, s5, v0
	v_lshl_add_u32 v191, s4, 6, v0
	s_nop 0
	v_lshlrev_b32_e32 v166, 4, v191
	v_and_b32_e32 v0, 0x1f0, v166
	v_add_u32_e32 v0, 0, v0
	v_ashrrev_i32_e32 v204, 5, v191
	v_mad_u64_u32 v[164:165], s[4:5], v204, s29, v[0:1]
	s_waitcnt vmcnt(23)
	ds_write_b128 v164, v[100:103]
	v_add_u32_e32 v164, 0x200, v191
	v_ashrrev_i32_e32 v202, 5, v164
	v_add_u32_e32 v165, 0x400, v191
	v_mad_u64_u32 v[100:101], s[4:5], v202, s29, v[0:1]
	v_ashrrev_i32_e32 v200, 5, v165
	v_add_u32_e32 v167, 0x600, v191
	s_waitcnt vmcnt(22)
	ds_write_b128 v100, v[104:107]
	v_mad_u64_u32 v[100:101], s[4:5], v200, s29, v[0:1]
	v_ashrrev_i32_e32 v198, 5, v167
	s_waitcnt vmcnt(21)
	ds_write_b128 v100, v[108:111]
	v_mad_u64_u32 v[100:101], s[4:5], v198, s29, v[0:1]
	s_waitcnt vmcnt(20)
	ds_write_b128 v100, v[116:119]
	v_add_u32_e32 v100, 0x800, v191
	v_ashrrev_i32_e32 v196, 5, v100
	v_mad_u64_u32 v[100:101], s[4:5], v196, s29, v[0:1]
	s_waitcnt vmcnt(19)
	ds_write_b128 v100, v[124:127]
	v_add_u32_e32 v100, 0xa00, v191
	v_ashrrev_i32_e32 v194, 5, v100
	v_mad_u64_u32 v[100:101], s[4:5], v194, s29, v[0:1]
	s_waitcnt vmcnt(18)
	ds_write_b128 v100, v[128:131]
	v_add_u32_e32 v100, 0xc00, v191
	v_ashrrev_i32_e32 v192, 5, v100
	v_mad_u64_u32 v[100:101], s[4:5], v192, s29, v[0:1]
	s_waitcnt vmcnt(17)
	ds_write_b128 v100, v[132:135]
	v_add_u32_e32 v100, 0xe00, v191
	v_ashrrev_i32_e32 v190, 5, v100
	v_mad_u64_u32 v[100:101], s[4:5], v190, s29, v[0:1]
	v_readlane_b32 s4, v252, 61
	v_and_b32_e32 v0, 0xf0, v166
	v_readlane_b32 s5, v252, 62
	v_ashrrev_i32_e32 v208, 4, v191
	v_ashrrev_i32_e32 v210, 4, v164
	v_lshl_add_u64 v[116:117], s[4:5], 0, v[0:1]
	s_add_u32 s4, s2, s68
	v_ashrrev_i32_e32 v212, 4, v165
	v_ashrrev_i32_e32 v214, 4, v167
	v_ashrrev_i32_e32 v209, 31, v208
	s_addc_u32 s5, s3, s69
	v_ashrrev_i32_e32 v211, 31, v210
	v_ashrrev_i32_e32 v213, 31, v212
	v_ashrrev_i32_e32 v215, 31, v214
	v_bfe_u32 v195, v191, 4, 2
	s_waitcnt vmcnt(16)
	ds_write_b128 v100, v[136:139]
	v_and_b32_e32 v189, 15, v191
	v_lshl_add_u64 v[100:101], s[4:5], 0, v[208:209]
	v_lshl_add_u64 v[104:105], s[4:5], 0, v[210:211]
	v_lshl_add_u64 v[108:109], s[4:5], 0, v[212:213]
	v_lshl_add_u64 v[118:119], s[4:5], 0, v[214:215]
	v_lshlrev_b32_e32 v206, 4, v195
	v_lshlrev_b64 v[100:101], 8, v[100:101]
	v_lshlrev_b64 v[104:105], 8, v[104:105]
	v_lshlrev_b64 v[108:109], 8, v[108:109]
	v_lshlrev_b64 v[118:119], 8, v[118:119]
	v_or_b32_e32 v193, v189, v241
	v_add_u32_e32 v209, 0, v206
	v_lshl_add_u64 v[100:101], v[116:117], 0, v[100:101]
	v_lshl_add_u64 v[104:105], v[116:117], 0, v[104:105]
	v_lshl_add_u64 v[108:109], v[116:117], 0, v[108:109]
	v_lshl_add_u64 v[116:117], v[116:117], 0, v[118:119]
	v_mad_u32_u24 v188, v193, s29, v209
	global_load_dwordx4 v[100:103], v[100:101], off
	s_nop 0
	global_load_dwordx4 v[104:107], v[104:105], off
	s_nop 0
	global_load_dwordx4 v[108:111], v[108:109], off
	s_nop 0
	global_load_dwordx4 v[116:119], v[116:117], off
	s_waitcnt lgkmcnt(0)
	s_barrier
	ds_read_b128 v[124:127], v188
	ds_read_b128 v[228:231], v188 offset:64
	s_waitcnt vmcnt(19) lgkmcnt(1)
	v_mfma_f32_16x16x32_bf16 v[128:131], v[124:127], v[156:159], 0
	s_waitcnt vmcnt(11)
	v_mfma_f32_16x16x32_bf16 v[132:135], v[124:127], v[160:163], 0
	v_mov_b32_e32 v124, 0x2100
	v_mad_u32_u24 v201, v193, s29, v124
	v_add_u32_e32 v199, v209, v201
	ds_read_b128 v[124:127], v199
	s_waitcnt lgkmcnt(0)
	v_mfma_f32_16x16x32_bf16 v[136:139], v[124:127], v[156:159], 0
	v_mfma_f32_16x16x32_bf16 v[164:167], v[124:127], v[160:163], 0
	v_mov_b32_e32 v124, 0x4200
	v_mad_u32_u24 v203, v193, s29, v124
	v_add_u32_e32 v207, v209, v203
	ds_read_b128 v[124:127], v207
	s_waitcnt lgkmcnt(0)
	v_mfma_f32_16x16x32_bf16 v[168:171], v[124:127], v[156:159], 0
	v_mfma_f32_16x16x32_bf16 v[172:175], v[124:127], v[160:163], 0
	v_mov_b32_e32 v124, 0x6300
	v_mad_u32_u24 v205, v193, s29, v124
	v_add_u32_e32 v124, v209, v205
	v_mfma_f32_16x16x32_bf16 v[126:129], v[228:231], v[144:147], v[128:131]
	ds_read_b128 v[220:223], v124
	s_waitcnt vmcnt(10)
	v_mfma_f32_16x16x32_bf16 v[130:133], v[228:231], v[152:155], v[132:135]
	ds_read_b128 v[228:231], v199 offset:64
	s_waitcnt lgkmcnt(0)
	v_mfma_f32_16x16x32_bf16 v[134:137], v[228:231], v[144:147], v[136:139]
	v_mfma_f32_16x16x32_bf16 v[164:167], v[228:231], v[152:155], v[164:167]
	ds_read_b128 v[228:231], v207 offset:64
	s_waitcnt lgkmcnt(0)
	v_mfma_f32_16x16x32_bf16 v[168:171], v[228:231], v[144:147], v[168:171]
	v_mfma_f32_16x16x32_bf16 v[172:175], v[228:231], v[152:155], v[172:175]
	ds_read_b128 v[228:231], v124 offset:64
	v_mfma_f32_16x16x32_bf16 v[224:227], v[220:223], v[156:159], 0
	v_mfma_f32_16x16x32_bf16 v[220:223], v[220:223], v[160:163], 0
	s_waitcnt lgkmcnt(0)
	v_mfma_f32_16x16x32_bf16 v[224:227], v[228:231], v[144:147], v[224:227]
	v_mfma_f32_16x16x32_bf16 v[220:223], v[228:231], v[152:155], v[220:223]
	ds_read_b128 v[228:231], v188 offset:128
	s_waitcnt lgkmcnt(0)
	v_mfma_f32_16x16x32_bf16 v[126:129], v[228:231], v[140:143], v[126:129]
	s_waitcnt vmcnt(9)
	v_mfma_f32_16x16x32_bf16 v[130:133], v[228:231], v[148:151], v[130:133]
	ds_read_b128 v[228:231], v199 offset:128
	s_waitcnt lgkmcnt(0)
	v_mfma_f32_16x16x32_bf16 v[134:137], v[228:231], v[140:143], v[134:137]
	v_mfma_f32_16x16x32_bf16 v[164:167], v[228:231], v[148:151], v[164:167]
	ds_read_b128 v[228:231], v207 offset:128
	s_waitcnt lgkmcnt(0)
	v_mfma_f32_16x16x32_bf16 v[168:171], v[228:231], v[140:143], v[168:171]
	v_mfma_f32_16x16x32_bf16 v[172:175], v[228:231], v[148:151], v[172:175]
	ds_read_b128 v[228:231], v124 offset:128
	s_waitcnt lgkmcnt(0)
; __device__ __forceinline__ void ret_core_phase(const Params& p, const PD& d, char* shm, const int wave_s) {
;     ...
;       for (int ks = 0; ks < 8; ++ks) {
; #pragma unroll
;         for (int jf = 0; jf < 4; ++jf) {
;           bf16x8 Kf = *(const bf16x8*)(R1 + (64 * wj + 16 * jf + frv) * 528 + (ks * 32 + fqv * 8) * 2);
; #pragma unroll
;           for (int f = 0; f < 2; ++f) PT[jf][f] = __builtin_amdgcn_mfma_f32_16x16x32_bf16(Kf, Qf[f][ks], PT[jf][f], 0, 0, 0);
;         }
;       }
	v_mfma_f32_16x16x32_bf16 v[224:227], v[228:231], v[140:143], v[224:227]
	v_mfma_f32_16x16x32_bf16 v[220:223], v[228:231], v[148:151], v[220:223]
	ds_read_b128 v[228:231], v188 offset:192
	s_waitcnt lgkmcnt(0)
	v_mfma_f32_16x16x32_bf16 v[126:129], v[228:231], v[96:99], v[126:129]
	s_waitcnt vmcnt(8)
	v_mfma_f32_16x16x32_bf16 v[130:133], v[228:231], v[120:123], v[130:133]
	ds_read_b128 v[228:231], v199 offset:192
	s_waitcnt lgkmcnt(0)
	v_mfma_f32_16x16x32_bf16 v[134:137], v[228:231], v[96:99], v[134:137]
	v_mfma_f32_16x16x32_bf16 v[164:167], v[228:231], v[120:123], v[164:167]
	ds_read_b128 v[228:231], v207 offset:192
	s_waitcnt lgkmcnt(0)
	v_mfma_f32_16x16x32_bf16 v[168:171], v[228:231], v[96:99], v[168:171]
	v_mfma_f32_16x16x32_bf16 v[172:175], v[228:231], v[120:123], v[172:175]
	ds_read_b128 v[228:231], v124 offset:192
	s_waitcnt lgkmcnt(0)
	v_mfma_f32_16x16x32_bf16 v[224:227], v[228:231], v[96:99], v[224:227]
	v_mfma_f32_16x16x32_bf16 v[220:223], v[228:231], v[120:123], v[220:223]
	ds_read_b128 v[228:231], v188 offset:256
	s_waitcnt lgkmcnt(0)
	v_mfma_f32_16x16x32_bf16 v[126:129], v[228:231], v[92:95], v[126:129]
	s_waitcnt vmcnt(7)
	v_mfma_f32_16x16x32_bf16 v[130:133], v[228:231], v[112:115], v[130:133]
	ds_read_b128 v[228:231], v199 offset:256
	s_waitcnt lgkmcnt(0)
	v_mfma_f32_16x16x32_bf16 v[134:137], v[228:231], v[92:95], v[134:137]
	v_mfma_f32_16x16x32_bf16 v[164:167], v[228:231], v[112:115], v[164:167]
	ds_read_b128 v[228:231], v207 offset:256
	s_waitcnt lgkmcnt(0)
	v_mfma_f32_16x16x32_bf16 v[168:171], v[228:231], v[92:95], v[168:171]
	v_mfma_f32_16x16x32_bf16 v[172:175], v[228:231], v[112:115], v[172:175]
	ds_read_b128 v[228:231], v124 offset:256
	s_waitcnt lgkmcnt(0)
	v_mfma_f32_16x16x32_bf16 v[224:227], v[228:231], v[92:95], v[224:227]
	v_mfma_f32_16x16x32_bf16 v[220:223], v[228:231], v[112:115], v[220:223]
	ds_read_b128 v[228:231], v188 offset:320
	s_waitcnt lgkmcnt(0)
	v_mfma_f32_16x16x32_bf16 v[126:129], v[228:231], v[80:83], v[126:129]
	s_waitcnt vmcnt(6)
	v_mfma_f32_16x16x32_bf16 v[130:133], v[228:231], v[88:91], v[130:133]
	ds_read_b128 v[228:231], v199 offset:320
	s_waitcnt lgkmcnt(0)
	v_mfma_f32_16x16x32_bf16 v[134:137], v[228:231], v[80:83], v[134:137]
	v_mfma_f32_16x16x32_bf16 v[164:167], v[228:231], v[88:91], v[164:167]
	ds_read_b128 v[228:231], v207 offset:320
	s_waitcnt lgkmcnt(0)
	v_mfma_f32_16x16x32_bf16 v[168:171], v[228:231], v[80:83], v[168:171]
	v_mfma_f32_16x16x32_bf16 v[172:175], v[228:231], v[88:91], v[172:175]
	ds_read_b128 v[228:231], v124 offset:320
	s_waitcnt lgkmcnt(0)
	v_mfma_f32_16x16x32_bf16 v[224:227], v[228:231], v[80:83], v[224:227]
	v_mfma_f32_16x16x32_bf16 v[220:223], v[228:231], v[88:91], v[220:223]
	ds_read_b128 v[228:231], v188 offset:384
	s_waitcnt lgkmcnt(0)
	v_mfma_f32_16x16x32_bf16 v[126:129], v[228:231], v[76:79], v[126:129]
	s_waitcnt vmcnt(5)
	v_mfma_f32_16x16x32_bf16 v[130:133], v[228:231], v[84:87], v[130:133]
	ds_read_b128 v[228:231], v199 offset:384
	s_waitcnt lgkmcnt(0)
	v_mfma_f32_16x16x32_bf16 v[134:137], v[228:231], v[76:79], v[134:137]
	v_mfma_f32_16x16x32_bf16 v[164:167], v[228:231], v[84:87], v[164:167]
	ds_read_b128 v[228:231], v207 offset:384
	s_waitcnt lgkmcnt(0)
	v_mfma_f32_16x16x32_bf16 v[244:247], v[228:231], v[76:79], v[168:171]
	s_nop 2
	ds_read_b128 v[168:171], v124 offset:384
	s_waitcnt lgkmcnt(0)
	v_mfma_f32_16x16x32_bf16 v[224:227], v[168:171], v[76:79], v[224:227]
	v_mfma_f32_16x16x32_bf16 v[220:223], v[168:171], v[84:87], v[220:223]
	ds_read_b128 v[168:171], v188 offset:448
	s_waitcnt lgkmcnt(0)
	v_mfma_f32_16x16x32_bf16 v[248:251], v[168:171], v[68:71], v[126:129]
	s_nop 2
	ds_read_b128 v[126:129], v199 offset:448
	v_mfma_f32_16x16x32_bf16 v[228:231], v[228:231], v[84:87], v[172:175]
	s_waitcnt vmcnt(4)
	v_mfma_f32_16x16x32_bf16 v[172:175], v[168:171], v[72:75], v[130:133]
	s_waitcnt lgkmcnt(0)
	v_mfma_f32_16x16x32_bf16 v[168:171], v[126:129], v[68:71], v[134:137]
	v_mfma_f32_16x16x32_bf16 v[164:167], v[126:129], v[72:75], v[164:167]
	ds_read_b128 v[126:129], v207 offset:448
	s_waitcnt lgkmcnt(0)
	v_mfma_f32_16x16x32_bf16 v[136:139], v[126:129], v[68:71], v[244:247]
	v_mfma_f32_16x16x32_bf16 v[128:131], v[126:129], v[72:75], v[228:231]
	ds_read_b128 v[124:127], v124 offset:448
	s_waitcnt lgkmcnt(0)
; __device__ __forceinline__ unsigned pack2(float a, float b) { return (unsigned)f2bf(a) | ((unsigned)f2bf(b) << 16); }
; __device__ __forceinline__ float fexp2(float x) { return __builtin_amdgcn_exp2f(x); }
; #define SCHED __builtin_amdgcn_sched_barrier(0)
; __device__ __forceinline__ void ret_core_phase(const Params& p, const PD& d, char* shm, const int wave_s) {
;     ...
; #pragma unroll
;       for (int jf = 0; jf < 4; ++jf)
; #pragma unroll
;         for (int f = 0; f < 2; ++f)
; #pragma unroll
;           for (int r = 0; r < 4; ++r) {
;             int j = 64 * wj + 16 * jf + 4 * fqv + r, i = 32 * wi + 16 * f + frv;
;             int df = i - j;
;             float fac = (df >= 0) ? fexp2(lg2v * (float)df) : 0.0f;
;             PT[jf][f][r] *= fac;
;           }
;       __syncthreads();
;       SCHED;
; #pragma unroll
;       for (int jf = 0; jf < 4; ++jf)
; #pragma unroll
;         for (int f = 0; f < 2; ++f) {
;           uint2 pk; pk.x = pack2(PT[jf][f][0], PT[jf][f][1]); pk.y = pack2(PT[jf][f][2], PT[jf][f][3]);
;           *(uint2*)(Pl + (32 * wi + 16 * f + frv) * 272 + (64 * wj + 16 * jf + 4 * fqv) * 2) = pk;
;         }
	v_mfma_f32_16x16x32_bf16 v[132:135], v[124:127], v[68:71], v[224:227]
	v_mfma_f32_16x16x32_bf16 v[124:127], v[124:127], v[72:75], v[220:223]
	v_mul_i32_i24_e32 v188, -4, v195
	v_or_b32_e32 v199, v189, v2
	v_sub_u32_e32 v188, v188, v241
	v_add_u32_e32 v207, v188, v199
	v_cvt_f32_u32_e32 v188, v207
	v_add_u32_e32 v211, -1, v207
	v_cvt_f32_u32_e32 v211, v211
	v_add_u32_e32 v215, -3, v207
	v_mul_f32_e32 v188, v197, v188
	v_exp_f32_e32 v213, v188
	v_mul_f32_e32 v188, v197, v211
	v_add_u32_e32 v211, -2, v207
	v_cvt_f32_u32_e32 v211, v211
	v_cvt_f32_u32_e32 v215, v215
	v_exp_f32_e32 v220, v188
	v_add_u32_e32 v216, 15, v207
	v_mul_f32_e32 v188, v197, v211
	v_exp_f32_e32 v211, v188
	v_mul_f32_e32 v188, v197, v215
	v_add_u32_e32 v215, 16, v207
	v_cvt_f32_u32_e32 v215, v215
	v_cvt_f32_u32_e32 v216, v216
	v_exp_f32_e32 v221, v188
	v_add_u32_e32 v217, 13, v207
	v_mul_f32_e32 v188, v197, v215
	v_exp_f32_e32 v215, v188
	v_mul_f32_e32 v188, v197, v216
	v_add_u32_e32 v216, 14, v207
	v_cvt_f32_u32_e32 v216, v216
	v_cvt_f32_u32_e32 v217, v217
	v_exp_f32_e32 v222, v188
	s_mov_b32 s4, 0x80000010
	v_mul_f32_e32 v188, v197, v216
	v_sub_u32_e32 v216, v199, v241
	v_mad_i32_i24 v216, v195, -4, v216
	v_add_u32_e32 v224, -16, v216
	v_exp_f32_e32 v223, v188
	v_mul_f32_e32 v188, v197, v217
	v_cvt_f32_u32_e32 v217, v224
	v_subrev_u32_e32 v218, 17, v216
	v_cvt_f32_u32_e32 v218, v218
	v_exp_f32_e32 v225, v188
	v_mul_f32_e32 v188, v197, v217
	v_subrev_u32_e32 v217, 18, v216
	v_exp_f32_e32 v226, v188
	v_mul_f32_e32 v188, v197, v218
	v_cvt_f32_u32_e32 v217, v217
	v_subrev_u32_e32 v218, 19, v216
	v_cvt_f32_u32_e32 v218, v218
	v_exp_f32_e32 v227, v188
	v_mul_f32_e32 v188, v197, v217
	v_exp_f32_e32 v228, v188
	v_mul_f32_e32 v188, v197, v218
	v_exp_f32_e32 v229, v188
	v_cvt_f32_u32_e32 v188, v216
	v_add_u32_e32 v217, -1, v216
	v_cvt_f32_u32_e32 v217, v217
	v_subrev_u32_e32 v233, 32, v216
	v_mul_f32_e32 v188, v197, v188
	v_exp_f32_e32 v230, v188
	v_mul_f32_e32 v188, v197, v217
	v_exp_f32_e32 v231, v188
	v_add_u32_e32 v188, -2, v216
	v_cvt_f32_u32_e32 v188, v188
	v_add_u32_e32 v217, -3, v216
	v_cvt_f32_u32_e32 v217, v217
	v_subrev_u32_e32 v218, 33, v216
	v_mul_f32_e32 v188, v197, v188
	v_exp_f32_e32 v232, v188
	v_mul_f32_e32 v188, v197, v217
	v_cvt_f32_u32_e32 v217, v233
	v_cvt_f32_u32_e32 v218, v218
	v_exp_f32_e32 v234, v188
	v_subrev_u32_e32 v238, 48, v216
	v_mul_f32_e32 v188, v197, v217
	v_subrev_u32_e32 v217, 34, v216
	v_cvt_f32_u32_e32 v217, v217
	v_exp_f32_e32 v235, v188
	v_mul_f32_e32 v188, v197, v218
	v_subrev_u32_e32 v218, 35, v216
	v_cvt_f32_u32_e32 v218, v218
	v_exp_f32_e32 v236, v188
	v_mul_f32_e32 v188, v197, v217
	v_cvt_f32_u32_e32 v217, v238
	v_exp_f32_e32 v237, v188
	v_mul_f32_e32 v188, v197, v218
	v_subrev_u32_e32 v218, 49, v216
	v_cvt_f32_u32_e32 v218, v218
	v_exp_f32_e32 v239, v188
	v_mul_f32_e32 v188, v197, v217
	v_subrev_u32_e32 v217, 50, v216
	v_cmp_gt_u32_e32 vcc, s4, v216
	v_cvt_f32_u32_e32 v217, v217
	v_subrev_u32_e32 v216, 51, v216
	v_cvt_f32_u32_e32 v216, v216
	v_exp_f32_e32 v240, v188
	v_mul_f32_e32 v188, v197, v218
	v_exp_f32_e32 v243, v188
	v_mul_f32_e32 v188, v197, v217
	v_cmp_lt_i32_e64 s[4:5], -15, v224
	v_exp_f32_e32 v244, v188
	v_mul_f32_e32 v188, v197, v216
	v_exp_f32_e32 v245, v188
	s_barrier
	v_cmp_lt_i32_e64 s[6:7], -1, v207
	v_mov_b32_e32 v218, v248
	v_mov_b32_e32 v219, v250
	v_cndmask_b32_e64 v216, 0, v213, s[6:7]
	v_cmp_lt_i32_e64 s[6:7], 1, v207
	v_mov_b32_e32 v250, v249
	s_movk_i32 s12, 0xffef
	v_cndmask_b32_e64 v217, 0, v211, s[6:7]
	v_cmp_lt_i32_e64 s[6:7], 2, v207
	v_pk_mul_f32 v[216:217], v[216:217], v[218:219]
	v_lshlrev_b32_e32 v188, 3, v195
	v_cndmask_b32_e64 v219, 0, v221, s[6:7]
	v_cmp_lt_i32_e64 s[6:7], 0, v207
	s_nop 0
	v_and_b32_sdwa v213, v216, v178 dst_sel:DWORD dst_unused:UNUSED_PAD src0_sel:WORD_1 src1_sel:DWORD
	v_cndmask_b32_e64 v218, 0, v220, s[6:7]
	v_pk_mul_f32 v[218:219], v[218:219], v[250:251]
	v_add3_u32 v213, v216, v213, s81
	v_cvt_pk_bf16_f32 v211, v217, v217
	s_nop 0
	s_nop 0
	v_cvt_pk_bf16_f32 v216, v219, v219
	v_cvt_pk_bf16_f32 v217, v218, v218
	v_cmp_lt_i32_e64 s[6:7], -15, v207
	v_and_b32_e32 v216, 0xffff0000, v216
	v_and_b32_e32 v218, 0xffff0000, v217
	v_cndmask_b32_e64 v219, 0, v223, s[6:7]
	v_cmp_lt_i32_e64 s[6:7], s12, v207
	v_or_b32_sdwa v217, v216, v211 dst_sel:DWORD dst_unused:UNUSED_PAD src0_sel:DWORD src1_sel:WORD_1
	v_or_b32_sdwa v216, v218, v213 dst_sel:DWORD dst_unused:UNUSED_PAD src0_sel:DWORD src1_sel:WORD_1
	v_cndmask_b32_e64 v218, 0, v215, s[6:7]
	v_mov_b32_e32 v220, v172
	v_mov_b32_e32 v221, v174
	v_cmp_lt_i32_e64 s[6:7], -14, v207
	v_pk_mul_f32 v[218:219], v[218:219], v[220:221]
	v_mov_b32_e32 v174, v173
	v_cndmask_b32_e64 v221, 0, v225, s[6:7]
	v_cmp_lt_i32_e64 s[6:7], -16, v207
	v_mul_lo_u32 v199, v199, s94
	v_add3_u32 v246, v242, v188, v199
	v_cndmask_b32_e64 v220, 0, v222, s[6:7]
	v_pk_mul_f32 v[172:173], v[220:221], v[174:175]
	s_nop 0
	v_and_b32_sdwa v211, v172, v178 dst_sel:DWORD dst_unused:UNUSED_PAD src0_sel:WORD_1 src1_sel:DWORD
	s_nop 0
	v_add3_u32 v172, v172, v211, s81
	s_nop 0
	v_cvt_pk_bf16_f32 v175, v218, v218
	v_cvt_pk_bf16_f32 v173, v173, v173
	v_and_b32_e32 v172, 0xffff0000, v172
	v_cmp_lt_i32_e64 s[6:7], 1, v224
	v_cvt_pk_bf16_f32 v174, v219, v219
	v_and_b32_e32 v173, 0xffff0000, v173
	v_or_b32_sdwa v172, v172, v175 dst_sel:DWORD dst_unused:UNUSED_PAD src0_sel:DWORD src1_sel:WORD_1
	v_cndmask_b32_e64 v175, 0, v228, s[6:7]
	v_cmp_lt_i32_e64 s[6:7], -1, v224
	v_or_b32_sdwa v173, v173, v174 dst_sel:DWORD dst_unused:UNUSED_PAD src0_sel:DWORD src1_sel:WORD_1
	v_mov_b32_e32 v218, v168
	v_cndmask_b32_e64 v174, 0, v226, s[6:7]
	v_mov_b32_e32 v219, v170
	v_cmp_lt_i32_e64 s[6:7], 2, v224
; __device__ __forceinline__ unsigned pack2(float a, float b) { return (unsigned)f2bf(a) | ((unsigned)f2bf(b) << 16); }
; __device__ __forceinline__ float fexp2(float x) { return __builtin_amdgcn_exp2f(x); }
; #define SCHED __builtin_amdgcn_sched_barrier(0)
; __device__ __forceinline__ void ret_core_phase(const Params& p, const PD& d, char* shm, const int wave_s) {
;     ...
;       for (int jf = 0; jf < 4; ++jf)
; #pragma unroll
;         for (int f = 0; f < 2; ++f)
; #pragma unroll
;           for (int r = 0; r < 4; ++r) {
;             int j = 64 * wj + 16 * jf + 4 * fqv + r, i = 32 * wi + 16 * f + frv;
;             int df = i - j;
;             float fac = (df >= 0) ? fexp2(lg2v * (float)df) : 0.0f;
;             PT[jf][f][r] *= fac;
;           }
;       __syncthreads();
;       SCHED;
; #pragma unroll
;       for (int jf = 0; jf < 4; ++jf)
; #pragma unroll
;         for (int f = 0; f < 2; ++f) {
;           uint2 pk; pk.x = pack2(PT[jf][f][0], PT[jf][f][1]); pk.y = pack2(PT[jf][f][2], PT[jf][f][3]);
;           *(uint2*)(Pl + (32 * wi + 16 * f + frv) * 272 + (64 * wj + 16 * jf + 4 * fqv) * 2) = pk;
;         }
; #pragma unroll
;       for (int i = 0; i < 4; ++i) {
;         int c = i * 512 + tidv, row = c >> 4, cc = c & 15;
;         *(bf16x8*)(Vl + row * 272 + cc * 16) = vpre[i];
	v_pk_mul_f32 v[174:175], v[174:175], v[218:219]
	v_mov_b32_e32 v170, v169
	v_cndmask_b32_e64 v219, 0, v229, s[6:7]
	v_cmp_lt_i32_e64 s[6:7], 0, v224
	v_add_u32_e32 v0, 0, v0
	s_nop 0
	v_cndmask_b32_e64 v218, 0, v227, s[6:7]
	v_pk_mul_f32 v[168:169], v[218:219], v[170:171]
	s_nop 0
	s_nop 0
	v_cvt_pk_bf16_f32 v171, v174, v174
	v_cvt_pk_bf16_f32 v170, v175, v175
	v_and_b32_sdwa v174, v169, v178 dst_sel:DWORD dst_unused:UNUSED_PAD src0_sel:WORD_1 src1_sel:DWORD
	v_and_b32_sdwa v175, v168, v178 dst_sel:DWORD dst_unused:UNUSED_PAD src0_sel:WORD_1 src1_sel:DWORD
	v_add3_u32 v169, v169, v174, s81
	v_add3_u32 v168, v168, v175, s81
	v_and_b32_e32 v169, 0xffff0000, v169
	v_and_b32_e32 v168, 0xffff0000, v168
	v_or_b32_sdwa v169, v169, v170 dst_sel:DWORD dst_unused:UNUSED_PAD src0_sel:DWORD src1_sel:WORD_1
	v_or_b32_sdwa v168, v168, v171 dst_sel:DWORD dst_unused:UNUSED_PAD src0_sel:DWORD src1_sel:WORD_1
	ds_write2_b64 v246, v[216:217], v[168:169] offset1:4
	v_cndmask_b32_e32 v168, 0, v230, vcc
	v_cndmask_b32_e64 v169, 0, v232, s[4:5]
	v_mov_b32_e32 v170, v164
	v_mov_b32_e32 v171, v166
	v_cmp_lt_i32_e32 vcc, -14, v224
	v_pk_mul_f32 v[168:169], v[168:169], v[170:171]
	v_mov_b32_e32 v166, v165
	v_cndmask_b32_e32 v171, 0, v234, vcc
	v_cmp_lt_i32_e32 vcc, -16, v224
	s_nop 1
	v_cndmask_b32_e32 v170, 0, v231, vcc
	v_pk_mul_f32 v[164:165], v[170:171], v[166:167]
	s_nop 0
	s_nop 0
	v_cvt_pk_bf16_f32 v167, v168, v168
	v_cvt_pk_bf16_f32 v166, v169, v169
	s_nop 0
	s_nop 0
	v_cvt_pk_bf16_f32 v165, v165, v165
	v_cvt_pk_bf16_f32 v164, v164, v164
	v_and_b32_e32 v165, 0xffff0000, v165
	v_and_b32_e32 v164, 0xffff0000, v164
	v_or_b32_sdwa v165, v165, v166 dst_sel:DWORD dst_unused:UNUSED_PAD src0_sel:DWORD src1_sel:WORD_1
	v_or_b32_sdwa v164, v164, v167 dst_sel:DWORD dst_unused:UNUSED_PAD src0_sel:DWORD src1_sel:WORD_1
	v_add_u32_e32 v168, 0x1000, v246
	v_cmp_lt_i32_e32 vcc, 1, v233
	ds_write2_b64 v168, v[172:173], v[164:165] offset0:32 offset1:36
	v_mov_b32_e32 v166, v136
	v_cndmask_b32_e32 v165, 0, v237, vcc
	v_cmp_lt_i32_e32 vcc, -1, v233
	v_mov_b32_e32 v167, v138
	v_mov_b32_e32 v138, v137
	v_cndmask_b32_e32 v164, 0, v235, vcc
	v_cmp_lt_i32_e32 vcc, 2, v233
	v_pk_mul_f32 v[164:165], v[164:165], v[166:167]
	s_nop 0
	v_cndmask_b32_e32 v167, 0, v239, vcc
	v_cmp_lt_i32_e32 vcc, 0, v233
	s_nop 1
	v_cndmask_b32_e32 v166, 0, v236, vcc
	v_pk_mul_f32 v[136:137], v[166:167], v[138:139]
	s_nop 0
	s_nop 0
	v_cvt_pk_bf16_f32 v138, v165, v165
	s_nop 0
	v_cvt_pk_bf16_f32 v139, v164, v164
	s_nop 0
	v_cvt_pk_bf16_f32 v136, v136, v136
	v_cvt_pk_bf16_f32 v137, v137, v137
	v_and_b32_e32 v136, 0xffff0000, v136
	v_cmp_lt_i32_e32 vcc, -15, v233
	v_and_b32_e32 v137, 0xffff0000, v137
	v_or_b32_sdwa v136, v136, v139 dst_sel:DWORD dst_unused:UNUSED_PAD src0_sel:DWORD src1_sel:WORD_1
	v_cndmask_b32_e32 v139, 0, v228, vcc
	v_cmp_lt_i32_e32 vcc, s12, v233
	v_or_b32_sdwa v137, v137, v138 dst_sel:DWORD dst_unused:UNUSED_PAD src0_sel:DWORD src1_sel:WORD_1
	v_mov_b32_e32 v164, v128
	v_cndmask_b32_e32 v138, 0, v226, vcc
	v_mov_b32_e32 v165, v130
	v_cmp_lt_i32_e32 vcc, -14, v233
	v_pk_mul_f32 v[138:139], v[138:139], v[164:165]
	v_mov_b32_e32 v130, v129
	v_cndmask_b32_e32 v165, 0, v229, vcc
	v_cmp_lt_i32_e32 vcc, -16, v233
	s_nop 1
	v_cndmask_b32_e32 v164, 0, v227, vcc
	v_pk_mul_f32 v[128:129], v[164:165], v[130:131]
	s_nop 0
	s_nop 0
	v_cvt_pk_bf16_f32 v130, v139, v139
	s_nop 0
	v_cvt_pk_bf16_f32 v131, v138, v138
	s_nop 0
	v_cvt_pk_bf16_f32 v128, v128, v128
	v_cvt_pk_bf16_f32 v129, v129, v129
	v_and_b32_e32 v128, 0xffff0000, v128
	v_cmp_lt_i32_e32 vcc, 1, v238
	v_and_b32_e32 v129, 0xffff0000, v129
	v_or_b32_sdwa v128, v128, v131 dst_sel:DWORD dst_unused:UNUSED_PAD src0_sel:DWORD src1_sel:WORD_1
	v_cndmask_b32_e32 v131, 0, v244, vcc
	v_cmp_lt_i32_e32 vcc, -1, v238
	v_or_b32_sdwa v129, v129, v130 dst_sel:DWORD dst_unused:UNUSED_PAD src0_sel:DWORD src1_sel:WORD_1
	v_mov_b32_e32 v138, v132
	v_cndmask_b32_e32 v130, 0, v240, vcc
	v_mov_b32_e32 v139, v134
	v_cmp_lt_i32_e32 vcc, 2, v238
	v_pk_mul_f32 v[130:131], v[130:131], v[138:139]
	v_mov_b32_e32 v134, v133
	v_cndmask_b32_e32 v139, 0, v245, vcc
	v_cmp_lt_i32_e32 vcc, 0, v238
	s_nop 1
	v_cndmask_b32_e32 v138, 0, v243, vcc
	v_pk_mul_f32 v[132:133], v[138:139], v[134:135]
	s_nop 0
	s_nop 0
	v_cvt_pk_bf16_f32 v130, v130, v130
	v_cvt_pk_bf16_f32 v131, v131, v131
	s_nop 0
	s_nop 0
	v_cvt_pk_bf16_f32 v133, v133, v133
	v_cvt_pk_bf16_f32 v132, v132, v132
	v_and_b32_e32 v133, 0xffff0000, v133
	v_and_b32_e32 v132, 0xffff0000, v132
	v_or_b32_sdwa v131, v133, v131 dst_sel:DWORD dst_unused:UNUSED_PAD src0_sel:DWORD src1_sel:WORD_1
	v_or_b32_sdwa v130, v132, v130 dst_sel:DWORD dst_unused:UNUSED_PAD src0_sel:DWORD src1_sel:WORD_1
	v_cmp_lt_i32_e32 vcc, -15, v238
	ds_write2_b64 v246, v[136:137], v[130:131] offset0:8 offset1:12
	v_mov_b32_e32 v132, v124
	v_cndmask_b32_e32 v131, 0, v237, vcc
	v_cmp_lt_i32_e32 vcc, s12, v238
	v_mov_b32_e32 v133, v126
	v_mov_b32_e32 v126, v125
	v_cndmask_b32_e32 v130, 0, v235, vcc
	v_cmp_lt_i32_e32 vcc, -14, v238
	v_pk_mul_f32 v[130:131], v[130:131], v[132:133]
	s_nop 0
	v_cndmask_b32_e32 v133, 0, v239, vcc
	v_cmp_lt_i32_e32 vcc, -16, v238
	s_nop 1
	v_cndmask_b32_e32 v132, 0, v236, vcc
	v_pk_mul_f32 v[124:125], v[132:133], v[126:127]
	s_nop 0
	s_nop 0
	v_cvt_pk_bf16_f32 v127, v130, v130
	v_cvt_pk_bf16_f32 v126, v131, v131
	v_and_b32_sdwa v130, v125, v178 dst_sel:DWORD dst_unused:UNUSED_PAD src0_sel:WORD_1 src1_sel:DWORD
	v_and_b32_sdwa v131, v124, v178 dst_sel:DWORD dst_unused:UNUSED_PAD src0_sel:WORD_1 src1_sel:DWORD
	v_add3_u32 v125, v125, v130, s81
	v_add3_u32 v124, v124, v131, s81
	v_and_b32_e32 v125, 0xffff0000, v125
	v_and_b32_e32 v124, 0xffff0000, v124
	v_or_b32_sdwa v125, v125, v126 dst_sel:DWORD dst_unused:UNUSED_PAD src0_sel:DWORD src1_sel:WORD_1
	v_or_b32_sdwa v124, v124, v127 dst_sel:DWORD dst_unused:UNUSED_PAD src0_sel:DWORD src1_sel:WORD_1
	ds_write2_b64 v168, v[128:129], v[124:125] offset0:40 offset1:44
	v_mad_u64_u32 v[124:125], s[4:5], v208, s94, v[0:1]
	s_waitcnt vmcnt(3)
; #define SCHED __builtin_amdgcn_sched_barrier(0)
; __device__ __forceinline__ void ret_core_phase(const Params& p, const PD& d, char* shm, const int wave_s) {
;     ...
;       for (int i = 0; i < 4; ++i) {
;         int c = i * 512 + tidv, row = c >> 4, cc = c & 15;
;         *(bf16x8*)(Vl + row * 272 + cc * 16) = vpre[i];
;       }
;       SCHED;
;       f32x4 OT[4][2];
; #pragma unroll
;       for (int a = 0; a < 4; ++a)
; #pragma unroll
;         for (int c = 0; c < 2; ++c) OT[a][c] = f32x4{0.f, 0.f, 0.f, 0.f};
; #pragma unroll
;       for (int ks = 0; ks < 8; ++ks) {
; #pragma unroll
;         for (int vf = 0; vf < 4; ++vf) {
;           bf16x8 Sf = *(const bf16x8*)(R2 + (64 * wj + 16 * vf + frv) * 528 + (ks * 32 + fqv * 8) * 2);
; #pragma unroll
;           for (int f = 0; f < 2; ++f) OT[vf][f] = __builtin_amdgcn_mfma_f32_16x16x32_bf16(Sf, Qf[f][ks], OT[vf][f], 0, 0, 0);
;         }
;       }
	ds_write_b128 v124, v[100:103] offset:34816
	v_mad_u64_u32 v[100:101], s[4:5], v210, s94, v[0:1]
	s_waitcnt vmcnt(2)
	ds_write_b128 v100, v[104:107] offset:34816
	v_mad_u64_u32 v[100:101], s[4:5], v212, s94, v[0:1]
	s_waitcnt vmcnt(1)
	ds_write_b128 v100, v[108:111] offset:34816
	v_mad_u64_u32 v[100:101], s[4:5], v214, s94, v[0:1]
	s_waitcnt vmcnt(0)
	ds_write_b128 v100, v[116:119] offset:34816
	v_add_u32_e32 v0, s73, v206
	v_mad_u32_u24 v164, v193, s29, v0
	v_add_u32_e32 v165, v0, v201
	v_add_u32_e32 v166, v0, v203
	v_add_u32_e32 v0, v0, v205
	ds_read_b128 v[100:103], v164
	ds_read_b128 v[132:135], v0
	ds_read_b128 v[108:111], v165
	ds_read_b128 v[124:127], v166
	s_waitcnt lgkmcnt(3)
	v_mfma_f32_16x16x32_bf16 v[104:107], v[100:103], v[156:159], 0
	s_waitcnt lgkmcnt(1)
	v_mfma_f32_16x16x32_bf16 v[116:119], v[108:111], v[156:159], 0
	s_waitcnt lgkmcnt(0)
	v_mfma_f32_16x16x32_bf16 v[128:131], v[124:127], v[156:159], 0
	v_mfma_f32_16x16x32_bf16 v[136:139], v[132:135], v[156:159], 0
	ds_read_b128 v[156:159], v164 offset:64
	v_mfma_f32_16x16x32_bf16 v[100:103], v[100:103], v[160:163], 0
	s_waitcnt lgkmcnt(0)
	v_mfma_f32_16x16x32_bf16 v[104:107], v[156:159], v[144:147], v[104:107]
	v_mfma_f32_16x16x32_bf16 v[100:103], v[156:159], v[152:155], v[100:103]
	ds_read_b128 v[156:159], v165 offset:64
	v_mfma_f32_16x16x32_bf16 v[108:111], v[108:111], v[160:163], 0
	s_waitcnt lgkmcnt(0)
	v_mfma_f32_16x16x32_bf16 v[116:119], v[156:159], v[144:147], v[116:119]
	v_mfma_f32_16x16x32_bf16 v[108:111], v[156:159], v[152:155], v[108:111]
	ds_read_b128 v[156:159], v166 offset:64
	v_mfma_f32_16x16x32_bf16 v[124:127], v[124:127], v[160:163], 0
	s_waitcnt lgkmcnt(0)
	v_mfma_f32_16x16x32_bf16 v[128:131], v[156:159], v[144:147], v[128:131]
	v_mfma_f32_16x16x32_bf16 v[124:127], v[156:159], v[152:155], v[124:127]
	ds_read_b128 v[156:159], v0 offset:64
	s_waitcnt lgkmcnt(0)
	v_mfma_f32_16x16x32_bf16 v[136:139], v[156:159], v[144:147], v[136:139]
	ds_read_b128 v[144:147], v164 offset:128
	s_waitcnt lgkmcnt(0)
	v_mfma_f32_16x16x32_bf16 v[104:107], v[144:147], v[140:143], v[104:107]
	v_mfma_f32_16x16x32_bf16 v[100:103], v[144:147], v[148:151], v[100:103]
	ds_read_b128 v[144:147], v165 offset:128
	s_waitcnt lgkmcnt(0)
	v_mfma_f32_16x16x32_bf16 v[116:119], v[144:147], v[140:143], v[116:119]
	v_mfma_f32_16x16x32_bf16 v[108:111], v[144:147], v[148:151], v[108:111]
	ds_read_b128 v[144:147], v166 offset:128
	s_waitcnt lgkmcnt(0)
	v_mfma_f32_16x16x32_bf16 v[128:131], v[144:147], v[140:143], v[128:131]
	v_mfma_f32_16x16x32_bf16 v[124:127], v[144:147], v[148:151], v[124:127]
	ds_read_b128 v[144:147], v0 offset:128
	s_waitcnt lgkmcnt(0)
	v_mfma_f32_16x16x32_bf16 v[136:139], v[144:147], v[140:143], v[136:139]
	ds_read_b128 v[140:143], v164 offset:192
	s_waitcnt lgkmcnt(0)
	v_mfma_f32_16x16x32_bf16 v[104:107], v[140:143], v[96:99], v[104:107]
	v_mfma_f32_16x16x32_bf16 v[100:103], v[140:143], v[120:123], v[100:103]
	ds_read_b128 v[140:143], v165 offset:192
	s_waitcnt lgkmcnt(0)
	v_mfma_f32_16x16x32_bf16 v[116:119], v[140:143], v[96:99], v[116:119]
	v_mfma_f32_16x16x32_bf16 v[108:111], v[140:143], v[120:123], v[108:111]
	ds_read_b128 v[140:143], v166 offset:192
	v_mfma_f32_16x16x32_bf16 v[132:135], v[132:135], v[160:163], 0
	s_waitcnt lgkmcnt(0)
	v_mfma_f32_16x16x32_bf16 v[128:131], v[140:143], v[96:99], v[128:131]
	v_mfma_f32_16x16x32_bf16 v[124:127], v[140:143], v[120:123], v[124:127]
	ds_read_b128 v[140:143], v0 offset:192
	v_mfma_f32_16x16x32_bf16 v[132:135], v[156:159], v[152:155], v[132:135]
	v_mfma_f32_16x16x32_bf16 v[132:135], v[144:147], v[148:151], v[132:135]
	s_waitcnt lgkmcnt(0)
	v_mfma_f32_16x16x32_bf16 v[120:123], v[140:143], v[120:123], v[132:135]
	v_mfma_f32_16x16x32_bf16 v[96:99], v[140:143], v[96:99], v[136:139]
	s_nop 4
	ds_read_b128 v[132:135], v164 offset:256
	s_waitcnt lgkmcnt(0)
	v_mfma_f32_16x16x32_bf16 v[104:107], v[132:135], v[92:95], v[104:107]
	v_mfma_f32_16x16x32_bf16 v[100:103], v[132:135], v[112:115], v[100:103]
	ds_read_b128 v[132:135], v165 offset:256
	s_waitcnt lgkmcnt(0)
	v_mfma_f32_16x16x32_bf16 v[116:119], v[132:135], v[92:95], v[116:119]
	v_mfma_f32_16x16x32_bf16 v[108:111], v[132:135], v[112:115], v[108:111]
	ds_read_b128 v[132:135], v166 offset:256
	s_waitcnt lgkmcnt(0)
	v_mfma_f32_16x16x32_bf16 v[128:131], v[132:135], v[92:95], v[128:131]
	v_mfma_f32_16x16x32_bf16 v[124:127], v[132:135], v[112:115], v[124:127]
	ds_read_b128 v[132:135], v0 offset:256
	s_waitcnt lgkmcnt(0)
	v_mfma_f32_16x16x32_bf16 v[92:95], v[132:135], v[92:95], v[96:99]
	v_mfma_f32_16x16x32_bf16 v[96:99], v[132:135], v[112:115], v[120:123]
	ds_read_b128 v[112:115], v164 offset:320
	s_waitcnt lgkmcnt(0)
	v_mfma_f32_16x16x32_bf16 v[104:107], v[112:115], v[80:83], v[104:107]
	v_mfma_f32_16x16x32_bf16 v[100:103], v[112:115], v[88:91], v[100:103]
	ds_read_b128 v[112:115], v165 offset:320
	s_waitcnt lgkmcnt(0)
	v_mfma_f32_16x16x32_bf16 v[116:119], v[112:115], v[80:83], v[116:119]
	v_mfma_f32_16x16x32_bf16 v[108:111], v[112:115], v[88:91], v[108:111]
	ds_read_b128 v[112:115], v166 offset:320
	s_waitcnt lgkmcnt(0)
	v_mfma_f32_16x16x32_bf16 v[120:123], v[112:115], v[80:83], v[128:131]
	v_mfma_f32_16x16x32_bf16 v[112:115], v[112:115], v[88:91], v[124:127]
	s_nop 2
	ds_read_b128 v[124:127], v0 offset:320
	s_waitcnt lgkmcnt(0)
	v_mfma_f32_16x16x32_bf16 v[80:83], v[124:127], v[80:83], v[92:95]
	s_nop 2
	ds_read_b128 v[92:95], v164 offset:384
	v_mfma_f32_16x16x32_bf16 v[88:91], v[124:127], v[88:91], v[96:99]
	s_waitcnt lgkmcnt(0)
	v_mfma_f32_16x16x32_bf16 v[96:99], v[92:95], v[76:79], v[104:107]
	v_mfma_f32_16x16x32_bf16 v[92:95], v[92:95], v[84:87], v[100:103]
	s_nop 2
	ds_read_b128 v[100:103], v165 offset:384
	s_waitcnt lgkmcnt(0)
; __device__ __forceinline__ float fexp2(float x) { return __builtin_amdgcn_exp2f(x); }
; #define SCHED __builtin_amdgcn_sched_barrier(0)
; __device__ __forceinline__ void ret_core_phase(const Params& p, const PD& d, char* shm, const int wave_s) {
;     ...
;       for (int ks = 0; ks < 8; ++ks) {
; #pragma unroll
;         for (int vf = 0; vf < 4; ++vf) {
;           bf16x8 Sf = *(const bf16x8*)(R2 + (64 * wj + 16 * vf + frv) * 528 + (ks * 32 + fqv * 8) * 2);
; #pragma unroll
;           for (int f = 0; f < 2; ++f) OT[vf][f] = __builtin_amdgcn_mfma_f32_16x16x32_bf16(Sf, Qf[f][ks], OT[vf][f], 0, 0, 0);
;         }
;       }
; #pragma unroll
;       for (int f = 0; f < 2; ++f) {
;         float qd = fexp2(lg2v * (float)(32 * wi + 16 * f + frv + 1));
; #pragma unroll
;         for (int vf = 0; vf < 4; ++vf) OT[vf][f] *= qd;
;       }
;       SCHED;
;       u16* got = GOb + (lt0 + 32 * wi + frv) * 2048 + hh * 512 + vs * 128 + 64 * wj + 4 * fqv;
;       uint2 gpre[4][2];
; #pragma unroll
;       for (int vf = 0; vf < 4; ++vf)
; #pragma unroll
;         for (int f = 0; f < 2; ++f) gpre[vf][f] = *(const uint2*)(got + f * 16 * 2048 + vf * 16);
;       bf16x8 ktf[4][4];
;       const u16* KTw = KTb + ((size_t)(bh * 16 + lc) * 256 + 64 * wi + frv) * 128 + fqv * 8;
; #pragma unroll
;       for (int ks = 0; ks < 2; ++ks)
; #pragma unroll
;         for (int df = 0; df < 4; ++df) ktf[ks][df] = *(const bf16x8*)(KTw + df * 16 * 128 + ks * 32);
;       __syncthreads();
	v_mfma_f32_16x16x32_bf16 v[104:107], v[100:103], v[76:79], v[116:119]
	v_mfma_f32_16x16x32_bf16 v[100:103], v[100:103], v[84:87], v[108:111]
	s_nop 2
	ds_read_b128 v[108:111], v166 offset:384
	s_waitcnt lgkmcnt(0)
	v_mfma_f32_16x16x32_bf16 v[116:119], v[108:111], v[76:79], v[120:123]
	v_mfma_f32_16x16x32_bf16 v[108:111], v[108:111], v[84:87], v[112:115]
	s_nop 2
	ds_read_b128 v[112:115], v0 offset:384
	s_waitcnt lgkmcnt(0)
	v_mfma_f32_16x16x32_bf16 v[76:79], v[112:115], v[76:79], v[80:83]
	v_mfma_f32_16x16x32_bf16 v[80:83], v[112:115], v[84:87], v[88:91]
	ds_read_b128 v[84:87], v164 offset:448
	s_waitcnt lgkmcnt(0)
	v_mfma_f32_16x16x32_bf16 v[88:91], v[84:87], v[68:71], v[96:99]
	v_mfma_f32_16x16x32_bf16 v[84:87], v[84:87], v[72:75], v[92:95]
	s_nop 2
	ds_read_b128 v[92:95], v165 offset:448
	s_waitcnt lgkmcnt(0)
	v_mfma_f32_16x16x32_bf16 v[96:99], v[92:95], v[68:71], v[104:107]
	v_mfma_f32_16x16x32_bf16 v[92:95], v[92:95], v[72:75], v[100:103]
	s_nop 2
	ds_read_b128 v[100:103], v166 offset:448
	s_waitcnt lgkmcnt(0)
	v_mfma_f32_16x16x32_bf16 v[104:107], v[100:103], v[68:71], v[116:119]
	v_mfma_f32_16x16x32_bf16 v[100:103], v[100:103], v[72:75], v[108:111]
	s_nop 2
	ds_read_b128 v[108:111], v0 offset:448
	v_or_b32_e32 v0, 1, v2
	s_waitcnt lgkmcnt(0)
	v_mfma_f32_16x16x32_bf16 v[68:71], v[108:111], v[68:71], v[76:79]
	s_nop 2
	v_add_u32_e32 v76, v189, v0
	v_cvt_f32_i32_e32 v0, v76
	v_mul_f32_e32 v0, v197, v0
	v_exp_f32_e32 v0, v0
	v_mfma_f32_16x16x32_bf16 v[72:75], v[108:111], v[72:75], v[80:83]
	v_mul_f32_e64 v110, v0, v90
	v_mul_f32_e64 v111, v0, v91
	v_pk_mul_f32 v[108:109], v[0:1], v[88:89] op_sel_hi:[0,1]
	v_pk_mul_f32 v[114:115], v[0:1], v[98:99] op_sel_hi:[0,1]
	v_pk_mul_f32 v[112:113], v[0:1], v[96:97] op_sel_hi:[0,1]
	v_pk_mul_f32 v[106:107], v[0:1], v[106:107] op_sel_hi:[0,1]
	v_pk_mul_f32 v[104:105], v[0:1], v[104:105] op_sel_hi:[0,1]
	v_pk_mul_f32 v[118:119], v[0:1], v[70:71] op_sel_hi:[0,1]
	v_pk_mul_f32 v[116:117], v[0:1], v[68:69] op_sel_hi:[0,1]
	v_add_u32_e32 v0, 16, v76
	v_cvt_f32_i32_e32 v0, v0
	v_mul_f32_e32 v0, v197, v0
	v_exp_f32_e32 v0, v0
	s_nop 0
	v_pk_mul_f32 v[122:123], v[0:1], v[86:87] op_sel_hi:[0,1]
	v_pk_mul_f32 v[120:121], v[0:1], v[84:85] op_sel_hi:[0,1]
	v_pk_mul_f32 v[126:127], v[0:1], v[94:95] op_sel_hi:[0,1]
	v_pk_mul_f32 v[124:125], v[0:1], v[92:93] op_sel_hi:[0,1]
	v_pk_mul_f32 v[102:103], v[0:1], v[102:103] op_sel_hi:[0,1]
	v_pk_mul_f32 v[100:101], v[0:1], v[100:101] op_sel_hi:[0,1]
	v_pk_mul_f32 v[130:131], v[0:1], v[74:75] op_sel_hi:[0,1]
	v_pk_mul_f32 v[128:129], v[0:1], v[72:73] op_sel_hi:[0,1]
	v_mov_b32_e32 v0, v189
	v_lshl_add_u64 v[68:69], v[176:177], 0, s[8:9]
	v_lshl_add_u64 v[152:153], v[68:69], 0, v[0:1]
	v_lshlrev_b64 v[68:69], 12, v[152:153]
	v_lshl_add_u64 v[68:69], v[180:181], 0, v[68:69]
	v_mov_b32_e32 v189, v1
	v_lshl_add_u64 v[148:149], v[68:69], 0, v[188:189]
	v_add_co_u32_e32 v68, vcc, s51, v148
	v_mov_b32_e32 v207, v1
	s_nop 0
	v_addc_co_u32_e32 v69, vcc, 0, v149, vcc
	global_load_dwordx2 v[158:159], v[148:149], off
	global_load_dwordx2 v[156:157], v[148:149], off offset:32
	global_load_dwordx2 v[154:155], v[148:149], off offset:64
	global_load_dwordx2 v[150:151], v[148:149], off offset:96
	global_load_dwordx2 v[146:147], v[68:69], off
	global_load_dwordx2 v[144:145], v[68:69], off offset:32
	global_load_dwordx2 v[142:143], v[68:69], off offset:64
	global_load_dwordx2 v[140:141], v[68:69], off offset:96
	v_lshl_add_u64 v[68:69], v[186:187], 0, v[0:1]
	v_lshlrev_b64 v[68:69], 8, v[68:69]
	v_lshl_add_u64 v[68:69], s[46:47], 0, v[68:69]
	v_lshl_add_u64 v[132:133], v[68:69], 0, v[206:207]
	s_movk_i32 s4, 0x1000
	v_add_co_u32_e32 v134, vcc, s4, v132
	s_movk_i32 s4, 0x2000
	s_nop 0
	v_addc_co_u32_e32 v135, vcc, 0, v133, vcc
	v_add_co_u32_e32 v136, vcc, s4, v132
	s_movk_i32 s4, 0x3000
	s_nop 0
	v_addc_co_u32_e32 v137, vcc, 0, v133, vcc
	v_add_co_u32_e32 v138, vcc, s4, v132
	s_nop 1
	v_addc_co_u32_e32 v139, vcc, 0, v133, vcc
	global_load_dwordx4 v[92:95], v[132:133], off
	global_load_dwordx4 v[80:83], v[132:133], off offset:64
	global_load_dwordx4 v[96:99], v[136:137], off offset:-4096
	global_load_dwordx4 v[76:79], v[134:135], off offset:64
	global_load_dwordx4 v[88:91], v[136:137], off
	global_load_dwordx4 v[72:75], v[136:137], off offset:64
	global_load_dwordx4 v[84:87], v[138:139], off
	global_load_dwordx4 v[68:71], v[138:139], off offset:64
	s_barrier
; __device__ __forceinline__ void ret_core_phase(const Params& p, const PD& d, char* shm, const int wave_s) {
;     ...
; #pragma unroll
;       for (int ks = 0; ks < 4; ++ks) {
;         bf16x8 Pf[2];
; #pragma unroll
;         for (int f = 0; f < 2; ++f) Pf[f] = *(const bf16x8*)(Pl + (32 * wi + 16 * f + frv) * 272 + (ks * 32 + fqv * 8) * 2);
; #pragma unroll
;         for (int vf = 0; vf < 4; ++vf) {
;           bf16x8 Vf = *(const bf16x8*)(Vl + (64 * wj + 16 * vf + frv) * 272 + (ks * 32 + fqv * 8) * 2);
; #pragma unroll
;           for (int f = 0; f < 2; ++f) OT[vf][f] = __builtin_amdgcn_mfma_f32_16x16x32_bf16(Vf, Pf[f], OT[vf][f], 0, 0, 0);
;         }
;       }
;       {
;         float* sst = p.sspart + ((lt0 + 32 * wi + frv) * 4 + hh) * 8 + vs * 2 + wj;
; #pragma unroll
;         for (int f = 0; f < 2; ++f) {
;           float ss = 0.f;
; #pragma unroll
;           for (int vf = 0; vf < 4; ++vf)
; #pragma unroll
;             for (int r = 0; r < 4; ++r) ss += OT[vf][f][r] * OT[vf][f][r];
;           ss += shfl_xor_l(ss, 16, fqv * 16 + frv); ss += shfl_xor_l(ss, 32, fqv * 16 + frv);
;           if (fqv == 0) sst[(16 * f) * 32] = ss;
	v_add_u32_e32 v189, v209, v199
	v_mad_u32_u24 v197, v193, s94, v209
	ds_read_b128 v[160:163], v189
	ds_read_b128 v[164:167], v189 offset:4352
	ds_read_b128 v[168:171], v197 offset:34816
	s_movk_i32 s4, 0x80
	v_lshlrev_b64 v[152:153], 7, v[152:153]
	v_lshl_add_u64 v[152:153], v[184:185], 0, v[152:153]
	v_cmp_eq_u32_e32 vcc, 0, v195
	s_waitcnt lgkmcnt(0)
	v_mfma_f32_16x16x32_bf16 v[108:111], v[168:171], v[160:163], v[108:111]
	v_mfma_f32_16x16x32_bf16 v[120:123], v[168:171], v[164:167], v[120:123]
	ds_read_b128 v[168:171], v197 offset:39168
	s_waitcnt lgkmcnt(0)
	v_mfma_f32_16x16x32_bf16 v[112:115], v[168:171], v[160:163], v[112:115]
	v_mfma_f32_16x16x32_bf16 v[124:127], v[168:171], v[164:167], v[124:127]
	ds_read_b128 v[168:171], v197 offset:43520
	s_waitcnt lgkmcnt(0)
	v_mfma_f32_16x16x32_bf16 v[104:107], v[168:171], v[160:163], v[104:107]
	v_mfma_f32_16x16x32_bf16 v[100:103], v[168:171], v[164:167], v[100:103]
	ds_read_b128 v[168:171], v197 offset:47872
	s_waitcnt lgkmcnt(0)
	v_mfma_f32_16x16x32_bf16 v[116:119], v[168:171], v[160:163], v[116:119]
	v_mfma_f32_16x16x32_bf16 v[128:131], v[168:171], v[164:167], v[128:131]
	ds_read_b128 v[160:163], v189 offset:64
	ds_read_b128 v[164:167], v189 offset:4416
	ds_read_b128 v[168:171], v197 offset:34880
	s_waitcnt lgkmcnt(0)
	v_mfma_f32_16x16x32_bf16 v[108:111], v[168:171], v[160:163], v[108:111]
	v_mfma_f32_16x16x32_bf16 v[120:123], v[168:171], v[164:167], v[120:123]
	ds_read_b128 v[168:171], v197 offset:39232
	s_waitcnt lgkmcnt(0)
	v_mfma_f32_16x16x32_bf16 v[112:115], v[168:171], v[160:163], v[112:115]
	v_mfma_f32_16x16x32_bf16 v[124:127], v[168:171], v[164:167], v[124:127]
	ds_read_b128 v[168:171], v197 offset:43584
	s_waitcnt lgkmcnt(0)
	v_mfma_f32_16x16x32_bf16 v[104:107], v[168:171], v[160:163], v[104:107]
	v_mfma_f32_16x16x32_bf16 v[100:103], v[168:171], v[164:167], v[100:103]
	ds_read_b128 v[168:171], v197 offset:47936
	s_waitcnt lgkmcnt(0)
	v_mfma_f32_16x16x32_bf16 v[116:119], v[168:171], v[160:163], v[116:119]
	v_mfma_f32_16x16x32_bf16 v[128:131], v[168:171], v[164:167], v[128:131]
	ds_read_b128 v[160:163], v189 offset:128
	ds_read_b128 v[164:167], v189 offset:4480
	ds_read_b128 v[168:171], v197 offset:34944
	s_waitcnt lgkmcnt(0)
	v_mfma_f32_16x16x32_bf16 v[108:111], v[168:171], v[160:163], v[108:111]
	v_mfma_f32_16x16x32_bf16 v[120:123], v[168:171], v[164:167], v[120:123]
	ds_read_b128 v[168:171], v197 offset:39296
	s_waitcnt lgkmcnt(0)
	v_mfma_f32_16x16x32_bf16 v[172:175], v[168:171], v[160:163], v[112:115]
	s_nop 2
	ds_read_b128 v[112:115], v197 offset:43648
	s_waitcnt lgkmcnt(0)
	v_mfma_f32_16x16x32_bf16 v[104:107], v[112:115], v[160:163], v[104:107]
	v_mfma_f32_16x16x32_bf16 v[100:103], v[112:115], v[164:167], v[100:103]
	ds_read_b128 v[112:115], v197 offset:48000
	v_mfma_f32_16x16x32_bf16 v[168:171], v[168:171], v[164:167], v[124:127]
	s_waitcnt lgkmcnt(0)
	v_mfma_f32_16x16x32_bf16 v[116:119], v[112:115], v[160:163], v[116:119]
	v_mfma_f32_16x16x32_bf16 v[160:163], v[112:115], v[164:167], v[128:131]
	ds_read_b128 v[164:167], v189 offset:192
	ds_read_b128 v[210:213], v189 offset:4544
	ds_read_b128 v[112:115], v197 offset:35008
	s_waitcnt lgkmcnt(0)
	v_mfma_f32_16x16x32_bf16 v[128:131], v[112:115], v[164:167], v[108:111]
	s_nop 2
	ds_read_b128 v[108:111], v197 offset:39360
	s_waitcnt lgkmcnt(0)
	v_mfma_f32_16x16x32_bf16 v[124:127], v[108:111], v[164:167], v[172:175]
	v_mfma_f32_16x16x32_bf16 v[108:111], v[108:111], v[210:213], v[168:171]
	s_nop 2
	ds_read_b128 v[168:171], v197 offset:43712
	v_mfma_f32_16x16x32_bf16 v[112:115], v[112:115], v[210:213], v[120:123]
	s_waitcnt lgkmcnt(0)
	v_mfma_f32_16x16x32_bf16 v[120:123], v[168:171], v[164:167], v[104:107]
	v_mfma_f32_16x16x32_bf16 v[104:107], v[168:171], v[210:213], v[100:103]
	s_nop 2
	ds_read_b128 v[100:103], v197 offset:48064
	s_waitcnt lgkmcnt(0)
	v_mfma_f32_16x16x32_bf16 v[116:119], v[100:103], v[164:167], v[116:119]
	v_mfma_f32_16x16x32_bf16 v[100:103], v[100:103], v[210:213], v[160:163]
	s_nop 2
	v_mul_f32_e32 v162, v129, v129
	v_fmac_f32_e32 v162, v128, v128
	v_fmac_f32_e32 v162, v130, v130
	v_fmac_f32_e32 v162, v131, v131
	v_fmac_f32_e32 v162, v124, v124
	v_fmac_f32_e32 v162, v125, v125
	v_fmac_f32_e32 v162, v126, v126
	v_fmac_f32_e32 v162, v127, v127
	v_fmac_f32_e32 v162, v120, v120
	v_fmac_f32_e32 v162, v121, v121
	v_fmac_f32_e32 v162, v122, v122
	v_fmac_f32_e32 v162, v123, v123
	v_fmac_f32_e32 v162, v116, v116
	v_fmac_f32_e32 v162, v117, v117
	v_lshlrev_b32_e32 v160, 2, v191
	v_fmac_f32_e32 v162, v118, v118
	v_bitop3_b32 v161, v160, 64, v179 bitop3:0x6c
	v_fmac_f32_e32 v162, v119, v119
	ds_bpermute_b32 v163, v161, v162
	v_bitop3_b32 v160, v160, s4, v179 bitop3:0x6c
	s_waitcnt lgkmcnt(0)
	v_add_f32_e32 v162, v162, v163
	ds_bpermute_b32 v163, v160, v162
	s_and_saveexec_b64 s[4:5], vcc
	s_cbranch_execz .LBB0_565
	s_waitcnt lgkmcnt(0)
	v_add_f32_e32 v162, v162, v163
	global_store_dword v[152:153], v162, off
; __device__ __forceinline__ unsigned pack2(float a, float b) { return (unsigned)f2bf(a) | ((unsigned)f2bf(b) << 16); }
; __device__ __forceinline__ void ret_core_phase(const Params& p, const PD& d, char* shm, const int wave_s) {
;     ...
;         for (int f = 0; f < 2; ++f) {
;           float ss = 0.f;
; #pragma unroll
;           for (int vf = 0; vf < 4; ++vf)
; #pragma unroll
;             for (int r = 0; r < 4; ++r) ss += OT[vf][f][r] * OT[vf][f][r];
;           ss += shfl_xor_l(ss, 16, fqv * 16 + frv); ss += shfl_xor_l(ss, 32, fqv * 16 + frv);
;           if (fqv == 0) sst[(16 * f) * 32] = ss;
; #pragma unroll
;           for (int vf = 0; vf < 4; ++vf) {
;             uint2 gq = gpre[vf][f];
;             float g0 = __uint_as_float(gq.x << 16), g1 = __uint_as_float(gq.x & 0xffff0000u);
;             float g2 = __uint_as_float(gq.y << 16), g3 = __uint_as_float(gq.y & 0xffff0000u);
;             uint2 o;
;             o.x = pack2(silu_f(g0) * OT[vf][f][0], silu_f(g1) * OT[vf][f][1]);
;             o.y = pack2(silu_f(g2) * OT[vf][f][2], silu_f(g3) * OT[vf][f][3]);
;             *(uint2*)(got + f * 16 * 2048 + vf * 16) = o;
;           }
.LBB0_565:
	s_or_b64 exec, exec, s[4:5]
	s_waitcnt vmcnt(15)
	v_lshlrev_b32_e32 v162, 16, v158
	v_and_b32_e32 v158, 0xffff0000, v158
	v_mul_f32_e32 v165, 0xbfb8aa3b, v158
	v_exp_f32_e32 v165, v165
	s_waitcnt lgkmcnt(0)
	v_lshlrev_b32_e32 v163, 16, v159
	v_mul_f32_e32 v164, 0xbfb8aa3b, v162
	v_exp_f32_e32 v164, v164
	v_add_f32_e32 v165, 1.0, v165
	v_rcp_f32_e32 v166, v165
	v_mul_f32_e32 v165, 0xbfb8aa3b, v163
	v_exp_f32_e32 v165, v165
	v_add_f32_e32 v164, 1.0, v164
	v_rcp_f32_e32 v164, v164
	v_and_b32_e32 v159, 0xffff0000, v159
	v_add_f32_e32 v165, 1.0, v165
	v_rcp_f32_e32 v165, v165
	s_nop 0
	v_pk_mul_f32 v[162:163], v[164:165], v[162:163]
	v_mov_b32_e32 v164, v128
	v_mul_f32_e32 v128, 0xbfb8aa3b, v159
	v_exp_f32_e32 v128, v128
	v_mov_b32_e32 v165, v130
	v_mov_b32_e32 v130, v129
	v_pk_mul_f32 v[162:163], v[162:163], v[164:165]
	v_add_f32_e32 v128, 1.0, v128
	v_rcp_f32_e32 v167, v128
	s_nop 0
	v_pk_mul_f32 v[158:159], v[166:167], v[158:159]
	s_nop 0
	v_pk_mul_f32 v[128:129], v[158:159], v[130:131]
	s_nop 0
	s_nop 0
	s_nop 0
	s_nop 0
	v_cvt_pk_bf16_f32 v129, v129, v129
	v_cvt_pk_bf16_f32 v128, v128, v128
	v_cvt_pk_bf16_f32 v131, v162, v162
	v_cvt_pk_bf16_f32 v130, v163, v163
	v_and_b32_e32 v129, 0xffff0000, v129
	v_and_b32_e32 v128, 0xffff0000, v128
	v_or_b32_sdwa v129, v129, v130 dst_sel:DWORD dst_unused:UNUSED_PAD src0_sel:DWORD src1_sel:WORD_1
	v_or_b32_sdwa v128, v128, v131 dst_sel:DWORD dst_unused:UNUSED_PAD src0_sel:DWORD src1_sel:WORD_1
	s_waitcnt vmcnt(14)
	v_and_b32_e32 v130, 0xffff0000, v156
	global_store_dwordx2 v[148:149], v[128:129], off
	v_lshlrev_b32_e32 v129, 16, v157
	v_and_b32_e32 v131, 0xffff0000, v157
	v_mul_f32_e32 v157, 0xbfb8aa3b, v130
	v_exp_f32_e32 v157, v157
	v_lshlrev_b32_e32 v128, 16, v156
	v_mul_f32_e32 v156, 0xbfb8aa3b, v128
	v_exp_f32_e32 v156, v156
	v_add_f32_e32 v157, 1.0, v157
	v_rcp_f32_e32 v158, v157
	v_mul_f32_e32 v157, 0xbfb8aa3b, v129
	v_exp_f32_e32 v157, v157
	v_add_f32_e32 v156, 1.0, v156
	v_rcp_f32_e32 v156, v156
	v_add_f32_e32 v157, 1.0, v157
	v_rcp_f32_e32 v157, v157
	s_nop 0
	v_pk_mul_f32 v[128:129], v[156:157], v[128:129]
	v_mov_b32_e32 v156, v124
	v_mul_f32_e32 v124, 0xbfb8aa3b, v131
	v_exp_f32_e32 v124, v124
	v_mov_b32_e32 v157, v126
	v_pk_mul_f32 v[128:129], v[128:129], v[156:157]
	v_mov_b32_e32 v126, v125
	v_add_f32_e32 v124, 1.0, v124
	v_rcp_f32_e32 v159, v124
	s_nop 0
	v_pk_mul_f32 v[130:131], v[158:159], v[130:131]
	s_nop 0
	v_pk_mul_f32 v[124:125], v[130:131], v[126:127]
	s_nop 0
	v_cvt_pk_bf16_f32 v127, v128, v128
	s_nop 0
	s_nop 0
	v_cvt_pk_bf16_f32 v125, v125, v125
	v_cvt_pk_bf16_f32 v126, v129, v129
	v_and_b32_e32 v125, 0xffff0000, v125
	s_nop 0
	v_or_b32_sdwa v125, v125, v126 dst_sel:DWORD dst_unused:UNUSED_PAD src0_sel:DWORD src1_sel:WORD_1
	s_waitcnt vmcnt(14)
	v_and_b32_e32 v126, 0xffff0000, v154
	v_cvt_pk_bf16_f32 v124, v124, v124
	v_mul_f32_e32 v129, 0xbfb8aa3b, v126
	v_exp_f32_e32 v129, v129
	v_and_b32_e32 v124, 0xffff0000, v124
	v_or_b32_sdwa v124, v124, v127 dst_sel:DWORD dst_unused:UNUSED_PAD src0_sel:DWORD src1_sel:WORD_1
	global_store_dwordx2 v[148:149], v[124:125], off offset:32
	v_lshlrev_b32_e32 v125, 16, v155
	v_lshlrev_b32_e32 v124, 16, v154
	v_add_f32_e32 v129, 1.0, v129
	v_mul_f32_e32 v128, 0xbfb8aa3b, v124
	v_rcp_f32_e32 v130, v129
	v_mul_f32_e32 v129, 0xbfb8aa3b, v125
	v_exp_f32_e32 v128, v128
	v_exp_f32_e32 v129, v129
	v_and_b32_e32 v127, 0xffff0000, v155
	v_add_f32_e32 v128, 1.0, v128
	v_add_f32_e32 v129, 1.0, v129
	v_rcp_f32_e32 v128, v128
	v_rcp_f32_e32 v129, v129
	s_nop 0
	v_pk_mul_f32 v[124:125], v[128:129], v[124:125]
	v_mov_b32_e32 v128, v120
	v_mul_f32_e32 v120, 0xbfb8aa3b, v127
	v_exp_f32_e32 v120, v120
	v_mov_b32_e32 v129, v122
	v_pk_mul_f32 v[124:125], v[124:125], v[128:129]
	v_mov_b32_e32 v122, v121
	v_add_f32_e32 v120, 1.0, v120
	v_rcp_f32_e32 v131, v120
	s_nop 0
	v_pk_mul_f32 v[126:127], v[130:131], v[126:127]
	s_nop 0
	v_pk_mul_f32 v[120:121], v[126:127], v[122:123]
	s_nop 0
	v_cvt_pk_bf16_f32 v123, v124, v124
	s_nop 0
	s_nop 0
	v_cvt_pk_bf16_f32 v121, v121, v121
	v_cvt_pk_bf16_f32 v122, v125, v125
	v_and_b32_e32 v121, 0xffff0000, v121
	s_nop 0
	v_or_b32_sdwa v121, v121, v122 dst_sel:DWORD dst_unused:UNUSED_PAD src0_sel:DWORD src1_sel:WORD_1
	s_waitcnt vmcnt(14)
	v_and_b32_e32 v122, 0xffff0000, v150
	v_cvt_pk_bf16_f32 v120, v120, v120
	v_mul_f32_e32 v125, 0xbfb8aa3b, v122
	v_exp_f32_e32 v125, v125
	v_and_b32_e32 v120, 0xffff0000, v120
	v_or_b32_sdwa v120, v120, v123 dst_sel:DWORD dst_unused:UNUSED_PAD src0_sel:DWORD src1_sel:WORD_1
	global_store_dwordx2 v[148:149], v[120:121], off offset:64
	v_lshlrev_b32_e32 v121, 16, v151
	v_lshlrev_b32_e32 v120, 16, v150
	v_add_f32_e32 v125, 1.0, v125
	v_mul_f32_e32 v124, 0xbfb8aa3b, v120
	v_rcp_f32_e32 v126, v125
	v_mul_f32_e32 v125, 0xbfb8aa3b, v121
	v_exp_f32_e32 v124, v124
	v_exp_f32_e32 v125, v125
	v_and_b32_e32 v123, 0xffff0000, v151
	v_add_f32_e32 v124, 1.0, v124
	v_add_f32_e32 v125, 1.0, v125
	v_rcp_f32_e32 v124, v124
	v_rcp_f32_e32 v125, v125
	s_nop 0
	v_pk_mul_f32 v[120:121], v[124:125], v[120:121]
	v_mov_b32_e32 v124, v116
	v_mul_f32_e32 v116, 0xbfb8aa3b, v123
	v_exp_f32_e32 v116, v116
	v_mov_b32_e32 v125, v118
	v_pk_mul_f32 v[120:121], v[120:121], v[124:125]
	v_mov_b32_e32 v118, v117
	v_add_f32_e32 v116, 1.0, v116
	v_rcp_f32_e32 v127, v116
	s_nop 0
	v_pk_mul_f32 v[122:123], v[126:127], v[122:123]
	s_nop 0
	v_pk_mul_f32 v[116:117], v[122:123], v[118:119]
	v_and_b32_sdwa v118, v121, v178 dst_sel:DWORD dst_unused:UNUSED_PAD src0_sel:WORD_1 src1_sel:DWORD
	v_and_b32_sdwa v119, v120, v178 dst_sel:DWORD dst_unused:UNUSED_PAD src0_sel:WORD_1 src1_sel:DWORD
	v_add3_u32 v119, v120, v119, s81
	v_add3_u32 v118, v121, v118, s81
	v_and_b32_sdwa v120, v117, v178 dst_sel:DWORD dst_unused:UNUSED_PAD src0_sel:WORD_1 src1_sel:DWORD
	v_and_b32_sdwa v121, v116, v178 dst_sel:DWORD dst_unused:UNUSED_PAD src0_sel:WORD_1 src1_sel:DWORD
	v_add3_u32 v117, v117, v120, s81
	v_add3_u32 v116, v116, v121, s81
	v_and_b32_e32 v117, 0xffff0000, v117
	v_and_b32_e32 v116, 0xffff0000, v116
	v_or_b32_sdwa v117, v117, v118 dst_sel:DWORD dst_unused:UNUSED_PAD src0_sel:DWORD src1_sel:WORD_1
	v_or_b32_sdwa v116, v116, v119 dst_sel:DWORD dst_unused:UNUSED_PAD src0_sel:DWORD src1_sel:WORD_1
	global_store_dwordx2 v[148:149], v[116:117], off offset:96
	v_mul_f32_e32 v116, v113, v113
	v_fmac_f32_e32 v116, v112, v112
	v_fmac_f32_e32 v116, v114, v114
	v_fmac_f32_e32 v116, v115, v115
	v_fmac_f32_e32 v116, v108, v108
	v_fmac_f32_e32 v116, v109, v109
	v_fmac_f32_e32 v116, v110, v110
	v_fmac_f32_e32 v116, v111, v111
	v_fmac_f32_e32 v116, v104, v104
	v_fmac_f32_e32 v116, v105, v105
	v_fmac_f32_e32 v116, v106, v106
	v_fmac_f32_e32 v116, v107, v107
	v_fmac_f32_e32 v116, v100, v100
	v_fmac_f32_e32 v116, v101, v101
	v_fmac_f32_e32 v116, v102, v102
	v_fmac_f32_e32 v116, v103, v103
	ds_bpermute_b32 v117, v161, v116
	s_waitcnt lgkmcnt(0)
	v_add_f32_e32 v116, v116, v117
	ds_bpermute_b32 v117, v160, v116
	s_and_saveexec_b64 s[4:5], vcc
	s_cbranch_execz .LBB0_562
; __device__ __forceinline__ void ret_core_phase(const Params& p, const PD& d, char* shm, const int wave_s) {
;     ...
;           ss += shfl_xor_l(ss, 16, fqv * 16 + frv); ss += shfl_xor_l(ss, 32, fqv * 16 + frv);
;           if (fqv == 0) sst[(16 * f) * 32] = ss;
	s_waitcnt lgkmcnt(0)
	v_add_f32_e32 v116, v116, v117
	global_store_dword v[152:153], v116, off offset:2048
	s_branch .LBB0_562

; __device__ __forceinline__ unsigned pack2(float a, float b) { return (unsigned)f2bf(a) | ((unsigned)f2bf(b) << 16); }
; #define SCHED __builtin_amdgcn_sched_barrier(0)
; template <int EPI, bool HS = false>
; __device__ __forceinline__ void gemm_phase(const Params& p, const GemmCfg& g, char* shm, const int wave_s) {
;     ...
;       } else if (pn < 16) {
;         const int hh = (pn - 8) >> 1, vb = ((pn - 8) & 1) * 256;
;         u16* vt_t = VTb + ((size_t)((b * 4 + hh) * 16 + (mt & 7) * 2) * 512 + vb) * 128;
;         const unsigned kb = (unsigned)((wc * 32 + fr) * 128 + wr * 64 + fq * 4);
; #pragma unroll
;         for (int ai = 0; ai < 2; ++ai)
; #pragma unroll
;           for (int m = 0; m < 4; ++m) {
;             const f32x4 r4 = *(const f32x4*)(rsw + ai * 128 + m * 16);
; #pragma unroll
;             for (int bj = 0; bj < 2; ++bj)
; #pragma unroll
;               for (int n = 0; n < 2; ++n) {
;                 uint2 pk;
;                 pk.x = pack2(r4[0] * acc[ai][bj][m][n][0] + swv[bj][n], r4[1] * acc[ai][bj][m][n][1] + swv[bj][n]);
;                 pk.y = pack2(r4[2] * acc[ai][bj][m][n][2] + swv[bj][n], r4[3] * acc[ai][bj][m][n][3] + swv[bj][n]);
;                 *(uint2*)(vt_t + kb + ai * 512 * 128 + (bj * 128 + n * 16) * 128 + m * 16) = pk;
;               }
;             SCHED;
;           }
.LBB0_592:
	s_andn2_b64 vcc, exec, s[6:7]
	s_cbranch_vccnz .LBB0_594
	s_lshl_b32 s4, s2, 3
	s_and_b32 s4, s4, 0x70
	s_lshl_b32 s5, s3, 1
	s_lshl_b32 s1, s10, 6
	s_or_b32 s4, s4, s5
	ds_read_b128 v[148:151], v154
	s_add_i32 s4, s4, s1
	s_sub_i32 s4, s4, 64
	s_ashr_i32 s5, s4, 31
	s_lshl_b64 s[4:5], s[4:5], 17
	v_readlane_b32 s6, v252, 61
	v_readlane_b32 s7, v252, 62
	s_add_u32 s1, s6, s4
	s_waitcnt lgkmcnt(0)
	v_pk_mul_f32 v[132:133], v[124:125], v[150:151]
	v_pk_mul_f32 v[142:143], v[122:123], v[148:149]
	s_addc_u32 s5, s7, s5
	s_lshl_b32 s4, s2, 16
	v_mov_b32_e32 v144, v142
	v_mov_b32_e32 v145, v132
	s_and_b32 s4, s4, 0x10000
	v_lshl_add_u32 v0, v135, 7, v139
	v_pk_add_f32 v[144:145], v[138:139], v[144:145] op_sel_hi:[0,1]
	v_mov_b32_e32 v132, v143
	s_add_u32 s4, s1, s4
	v_or_b32_e32 v0, v0, v141
	v_pk_add_f32 v[132:133], v[138:139], v[132:133] op_sel_hi:[0,1]
	s_nop 0
	s_addc_u32 s5, s5, 0
	v_lshl_add_u32 v0, v137, 12, v0
	v_cvt_pk_bf16_f32 v142, v144, v144
	s_nop 0
	s_nop 0
	v_lshl_add_u64 v[130:131], v[0:1], 1, s[4:5]
	s_nop 0
	v_cvt_pk_bf16_f32 v133, v133, v133
	v_cvt_pk_bf16_f32 v132, v132, v132
	v_cvt_pk_bf16_f32 v0, v145, v145
	v_and_b32_e32 v133, 0xffff0000, v133
	v_and_b32_e32 v132, 0xffff0000, v132
	v_or_b32_sdwa v133, v133, v0 dst_sel:DWORD dst_unused:UNUSED_PAD src0_sel:DWORD src1_sel:WORD_1
	v_or_b32_sdwa v132, v132, v142 dst_sel:DWORD dst_unused:UNUSED_PAD src0_sel:DWORD src1_sel:WORD_1
	global_store_dwordx2 v[130:131], v[132:133], off
	v_pk_mul_f32 v[132:133], v[128:129], v[150:151]
	v_pk_mul_f32 v[142:143], v[126:127], v[148:149]
	v_mov_b32_e32 v145, v132
	v_mov_b32_e32 v144, v142
	v_pk_add_f32 v[144:145], v[140:141], v[144:145] op_sel_hi:[0,1]
	v_mov_b32_e32 v132, v143
	v_pk_add_f32 v[132:133], v[140:141], v[132:133] op_sel_hi:[0,1]
	s_nop 0
	v_cvt_pk_bf16_f32 v142, v144, v144
	s_nop 0
	s_nop 0
	v_cvt_pk_bf16_f32 v132, v132, v132
	s_nop 0
	v_cvt_pk_bf16_f32 v133, v133, v133
	v_and_b32_e32 v132, 0xffff0000, v132
	s_movk_i32 s1, 0x1000
	v_cvt_pk_bf16_f32 v0, v145, v145
	v_and_b32_e32 v133, 0xffff0000, v133
	v_or_b32_sdwa v132, v132, v142 dst_sel:DWORD dst_unused:UNUSED_PAD src0_sel:DWORD src1_sel:WORD_1
	v_add_co_u32_e32 v142, vcc, s1, v130
	v_or_b32_sdwa v133, v133, v0 dst_sel:DWORD dst_unused:UNUSED_PAD src0_sel:DWORD src1_sel:WORD_1
	s_nop 0
	v_addc_co_u32_e32 v143, vcc, 0, v131, vcc
	global_store_dwordx2 v[142:143], v[132:133], off
	v_pk_mul_f32 v[132:133], v[116:117], v[150:151]
	v_pk_mul_f32 v[144:145], v[114:115], v[148:149]
	v_mov_b32_e32 v153, v132
	v_mov_b32_e32 v152, v144
	v_pk_add_f32 v[152:153], v[134:135], v[152:153] op_sel_hi:[0,1]
	v_mov_b32_e32 v132, v145
	v_pk_add_f32 v[132:133], v[134:135], v[132:133] op_sel_hi:[0,1]
	s_nop 0
	v_cvt_pk_bf16_f32 v144, v152, v152
	s_nop 0
	v_cvt_pk_bf16_f32 v132, v132, v132
	v_and_b32_e32 v132, 0xffff0000, v132
	s_mov_b32 s1, 0x8000
	s_nop 0
	v_or_b32_sdwa v152, v132, v144 dst_sel:DWORD dst_unused:UNUSED_PAD src0_sel:DWORD src1_sel:WORD_1
	v_add_co_u32_e32 v144, vcc, s1, v130
	s_nop 0
	v_cvt_pk_bf16_f32 v133, v133, v133
	v_addc_co_u32_e32 v145, vcc, 0, v131, vcc
	v_cvt_pk_bf16_f32 v0, v153, v153
	v_and_b32_e32 v133, 0xffff0000, v133
	v_add_co_u32_e32 v132, vcc, s80, v130
	v_or_b32_sdwa v153, v133, v0 dst_sel:DWORD dst_unused:UNUSED_PAD src0_sel:DWORD src1_sel:WORD_1
	s_nop 0
	v_addc_co_u32_e32 v133, vcc, 0, v131, vcc
	v_pk_mul_f32 v[150:151], v[120:121], v[150:151]
	v_pk_mul_f32 v[148:149], v[118:119], v[148:149]
	global_store_dwordx2 v[132:133], v[152:153], off offset:-4096
	v_mov_b32_e32 v152, v148
	v_mov_b32_e32 v153, v150
	v_pk_add_f32 v[152:153], v[136:137], v[152:153] op_sel_hi:[0,1]
	v_mov_b32_e32 v150, v149
	v_pk_add_f32 v[148:149], v[136:137], v[150:151] op_sel_hi:[0,1]
	s_nop 0
	v_cvt_pk_bf16_f32 v150, v152, v152
	s_nop 0
	s_nop 0
	s_nop 0
	v_cvt_pk_bf16_f32 v149, v149, v149
	v_cvt_pk_bf16_f32 v148, v148, v148
	v_cvt_pk_bf16_f32 v0, v153, v153
	v_and_b32_e32 v149, 0xffff0000, v149
	v_and_b32_e32 v148, 0xffff0000, v148
	v_or_b32_sdwa v149, v149, v0 dst_sel:DWORD dst_unused:UNUSED_PAD src0_sel:DWORD src1_sel:WORD_1
	v_or_b32_sdwa v148, v148, v150 dst_sel:DWORD dst_unused:UNUSED_PAD src0_sel:DWORD src1_sel:WORD_1
	global_store_dwordx2 v[132:133], v[148:149], off
	ds_read_b128 v[148:151], v154 offset:64
	s_waitcnt lgkmcnt(0)
; __device__ __forceinline__ unsigned pack2(float a, float b) { return (unsigned)f2bf(a) | ((unsigned)f2bf(b) << 16); }
; #define SCHED __builtin_amdgcn_sched_barrier(0)
; template <int EPI, bool HS = false>
; __device__ __forceinline__ void gemm_phase(const Params& p, const GemmCfg& g, char* shm, const int wave_s) {
;     ...
; #pragma unroll
;         for (int ai = 0; ai < 2; ++ai)
; #pragma unroll
;           for (int m = 0; m < 4; ++m) {
;             const f32x4 r4 = *(const f32x4*)(rsw + ai * 128 + m * 16);
; #pragma unroll
;             for (int bj = 0; bj < 2; ++bj)
; #pragma unroll
;               for (int n = 0; n < 2; ++n) {
;                 uint2 pk;
;                 pk.x = pack2(r4[0] * acc[ai][bj][m][n][0] + swv[bj][n], r4[1] * acc[ai][bj][m][n][1] + swv[bj][n]);
;                 pk.y = pack2(r4[2] * acc[ai][bj][m][n][2] + swv[bj][n], r4[3] * acc[ai][bj][m][n][3] + swv[bj][n]);
;                 *(uint2*)(vt_t + kb + ai * 512 * 128 + (bj * 128 + n * 16) * 128 + m * 16) = pk;
;               }
;             SCHED;
;           }
	v_pk_mul_f32 v[152:153], v[108:109], v[150:151]
	v_pk_mul_f32 v[156:157], v[106:107], v[148:149]
	v_mov_b32_e32 v159, v152
	v_mov_b32_e32 v158, v156
	v_mov_b32_e32 v152, v157
	v_pk_add_f32 v[156:157], v[138:139], v[158:159] op_sel_hi:[0,1]
	v_pk_add_f32 v[152:153], v[138:139], v[152:153] op_sel_hi:[0,1]
	s_nop 0
	s_nop 0
	v_cvt_pk_bf16_f32 v155, v156, v156
	v_cvt_pk_bf16_f32 v0, v157, v157
	s_nop 0
	s_nop 0
	v_cvt_pk_bf16_f32 v153, v153, v153
	v_cvt_pk_bf16_f32 v152, v152, v152
	v_and_b32_e32 v153, 0xffff0000, v153
	v_and_b32_e32 v152, 0xffff0000, v152
	v_or_b32_sdwa v153, v153, v0 dst_sel:DWORD dst_unused:UNUSED_PAD src0_sel:DWORD src1_sel:WORD_1
	v_or_b32_sdwa v152, v152, v155 dst_sel:DWORD dst_unused:UNUSED_PAD src0_sel:DWORD src1_sel:WORD_1
	global_store_dwordx2 v[130:131], v[152:153], off offset:32
	v_pk_mul_f32 v[152:153], v[112:113], v[150:151]
	v_pk_mul_f32 v[156:157], v[110:111], v[148:149]
	v_mov_b32_e32 v159, v152
	v_mov_b32_e32 v152, v157
	v_mov_b32_e32 v158, v156
	v_pk_add_f32 v[152:153], v[140:141], v[152:153] op_sel_hi:[0,1]
	v_pk_add_f32 v[158:159], v[140:141], v[158:159] op_sel_hi:[0,1]
	s_nop 0
	s_nop 0
	s_nop 0
	s_nop 0
	v_cvt_pk_bf16_f32 v153, v153, v153
	v_cvt_pk_bf16_f32 v152, v152, v152
	v_cvt_pk_bf16_f32 v155, v158, v158
	v_cvt_pk_bf16_f32 v0, v159, v159
	v_and_b32_e32 v153, 0xffff0000, v153
	v_and_b32_e32 v152, 0xffff0000, v152
	v_or_b32_sdwa v153, v153, v0 dst_sel:DWORD dst_unused:UNUSED_PAD src0_sel:DWORD src1_sel:WORD_1
	v_or_b32_sdwa v152, v152, v155 dst_sel:DWORD dst_unused:UNUSED_PAD src0_sel:DWORD src1_sel:WORD_1
	global_store_dwordx2 v[142:143], v[152:153], off offset:32
	v_pk_mul_f32 v[152:153], v[100:101], v[150:151]
	v_pk_mul_f32 v[156:157], v[98:99], v[148:149]
	v_mov_b32_e32 v159, v152
	v_mov_b32_e32 v152, v157
	v_mov_b32_e32 v158, v156
	v_pk_add_f32 v[152:153], v[134:135], v[152:153] op_sel_hi:[0,1]
	v_pk_add_f32 v[158:159], v[134:135], v[158:159] op_sel_hi:[0,1]
	s_nop 0
	s_nop 0
	s_nop 0
	s_nop 0
	v_cvt_pk_bf16_f32 v153, v153, v153
	v_cvt_pk_bf16_f32 v152, v152, v152
	v_cvt_pk_bf16_f32 v155, v158, v158
	v_cvt_pk_bf16_f32 v0, v159, v159
	v_and_b32_e32 v153, 0xffff0000, v153
	v_and_b32_e32 v152, 0xffff0000, v152
	v_or_b32_sdwa v153, v153, v0 dst_sel:DWORD dst_unused:UNUSED_PAD src0_sel:DWORD src1_sel:WORD_1
	v_or_b32_sdwa v152, v152, v155 dst_sel:DWORD dst_unused:UNUSED_PAD src0_sel:DWORD src1_sel:WORD_1
	v_pk_mul_f32 v[150:151], v[104:105], v[150:151]
	v_pk_mul_f32 v[148:149], v[102:103], v[148:149]
	global_store_dwordx2 v[144:145], v[152:153], off offset:32
	v_mov_b32_e32 v152, v148
	v_mov_b32_e32 v153, v150
	v_pk_add_f32 v[152:153], v[136:137], v[152:153] op_sel_hi:[0,1]
	v_mov_b32_e32 v150, v149
	v_pk_add_f32 v[148:149], v[136:137], v[150:151] op_sel_hi:[0,1]
	s_nop 0
	v_cvt_pk_bf16_f32 v150, v152, v152
	s_nop 0
	s_nop 0
	s_nop 0
	v_cvt_pk_bf16_f32 v149, v149, v149
	v_cvt_pk_bf16_f32 v148, v148, v148
	v_cvt_pk_bf16_f32 v0, v153, v153
	v_and_b32_e32 v149, 0xffff0000, v149
	v_and_b32_e32 v148, 0xffff0000, v148
	v_or_b32_sdwa v149, v149, v0 dst_sel:DWORD dst_unused:UNUSED_PAD src0_sel:DWORD src1_sel:WORD_1
	v_or_b32_sdwa v148, v148, v150 dst_sel:DWORD dst_unused:UNUSED_PAD src0_sel:DWORD src1_sel:WORD_1
	global_store_dwordx2 v[132:133], v[148:149], off offset:32
	ds_read_b128 v[148:151], v154 offset:128
	s_waitcnt lgkmcnt(0)
	v_pk_mul_f32 v[152:153], v[92:93], v[150:151]
	v_pk_mul_f32 v[156:157], v[90:91], v[148:149]
	v_mov_b32_e32 v159, v152
	v_mov_b32_e32 v158, v156
	v_mov_b32_e32 v152, v157
	v_pk_add_f32 v[156:157], v[138:139], v[158:159] op_sel_hi:[0,1]
	v_pk_add_f32 v[152:153], v[138:139], v[152:153] op_sel_hi:[0,1]
	s_nop 0
	s_nop 0
	v_cvt_pk_bf16_f32 v155, v156, v156
	v_cvt_pk_bf16_f32 v0, v157, v157
	s_nop 0
	s_nop 0
	v_cvt_pk_bf16_f32 v153, v153, v153
	v_cvt_pk_bf16_f32 v152, v152, v152
	v_and_b32_e32 v153, 0xffff0000, v153
	v_and_b32_e32 v152, 0xffff0000, v152
	v_or_b32_sdwa v153, v153, v0 dst_sel:DWORD dst_unused:UNUSED_PAD src0_sel:DWORD src1_sel:WORD_1
	v_or_b32_sdwa v152, v152, v155 dst_sel:DWORD dst_unused:UNUSED_PAD src0_sel:DWORD src1_sel:WORD_1
	global_store_dwordx2 v[130:131], v[152:153], off offset:64
	v_pk_mul_f32 v[152:153], v[96:97], v[150:151]
	v_pk_mul_f32 v[156:157], v[94:95], v[148:149]
	v_mov_b32_e32 v159, v152
	v_mov_b32_e32 v152, v157
	v_mov_b32_e32 v158, v156
	v_pk_add_f32 v[152:153], v[140:141], v[152:153] op_sel_hi:[0,1]
	v_pk_add_f32 v[158:159], v[140:141], v[158:159] op_sel_hi:[0,1]
	s_nop 0
	s_nop 0
	s_nop 0
	s_nop 0
	v_cvt_pk_bf16_f32 v153, v153, v153
	v_cvt_pk_bf16_f32 v152, v152, v152
	v_cvt_pk_bf16_f32 v155, v158, v158
	v_cvt_pk_bf16_f32 v0, v159, v159
	v_and_b32_e32 v153, 0xffff0000, v153
	v_and_b32_e32 v152, 0xffff0000, v152
	v_or_b32_sdwa v153, v153, v0 dst_sel:DWORD dst_unused:UNUSED_PAD src0_sel:DWORD src1_sel:WORD_1
	v_or_b32_sdwa v152, v152, v155 dst_sel:DWORD dst_unused:UNUSED_PAD src0_sel:DWORD src1_sel:WORD_1
	global_store_dwordx2 v[142:143], v[152:153], off offset:64
	v_pk_mul_f32 v[152:153], v[84:85], v[150:151]
	v_pk_mul_f32 v[156:157], v[82:83], v[148:149]
	v_mov_b32_e32 v159, v152
	v_mov_b32_e32 v152, v157
	v_mov_b32_e32 v158, v156
	v_pk_add_f32 v[152:153], v[134:135], v[152:153] op_sel_hi:[0,1]
	v_pk_add_f32 v[158:159], v[134:135], v[158:159] op_sel_hi:[0,1]
	s_nop 0
	s_nop 0
	s_nop 0
	s_nop 0
	v_cvt_pk_bf16_f32 v153, v153, v153
	v_cvt_pk_bf16_f32 v152, v152, v152
	v_cvt_pk_bf16_f32 v155, v158, v158
	v_cvt_pk_bf16_f32 v0, v159, v159
	v_and_b32_e32 v153, 0xffff0000, v153
	v_and_b32_e32 v152, 0xffff0000, v152
	v_or_b32_sdwa v153, v153, v0 dst_sel:DWORD dst_unused:UNUSED_PAD src0_sel:DWORD src1_sel:WORD_1
	v_or_b32_sdwa v152, v152, v155 dst_sel:DWORD dst_unused:UNUSED_PAD src0_sel:DWORD src1_sel:WORD_1
	v_pk_mul_f32 v[150:151], v[88:89], v[150:151]
	v_pk_mul_f32 v[148:149], v[86:87], v[148:149]
	global_store_dwordx2 v[144:145], v[152:153], off offset:64
	v_mov_b32_e32 v152, v148
	v_mov_b32_e32 v153, v150
	v_pk_add_f32 v[152:153], v[136:137], v[152:153] op_sel_hi:[0,1]
	v_mov_b32_e32 v150, v149
	v_pk_add_f32 v[148:149], v[136:137], v[150:151] op_sel_hi:[0,1]
	s_nop 0
	v_cvt_pk_bf16_f32 v150, v152, v152
	s_nop 0
	s_nop 0
	s_nop 0
	v_cvt_pk_bf16_f32 v149, v149, v149
	v_cvt_pk_bf16_f32 v148, v148, v148
	v_cvt_pk_bf16_f32 v0, v153, v153
	v_and_b32_e32 v149, 0xffff0000, v149
	v_and_b32_e32 v148, 0xffff0000, v148
	v_or_b32_sdwa v149, v149, v0 dst_sel:DWORD dst_unused:UNUSED_PAD src0_sel:DWORD src1_sel:WORD_1
	v_or_b32_sdwa v148, v148, v150 dst_sel:DWORD dst_unused:UNUSED_PAD src0_sel:DWORD src1_sel:WORD_1
	global_store_dwordx2 v[132:133], v[148:149], off offset:64
	ds_read_b128 v[148:151], v154 offset:192
	s_waitcnt lgkmcnt(0)
; __device__ __forceinline__ unsigned pack2(float a, float b) { return (unsigned)f2bf(a) | ((unsigned)f2bf(b) << 16); }
; #define SCHED __builtin_amdgcn_sched_barrier(0)
; template <int EPI, bool HS = false>
; __device__ __forceinline__ void gemm_phase(const Params& p, const GemmCfg& g, char* shm, const int wave_s) {
;     ...
; #pragma unroll
;         for (int ai = 0; ai < 2; ++ai)
; #pragma unroll
;           for (int m = 0; m < 4; ++m) {
;             const f32x4 r4 = *(const f32x4*)(rsw + ai * 128 + m * 16);
; #pragma unroll
;             for (int bj = 0; bj < 2; ++bj)
; #pragma unroll
;               for (int n = 0; n < 2; ++n) {
;                 uint2 pk;
;                 pk.x = pack2(r4[0] * acc[ai][bj][m][n][0] + swv[bj][n], r4[1] * acc[ai][bj][m][n][1] + swv[bj][n]);
;                 pk.y = pack2(r4[2] * acc[ai][bj][m][n][2] + swv[bj][n], r4[3] * acc[ai][bj][m][n][3] + swv[bj][n]);
;                 *(uint2*)(vt_t + kb + ai * 512 * 128 + (bj * 128 + n * 16) * 128 + m * 16) = pk;
;               }
;             SCHED;
;           }
	v_pk_mul_f32 v[152:153], v[76:77], v[150:151]
	v_pk_mul_f32 v[156:157], v[74:75], v[148:149]
	v_mov_b32_e32 v159, v152
	v_mov_b32_e32 v158, v156
	v_mov_b32_e32 v152, v157
	v_pk_add_f32 v[156:157], v[138:139], v[158:159] op_sel_hi:[0,1]
	v_pk_add_f32 v[152:153], v[138:139], v[152:153] op_sel_hi:[0,1]
	s_nop 0
	s_nop 0
	v_cvt_pk_bf16_f32 v155, v156, v156
	v_cvt_pk_bf16_f32 v0, v157, v157
	s_nop 0
	s_nop 0
	v_cvt_pk_bf16_f32 v153, v153, v153
	v_cvt_pk_bf16_f32 v152, v152, v152
	v_and_b32_e32 v153, 0xffff0000, v153
	v_and_b32_e32 v152, 0xffff0000, v152
	v_or_b32_sdwa v153, v153, v0 dst_sel:DWORD dst_unused:UNUSED_PAD src0_sel:DWORD src1_sel:WORD_1
	v_or_b32_sdwa v152, v152, v155 dst_sel:DWORD dst_unused:UNUSED_PAD src0_sel:DWORD src1_sel:WORD_1
	global_store_dwordx2 v[130:131], v[152:153], off offset:96
	v_pk_mul_f32 v[152:153], v[80:81], v[150:151]
	v_pk_mul_f32 v[156:157], v[78:79], v[148:149]
	v_mov_b32_e32 v159, v152
	v_mov_b32_e32 v152, v157
	v_mov_b32_e32 v158, v156
	v_pk_add_f32 v[152:153], v[140:141], v[152:153] op_sel_hi:[0,1]
	v_pk_add_f32 v[158:159], v[140:141], v[158:159] op_sel_hi:[0,1]
	s_nop 0
	s_nop 0
	s_nop 0
	s_nop 0
	v_cvt_pk_bf16_f32 v153, v153, v153
	v_cvt_pk_bf16_f32 v152, v152, v152
	v_cvt_pk_bf16_f32 v155, v158, v158
	v_cvt_pk_bf16_f32 v0, v159, v159
	v_and_b32_e32 v153, 0xffff0000, v153
	v_and_b32_e32 v152, 0xffff0000, v152
	v_or_b32_sdwa v153, v153, v0 dst_sel:DWORD dst_unused:UNUSED_PAD src0_sel:DWORD src1_sel:WORD_1
	v_or_b32_sdwa v152, v152, v155 dst_sel:DWORD dst_unused:UNUSED_PAD src0_sel:DWORD src1_sel:WORD_1
	global_store_dwordx2 v[142:143], v[152:153], off offset:96
	v_pk_mul_f32 v[142:143], v[68:69], v[150:151]
	v_pk_mul_f32 v[152:153], v[66:67], v[148:149]
	v_mov_b32_e32 v157, v142
	v_mov_b32_e32 v142, v153
	v_mov_b32_e32 v156, v152
	v_pk_add_f32 v[142:143], v[134:135], v[142:143] op_sel_hi:[0,1]
	v_pk_add_f32 v[156:157], v[134:135], v[156:157] op_sel_hi:[0,1]
	s_nop 0
	s_nop 0
	s_nop 0
	s_nop 0
	v_cvt_pk_bf16_f32 v143, v143, v143
	v_cvt_pk_bf16_f32 v142, v142, v142
	v_cvt_pk_bf16_f32 v152, v156, v156
	v_cvt_pk_bf16_f32 v0, v157, v157
	v_and_b32_e32 v143, 0xffff0000, v143
	v_and_b32_e32 v142, 0xffff0000, v142
	v_or_b32_sdwa v143, v143, v0 dst_sel:DWORD dst_unused:UNUSED_PAD src0_sel:DWORD src1_sel:WORD_1
	v_or_b32_sdwa v142, v142, v152 dst_sel:DWORD dst_unused:UNUSED_PAD src0_sel:DWORD src1_sel:WORD_1
	global_store_dwordx2 v[144:145], v[142:143], off offset:96
	v_pk_mul_f32 v[142:143], v[72:73], v[150:151]
	v_pk_mul_f32 v[144:145], v[70:71], v[148:149]
	v_mov_b32_e32 v149, v142
	v_mov_b32_e32 v148, v144
	v_pk_add_f32 v[148:149], v[136:137], v[148:149] op_sel_hi:[0,1]
	v_mov_b32_e32 v142, v145
	v_pk_add_f32 v[142:143], v[136:137], v[142:143] op_sel_hi:[0,1]
	s_nop 0
	v_cvt_pk_bf16_f32 v144, v148, v148
	s_nop 0
	s_nop 0
	s_nop 0
	v_cvt_pk_bf16_f32 v143, v143, v143
	v_cvt_pk_bf16_f32 v142, v142, v142
	v_cvt_pk_bf16_f32 v0, v149, v149
	v_and_b32_e32 v143, 0xffff0000, v143
	v_and_b32_e32 v142, 0xffff0000, v142
	v_or_b32_sdwa v143, v143, v0 dst_sel:DWORD dst_unused:UNUSED_PAD src0_sel:DWORD src1_sel:WORD_1
	v_or_b32_sdwa v142, v142, v144 dst_sel:DWORD dst_unused:UNUSED_PAD src0_sel:DWORD src1_sel:WORD_1
	global_store_dwordx2 v[132:133], v[142:143], off offset:96
	ds_read_b128 v[148:151], v154 offset:512
	s_mov_b32 s1, 0x20000
	s_waitcnt lgkmcnt(0)
	v_pk_mul_f32 v[132:133], v[60:61], v[150:151]
	v_pk_mul_f32 v[142:143], v[58:59], v[148:149]
	v_mov_b32_e32 v145, v132
	v_mov_b32_e32 v144, v142
	v_mov_b32_e32 v132, v143
	v_pk_add_f32 v[142:143], v[138:139], v[144:145] op_sel_hi:[0,1]
	v_pk_add_f32 v[132:133], v[138:139], v[132:133] op_sel_hi:[0,1]
	s_nop 0
	v_cvt_pk_bf16_f32 v142, v142, v142
	s_nop 0
	v_cvt_pk_bf16_f32 v132, v132, v132
	s_nop 0
	v_and_b32_e32 v132, 0xffff0000, v132
	v_cvt_pk_bf16_f32 v0, v143, v143
	s_nop 0
	v_or_b32_sdwa v144, v132, v142 dst_sel:DWORD dst_unused:UNUSED_PAD src0_sel:DWORD src1_sel:WORD_1
	v_add_co_u32_e32 v142, vcc, s1, v130
	v_cvt_pk_bf16_f32 v133, v133, v133
	s_nop 0
	v_addc_co_u32_e32 v143, vcc, 0, v131, vcc
	s_mov_b32 s1, 0x21000
	v_and_b32_e32 v133, 0xffff0000, v133
	v_add_co_u32_e32 v132, vcc, s1, v130
	v_or_b32_sdwa v145, v133, v0 dst_sel:DWORD dst_unused:UNUSED_PAD src0_sel:DWORD src1_sel:WORD_1
	s_nop 0
	v_addc_co_u32_e32 v133, vcc, 0, v131, vcc
	global_store_dwordx2 v[132:133], v[144:145], off offset:-4096
	v_pk_mul_f32 v[144:145], v[64:65], v[150:151]
	v_pk_mul_f32 v[152:153], v[62:63], v[148:149]
	v_mov_b32_e32 v157, v144
	v_mov_b32_e32 v144, v153
	v_mov_b32_e32 v156, v152
	v_pk_add_f32 v[144:145], v[140:141], v[144:145] op_sel_hi:[0,1]
	v_pk_add_f32 v[156:157], v[140:141], v[156:157] op_sel_hi:[0,1]
	s_nop 0
	s_nop 0
	s_nop 0
	s_nop 0
	v_cvt_pk_bf16_f32 v145, v145, v145
	v_cvt_pk_bf16_f32 v144, v144, v144
	v_cvt_pk_bf16_f32 v152, v156, v156
	v_cvt_pk_bf16_f32 v0, v157, v157
	v_and_b32_e32 v145, 0xffff0000, v145
	v_and_b32_e32 v144, 0xffff0000, v144
	v_or_b32_sdwa v145, v145, v0 dst_sel:DWORD dst_unused:UNUSED_PAD src0_sel:DWORD src1_sel:WORD_1
	v_or_b32_sdwa v144, v144, v152 dst_sel:DWORD dst_unused:UNUSED_PAD src0_sel:DWORD src1_sel:WORD_1
	global_store_dwordx2 v[132:133], v[144:145], off
	v_pk_mul_f32 v[144:145], v[52:53], v[150:151]
	v_pk_mul_f32 v[152:153], v[50:51], v[148:149]
	v_mov_b32_e32 v157, v144
	v_mov_b32_e32 v144, v153
	v_mov_b32_e32 v156, v152
	v_pk_add_f32 v[144:145], v[134:135], v[144:145] op_sel_hi:[0,1]
	v_pk_add_f32 v[156:157], v[134:135], v[156:157] op_sel_hi:[0,1]
	s_nop 0
	s_nop 0
	s_nop 0
	v_cvt_pk_bf16_f32 v144, v144, v144
	s_nop 0
	v_cvt_pk_bf16_f32 v152, v156, v156
	v_cvt_pk_bf16_f32 v145, v145, v145
	v_and_b32_e32 v144, 0xffff0000, v144
; __device__ __forceinline__ unsigned pack2(float a, float b) { return (unsigned)f2bf(a) | ((unsigned)f2bf(b) << 16); }
; #define SCHED __builtin_amdgcn_sched_barrier(0)
; template <int EPI, bool HS = false>
; __device__ __forceinline__ void gemm_phase(const Params& p, const GemmCfg& g, char* shm, const int wave_s) {
;     ...
; #pragma unroll
;         for (int ai = 0; ai < 2; ++ai)
; #pragma unroll
;           for (int m = 0; m < 4; ++m) {
;             const f32x4 r4 = *(const f32x4*)(rsw + ai * 128 + m * 16);
; #pragma unroll
;             for (int bj = 0; bj < 2; ++bj)
; #pragma unroll
;               for (int n = 0; n < 2; ++n) {
;                 uint2 pk;
;                 pk.x = pack2(r4[0] * acc[ai][bj][m][n][0] + swv[bj][n], r4[1] * acc[ai][bj][m][n][1] + swv[bj][n]);
;                 pk.y = pack2(r4[2] * acc[ai][bj][m][n][2] + swv[bj][n], r4[3] * acc[ai][bj][m][n][3] + swv[bj][n]);
;                 *(uint2*)(vt_t + kb + ai * 512 * 128 + (bj * 128 + n * 16) * 128 + m * 16) = pk;
;               }
;             SCHED;
;           }
	s_mov_b32 s1, 0x28000
	v_cvt_pk_bf16_f32 v0, v157, v157
	v_and_b32_e32 v145, 0xffff0000, v145
	v_or_b32_sdwa v152, v144, v152 dst_sel:DWORD dst_unused:UNUSED_PAD src0_sel:DWORD src1_sel:WORD_1
	v_add_co_u32_e32 v144, vcc, s1, v130
	v_or_b32_sdwa v153, v145, v0 dst_sel:DWORD dst_unused:UNUSED_PAD src0_sel:DWORD src1_sel:WORD_1
	s_nop 0
	v_addc_co_u32_e32 v145, vcc, 0, v131, vcc
	s_mov_b32 s1, 0x29000
	v_add_co_u32_e32 v130, vcc, s1, v130
	v_pk_mul_f32 v[150:151], v[56:57], v[150:151]
	s_nop 0
	v_addc_co_u32_e32 v131, vcc, 0, v131, vcc
	v_pk_mul_f32 v[148:149], v[54:55], v[148:149]
	global_store_dwordx2 v[130:131], v[152:153], off offset:-4096
	v_mov_b32_e32 v152, v148
	v_mov_b32_e32 v153, v150
	v_pk_add_f32 v[152:153], v[136:137], v[152:153] op_sel_hi:[0,1]
	v_mov_b32_e32 v150, v149
	v_pk_add_f32 v[148:149], v[136:137], v[150:151] op_sel_hi:[0,1]
	s_nop 0
	v_cvt_pk_bf16_f32 v150, v152, v152
	s_nop 0
	s_nop 0
	s_nop 0
	v_cvt_pk_bf16_f32 v149, v149, v149
	v_cvt_pk_bf16_f32 v148, v148, v148
	v_cvt_pk_bf16_f32 v0, v153, v153
	v_and_b32_e32 v149, 0xffff0000, v149
	v_and_b32_e32 v148, 0xffff0000, v148
	v_or_b32_sdwa v149, v149, v0 dst_sel:DWORD dst_unused:UNUSED_PAD src0_sel:DWORD src1_sel:WORD_1
	v_or_b32_sdwa v148, v148, v150 dst_sel:DWORD dst_unused:UNUSED_PAD src0_sel:DWORD src1_sel:WORD_1
	global_store_dwordx2 v[130:131], v[148:149], off
	ds_read_b128 v[148:151], v154 offset:576
	s_waitcnt lgkmcnt(0)
	v_pk_mul_f32 v[152:153], v[44:45], v[150:151]
	v_pk_mul_f32 v[156:157], v[42:43], v[148:149]
	v_mov_b32_e32 v159, v152
	v_mov_b32_e32 v158, v156
	v_mov_b32_e32 v152, v157
	v_pk_add_f32 v[156:157], v[138:139], v[158:159] op_sel_hi:[0,1]
	v_pk_add_f32 v[152:153], v[138:139], v[152:153] op_sel_hi:[0,1]
	s_nop 0
	s_nop 0
	v_cvt_pk_bf16_f32 v155, v156, v156
	v_cvt_pk_bf16_f32 v0, v157, v157
	s_nop 0
	s_nop 0
	v_cvt_pk_bf16_f32 v153, v153, v153
	v_cvt_pk_bf16_f32 v152, v152, v152
	v_and_b32_e32 v153, 0xffff0000, v153
	v_and_b32_e32 v152, 0xffff0000, v152
	v_or_b32_sdwa v153, v153, v0 dst_sel:DWORD dst_unused:UNUSED_PAD src0_sel:DWORD src1_sel:WORD_1
	v_or_b32_sdwa v152, v152, v155 dst_sel:DWORD dst_unused:UNUSED_PAD src0_sel:DWORD src1_sel:WORD_1
	global_store_dwordx2 v[142:143], v[152:153], off offset:32
	v_pk_mul_f32 v[152:153], v[48:49], v[150:151]
	v_pk_mul_f32 v[156:157], v[46:47], v[148:149]
	v_mov_b32_e32 v159, v152
	v_mov_b32_e32 v152, v157
	v_mov_b32_e32 v158, v156
	v_pk_add_f32 v[152:153], v[140:141], v[152:153] op_sel_hi:[0,1]
	v_pk_add_f32 v[158:159], v[140:141], v[158:159] op_sel_hi:[0,1]
	s_nop 0
	s_nop 0
	s_nop 0
	s_nop 0
	v_cvt_pk_bf16_f32 v153, v153, v153
	v_cvt_pk_bf16_f32 v152, v152, v152
	v_cvt_pk_bf16_f32 v155, v158, v158
	v_cvt_pk_bf16_f32 v0, v159, v159
	v_and_b32_e32 v153, 0xffff0000, v153
	v_and_b32_e32 v152, 0xffff0000, v152
	v_or_b32_sdwa v153, v153, v0 dst_sel:DWORD dst_unused:UNUSED_PAD src0_sel:DWORD src1_sel:WORD_1
	v_or_b32_sdwa v152, v152, v155 dst_sel:DWORD dst_unused:UNUSED_PAD src0_sel:DWORD src1_sel:WORD_1
	global_store_dwordx2 v[132:133], v[152:153], off offset:32
	v_pk_mul_f32 v[152:153], v[36:37], v[150:151]
	v_pk_mul_f32 v[156:157], v[34:35], v[148:149]
	v_mov_b32_e32 v159, v152
	v_mov_b32_e32 v152, v157
	v_mov_b32_e32 v158, v156
	v_pk_add_f32 v[152:153], v[134:135], v[152:153] op_sel_hi:[0,1]
	v_pk_add_f32 v[158:159], v[134:135], v[158:159] op_sel_hi:[0,1]
	s_nop 0
	s_nop 0
	s_nop 0
	s_nop 0
	v_cvt_pk_bf16_f32 v153, v153, v153
	v_cvt_pk_bf16_f32 v152, v152, v152
	v_cvt_pk_bf16_f32 v155, v158, v158
	v_cvt_pk_bf16_f32 v0, v159, v159
	v_and_b32_e32 v153, 0xffff0000, v153
	v_and_b32_e32 v152, 0xffff0000, v152
	v_or_b32_sdwa v153, v153, v0 dst_sel:DWORD dst_unused:UNUSED_PAD src0_sel:DWORD src1_sel:WORD_1
	v_or_b32_sdwa v152, v152, v155 dst_sel:DWORD dst_unused:UNUSED_PAD src0_sel:DWORD src1_sel:WORD_1
	v_pk_mul_f32 v[150:151], v[40:41], v[150:151]
	v_pk_mul_f32 v[148:149], v[38:39], v[148:149]
	global_store_dwordx2 v[144:145], v[152:153], off offset:32
	v_mov_b32_e32 v152, v148
	v_mov_b32_e32 v153, v150
	v_pk_add_f32 v[152:153], v[136:137], v[152:153] op_sel_hi:[0,1]
	v_mov_b32_e32 v150, v149
	v_pk_add_f32 v[148:149], v[136:137], v[150:151] op_sel_hi:[0,1]
	s_nop 0
	v_cvt_pk_bf16_f32 v150, v152, v152
	s_nop 0
	s_nop 0
	s_nop 0
	v_cvt_pk_bf16_f32 v149, v149, v149
	v_cvt_pk_bf16_f32 v148, v148, v148
	v_cvt_pk_bf16_f32 v0, v153, v153
	v_and_b32_e32 v149, 0xffff0000, v149
	v_and_b32_e32 v148, 0xffff0000, v148
	v_or_b32_sdwa v149, v149, v0 dst_sel:DWORD dst_unused:UNUSED_PAD src0_sel:DWORD src1_sel:WORD_1
	v_or_b32_sdwa v148, v148, v150 dst_sel:DWORD dst_unused:UNUSED_PAD src0_sel:DWORD src1_sel:WORD_1
	global_store_dwordx2 v[130:131], v[148:149], off offset:32
	ds_read_b128 v[148:151], v154 offset:640
	s_waitcnt lgkmcnt(0)
; __device__ __forceinline__ unsigned pack2(float a, float b) { return (unsigned)f2bf(a) | ((unsigned)f2bf(b) << 16); }
; #define SCHED __builtin_amdgcn_sched_barrier(0)
; template <int EPI, bool HS = false>
; __device__ __forceinline__ void gemm_phase(const Params& p, const GemmCfg& g, char* shm, const int wave_s) {
;     ...
; #pragma unroll
;         for (int ai = 0; ai < 2; ++ai)
; #pragma unroll
;           for (int m = 0; m < 4; ++m) {
;             const f32x4 r4 = *(const f32x4*)(rsw + ai * 128 + m * 16);
; #pragma unroll
;             for (int bj = 0; bj < 2; ++bj)
; #pragma unroll
;               for (int n = 0; n < 2; ++n) {
;                 uint2 pk;
;                 pk.x = pack2(r4[0] * acc[ai][bj][m][n][0] + swv[bj][n], r4[1] * acc[ai][bj][m][n][1] + swv[bj][n]);
;                 pk.y = pack2(r4[2] * acc[ai][bj][m][n][2] + swv[bj][n], r4[3] * acc[ai][bj][m][n][3] + swv[bj][n]);
;                 *(uint2*)(vt_t + kb + ai * 512 * 128 + (bj * 128 + n * 16) * 128 + m * 16) = pk;
;               }
;             SCHED;
;           }
	v_pk_mul_f32 v[152:153], v[28:29], v[150:151]
	v_pk_mul_f32 v[156:157], v[26:27], v[148:149]
	v_mov_b32_e32 v159, v152
	v_mov_b32_e32 v158, v156
	v_mov_b32_e32 v152, v157
	v_pk_add_f32 v[156:157], v[138:139], v[158:159] op_sel_hi:[0,1]
	v_pk_add_f32 v[152:153], v[138:139], v[152:153] op_sel_hi:[0,1]
	s_nop 0
	s_nop 0
	v_cvt_pk_bf16_f32 v155, v156, v156
	v_cvt_pk_bf16_f32 v0, v157, v157
	s_nop 0
	s_nop 0
	v_cvt_pk_bf16_f32 v153, v153, v153
	v_cvt_pk_bf16_f32 v152, v152, v152
	v_and_b32_e32 v153, 0xffff0000, v153
	v_and_b32_e32 v152, 0xffff0000, v152
	v_or_b32_sdwa v153, v153, v0 dst_sel:DWORD dst_unused:UNUSED_PAD src0_sel:DWORD src1_sel:WORD_1
	v_or_b32_sdwa v152, v152, v155 dst_sel:DWORD dst_unused:UNUSED_PAD src0_sel:DWORD src1_sel:WORD_1
	global_store_dwordx2 v[142:143], v[152:153], off offset:64
	v_pk_mul_f32 v[152:153], v[32:33], v[150:151]
	v_pk_mul_f32 v[156:157], v[30:31], v[148:149]
	v_mov_b32_e32 v159, v152
	v_mov_b32_e32 v152, v157
	v_mov_b32_e32 v158, v156
	v_pk_add_f32 v[152:153], v[140:141], v[152:153] op_sel_hi:[0,1]
	v_pk_add_f32 v[158:159], v[140:141], v[158:159] op_sel_hi:[0,1]
	s_nop 0
	s_nop 0
	s_nop 0
	s_nop 0
	v_cvt_pk_bf16_f32 v153, v153, v153
	v_cvt_pk_bf16_f32 v152, v152, v152
	v_cvt_pk_bf16_f32 v155, v158, v158
	v_cvt_pk_bf16_f32 v0, v159, v159
	v_and_b32_e32 v153, 0xffff0000, v153
	v_and_b32_e32 v152, 0xffff0000, v152
	v_or_b32_sdwa v153, v153, v0 dst_sel:DWORD dst_unused:UNUSED_PAD src0_sel:DWORD src1_sel:WORD_1
	v_or_b32_sdwa v152, v152, v155 dst_sel:DWORD dst_unused:UNUSED_PAD src0_sel:DWORD src1_sel:WORD_1
	global_store_dwordx2 v[132:133], v[152:153], off offset:64
	v_pk_mul_f32 v[152:153], v[20:21], v[150:151]
	v_pk_mul_f32 v[156:157], v[18:19], v[148:149]
	v_mov_b32_e32 v159, v152
	v_mov_b32_e32 v152, v157
	v_mov_b32_e32 v158, v156
	v_pk_add_f32 v[152:153], v[134:135], v[152:153] op_sel_hi:[0,1]
	v_pk_add_f32 v[158:159], v[134:135], v[158:159] op_sel_hi:[0,1]
	s_nop 0
	s_nop 0
	s_nop 0
	s_nop 0
	v_cvt_pk_bf16_f32 v153, v153, v153
	v_cvt_pk_bf16_f32 v152, v152, v152
	v_cvt_pk_bf16_f32 v155, v158, v158
	v_cvt_pk_bf16_f32 v0, v159, v159
	v_and_b32_e32 v153, 0xffff0000, v153
	v_and_b32_e32 v152, 0xffff0000, v152
	v_or_b32_sdwa v153, v153, v0 dst_sel:DWORD dst_unused:UNUSED_PAD src0_sel:DWORD src1_sel:WORD_1
	v_or_b32_sdwa v152, v152, v155 dst_sel:DWORD dst_unused:UNUSED_PAD src0_sel:DWORD src1_sel:WORD_1
	v_pk_mul_f32 v[150:151], v[24:25], v[150:151]
	v_pk_mul_f32 v[148:149], v[22:23], v[148:149]
	global_store_dwordx2 v[144:145], v[152:153], off offset:64
	v_mov_b32_e32 v152, v148
	v_mov_b32_e32 v153, v150
	v_pk_add_f32 v[152:153], v[136:137], v[152:153] op_sel_hi:[0,1]
	v_mov_b32_e32 v150, v149
	v_pk_add_f32 v[148:149], v[136:137], v[150:151] op_sel_hi:[0,1]
	s_nop 0
	v_cvt_pk_bf16_f32 v150, v152, v152
	s_nop 0
	s_nop 0
	s_nop 0
	v_cvt_pk_bf16_f32 v149, v149, v149
	v_cvt_pk_bf16_f32 v148, v148, v148
	v_cvt_pk_bf16_f32 v0, v153, v153
	v_and_b32_e32 v149, 0xffff0000, v149
	v_and_b32_e32 v148, 0xffff0000, v148
	v_or_b32_sdwa v149, v149, v0 dst_sel:DWORD dst_unused:UNUSED_PAD src0_sel:DWORD src1_sel:WORD_1
	v_or_b32_sdwa v148, v148, v150 dst_sel:DWORD dst_unused:UNUSED_PAD src0_sel:DWORD src1_sel:WORD_1
	global_store_dwordx2 v[130:131], v[148:149], off offset:64
	ds_read_b128 v[148:151], v154 offset:704
	s_waitcnt lgkmcnt(0)
; __device__ __forceinline__ unsigned pack2(float a, float b) { return (unsigned)f2bf(a) | ((unsigned)f2bf(b) << 16); }
; #define SCHED __builtin_amdgcn_sched_barrier(0)
; template <int EPI, bool HS = false>
; __device__ __forceinline__ void gemm_phase(const Params& p, const GemmCfg& g, char* shm, const int wave_s) {
;     ...
; #pragma unroll
;         for (int ai = 0; ai < 2; ++ai)
; #pragma unroll
;           for (int m = 0; m < 4; ++m) {
;             const f32x4 r4 = *(const f32x4*)(rsw + ai * 128 + m * 16);
; #pragma unroll
;             for (int bj = 0; bj < 2; ++bj)
; #pragma unroll
;               for (int n = 0; n < 2; ++n) {
;                 uint2 pk;
;                 pk.x = pack2(r4[0] * acc[ai][bj][m][n][0] + swv[bj][n], r4[1] * acc[ai][bj][m][n][1] + swv[bj][n]);
;                 pk.y = pack2(r4[2] * acc[ai][bj][m][n][2] + swv[bj][n], r4[3] * acc[ai][bj][m][n][3] + swv[bj][n]);
;                 *(uint2*)(vt_t + kb + ai * 512 * 128 + (bj * 128 + n * 16) * 128 + m * 16) = pk;
;               }
;             SCHED;
;           }
	v_pk_mul_f32 v[152:153], v[12:13], v[150:151]
	v_pk_mul_f32 v[156:157], v[10:11], v[148:149]
	v_mov_b32_e32 v159, v152
	v_mov_b32_e32 v158, v156
	v_mov_b32_e32 v152, v157
	v_pk_add_f32 v[156:157], v[138:139], v[158:159] op_sel_hi:[0,1]
	v_pk_add_f32 v[152:153], v[138:139], v[152:153] op_sel_hi:[0,1]
	s_nop 0
	s_nop 0
	v_cvt_pk_bf16_f32 v155, v156, v156
	v_cvt_pk_bf16_f32 v0, v157, v157
	s_nop 0
	s_nop 0
	v_cvt_pk_bf16_f32 v153, v153, v153
	v_cvt_pk_bf16_f32 v152, v152, v152
	v_and_b32_e32 v153, 0xffff0000, v153
	v_and_b32_e32 v152, 0xffff0000, v152
	v_or_b32_sdwa v153, v153, v0 dst_sel:DWORD dst_unused:UNUSED_PAD src0_sel:DWORD src1_sel:WORD_1
	v_or_b32_sdwa v152, v152, v155 dst_sel:DWORD dst_unused:UNUSED_PAD src0_sel:DWORD src1_sel:WORD_1
	global_store_dwordx2 v[142:143], v[152:153], off offset:96
	v_pk_mul_f32 v[142:143], v[16:17], v[150:151]
	v_pk_mul_f32 v[152:153], v[14:15], v[148:149]
	v_mov_b32_e32 v157, v142
	v_mov_b32_e32 v142, v153
	v_mov_b32_e32 v156, v152
	v_pk_add_f32 v[142:143], v[140:141], v[142:143] op_sel_hi:[0,1]
	v_pk_add_f32 v[156:157], v[140:141], v[156:157] op_sel_hi:[0,1]
	s_nop 0
	v_and_b32_sdwa v155, v142, v178 dst_sel:DWORD dst_unused:UNUSED_PAD src0_sel:WORD_1 src1_sel:DWORD
	s_nop 0
	s_nop 0
	v_cvt_pk_bf16_f32 v143, v143, v143
	v_add3_u32 v142, v142, v155, s81
	v_cvt_pk_bf16_f32 v152, v156, v156
	v_cvt_pk_bf16_f32 v0, v157, v157
	v_and_b32_e32 v143, 0xffff0000, v143
	v_and_b32_e32 v142, 0xffff0000, v142
	v_or_b32_sdwa v143, v143, v0 dst_sel:DWORD dst_unused:UNUSED_PAD src0_sel:DWORD src1_sel:WORD_1
	v_or_b32_sdwa v142, v142, v152 dst_sel:DWORD dst_unused:UNUSED_PAD src0_sel:DWORD src1_sel:WORD_1
	global_store_dwordx2 v[132:133], v[142:143], off offset:96
	v_pk_mul_f32 v[132:133], v[4:5], v[150:151]
	v_pk_mul_f32 v[142:143], v[2:3], v[148:149]
	v_mov_b32_e32 v153, v132
	v_mov_b32_e32 v152, v142
	v_pk_add_f32 v[152:153], v[134:135], v[152:153] op_sel_hi:[0,1]
	v_mov_b32_e32 v132, v143
	v_pk_add_f32 v[132:133], v[134:135], v[132:133] op_sel_hi:[0,1]
	s_nop 0
	v_cvt_pk_bf16_f32 v142, v152, v152
	s_nop 0
	v_and_b32_sdwa v152, v132, v178 dst_sel:DWORD dst_unused:UNUSED_PAD src0_sel:WORD_1 src1_sel:DWORD
	s_nop 0
	v_cvt_pk_bf16_f32 v133, v133, v133
	v_add3_u32 v132, v132, v152, s81
	v_cvt_pk_bf16_f32 v0, v153, v153
	v_and_b32_e32 v133, 0xffff0000, v133
	v_and_b32_e32 v132, 0xffff0000, v132
	v_or_b32_sdwa v133, v133, v0 dst_sel:DWORD dst_unused:UNUSED_PAD src0_sel:DWORD src1_sel:WORD_1
	v_or_b32_sdwa v132, v132, v142 dst_sel:DWORD dst_unused:UNUSED_PAD src0_sel:DWORD src1_sel:WORD_1
	global_store_dwordx2 v[144:145], v[132:133], off offset:96
	v_pk_mul_f32 v[132:133], v[8:9], v[150:151]
	v_pk_mul_f32 v[142:143], v[6:7], v[148:149]
	v_mov_b32_e32 v145, v132
	v_mov_b32_e32 v144, v142
	v_pk_add_f32 v[144:145], v[136:137], v[144:145] op_sel_hi:[0,1]
	v_mov_b32_e32 v132, v143
	v_pk_add_f32 v[132:133], v[136:137], v[132:133] op_sel_hi:[0,1]
	v_and_b32_sdwa v142, v144, v178 dst_sel:DWORD dst_unused:UNUSED_PAD src0_sel:WORD_1 src1_sel:DWORD
	v_add3_u32 v142, v144, v142, s81
	v_and_b32_sdwa v143, v133, v178 dst_sel:DWORD dst_unused:UNUSED_PAD src0_sel:WORD_1 src1_sel:DWORD
	v_and_b32_sdwa v144, v132, v178 dst_sel:DWORD dst_unused:UNUSED_PAD src0_sel:WORD_1 src1_sel:DWORD
	v_and_b32_sdwa v0, v145, v178 dst_sel:DWORD dst_unused:UNUSED_PAD src0_sel:WORD_1 src1_sel:DWORD
	v_add3_u32 v133, v133, v143, s81
	v_add3_u32 v132, v132, v144, s81
	v_add3_u32 v0, v145, v0, s81
	v_and_b32_e32 v133, 0xffff0000, v133
	v_and_b32_e32 v132, 0xffff0000, v132
	v_or_b32_sdwa v133, v133, v0 dst_sel:DWORD dst_unused:UNUSED_PAD src0_sel:DWORD src1_sel:WORD_1
	v_or_b32_sdwa v132, v132, v142 dst_sel:DWORD dst_unused:UNUSED_PAD src0_sel:DWORD src1_sel:WORD_1
	global_store_dwordx2 v[130:131], v[132:133], off offset:96

; #define WAIT_V(n) asm volatile("s_waitcnt vmcnt(" #n ")" ::: "memory")
; template <int EPI, bool HS = false>
; __device__ __forceinline__ void gemm_phase(const Params& p, const GemmCfg& g, char* shm, const int wave_s) {
;     ...
;       if (pn < 8) {
;         const int hh = pn & 3;
;         const bool isk = pn >= 4;
;         u16* dst = (isk ? Kb : Qb) + (size_t)orow0 * 1024 + hh * 256;
;         u16* kt_t = KTb + ((size_t)((b * 4 + hh) * 16 + (mt & 7) * 2) * 256) * 128;
;         const float lg2 = log2f(1.0f - exp2f(-5.0f - (float)hh));
;         const float scl = isk ? 0.0625f : 1.0f;
;         const float* rc_t = p.ropec + (size_t)s0 * 128;
;         const float* rs_t = p.ropes + (size_t)s0 * 128;
;         const unsigned tb = (unsigned)((wr * 64 + fq * 4) * 1024 + wc * 32 + fr);
;         const unsigned kb = (unsigned)((wc * 32 + fr) * 128 + wr * 64 + fq * 4);
;         const unsigned ldsb = (unsigned)(size_t)(__attribute__((address_space(3))) char*)shm;
;         const int wv_s = __builtin_amdgcn_readfirstlane(wid);
;         const char* rl = shm + ((wr * 64 + fq * 4) * 128 + wc * 16 + fr) * 4;
; #pragma unroll
;         for (int ai = 0; ai < 2; ++ai) {
; #pragma unroll
;           for (int i = 0; i < 8; ++i) {
;             const int ch = wv_s * 8 + i;
;             glds_row(rc_t + (size_t)(ai * 128) * 128 + ch * 256, (unsigned)lane * 16u, ldsb + (unsigned)(ch * 1024));
;             glds_row(rs_t + (size_t)(ai * 128) * 128 + ch * 256, (unsigned)lane * 16u, ldsb + 65536u + (unsigned)(ch * 1024));
;           }
;           WAIT_V(0);
;           __syncthreads();
.LBB0_595:
	s_andn2_b64 vcc, exec, s[8:9]
	s_cbranch_vccnz .LBB0_577
	s_lshl_b32 s1, s3, 8
	s_or_b32 s6, s1, s43
	s_and_b32 s2, s2, 3
	s_cmp_gt_i32 s88, 31
	s_cselect_b64 s[4:5], -1, 0
	v_readlane_b32 s12, v254, 47
	s_and_b64 s[8:9], s[4:5], exec
	v_readlane_b32 s14, v254, 49
	s_cselect_b32 s1, 0x4000000, 0
	v_readlane_b32 s15, v254, 50
	s_add_u32 s7, s14, s1
	s_addc_u32 s8, s15, 0
	s_ashr_i32 s1, s0, 31
	s_lshl_b64 s[0:1], s[0:1], 11
	s_add_u32 s0, s7, s0
	s_addc_u32 s1, s8, s1
	s_lshl_b32 s7, s2, 9
	v_mov_b32_e32 v0, 0x3d800000
	s_add_u32 s0, s0, s7
	v_cndmask_b32_e64 v142, 1.0, v0, s[4:5]
	s_addc_u32 s1, s1, 0
	s_lshl_b32 s7, s10, 6
	s_lshl_b32 s8, s2, 4
	v_cvt_f32_ubyte0_e32 v0, s2
	s_or_b32 s7, s7, s8
	s_lshl_b32 s3, s3, 1
	v_sub_f32_e32 v0, 0xc0a00000, v0
	s_mov_b32 s2, 0xc2fc0000
	s_or_b32 s8, s7, s3
	v_cmp_gt_f32_e32 vcc, s2, v0
	v_mov_b32_e32 v130, 0x42800000
	s_ashr_i32 s9, s8, 31
	v_cndmask_b32_e32 v130, 0, v130, vcc
	s_mov_b64 s[16:17], s[46:47]
	s_lshl_b64 s[8:9], s[8:9], 16
	v_add_f32_e32 v0, v0, v130
	s_add_u32 s10, s16, s8
	v_exp_f32_e32 v0, v0
	s_addc_u32 s11, s17, s9
	s_and_b64 s[2:3], vcc, exec
	s_cselect_b32 s2, 0xffffffc0, 0
	v_ldexp_f32 v0, v0, s2
	v_sub_f32_e32 v130, 1.0, v0
	v_cmp_gt_f32_e32 vcc, s42, v130
	s_and_b64 s[2:3], vcc, exec
	s_mov_b32 s92, s45
	s_cselect_b32 s45, 32, 0
	s_ashr_i32 s7, s6, 31
	v_readlane_b32 s52, v252, 26
	s_lshl_b64 s[2:3], s[6:7], 9
	v_readlane_b32 s64, v252, 38
	v_readlane_b32 s65, v252, 39
	s_add_u32 s27, s64, s2
	v_readlane_b32 s66, v252, 40
	s_addc_u32 s90, s65, s3
	v_readlane_b32 s67, v252, 41
	s_add_u32 s91, s66, s2
	v_readfirstlane_b32 s8, v147
	s_addc_u32 s84, s67, s3
	s_lshl_b32 s2, s8, 11
	s_ashr_i32 s3, s2, 31
	s_mov_b32 s47, s44
	s_lshl_b32 s44, s8, 3
	s_lshl_b64 s[76:77], s[2:3], 2
	s_add_u32 s6, s27, s76
	s_addc_u32 s7, s90, s77
	s_lshl_b32 s2, s8, 13
	s_add_i32 s85, s2, 0
	s_add_u32 s68, s91, s76
	v_readlane_b32 s62, v252, 36
	s_addc_u32 s69, s84, s77
	s_or_b32 s8, s44, 1
	s_add_i32 s62, s2, s89
	s_lshl_b32 s2, s8, 8
	s_ashr_i32 s3, s2, 31
	s_lshl_b64 s[74:75], s[2:3], 2
	v_readlane_b32 s13, v254, 48
	s_add_u32 s12, s27, s74
	s_addc_u32 s13, s90, s75
	s_lshl_b32 s2, s8, 10
	s_add_i32 s26, s2, 0
	s_add_u32 s14, s91, s74
	v_readlane_b32 s60, v252, 34
	s_addc_u32 s15, s84, s75
	s_or_b32 s8, s44, 2
	s_add_i32 s60, s2, s89
	s_lshl_b32 s2, s8, 8
	s_ashr_i32 s3, s2, 31
	s_lshl_b64 s[72:73], s[2:3], 2
	s_mov_b64 s[48:49], s[16:17]
	s_add_u32 s16, s27, s72
	v_readlane_b32 s61, v252, 35
	s_addc_u32 s17, s90, s73
	s_lshl_b32 s2, s8, 10
	s_add_i32 s61, s2, 0
	s_add_u32 s18, s91, s72
	v_readlane_b32 s57, v252, 31
	s_addc_u32 s19, s84, s73
	s_or_b32 s8, s44, 3
	s_add_i32 s57, s2, s89
	s_lshl_b32 s2, s8, 8
	s_ashr_i32 s3, s2, 31
	s_lshl_b64 s[70:71], s[2:3], 2
	s_add_u32 s20, s27, s70
	v_readlane_b32 s58, v252, 32
	s_addc_u32 s21, s90, s71
	s_lshl_b32 s2, s8, 10
	s_add_i32 s58, s2, 0
	s_add_u32 s22, s91, s70
	v_readlane_b32 s55, v252, 29
	s_addc_u32 s23, s84, s71
	s_or_b32 s36, s44, 4
	s_add_i32 s55, s2, s89
	s_lshl_b32 s2, s36, 8
	s_ashr_i32 s3, s2, 31
	s_lshl_b64 s[8:9], s[2:3], 2
	s_add_u32 s24, s27, s8
	v_readlane_b32 s56, v252, 30
	s_addc_u32 s25, s90, s9
	s_lshl_b32 s2, s36, 10
	s_add_i32 s56, s2, 0
	s_add_u32 s36, s91, s8
	v_readlane_b32 s53, v252, 27
	s_addc_u32 s37, s84, s9
	s_or_b32 s40, s44, 5
	s_add_i32 s53, s2, s89
	s_lshl_b32 s2, s40, 8
	s_ashr_i32 s3, s2, 31
	s_lshl_b64 s[2:3], s[2:3], 2
	v_mov_b32_e32 v0, 0x42000000
	s_add_u32 s38, s27, s2
	v_lshlrev_b32_e32 v132, 5, v137
	v_cndmask_b32_e32 v131, 0, v0, vcc
	v_readlane_b32 s54, v252, 28
	s_addc_u32 s39, s90, s3
	s_lshl_b32 s42, s40, 10
	v_or_b32_e32 v0, v132, v135
	s_add_i32 s54, s42, 0
	v_lshl_add_u32 v0, v0, 7, v139
	s_add_u32 s40, s91, s2
	v_or_b32_e32 v0, v0, v141
	s_addc_u32 s41, s84, s3
	s_add_i32 s52, s42, s89
	v_lshl_add_u64 v[144:145], v[0:1], 1, s[10:11]
	s_or_b32 s42, s44, 6
	v_lshlrev_b32_e32 v0, 4, v146
	v_and_b32_e32 v156, 0x3f0, v0
	s_mov_b32 m0, s85
	s_nop 0
	global_load_lds_dwordx4 v156, s[6:7]
	s_lshl_b32 s6, s42, 8
	s_ashr_i32 s7, s6, 31
	s_lshl_b64 s[10:11], s[6:7], 2
	s_mov_b32 m0, s62
	s_nop 0
	global_load_lds_dwordx4 v156, s[68:69]
	s_add_u32 s6, s27, s10
	v_readlane_b32 s59, v252, 33
	s_addc_u32 s7, s90, s11
	s_lshl_b32 s46, s42, 10
	v_ldexp_f32 v0, v130, s45
	s_add_i32 s59, s46, 0
	s_mov_b32 m0, s26
	s_nop 0
	global_load_lds_dwordx4 v156, s[12:13]
	v_log_f32_e32 v0, v0
	s_add_u32 s42, s91, s10
	s_mov_b32 s50, s43
	s_addc_u32 s43, s84, s11
	s_or_b32 s13, s44, 7
	s_mov_b32 m0, s60
	s_nop 0
	global_load_lds_dwordx4 v156, s[14:15]
	s_lshl_b32 s14, s13, 8
	v_or_b32_e32 v161, v139, v141
	s_ashr_i32 s15, s14, 31
	v_sub_f32_e32 v160, v0, v131
	v_lshlrev_b32_e32 v0, 10, v161
	v_lshlrev_b32_e32 v130, 7, v161
	v_lshlrev_b32_e32 v131, 4, v137
	s_lshl_b64 s[68:69], s[14:15], 2
	s_mov_b32 m0, s61
	s_nop 0
	global_load_lds_dwordx4 v156, s[16:17]
	v_or3_b32 v130, v130, v131, v135
	v_or3_b32 v146, v0, v135, v132
	v_sub_u32_e32 v0, 0x7f, v161
	v_lshl_add_u32 v155, v130, 2, 0
	s_mov_b32 m0, s57
	s_nop 0
	global_load_lds_dwordx4 v156, s[18:19]
	v_cvt_f32_i32_e32 v0, v0
	v_sub_u32_e32 v130, 0x7e, v161
	s_mov_b32 m0, s58
	s_nop 0
	global_load_lds_dwordx4 v156, s[20:21]
	v_cvt_f32_i32_e32 v130, v130
	s_mov_b32 m0, s55
	s_nop 0
	global_load_lds_dwordx4 v156, s[22:23]
	v_mul_f32_e32 v0, v160, v0
	s_mov_b32 m0, s56
	s_nop 0
	global_load_lds_dwordx4 v156, s[24:25]
	s_add_i32 s12, s46, s89
	s_mov_b32 m0, s53
	s_nop 0
	global_load_lds_dwordx4 v156, s[36:37]
	v_exp_f32_e32 v148, v0
	s_mov_b32 m0, s54
	s_nop 0
	global_load_lds_dwordx4 v156, s[38:39]
	v_mul_f32_e32 v0, v160, v130
	v_sub_u32_e32 v130, 0x7d, v161
	s_add_u32 s16, s27, s68
	s_mov_b32 m0, s52
	s_nop 0
	global_load_lds_dwordx4 v156, s[40:41]
	v_cvt_f32_i32_e32 v130, v130
	v_sub_u32_e32 v131, 0x7c, v161
	s_addc_u32 s17, s90, s69
	s_lshl_b32 s13, s13, 10
	s_mov_b32 m0, s59
	s_nop 0
	global_load_lds_dwordx4 v156, s[6:7]
	v_cvt_f32_i32_e32 v131, v131
	s_add_i32 s14, s13, 0
	s_mov_b32 m0, s12
	s_nop 0
	global_load_lds_dwordx4 v156, s[42:43]
	s_add_u32 s44, s91, s68
	s_mov_b32 m0, s14
	s_nop 0
	global_load_lds_dwordx4 v156, s[16:17]
	s_addc_u32 s45, s84, s69
	s_add_i32 s13, s13, s89
	s_mov_b32 m0, s13
	s_nop 0
	global_load_lds_dwordx4 v156, s[44:45]
	v_exp_f32_e32 v150, v0
	v_mul_f32_e32 v0, v160, v130
	v_mov_b32_e32 v147, v1
	v_add_u32_e32 v157, 0x10000, v155
	s_waitcnt vmcnt(0)
	s_waitcnt vmcnt(63) expcnt(7) lgkmcnt(15)
	s_barrier
; __device__ __forceinline__ unsigned pack2(float a, float b) { return (unsigned)f2bf(a) | ((unsigned)f2bf(b) << 16); }
; __device__ __forceinline__ float fexp2(float x) { return __builtin_amdgcn_exp2f(x); }
; template <int EPI, bool HS = false>
; __device__ __forceinline__ void gemm_phase(const Params& p, const GemmCfg& g, char* shm, const int wave_s) {
;     ...
;           for (int m = 0; m < 4; ++m) {
;             const int jj0 = wr * 64 + m * 16 + fq * 4;
;             const float k0 = fexp2(lg2 * (float)(127 - jj0));
;             const f32x4 r4 = *(const f32x4*)(rsw + ai * 128 + m * 16);
; #pragma unroll
;             for (int bj = 0; bj < 2; ++bj) {
;               float y1[4], y2[4];
; #pragma unroll
;               for (int j = 0; j < 4; ++j) {
;                 const int lr = ai * 128 + m * 16 + j;
;                 float cs = *(const float*)(rl + ((m * 16 + j) * 128 + bj * 64) * 4), sn = *(const float*)(rl + 65536 + ((m * 16 + j) * 128 + bj * 64) * 4);
;                 float x1 = r4[j] * acc[ai][bj][m][0][j] + swv[bj][0], x2 = r4[j] * acc[ai][bj][m][1][j] + swv[bj][1];
;                 y1[j] = (x1 * cs - x2 * sn) * scl;
;                 y2[j] = (x2 * cs + x1 * sn) * scl;
;                 dst[tb + lr * 1024 + bj * 128] = f2bf(y1[j]);
;                 dst[tb + lr * 1024 + bj * 128 + 16] = f2bf(y2[j]);
;               }
;               if (isk) {
;                 float d0 = k0, d1 = fexp2(lg2 * (float)(126 - jj0)), d2 = fexp2(lg2 * (float)(125 - jj0)),
;                       d3 = fexp2(lg2 * (float)(124 - jj0));
;                 uint2 v1, v2;
;                 v1.x = pack2(y1[0] * d0, y1[1] * d1); v1.y = pack2(y1[2] * d2, y1[3] * d3);
;                 v2.x = pack2(y2[0] * d0, y2[1] * d1); v2.y = pack2(y2[2] * d2, y2[3] * d3);
;                 *(uint2*)(kt_t + kb + ai * 256 * 128 + (bj * 128) * 128 + m * 16) = v1;
;                 *(uint2*)(kt_t + kb + ai * 256 * 128 + (bj * 128 + 16) * 128 + m * 16) = v2;
;               }
	v_exp_f32_e32 v149, v0
	v_mul_f32_e32 v0, v160, v131
	ds_read2st64_b32 v[164:165], v155 offset1:2
	v_lshl_add_u64 v[152:153], v[146:147], 1, s[0:1]
	v_add_u32_e32 v147, 0x10200, v155
	ds_read2st64_b32 v[166:167], v155 offset0:4 offset1:6
	v_add_u32_e32 v158, 0x10400, v155
	ds_read_b128 v[130:133], v154
	ds_read_b32 v168, v157
	ds_read_b32 v170, v147
	ds_read_b32 v169, v158
	v_add_u32_e32 v159, 0x10600, v155
	ds_read_b32 v171, v159
	s_waitcnt lgkmcnt(4)
	v_pk_mul_f32 v[128:129], v[128:129], v[132:133]
	v_pk_mul_f32 v[126:127], v[126:127], v[130:131]
	v_mov_b32_e32 v177, v128
	v_mov_b32_e32 v176, v126
	v_pk_mul_f32 v[124:125], v[124:125], v[132:133]
	v_pk_mul_f32 v[180:181], v[122:123], v[130:131]
	v_pk_add_f32 v[176:177], v[140:141], v[176:177] op_sel_hi:[0,1]
	v_mov_b32_e32 v122, v180
	v_mov_b32_e32 v123, v124
	v_pk_add_f32 v[182:183], v[138:139], v[122:123] op_sel_hi:[0,1]
	v_mov_b32_e32 v184, v164
	v_mov_b32_e32 v185, v166
	s_waitcnt lgkmcnt(1)
	v_pk_mul_f32 v[122:123], v[168:169], v[176:177]
	v_mov_b32_e32 v128, v127
	v_exp_f32_e32 v151, v0
	v_or_b32_e32 v0, 0x800, v146
	v_pk_fma_f32 v[122:123], v[184:185], v[182:183], v[122:123] neg_lo:[0,0,1] neg_hi:[0,0,1]
	v_pk_add_f32 v[128:129], v[140:141], v[128:129] op_sel_hi:[0,1]
	v_mov_b32_e32 v124, v181
	v_lshl_add_u64 v[172:173], v[0:1], 1, s[0:1]
	v_or_b32_e32 v0, 0x810, v146
	v_pk_mul_f32 v[122:123], v[142:143], v[122:123] op_sel_hi:[0,1]
	v_pk_add_f32 v[180:181], v[138:139], v[124:125] op_sel_hi:[0,1]
	v_mov_b32_e32 v166, v165
	s_waitcnt lgkmcnt(0)
	v_pk_mul_f32 v[124:125], v[128:129], v[170:171]
	v_lshl_add_u64 v[174:175], v[0:1], 1, s[0:1]
	s_nop 0
	v_pk_fma_f32 v[124:125], v[180:181], v[166:167], v[124:125] neg_lo:[0,0,1] neg_hi:[0,0,1]
	v_cvt_pk_bf16_f32 v0, v122, v122
	v_pk_mul_f32 v[124:125], v[142:143], v[124:125] op_sel_hi:[0,1]
	global_store_short_d16_hi v[152:153], v0, off
	s_nop 0
	v_cvt_pk_bf16_f32 v0, v124, v124
	v_pk_mul_f32 v[126:127], v[168:169], v[182:183]
	global_store_short_d16_hi v[152:153], v0, off offset:2048
	s_nop 0
	v_pk_fma_f32 v[126:127], v[184:185], v[176:177], v[126:127]
	v_cvt_pk_bf16_f32 v0, v123, v123
	v_pk_mul_f32 v[126:127], v[142:143], v[126:127] op_sel_hi:[0,1]
	v_pk_mul_f32 v[164:165], v[180:181], v[170:171]
	global_store_short_d16_hi v[172:173], v0, off
	s_nop 0
	v_pk_fma_f32 v[128:129], v[128:129], v[166:167], v[164:165]
	v_cvt_pk_bf16_f32 v0, v126, v126
	v_pk_mul_f32 v[128:129], v[142:143], v[128:129] op_sel_hi:[0,1]
	global_store_short_d16_hi v[152:153], v0, off offset:32
	s_nop 0
	v_cvt_pk_bf16_f32 v0, v128, v128
	global_store_short_d16_hi v[152:153], v0, off offset:2080
	s_nop 0
	v_cvt_pk_bf16_f32 v0, v127, v127
	global_store_short_d16_hi v[174:175], v0, off
	s_nop 0
	v_cvt_pk_bf16_f32 v135, v125, v125
	v_or_b32_e32 v0, 0xc00, v146
	v_lshl_add_u64 v[164:165], v[0:1], 1, s[0:1]
	v_bfe_u32 v0, v129, 16, 1
	global_store_short_d16_hi v[164:165], v135, off
	v_add3_u32 v135, v129, v0, s81
	v_or_b32_e32 v0, 0xc10, v146
	s_cmp_lt_i32 s88, 32
	v_lshl_add_u64 v[164:165], v[0:1], 1, s[0:1]
	v_readlane_b32 s63, v252, 37
	global_store_short_d16_hi v[164:165], v135, off
	s_cbranch_scc1 .LBB0_598
	v_pk_mul_f32 v[122:123], v[148:149], v[122:123]
	v_pk_mul_f32 v[124:125], v[150:151], v[124:125]
	s_nop 0
	s_nop 0
	v_cvt_pk_bf16_f32 v122, v122, v122
	v_cvt_pk_bf16_f32 v0, v123, v123
	s_nop 0
	v_and_b32_sdwa v135, v124, v178 dst_sel:DWORD dst_unused:UNUSED_PAD src0_sel:WORD_1 src1_sel:DWORD
	v_cvt_pk_bf16_f32 v123, v125, v125
	v_add3_u32 v124, v124, v135, s81
	v_pk_mul_f32 v[128:129], v[150:151], v[128:129]
	v_and_b32_e32 v123, 0xffff0000, v123
	v_and_b32_e32 v124, 0xffff0000, v124
	v_pk_mul_f32 v[126:127], v[148:149], v[126:127]
	v_or_b32_sdwa v123, v123, v0 dst_sel:DWORD dst_unused:UNUSED_PAD src0_sel:DWORD src1_sel:WORD_1
	v_or_b32_sdwa v122, v124, v122 dst_sel:DWORD dst_unused:UNUSED_PAD src0_sel:DWORD src1_sel:WORD_1
	s_nop 0
	global_store_dwordx2 v[144:145], v[122:123], off
	s_nop 0
	s_nop 0
	v_cvt_pk_bf16_f32 v124, v128, v128
	s_nop 0
	v_cvt_pk_bf16_f32 v122, v126, v126
	v_cvt_pk_bf16_f32 v123, v129, v129
	v_and_b32_e32 v124, 0xffff0000, v124
	v_cvt_pk_bf16_f32 v0, v127, v127
	v_and_b32_e32 v123, 0xffff0000, v123
	v_or_b32_sdwa v122, v124, v122 dst_sel:DWORD dst_unused:UNUSED_PAD src0_sel:DWORD src1_sel:WORD_1
	v_add_co_u32_e32 v124, vcc, 0x1000, v144
	v_or_b32_sdwa v123, v123, v0 dst_sel:DWORD dst_unused:UNUSED_PAD src0_sel:DWORD src1_sel:WORD_1
	s_nop 0
	v_addc_co_u32_e32 v125, vcc, 0, v145, vcc
	global_store_dwordx2 v[124:125], v[122:123], off
; __device__ __forceinline__ unsigned pack2(float a, float b) { return (unsigned)f2bf(a) | ((unsigned)f2bf(b) << 16); }
; __device__ __forceinline__ float fexp2(float x) { return __builtin_amdgcn_exp2f(x); }
; template <int EPI, bool HS = false>
; __device__ __forceinline__ void gemm_phase(const Params& p, const GemmCfg& g, char* shm, const int wave_s) {
;     ...
;           for (int m = 0; m < 4; ++m) {
;             const int jj0 = wr * 64 + m * 16 + fq * 4;
;             const float k0 = fexp2(lg2 * (float)(127 - jj0));
;             const f32x4 r4 = *(const f32x4*)(rsw + ai * 128 + m * 16);
; #pragma unroll
;             for (int bj = 0; bj < 2; ++bj) {
;               float y1[4], y2[4];
; #pragma unroll
;               for (int j = 0; j < 4; ++j) {
;                 const int lr = ai * 128 + m * 16 + j;
;                 float cs = *(const float*)(rl + ((m * 16 + j) * 128 + bj * 64) * 4), sn = *(const float*)(rl + 65536 + ((m * 16 + j) * 128 + bj * 64) * 4);
;                 float x1 = r4[j] * acc[ai][bj][m][0][j] + swv[bj][0], x2 = r4[j] * acc[ai][bj][m][1][j] + swv[bj][1];
;                 y1[j] = (x1 * cs - x2 * sn) * scl;
;                 y2[j] = (x2 * cs + x1 * sn) * scl;
;                 dst[tb + lr * 1024 + bj * 128] = f2bf(y1[j]);
;                 dst[tb + lr * 1024 + bj * 128 + 16] = f2bf(y2[j]);
;               }
;               if (isk) {
;                 float d0 = k0, d1 = fexp2(lg2 * (float)(126 - jj0)), d2 = fexp2(lg2 * (float)(125 - jj0)),
;                       d3 = fexp2(lg2 * (float)(124 - jj0));
;                 uint2 v1, v2;
;                 v1.x = pack2(y1[0] * d0, y1[1] * d1); v1.y = pack2(y1[2] * d2, y1[3] * d3);
;                 v2.x = pack2(y2[0] * d0, y2[1] * d1); v2.y = pack2(y2[2] * d2, y2[3] * d3);
;                 *(uint2*)(kt_t + kb + ai * 256 * 128 + (bj * 128) * 128 + m * 16) = v1;
;                 *(uint2*)(kt_t + kb + ai * 256 * 128 + (bj * 128 + 16) * 128 + m * 16) = v2;
;               }
.LBB0_598:
	ds_read2st64_b32 v[126:127], v155 offset0:1 offset1:3
	v_add_u32_e32 v122, 0x10100, v155
	ds_read2st64_b32 v[128:129], v155 offset0:5 offset1:7
	v_add_u32_e32 v123, 0x10300, v155
	v_add_u32_e32 v124, 0x10500, v155
	v_add_u32_e32 v125, 0x10700, v155
	ds_read_b32 v168, v122
	ds_read_b32 v170, v123
	ds_read_b32 v169, v124
	ds_read_b32 v171, v125
	v_pk_mul_f32 v[120:121], v[120:121], v[132:133]
	v_pk_mul_f32 v[118:119], v[118:119], v[130:131]
	v_mov_b32_e32 v173, v120
	v_mov_b32_e32 v172, v118
	v_pk_mul_f32 v[116:117], v[116:117], v[132:133]
	v_pk_mul_f32 v[130:131], v[114:115], v[130:131]
	v_pk_add_f32 v[172:173], v[136:137], v[172:173] op_sel_hi:[0,1]
	v_mov_b32_e32 v114, v130
	v_mov_b32_e32 v115, v116
	v_pk_add_f32 v[132:133], v[134:135], v[114:115] op_sel_hi:[0,1]
	s_waitcnt lgkmcnt(5)
	v_mov_b32_e32 v174, v126
	s_waitcnt lgkmcnt(4)
	v_mov_b32_e32 v175, v128
	s_waitcnt lgkmcnt(1)
	v_pk_mul_f32 v[114:115], v[172:173], v[168:169]
	v_mov_b32_e32 v120, v119
	v_mov_b32_e32 v143, v142
	v_or_b32_e32 v0, 0x880, v146
	v_pk_fma_f32 v[114:115], v[132:133], v[174:175], v[114:115] neg_lo:[0,0,1] neg_hi:[0,0,1]
	v_pk_add_f32 v[120:121], v[136:137], v[120:121] op_sel_hi:[0,1]
	v_mov_b32_e32 v116, v131
	v_lshl_add_u64 v[164:165], v[0:1], 1, s[0:1]
	v_or_b32_e32 v0, 0x890, v146
	v_pk_mul_f32 v[114:115], v[142:143], v[114:115]
	v_pk_add_f32 v[130:131], v[134:135], v[116:117] op_sel_hi:[0,1]
	v_mov_b32_e32 v128, v127
	s_waitcnt lgkmcnt(0)
	v_pk_mul_f32 v[116:117], v[120:121], v[170:171]
	v_lshl_add_u64 v[166:167], v[0:1], 1, s[0:1]
	s_nop 0
	v_pk_fma_f32 v[116:117], v[130:131], v[128:129], v[116:117] neg_lo:[0,0,1] neg_hi:[0,0,1]
	v_cvt_pk_bf16_f32 v0, v114, v114
	v_pk_mul_f32 v[116:117], v[142:143], v[116:117]
	global_store_short_d16_hi v[152:153], v0, off offset:256
	s_nop 0
	v_cvt_pk_bf16_f32 v0, v116, v116
	v_pk_mul_f32 v[118:119], v[132:133], v[168:169]
	global_store_short_d16_hi v[152:153], v0, off offset:2304
	s_nop 0
	v_pk_fma_f32 v[118:119], v[172:173], v[174:175], v[118:119]
	v_cvt_pk_bf16_f32 v0, v115, v115
	v_pk_mul_f32 v[118:119], v[142:143], v[118:119]
	v_pk_mul_f32 v[126:127], v[130:131], v[170:171]
	global_store_short_d16_hi v[164:165], v0, off
	s_nop 0
	v_pk_fma_f32 v[120:121], v[120:121], v[128:129], v[126:127]
	v_cvt_pk_bf16_f32 v0, v118, v118
	v_pk_mul_f32 v[120:121], v[142:143], v[120:121]
	global_store_short_d16_hi v[152:153], v0, off offset:288
	s_nop 0
	v_cvt_pk_bf16_f32 v0, v120, v120
	global_store_short_d16_hi v[152:153], v0, off offset:2336
	s_nop 0
	v_cvt_pk_bf16_f32 v0, v119, v119
	global_store_short_d16_hi v[166:167], v0, off
	s_nop 0
	v_cvt_pk_bf16_f32 v128, v117, v117
	v_or_b32_e32 v0, 0xc80, v146
	v_lshl_add_u64 v[126:127], v[0:1], 1, s[0:1]
	v_bfe_u32 v0, v121, 16, 1
	global_store_short_d16_hi v[126:127], v128, off
	v_add3_u32 v128, v121, v0, s81
	v_or_b32_e32 v0, 0xc90, v146
	v_lshl_add_u64 v[126:127], v[0:1], 1, s[0:1]
	v_cndmask_b32_e64 v0, 0, 1, s[4:5]
	v_cmp_ne_u32_e64 s[6:7], 1, v0
	s_andn2_b64 vcc, exec, s[4:5]
	global_store_short_d16_hi v[126:127], v128, off
	s_cbranch_vccnz .LBB0_600
	v_pk_mul_f32 v[114:115], v[148:149], v[114:115]
	v_pk_mul_f32 v[116:117], v[150:151], v[116:117]
	s_nop 0
	s_nop 0
	v_cvt_pk_bf16_f32 v114, v114, v114
	s_nop 0
	v_cvt_pk_bf16_f32 v0, v115, v115
	s_nop 0
	v_cvt_pk_bf16_f32 v116, v116, v116
	v_cvt_pk_bf16_f32 v115, v117, v117
	v_and_b32_e32 v116, 0xffff0000, v116
	s_mov_b32 s4, 0x8000
	v_and_b32_e32 v115, 0xffff0000, v115
	v_or_b32_sdwa v114, v116, v114 dst_sel:DWORD dst_unused:UNUSED_PAD src0_sel:DWORD src1_sel:WORD_1
	v_add_co_u32_e32 v116, vcc, s4, v144
	v_pk_mul_f32 v[120:121], v[150:151], v[120:121]
	v_or_b32_sdwa v115, v115, v0 dst_sel:DWORD dst_unused:UNUSED_PAD src0_sel:DWORD src1_sel:WORD_1
	v_addc_co_u32_e32 v117, vcc, 0, v145, vcc
	v_pk_mul_f32 v[118:119], v[148:149], v[118:119]
	global_store_dwordx2 v[116:117], v[114:115], off
	s_nop 0
	s_nop 0
	s_nop 0
	v_cvt_pk_bf16_f32 v116, v120, v120
	s_nop 0
	v_cvt_pk_bf16_f32 v114, v118, v118
	v_cvt_pk_bf16_f32 v115, v121, v121
	v_and_b32_e32 v116, 0xffff0000, v116
	v_cvt_pk_bf16_f32 v0, v119, v119
	v_and_b32_e32 v115, 0xffff0000, v115
	v_or_b32_sdwa v114, v116, v114 dst_sel:DWORD dst_unused:UNUSED_PAD src0_sel:DWORD src1_sel:WORD_1
	v_add_co_u32_e32 v116, vcc, 0x9000, v144
	v_or_b32_sdwa v115, v115, v0 dst_sel:DWORD dst_unused:UNUSED_PAD src0_sel:DWORD src1_sel:WORD_1
	s_nop 0
	v_addc_co_u32_e32 v117, vcc, 0, v145, vcc
	global_store_dwordx2 v[116:117], v[114:115], off
; __device__ __forceinline__ unsigned pack2(float a, float b) { return (unsigned)f2bf(a) | ((unsigned)f2bf(b) << 16); }
; __device__ __forceinline__ float fexp2(float x) { return __builtin_amdgcn_exp2f(x); }
; template <int EPI, bool HS = false>
; __device__ __forceinline__ void gemm_phase(const Params& p, const GemmCfg& g, char* shm, const int wave_s) {
;     ...
;           for (int m = 0; m < 4; ++m) {
;             const int jj0 = wr * 64 + m * 16 + fq * 4;
;             const float k0 = fexp2(lg2 * (float)(127 - jj0));
;             const f32x4 r4 = *(const f32x4*)(rsw + ai * 128 + m * 16);
; #pragma unroll
;             for (int bj = 0; bj < 2; ++bj) {
;               float y1[4], y2[4];
; #pragma unroll
;               for (int j = 0; j < 4; ++j) {
;                 const int lr = ai * 128 + m * 16 + j;
;                 float cs = *(const float*)(rl + ((m * 16 + j) * 128 + bj * 64) * 4), sn = *(const float*)(rl + 65536 + ((m * 16 + j) * 128 + bj * 64) * 4);
;                 float x1 = r4[j] * acc[ai][bj][m][0][j] + swv[bj][0], x2 = r4[j] * acc[ai][bj][m][1][j] + swv[bj][1];
;                 y1[j] = (x1 * cs - x2 * sn) * scl;
;                 y2[j] = (x2 * cs + x1 * sn) * scl;
;                 dst[tb + lr * 1024 + bj * 128] = f2bf(y1[j]);
;                 dst[tb + lr * 1024 + bj * 128 + 16] = f2bf(y2[j]);
;               }
;               if (isk) {
;                 float d0 = k0, d1 = fexp2(lg2 * (float)(126 - jj0)), d2 = fexp2(lg2 * (float)(125 - jj0)),
;                       d3 = fexp2(lg2 * (float)(124 - jj0));
;                 uint2 v1, v2;
;                 v1.x = pack2(y1[0] * d0, y1[1] * d1); v1.y = pack2(y1[2] * d2, y1[3] * d3);
;                 v2.x = pack2(y2[0] * d0, y2[1] * d1); v2.y = pack2(y2[2] * d2, y2[3] * d3);
;                 *(uint2*)(kt_t + kb + ai * 256 * 128 + (bj * 128) * 128 + m * 16) = v1;
;                 *(uint2*)(kt_t + kb + ai * 256 * 128 + (bj * 128 + 16) * 128 + m * 16) = v2;
;               }
.LBB0_600:
	v_mov_b32_e32 v141, v140
	v_mov_b32_e32 v139, v138
	v_or_b32_e32 v0, 16, v161
	v_sub_u32_e32 v114, 0x7f, v0
	v_cvt_f32_i32_e32 v114, v114
	v_sub_u32_e32 v115, 0x7e, v0
	v_cvt_f32_i32_e32 v115, v115
	ds_read2st64_b32 v[130:131], v155 offset0:32 offset1:34
	v_mul_f32_e32 v114, v160, v114
	v_exp_f32_e32 v118, v114
	v_sub_u32_e32 v114, 0x7d, v0
	v_cvt_f32_i32_e32 v114, v114
	v_sub_u32_e32 v0, 0x7c, v0
	v_cvt_f32_i32_e32 v0, v0
	v_mul_f32_e32 v115, v160, v115
	v_mul_f32_e32 v114, v160, v114
	v_exp_f32_e32 v120, v115
	v_exp_f32_e32 v119, v114
	v_add_u32_e32 v126, 0x12000, v155
	v_add_u32_e32 v127, 0x12200, v155
	ds_read2st64_b32 v[168:169], v155 offset0:36 offset1:38
	v_add_u32_e32 v128, 0x12400, v155
	ds_read_b128 v[114:117], v154 offset:64
	ds_read_b32 v170, v126
	ds_read_b32 v172, v127
	ds_read_b32 v171, v128
	v_mul_f32_e32 v0, v160, v0
	v_exp_f32_e32 v121, v0
	v_or_b32_e32 v0, 0x4000, v146
	s_waitcnt lgkmcnt(3)
	v_pk_mul_f32 v[112:113], v[112:113], v[116:117]
	v_pk_mul_f32 v[110:111], v[110:111], v[114:115]
	v_lshl_add_u64 v[132:133], v[0:1], 1, s[0:1]
	v_or_b32_e32 v0, 0x4010, v146
	v_mov_b32_e32 v180, v110
	v_mov_b32_e32 v181, v112
	v_pk_mul_f32 v[108:109], v[108:109], v[116:117]
	v_pk_mul_f32 v[182:183], v[106:107], v[114:115]
	v_lshl_add_u64 v[152:153], v[0:1], 1, s[0:1]
	v_or_b32_e32 v0, 0x4400, v146
	v_add_u32_e32 v129, 0x12600, v155
	v_pk_add_f32 v[180:181], v[140:141], v[180:181]
	v_mov_b32_e32 v106, v182
	v_mov_b32_e32 v107, v108
	v_lshl_add_u64 v[164:165], v[0:1], 1, s[0:1]
	v_or_b32_e32 v0, 0x4410, v146
	ds_read_b32 v173, v129
	v_pk_add_f32 v[184:185], v[138:139], v[106:107]
	v_mov_b32_e32 v186, v130
	v_mov_b32_e32 v187, v168
	s_waitcnt lgkmcnt(1)
	v_pk_mul_f32 v[106:107], v[170:171], v[180:181]
	v_lshl_add_u64 v[166:167], v[0:1], 1, s[0:1]
	v_or_b32_e32 v0, 0x4800, v146
	v_pk_fma_f32 v[106:107], v[186:187], v[184:185], v[106:107] neg_lo:[0,0,1] neg_hi:[0,0,1]
	v_lshl_add_u64 v[174:175], v[0:1], 1, s[0:1]
	v_or_b32_e32 v0, 0x4810, v146
	v_pk_mul_f32 v[106:107], v[142:143], v[106:107]
	v_lshl_add_u64 v[176:177], v[0:1], 1, s[0:1]
	s_nop 0
	v_mov_b32_e32 v112, v111
	v_cvt_pk_bf16_f32 v0, v106, v106
	v_pk_add_f32 v[112:113], v[140:141], v[112:113]
	v_mov_b32_e32 v108, v183
	global_store_short_d16_hi v[132:133], v0, off
	v_pk_add_f32 v[132:133], v[138:139], v[108:109]
	v_mov_b32_e32 v168, v131
	s_waitcnt lgkmcnt(0)
	v_pk_mul_f32 v[108:109], v[112:113], v[172:173]
	v_pk_mul_f32 v[110:111], v[170:171], v[184:185]
	v_pk_fma_f32 v[108:109], v[132:133], v[168:169], v[108:109] neg_lo:[0,0,1] neg_hi:[0,0,1]
	v_pk_fma_f32 v[110:111], v[186:187], v[180:181], v[110:111]
	v_pk_mul_f32 v[108:109], v[142:143], v[108:109]
	v_pk_mul_f32 v[110:111], v[142:143], v[110:111]
	s_nop 0
	v_cvt_pk_bf16_f32 v0, v108, v108
	global_store_short_d16_hi v[164:165], v0, off
	s_nop 0
	v_cvt_pk_bf16_f32 v0, v107, v107
	v_pk_mul_f32 v[130:131], v[132:133], v[172:173]
	global_store_short_d16_hi v[174:175], v0, off
	s_nop 0
	v_pk_fma_f32 v[112:113], v[112:113], v[168:169], v[130:131]
	v_cvt_pk_bf16_f32 v0, v110, v110
	v_pk_mul_f32 v[112:113], v[142:143], v[112:113]
	global_store_short_d16_hi v[152:153], v0, off
	s_nop 0
	v_cvt_pk_bf16_f32 v0, v112, v112
	global_store_short_d16_hi v[166:167], v0, off
	s_nop 0
	v_cvt_pk_bf16_f32 v0, v111, v111
	global_store_short_d16_hi v[176:177], v0, off
	s_nop 0
	v_cvt_pk_bf16_f32 v132, v109, v109
	v_or_b32_e32 v0, 0x4c00, v146
	v_lshl_add_u64 v[130:131], v[0:1], 1, s[0:1]
	v_bfe_u32 v0, v113, 16, 1
	global_store_short_d16_hi v[130:131], v132, off
	v_add3_u32 v132, v113, v0, s81
	v_or_b32_e32 v0, 0x4c10, v146
	v_lshl_add_u64 v[130:131], v[0:1], 1, s[0:1]
	s_and_b64 vcc, exec, s[6:7]
	s_mov_b32 s44, s47
	s_mov_b32 s45, s92
	s_mov_b32 s42, 0x800000
	s_mov_b32 s43, s50
	global_store_short_d16_hi v[130:131], v132, off
	s_cbranch_vccnz .LBB0_602
	v_pk_mul_f32 v[106:107], v[118:119], v[106:107]
	v_pk_mul_f32 v[108:109], v[120:121], v[108:109]
	s_nop 0
	s_nop 0
	v_cvt_pk_bf16_f32 v106, v106, v106
	v_cvt_pk_bf16_f32 v0, v107, v107
	s_nop 0
	s_nop 0
	v_cvt_pk_bf16_f32 v107, v109, v109
	v_cvt_pk_bf16_f32 v108, v108, v108
	v_pk_mul_f32 v[112:113], v[120:121], v[112:113]
	v_and_b32_e32 v107, 0xffff0000, v107
	v_and_b32_e32 v108, 0xffff0000, v108
	v_pk_mul_f32 v[110:111], v[118:119], v[110:111]
	v_or_b32_sdwa v107, v107, v0 dst_sel:DWORD dst_unused:UNUSED_PAD src0_sel:DWORD src1_sel:WORD_1
	v_or_b32_sdwa v106, v108, v106 dst_sel:DWORD dst_unused:UNUSED_PAD src0_sel:DWORD src1_sel:WORD_1
	s_nop 0
	global_store_dwordx2 v[144:145], v[106:107], off offset:32
	s_nop 0
	s_nop 0
	v_cvt_pk_bf16_f32 v108, v112, v112
	s_nop 0
	v_cvt_pk_bf16_f32 v106, v110, v110
	v_cvt_pk_bf16_f32 v107, v113, v113
	v_and_b32_e32 v108, 0xffff0000, v108
	v_cvt_pk_bf16_f32 v0, v111, v111
	v_and_b32_e32 v107, 0xffff0000, v107
	v_or_b32_sdwa v106, v108, v106 dst_sel:DWORD dst_unused:UNUSED_PAD src0_sel:DWORD src1_sel:WORD_1
	v_add_co_u32_e32 v108, vcc, 0x1000, v144
	v_or_b32_sdwa v107, v107, v0 dst_sel:DWORD dst_unused:UNUSED_PAD src0_sel:DWORD src1_sel:WORD_1
	s_nop 0
	v_addc_co_u32_e32 v109, vcc, 0, v145, vcc
	global_store_dwordx2 v[108:109], v[106:107], off offset:32
; __device__ __forceinline__ unsigned pack2(float a, float b) { return (unsigned)f2bf(a) | ((unsigned)f2bf(b) << 16); }
; __device__ __forceinline__ float fexp2(float x) { return __builtin_amdgcn_exp2f(x); }
; template <int EPI, bool HS = false>
; __device__ __forceinline__ void gemm_phase(const Params& p, const GemmCfg& g, char* shm, const int wave_s) {
;     ...
;           for (int m = 0; m < 4; ++m) {
;             const int jj0 = wr * 64 + m * 16 + fq * 4;
;             const float k0 = fexp2(lg2 * (float)(127 - jj0));
;             const f32x4 r4 = *(const f32x4*)(rsw + ai * 128 + m * 16);
; #pragma unroll
;             for (int bj = 0; bj < 2; ++bj) {
;               float y1[4], y2[4];
; #pragma unroll
;               for (int j = 0; j < 4; ++j) {
;                 const int lr = ai * 128 + m * 16 + j;
;                 float cs = *(const float*)(rl + ((m * 16 + j) * 128 + bj * 64) * 4), sn = *(const float*)(rl + 65536 + ((m * 16 + j) * 128 + bj * 64) * 4);
;                 float x1 = r4[j] * acc[ai][bj][m][0][j] + swv[bj][0], x2 = r4[j] * acc[ai][bj][m][1][j] + swv[bj][1];
;                 y1[j] = (x1 * cs - x2 * sn) * scl;
;                 y2[j] = (x2 * cs + x1 * sn) * scl;
;                 dst[tb + lr * 1024 + bj * 128] = f2bf(y1[j]);
;                 dst[tb + lr * 1024 + bj * 128 + 16] = f2bf(y2[j]);
;               }
;               if (isk) {
;                 float d0 = k0, d1 = fexp2(lg2 * (float)(126 - jj0)), d2 = fexp2(lg2 * (float)(125 - jj0)),
;                       d3 = fexp2(lg2 * (float)(124 - jj0));
;                 uint2 v1, v2;
;                 v1.x = pack2(y1[0] * d0, y1[1] * d1); v1.y = pack2(y1[2] * d2, y1[3] * d3);
;                 v2.x = pack2(y2[0] * d0, y2[1] * d1); v2.y = pack2(y2[2] * d2, y2[3] * d3);
;                 *(uint2*)(kt_t + kb + ai * 256 * 128 + (bj * 128) * 128 + m * 16) = v1;
;                 *(uint2*)(kt_t + kb + ai * 256 * 128 + (bj * 128 + 16) * 128 + m * 16) = v2;
;               }
.LBB0_602:
	ds_read2st64_b32 v[110:111], v155 offset0:33 offset1:35
	v_add_u32_e32 v106, 0x12100, v155
	ds_read2st64_b32 v[164:165], v155 offset0:37 offset1:39
	v_add_u32_e32 v107, 0x12300, v155
	v_add_u32_e32 v108, 0x12500, v155
	v_add_u32_e32 v109, 0x12700, v155
	ds_read_b32 v170, v106
	ds_read_b32 v172, v107
	ds_read_b32 v171, v108
	ds_read_b32 v173, v109
	v_or_b32_e32 v0, 0x4080, v146
	v_pk_mul_f32 v[104:105], v[104:105], v[116:117]
	v_pk_mul_f32 v[102:103], v[102:103], v[114:115]
	v_mov_b32_e32 v137, v136
	v_lshl_add_u64 v[112:113], v[0:1], 1, s[0:1]
	v_or_b32_e32 v0, 0x4090, v146
	v_mov_b32_e32 v174, v102
	v_mov_b32_e32 v175, v104
	v_pk_mul_f32 v[100:101], v[100:101], v[116:117]
	v_pk_mul_f32 v[114:115], v[98:99], v[114:115]
	v_mov_b32_e32 v135, v134
	v_lshl_add_u64 v[130:131], v[0:1], 1, s[0:1]
	v_or_b32_e32 v0, 0x4480, v146
	v_pk_add_f32 v[174:175], v[136:137], v[174:175]
	v_mov_b32_e32 v98, v114
	v_mov_b32_e32 v99, v100
	v_lshl_add_u64 v[132:133], v[0:1], 1, s[0:1]
	v_or_b32_e32 v0, 0x4490, v146
	v_pk_add_f32 v[116:117], v[134:135], v[98:99]
	s_waitcnt lgkmcnt(5)
	v_mov_b32_e32 v176, v110
	s_waitcnt lgkmcnt(4)
	v_mov_b32_e32 v177, v164
	s_waitcnt lgkmcnt(1)
	v_pk_mul_f32 v[98:99], v[174:175], v[170:171]
	v_lshl_add_u64 v[152:153], v[0:1], 1, s[0:1]
	v_or_b32_e32 v0, 0x4880, v146
	v_pk_fma_f32 v[98:99], v[116:117], v[176:177], v[98:99] neg_lo:[0,0,1] neg_hi:[0,0,1]
	v_lshl_add_u64 v[166:167], v[0:1], 1, s[0:1]
	v_or_b32_e32 v0, 0x4890, v146
	v_pk_mul_f32 v[98:99], v[142:143], v[98:99]
	v_lshl_add_u64 v[168:169], v[0:1], 1, s[0:1]
	s_nop 0
	v_mov_b32_e32 v104, v103
	v_cvt_pk_bf16_f32 v0, v98, v98
	v_pk_add_f32 v[104:105], v[136:137], v[104:105]
	v_mov_b32_e32 v100, v115
	global_store_short_d16_hi v[112:113], v0, off
	v_pk_add_f32 v[112:113], v[134:135], v[100:101]
	v_mov_b32_e32 v164, v111
	s_waitcnt lgkmcnt(0)
	v_pk_mul_f32 v[100:101], v[104:105], v[172:173]
	v_pk_mul_f32 v[102:103], v[116:117], v[170:171]
	v_pk_fma_f32 v[100:101], v[112:113], v[164:165], v[100:101] neg_lo:[0,0,1] neg_hi:[0,0,1]
	v_pk_fma_f32 v[102:103], v[174:175], v[176:177], v[102:103]
	v_pk_mul_f32 v[100:101], v[142:143], v[100:101]
	v_pk_mul_f32 v[102:103], v[142:143], v[102:103]
	s_nop 0
	v_cvt_pk_bf16_f32 v0, v100, v100
	global_store_short_d16_hi v[132:133], v0, off
	s_nop 0
	v_cvt_pk_bf16_f32 v0, v99, v99
	v_pk_mul_f32 v[110:111], v[112:113], v[172:173]
	global_store_short_d16_hi v[166:167], v0, off
	s_nop 0
	v_pk_fma_f32 v[104:105], v[104:105], v[164:165], v[110:111]
	v_cvt_pk_bf16_f32 v0, v102, v102
	v_pk_mul_f32 v[104:105], v[142:143], v[104:105]
	global_store_short_d16_hi v[130:131], v0, off
	s_nop 0
	v_cvt_pk_bf16_f32 v0, v104, v104
	global_store_short_d16_hi v[152:153], v0, off
	s_nop 0
	v_cvt_pk_bf16_f32 v0, v103, v103
	global_store_short_d16_hi v[168:169], v0, off
	s_nop 0
	v_cvt_pk_bf16_f32 v112, v101, v101
	v_or_b32_e32 v0, 0x4c80, v146
	v_lshl_add_u64 v[110:111], v[0:1], 1, s[0:1]
	v_bfe_u32 v0, v105, 16, 1
	global_store_short_d16_hi v[110:111], v112, off
	v_add3_u32 v112, v105, v0, s81
	v_or_b32_e32 v0, 0x4c90, v146
	v_lshl_add_u64 v[110:111], v[0:1], 1, s[0:1]
	s_and_b64 vcc, exec, s[6:7]
	s_mov_b64 s[46:47], s[48:49]
	global_store_short_d16_hi v[110:111], v112, off
	s_cbranch_vccnz .LBB0_604
	v_pk_mul_f32 v[98:99], v[118:119], v[98:99]
	v_pk_mul_f32 v[100:101], v[120:121], v[100:101]
	s_nop 0
	s_nop 0
	v_cvt_pk_bf16_f32 v98, v98, v98
	s_nop 0
	v_cvt_pk_bf16_f32 v0, v99, v99
	s_nop 0
	v_cvt_pk_bf16_f32 v100, v100, v100
	v_cvt_pk_bf16_f32 v99, v101, v101
	v_and_b32_e32 v100, 0xffff0000, v100
	s_mov_b32 s4, 0x8000
	v_and_b32_e32 v99, 0xffff0000, v99
	v_or_b32_sdwa v98, v100, v98 dst_sel:DWORD dst_unused:UNUSED_PAD src0_sel:DWORD src1_sel:WORD_1
	v_add_co_u32_e32 v100, vcc, s4, v144
	v_pk_mul_f32 v[104:105], v[120:121], v[104:105]
	v_or_b32_sdwa v99, v99, v0 dst_sel:DWORD dst_unused:UNUSED_PAD src0_sel:DWORD src1_sel:WORD_1
	v_addc_co_u32_e32 v101, vcc, 0, v145, vcc
	v_pk_mul_f32 v[102:103], v[118:119], v[102:103]
	global_store_dwordx2 v[100:101], v[98:99], off offset:32
	s_nop 0
	s_nop 0
	s_nop 0
	v_cvt_pk_bf16_f32 v100, v104, v104
	s_nop 0
	v_cvt_pk_bf16_f32 v98, v102, v102
	v_cvt_pk_bf16_f32 v99, v105, v105
	v_and_b32_e32 v100, 0xffff0000, v100
	v_cvt_pk_bf16_f32 v0, v103, v103
	v_and_b32_e32 v99, 0xffff0000, v99
	v_or_b32_sdwa v98, v100, v98 dst_sel:DWORD dst_unused:UNUSED_PAD src0_sel:DWORD src1_sel:WORD_1
	v_add_co_u32_e32 v100, vcc, 0x9000, v144
	v_or_b32_sdwa v99, v99, v0 dst_sel:DWORD dst_unused:UNUSED_PAD src0_sel:DWORD src1_sel:WORD_1
	s_nop 0
	v_addc_co_u32_e32 v101, vcc, 0, v145, vcc
	global_store_dwordx2 v[100:101], v[98:99], off offset:32
; __device__ __forceinline__ unsigned pack2(float a, float b) { return (unsigned)f2bf(a) | ((unsigned)f2bf(b) << 16); }
; __device__ __forceinline__ float fexp2(float x) { return __builtin_amdgcn_exp2f(x); }
; template <int EPI, bool HS = false>
; __device__ __forceinline__ void gemm_phase(const Params& p, const GemmCfg& g, char* shm, const int wave_s) {
;     ...
;           for (int m = 0; m < 4; ++m) {
;             const int jj0 = wr * 64 + m * 16 + fq * 4;
;             const float k0 = fexp2(lg2 * (float)(127 - jj0));
;             const f32x4 r4 = *(const f32x4*)(rsw + ai * 128 + m * 16);
; #pragma unroll
;             for (int bj = 0; bj < 2; ++bj) {
;               float y1[4], y2[4];
; #pragma unroll
;               for (int j = 0; j < 4; ++j) {
;                 const int lr = ai * 128 + m * 16 + j;
;                 float cs = *(const float*)(rl + ((m * 16 + j) * 128 + bj * 64) * 4), sn = *(const float*)(rl + 65536 + ((m * 16 + j) * 128 + bj * 64) * 4);
;                 float x1 = r4[j] * acc[ai][bj][m][0][j] + swv[bj][0], x2 = r4[j] * acc[ai][bj][m][1][j] + swv[bj][1];
;                 y1[j] = (x1 * cs - x2 * sn) * scl;
;                 y2[j] = (x2 * cs + x1 * sn) * scl;
;                 dst[tb + lr * 1024 + bj * 128] = f2bf(y1[j]);
;                 dst[tb + lr * 1024 + bj * 128 + 16] = f2bf(y2[j]);
;               }
;               if (isk) {
;                 float d0 = k0, d1 = fexp2(lg2 * (float)(126 - jj0)), d2 = fexp2(lg2 * (float)(125 - jj0)),
;                       d3 = fexp2(lg2 * (float)(124 - jj0));
;                 uint2 v1, v2;
;                 v1.x = pack2(y1[0] * d0, y1[1] * d1); v1.y = pack2(y1[2] * d2, y1[3] * d3);
;                 v2.x = pack2(y2[0] * d0, y2[1] * d1); v2.y = pack2(y2[2] * d2, y2[3] * d3);
;                 *(uint2*)(kt_t + kb + ai * 256 * 128 + (bj * 128) * 128 + m * 16) = v1;
;                 *(uint2*)(kt_t + kb + ai * 256 * 128 + (bj * 128 + 16) * 128 + m * 16) = v2;
;               }
.LBB0_604:
	v_or_b32_e32 v0, 32, v161
	v_sub_u32_e32 v98, 0x7f, v0
	v_cvt_f32_i32_e32 v98, v98
	v_sub_u32_e32 v99, 0x7e, v0
	v_cvt_f32_i32_e32 v99, v99
	ds_read2st64_b32 v[114:115], v155 offset0:64 offset1:66
	v_mul_f32_e32 v98, v160, v98
	v_exp_f32_e32 v102, v98
	v_sub_u32_e32 v98, 0x7d, v0
	v_cvt_f32_i32_e32 v98, v98
	v_sub_u32_e32 v0, 0x7c, v0
	v_cvt_f32_i32_e32 v0, v0
	v_mul_f32_e32 v99, v160, v99
	v_mul_f32_e32 v98, v160, v98
	v_exp_f32_e32 v104, v99
	v_exp_f32_e32 v103, v98
	v_add_u32_e32 v110, 0x14000, v155
	v_add_u32_e32 v111, 0x14200, v155
	ds_read2st64_b32 v[164:165], v155 offset0:68 offset1:70
	v_add_u32_e32 v112, 0x14400, v155
	ds_read_b128 v[98:101], v154 offset:128
	ds_read_b32 v166, v110
	ds_read_b32 v168, v111
	ds_read_b32 v167, v112
	v_mul_f32_e32 v0, v160, v0
	v_exp_f32_e32 v105, v0
	v_or_b32_e32 v0, 0x8000, v146
	s_waitcnt lgkmcnt(3)
	v_pk_mul_f32 v[96:97], v[96:97], v[100:101]
	v_pk_mul_f32 v[94:95], v[94:95], v[98:99]
	v_lshl_add_u64 v[116:117], v[0:1], 1, s[0:1]
	v_or_b32_e32 v0, 0x8010, v146
	v_mov_b32_e32 v174, v94
	v_mov_b32_e32 v175, v96
	v_pk_mul_f32 v[92:93], v[92:93], v[100:101]
	v_pk_mul_f32 v[176:177], v[90:91], v[98:99]
	v_lshl_add_u64 v[130:131], v[0:1], 1, s[0:1]
	v_or_b32_e32 v0, 0x8400, v146
	v_add_u32_e32 v113, 0x14600, v155
	v_pk_add_f32 v[174:175], v[140:141], v[174:175]
	v_mov_b32_e32 v90, v176
	v_mov_b32_e32 v91, v92
	v_lshl_add_u64 v[132:133], v[0:1], 1, s[0:1]
	v_or_b32_e32 v0, 0x8410, v146
	ds_read_b32 v169, v113
	v_pk_add_f32 v[180:181], v[138:139], v[90:91]
	v_mov_b32_e32 v182, v114
	v_mov_b32_e32 v183, v164
	s_waitcnt lgkmcnt(1)
	v_pk_mul_f32 v[90:91], v[166:167], v[174:175]
	v_lshl_add_u64 v[152:153], v[0:1], 1, s[0:1]
	v_or_b32_e32 v0, 0x8800, v146
	v_pk_fma_f32 v[90:91], v[182:183], v[180:181], v[90:91] neg_lo:[0,0,1] neg_hi:[0,0,1]
	v_lshl_add_u64 v[170:171], v[0:1], 1, s[0:1]
	v_or_b32_e32 v0, 0x8810, v146
	v_pk_mul_f32 v[90:91], v[142:143], v[90:91]
	v_lshl_add_u64 v[172:173], v[0:1], 1, s[0:1]
	s_nop 0
	v_mov_b32_e32 v96, v95
	v_cvt_pk_bf16_f32 v0, v90, v90
	v_pk_add_f32 v[96:97], v[140:141], v[96:97]
	v_mov_b32_e32 v92, v177
	global_store_short_d16_hi v[116:117], v0, off
	v_pk_add_f32 v[116:117], v[138:139], v[92:93]
	v_mov_b32_e32 v164, v115
	s_waitcnt lgkmcnt(0)
	v_pk_mul_f32 v[92:93], v[96:97], v[168:169]
	v_pk_mul_f32 v[94:95], v[166:167], v[180:181]
	v_pk_fma_f32 v[92:93], v[116:117], v[164:165], v[92:93] neg_lo:[0,0,1] neg_hi:[0,0,1]
	v_pk_fma_f32 v[94:95], v[182:183], v[174:175], v[94:95]
	v_pk_mul_f32 v[92:93], v[142:143], v[92:93]
	v_pk_mul_f32 v[94:95], v[142:143], v[94:95]
	s_nop 0
	v_cvt_pk_bf16_f32 v0, v92, v92
	global_store_short_d16_hi v[132:133], v0, off
	s_nop 0
	v_cvt_pk_bf16_f32 v0, v91, v91
	v_pk_mul_f32 v[114:115], v[116:117], v[168:169]
	global_store_short_d16_hi v[170:171], v0, off
	s_nop 0
	v_pk_fma_f32 v[96:97], v[96:97], v[164:165], v[114:115]
	v_cvt_pk_bf16_f32 v0, v94, v94
	v_pk_mul_f32 v[96:97], v[142:143], v[96:97]
	global_store_short_d16_hi v[130:131], v0, off
	s_nop 0
	v_cvt_pk_bf16_f32 v0, v96, v96
	global_store_short_d16_hi v[152:153], v0, off
	s_nop 0
	v_cvt_pk_bf16_f32 v0, v95, v95
	global_store_short_d16_hi v[172:173], v0, off
	s_nop 0
	v_cvt_pk_bf16_f32 v116, v93, v93
	v_or_b32_e32 v0, 0x8c00, v146
	v_lshl_add_u64 v[114:115], v[0:1], 1, s[0:1]
	v_bfe_u32 v0, v97, 16, 1
	global_store_short_d16_hi v[114:115], v116, off
	v_add3_u32 v116, v97, v0, s81
	v_or_b32_e32 v0, 0x8c10, v146
	v_lshl_add_u64 v[114:115], v[0:1], 1, s[0:1]
	s_and_b64 vcc, exec, s[6:7]
	v_readlane_b32 s49, v254, 53
	global_store_short_d16_hi v[114:115], v116, off
	s_cbranch_vccnz .LBB0_606
	v_pk_mul_f32 v[90:91], v[102:103], v[90:91]
	v_pk_mul_f32 v[92:93], v[104:105], v[92:93]
	s_nop 0
	s_nop 0
	v_cvt_pk_bf16_f32 v90, v90, v90
	v_cvt_pk_bf16_f32 v0, v91, v91
	s_nop 0
	s_nop 0
	v_cvt_pk_bf16_f32 v91, v93, v93
	v_cvt_pk_bf16_f32 v92, v92, v92
	v_pk_mul_f32 v[96:97], v[104:105], v[96:97]
	v_and_b32_e32 v91, 0xffff0000, v91
	v_and_b32_e32 v92, 0xffff0000, v92
	v_pk_mul_f32 v[94:95], v[102:103], v[94:95]
	v_or_b32_sdwa v91, v91, v0 dst_sel:DWORD dst_unused:UNUSED_PAD src0_sel:DWORD src1_sel:WORD_1
	v_or_b32_sdwa v90, v92, v90 dst_sel:DWORD dst_unused:UNUSED_PAD src0_sel:DWORD src1_sel:WORD_1
	s_nop 0
	global_store_dwordx2 v[144:145], v[90:91], off offset:64
	s_nop 0
	s_nop 0
	v_cvt_pk_bf16_f32 v92, v96, v96
	s_nop 0
	v_cvt_pk_bf16_f32 v90, v94, v94
	v_cvt_pk_bf16_f32 v91, v97, v97
	v_and_b32_e32 v92, 0xffff0000, v92
	v_cvt_pk_bf16_f32 v0, v95, v95
	v_and_b32_e32 v91, 0xffff0000, v91
	v_or_b32_sdwa v90, v92, v90 dst_sel:DWORD dst_unused:UNUSED_PAD src0_sel:DWORD src1_sel:WORD_1
	v_add_co_u32_e32 v92, vcc, 0x1000, v144
	v_or_b32_sdwa v91, v91, v0 dst_sel:DWORD dst_unused:UNUSED_PAD src0_sel:DWORD src1_sel:WORD_1
	s_nop 0
	v_addc_co_u32_e32 v93, vcc, 0, v145, vcc
	global_store_dwordx2 v[92:93], v[90:91], off offset:64
; __device__ __forceinline__ unsigned pack2(float a, float b) { return (unsigned)f2bf(a) | ((unsigned)f2bf(b) << 16); }
; __device__ __forceinline__ float fexp2(float x) { return __builtin_amdgcn_exp2f(x); }
; template <int EPI, bool HS = false>
; __device__ __forceinline__ void gemm_phase(const Params& p, const GemmCfg& g, char* shm, const int wave_s) {
;     ...
;           for (int m = 0; m < 4; ++m) {
;             const int jj0 = wr * 64 + m * 16 + fq * 4;
;             const float k0 = fexp2(lg2 * (float)(127 - jj0));
;             const f32x4 r4 = *(const f32x4*)(rsw + ai * 128 + m * 16);
; #pragma unroll
;             for (int bj = 0; bj < 2; ++bj) {
;               float y1[4], y2[4];
; #pragma unroll
;               for (int j = 0; j < 4; ++j) {
;                 const int lr = ai * 128 + m * 16 + j;
;                 float cs = *(const float*)(rl + ((m * 16 + j) * 128 + bj * 64) * 4), sn = *(const float*)(rl + 65536 + ((m * 16 + j) * 128 + bj * 64) * 4);
;                 float x1 = r4[j] * acc[ai][bj][m][0][j] + swv[bj][0], x2 = r4[j] * acc[ai][bj][m][1][j] + swv[bj][1];
;                 y1[j] = (x1 * cs - x2 * sn) * scl;
;                 y2[j] = (x2 * cs + x1 * sn) * scl;
;                 dst[tb + lr * 1024 + bj * 128] = f2bf(y1[j]);
;                 dst[tb + lr * 1024 + bj * 128 + 16] = f2bf(y2[j]);
;               }
;               if (isk) {
;                 float d0 = k0, d1 = fexp2(lg2 * (float)(126 - jj0)), d2 = fexp2(lg2 * (float)(125 - jj0)),
;                       d3 = fexp2(lg2 * (float)(124 - jj0));
;                 uint2 v1, v2;
;                 v1.x = pack2(y1[0] * d0, y1[1] * d1); v1.y = pack2(y1[2] * d2, y1[3] * d3);
;                 v2.x = pack2(y2[0] * d0, y2[1] * d1); v2.y = pack2(y2[2] * d2, y2[3] * d3);
;                 *(uint2*)(kt_t + kb + ai * 256 * 128 + (bj * 128) * 128 + m * 16) = v1;
;                 *(uint2*)(kt_t + kb + ai * 256 * 128 + (bj * 128 + 16) * 128 + m * 16) = v2;
;               }
.LBB0_606:
	ds_read2st64_b32 v[94:95], v155 offset0:65 offset1:67
	v_add_u32_e32 v90, 0x14100, v155
	ds_read2st64_b32 v[132:133], v155 offset0:69 offset1:71
	v_add_u32_e32 v91, 0x14300, v155
	v_add_u32_e32 v92, 0x14500, v155
	v_add_u32_e32 v93, 0x14700, v155
	ds_read_b32 v166, v90
	ds_read_b32 v168, v91
	ds_read_b32 v167, v92
	ds_read_b32 v169, v93
	v_or_b32_e32 v0, 0x8080, v146
	v_pk_mul_f32 v[88:89], v[88:89], v[100:101]
	v_pk_mul_f32 v[86:87], v[86:87], v[98:99]
	v_lshl_add_u64 v[96:97], v[0:1], 1, s[0:1]
	v_or_b32_e32 v0, 0x8090, v146
	v_mov_b32_e32 v170, v86
	v_mov_b32_e32 v171, v88
	v_pk_mul_f32 v[84:85], v[84:85], v[100:101]
	v_pk_mul_f32 v[98:99], v[82:83], v[98:99]
	v_lshl_add_u64 v[114:115], v[0:1], 1, s[0:1]
	v_or_b32_e32 v0, 0x8480, v146
	v_pk_add_f32 v[170:171], v[136:137], v[170:171]
	v_mov_b32_e32 v82, v98
	v_mov_b32_e32 v83, v84
	v_lshl_add_u64 v[116:117], v[0:1], 1, s[0:1]
	v_or_b32_e32 v0, 0x8490, v146
	v_pk_add_f32 v[100:101], v[134:135], v[82:83]
	s_waitcnt lgkmcnt(5)
	v_mov_b32_e32 v172, v94
	s_waitcnt lgkmcnt(4)
	v_mov_b32_e32 v173, v132
	s_waitcnt lgkmcnt(1)
	v_pk_mul_f32 v[82:83], v[170:171], v[166:167]
	v_lshl_add_u64 v[130:131], v[0:1], 1, s[0:1]
	v_or_b32_e32 v0, 0x8880, v146
	v_pk_fma_f32 v[82:83], v[100:101], v[172:173], v[82:83] neg_lo:[0,0,1] neg_hi:[0,0,1]
	v_lshl_add_u64 v[152:153], v[0:1], 1, s[0:1]
	v_or_b32_e32 v0, 0x8890, v146
	v_pk_mul_f32 v[82:83], v[142:143], v[82:83]
	v_lshl_add_u64 v[164:165], v[0:1], 1, s[0:1]
	s_nop 0
	v_mov_b32_e32 v88, v87
	v_cvt_pk_bf16_f32 v0, v82, v82
	v_pk_add_f32 v[88:89], v[136:137], v[88:89]
	v_mov_b32_e32 v84, v99
	global_store_short_d16_hi v[96:97], v0, off
	v_pk_add_f32 v[96:97], v[134:135], v[84:85]
	v_mov_b32_e32 v132, v95
	s_waitcnt lgkmcnt(0)
	v_pk_mul_f32 v[84:85], v[88:89], v[168:169]
	v_pk_mul_f32 v[86:87], v[100:101], v[166:167]
	v_pk_fma_f32 v[84:85], v[96:97], v[132:133], v[84:85] neg_lo:[0,0,1] neg_hi:[0,0,1]
	v_pk_fma_f32 v[86:87], v[170:171], v[172:173], v[86:87]
	v_pk_mul_f32 v[84:85], v[142:143], v[84:85]
	v_pk_mul_f32 v[86:87], v[142:143], v[86:87]
	s_nop 0
	v_cvt_pk_bf16_f32 v0, v84, v84
	global_store_short_d16_hi v[116:117], v0, off
	s_nop 0
	v_cvt_pk_bf16_f32 v0, v83, v83
	v_pk_mul_f32 v[94:95], v[96:97], v[168:169]
	global_store_short_d16_hi v[152:153], v0, off
	s_nop 0
	v_pk_fma_f32 v[88:89], v[88:89], v[132:133], v[94:95]
	v_cvt_pk_bf16_f32 v0, v86, v86
	v_pk_mul_f32 v[88:89], v[142:143], v[88:89]
	global_store_short_d16_hi v[114:115], v0, off
	s_nop 0
	v_cvt_pk_bf16_f32 v0, v88, v88
	global_store_short_d16_hi v[130:131], v0, off
	s_nop 0
	v_cvt_pk_bf16_f32 v0, v87, v87
	global_store_short_d16_hi v[164:165], v0, off
	s_nop 0
	v_cvt_pk_bf16_f32 v96, v85, v85
	v_or_b32_e32 v0, 0x8c80, v146
	v_lshl_add_u64 v[94:95], v[0:1], 1, s[0:1]
	v_bfe_u32 v0, v89, 16, 1
	global_store_short_d16_hi v[94:95], v96, off
	v_add3_u32 v96, v89, v0, s81
	v_or_b32_e32 v0, 0x8c90, v146
	v_lshl_add_u64 v[94:95], v[0:1], 1, s[0:1]
	s_and_b64 vcc, exec, s[6:7]
	global_store_short_d16_hi v[94:95], v96, off
	s_cbranch_vccnz .LBB0_608
	v_pk_mul_f32 v[82:83], v[102:103], v[82:83]
	v_pk_mul_f32 v[84:85], v[104:105], v[84:85]
	s_nop 0
	s_nop 0
	v_cvt_pk_bf16_f32 v82, v82, v82
	s_nop 0
	v_cvt_pk_bf16_f32 v0, v83, v83
	s_nop 0
	v_cvt_pk_bf16_f32 v84, v84, v84
	v_cvt_pk_bf16_f32 v83, v85, v85
	v_and_b32_e32 v84, 0xffff0000, v84
	s_mov_b32 s4, 0x8000
	v_and_b32_e32 v83, 0xffff0000, v83
	v_or_b32_sdwa v82, v84, v82 dst_sel:DWORD dst_unused:UNUSED_PAD src0_sel:DWORD src1_sel:WORD_1
	v_add_co_u32_e32 v84, vcc, s4, v144
	v_pk_mul_f32 v[88:89], v[104:105], v[88:89]
	v_or_b32_sdwa v83, v83, v0 dst_sel:DWORD dst_unused:UNUSED_PAD src0_sel:DWORD src1_sel:WORD_1
	v_addc_co_u32_e32 v85, vcc, 0, v145, vcc
	v_pk_mul_f32 v[86:87], v[102:103], v[86:87]
	global_store_dwordx2 v[84:85], v[82:83], off offset:64
	s_nop 0
	s_nop 0
	s_nop 0
	v_cvt_pk_bf16_f32 v84, v88, v88
	s_nop 0
	v_cvt_pk_bf16_f32 v82, v86, v86
	v_cvt_pk_bf16_f32 v83, v89, v89
	v_and_b32_e32 v84, 0xffff0000, v84
	v_cvt_pk_bf16_f32 v0, v87, v87
	v_and_b32_e32 v83, 0xffff0000, v83
	v_or_b32_sdwa v82, v84, v82 dst_sel:DWORD dst_unused:UNUSED_PAD src0_sel:DWORD src1_sel:WORD_1
	v_add_co_u32_e32 v84, vcc, 0x9000, v144
	v_or_b32_sdwa v83, v83, v0 dst_sel:DWORD dst_unused:UNUSED_PAD src0_sel:DWORD src1_sel:WORD_1
	s_nop 0
	v_addc_co_u32_e32 v85, vcc, 0, v145, vcc
	global_store_dwordx2 v[84:85], v[82:83], off offset:64
; __device__ __forceinline__ unsigned pack2(float a, float b) { return (unsigned)f2bf(a) | ((unsigned)f2bf(b) << 16); }
; __device__ __forceinline__ float fexp2(float x) { return __builtin_amdgcn_exp2f(x); }
; template <int EPI, bool HS = false>
; __device__ __forceinline__ void gemm_phase(const Params& p, const GemmCfg& g, char* shm, const int wave_s) {
;     ...
;           for (int m = 0; m < 4; ++m) {
;             const int jj0 = wr * 64 + m * 16 + fq * 4;
;             const float k0 = fexp2(lg2 * (float)(127 - jj0));
;             const f32x4 r4 = *(const f32x4*)(rsw + ai * 128 + m * 16);
; #pragma unroll
;             for (int bj = 0; bj < 2; ++bj) {
;               float y1[4], y2[4];
; #pragma unroll
;               for (int j = 0; j < 4; ++j) {
;                 const int lr = ai * 128 + m * 16 + j;
;                 float cs = *(const float*)(rl + ((m * 16 + j) * 128 + bj * 64) * 4), sn = *(const float*)(rl + 65536 + ((m * 16 + j) * 128 + bj * 64) * 4);
;                 float x1 = r4[j] * acc[ai][bj][m][0][j] + swv[bj][0], x2 = r4[j] * acc[ai][bj][m][1][j] + swv[bj][1];
;                 y1[j] = (x1 * cs - x2 * sn) * scl;
;                 y2[j] = (x2 * cs + x1 * sn) * scl;
;                 dst[tb + lr * 1024 + bj * 128] = f2bf(y1[j]);
;                 dst[tb + lr * 1024 + bj * 128 + 16] = f2bf(y2[j]);
;               }
;               if (isk) {
;                 float d0 = k0, d1 = fexp2(lg2 * (float)(126 - jj0)), d2 = fexp2(lg2 * (float)(125 - jj0)),
;                       d3 = fexp2(lg2 * (float)(124 - jj0));
;                 uint2 v1, v2;
;                 v1.x = pack2(y1[0] * d0, y1[1] * d1); v1.y = pack2(y1[2] * d2, y1[3] * d3);
;                 v2.x = pack2(y2[0] * d0, y2[1] * d1); v2.y = pack2(y2[2] * d2, y2[3] * d3);
;                 *(uint2*)(kt_t + kb + ai * 256 * 128 + (bj * 128) * 128 + m * 16) = v1;
;                 *(uint2*)(kt_t + kb + ai * 256 * 128 + (bj * 128 + 16) * 128 + m * 16) = v2;
;               }
.LBB0_608:
	v_or_b32_e32 v0, 48, v161
	v_sub_u32_e32 v82, 0x7f, v0
	v_cvt_f32_i32_e32 v82, v82
	v_sub_u32_e32 v83, 0x7e, v0
	v_cvt_f32_i32_e32 v83, v83
	ds_read2st64_b32 v[98:99], v155 offset0:96 offset1:98
	v_mul_f32_e32 v82, v160, v82
	v_exp_f32_e32 v86, v82
	v_sub_u32_e32 v82, 0x7d, v0
	v_cvt_f32_i32_e32 v82, v82
	v_sub_u32_e32 v0, 0x7c, v0
	v_cvt_f32_i32_e32 v0, v0
	v_mul_f32_e32 v83, v160, v83
	v_mul_f32_e32 v82, v160, v82
	v_exp_f32_e32 v88, v83
	v_exp_f32_e32 v87, v82
	v_mul_f32_e32 v0, v160, v0
	v_add_u32_e32 v94, 0x16000, v155
	v_add_u32_e32 v95, 0x16200, v155
	ds_read2st64_b32 v[132:133], v155 offset0:100 offset1:102
	v_add_u32_e32 v96, 0x16400, v155
	ds_read_b128 v[82:85], v154 offset:192
	ds_read_b32 v152, v94
	ds_read_b32 v160, v95
	ds_read_b32 v153, v96
	v_exp_f32_e32 v89, v0
	v_or_b32_e32 v0, 0xc000, v146
	s_waitcnt lgkmcnt(3)
	v_pk_mul_f32 v[80:81], v[80:81], v[84:85]
	v_pk_mul_f32 v[78:79], v[78:79], v[82:83]
	v_lshl_add_u64 v[100:101], v[0:1], 1, s[0:1]
	v_or_b32_e32 v0, 0xc010, v146
	v_mov_b32_e32 v168, v78
	v_mov_b32_e32 v169, v80
	v_pk_mul_f32 v[76:77], v[76:77], v[84:85]
	v_pk_mul_f32 v[170:171], v[74:75], v[82:83]
	v_lshl_add_u64 v[114:115], v[0:1], 1, s[0:1]
	v_or_b32_e32 v0, 0xc400, v146
	v_add_u32_e32 v97, 0x16600, v155
	v_pk_add_f32 v[168:169], v[140:141], v[168:169]
	v_mov_b32_e32 v74, v170
	v_mov_b32_e32 v75, v76
	v_lshl_add_u64 v[116:117], v[0:1], 1, s[0:1]
	v_or_b32_e32 v0, 0xc410, v146
	ds_read_b32 v161, v97
	v_pk_add_f32 v[172:173], v[138:139], v[74:75]
	v_mov_b32_e32 v174, v98
	v_mov_b32_e32 v175, v132
	s_waitcnt lgkmcnt(1)
	v_pk_mul_f32 v[74:75], v[152:153], v[168:169]
	v_lshl_add_u64 v[130:131], v[0:1], 1, s[0:1]
	v_or_b32_e32 v0, 0xc800, v146
	v_pk_fma_f32 v[74:75], v[174:175], v[172:173], v[74:75] neg_lo:[0,0,1] neg_hi:[0,0,1]
	v_lshl_add_u64 v[164:165], v[0:1], 1, s[0:1]
	v_or_b32_e32 v0, 0xc810, v146
	v_pk_mul_f32 v[74:75], v[142:143], v[74:75]
	v_lshl_add_u64 v[166:167], v[0:1], 1, s[0:1]
	s_nop 0
	v_mov_b32_e32 v80, v79
	v_cvt_pk_bf16_f32 v0, v74, v74
	v_pk_add_f32 v[80:81], v[140:141], v[80:81]
	v_mov_b32_e32 v76, v171
	global_store_short_d16_hi v[100:101], v0, off
	v_pk_add_f32 v[100:101], v[138:139], v[76:77]
	v_mov_b32_e32 v132, v99
	s_waitcnt lgkmcnt(0)
	v_pk_mul_f32 v[76:77], v[80:81], v[160:161]
	v_pk_mul_f32 v[78:79], v[152:153], v[172:173]
	v_pk_fma_f32 v[76:77], v[100:101], v[132:133], v[76:77] neg_lo:[0,0,1] neg_hi:[0,0,1]
	v_pk_fma_f32 v[78:79], v[174:175], v[168:169], v[78:79]
	v_pk_mul_f32 v[76:77], v[142:143], v[76:77]
	v_pk_mul_f32 v[78:79], v[142:143], v[78:79]
	s_nop 0
	v_cvt_pk_bf16_f32 v0, v76, v76
	global_store_short_d16_hi v[116:117], v0, off
	s_nop 0
	v_cvt_pk_bf16_f32 v0, v75, v75
	v_pk_mul_f32 v[98:99], v[100:101], v[160:161]
	global_store_short_d16_hi v[164:165], v0, off
	s_nop 0
	v_pk_fma_f32 v[80:81], v[80:81], v[132:133], v[98:99]
	v_cvt_pk_bf16_f32 v0, v78, v78
	v_pk_mul_f32 v[80:81], v[142:143], v[80:81]
	global_store_short_d16_hi v[114:115], v0, off
	s_nop 0
	v_cvt_pk_bf16_f32 v0, v80, v80
	global_store_short_d16_hi v[130:131], v0, off
	s_nop 0
	v_cvt_pk_bf16_f32 v0, v79, v79
	global_store_short_d16_hi v[166:167], v0, off
	s_nop 0
	v_cvt_pk_bf16_f32 v100, v77, v77
	v_or_b32_e32 v0, 0xcc00, v146
	v_lshl_add_u64 v[98:99], v[0:1], 1, s[0:1]
	v_bfe_u32 v0, v81, 16, 1
	global_store_short_d16_hi v[98:99], v100, off
	v_add3_u32 v100, v81, v0, s81
	v_or_b32_e32 v0, 0xcc10, v146
	v_lshl_add_u64 v[98:99], v[0:1], 1, s[0:1]
	s_and_b64 vcc, exec, s[6:7]
	global_store_short_d16_hi v[98:99], v100, off
	s_cbranch_vccnz .LBB0_610
	v_pk_mul_f32 v[74:75], v[86:87], v[74:75]
	v_pk_mul_f32 v[76:77], v[88:89], v[76:77]
	s_nop 0
	s_nop 0
	v_cvt_pk_bf16_f32 v74, v74, v74
	v_cvt_pk_bf16_f32 v0, v75, v75
	s_nop 0
	s_nop 0
	v_cvt_pk_bf16_f32 v75, v77, v77
	v_cvt_pk_bf16_f32 v76, v76, v76
	v_pk_mul_f32 v[80:81], v[88:89], v[80:81]
	v_and_b32_e32 v75, 0xffff0000, v75
	v_and_b32_e32 v76, 0xffff0000, v76
	v_pk_mul_f32 v[78:79], v[86:87], v[78:79]
	v_or_b32_sdwa v75, v75, v0 dst_sel:DWORD dst_unused:UNUSED_PAD src0_sel:DWORD src1_sel:WORD_1
	v_or_b32_sdwa v74, v76, v74 dst_sel:DWORD dst_unused:UNUSED_PAD src0_sel:DWORD src1_sel:WORD_1
	s_nop 0
	global_store_dwordx2 v[144:145], v[74:75], off offset:96
	s_nop 0
	s_nop 0
	v_cvt_pk_bf16_f32 v76, v80, v80
	s_nop 0
	v_cvt_pk_bf16_f32 v74, v78, v78
	v_cvt_pk_bf16_f32 v75, v81, v81
	v_and_b32_e32 v76, 0xffff0000, v76
	v_cvt_pk_bf16_f32 v0, v79, v79
	v_and_b32_e32 v75, 0xffff0000, v75
	v_or_b32_sdwa v74, v76, v74 dst_sel:DWORD dst_unused:UNUSED_PAD src0_sel:DWORD src1_sel:WORD_1
	v_add_co_u32_e32 v76, vcc, 0x1000, v144
	v_or_b32_sdwa v75, v75, v0 dst_sel:DWORD dst_unused:UNUSED_PAD src0_sel:DWORD src1_sel:WORD_1
	s_nop 0
	v_addc_co_u32_e32 v77, vcc, 0, v145, vcc
	global_store_dwordx2 v[76:77], v[74:75], off offset:96
; __device__ __forceinline__ unsigned pack2(float a, float b) { return (unsigned)f2bf(a) | ((unsigned)f2bf(b) << 16); }
; __device__ __forceinline__ float fexp2(float x) { return __builtin_amdgcn_exp2f(x); }
; template <int EPI, bool HS = false>
; __device__ __forceinline__ void gemm_phase(const Params& p, const GemmCfg& g, char* shm, const int wave_s) {
;     ...
;             for (int bj = 0; bj < 2; ++bj) {
;               float y1[4], y2[4];
; #pragma unroll
;               for (int j = 0; j < 4; ++j) {
;                 const int lr = ai * 128 + m * 16 + j;
;                 float cs = *(const float*)(rl + ((m * 16 + j) * 128 + bj * 64) * 4), sn = *(const float*)(rl + 65536 + ((m * 16 + j) * 128 + bj * 64) * 4);
;                 float x1 = r4[j] * acc[ai][bj][m][0][j] + swv[bj][0], x2 = r4[j] * acc[ai][bj][m][1][j] + swv[bj][1];
;                 y1[j] = (x1 * cs - x2 * sn) * scl;
;                 y2[j] = (x2 * cs + x1 * sn) * scl;
;                 dst[tb + lr * 1024 + bj * 128] = f2bf(y1[j]);
;                 dst[tb + lr * 1024 + bj * 128 + 16] = f2bf(y2[j]);
;               }
;               if (isk) {
;                 float d0 = k0, d1 = fexp2(lg2 * (float)(126 - jj0)), d2 = fexp2(lg2 * (float)(125 - jj0)),
;                       d3 = fexp2(lg2 * (float)(124 - jj0));
;                 uint2 v1, v2;
;                 v1.x = pack2(y1[0] * d0, y1[1] * d1); v1.y = pack2(y1[2] * d2, y1[3] * d3);
;                 v2.x = pack2(y2[0] * d0, y2[1] * d1); v2.y = pack2(y2[2] * d2, y2[3] * d3);
;                 *(uint2*)(kt_t + kb + ai * 256 * 128 + (bj * 128) * 128 + m * 16) = v1;
;                 *(uint2*)(kt_t + kb + ai * 256 * 128 + (bj * 128 + 16) * 128 + m * 16) = v2;
;               }
.LBB0_610:
	ds_read2st64_b32 v[78:79], v155 offset0:97 offset1:99
	v_add_u32_e32 v74, 0x16100, v155
	ds_read2st64_b32 v[116:117], v155 offset0:101 offset1:103
	v_add_u32_e32 v75, 0x16300, v155
	v_add_u32_e32 v76, 0x16500, v155
	v_add_u32_e32 v77, 0x16700, v155
	ds_read_b32 v152, v74
	ds_read_b32 v160, v75
	ds_read_b32 v153, v76
	ds_read_b32 v161, v77
	v_or_b32_e32 v0, 0xc080, v146
	v_pk_mul_f32 v[72:73], v[72:73], v[84:85]
	v_pk_mul_f32 v[70:71], v[70:71], v[82:83]
	v_lshl_add_u64 v[80:81], v[0:1], 1, s[0:1]
	v_or_b32_e32 v0, 0xc090, v146
	v_mov_b32_e32 v164, v70
	v_mov_b32_e32 v165, v72
	v_pk_mul_f32 v[68:69], v[68:69], v[84:85]
	v_pk_mul_f32 v[82:83], v[66:67], v[82:83]
	v_lshl_add_u64 v[98:99], v[0:1], 1, s[0:1]
	v_or_b32_e32 v0, 0xc480, v146
	v_pk_add_f32 v[164:165], v[136:137], v[164:165]
	v_mov_b32_e32 v66, v82
	v_mov_b32_e32 v67, v68
	v_lshl_add_u64 v[100:101], v[0:1], 1, s[0:1]
	v_or_b32_e32 v0, 0xc490, v146
	v_pk_add_f32 v[84:85], v[134:135], v[66:67]
	s_waitcnt lgkmcnt(5)
	v_mov_b32_e32 v166, v78
	s_waitcnt lgkmcnt(4)
	v_mov_b32_e32 v167, v116
	s_waitcnt lgkmcnt(1)
	v_pk_mul_f32 v[66:67], v[164:165], v[152:153]
	v_lshl_add_u64 v[114:115], v[0:1], 1, s[0:1]
	v_or_b32_e32 v0, 0xc880, v146
	v_pk_fma_f32 v[66:67], v[84:85], v[166:167], v[66:67] neg_lo:[0,0,1] neg_hi:[0,0,1]
	v_lshl_add_u64 v[130:131], v[0:1], 1, s[0:1]
	v_or_b32_e32 v0, 0xc890, v146
	v_pk_mul_f32 v[66:67], v[142:143], v[66:67]
	v_lshl_add_u64 v[132:133], v[0:1], 1, s[0:1]
	s_nop 0
	v_mov_b32_e32 v72, v71
	v_cvt_pk_bf16_f32 v0, v66, v66
	v_pk_add_f32 v[72:73], v[136:137], v[72:73]
	v_mov_b32_e32 v68, v83
	global_store_short_d16_hi v[80:81], v0, off
	v_pk_add_f32 v[80:81], v[134:135], v[68:69]
	v_mov_b32_e32 v116, v79
	s_waitcnt lgkmcnt(0)
	v_pk_mul_f32 v[68:69], v[72:73], v[160:161]
	v_pk_mul_f32 v[70:71], v[84:85], v[152:153]
	v_pk_fma_f32 v[68:69], v[80:81], v[116:117], v[68:69] neg_lo:[0,0,1] neg_hi:[0,0,1]
	v_pk_fma_f32 v[70:71], v[164:165], v[166:167], v[70:71]
	v_pk_mul_f32 v[68:69], v[142:143], v[68:69]
	v_pk_mul_f32 v[70:71], v[142:143], v[70:71]
	s_nop 0
	v_cvt_pk_bf16_f32 v0, v68, v68
	global_store_short_d16_hi v[100:101], v0, off
	s_nop 0
	v_cvt_pk_bf16_f32 v0, v67, v67
	v_pk_mul_f32 v[78:79], v[80:81], v[160:161]
	global_store_short_d16_hi v[130:131], v0, off
	s_nop 0
	v_pk_fma_f32 v[72:73], v[72:73], v[116:117], v[78:79]
	v_cvt_pk_bf16_f32 v0, v70, v70
	v_pk_mul_f32 v[72:73], v[142:143], v[72:73]
	global_store_short_d16_hi v[98:99], v0, off
	s_nop 0
	v_cvt_pk_bf16_f32 v0, v72, v72
	global_store_short_d16_hi v[114:115], v0, off
	s_nop 0
	v_cvt_pk_bf16_f32 v0, v71, v71
	global_store_short_d16_hi v[132:133], v0, off
	s_nop 0
	v_cvt_pk_bf16_f32 v80, v69, v69
	v_or_b32_e32 v0, 0xcc80, v146
	v_lshl_add_u64 v[78:79], v[0:1], 1, s[0:1]
	v_bfe_u32 v0, v73, 16, 1
	global_store_short_d16_hi v[78:79], v80, off
	v_add3_u32 v80, v73, v0, s81
	v_or_b32_e32 v0, 0xcc90, v146
	v_lshl_add_u64 v[78:79], v[0:1], 1, s[0:1]
	s_and_b64 vcc, exec, s[6:7]
	global_store_short_d16_hi v[78:79], v80, off
	s_cbranch_vccnz .LBB0_612
	v_pk_mul_f32 v[66:67], v[86:87], v[66:67]
	v_pk_mul_f32 v[68:69], v[88:89], v[68:69]
	s_nop 0
	s_nop 0
	v_cvt_pk_bf16_f32 v66, v66, v66
	s_nop 0
	v_cvt_pk_bf16_f32 v0, v67, v67
	s_nop 0
	v_cvt_pk_bf16_f32 v68, v68, v68
	v_cvt_pk_bf16_f32 v67, v69, v69
	v_and_b32_e32 v68, 0xffff0000, v68
	s_mov_b32 s4, 0x8000
	v_and_b32_e32 v67, 0xffff0000, v67
	v_or_b32_sdwa v66, v68, v66 dst_sel:DWORD dst_unused:UNUSED_PAD src0_sel:DWORD src1_sel:WORD_1
	v_add_co_u32_e32 v68, vcc, s4, v144
	v_pk_mul_f32 v[72:73], v[88:89], v[72:73]
	v_or_b32_sdwa v67, v67, v0 dst_sel:DWORD dst_unused:UNUSED_PAD src0_sel:DWORD src1_sel:WORD_1
	v_addc_co_u32_e32 v69, vcc, 0, v145, vcc
	v_pk_mul_f32 v[70:71], v[86:87], v[70:71]
	global_store_dwordx2 v[68:69], v[66:67], off offset:96
	s_nop 0
	s_nop 0
	s_nop 0
	v_cvt_pk_bf16_f32 v68, v72, v72
	s_nop 0
	v_cvt_pk_bf16_f32 v66, v70, v70
	v_cvt_pk_bf16_f32 v67, v73, v73
	v_and_b32_e32 v68, 0xffff0000, v68
	v_cvt_pk_bf16_f32 v0, v71, v71
	v_and_b32_e32 v67, 0xffff0000, v67
	v_or_b32_sdwa v66, v68, v66 dst_sel:DWORD dst_unused:UNUSED_PAD src0_sel:DWORD src1_sel:WORD_1
	v_add_co_u32_e32 v68, vcc, 0x9000, v144
	v_or_b32_sdwa v67, v67, v0 dst_sel:DWORD dst_unused:UNUSED_PAD src0_sel:DWORD src1_sel:WORD_1
	s_nop 0
	v_addc_co_u32_e32 v69, vcc, 0, v145, vcc
	global_store_dwordx2 v[68:69], v[66:67], off offset:96
; __device__ __forceinline__ float fexp2(float x) { return __builtin_amdgcn_exp2f(x); }
; #define WAIT_V(n) asm volatile("s_waitcnt vmcnt(" #n ")" ::: "memory")
; template <int EPI, bool HS = false>
; __device__ __forceinline__ void gemm_phase(const Params& p, const GemmCfg& g, char* shm, const int wave_s) {
;     ...
;         for (int ai = 0; ai < 2; ++ai) {
; #pragma unroll
;           for (int i = 0; i < 8; ++i) {
;             const int ch = wv_s * 8 + i;
;             glds_row(rc_t + (size_t)(ai * 128) * 128 + ch * 256, (unsigned)lane * 16u, ldsb + (unsigned)(ch * 1024));
;             glds_row(rs_t + (size_t)(ai * 128) * 128 + ch * 256, (unsigned)lane * 16u, ldsb + 65536u + (unsigned)(ch * 1024));
;           }
;           WAIT_V(0);
;           __syncthreads();
; #pragma unroll
;           for (int m = 0; m < 4; ++m) {
;             const int jj0 = wr * 64 + m * 16 + fq * 4;
;             const float k0 = fexp2(lg2 * (float)(127 - jj0));
;             const f32x4 r4 = *(const f32x4*)(rsw + ai * 128 + m * 16);
; #pragma unroll
;             for (int bj = 0; bj < 2; ++bj) {
;               float y1[4], y2[4];
; #pragma unroll
;               for (int j = 0; j < 4; ++j) {
;                 const int lr = ai * 128 + m * 16 + j;
;                 float cs = *(const float*)(rl + ((m * 16 + j) * 128 + bj * 64) * 4), sn = *(const float*)(rl + 65536 + ((m * 16 + j) * 128 + bj * 64) * 4);
;                 float x1 = r4[j] * acc[ai][bj][m][0][j] + swv[bj][0], x2 = r4[j] * acc[ai][bj][m][1][j] + swv[bj][1];
;                 y1[j] = (x1 * cs - x2 * sn) * scl;
;                 y2[j] = (x2 * cs + x1 * sn) * scl;
;                 dst[tb + lr * 1024 + bj * 128] = f2bf(y1[j]);
;                 dst[tb + lr * 1024 + bj * 128 + 16] = f2bf(y2[j]);
.LBB0_612:
	s_add_u32 s15, s27, 0x10000
	s_addc_u32 s16, s90, 0
	s_add_u32 s17, s91, 0x10000
	s_addc_u32 s18, s84, 0
	s_add_u32 s4, s15, s76
	s_addc_u32 s5, s16, s77
	s_waitcnt vmcnt(63) expcnt(7) lgkmcnt(15)
	s_barrier
	s_mov_b32 m0, s85
	s_nop 0
	global_load_lds_dwordx4 v156, s[4:5]
	s_add_u32 s4, s17, s76
	s_addc_u32 s5, s18, s77
	s_mov_b32 m0, s62
	s_nop 0
	global_load_lds_dwordx4 v156, s[4:5]
	s_add_u32 s4, s15, s74
	s_addc_u32 s5, s16, s75
	s_mov_b32 m0, s26
	s_nop 0
	global_load_lds_dwordx4 v156, s[4:5]
	s_add_u32 s4, s17, s74
	s_addc_u32 s5, s18, s75
	s_mov_b32 m0, s60
	s_nop 0
	global_load_lds_dwordx4 v156, s[4:5]
	s_add_u32 s4, s15, s72
	s_addc_u32 s5, s16, s73
	s_mov_b32 m0, s61
	s_nop 0
	global_load_lds_dwordx4 v156, s[4:5]
	s_add_u32 s4, s17, s72
	s_addc_u32 s5, s18, s73
	s_mov_b32 m0, s57
	s_nop 0
	global_load_lds_dwordx4 v156, s[4:5]
	s_add_u32 s4, s15, s70
	s_addc_u32 s5, s16, s71
	s_mov_b32 m0, s58
	s_nop 0
	global_load_lds_dwordx4 v156, s[4:5]
	s_add_u32 s4, s17, s70
	s_addc_u32 s5, s18, s71
	s_mov_b32 m0, s55
	s_nop 0
	global_load_lds_dwordx4 v156, s[4:5]
	s_add_u32 s4, s15, s8
	s_addc_u32 s5, s16, s9
	s_mov_b32 m0, s56
	s_nop 0
	global_load_lds_dwordx4 v156, s[4:5]
	s_add_u32 s4, s17, s8
	s_addc_u32 s5, s18, s9
	s_mov_b32 m0, s53
	s_nop 0
	global_load_lds_dwordx4 v156, s[4:5]
	s_add_u32 s4, s15, s2
	s_addc_u32 s5, s16, s3
	s_add_u32 s2, s17, s2
	s_mov_b32 m0, s54
	s_nop 0
	global_load_lds_dwordx4 v156, s[4:5]
	s_addc_u32 s3, s18, s3
	s_mov_b32 m0, s52
	s_nop 0
	global_load_lds_dwordx4 v156, s[2:3]
	s_add_u32 s2, s15, s10
	s_addc_u32 s3, s16, s11
	s_mov_b32 m0, s59
	s_nop 0
	global_load_lds_dwordx4 v156, s[2:3]
	s_add_u32 s2, s17, s10
	s_addc_u32 s3, s18, s11
	s_mov_b32 m0, s12
	s_nop 0
	global_load_lds_dwordx4 v156, s[2:3]
	s_add_u32 s2, s15, s68
	s_addc_u32 s3, s16, s69
	s_mov_b32 m0, s14
	s_nop 0
	global_load_lds_dwordx4 v156, s[2:3]
	s_add_u32 s2, s17, s68
	s_addc_u32 s3, s18, s69
	s_mov_b32 m0, s13
	s_nop 0
	global_load_lds_dwordx4 v156, s[2:3]
	s_waitcnt vmcnt(0)
	s_barrier
	ds_read2st64_b32 v[70:71], v155 offset1:2
	ds_read2st64_b32 v[80:81], v155 offset0:4 offset1:6
	ds_read_b128 v[66:69], v154 offset:512
	ds_read_b32 v82, v157
	ds_read_b32 v84, v147
	ds_read_b32 v83, v158
	ds_read_b32 v85, v159
	s_waitcnt lgkmcnt(4)
	v_pk_mul_f32 v[64:65], v[64:65], v[68:69]
	v_pk_mul_f32 v[62:63], v[62:63], v[66:67]
	v_mov_b32_e32 v101, v64
	v_mov_b32_e32 v100, v62
	v_pk_mul_f32 v[60:61], v[60:61], v[68:69]
	v_pk_mul_f32 v[114:115], v[58:59], v[66:67]
	v_pk_add_f32 v[100:101], v[140:141], v[100:101]
	v_mov_b32_e32 v58, v114
	v_mov_b32_e32 v59, v60
	v_add_u32_e32 v0, 0x20000, v146
	v_pk_add_f32 v[116:117], v[138:139], v[58:59]
	v_mov_b32_e32 v130, v70
	v_mov_b32_e32 v131, v80
	s_waitcnt lgkmcnt(1)
	v_pk_mul_f32 v[58:59], v[82:83], v[100:101]
	v_mov_b32_e32 v64, v63
	v_lshl_add_u64 v[72:73], v[0:1], 1, s[0:1]
	v_add_u32_e32 v0, 0x20400, v146
	v_pk_fma_f32 v[58:59], v[130:131], v[116:117], v[58:59] neg_lo:[0,0,1] neg_hi:[0,0,1]
	v_pk_add_f32 v[64:65], v[140:141], v[64:65]
	v_mov_b32_e32 v60, v115
	v_lshl_add_u64 v[78:79], v[0:1], 1, s[0:1]
	v_add_u32_e32 v0, 0x20800, v146
	v_pk_mul_f32 v[58:59], v[142:143], v[58:59]
	v_pk_add_f32 v[114:115], v[138:139], v[60:61]
	v_mov_b32_e32 v80, v71
	s_waitcnt lgkmcnt(0)
	v_pk_mul_f32 v[60:61], v[64:65], v[84:85]
	v_lshl_add_u64 v[98:99], v[0:1], 1, s[0:1]
	s_nop 0
	v_pk_fma_f32 v[60:61], v[114:115], v[80:81], v[60:61] neg_lo:[0,0,1] neg_hi:[0,0,1]
	v_cvt_pk_bf16_f32 v0, v58, v58
	v_pk_mul_f32 v[60:61], v[142:143], v[60:61]
	global_store_short_d16_hi v[72:73], v0, off
	s_nop 0
	v_cvt_pk_bf16_f32 v0, v60, v60
	v_pk_mul_f32 v[62:63], v[82:83], v[116:117]
	global_store_short_d16_hi v[78:79], v0, off
	s_nop 0
	v_pk_fma_f32 v[62:63], v[130:131], v[100:101], v[62:63]
	v_cvt_pk_bf16_f32 v0, v59, v59
	v_pk_mul_f32 v[62:63], v[142:143], v[62:63]
	v_pk_mul_f32 v[70:71], v[114:115], v[84:85]
	global_store_short_d16_hi v[98:99], v0, off
	s_nop 0
	v_pk_fma_f32 v[64:65], v[64:65], v[80:81], v[70:71]
	v_cvt_pk_bf16_f32 v0, v62, v62
	v_pk_mul_f32 v[64:65], v[142:143], v[64:65]
	global_store_short_d16_hi v[72:73], v0, off offset:32
	s_nop 0
	v_cvt_pk_bf16_f32 v0, v64, v64
	global_store_short_d16_hi v[78:79], v0, off offset:32
	s_nop 0
	v_cvt_pk_bf16_f32 v0, v63, v63
	global_store_short_d16_hi v[98:99], v0, off offset:32
	v_bfe_u32 v0, v61, 16, 1
	v_add3_u32 v72, v61, v0, s81
	v_add_u32_e32 v0, 0x20c00, v146
	v_lshl_add_u64 v[70:71], v[0:1], 1, s[0:1]
	v_bfe_u32 v0, v65, 16, 1
	v_add3_u32 v0, v65, v0, s81
	s_and_b64 vcc, exec, s[6:7]
	global_store_short_d16_hi v[70:71], v72, off
	global_store_short_d16_hi v[70:71], v0, off offset:32
	s_cbranch_vccnz .LBB0_614
	v_pk_mul_f32 v[58:59], v[148:149], v[58:59]
	v_pk_mul_f32 v[60:61], v[150:151], v[60:61]
	s_nop 0
	s_nop 0
	v_cvt_pk_bf16_f32 v58, v58, v58
	s_nop 0
	v_cvt_pk_bf16_f32 v0, v59, v59
	s_nop 0
	v_cvt_pk_bf16_f32 v60, v60, v60
	v_cvt_pk_bf16_f32 v59, v61, v61
	v_and_b32_e32 v60, 0xffff0000, v60
	v_and_b32_e32 v59, 0xffff0000, v59
	v_or_b32_sdwa v58, v60, v58 dst_sel:DWORD dst_unused:UNUSED_PAD src0_sel:DWORD src1_sel:WORD_1
	v_add_co_u32_e32 v60, vcc, s51, v144
	v_pk_mul_f32 v[64:65], v[150:151], v[64:65]
	v_or_b32_sdwa v59, v59, v0 dst_sel:DWORD dst_unused:UNUSED_PAD src0_sel:DWORD src1_sel:WORD_1
	v_addc_co_u32_e32 v61, vcc, 0, v145, vcc
	v_pk_mul_f32 v[62:63], v[148:149], v[62:63]
	global_store_dwordx2 v[60:61], v[58:59], off
	s_nop 0
	s_nop 0
	s_nop 0
	v_cvt_pk_bf16_f32 v60, v64, v64
	s_nop 0
	v_cvt_pk_bf16_f32 v58, v62, v62
	v_cvt_pk_bf16_f32 v59, v65, v65
	v_and_b32_e32 v60, 0xffff0000, v60
	v_cvt_pk_bf16_f32 v0, v63, v63
	v_and_b32_e32 v59, 0xffff0000, v59
	v_or_b32_sdwa v58, v60, v58 dst_sel:DWORD dst_unused:UNUSED_PAD src0_sel:DWORD src1_sel:WORD_1
	v_add_co_u32_e32 v60, vcc, 0x11000, v144
	v_or_b32_sdwa v59, v59, v0 dst_sel:DWORD dst_unused:UNUSED_PAD src0_sel:DWORD src1_sel:WORD_1
	s_nop 0
	v_addc_co_u32_e32 v61, vcc, 0, v145, vcc
	global_store_dwordx2 v[60:61], v[58:59], off
; __device__ __forceinline__ unsigned pack2(float a, float b) { return (unsigned)f2bf(a) | ((unsigned)f2bf(b) << 16); }
; __device__ __forceinline__ float fexp2(float x) { return __builtin_amdgcn_exp2f(x); }
; template <int EPI, bool HS = false>
; __device__ __forceinline__ void gemm_phase(const Params& p, const GemmCfg& g, char* shm, const int wave_s) {
;     ...
;           for (int m = 0; m < 4; ++m) {
;             const int jj0 = wr * 64 + m * 16 + fq * 4;
;             const float k0 = fexp2(lg2 * (float)(127 - jj0));
;             const f32x4 r4 = *(const f32x4*)(rsw + ai * 128 + m * 16);
; #pragma unroll
;             for (int bj = 0; bj < 2; ++bj) {
;               float y1[4], y2[4];
; #pragma unroll
;               for (int j = 0; j < 4; ++j) {
;                 const int lr = ai * 128 + m * 16 + j;
;                 float cs = *(const float*)(rl + ((m * 16 + j) * 128 + bj * 64) * 4), sn = *(const float*)(rl + 65536 + ((m * 16 + j) * 128 + bj * 64) * 4);
;                 float x1 = r4[j] * acc[ai][bj][m][0][j] + swv[bj][0], x2 = r4[j] * acc[ai][bj][m][1][j] + swv[bj][1];
;                 y1[j] = (x1 * cs - x2 * sn) * scl;
;                 y2[j] = (x2 * cs + x1 * sn) * scl;
;                 dst[tb + lr * 1024 + bj * 128] = f2bf(y1[j]);
;                 dst[tb + lr * 1024 + bj * 128 + 16] = f2bf(y2[j]);
;               }
;               if (isk) {
;                 float d0 = k0, d1 = fexp2(lg2 * (float)(126 - jj0)), d2 = fexp2(lg2 * (float)(125 - jj0)),
;                       d3 = fexp2(lg2 * (float)(124 - jj0));
;                 uint2 v1, v2;
;                 v1.x = pack2(y1[0] * d0, y1[1] * d1); v1.y = pack2(y1[2] * d2, y1[3] * d3);
;                 v2.x = pack2(y2[0] * d0, y2[1] * d1); v2.y = pack2(y2[2] * d2, y2[3] * d3);
;                 *(uint2*)(kt_t + kb + ai * 256 * 128 + (bj * 128) * 128 + m * 16) = v1;
;                 *(uint2*)(kt_t + kb + ai * 256 * 128 + (bj * 128 + 16) * 128 + m * 16) = v2;
;               }
.LBB0_614:
	ds_read2st64_b32 v[58:59], v155 offset0:1 offset1:3
	ds_read2st64_b32 v[64:65], v155 offset0:5 offset1:7
	ds_read_b32 v72, v122
	ds_read_b32 v78, v123
	ds_read_b32 v73, v124
	ds_read_b32 v79, v125
	v_pk_mul_f32 v[56:57], v[56:57], v[68:69]
	v_pk_mul_f32 v[54:55], v[54:55], v[66:67]
	v_mov_b32_e32 v81, v56
	v_mov_b32_e32 v80, v54
	v_pk_mul_f32 v[52:53], v[52:53], v[68:69]
	v_pk_mul_f32 v[66:67], v[50:51], v[66:67]
	v_pk_add_f32 v[80:81], v[136:137], v[80:81]
	v_mov_b32_e32 v50, v66
	v_mov_b32_e32 v51, v52
	v_add_u32_e32 v0, 0x20080, v146
	v_pk_add_f32 v[68:69], v[134:135], v[50:51]
	s_waitcnt lgkmcnt(5)
	v_mov_b32_e32 v82, v58
	s_waitcnt lgkmcnt(4)
	v_mov_b32_e32 v83, v64
	s_waitcnt lgkmcnt(1)
	v_pk_mul_f32 v[50:51], v[80:81], v[72:73]
	v_mov_b32_e32 v56, v55
	v_lshl_add_u64 v[60:61], v[0:1], 1, s[0:1]
	v_add_u32_e32 v0, 0x20480, v146
	v_pk_fma_f32 v[50:51], v[68:69], v[82:83], v[50:51] neg_lo:[0,0,1] neg_hi:[0,0,1]
	v_pk_add_f32 v[56:57], v[136:137], v[56:57]
	v_mov_b32_e32 v52, v67
	v_lshl_add_u64 v[62:63], v[0:1], 1, s[0:1]
	v_add_u32_e32 v0, 0x20880, v146
	v_pk_mul_f32 v[50:51], v[142:143], v[50:51]
	v_pk_add_f32 v[66:67], v[134:135], v[52:53]
	v_mov_b32_e32 v64, v59
	s_waitcnt lgkmcnt(0)
	v_pk_mul_f32 v[52:53], v[56:57], v[78:79]
	v_lshl_add_u64 v[70:71], v[0:1], 1, s[0:1]
	s_nop 0
	v_pk_fma_f32 v[52:53], v[66:67], v[64:65], v[52:53] neg_lo:[0,0,1] neg_hi:[0,0,1]
	v_cvt_pk_bf16_f32 v0, v50, v50
	v_pk_mul_f32 v[52:53], v[142:143], v[52:53]
	global_store_short_d16_hi v[60:61], v0, off
	s_nop 0
	v_cvt_pk_bf16_f32 v0, v52, v52
	v_pk_mul_f32 v[54:55], v[68:69], v[72:73]
	global_store_short_d16_hi v[62:63], v0, off
	s_nop 0
	v_pk_fma_f32 v[54:55], v[80:81], v[82:83], v[54:55]
	v_cvt_pk_bf16_f32 v0, v51, v51
	v_pk_mul_f32 v[54:55], v[142:143], v[54:55]
	v_pk_mul_f32 v[58:59], v[66:67], v[78:79]
	global_store_short_d16_hi v[70:71], v0, off
	s_nop 0
	v_pk_fma_f32 v[56:57], v[56:57], v[64:65], v[58:59]
	v_cvt_pk_bf16_f32 v0, v54, v54
	v_pk_mul_f32 v[56:57], v[142:143], v[56:57]
	global_store_short_d16_hi v[60:61], v0, off offset:32
	s_nop 0
	v_cvt_pk_bf16_f32 v0, v56, v56
	global_store_short_d16_hi v[62:63], v0, off offset:32
	s_nop 0
	v_cvt_pk_bf16_f32 v0, v55, v55
	global_store_short_d16_hi v[70:71], v0, off offset:32
	v_bfe_u32 v0, v53, 16, 1
	v_add3_u32 v60, v53, v0, s81
	v_add_u32_e32 v0, 0x20c80, v146
	v_lshl_add_u64 v[58:59], v[0:1], 1, s[0:1]
	v_bfe_u32 v0, v57, 16, 1
	v_readlane_b32 s8, v254, 47
	v_add3_u32 v0, v57, v0, s81
	s_and_b64 vcc, exec, s[6:7]
	v_readlane_b32 s9, v254, 48
	global_store_short_d16_hi v[58:59], v60, off
	global_store_short_d16_hi v[58:59], v0, off offset:32
	v_readlane_b32 s10, v254, 49
	v_readlane_b32 s11, v254, 50
	s_cbranch_vccnz .LBB0_616
	v_pk_mul_f32 v[50:51], v[148:149], v[50:51]
	v_pk_mul_f32 v[52:53], v[150:151], v[52:53]
	s_nop 0
	s_nop 0
	v_cvt_pk_bf16_f32 v50, v50, v50
	s_nop 0
	v_cvt_pk_bf16_f32 v0, v51, v51
	s_nop 0
	v_cvt_pk_bf16_f32 v52, v52, v52
	v_cvt_pk_bf16_f32 v51, v53, v53
	v_and_b32_e32 v52, 0xffff0000, v52
	s_mov_b32 s2, 0x18000
	v_and_b32_e32 v51, 0xffff0000, v51
	v_or_b32_sdwa v50, v52, v50 dst_sel:DWORD dst_unused:UNUSED_PAD src0_sel:DWORD src1_sel:WORD_1
	v_add_co_u32_e32 v52, vcc, s2, v144
	v_pk_mul_f32 v[56:57], v[150:151], v[56:57]
	v_or_b32_sdwa v51, v51, v0 dst_sel:DWORD dst_unused:UNUSED_PAD src0_sel:DWORD src1_sel:WORD_1
	v_addc_co_u32_e32 v53, vcc, 0, v145, vcc
	v_pk_mul_f32 v[54:55], v[148:149], v[54:55]
	global_store_dwordx2 v[52:53], v[50:51], off
	s_nop 0
	s_nop 0
	s_nop 0
	v_cvt_pk_bf16_f32 v52, v56, v56
	s_nop 0
	v_cvt_pk_bf16_f32 v50, v54, v54
	v_cvt_pk_bf16_f32 v51, v57, v57
	v_and_b32_e32 v52, 0xffff0000, v52
	v_cvt_pk_bf16_f32 v0, v55, v55
	v_and_b32_e32 v51, 0xffff0000, v51
	v_or_b32_sdwa v50, v52, v50 dst_sel:DWORD dst_unused:UNUSED_PAD src0_sel:DWORD src1_sel:WORD_1
	v_add_co_u32_e32 v52, vcc, 0x19000, v144
	v_or_b32_sdwa v51, v51, v0 dst_sel:DWORD dst_unused:UNUSED_PAD src0_sel:DWORD src1_sel:WORD_1
	s_nop 0
	v_addc_co_u32_e32 v53, vcc, 0, v145, vcc
	global_store_dwordx2 v[52:53], v[50:51], off
.LBB0_616:
	ds_read2st64_b32 v[54:55], v155 offset0:32 offset1:34
	ds_read2st64_b32 v[60:61], v155 offset0:36 offset1:38
	ds_read_b128 v[50:53], v154 offset:576
	ds_read_b32 v62, v126
	ds_read_b32 v64, v127
	ds_read_b32 v63, v128
	ds_read_b32 v65, v129
	s_waitcnt lgkmcnt(4)
	v_pk_mul_f32 v[48:49], v[48:49], v[52:53]
	v_pk_mul_f32 v[46:47], v[46:47], v[50:51]
	v_mov_b32_e32 v69, v48
	v_mov_b32_e32 v68, v46
	v_pk_mul_f32 v[44:45], v[44:45], v[52:53]
	v_pk_mul_f32 v[70:71], v[42:43], v[50:51]
	v_pk_add_f32 v[68:69], v[140:141], v[68:69]
	v_mov_b32_e32 v42, v70
	v_mov_b32_e32 v43, v44
	v_add_u32_e32 v0, 0x24000, v146
	v_pk_add_f32 v[72:73], v[138:139], v[42:43]
	v_mov_b32_e32 v78, v54
	v_mov_b32_e32 v79, v60
	s_waitcnt lgkmcnt(1)
	v_pk_mul_f32 v[42:43], v[62:63], v[68:69]
	v_mov_b32_e32 v48, v47
	v_lshl_add_u64 v[56:57], v[0:1], 1, s[0:1]
	v_add_u32_e32 v0, 0x24400, v146
	v_pk_fma_f32 v[42:43], v[78:79], v[72:73], v[42:43] neg_lo:[0,0,1] neg_hi:[0,0,1]
	v_pk_add_f32 v[48:49], v[140:141], v[48:49]
	v_mov_b32_e32 v44, v71
	v_lshl_add_u64 v[58:59], v[0:1], 1, s[0:1]
	v_add_u32_e32 v0, 0x24800, v146
	v_pk_mul_f32 v[42:43], v[142:143], v[42:43]
	v_pk_add_f32 v[70:71], v[138:139], v[44:45]
	v_mov_b32_e32 v60, v55
	s_waitcnt lgkmcnt(0)
	v_pk_mul_f32 v[44:45], v[48:49], v[64:65]
	v_lshl_add_u64 v[66:67], v[0:1], 1, s[0:1]
	s_nop 0
	v_pk_fma_f32 v[44:45], v[70:71], v[60:61], v[44:45] neg_lo:[0,0,1] neg_hi:[0,0,1]
	v_cvt_pk_bf16_f32 v0, v42, v42
	v_pk_mul_f32 v[44:45], v[142:143], v[44:45]
	global_store_short_d16_hi v[56:57], v0, off
	s_nop 0
	v_cvt_pk_bf16_f32 v0, v44, v44
	v_pk_mul_f32 v[46:47], v[62:63], v[72:73]
	global_store_short_d16_hi v[58:59], v0, off
	s_nop 0
	v_pk_fma_f32 v[46:47], v[78:79], v[68:69], v[46:47]
	v_cvt_pk_bf16_f32 v0, v43, v43
	v_pk_mul_f32 v[46:47], v[142:143], v[46:47]
	v_pk_mul_f32 v[54:55], v[70:71], v[64:65]
	global_store_short_d16_hi v[66:67], v0, off
	s_nop 0
	v_pk_fma_f32 v[48:49], v[48:49], v[60:61], v[54:55]
	v_cvt_pk_bf16_f32 v0, v46, v46
	v_pk_mul_f32 v[48:49], v[142:143], v[48:49]
	global_store_short_d16_hi v[56:57], v0, off offset:32
	s_nop 0
	v_cvt_pk_bf16_f32 v0, v48, v48
	global_store_short_d16_hi v[58:59], v0, off offset:32
	s_nop 0
	v_cvt_pk_bf16_f32 v0, v47, v47
	global_store_short_d16_hi v[66:67], v0, off offset:32
	v_bfe_u32 v0, v45, 16, 1
	v_add3_u32 v56, v45, v0, s81
	v_add_u32_e32 v0, 0x24c00, v146
	v_lshl_add_u64 v[54:55], v[0:1], 1, s[0:1]
	v_bfe_u32 v0, v49, 16, 1
	v_add3_u32 v0, v49, v0, s81
	s_and_b64 vcc, exec, s[6:7]
	global_store_short_d16_hi v[54:55], v56, off
	global_store_short_d16_hi v[54:55], v0, off offset:32
	s_cbranch_vccnz .LBB0_618
; __device__ __forceinline__ unsigned pack2(float a, float b) { return (unsigned)f2bf(a) | ((unsigned)f2bf(b) << 16); }
; __device__ __forceinline__ float fexp2(float x) { return __builtin_amdgcn_exp2f(x); }
; template <int EPI, bool HS = false>
; __device__ __forceinline__ void gemm_phase(const Params& p, const GemmCfg& g, char* shm, const int wave_s) {
;     ...
;           for (int m = 0; m < 4; ++m) {
;             const int jj0 = wr * 64 + m * 16 + fq * 4;
;             const float k0 = fexp2(lg2 * (float)(127 - jj0));
;             const f32x4 r4 = *(const f32x4*)(rsw + ai * 128 + m * 16);
; #pragma unroll
;             for (int bj = 0; bj < 2; ++bj) {
;               float y1[4], y2[4];
; #pragma unroll
;               for (int j = 0; j < 4; ++j) {
;                 const int lr = ai * 128 + m * 16 + j;
;                 float cs = *(const float*)(rl + ((m * 16 + j) * 128 + bj * 64) * 4), sn = *(const float*)(rl + 65536 + ((m * 16 + j) * 128 + bj * 64) * 4);
;                 float x1 = r4[j] * acc[ai][bj][m][0][j] + swv[bj][0], x2 = r4[j] * acc[ai][bj][m][1][j] + swv[bj][1];
;                 y1[j] = (x1 * cs - x2 * sn) * scl;
;                 y2[j] = (x2 * cs + x1 * sn) * scl;
;                 dst[tb + lr * 1024 + bj * 128] = f2bf(y1[j]);
;                 dst[tb + lr * 1024 + bj * 128 + 16] = f2bf(y2[j]);
;     ...
;               if (isk) {
;                 float d0 = k0, d1 = fexp2(lg2 * (float)(126 - jj0)), d2 = fexp2(lg2 * (float)(125 - jj0)),
;                       d3 = fexp2(lg2 * (float)(124 - jj0));
;                 uint2 v1, v2;
;                 v1.x = pack2(y1[0] * d0, y1[1] * d1); v1.y = pack2(y1[2] * d2, y1[3] * d3);
;                 v2.x = pack2(y2[0] * d0, y2[1] * d1); v2.y = pack2(y2[2] * d2, y2[3] * d3);
;                 *(uint2*)(kt_t + kb + ai * 256 * 128 + (bj * 128) * 128 + m * 16) = v1;
;                 *(uint2*)(kt_t + kb + ai * 256 * 128 + (bj * 128 + 16) * 128 + m * 16) = v2;
;               }
	v_pk_mul_f32 v[42:43], v[118:119], v[42:43]
	v_pk_mul_f32 v[44:45], v[120:121], v[44:45]
	s_nop 0
	s_nop 0
	v_cvt_pk_bf16_f32 v42, v42, v42
	s_nop 0
	v_cvt_pk_bf16_f32 v0, v43, v43
	s_nop 0
	v_cvt_pk_bf16_f32 v44, v44, v44
	v_cvt_pk_bf16_f32 v43, v45, v45
	v_and_b32_e32 v44, 0xffff0000, v44
	v_and_b32_e32 v43, 0xffff0000, v43
	v_or_b32_sdwa v42, v44, v42 dst_sel:DWORD dst_unused:UNUSED_PAD src0_sel:DWORD src1_sel:WORD_1
	v_add_co_u32_e32 v44, vcc, s51, v144
	v_pk_mul_f32 v[48:49], v[120:121], v[48:49]
	v_or_b32_sdwa v43, v43, v0 dst_sel:DWORD dst_unused:UNUSED_PAD src0_sel:DWORD src1_sel:WORD_1
	v_addc_co_u32_e32 v45, vcc, 0, v145, vcc
	v_pk_mul_f32 v[46:47], v[118:119], v[46:47]
	global_store_dwordx2 v[44:45], v[42:43], off offset:32
	s_nop 0
	s_nop 0
	s_nop 0
	v_cvt_pk_bf16_f32 v44, v48, v48
	s_nop 0
	v_cvt_pk_bf16_f32 v42, v46, v46
	v_cvt_pk_bf16_f32 v43, v49, v49
	v_and_b32_e32 v44, 0xffff0000, v44
	v_cvt_pk_bf16_f32 v0, v47, v47
	v_and_b32_e32 v43, 0xffff0000, v43
	v_or_b32_sdwa v42, v44, v42 dst_sel:DWORD dst_unused:UNUSED_PAD src0_sel:DWORD src1_sel:WORD_1
	v_add_co_u32_e32 v44, vcc, 0x11000, v144
	v_or_b32_sdwa v43, v43, v0 dst_sel:DWORD dst_unused:UNUSED_PAD src0_sel:DWORD src1_sel:WORD_1
	s_nop 0
	v_addc_co_u32_e32 v45, vcc, 0, v145, vcc
	global_store_dwordx2 v[44:45], v[42:43], off offset:32
.LBB0_618:
	ds_read2st64_b32 v[42:43], v155 offset0:33 offset1:35
	ds_read2st64_b32 v[48:49], v155 offset0:37 offset1:39
	ds_read_b32 v56, v106
	ds_read_b32 v58, v107
	ds_read_b32 v57, v108
	ds_read_b32 v59, v109
	v_pk_mul_f32 v[40:41], v[40:41], v[52:53]
	v_pk_mul_f32 v[38:39], v[38:39], v[50:51]
	v_mov_b32_e32 v61, v40
	v_mov_b32_e32 v60, v38
	v_pk_mul_f32 v[36:37], v[36:37], v[52:53]
	v_pk_mul_f32 v[50:51], v[34:35], v[50:51]
	v_pk_add_f32 v[60:61], v[136:137], v[60:61]
	v_mov_b32_e32 v34, v50
	v_mov_b32_e32 v35, v36
	v_add_u32_e32 v0, 0x24080, v146
	v_pk_add_f32 v[52:53], v[134:135], v[34:35]
	s_waitcnt lgkmcnt(5)
	v_mov_b32_e32 v62, v42
	s_waitcnt lgkmcnt(4)
	v_mov_b32_e32 v63, v48
	s_waitcnt lgkmcnt(1)
	v_pk_mul_f32 v[34:35], v[60:61], v[56:57]
	v_mov_b32_e32 v40, v39
	v_lshl_add_u64 v[44:45], v[0:1], 1, s[0:1]
	v_add_u32_e32 v0, 0x24480, v146
	v_pk_fma_f32 v[34:35], v[52:53], v[62:63], v[34:35] neg_lo:[0,0,1] neg_hi:[0,0,1]
	v_pk_add_f32 v[40:41], v[136:137], v[40:41]
	v_mov_b32_e32 v36, v51
	v_lshl_add_u64 v[46:47], v[0:1], 1, s[0:1]
	v_add_u32_e32 v0, 0x24880, v146
	v_pk_mul_f32 v[34:35], v[142:143], v[34:35]
	v_pk_add_f32 v[50:51], v[134:135], v[36:37]
	v_mov_b32_e32 v48, v43
	s_waitcnt lgkmcnt(0)
	v_pk_mul_f32 v[36:37], v[40:41], v[58:59]
	v_lshl_add_u64 v[54:55], v[0:1], 1, s[0:1]
	s_nop 0
	v_pk_fma_f32 v[36:37], v[50:51], v[48:49], v[36:37] neg_lo:[0,0,1] neg_hi:[0,0,1]
	v_cvt_pk_bf16_f32 v0, v34, v34
	v_pk_mul_f32 v[36:37], v[142:143], v[36:37]
	global_store_short_d16_hi v[44:45], v0, off
	s_nop 0
	v_cvt_pk_bf16_f32 v0, v36, v36
	v_pk_mul_f32 v[38:39], v[52:53], v[56:57]
	global_store_short_d16_hi v[46:47], v0, off
	s_nop 0
	v_pk_fma_f32 v[38:39], v[60:61], v[62:63], v[38:39]
	v_cvt_pk_bf16_f32 v0, v35, v35
	v_pk_mul_f32 v[38:39], v[142:143], v[38:39]
	v_pk_mul_f32 v[42:43], v[50:51], v[58:59]
	global_store_short_d16_hi v[54:55], v0, off
	s_nop 0
	v_pk_fma_f32 v[40:41], v[40:41], v[48:49], v[42:43]
	v_cvt_pk_bf16_f32 v0, v38, v38
	v_pk_mul_f32 v[40:41], v[142:143], v[40:41]
	global_store_short_d16_hi v[44:45], v0, off offset:32
	s_nop 0
	v_cvt_pk_bf16_f32 v0, v40, v40
	global_store_short_d16_hi v[46:47], v0, off offset:32
	s_nop 0
	v_cvt_pk_bf16_f32 v0, v39, v39
	global_store_short_d16_hi v[54:55], v0, off offset:32
	v_bfe_u32 v0, v37, 16, 1
	v_add3_u32 v44, v37, v0, s81
	v_add_u32_e32 v0, 0x24c80, v146
	v_lshl_add_u64 v[42:43], v[0:1], 1, s[0:1]
	v_bfe_u32 v0, v41, 16, 1
	v_add3_u32 v0, v41, v0, s81
	s_and_b64 vcc, exec, s[6:7]
	global_store_short_d16_hi v[42:43], v44, off
	global_store_short_d16_hi v[42:43], v0, off offset:32
	s_cbranch_vccnz .LBB0_620
	v_pk_mul_f32 v[34:35], v[118:119], v[34:35]
	v_pk_mul_f32 v[36:37], v[120:121], v[36:37]
	s_nop 0
	s_nop 0
	v_cvt_pk_bf16_f32 v34, v34, v34
	s_nop 0
	v_cvt_pk_bf16_f32 v0, v35, v35
	s_nop 0
	v_cvt_pk_bf16_f32 v36, v36, v36
	v_cvt_pk_bf16_f32 v35, v37, v37
	v_and_b32_e32 v36, 0xffff0000, v36
	s_mov_b32 s2, 0x18000
	v_and_b32_e32 v35, 0xffff0000, v35
	v_or_b32_sdwa v34, v36, v34 dst_sel:DWORD dst_unused:UNUSED_PAD src0_sel:DWORD src1_sel:WORD_1
	v_add_co_u32_e32 v36, vcc, s2, v144
	v_pk_mul_f32 v[40:41], v[120:121], v[40:41]
	v_or_b32_sdwa v35, v35, v0 dst_sel:DWORD dst_unused:UNUSED_PAD src0_sel:DWORD src1_sel:WORD_1
	v_addc_co_u32_e32 v37, vcc, 0, v145, vcc
	v_pk_mul_f32 v[38:39], v[118:119], v[38:39]
	global_store_dwordx2 v[36:37], v[34:35], off offset:32
	s_nop 0
	s_nop 0
	s_nop 0
	v_cvt_pk_bf16_f32 v36, v40, v40
	s_nop 0
	v_cvt_pk_bf16_f32 v34, v38, v38
	v_cvt_pk_bf16_f32 v35, v41, v41
	v_and_b32_e32 v36, 0xffff0000, v36
	v_cvt_pk_bf16_f32 v0, v39, v39
	v_and_b32_e32 v35, 0xffff0000, v35
	v_or_b32_sdwa v34, v36, v34 dst_sel:DWORD dst_unused:UNUSED_PAD src0_sel:DWORD src1_sel:WORD_1
	v_add_co_u32_e32 v36, vcc, 0x19000, v144
	v_or_b32_sdwa v35, v35, v0 dst_sel:DWORD dst_unused:UNUSED_PAD src0_sel:DWORD src1_sel:WORD_1
	s_nop 0
	v_addc_co_u32_e32 v37, vcc, 0, v145, vcc
	global_store_dwordx2 v[36:37], v[34:35], off offset:32
; __device__ __forceinline__ unsigned pack2(float a, float b) { return (unsigned)f2bf(a) | ((unsigned)f2bf(b) << 16); }
; __device__ __forceinline__ float fexp2(float x) { return __builtin_amdgcn_exp2f(x); }
; template <int EPI, bool HS = false>
; __device__ __forceinline__ void gemm_phase(const Params& p, const GemmCfg& g, char* shm, const int wave_s) {
;     ...
;           for (int m = 0; m < 4; ++m) {
;             const int jj0 = wr * 64 + m * 16 + fq * 4;
;             const float k0 = fexp2(lg2 * (float)(127 - jj0));
;             const f32x4 r4 = *(const f32x4*)(rsw + ai * 128 + m * 16);
; #pragma unroll
;             for (int bj = 0; bj < 2; ++bj) {
;               float y1[4], y2[4];
; #pragma unroll
;               for (int j = 0; j < 4; ++j) {
;                 const int lr = ai * 128 + m * 16 + j;
;                 float cs = *(const float*)(rl + ((m * 16 + j) * 128 + bj * 64) * 4), sn = *(const float*)(rl + 65536 + ((m * 16 + j) * 128 + bj * 64) * 4);
;                 float x1 = r4[j] * acc[ai][bj][m][0][j] + swv[bj][0], x2 = r4[j] * acc[ai][bj][m][1][j] + swv[bj][1];
;                 y1[j] = (x1 * cs - x2 * sn) * scl;
;                 y2[j] = (x2 * cs + x1 * sn) * scl;
;                 dst[tb + lr * 1024 + bj * 128] = f2bf(y1[j]);
;                 dst[tb + lr * 1024 + bj * 128 + 16] = f2bf(y2[j]);
;               }
;               if (isk) {
;                 float d0 = k0, d1 = fexp2(lg2 * (float)(126 - jj0)), d2 = fexp2(lg2 * (float)(125 - jj0)),
;                       d3 = fexp2(lg2 * (float)(124 - jj0));
;                 uint2 v1, v2;
;                 v1.x = pack2(y1[0] * d0, y1[1] * d1); v1.y = pack2(y1[2] * d2, y1[3] * d3);
;                 v2.x = pack2(y2[0] * d0, y2[1] * d1); v2.y = pack2(y2[2] * d2, y2[3] * d3);
;                 *(uint2*)(kt_t + kb + ai * 256 * 128 + (bj * 128) * 128 + m * 16) = v1;
;                 *(uint2*)(kt_t + kb + ai * 256 * 128 + (bj * 128 + 16) * 128 + m * 16) = v2;
;               }
.LBB0_620:
	ds_read2st64_b32 v[38:39], v155 offset0:64 offset1:66
	ds_read2st64_b32 v[44:45], v155 offset0:68 offset1:70
	ds_read_b128 v[34:37], v154 offset:640
	ds_read_b32 v46, v110
	ds_read_b32 v48, v111
	ds_read_b32 v47, v112
	ds_read_b32 v49, v113
	s_waitcnt lgkmcnt(4)
	v_pk_mul_f32 v[32:33], v[32:33], v[36:37]
	v_pk_mul_f32 v[30:31], v[30:31], v[34:35]
	v_mov_b32_e32 v53, v32
	v_mov_b32_e32 v52, v30
	v_pk_mul_f32 v[28:29], v[28:29], v[36:37]
	v_pk_mul_f32 v[54:55], v[26:27], v[34:35]
	v_pk_add_f32 v[52:53], v[140:141], v[52:53]
	v_mov_b32_e32 v26, v54
	v_mov_b32_e32 v27, v28
	v_add_u32_e32 v0, 0x28000, v146
	v_pk_add_f32 v[56:57], v[138:139], v[26:27]
	v_mov_b32_e32 v58, v38
	v_mov_b32_e32 v59, v44
	s_waitcnt lgkmcnt(1)
	v_pk_mul_f32 v[26:27], v[46:47], v[52:53]
	v_mov_b32_e32 v32, v31
	v_lshl_add_u64 v[40:41], v[0:1], 1, s[0:1]
	v_add_u32_e32 v0, 0x28400, v146
	v_pk_fma_f32 v[26:27], v[58:59], v[56:57], v[26:27] neg_lo:[0,0,1] neg_hi:[0,0,1]
	v_pk_add_f32 v[32:33], v[140:141], v[32:33]
	v_mov_b32_e32 v28, v55
	v_lshl_add_u64 v[42:43], v[0:1], 1, s[0:1]
	v_add_u32_e32 v0, 0x28800, v146
	v_pk_mul_f32 v[26:27], v[142:143], v[26:27]
	v_pk_add_f32 v[54:55], v[138:139], v[28:29]
	v_mov_b32_e32 v44, v39
	s_waitcnt lgkmcnt(0)
	v_pk_mul_f32 v[28:29], v[32:33], v[48:49]
	v_lshl_add_u64 v[50:51], v[0:1], 1, s[0:1]
	s_nop 0
	v_pk_fma_f32 v[28:29], v[54:55], v[44:45], v[28:29] neg_lo:[0,0,1] neg_hi:[0,0,1]
	v_cvt_pk_bf16_f32 v0, v26, v26
	v_pk_mul_f32 v[28:29], v[142:143], v[28:29]
	global_store_short_d16_hi v[40:41], v0, off
	s_nop 0
	v_cvt_pk_bf16_f32 v0, v28, v28
	v_pk_mul_f32 v[30:31], v[46:47], v[56:57]
	global_store_short_d16_hi v[42:43], v0, off
	s_nop 0
	v_pk_fma_f32 v[30:31], v[58:59], v[52:53], v[30:31]
	v_cvt_pk_bf16_f32 v0, v27, v27
	v_pk_mul_f32 v[30:31], v[142:143], v[30:31]
	v_pk_mul_f32 v[38:39], v[54:55], v[48:49]
	global_store_short_d16_hi v[50:51], v0, off
	s_nop 0
	v_pk_fma_f32 v[32:33], v[32:33], v[44:45], v[38:39]
	v_cvt_pk_bf16_f32 v0, v30, v30
	v_pk_mul_f32 v[32:33], v[142:143], v[32:33]
	global_store_short_d16_hi v[40:41], v0, off offset:32
	s_nop 0
	v_cvt_pk_bf16_f32 v0, v32, v32
	global_store_short_d16_hi v[42:43], v0, off offset:32
	s_nop 0
	v_cvt_pk_bf16_f32 v0, v31, v31
	global_store_short_d16_hi v[50:51], v0, off offset:32
	v_bfe_u32 v0, v29, 16, 1
	v_add3_u32 v40, v29, v0, s81
	v_add_u32_e32 v0, 0x28c00, v146
	v_lshl_add_u64 v[38:39], v[0:1], 1, s[0:1]
	v_bfe_u32 v0, v33, 16, 1
	v_add3_u32 v0, v33, v0, s81
	s_and_b64 vcc, exec, s[6:7]
	global_store_short_d16_hi v[38:39], v40, off
	global_store_short_d16_hi v[38:39], v0, off offset:32
	s_cbranch_vccnz .LBB0_622
	v_pk_mul_f32 v[26:27], v[102:103], v[26:27]
	v_pk_mul_f32 v[28:29], v[104:105], v[28:29]
	s_nop 0
	s_nop 0
	v_cvt_pk_bf16_f32 v26, v26, v26
	s_nop 0
	v_cvt_pk_bf16_f32 v0, v27, v27
	s_nop 0
	v_cvt_pk_bf16_f32 v28, v28, v28
	v_cvt_pk_bf16_f32 v27, v29, v29
	v_and_b32_e32 v28, 0xffff0000, v28
	v_and_b32_e32 v27, 0xffff0000, v27
	v_or_b32_sdwa v26, v28, v26 dst_sel:DWORD dst_unused:UNUSED_PAD src0_sel:DWORD src1_sel:WORD_1
	v_add_co_u32_e32 v28, vcc, s51, v144
	v_pk_mul_f32 v[32:33], v[104:105], v[32:33]
	v_or_b32_sdwa v27, v27, v0 dst_sel:DWORD dst_unused:UNUSED_PAD src0_sel:DWORD src1_sel:WORD_1
	v_addc_co_u32_e32 v29, vcc, 0, v145, vcc
	v_pk_mul_f32 v[30:31], v[102:103], v[30:31]
	global_store_dwordx2 v[28:29], v[26:27], off offset:64
	s_nop 0
	s_nop 0
	s_nop 0
	v_cvt_pk_bf16_f32 v28, v32, v32
	s_nop 0
	v_cvt_pk_bf16_f32 v26, v30, v30
	v_cvt_pk_bf16_f32 v27, v33, v33
	v_and_b32_e32 v28, 0xffff0000, v28
	v_cvt_pk_bf16_f32 v0, v31, v31
	v_and_b32_e32 v27, 0xffff0000, v27
	v_or_b32_sdwa v26, v28, v26 dst_sel:DWORD dst_unused:UNUSED_PAD src0_sel:DWORD src1_sel:WORD_1
	v_add_co_u32_e32 v28, vcc, 0x11000, v144
	v_or_b32_sdwa v27, v27, v0 dst_sel:DWORD dst_unused:UNUSED_PAD src0_sel:DWORD src1_sel:WORD_1
	s_nop 0
	v_addc_co_u32_e32 v29, vcc, 0, v145, vcc
	global_store_dwordx2 v[28:29], v[26:27], off offset:64
.LBB0_622:
	ds_read2st64_b32 v[26:27], v155 offset0:65 offset1:67
	ds_read2st64_b32 v[32:33], v155 offset0:69 offset1:71
	ds_read_b32 v40, v90
	ds_read_b32 v42, v91
	ds_read_b32 v41, v92
	ds_read_b32 v43, v93
	v_pk_mul_f32 v[24:25], v[24:25], v[36:37]
	v_pk_mul_f32 v[22:23], v[22:23], v[34:35]
	v_mov_b32_e32 v45, v24
	v_mov_b32_e32 v44, v22
	v_pk_mul_f32 v[20:21], v[20:21], v[36:37]
	v_pk_mul_f32 v[34:35], v[18:19], v[34:35]
	v_pk_add_f32 v[44:45], v[136:137], v[44:45]
	v_mov_b32_e32 v18, v34
	v_mov_b32_e32 v19, v20
	v_add_u32_e32 v0, 0x28080, v146
	v_pk_add_f32 v[36:37], v[134:135], v[18:19]
	s_waitcnt lgkmcnt(5)
	v_mov_b32_e32 v46, v26
	s_waitcnt lgkmcnt(4)
	v_mov_b32_e32 v47, v32
	s_waitcnt lgkmcnt(1)
	v_pk_mul_f32 v[18:19], v[44:45], v[40:41]
	v_mov_b32_e32 v24, v23
	v_lshl_add_u64 v[28:29], v[0:1], 1, s[0:1]
	v_add_u32_e32 v0, 0x28480, v146
	v_pk_fma_f32 v[18:19], v[36:37], v[46:47], v[18:19] neg_lo:[0,0,1] neg_hi:[0,0,1]
	v_pk_add_f32 v[24:25], v[136:137], v[24:25]
	v_mov_b32_e32 v20, v35
	v_lshl_add_u64 v[30:31], v[0:1], 1, s[0:1]
	v_add_u32_e32 v0, 0x28880, v146
	v_pk_mul_f32 v[18:19], v[142:143], v[18:19]
	v_pk_add_f32 v[34:35], v[134:135], v[20:21]
	v_mov_b32_e32 v32, v27
	s_waitcnt lgkmcnt(0)
	v_pk_mul_f32 v[20:21], v[24:25], v[42:43]
	v_lshl_add_u64 v[38:39], v[0:1], 1, s[0:1]
	s_nop 0
	v_pk_fma_f32 v[20:21], v[34:35], v[32:33], v[20:21] neg_lo:[0,0,1] neg_hi:[0,0,1]
	v_cvt_pk_bf16_f32 v0, v18, v18
	v_pk_mul_f32 v[20:21], v[142:143], v[20:21]
	global_store_short_d16_hi v[28:29], v0, off
	s_nop 0
	v_cvt_pk_bf16_f32 v0, v20, v20
	v_pk_mul_f32 v[22:23], v[36:37], v[40:41]
	global_store_short_d16_hi v[30:31], v0, off
	s_nop 0
	v_pk_fma_f32 v[22:23], v[44:45], v[46:47], v[22:23]
	v_cvt_pk_bf16_f32 v0, v19, v19
	v_pk_mul_f32 v[22:23], v[142:143], v[22:23]
	v_pk_mul_f32 v[26:27], v[34:35], v[42:43]
	global_store_short_d16_hi v[38:39], v0, off
	s_nop 0
	v_pk_fma_f32 v[24:25], v[24:25], v[32:33], v[26:27]
	v_cvt_pk_bf16_f32 v0, v22, v22
	v_pk_mul_f32 v[24:25], v[142:143], v[24:25]
	global_store_short_d16_hi v[28:29], v0, off offset:32
	s_nop 0
	v_cvt_pk_bf16_f32 v0, v24, v24
	global_store_short_d16_hi v[30:31], v0, off offset:32
	s_nop 0
	v_cvt_pk_bf16_f32 v0, v23, v23
	global_store_short_d16_hi v[38:39], v0, off offset:32
	v_bfe_u32 v0, v21, 16, 1
	v_add3_u32 v28, v21, v0, s81
	v_add_u32_e32 v0, 0x28c80, v146
	v_lshl_add_u64 v[26:27], v[0:1], 1, s[0:1]
	v_bfe_u32 v0, v25, 16, 1
	v_add3_u32 v0, v25, v0, s81
	s_and_b64 vcc, exec, s[6:7]
	global_store_short_d16_hi v[26:27], v28, off
	global_store_short_d16_hi v[26:27], v0, off offset:32
	s_cbranch_vccnz .LBB0_624
; __device__ __forceinline__ unsigned pack2(float a, float b) { return (unsigned)f2bf(a) | ((unsigned)f2bf(b) << 16); }
; __device__ __forceinline__ float fexp2(float x) { return __builtin_amdgcn_exp2f(x); }
; template <int EPI, bool HS = false>
; __device__ __forceinline__ void gemm_phase(const Params& p, const GemmCfg& g, char* shm, const int wave_s) {
;     ...
;           for (int m = 0; m < 4; ++m) {
;             const int jj0 = wr * 64 + m * 16 + fq * 4;
;             const float k0 = fexp2(lg2 * (float)(127 - jj0));
;             const f32x4 r4 = *(const f32x4*)(rsw + ai * 128 + m * 16);
; #pragma unroll
;             for (int bj = 0; bj < 2; ++bj) {
;               float y1[4], y2[4];
; #pragma unroll
;               for (int j = 0; j < 4; ++j) {
;                 const int lr = ai * 128 + m * 16 + j;
;                 float cs = *(const float*)(rl + ((m * 16 + j) * 128 + bj * 64) * 4), sn = *(const float*)(rl + 65536 + ((m * 16 + j) * 128 + bj * 64) * 4);
;                 float x1 = r4[j] * acc[ai][bj][m][0][j] + swv[bj][0], x2 = r4[j] * acc[ai][bj][m][1][j] + swv[bj][1];
;                 y1[j] = (x1 * cs - x2 * sn) * scl;
;                 y2[j] = (x2 * cs + x1 * sn) * scl;
;                 dst[tb + lr * 1024 + bj * 128] = f2bf(y1[j]);
;                 dst[tb + lr * 1024 + bj * 128 + 16] = f2bf(y2[j]);
;     ...
;               if (isk) {
;                 float d0 = k0, d1 = fexp2(lg2 * (float)(126 - jj0)), d2 = fexp2(lg2 * (float)(125 - jj0)),
;                       d3 = fexp2(lg2 * (float)(124 - jj0));
;                 uint2 v1, v2;
;                 v1.x = pack2(y1[0] * d0, y1[1] * d1); v1.y = pack2(y1[2] * d2, y1[3] * d3);
;                 v2.x = pack2(y2[0] * d0, y2[1] * d1); v2.y = pack2(y2[2] * d2, y2[3] * d3);
;                 *(uint2*)(kt_t + kb + ai * 256 * 128 + (bj * 128) * 128 + m * 16) = v1;
;                 *(uint2*)(kt_t + kb + ai * 256 * 128 + (bj * 128 + 16) * 128 + m * 16) = v2;
;               }
	v_pk_mul_f32 v[18:19], v[102:103], v[18:19]
	v_pk_mul_f32 v[20:21], v[104:105], v[20:21]
	s_nop 0
	s_nop 0
	v_cvt_pk_bf16_f32 v18, v18, v18
	s_nop 0
	v_cvt_pk_bf16_f32 v0, v19, v19
	s_nop 0
	v_cvt_pk_bf16_f32 v20, v20, v20
	v_cvt_pk_bf16_f32 v19, v21, v21
	v_and_b32_e32 v20, 0xffff0000, v20
	s_mov_b32 s2, 0x18000
	v_and_b32_e32 v19, 0xffff0000, v19
	v_or_b32_sdwa v18, v20, v18 dst_sel:DWORD dst_unused:UNUSED_PAD src0_sel:DWORD src1_sel:WORD_1
	v_add_co_u32_e32 v20, vcc, s2, v144
	v_pk_mul_f32 v[24:25], v[104:105], v[24:25]
	v_or_b32_sdwa v19, v19, v0 dst_sel:DWORD dst_unused:UNUSED_PAD src0_sel:DWORD src1_sel:WORD_1
	v_addc_co_u32_e32 v21, vcc, 0, v145, vcc
	v_pk_mul_f32 v[22:23], v[102:103], v[22:23]
	global_store_dwordx2 v[20:21], v[18:19], off offset:64
	s_nop 0
	s_nop 0
	s_nop 0
	v_cvt_pk_bf16_f32 v20, v24, v24
	s_nop 0
	v_cvt_pk_bf16_f32 v18, v22, v22
	v_cvt_pk_bf16_f32 v19, v25, v25
	v_and_b32_e32 v20, 0xffff0000, v20
	v_cvt_pk_bf16_f32 v0, v23, v23
	v_and_b32_e32 v19, 0xffff0000, v19
	v_or_b32_sdwa v18, v20, v18 dst_sel:DWORD dst_unused:UNUSED_PAD src0_sel:DWORD src1_sel:WORD_1
	v_add_co_u32_e32 v20, vcc, 0x19000, v144
	v_or_b32_sdwa v19, v19, v0 dst_sel:DWORD dst_unused:UNUSED_PAD src0_sel:DWORD src1_sel:WORD_1
	s_nop 0
	v_addc_co_u32_e32 v21, vcc, 0, v145, vcc
	global_store_dwordx2 v[20:21], v[18:19], off offset:64
.LBB0_624:
	ds_read2st64_b32 v[22:23], v155 offset0:96 offset1:98
	ds_read2st64_b32 v[28:29], v155 offset0:100 offset1:102
	ds_read_b128 v[18:21], v154 offset:704
	ds_read_b32 v30, v94
	ds_read_b32 v32, v95
	ds_read_b32 v31, v96
	ds_read_b32 v33, v97
	s_waitcnt lgkmcnt(4)
	v_pk_mul_f32 v[16:17], v[16:17], v[20:21]
	v_pk_mul_f32 v[14:15], v[14:15], v[18:19]
	v_mov_b32_e32 v37, v16
	v_mov_b32_e32 v36, v14
	v_pk_mul_f32 v[12:13], v[12:13], v[20:21]
	v_pk_mul_f32 v[38:39], v[10:11], v[18:19]
	v_pk_add_f32 v[36:37], v[140:141], v[36:37]
	v_mov_b32_e32 v10, v38
	v_mov_b32_e32 v11, v12
	v_add_u32_e32 v0, 0x2c000, v146
	v_pk_add_f32 v[40:41], v[138:139], v[10:11]
	v_mov_b32_e32 v42, v22
	v_mov_b32_e32 v43, v28
	s_waitcnt lgkmcnt(1)
	v_pk_mul_f32 v[10:11], v[30:31], v[36:37]
	v_mov_b32_e32 v16, v15
	v_lshl_add_u64 v[24:25], v[0:1], 1, s[0:1]
	v_add_u32_e32 v0, 0x2c400, v146
	v_pk_fma_f32 v[10:11], v[42:43], v[40:41], v[10:11] neg_lo:[0,0,1] neg_hi:[0,0,1]
	v_pk_add_f32 v[16:17], v[140:141], v[16:17]
	v_mov_b32_e32 v12, v39
	v_lshl_add_u64 v[26:27], v[0:1], 1, s[0:1]
	v_add_u32_e32 v0, 0x2c800, v146
	v_pk_mul_f32 v[10:11], v[142:143], v[10:11]
	v_pk_add_f32 v[38:39], v[138:139], v[12:13]
	v_mov_b32_e32 v28, v23
	s_waitcnt lgkmcnt(0)
	v_pk_mul_f32 v[12:13], v[16:17], v[32:33]
	v_lshl_add_u64 v[34:35], v[0:1], 1, s[0:1]
	s_nop 0
	v_pk_fma_f32 v[12:13], v[38:39], v[28:29], v[12:13] neg_lo:[0,0,1] neg_hi:[0,0,1]
	v_cvt_pk_bf16_f32 v0, v10, v10
	v_pk_mul_f32 v[12:13], v[142:143], v[12:13]
	global_store_short_d16_hi v[24:25], v0, off
	s_nop 0
	v_cvt_pk_bf16_f32 v0, v12, v12
	v_pk_mul_f32 v[14:15], v[30:31], v[40:41]
	global_store_short_d16_hi v[26:27], v0, off
	s_nop 0
	v_pk_fma_f32 v[14:15], v[42:43], v[36:37], v[14:15]
	v_cvt_pk_bf16_f32 v0, v11, v11
	v_pk_mul_f32 v[14:15], v[142:143], v[14:15]
	v_pk_mul_f32 v[22:23], v[38:39], v[32:33]
	global_store_short_d16_hi v[34:35], v0, off
	s_nop 0
	v_pk_fma_f32 v[16:17], v[16:17], v[28:29], v[22:23]
	v_cvt_pk_bf16_f32 v0, v14, v14
	v_pk_mul_f32 v[16:17], v[142:143], v[16:17]
	global_store_short_d16_hi v[24:25], v0, off offset:32
	s_nop 0
	v_cvt_pk_bf16_f32 v0, v16, v16
	global_store_short_d16_hi v[26:27], v0, off offset:32
	s_nop 0
	v_cvt_pk_bf16_f32 v0, v15, v15
	global_store_short_d16_hi v[34:35], v0, off offset:32
	v_bfe_u32 v0, v13, 16, 1
	v_add3_u32 v24, v13, v0, s81
	v_add_u32_e32 v0, 0x2cc00, v146
	v_lshl_add_u64 v[22:23], v[0:1], 1, s[0:1]
	v_bfe_u32 v0, v17, 16, 1
	v_add3_u32 v0, v17, v0, s81
	s_and_b64 vcc, exec, s[6:7]
	global_store_short_d16_hi v[22:23], v24, off
	global_store_short_d16_hi v[22:23], v0, off offset:32
	s_cbranch_vccnz .LBB0_626
	v_pk_mul_f32 v[10:11], v[86:87], v[10:11]
	v_pk_mul_f32 v[12:13], v[88:89], v[12:13]
	s_nop 0
	s_nop 0
	v_cvt_pk_bf16_f32 v10, v10, v10
	s_nop 0
	v_cvt_pk_bf16_f32 v0, v11, v11
	s_nop 0
	v_cvt_pk_bf16_f32 v12, v12, v12
	v_cvt_pk_bf16_f32 v11, v13, v13
	v_and_b32_e32 v12, 0xffff0000, v12
	v_and_b32_e32 v11, 0xffff0000, v11
	v_or_b32_sdwa v10, v12, v10 dst_sel:DWORD dst_unused:UNUSED_PAD src0_sel:DWORD src1_sel:WORD_1
	v_add_co_u32_e32 v12, vcc, s51, v144
	v_pk_mul_f32 v[16:17], v[88:89], v[16:17]
	v_or_b32_sdwa v11, v11, v0 dst_sel:DWORD dst_unused:UNUSED_PAD src0_sel:DWORD src1_sel:WORD_1
	v_addc_co_u32_e32 v13, vcc, 0, v145, vcc
	v_pk_mul_f32 v[14:15], v[86:87], v[14:15]
	global_store_dwordx2 v[12:13], v[10:11], off offset:96
	s_nop 0
	s_nop 0
	s_nop 0
	v_cvt_pk_bf16_f32 v12, v16, v16
	s_nop 0
	v_cvt_pk_bf16_f32 v10, v14, v14
	v_cvt_pk_bf16_f32 v11, v17, v17
	v_and_b32_e32 v12, 0xffff0000, v12
	v_cvt_pk_bf16_f32 v0, v15, v15
	v_and_b32_e32 v11, 0xffff0000, v11
	v_or_b32_sdwa v10, v12, v10 dst_sel:DWORD dst_unused:UNUSED_PAD src0_sel:DWORD src1_sel:WORD_1
	v_add_co_u32_e32 v12, vcc, 0x11000, v144
	v_or_b32_sdwa v11, v11, v0 dst_sel:DWORD dst_unused:UNUSED_PAD src0_sel:DWORD src1_sel:WORD_1
	s_nop 0
	v_addc_co_u32_e32 v13, vcc, 0, v145, vcc
	global_store_dwordx2 v[12:13], v[10:11], off offset:96
; __device__ __forceinline__ unsigned pack2(float a, float b) { return (unsigned)f2bf(a) | ((unsigned)f2bf(b) << 16); }
; __device__ __forceinline__ float fexp2(float x) { return __builtin_amdgcn_exp2f(x); }
; template <int EPI, bool HS = false>
; __device__ __forceinline__ void gemm_phase(const Params& p, const GemmCfg& g, char* shm, const int wave_s) {
;     ...
;           for (int m = 0; m < 4; ++m) {
;             const int jj0 = wr * 64 + m * 16 + fq * 4;
;             const float k0 = fexp2(lg2 * (float)(127 - jj0));
;             const f32x4 r4 = *(const f32x4*)(rsw + ai * 128 + m * 16);
; #pragma unroll
;             for (int bj = 0; bj < 2; ++bj) {
;               float y1[4], y2[4];
; #pragma unroll
;               for (int j = 0; j < 4; ++j) {
;                 const int lr = ai * 128 + m * 16 + j;
;                 float cs = *(const float*)(rl + ((m * 16 + j) * 128 + bj * 64) * 4), sn = *(const float*)(rl + 65536 + ((m * 16 + j) * 128 + bj * 64) * 4);
;                 float x1 = r4[j] * acc[ai][bj][m][0][j] + swv[bj][0], x2 = r4[j] * acc[ai][bj][m][1][j] + swv[bj][1];
;                 y1[j] = (x1 * cs - x2 * sn) * scl;
;                 y2[j] = (x2 * cs + x1 * sn) * scl;
;                 dst[tb + lr * 1024 + bj * 128] = f2bf(y1[j]);
;                 dst[tb + lr * 1024 + bj * 128 + 16] = f2bf(y2[j]);
;               }
;               if (isk) {
;                 float d0 = k0, d1 = fexp2(lg2 * (float)(126 - jj0)), d2 = fexp2(lg2 * (float)(125 - jj0)),
;                       d3 = fexp2(lg2 * (float)(124 - jj0));
;                 uint2 v1, v2;
;                 v1.x = pack2(y1[0] * d0, y1[1] * d1); v1.y = pack2(y1[2] * d2, y1[3] * d3);
;                 v2.x = pack2(y2[0] * d0, y2[1] * d1); v2.y = pack2(y2[2] * d2, y2[3] * d3);
;                 *(uint2*)(kt_t + kb + ai * 256 * 128 + (bj * 128) * 128 + m * 16) = v1;
;                 *(uint2*)(kt_t + kb + ai * 256 * 128 + (bj * 128 + 16) * 128 + m * 16) = v2;
;               }
.LBB0_626:
	ds_read2st64_b32 v[10:11], v155 offset0:97 offset1:99
	ds_read2st64_b32 v[16:17], v155 offset0:101 offset1:103
	ds_read_b32 v24, v74
	ds_read_b32 v26, v75
	ds_read_b32 v25, v76
	ds_read_b32 v27, v77
	v_pk_mul_f32 v[8:9], v[8:9], v[20:21]
	v_pk_mul_f32 v[6:7], v[6:7], v[18:19]
	v_mov_b32_e32 v29, v8
	v_mov_b32_e32 v28, v6
	v_pk_mul_f32 v[4:5], v[4:5], v[20:21]
	v_pk_mul_f32 v[18:19], v[2:3], v[18:19]
	v_pk_add_f32 v[28:29], v[136:137], v[28:29]
	v_mov_b32_e32 v2, v18
	v_mov_b32_e32 v3, v4
	v_add_u32_e32 v0, 0x2c080, v146
	v_pk_add_f32 v[20:21], v[134:135], v[2:3]
	s_waitcnt lgkmcnt(5)
	v_mov_b32_e32 v30, v10
	s_waitcnt lgkmcnt(4)
	v_mov_b32_e32 v31, v16
	s_waitcnt lgkmcnt(1)
	v_pk_mul_f32 v[2:3], v[28:29], v[24:25]
	v_mov_b32_e32 v8, v7
	v_lshl_add_u64 v[12:13], v[0:1], 1, s[0:1]
	v_add_u32_e32 v0, 0x2c480, v146
	v_pk_fma_f32 v[2:3], v[20:21], v[30:31], v[2:3] neg_lo:[0,0,1] neg_hi:[0,0,1]
	v_pk_add_f32 v[8:9], v[136:137], v[8:9]
	v_mov_b32_e32 v4, v19
	v_lshl_add_u64 v[14:15], v[0:1], 1, s[0:1]
	v_add_u32_e32 v0, 0x2c880, v146
	v_pk_mul_f32 v[2:3], v[142:143], v[2:3]
	v_pk_add_f32 v[18:19], v[134:135], v[4:5]
	v_mov_b32_e32 v16, v11
	s_waitcnt lgkmcnt(0)
	v_pk_mul_f32 v[4:5], v[8:9], v[26:27]
	v_lshl_add_u64 v[22:23], v[0:1], 1, s[0:1]
	s_nop 0
	v_pk_fma_f32 v[4:5], v[18:19], v[16:17], v[4:5] neg_lo:[0,0,1] neg_hi:[0,0,1]
	v_cvt_pk_bf16_f32 v0, v2, v2
	v_pk_mul_f32 v[4:5], v[142:143], v[4:5]
	global_store_short_d16_hi v[12:13], v0, off
	s_nop 0
	v_cvt_pk_bf16_f32 v0, v4, v4
	v_pk_mul_f32 v[6:7], v[20:21], v[24:25]
	global_store_short_d16_hi v[14:15], v0, off
	s_nop 0
	v_pk_fma_f32 v[6:7], v[28:29], v[30:31], v[6:7]
	v_cvt_pk_bf16_f32 v0, v3, v3
	v_pk_mul_f32 v[6:7], v[142:143], v[6:7]
	v_pk_mul_f32 v[10:11], v[18:19], v[26:27]
	global_store_short_d16_hi v[22:23], v0, off
	s_nop 0
	v_pk_fma_f32 v[8:9], v[8:9], v[16:17], v[10:11]
	v_cvt_pk_bf16_f32 v0, v6, v6
	v_pk_mul_f32 v[8:9], v[142:143], v[8:9]
	global_store_short_d16_hi v[12:13], v0, off offset:32
	s_nop 0
	v_cvt_pk_bf16_f32 v0, v8, v8
	global_store_short_d16_hi v[14:15], v0, off offset:32
	s_nop 0
	v_cvt_pk_bf16_f32 v0, v7, v7
	global_store_short_d16_hi v[22:23], v0, off offset:32
	v_bfe_u32 v0, v5, 16, 1
	v_add3_u32 v12, v5, v0, s81
	v_add_u32_e32 v0, 0x2cc80, v146
	v_lshl_add_u64 v[10:11], v[0:1], 1, s[0:1]
	v_bfe_u32 v0, v9, 16, 1
	v_add3_u32 v0, v9, v0, s81
	s_and_b64 vcc, exec, s[6:7]
	global_store_short_d16_hi v[10:11], v12, off
	global_store_short_d16_hi v[10:11], v0, off offset:32
	s_cbranch_vccnz .LBB0_628
	v_pk_mul_f32 v[2:3], v[86:87], v[2:3]
	v_pk_mul_f32 v[4:5], v[88:89], v[4:5]
	s_nop 0
	s_nop 0
	v_cvt_pk_bf16_f32 v2, v2, v2
	v_and_b32_sdwa v10, v4, v178 dst_sel:DWORD dst_unused:UNUSED_PAD src0_sel:WORD_1 src1_sel:DWORD
	v_cvt_pk_bf16_f32 v0, v3, v3
	s_nop 0
	v_add3_u32 v4, v4, v10, s81
	v_cvt_pk_bf16_f32 v3, v5, v5
	v_and_b32_e32 v4, 0xffff0000, v4
	s_mov_b32 s0, 0x18000
	v_and_b32_e32 v3, 0xffff0000, v3
	v_or_b32_sdwa v2, v4, v2 dst_sel:DWORD dst_unused:UNUSED_PAD src0_sel:DWORD src1_sel:WORD_1
	v_add_co_u32_e32 v4, vcc, s0, v144
	v_pk_mul_f32 v[8:9], v[88:89], v[8:9]
	v_or_b32_sdwa v3, v3, v0 dst_sel:DWORD dst_unused:UNUSED_PAD src0_sel:DWORD src1_sel:WORD_1
	v_addc_co_u32_e32 v5, vcc, 0, v145, vcc
	v_pk_mul_f32 v[6:7], v[86:87], v[6:7]
	global_store_dwordx2 v[4:5], v[2:3], off offset:96
	s_nop 0
	s_nop 0
	s_nop 0
	v_cvt_pk_bf16_f32 v4, v8, v8
	v_and_b32_sdwa v0, v7, v178 dst_sel:DWORD dst_unused:UNUSED_PAD src0_sel:WORD_1 src1_sel:DWORD
	v_cvt_pk_bf16_f32 v2, v6, v6
	v_cvt_pk_bf16_f32 v3, v9, v9
	v_and_b32_e32 v4, 0xffff0000, v4
	v_add3_u32 v0, v7, v0, s81
	v_and_b32_e32 v3, 0xffff0000, v3
	v_or_b32_sdwa v2, v4, v2 dst_sel:DWORD dst_unused:UNUSED_PAD src0_sel:DWORD src1_sel:WORD_1
	v_add_co_u32_e32 v4, vcc, 0x19000, v144
	v_or_b32_sdwa v3, v3, v0 dst_sel:DWORD dst_unused:UNUSED_PAD src0_sel:DWORD src1_sel:WORD_1
	s_nop 0
	v_addc_co_u32_e32 v5, vcc, 0, v145, vcc
	global_store_dwordx2 v[4:5], v[2:3], off offset:96

; __device__ __forceinline__ unsigned pack2(float a, float b) { return (unsigned)f2bf(a) | ((unsigned)f2bf(b) << 16); }
; #define WAIT_V(n) asm volatile("s_waitcnt vmcnt(" #n ")" ::: "memory")
; template <int EPI, bool HS = false>
; __device__ __forceinline__ void gemm_phase(const Params& p, const GemmCfg& g, char* shm, const int wave_s) {
;     ...
;       const float* xin_t = g.xin + (size_t)orow0 * 1024 + pn * 256;
;       float* xout_t = g.xout + (size_t)orow0 * 1024 + pn * 256;
;       u16* xg_t = p.h + (size_t)orow0 * 1024 + pn * 256;
;       float* rss_t = p.rowss + (size_t)orow0 * 16 + pn * 4 + wc;
;       const unsigned tb = (unsigned)((wr * 64 + fq * 4) * 1024 + wc * 32 + 2 * fr);
;       const unsigned ldsb = (unsigned)(size_t)(__attribute__((address_space(3))) char*)shm;
;       const int wv_s = __builtin_amdgcn_readfirstlane(wid);
;       constexpr int XROW = 1040;
;       const char* xl = shm + (wr * 64 + fq * 4) * XROW + (wc * 32 + 2 * fr) * 4;
; #pragma unroll
;       for (int ai = 0; ai < 2; ++ai) {
; #pragma unroll
;         for (int i = 0; i < 16; ++i) {
;           const int r = wv_s * 16 + i;
;           glds_row(xin_t + (size_t)(ai * 128 + r) * 1024, (unsigned)lane * 16u, ldsb + (unsigned)(r * XROW));
;         }
;         WAIT_V(0);
;         __syncthreads();
; #pragma unroll
;         for (int m = 0; m < 4; ++m) {
;           float2 xv[4][2];
; #pragma unroll
;           for (int j = 0; j < 4; ++j)
; #pragma unroll
;             for (int bj = 0; bj < 2; ++bj) xv[j][bj] = *(const float2*)(xl + (m * 16 + j) * XROW + bj * 512);
; #pragma unroll
;           for (int j = 0; j < 4; ++j) {
;             float ss = 0.f;
; #pragma unroll
;             for (int bj = 0; bj < 2; ++bj) {
;               float2 xn;
;               xn.x = xv[j][bj].x + gt[bj][0] * acc[ai][bj][m][0][j];
;               xn.y = xv[j][bj].y + gt[bj][1] * acc[ai][bj][m][1][j];
;               const unsigned o = tb + (unsigned)((ai * 128 + m * 16 + j) * 1024 + bj * 128);
;               *(float2*)(xout_t + o) = xn;
;               if (g.has_next) *(unsigned*)(xg_t + o) = pack2(xn.x * gn[bj][0], xn.y * gn[bj][1]);
;               ss += xn.x * xn.x + xn.y * xn.y;
.LBB0_654:
	s_or_b64 exec, exec, s[0:1]
	s_mov_b32 s0, s82
	s_mov_b32 s1, -1
	v_readlane_b32 s3, v254, 56
	v_mbcnt_lo_u32_b32 v0, s1, 0
	v_mbcnt_hi_u32_b32 v0, s1, v0
	v_lshl_add_u32 v0, s0, 6, v0
	s_lshl_b64 s[0:1], s[4:5], 12
	s_add_u32 s11, s3, s0
	v_readlane_b32 s3, v254, 55
	s_addc_u32 s12, s3, s1
	s_ashr_i32 s3, s2, 31
	s_lshl_b64 s[8:9], s[2:3], 2
	s_add_u32 s71, s11, s8
	s_addc_u32 s72, s12, s9
	v_readlane_b32 s12, v253, 25
	v_readlane_b32 s24, v253, 37
	v_readlane_b32 s25, v253, 38
	s_add_u32 s0, s24, s0
	s_addc_u32 s1, s25, s1
	s_add_u32 s0, s0, s8
	s_addc_u32 s1, s1, s9
	s_lshl_b64 s[8:9], s[4:5], 11
	s_add_u32 s8, s88, s8
	s_addc_u32 s9, s89, s9
	v_lshrrev_b32_e32 v132, 2, v0
	s_lshl_b64 s[2:3], s[2:3], 1
	v_ashrrev_i32_e32 v130, 6, v0
	v_ashrrev_i32_e32 v131, 2, v0
	v_and_b32_e32 v132, 12, v132
	s_add_u32 s2, s8, s2
	s_movk_i32 s8, 0xffc0
	v_and_or_b32 v163, v131, s8, v132
	v_readfirstlane_b32 s8, v130
	s_addc_u32 s3, s9, s3
	s_movk_i32 s9, 0x410
	s_lshl_b32 s8, s8, 4
	v_and_b32_e32 v169, 3, v130
	v_readlane_b32 s13, v253, 26
	v_mul_lo_u32 v130, v163, s9
	s_ashr_i32 s9, s8, 31
	s_lshl_b64 s[12:13], s[8:9], 12
	v_and_b32_e32 v168, 15, v0
	v_lshlrev_b32_e32 v0, 4, v0
	s_add_u32 s12, s71, s12
	s_mul_i32 s73, s8, 0x410
	v_and_b32_e32 v167, 0x3f0, v0
	s_addc_u32 s13, s72, s13
	s_add_i32 s73, s73, 0
	s_mov_b32 m0, s73
	s_nop 0
	global_load_lds_dwordx4 v167, s[12:13]
	s_or_b32 s12, s8, 1
	v_readlane_b32 s14, v253, 27
	v_readlane_b32 s15, v253, 28
	s_ashr_i32 s13, s12, 31
	s_lshl_b64 s[14:15], s[12:13], 12
	s_add_u32 s14, s71, s14
	s_addc_u32 s15, s72, s15
	s_mul_i32 s74, s12, 0x410
	s_or_b32 s12, s8, 2
	s_ashr_i32 s13, s12, 31
	s_add_i32 s74, s74, 0
	s_mov_b32 m0, s74
	s_nop 0
	global_load_lds_dwordx4 v167, s[14:15]
	s_lshl_b64 s[14:15], s[12:13], 12
	s_add_u32 s14, s71, s14
	s_mulk_i32 s12, 0x410
	s_addc_u32 s15, s72, s15
	s_add_i32 s12, s12, 0
	s_mov_b32 m0, s12
	s_nop 0
	global_load_lds_dwordx4 v167, s[14:15]
	s_or_b32 s14, s8, 3
	v_readlane_b32 s16, v253, 29
	v_readlane_b32 s17, v253, 30
	s_ashr_i32 s15, s14, 31
	s_lshl_b64 s[16:17], s[14:15], 12
	s_add_u32 s16, s71, s16
	s_addc_u32 s17, s72, s17
	s_mul_i32 s13, s14, 0x410
	s_or_b32 s14, s8, 4
	s_ashr_i32 s15, s14, 31
	s_add_i32 s13, s13, 0
	s_mov_b32 m0, s13
	s_nop 0
	global_load_lds_dwordx4 v167, s[16:17]
	s_lshl_b64 s[16:17], s[14:15], 12
	s_add_u32 s16, s71, s16
	s_mulk_i32 s14, 0x410
	s_addc_u32 s17, s72, s17
	s_add_i32 s14, s14, 0
	s_mov_b32 m0, s14
	s_nop 0
	global_load_lds_dwordx4 v167, s[16:17]
	s_or_b32 s16, s8, 5
	v_readlane_b32 s18, v253, 31
	v_readlane_b32 s19, v253, 32
	s_ashr_i32 s17, s16, 31
	s_lshl_b64 s[18:19], s[16:17], 12
	s_add_u32 s18, s71, s18
	s_addc_u32 s19, s72, s19
	s_mul_i32 s15, s16, 0x410
	s_or_b32 s16, s8, 6
	s_ashr_i32 s17, s16, 31
	s_add_i32 s15, s15, 0
	s_mov_b32 m0, s15
	s_nop 0
	global_load_lds_dwordx4 v167, s[18:19]
	s_lshl_b64 s[18:19], s[16:17], 12
	s_add_u32 s18, s71, s18
	s_mulk_i32 s16, 0x410
	s_addc_u32 s19, s72, s19
	s_add_i32 s16, s16, 0
	s_mov_b32 m0, s16
	s_nop 0
	global_load_lds_dwordx4 v167, s[18:19]
	s_or_b32 s18, s8, 7
	v_readlane_b32 s20, v253, 33
	v_readlane_b32 s21, v253, 34
	s_ashr_i32 s19, s18, 31
	s_lshl_b64 s[20:21], s[18:19], 12
	s_add_u32 s20, s71, s20
	s_addc_u32 s21, s72, s21
	s_mul_i32 s17, s18, 0x410
	s_or_b32 s18, s8, 8
	s_ashr_i32 s19, s18, 31
	s_add_i32 s17, s17, 0
	s_mov_b32 m0, s17
	s_nop 0
	global_load_lds_dwordx4 v167, s[20:21]
	s_lshl_b64 s[20:21], s[18:19], 12
	s_add_u32 s20, s71, s20
	s_mulk_i32 s18, 0x410
	s_addc_u32 s21, s72, s21
	s_add_i32 s18, s18, 0
	s_mov_b32 m0, s18
	s_nop 0
	global_load_lds_dwordx4 v167, s[20:21]
	s_or_b32 s20, s8, 9
	v_readlane_b32 s22, v253, 35
	v_readlane_b32 s23, v253, 36
	s_ashr_i32 s21, s20, 31
	s_lshl_b64 s[22:23], s[20:21], 12
	s_add_u32 s22, s71, s22
	s_addc_u32 s23, s72, s23
	s_mul_i32 s19, s20, 0x410
	s_or_b32 s20, s8, 10
	s_ashr_i32 s21, s20, 31
	s_add_i32 s19, s19, 0
	s_mov_b32 m0, s19
	s_nop 0
	global_load_lds_dwordx4 v167, s[22:23]
	s_lshl_b64 s[22:23], s[20:21], 12
	s_add_u32 s22, s71, s22
	s_mulk_i32 s20, 0x410
	s_addc_u32 s23, s72, s23
	s_add_i32 s20, s20, 0
	s_mov_b32 m0, s20
	s_nop 0
	global_load_lds_dwordx4 v167, s[22:23]
	s_or_b32 s22, s8, 11
	s_ashr_i32 s23, s22, 31
	s_lshl_b64 s[24:25], s[22:23], 12
	s_add_u32 s24, s71, s24
	s_addc_u32 s25, s72, s25
	s_mul_i32 s21, s22, 0x410
	s_or_b32 s22, s8, 12
	s_ashr_i32 s23, s22, 31
	s_add_i32 s21, s21, 0
	s_mov_b32 m0, s21
	s_nop 0
	global_load_lds_dwordx4 v167, s[24:25]
	s_lshl_b64 s[24:25], s[22:23], 12
	s_add_u32 s24, s71, s24
	s_mulk_i32 s22, 0x410
	s_addc_u32 s25, s72, s25
	s_add_i32 s22, s22, 0
	s_mov_b32 m0, s22
	s_nop 0
	global_load_lds_dwordx4 v167, s[24:25]
	s_or_b32 s24, s8, 13
	v_readlane_b32 s26, v253, 39
	v_readlane_b32 s27, v253, 40
	s_ashr_i32 s25, s24, 31
	s_lshl_b64 s[26:27], s[24:25], 12
	s_add_u32 s26, s71, s26
	s_addc_u32 s27, s72, s27
	s_mul_i32 s23, s24, 0x410
	s_or_b32 s24, s8, 14
	s_ashr_i32 s25, s24, 31
	s_add_i32 s23, s23, 0
	s_mov_b32 m0, s23
	s_nop 0
	global_load_lds_dwordx4 v167, s[26:27]
	s_lshl_b64 s[26:27], s[24:25], 12
	s_add_u32 s26, s71, s26
	s_mulk_i32 s24, 0x410
	v_lshlrev_b32_e32 v132, 5, v169
	v_lshlrev_b32_e32 v133, 1, v168
	s_addc_u32 s27, s72, s27
	s_add_i32 s24, s24, 0
	s_mov_b32 m0, s24
	s_nop 0
	global_load_lds_dwordx4 v167, s[26:27]
	s_or_b32 s26, s8, 15
	v_or_b32_e32 v134, v132, v133
	s_ashr_i32 s27, s26, 31
	v_add_u32_e32 v130, 0, v130
	v_lshlrev_b32_e32 v134, 2, v134
	s_lshl_b64 s[76:77], s[26:27], 12
	v_add_u32_e32 v164, v130, v134
	s_add_u32 s76, s71, s76
	s_mul_i32 s25, s26, 0x410
	v_lshlrev_b32_e32 v131, 10, v163
	s_addc_u32 s77, s72, s77
	s_add_i32 s25, s25, 0
	s_mov_b32 m0, s25
	s_nop 0
	global_load_lds_dwordx4 v167, s[76:77]
	v_add_u32_e32 v165, 32, v164
	v_add_u32_e32 v166, 48, v164
	v_or3_b32 v0, v131, v133, v132
	s_waitcnt vmcnt(0)
	s_barrier
	ds_read2st64_b64 v[142:145], v164 offset1:1
	ds_read2_b64 v[138:141], v164 offset0:130 offset1:194
	ds_read2st64_b64 v[134:137], v165 offset0:4 offset1:5
	ds_read2st64_b64 v[130:133], v166 offset0:6 offset1:7
	v_readlane_b32 s26, v254, 60
	v_mov_b32_e32 v156, v122
	v_mov_b32_e32 v157, v126
	v_readlane_b32 s27, v254, 61
	s_waitcnt lgkmcnt(3)
	v_pk_fma_f32 v[158:159], v[154:155], v[156:157], v[142:143]
	v_lshl_add_u64 v[160:161], v[0:1], 2, s[0:1]
	s_and_b64 vcc, exec, s[26:27]
	v_lshl_add_u64 v[156:157], v[0:1], 1, s[2:3]
	global_store_dwordx2 v[160:161], v[158:159], off
	s_cbranch_vccz .LBB0_656
	v_pk_mul_f32 v[142:143], v[148:149], v[158:159]
	s_nop 0
	s_nop 0
	v_and_b32_sdwa v122, v143, v178 dst_sel:DWORD dst_unused:UNUSED_PAD src0_sel:WORD_1 src1_sel:DWORD
	v_cvt_pk_bf16_f32 v126, v142, v142
	v_add3_u32 v122, v143, v122, s81
	v_lshrrev_b32_e32 v126, 16, v126
	v_and_or_b32 v122, v122, s28, v126
	global_store_dword v[156:157], v122, off
; __device__ __forceinline__ unsigned pack2(float a, float b) { return (unsigned)f2bf(a) | ((unsigned)f2bf(b) << 16); }
; template <int EPI, bool HS = false>
; __device__ __forceinline__ void gemm_phase(const Params& p, const GemmCfg& g, char* shm, const int wave_s) {
;     ...
;           for (int j = 0; j < 4; ++j) {
;             float ss = 0.f;
; #pragma unroll
;             for (int bj = 0; bj < 2; ++bj) {
;               float2 xn;
;               xn.x = xv[j][bj].x + gt[bj][0] * acc[ai][bj][m][0][j];
;               xn.y = xv[j][bj].y + gt[bj][1] * acc[ai][bj][m][1][j];
;               const unsigned o = tb + (unsigned)((ai * 128 + m * 16 + j) * 1024 + bj * 128);
;               *(float2*)(xout_t + o) = xn;
;               if (g.has_next) *(unsigned*)(xg_t + o) = pack2(xn.x * gn[bj][0], xn.y * gn[bj][1]);
;               ss += xn.x * xn.x + xn.y * xn.y;
;             }
;             if (g.has_next) {
;               ss = dpp_row_sum16(ss);
;               if (fr == 0) rss_t[(wr * 64 + fq * 4 + ai * 128 + m * 16 + j) * 16] = ss;
;             }
.LBB0_656:
	v_readlane_b32 s36, v252, 0
	s_lshl_b64 s[4:5], s[4:5], 6
	v_readlane_b32 s42, v252, 6
	v_readlane_b32 s43, v252, 7
	s_add_u32 s11, s42, s4
	s_addc_u32 s26, s43, s5
	s_lshl_b32 s4, s10, 2
	s_ashr_i32 s5, s4, 31
	s_lshl_b64 s[4:5], s[4:5], 2
	s_add_u32 s4, s11, s4
	s_addc_u32 s5, s26, s5
	v_lshlrev_b32_e32 v142, 2, v169
	v_mov_b32_e32 v143, v1
	v_lshl_add_u64 v[142:143], s[4:5], 0, v[142:143]
	v_cmp_eq_u32_e64 s[4:5], 0, v168
	v_mov_b32_e32 v168, v114
	v_mov_b32_e32 v169, v118
	v_pk_fma_f32 v[144:145], v[150:151], v[168:169], v[144:145]
	s_and_b64 vcc, exec, s[6:7]
	s_mov_b64 s[10:11], -1
	v_readlane_b32 s37, v252, 1
	v_readlane_b32 s38, v252, 2
	v_readlane_b32 s39, v252, 3
	v_readlane_b32 s40, v252, 4
	v_readlane_b32 s41, v252, 5
	global_store_dwordx2 v[160:161], v[144:145], off offset:512
	s_cbranch_vccnz .LBB0_662
	v_pk_mul_f32 v[160:161], v[152:153], v[144:145]
	v_pk_mul_f32 v[158:159], v[158:159], v[158:159]
	s_nop 0
	v_and_b32_sdwa v114, v161, v178 dst_sel:DWORD dst_unused:UNUSED_PAD src0_sel:WORD_1 src1_sel:DWORD
	v_cvt_pk_bf16_f32 v118, v160, v160
	v_add3_u32 v114, v161, v114, s81
	v_lshrrev_b32_e32 v118, 16, v118
	v_and_or_b32 v114, v114, s28, v118
	v_pk_mul_f32 v[144:145], v[144:145], v[144:145]
	global_store_dword v[156:157], v114, off offset:256
	v_add_f32_e32 v114, v144, v145
	v_add_f32_e32 v118, v158, v159
	v_add_f32_e32 v114, v118, v114
	s_nop 1
	v_add_f32_dpp v114, v114, v114 quad_perm:[1,0,3,2] row_mask:0xf bank_mask:0xf bound_ctrl:1
	s_nop 1
	v_add_f32_dpp v114, v114, v114 quad_perm:[2,3,0,1] row_mask:0xf bank_mask:0xf bound_ctrl:1
	s_nop 1
	v_add_f32_dpp v114, v114, v114 row_half_mirror row_mask:0xf bank_mask:0xf bound_ctrl:1
	s_nop 1
	v_mov_b32_dpp v118, v114 row_mirror row_mask:0xf bank_mask:0xf bound_ctrl:1
	s_and_saveexec_b64 s[10:11], s[4:5]
	s_cbranch_execz .LBB0_659
	v_lshlrev_b32_e32 v144, 4, v163
	v_ashrrev_i32_e32 v145, 31, v144
	v_add_f32_e32 v114, v114, v118
	v_lshl_add_u64 v[144:145], v[144:145], 2, v[142:143]
	global_store_dword v[144:145], v114, off
.LBB0_659:
	s_or_b64 exec, exec, s[10:11]
	v_or_b32_e32 v144, 0x400, v0
	v_mov_b32_e32 v126, v123
	v_mov_b32_e32 v145, v1
	s_waitcnt lgkmcnt(2)
	v_pk_fma_f32 v[158:159], v[154:155], v[126:127], v[138:139]
	v_lshl_add_u64 v[144:145], v[144:145], 2, s[0:1]
	global_store_dwordx2 v[144:145], v[158:159], off
	v_pk_mul_f32 v[144:145], v[148:149], v[158:159]
	v_or_b32_e32 v160, 0x480, v0
	s_nop 0
	v_and_b32_sdwa v114, v145, v178 dst_sel:DWORD dst_unused:UNUSED_PAD src0_sel:WORD_1 src1_sel:DWORD
	v_cvt_pk_bf16_f32 v118, v144, v144
	v_add3_u32 v114, v145, v114, s81
	v_lshrrev_b32_e32 v118, 16, v118
	v_and_or_b32 v114, v114, s28, v118
	v_mov_b32_e32 v118, v115
	v_mov_b32_e32 v161, v1
	v_pk_fma_f32 v[144:145], v[150:151], v[118:119], v[140:141]
	v_lshl_add_u64 v[160:161], v[160:161], 2, s[0:1]
	global_store_dword v[156:157], v114, off offset:2048
	global_store_dwordx2 v[160:161], v[144:145], off
	v_pk_mul_f32 v[160:161], v[152:153], v[144:145]
	v_pk_mul_f32 v[158:159], v[158:159], v[158:159]
	s_nop 0
	v_and_b32_sdwa v114, v161, v178 dst_sel:DWORD dst_unused:UNUSED_PAD src0_sel:WORD_1 src1_sel:DWORD
	v_cvt_pk_bf16_f32 v118, v160, v160
	v_add3_u32 v114, v161, v114, s81
	v_lshrrev_b32_e32 v118, 16, v118
	v_and_or_b32 v114, v114, s28, v118
	v_pk_mul_f32 v[144:145], v[144:145], v[144:145]
	global_store_dword v[156:157], v114, off offset:2304
	v_add_f32_e32 v114, v144, v145
	v_add_f32_e32 v118, v158, v159
	v_add_f32_e32 v114, v118, v114
	s_nop 1
	v_add_f32_dpp v114, v114, v114 quad_perm:[1,0,3,2] row_mask:0xf bank_mask:0xf bound_ctrl:1
	s_nop 1
	v_add_f32_dpp v114, v114, v114 quad_perm:[2,3,0,1] row_mask:0xf bank_mask:0xf bound_ctrl:1
	s_nop 1
	v_add_f32_dpp v114, v114, v114 row_half_mirror row_mask:0xf bank_mask:0xf bound_ctrl:1
	s_nop 1
	v_mov_b32_dpp v118, v114 row_mirror row_mask:0xf bank_mask:0xf bound_ctrl:1
	s_and_saveexec_b64 s[10:11], s[4:5]
	s_cbranch_execz .LBB0_661
	v_lshlrev_b32_e32 v144, 4, v163
	v_ashrrev_i32_e32 v145, 31, v144
	v_add_f32_e32 v114, v114, v118
	v_lshl_add_u64 v[144:145], v[144:145], 2, v[142:143]
	global_store_dword v[144:145], v114, off offset:64

; __device__ __forceinline__ unsigned pack2(float a, float b) { return (unsigned)f2bf(a) | ((unsigned)f2bf(b) << 16); }
; template <int EPI, bool HS = false>
; __device__ __forceinline__ void gemm_phase(const Params& p, const GemmCfg& g, char* shm, const int wave_s) {
;     ...
;               xn.x = xv[j][bj].x + gt[bj][0] * acc[ai][bj][m][0][j];
;               xn.y = xv[j][bj].y + gt[bj][1] * acc[ai][bj][m][1][j];
;               const unsigned o = tb + (unsigned)((ai * 128 + m * 16 + j) * 1024 + bj * 128);
;               *(float2*)(xout_t + o) = xn;
;               if (g.has_next) *(unsigned*)(xg_t + o) = pack2(xn.x * gn[bj][0], xn.y * gn[bj][1]);
;               ss += xn.x * xn.x + xn.y * xn.y;
;             }
;             if (g.has_next) {
;               ss = dpp_row_sum16(ss);
;               if (fr == 0) rss_t[(wr * 64 + fq * 4 + ai * 128 + m * 16 + j) * 16] = ss;
;             }
.LBB0_664:
	v_or_b32_e32 v122, 0x800, v0
	v_mov_b32_e32 v114, v124
	v_mov_b32_e32 v115, v128
	v_mov_b32_e32 v123, v1
	s_waitcnt lgkmcnt(1)
	v_pk_fma_f32 v[118:119], v[154:155], v[114:115], v[134:135]
	v_lshl_add_u64 v[114:115], v[122:123], 2, s[0:1]
	global_store_dwordx2 v[114:115], v[118:119], off
	s_mov_b64 s[10:11], -1
	s_and_b64 vcc, exec, s[6:7]
	v_or_b32_e32 v114, 0x880, v0
	s_mov_b32 s42, 0x800000
	s_cbranch_vccnz .LBB0_668
	v_pk_mul_f32 v[126:127], v[148:149], v[118:119]
	v_lshl_add_u64 v[122:123], v[122:123], 1, s[2:3]
	s_nop 0
	v_and_b32_sdwa v115, v127, v178 dst_sel:DWORD dst_unused:UNUSED_PAD src0_sel:WORD_1 src1_sel:DWORD
	v_cvt_pk_bf16_f32 v124, v126, v126
	v_add3_u32 v115, v127, v115, s81
	v_lshrrev_b32_e32 v124, 16, v124
	v_and_or_b32 v115, v115, s28, v124
	global_store_dword v[122:123], v115, off
	v_mov_b32_e32 v122, v116
	v_mov_b32_e32 v123, v120
	v_mov_b32_e32 v115, v1
	v_pk_fma_f32 v[122:123], v[150:151], v[122:123], v[136:137]
	v_lshl_add_u64 v[126:127], v[114:115], 2, s[0:1]
	global_store_dwordx2 v[126:127], v[122:123], off
	v_pk_mul_f32 v[126:127], v[152:153], v[122:123]
	v_pk_mul_f32 v[118:119], v[118:119], v[118:119]
	v_and_b32_sdwa v128, v126, v178 dst_sel:DWORD dst_unused:UNUSED_PAD src0_sel:WORD_1 src1_sel:DWORD
	v_and_b32_sdwa v124, v127, v178 dst_sel:DWORD dst_unused:UNUSED_PAD src0_sel:WORD_1 src1_sel:DWORD
	v_add3_u32 v126, v126, v128, s81
	v_add3_u32 v124, v127, v124, s81
	v_lshrrev_b32_e32 v126, 16, v126
	v_pk_mul_f32 v[122:123], v[122:123], v[122:123]
	v_and_or_b32 v124, v124, s28, v126
	v_lshl_add_u64 v[126:127], v[114:115], 1, s[2:3]
	v_add_f32_e32 v115, v122, v123
	v_add_f32_e32 v118, v118, v119
	v_add_f32_e32 v115, v118, v115
	global_store_dword v[126:127], v124, off
	s_nop 0
	v_add_f32_dpp v115, v115, v115 quad_perm:[1,0,3,2] row_mask:0xf bank_mask:0xf bound_ctrl:1
	s_nop 1
	v_add_f32_dpp v115, v115, v115 quad_perm:[2,3,0,1] row_mask:0xf bank_mask:0xf bound_ctrl:1
	s_nop 1
	v_add_f32_dpp v115, v115, v115 row_half_mirror row_mask:0xf bank_mask:0xf bound_ctrl:1
	s_nop 1
	v_mov_b32_dpp v118, v115 row_mirror row_mask:0xf bank_mask:0xf bound_ctrl:1
	s_and_saveexec_b64 s[10:11], s[4:5]
	s_cbranch_execz .LBB0_667
	v_add_f32_e32 v115, v115, v118
	v_lshlrev_b32_e32 v118, 4, v163
	v_ashrrev_i32_e32 v119, 31, v118
	v_lshl_add_u64 v[118:119], v[118:119], 2, v[142:143]
	global_store_dword v[118:119], v115, off offset:128

; __device__ __forceinline__ unsigned pack2(float a, float b) { return (unsigned)f2bf(a) | ((unsigned)f2bf(b) << 16); }
; template <int EPI, bool HS = false>
; __device__ __forceinline__ void gemm_phase(const Params& p, const GemmCfg& g, char* shm, const int wave_s) {
;     ...
;               xn.x = xv[j][bj].x + gt[bj][0] * acc[ai][bj][m][0][j];
;               xn.y = xv[j][bj].y + gt[bj][1] * acc[ai][bj][m][1][j];
;               const unsigned o = tb + (unsigned)((ai * 128 + m * 16 + j) * 1024 + bj * 128);
;               *(float2*)(xout_t + o) = xn;
;               if (g.has_next) *(unsigned*)(xg_t + o) = pack2(xn.x * gn[bj][0], xn.y * gn[bj][1]);
;               ss += xn.x * xn.x + xn.y * xn.y;
;             }
;             if (g.has_next) {
;               ss = dpp_row_sum16(ss);
;               if (fr == 0) rss_t[(wr * 64 + fq * 4 + ai * 128 + m * 16 + j) * 16] = ss;
;             }
.LBB0_670:
	v_or_b32_e32 v122, 0xc00, v0
	v_mov_b32_e32 v128, v125
	v_mov_b32_e32 v123, v1
	s_waitcnt lgkmcnt(0)
	v_pk_fma_f32 v[118:119], v[154:155], v[128:129], v[130:131]
	v_lshl_add_u64 v[114:115], v[122:123], 2, s[0:1]
	global_store_dwordx2 v[114:115], v[118:119], off
	s_mov_b64 s[10:11], -1
	s_and_b64 vcc, exec, s[6:7]
	v_or_b32_e32 v114, 0xc80, v0
	s_cbranch_vccnz .LBB0_674
	v_pk_mul_f32 v[124:125], v[148:149], v[118:119]
	v_lshl_add_u64 v[122:123], v[122:123], 1, s[2:3]
	s_nop 0
	v_and_b32_sdwa v115, v125, v178 dst_sel:DWORD dst_unused:UNUSED_PAD src0_sel:WORD_1 src1_sel:DWORD
	v_cvt_pk_bf16_f32 v116, v124, v124
	v_add3_u32 v115, v125, v115, s81
	v_lshrrev_b32_e32 v116, 16, v116
	v_and_or_b32 v115, v115, s28, v116
	global_store_dword v[122:123], v115, off
	v_mov_b32_e32 v120, v117
	v_mov_b32_e32 v115, v1
	v_pk_fma_f32 v[122:123], v[150:151], v[120:121], v[132:133]
	v_lshl_add_u64 v[124:125], v[114:115], 2, s[0:1]
	global_store_dwordx2 v[124:125], v[122:123], off
	v_pk_mul_f32 v[124:125], v[152:153], v[122:123]
	v_pk_mul_f32 v[118:119], v[118:119], v[118:119]
	s_nop 0
	v_and_b32_sdwa v116, v125, v178 dst_sel:DWORD dst_unused:UNUSED_PAD src0_sel:WORD_1 src1_sel:DWORD
	v_cvt_pk_bf16_f32 v120, v124, v124
	v_add3_u32 v116, v125, v116, s81
	v_lshrrev_b32_e32 v120, 16, v120
	v_and_or_b32 v116, v116, s28, v120
	v_lshl_add_u64 v[124:125], v[114:115], 1, s[2:3]
	v_pk_mul_f32 v[122:123], v[122:123], v[122:123]
	global_store_dword v[124:125], v116, off
	v_add_f32_e32 v115, v122, v123
	v_add_f32_e32 v116, v118, v119
	v_add_f32_e32 v115, v116, v115
	s_nop 1
	v_add_f32_dpp v115, v115, v115 quad_perm:[1,0,3,2] row_mask:0xf bank_mask:0xf bound_ctrl:1
	s_nop 1
	v_add_f32_dpp v115, v115, v115 quad_perm:[2,3,0,1] row_mask:0xf bank_mask:0xf bound_ctrl:1
	s_nop 1
	v_add_f32_dpp v115, v115, v115 row_half_mirror row_mask:0xf bank_mask:0xf bound_ctrl:1
	s_nop 1
	v_mov_b32_dpp v116, v115 row_mirror row_mask:0xf bank_mask:0xf bound_ctrl:1
	s_and_saveexec_b64 s[10:11], s[4:5]
	s_cbranch_execz .LBB0_673
	v_lshlrev_b32_e32 v118, 4, v163
	v_ashrrev_i32_e32 v119, 31, v118
	v_add_f32_e32 v115, v115, v116
	v_lshl_add_u64 v[118:119], v[118:119], 2, v[142:143]
	global_store_dword v[118:119], v115, off offset:192

; __device__ __forceinline__ unsigned pack2(float a, float b) { return (unsigned)f2bf(a) | ((unsigned)f2bf(b) << 16); }
; template <int EPI, bool HS = false>
; __device__ __forceinline__ void gemm_phase(const Params& p, const GemmCfg& g, char* shm, const int wave_s) {
;     ...
;         for (int m = 0; m < 4; ++m) {
;           float2 xv[4][2];
; #pragma unroll
;           for (int j = 0; j < 4; ++j)
; #pragma unroll
;             for (int bj = 0; bj < 2; ++bj) xv[j][bj] = *(const float2*)(xl + (m * 16 + j) * XROW + bj * 512);
; #pragma unroll
;           for (int j = 0; j < 4; ++j) {
;             float ss = 0.f;
; #pragma unroll
;             for (int bj = 0; bj < 2; ++bj) {
;               float2 xn;
;               xn.x = xv[j][bj].x + gt[bj][0] * acc[ai][bj][m][0][j];
;               xn.y = xv[j][bj].y + gt[bj][1] * acc[ai][bj][m][1][j];
;               const unsigned o = tb + (unsigned)((ai * 128 + m * 16 + j) * 1024 + bj * 128);
;               *(float2*)(xout_t + o) = xn;
;               if (g.has_next) *(unsigned*)(xg_t + o) = pack2(xn.x * gn[bj][0], xn.y * gn[bj][1]);
;               ss += xn.x * xn.x + xn.y * xn.y;
;             }
;             if (g.has_next) {
;               ss = dpp_row_sum16(ss);
;               if (fr == 0) rss_t[(wr * 64 + fq * 4 + ai * 128 + m * 16 + j) * 16] = ss;
;             }
.LBB0_676:
	v_add_u32_e32 v134, 0x100, v164
	ds_read2st64_b64 v[126:129], v134 offset0:32 offset1:33
	v_add_u32_e32 v135, 0x110, v164
	v_add_u32_e32 v136, 0x120, v164
	v_add_u32_e32 v137, 0x130, v164
	ds_read2st64_b64 v[122:125], v135 offset0:34 offset1:35
	ds_read2st64_b64 v[118:121], v136 offset0:36 offset1:37
	ds_read2st64_b64 v[114:117], v137 offset0:38 offset1:39
	v_or_b32_e32 v132, 0x4000, v0
	v_mov_b32_e32 v130, v106
	v_mov_b32_e32 v131, v110
	v_mov_b32_e32 v133, v1
	s_waitcnt lgkmcnt(3)
	v_pk_fma_f32 v[130:131], v[154:155], v[130:131], v[126:127]
	v_lshl_add_u64 v[126:127], v[132:133], 2, s[0:1]
	global_store_dwordx2 v[126:127], v[130:131], off
	s_mov_b64 s[10:11], -1
	s_and_b64 vcc, exec, s[6:7]
	v_or_b32_e32 v126, 0x4080, v0
	s_cbranch_vccnz .LBB0_680
	v_pk_mul_f32 v[138:139], v[148:149], v[130:131]
	v_lshl_add_u64 v[132:133], v[132:133], 1, s[2:3]
	s_nop 0
	v_and_b32_sdwa v106, v139, v178 dst_sel:DWORD dst_unused:UNUSED_PAD src0_sel:WORD_1 src1_sel:DWORD
	v_cvt_pk_bf16_f32 v110, v138, v138
	v_add3_u32 v106, v139, v106, s81
	v_lshrrev_b32_e32 v110, 16, v110
	v_and_or_b32 v106, v106, s28, v110
	global_store_dword v[132:133], v106, off
	v_mov_b32_e32 v132, v98
	v_mov_b32_e32 v133, v102
	v_mov_b32_e32 v127, v1
	v_pk_fma_f32 v[132:133], v[150:151], v[132:133], v[128:129]
	v_lshl_add_u64 v[138:139], v[126:127], 2, s[0:1]
	global_store_dwordx2 v[138:139], v[132:133], off
	v_pk_mul_f32 v[138:139], v[152:153], v[132:133]
	v_pk_mul_f32 v[130:131], v[130:131], v[130:131]
	s_nop 0
	v_and_b32_sdwa v106, v139, v178 dst_sel:DWORD dst_unused:UNUSED_PAD src0_sel:WORD_1 src1_sel:DWORD
	v_cvt_pk_bf16_f32 v110, v138, v138
	v_add3_u32 v106, v139, v106, s81
	v_lshrrev_b32_e32 v110, 16, v110
	v_and_or_b32 v106, v106, s28, v110
	v_lshl_add_u64 v[138:139], v[126:127], 1, s[2:3]
	v_pk_mul_f32 v[132:133], v[132:133], v[132:133]
	global_store_dword v[138:139], v106, off
	v_add_f32_e32 v106, v132, v133
	v_add_f32_e32 v110, v130, v131
	v_add_f32_e32 v106, v110, v106
	s_nop 1
	v_add_f32_dpp v106, v106, v106 quad_perm:[1,0,3,2] row_mask:0xf bank_mask:0xf bound_ctrl:1
	s_nop 1
	v_add_f32_dpp v106, v106, v106 quad_perm:[2,3,0,1] row_mask:0xf bank_mask:0xf bound_ctrl:1
	s_nop 1
	v_add_f32_dpp v106, v106, v106 row_half_mirror row_mask:0xf bank_mask:0xf bound_ctrl:1
	s_nop 1
	v_mov_b32_dpp v110, v106 row_mirror row_mask:0xf bank_mask:0xf bound_ctrl:1
	s_and_saveexec_b64 s[10:11], s[4:5]
	s_cbranch_execz .LBB0_679
	v_lshlrev_b32_e32 v130, 4, v163
	v_ashrrev_i32_e32 v131, 31, v130
	v_add_f32_e32 v106, v106, v110
	v_lshl_add_u64 v[130:131], v[130:131], 2, v[142:143]
	global_store_dword v[130:131], v106, off offset:1024

; __device__ __forceinline__ unsigned pack2(float a, float b) { return (unsigned)f2bf(a) | ((unsigned)f2bf(b) << 16); }
; template <int EPI, bool HS = false>
; __device__ __forceinline__ void gemm_phase(const Params& p, const GemmCfg& g, char* shm, const int wave_s) {
;     ...
;               xn.x = xv[j][bj].x + gt[bj][0] * acc[ai][bj][m][0][j];
;               xn.y = xv[j][bj].y + gt[bj][1] * acc[ai][bj][m][1][j];
;               const unsigned o = tb + (unsigned)((ai * 128 + m * 16 + j) * 1024 + bj * 128);
;               *(float2*)(xout_t + o) = xn;
;               if (g.has_next) *(unsigned*)(xg_t + o) = pack2(xn.x * gn[bj][0], xn.y * gn[bj][1]);
;               ss += xn.x * xn.x + xn.y * xn.y;
;             }
;             if (g.has_next) {
;               ss = dpp_row_sum16(ss);
;               if (fr == 0) rss_t[(wr * 64 + fq * 4 + ai * 128 + m * 16 + j) * 16] = ss;
;             }
.LBB0_682:
	v_or_b32_e32 v126, 0x4400, v0
	v_mov_b32_e32 v110, v107
	v_mov_b32_e32 v127, v1
	s_waitcnt lgkmcnt(2)
	v_pk_fma_f32 v[110:111], v[154:155], v[110:111], v[122:123]
	v_lshl_add_u64 v[106:107], v[126:127], 2, s[0:1]
	global_store_dwordx2 v[106:107], v[110:111], off
	s_mov_b64 s[10:11], -1
	s_and_b64 vcc, exec, s[6:7]
	v_or_b32_e32 v106, 0x4480, v0
	s_cbranch_vccnz .LBB0_686
	v_pk_mul_f32 v[122:123], v[148:149], v[110:111]
	v_mov_b32_e32 v107, v1
	s_nop 0
	v_and_b32_sdwa v98, v123, v178 dst_sel:DWORD dst_unused:UNUSED_PAD src0_sel:WORD_1 src1_sel:DWORD
	v_cvt_pk_bf16_f32 v102, v122, v122
	v_add3_u32 v98, v123, v98, s81
	v_lshrrev_b32_e32 v102, 16, v102
	v_and_or_b32 v98, v98, s28, v102
	v_lshl_add_u64 v[122:123], v[126:127], 1, s[2:3]
	v_mov_b32_e32 v102, v99
	global_store_dword v[122:123], v98, off
	v_pk_fma_f32 v[122:123], v[150:151], v[102:103], v[124:125]
	v_lshl_add_u64 v[126:127], v[106:107], 2, s[0:1]
	global_store_dwordx2 v[126:127], v[122:123], off
	v_pk_mul_f32 v[126:127], v[152:153], v[122:123]
	v_pk_mul_f32 v[110:111], v[110:111], v[110:111]
	s_nop 0
	v_and_b32_sdwa v98, v127, v178 dst_sel:DWORD dst_unused:UNUSED_PAD src0_sel:WORD_1 src1_sel:DWORD
	v_cvt_pk_bf16_f32 v102, v126, v126
	v_add3_u32 v98, v127, v98, s81
	v_lshrrev_b32_e32 v102, 16, v102
	v_and_or_b32 v98, v98, s28, v102
	v_lshl_add_u64 v[126:127], v[106:107], 1, s[2:3]
	v_pk_mul_f32 v[122:123], v[122:123], v[122:123]
	global_store_dword v[126:127], v98, off
	v_add_f32_e32 v98, v122, v123
	v_add_f32_e32 v102, v110, v111
	v_add_f32_e32 v98, v102, v98
	s_nop 1
	v_add_f32_dpp v98, v98, v98 quad_perm:[1,0,3,2] row_mask:0xf bank_mask:0xf bound_ctrl:1
	s_nop 1
	v_add_f32_dpp v98, v98, v98 quad_perm:[2,3,0,1] row_mask:0xf bank_mask:0xf bound_ctrl:1
	s_nop 1
	v_add_f32_dpp v98, v98, v98 row_half_mirror row_mask:0xf bank_mask:0xf bound_ctrl:1
	s_nop 1
	v_mov_b32_dpp v102, v98 row_mirror row_mask:0xf bank_mask:0xf bound_ctrl:1
	s_and_saveexec_b64 s[10:11], s[4:5]
	s_cbranch_execz .LBB0_685
	v_lshlrev_b32_e32 v110, 4, v163
	v_ashrrev_i32_e32 v111, 31, v110
	v_add_f32_e32 v98, v98, v102
	v_lshl_add_u64 v[110:111], v[110:111], 2, v[142:143]
	global_store_dword v[110:111], v98, off offset:1088

; __device__ __forceinline__ unsigned pack2(float a, float b) { return (unsigned)f2bf(a) | ((unsigned)f2bf(b) << 16); }
; template <int EPI, bool HS = false>
; __device__ __forceinline__ void gemm_phase(const Params& p, const GemmCfg& g, char* shm, const int wave_s) {
;     ...
;               xn.x = xv[j][bj].x + gt[bj][0] * acc[ai][bj][m][0][j];
;               xn.y = xv[j][bj].y + gt[bj][1] * acc[ai][bj][m][1][j];
;               const unsigned o = tb + (unsigned)((ai * 128 + m * 16 + j) * 1024 + bj * 128);
;               *(float2*)(xout_t + o) = xn;
;               if (g.has_next) *(unsigned*)(xg_t + o) = pack2(xn.x * gn[bj][0], xn.y * gn[bj][1]);
;               ss += xn.x * xn.x + xn.y * xn.y;
;             }
;             if (g.has_next) {
;               ss = dpp_row_sum16(ss);
;               if (fr == 0) rss_t[(wr * 64 + fq * 4 + ai * 128 + m * 16 + j) * 16] = ss;
;             }
.LBB0_688:
	v_or_b32_e32 v106, 0x4800, v0
	v_mov_b32_e32 v98, v108
	v_mov_b32_e32 v99, v112
	v_mov_b32_e32 v107, v1
	s_waitcnt lgkmcnt(1)
	v_pk_fma_f32 v[102:103], v[154:155], v[98:99], v[118:119]
	v_lshl_add_u64 v[98:99], v[106:107], 2, s[0:1]
	global_store_dwordx2 v[98:99], v[102:103], off
	s_mov_b64 s[10:11], -1
	s_and_b64 vcc, exec, s[6:7]
	v_or_b32_e32 v98, 0x4880, v0
	s_cbranch_vccnz .LBB0_692
	v_pk_mul_f32 v[110:111], v[148:149], v[102:103]
	v_lshl_add_u64 v[106:107], v[106:107], 1, s[2:3]
	s_nop 0
	v_and_b32_sdwa v99, v111, v178 dst_sel:DWORD dst_unused:UNUSED_PAD src0_sel:WORD_1 src1_sel:DWORD
	v_cvt_pk_bf16_f32 v108, v110, v110
	v_add3_u32 v99, v111, v99, s81
	v_lshrrev_b32_e32 v108, 16, v108
	v_and_or_b32 v99, v99, s28, v108
	global_store_dword v[106:107], v99, off
	v_mov_b32_e32 v106, v100
	v_mov_b32_e32 v107, v104
	v_mov_b32_e32 v99, v1
	v_pk_fma_f32 v[106:107], v[150:151], v[106:107], v[120:121]
	v_lshl_add_u64 v[110:111], v[98:99], 2, s[0:1]
	global_store_dwordx2 v[110:111], v[106:107], off
	v_pk_mul_f32 v[110:111], v[152:153], v[106:107]
	v_pk_mul_f32 v[102:103], v[102:103], v[102:103]
	v_and_b32_sdwa v112, v110, v178 dst_sel:DWORD dst_unused:UNUSED_PAD src0_sel:WORD_1 src1_sel:DWORD
	v_and_b32_sdwa v108, v111, v178 dst_sel:DWORD dst_unused:UNUSED_PAD src0_sel:WORD_1 src1_sel:DWORD
	v_add3_u32 v110, v110, v112, s81
	v_add3_u32 v108, v111, v108, s81
	v_lshrrev_b32_e32 v110, 16, v110
	v_pk_mul_f32 v[106:107], v[106:107], v[106:107]
	v_and_or_b32 v108, v108, s28, v110
	v_lshl_add_u64 v[110:111], v[98:99], 1, s[2:3]
	v_add_f32_e32 v99, v106, v107
	v_add_f32_e32 v102, v102, v103
	v_add_f32_e32 v99, v102, v99
	global_store_dword v[110:111], v108, off
	s_nop 0
	v_add_f32_dpp v99, v99, v99 quad_perm:[1,0,3,2] row_mask:0xf bank_mask:0xf bound_ctrl:1
	s_nop 1
	v_add_f32_dpp v99, v99, v99 quad_perm:[2,3,0,1] row_mask:0xf bank_mask:0xf bound_ctrl:1
	s_nop 1
	v_add_f32_dpp v99, v99, v99 row_half_mirror row_mask:0xf bank_mask:0xf bound_ctrl:1
	s_nop 1
	v_mov_b32_dpp v102, v99 row_mirror row_mask:0xf bank_mask:0xf bound_ctrl:1
	s_and_saveexec_b64 s[10:11], s[4:5]
	s_cbranch_execz .LBB0_691
	v_add_f32_e32 v99, v99, v102
	v_lshlrev_b32_e32 v102, 4, v163
	v_ashrrev_i32_e32 v103, 31, v102
	v_lshl_add_u64 v[102:103], v[102:103], 2, v[142:143]
	global_store_dword v[102:103], v99, off offset:1152

; __device__ __forceinline__ unsigned pack2(float a, float b) { return (unsigned)f2bf(a) | ((unsigned)f2bf(b) << 16); }
; template <int EPI, bool HS = false>
; __device__ __forceinline__ void gemm_phase(const Params& p, const GemmCfg& g, char* shm, const int wave_s) {
;     ...
;               xn.x = xv[j][bj].x + gt[bj][0] * acc[ai][bj][m][0][j];
;               xn.y = xv[j][bj].y + gt[bj][1] * acc[ai][bj][m][1][j];
;               const unsigned o = tb + (unsigned)((ai * 128 + m * 16 + j) * 1024 + bj * 128);
;               *(float2*)(xout_t + o) = xn;
;               if (g.has_next) *(unsigned*)(xg_t + o) = pack2(xn.x * gn[bj][0], xn.y * gn[bj][1]);
;               ss += xn.x * xn.x + xn.y * xn.y;
;             }
;             if (g.has_next) {
;               ss = dpp_row_sum16(ss);
;               if (fr == 0) rss_t[(wr * 64 + fq * 4 + ai * 128 + m * 16 + j) * 16] = ss;
;             }
.LBB0_694:
	v_or_b32_e32 v106, 0x4c00, v0
	v_mov_b32_e32 v112, v109
	v_mov_b32_e32 v107, v1
	s_waitcnt lgkmcnt(0)
	v_pk_fma_f32 v[102:103], v[154:155], v[112:113], v[114:115]
	v_lshl_add_u64 v[98:99], v[106:107], 2, s[0:1]
	global_store_dwordx2 v[98:99], v[102:103], off
	s_mov_b64 s[10:11], -1
	s_and_b64 vcc, exec, s[6:7]
	v_or_b32_e32 v98, 0x4c80, v0
	s_cbranch_vccnz .LBB0_698
	v_pk_mul_f32 v[108:109], v[148:149], v[102:103]
	v_lshl_add_u64 v[106:107], v[106:107], 1, s[2:3]
	s_nop 0
	v_and_b32_sdwa v99, v109, v178 dst_sel:DWORD dst_unused:UNUSED_PAD src0_sel:WORD_1 src1_sel:DWORD
	v_cvt_pk_bf16_f32 v100, v108, v108
	v_add3_u32 v99, v109, v99, s81
	v_lshrrev_b32_e32 v100, 16, v100
	v_and_or_b32 v99, v99, s28, v100
	global_store_dword v[106:107], v99, off
	v_mov_b32_e32 v104, v101
	v_mov_b32_e32 v99, v1
	v_pk_fma_f32 v[106:107], v[150:151], v[104:105], v[116:117]
	v_lshl_add_u64 v[108:109], v[98:99], 2, s[0:1]
	global_store_dwordx2 v[108:109], v[106:107], off
	v_pk_mul_f32 v[108:109], v[152:153], v[106:107]
	v_pk_mul_f32 v[102:103], v[102:103], v[102:103]
	s_nop 0
	v_and_b32_sdwa v100, v109, v178 dst_sel:DWORD dst_unused:UNUSED_PAD src0_sel:WORD_1 src1_sel:DWORD
	v_cvt_pk_bf16_f32 v104, v108, v108
	v_add3_u32 v100, v109, v100, s81
	v_lshrrev_b32_e32 v104, 16, v104
	v_and_or_b32 v100, v100, s28, v104
	v_lshl_add_u64 v[108:109], v[98:99], 1, s[2:3]
	v_pk_mul_f32 v[106:107], v[106:107], v[106:107]
	global_store_dword v[108:109], v100, off
	v_add_f32_e32 v99, v106, v107
	v_add_f32_e32 v100, v102, v103
	v_add_f32_e32 v99, v100, v99
	s_nop 1
	v_add_f32_dpp v99, v99, v99 quad_perm:[1,0,3,2] row_mask:0xf bank_mask:0xf bound_ctrl:1
	s_nop 1
	v_add_f32_dpp v99, v99, v99 quad_perm:[2,3,0,1] row_mask:0xf bank_mask:0xf bound_ctrl:1
	s_nop 1
	v_add_f32_dpp v99, v99, v99 row_half_mirror row_mask:0xf bank_mask:0xf bound_ctrl:1
	s_nop 1
	v_mov_b32_dpp v100, v99 row_mirror row_mask:0xf bank_mask:0xf bound_ctrl:1
	s_and_saveexec_b64 s[10:11], s[4:5]
	s_cbranch_execz .LBB0_697
	v_lshlrev_b32_e32 v102, 4, v163
	v_ashrrev_i32_e32 v103, 31, v102
	v_add_f32_e32 v99, v99, v100
	v_lshl_add_u64 v[102:103], v[102:103], 2, v[142:143]
	global_store_dword v[102:103], v99, off offset:1216

; __device__ __forceinline__ unsigned pack2(float a, float b) { return (unsigned)f2bf(a) | ((unsigned)f2bf(b) << 16); }
; template <int EPI, bool HS = false>
; __device__ __forceinline__ void gemm_phase(const Params& p, const GemmCfg& g, char* shm, const int wave_s) {
;     ...
;         for (int m = 0; m < 4; ++m) {
;           float2 xv[4][2];
; #pragma unroll
;           for (int j = 0; j < 4; ++j)
; #pragma unroll
;             for (int bj = 0; bj < 2; ++bj) xv[j][bj] = *(const float2*)(xl + (m * 16 + j) * XROW + bj * 512);
; #pragma unroll
;           for (int j = 0; j < 4; ++j) {
;             float ss = 0.f;
; #pragma unroll
;             for (int bj = 0; bj < 2; ++bj) {
;               float2 xn;
;               xn.x = xv[j][bj].x + gt[bj][0] * acc[ai][bj][m][0][j];
;               xn.y = xv[j][bj].y + gt[bj][1] * acc[ai][bj][m][1][j];
;               const unsigned o = tb + (unsigned)((ai * 128 + m * 16 + j) * 1024 + bj * 128);
;               *(float2*)(xout_t + o) = xn;
;               if (g.has_next) *(unsigned*)(xg_t + o) = pack2(xn.x * gn[bj][0], xn.y * gn[bj][1]);
;               ss += xn.x * xn.x + xn.y * xn.y;
;             }
;             if (g.has_next) {
;               ss = dpp_row_sum16(ss);
;               if (fr == 0) rss_t[(wr * 64 + fq * 4 + ai * 128 + m * 16 + j) * 16] = ss;
;             }
.LBB0_700:
	ds_read2st64_b64 v[110:113], v164 offset0:65 offset1:66
	v_add_u32_e32 v118, 16, v164
	ds_read2st64_b64 v[106:109], v118 offset0:67 offset1:68
	ds_read2st64_b64 v[102:105], v165 offset0:69 offset1:70
	ds_read2st64_b64 v[98:101], v166 offset0:71 offset1:72
	v_or_b32_e32 v116, 0x8000, v0
	v_mov_b32_e32 v114, v90
	v_mov_b32_e32 v115, v94
	v_mov_b32_e32 v117, v1
	s_waitcnt lgkmcnt(3)
	v_pk_fma_f32 v[114:115], v[154:155], v[114:115], v[110:111]
	v_lshl_add_u64 v[110:111], v[116:117], 2, s[0:1]
	global_store_dwordx2 v[110:111], v[114:115], off
	s_mov_b64 s[10:11], -1
	s_and_b64 vcc, exec, s[6:7]
	v_or_b32_e32 v110, 0x8080, v0
	s_cbranch_vccnz .LBB0_704
	v_pk_mul_f32 v[120:121], v[148:149], v[114:115]
	v_lshl_add_u64 v[116:117], v[116:117], 1, s[2:3]
	s_nop 0
	v_and_b32_sdwa v90, v121, v178 dst_sel:DWORD dst_unused:UNUSED_PAD src0_sel:WORD_1 src1_sel:DWORD
	v_cvt_pk_bf16_f32 v94, v120, v120
	v_add3_u32 v90, v121, v90, s81
	v_lshrrev_b32_e32 v94, 16, v94
	v_and_or_b32 v90, v90, s28, v94
	global_store_dword v[116:117], v90, off
	v_mov_b32_e32 v116, v82
	v_mov_b32_e32 v117, v86
	v_mov_b32_e32 v111, v1
	v_pk_fma_f32 v[116:117], v[150:151], v[116:117], v[112:113]
	v_lshl_add_u64 v[120:121], v[110:111], 2, s[0:1]
	global_store_dwordx2 v[120:121], v[116:117], off
	v_pk_mul_f32 v[120:121], v[152:153], v[116:117]
	v_pk_mul_f32 v[114:115], v[114:115], v[114:115]
	s_nop 0
	v_and_b32_sdwa v90, v121, v178 dst_sel:DWORD dst_unused:UNUSED_PAD src0_sel:WORD_1 src1_sel:DWORD
	v_cvt_pk_bf16_f32 v94, v120, v120
	v_add3_u32 v90, v121, v90, s81
	v_lshrrev_b32_e32 v94, 16, v94
	v_and_or_b32 v90, v90, s28, v94
	v_lshl_add_u64 v[120:121], v[110:111], 1, s[2:3]
	v_pk_mul_f32 v[116:117], v[116:117], v[116:117]
	global_store_dword v[120:121], v90, off
	v_add_f32_e32 v90, v116, v117
	v_add_f32_e32 v94, v114, v115
	v_add_f32_e32 v90, v94, v90
	s_nop 1
	v_add_f32_dpp v90, v90, v90 quad_perm:[1,0,3,2] row_mask:0xf bank_mask:0xf bound_ctrl:1
	s_nop 1
	v_add_f32_dpp v90, v90, v90 quad_perm:[2,3,0,1] row_mask:0xf bank_mask:0xf bound_ctrl:1
	s_nop 1
	v_add_f32_dpp v90, v90, v90 row_half_mirror row_mask:0xf bank_mask:0xf bound_ctrl:1
	s_nop 1
	v_mov_b32_dpp v94, v90 row_mirror row_mask:0xf bank_mask:0xf bound_ctrl:1
	s_and_saveexec_b64 s[10:11], s[4:5]
	s_cbranch_execz .LBB0_703
	v_lshlrev_b32_e32 v114, 4, v163
	v_ashrrev_i32_e32 v115, 31, v114
	v_add_f32_e32 v90, v90, v94
	v_lshl_add_u64 v[114:115], v[114:115], 2, v[142:143]
	global_store_dword v[114:115], v90, off offset:2048

; __device__ __forceinline__ unsigned pack2(float a, float b) { return (unsigned)f2bf(a) | ((unsigned)f2bf(b) << 16); }
; template <int EPI, bool HS = false>
; __device__ __forceinline__ void gemm_phase(const Params& p, const GemmCfg& g, char* shm, const int wave_s) {
;     ...
;               xn.x = xv[j][bj].x + gt[bj][0] * acc[ai][bj][m][0][j];
;               xn.y = xv[j][bj].y + gt[bj][1] * acc[ai][bj][m][1][j];
;               const unsigned o = tb + (unsigned)((ai * 128 + m * 16 + j) * 1024 + bj * 128);
;               *(float2*)(xout_t + o) = xn;
;               if (g.has_next) *(unsigned*)(xg_t + o) = pack2(xn.x * gn[bj][0], xn.y * gn[bj][1]);
;               ss += xn.x * xn.x + xn.y * xn.y;
;             }
;             if (g.has_next) {
;               ss = dpp_row_sum16(ss);
;               if (fr == 0) rss_t[(wr * 64 + fq * 4 + ai * 128 + m * 16 + j) * 16] = ss;
;             }
.LBB0_706:
	v_or_b32_e32 v110, 0x8400, v0
	v_mov_b32_e32 v94, v91
	v_mov_b32_e32 v111, v1
	s_waitcnt lgkmcnt(2)
	v_pk_fma_f32 v[94:95], v[154:155], v[94:95], v[106:107]
	v_lshl_add_u64 v[90:91], v[110:111], 2, s[0:1]
	global_store_dwordx2 v[90:91], v[94:95], off
	s_mov_b64 s[10:11], -1
	s_and_b64 vcc, exec, s[6:7]
	v_or_b32_e32 v90, 0x8480, v0
	s_cbranch_vccnz .LBB0_710
	v_pk_mul_f32 v[106:107], v[148:149], v[94:95]
	v_mov_b32_e32 v91, v1
	s_nop 0
	v_and_b32_sdwa v82, v107, v178 dst_sel:DWORD dst_unused:UNUSED_PAD src0_sel:WORD_1 src1_sel:DWORD
	v_cvt_pk_bf16_f32 v86, v106, v106
	v_add3_u32 v82, v107, v82, s81
	v_lshrrev_b32_e32 v86, 16, v86
	v_and_or_b32 v82, v82, s28, v86
	v_lshl_add_u64 v[106:107], v[110:111], 1, s[2:3]
	v_mov_b32_e32 v86, v83
	global_store_dword v[106:107], v82, off
	v_pk_fma_f32 v[106:107], v[150:151], v[86:87], v[108:109]
	v_lshl_add_u64 v[110:111], v[90:91], 2, s[0:1]
	global_store_dwordx2 v[110:111], v[106:107], off
	v_pk_mul_f32 v[110:111], v[152:153], v[106:107]
	v_pk_mul_f32 v[94:95], v[94:95], v[94:95]
	s_nop 0
	v_and_b32_sdwa v82, v111, v178 dst_sel:DWORD dst_unused:UNUSED_PAD src0_sel:WORD_1 src1_sel:DWORD
	v_cvt_pk_bf16_f32 v86, v110, v110
	v_add3_u32 v82, v111, v82, s81
	v_lshrrev_b32_e32 v86, 16, v86
	v_and_or_b32 v82, v82, s28, v86
	v_lshl_add_u64 v[110:111], v[90:91], 1, s[2:3]
	v_pk_mul_f32 v[106:107], v[106:107], v[106:107]
	global_store_dword v[110:111], v82, off
	v_add_f32_e32 v82, v106, v107
	v_add_f32_e32 v86, v94, v95
	v_add_f32_e32 v82, v86, v82
	s_nop 1
	v_add_f32_dpp v82, v82, v82 quad_perm:[1,0,3,2] row_mask:0xf bank_mask:0xf bound_ctrl:1
	s_nop 1
	v_add_f32_dpp v82, v82, v82 quad_perm:[2,3,0,1] row_mask:0xf bank_mask:0xf bound_ctrl:1
	s_nop 1
	v_add_f32_dpp v82, v82, v82 row_half_mirror row_mask:0xf bank_mask:0xf bound_ctrl:1
	s_nop 1
	v_mov_b32_dpp v86, v82 row_mirror row_mask:0xf bank_mask:0xf bound_ctrl:1
	s_and_saveexec_b64 s[10:11], s[4:5]
	s_cbranch_execz .LBB0_709
	v_lshlrev_b32_e32 v94, 4, v163
	v_ashrrev_i32_e32 v95, 31, v94
	v_add_f32_e32 v82, v82, v86
	v_lshl_add_u64 v[94:95], v[94:95], 2, v[142:143]
	global_store_dword v[94:95], v82, off offset:2112

; __device__ __forceinline__ unsigned pack2(float a, float b) { return (unsigned)f2bf(a) | ((unsigned)f2bf(b) << 16); }
; template <int EPI, bool HS = false>
; __device__ __forceinline__ void gemm_phase(const Params& p, const GemmCfg& g, char* shm, const int wave_s) {
;     ...
;               xn.x = xv[j][bj].x + gt[bj][0] * acc[ai][bj][m][0][j];
;               xn.y = xv[j][bj].y + gt[bj][1] * acc[ai][bj][m][1][j];
;               const unsigned o = tb + (unsigned)((ai * 128 + m * 16 + j) * 1024 + bj * 128);
;               *(float2*)(xout_t + o) = xn;
;               if (g.has_next) *(unsigned*)(xg_t + o) = pack2(xn.x * gn[bj][0], xn.y * gn[bj][1]);
;               ss += xn.x * xn.x + xn.y * xn.y;
;             }
;             if (g.has_next) {
;               ss = dpp_row_sum16(ss);
;               if (fr == 0) rss_t[(wr * 64 + fq * 4 + ai * 128 + m * 16 + j) * 16] = ss;
;             }
.LBB0_712:
	v_or_b32_e32 v90, 0x8800, v0
	v_mov_b32_e32 v82, v92
	v_mov_b32_e32 v83, v96
	v_mov_b32_e32 v91, v1
	s_waitcnt lgkmcnt(1)
	v_pk_fma_f32 v[86:87], v[154:155], v[82:83], v[102:103]
	v_lshl_add_u64 v[82:83], v[90:91], 2, s[0:1]
	global_store_dwordx2 v[82:83], v[86:87], off
	s_mov_b64 s[10:11], -1
	s_and_b64 vcc, exec, s[6:7]
	v_or_b32_e32 v82, 0x8880, v0
	s_cbranch_vccnz .LBB0_716
	v_pk_mul_f32 v[94:95], v[148:149], v[86:87]
	v_lshl_add_u64 v[90:91], v[90:91], 1, s[2:3]
	s_nop 0
	v_and_b32_sdwa v83, v95, v178 dst_sel:DWORD dst_unused:UNUSED_PAD src0_sel:WORD_1 src1_sel:DWORD
	v_cvt_pk_bf16_f32 v92, v94, v94
	v_add3_u32 v83, v95, v83, s81
	v_lshrrev_b32_e32 v92, 16, v92
	v_and_or_b32 v83, v83, s28, v92
	global_store_dword v[90:91], v83, off
	v_mov_b32_e32 v90, v84
	v_mov_b32_e32 v91, v88
	v_mov_b32_e32 v83, v1
	v_pk_fma_f32 v[90:91], v[150:151], v[90:91], v[104:105]
	v_lshl_add_u64 v[94:95], v[82:83], 2, s[0:1]
	global_store_dwordx2 v[94:95], v[90:91], off
	v_pk_mul_f32 v[94:95], v[152:153], v[90:91]
	v_pk_mul_f32 v[86:87], v[86:87], v[86:87]
	v_and_b32_sdwa v96, v94, v178 dst_sel:DWORD dst_unused:UNUSED_PAD src0_sel:WORD_1 src1_sel:DWORD
	v_and_b32_sdwa v92, v95, v178 dst_sel:DWORD dst_unused:UNUSED_PAD src0_sel:WORD_1 src1_sel:DWORD
	v_add3_u32 v94, v94, v96, s81
	v_add3_u32 v92, v95, v92, s81
	v_lshrrev_b32_e32 v94, 16, v94
	v_pk_mul_f32 v[90:91], v[90:91], v[90:91]
	v_and_or_b32 v92, v92, s28, v94
	v_lshl_add_u64 v[94:95], v[82:83], 1, s[2:3]
	v_add_f32_e32 v83, v90, v91
	v_add_f32_e32 v86, v86, v87
	v_add_f32_e32 v83, v86, v83
	global_store_dword v[94:95], v92, off
	s_nop 0
	v_add_f32_dpp v83, v83, v83 quad_perm:[1,0,3,2] row_mask:0xf bank_mask:0xf bound_ctrl:1
	s_nop 1
	v_add_f32_dpp v83, v83, v83 quad_perm:[2,3,0,1] row_mask:0xf bank_mask:0xf bound_ctrl:1
	s_nop 1
	v_add_f32_dpp v83, v83, v83 row_half_mirror row_mask:0xf bank_mask:0xf bound_ctrl:1
	s_nop 1
	v_mov_b32_dpp v86, v83 row_mirror row_mask:0xf bank_mask:0xf bound_ctrl:1
	s_and_saveexec_b64 s[10:11], s[4:5]
	s_cbranch_execz .LBB0_715
	v_add_f32_e32 v83, v83, v86
	v_lshlrev_b32_e32 v86, 4, v163
	v_ashrrev_i32_e32 v87, 31, v86
	v_lshl_add_u64 v[86:87], v[86:87], 2, v[142:143]
	global_store_dword v[86:87], v83, off offset:2176

; __device__ __forceinline__ unsigned pack2(float a, float b) { return (unsigned)f2bf(a) | ((unsigned)f2bf(b) << 16); }
; template <int EPI, bool HS = false>
; __device__ __forceinline__ void gemm_phase(const Params& p, const GemmCfg& g, char* shm, const int wave_s) {
;     ...
;               xn.x = xv[j][bj].x + gt[bj][0] * acc[ai][bj][m][0][j];
;               xn.y = xv[j][bj].y + gt[bj][1] * acc[ai][bj][m][1][j];
;               const unsigned o = tb + (unsigned)((ai * 128 + m * 16 + j) * 1024 + bj * 128);
;               *(float2*)(xout_t + o) = xn;
;               if (g.has_next) *(unsigned*)(xg_t + o) = pack2(xn.x * gn[bj][0], xn.y * gn[bj][1]);
;               ss += xn.x * xn.x + xn.y * xn.y;
;             }
;             if (g.has_next) {
;               ss = dpp_row_sum16(ss);
;               if (fr == 0) rss_t[(wr * 64 + fq * 4 + ai * 128 + m * 16 + j) * 16] = ss;
;             }
.LBB0_718:
	v_or_b32_e32 v90, 0x8c00, v0
	v_mov_b32_e32 v96, v93
	v_mov_b32_e32 v91, v1
	s_waitcnt lgkmcnt(0)
	v_pk_fma_f32 v[86:87], v[154:155], v[96:97], v[98:99]
	v_lshl_add_u64 v[82:83], v[90:91], 2, s[0:1]
	global_store_dwordx2 v[82:83], v[86:87], off
	s_mov_b64 s[10:11], -1
	s_and_b64 vcc, exec, s[6:7]
	v_or_b32_e32 v82, 0x8c80, v0
	s_cbranch_vccnz .LBB0_722
	v_pk_mul_f32 v[92:93], v[148:149], v[86:87]
	v_lshl_add_u64 v[90:91], v[90:91], 1, s[2:3]
	s_nop 0
	v_and_b32_sdwa v83, v93, v178 dst_sel:DWORD dst_unused:UNUSED_PAD src0_sel:WORD_1 src1_sel:DWORD
	v_cvt_pk_bf16_f32 v84, v92, v92
	v_add3_u32 v83, v93, v83, s81
	v_lshrrev_b32_e32 v84, 16, v84
	v_and_or_b32 v83, v83, s28, v84
	global_store_dword v[90:91], v83, off
	v_mov_b32_e32 v88, v85
	v_mov_b32_e32 v83, v1
	v_pk_fma_f32 v[90:91], v[150:151], v[88:89], v[100:101]
	v_lshl_add_u64 v[92:93], v[82:83], 2, s[0:1]
	global_store_dwordx2 v[92:93], v[90:91], off
	v_pk_mul_f32 v[92:93], v[152:153], v[90:91]
	v_pk_mul_f32 v[86:87], v[86:87], v[86:87]
	s_nop 0
	v_and_b32_sdwa v84, v93, v178 dst_sel:DWORD dst_unused:UNUSED_PAD src0_sel:WORD_1 src1_sel:DWORD
	v_cvt_pk_bf16_f32 v88, v92, v92
	v_add3_u32 v84, v93, v84, s81
	v_lshrrev_b32_e32 v88, 16, v88
	v_and_or_b32 v84, v84, s28, v88
	v_lshl_add_u64 v[92:93], v[82:83], 1, s[2:3]
	v_pk_mul_f32 v[90:91], v[90:91], v[90:91]
	global_store_dword v[92:93], v84, off
	v_add_f32_e32 v83, v90, v91
	v_add_f32_e32 v84, v86, v87
	v_add_f32_e32 v83, v84, v83
	s_nop 1
	v_add_f32_dpp v83, v83, v83 quad_perm:[1,0,3,2] row_mask:0xf bank_mask:0xf bound_ctrl:1
	s_nop 1
	v_add_f32_dpp v83, v83, v83 quad_perm:[2,3,0,1] row_mask:0xf bank_mask:0xf bound_ctrl:1
	s_nop 1
	v_add_f32_dpp v83, v83, v83 row_half_mirror row_mask:0xf bank_mask:0xf bound_ctrl:1
	s_nop 1
	v_mov_b32_dpp v84, v83 row_mirror row_mask:0xf bank_mask:0xf bound_ctrl:1
	s_and_saveexec_b64 s[10:11], s[4:5]
	s_cbranch_execz .LBB0_721
	v_lshlrev_b32_e32 v86, 4, v163
	v_ashrrev_i32_e32 v87, 31, v86
	v_add_f32_e32 v83, v83, v84
	v_lshl_add_u64 v[86:87], v[86:87], 2, v[142:143]
	global_store_dword v[86:87], v83, off offset:2240

; __device__ __forceinline__ unsigned pack2(float a, float b) { return (unsigned)f2bf(a) | ((unsigned)f2bf(b) << 16); }
; template <int EPI, bool HS = false>
; __device__ __forceinline__ void gemm_phase(const Params& p, const GemmCfg& g, char* shm, const int wave_s) {
;     ...
;         for (int m = 0; m < 4; ++m) {
;           float2 xv[4][2];
; #pragma unroll
;           for (int j = 0; j < 4; ++j)
; #pragma unroll
;             for (int bj = 0; bj < 2; ++bj) xv[j][bj] = *(const float2*)(xl + (m * 16 + j) * XROW + bj * 512);
; #pragma unroll
;           for (int j = 0; j < 4; ++j) {
;             float ss = 0.f;
; #pragma unroll
;             for (int bj = 0; bj < 2; ++bj) {
;               float2 xn;
;               xn.x = xv[j][bj].x + gt[bj][0] * acc[ai][bj][m][0][j];
;               xn.y = xv[j][bj].y + gt[bj][1] * acc[ai][bj][m][1][j];
;               const unsigned o = tb + (unsigned)((ai * 128 + m * 16 + j) * 1024 + bj * 128);
;               *(float2*)(xout_t + o) = xn;
;               if (g.has_next) *(unsigned*)(xg_t + o) = pack2(xn.x * gn[bj][0], xn.y * gn[bj][1]);
;               ss += xn.x * xn.x + xn.y * xn.y;
;             }
;             if (g.has_next) {
;               ss = dpp_row_sum16(ss);
;               if (fr == 0) rss_t[(wr * 64 + fq * 4 + ai * 128 + m * 16 + j) * 16] = ss;
;             }
.LBB0_724:
	ds_read2st64_b64 v[94:97], v134 offset0:97 offset1:98
	ds_read2st64_b64 v[90:93], v135 offset0:99 offset1:100
	ds_read2st64_b64 v[86:89], v136 offset0:101 offset1:102
	ds_read2st64_b64 v[82:85], v137 offset0:103 offset1:104
	v_or_b32_e32 v100, 0xc000, v0
	v_mov_b32_e32 v98, v74
	v_mov_b32_e32 v99, v78
	v_mov_b32_e32 v101, v1
	s_waitcnt lgkmcnt(3)
	v_pk_fma_f32 v[98:99], v[154:155], v[98:99], v[94:95]
	v_lshl_add_u64 v[94:95], v[100:101], 2, s[0:1]
	global_store_dwordx2 v[94:95], v[98:99], off
	s_mov_b64 s[10:11], -1
	s_and_b64 vcc, exec, s[6:7]
	v_or_b32_e32 v94, 0xc080, v0
	s_cbranch_vccnz .LBB0_728
	v_pk_mul_f32 v[102:103], v[148:149], v[98:99]
	v_lshl_add_u64 v[100:101], v[100:101], 1, s[2:3]
	s_nop 0
	v_and_b32_sdwa v74, v103, v178 dst_sel:DWORD dst_unused:UNUSED_PAD src0_sel:WORD_1 src1_sel:DWORD
	v_cvt_pk_bf16_f32 v78, v102, v102
	v_add3_u32 v74, v103, v74, s81
	v_lshrrev_b32_e32 v78, 16, v78
	v_and_or_b32 v74, v74, s28, v78
	global_store_dword v[100:101], v74, off
	v_mov_b32_e32 v100, v66
	v_mov_b32_e32 v101, v70
	v_mov_b32_e32 v95, v1
	v_pk_fma_f32 v[100:101], v[150:151], v[100:101], v[96:97]
	v_lshl_add_u64 v[102:103], v[94:95], 2, s[0:1]
	global_store_dwordx2 v[102:103], v[100:101], off
	v_pk_mul_f32 v[102:103], v[152:153], v[100:101]
	v_pk_mul_f32 v[98:99], v[98:99], v[98:99]
	s_nop 0
	v_and_b32_sdwa v74, v103, v178 dst_sel:DWORD dst_unused:UNUSED_PAD src0_sel:WORD_1 src1_sel:DWORD
	v_cvt_pk_bf16_f32 v78, v102, v102
	v_add3_u32 v74, v103, v74, s81
	v_lshrrev_b32_e32 v78, 16, v78
	v_and_or_b32 v74, v74, s28, v78
	v_lshl_add_u64 v[102:103], v[94:95], 1, s[2:3]
	v_pk_mul_f32 v[100:101], v[100:101], v[100:101]
	global_store_dword v[102:103], v74, off
	v_add_f32_e32 v74, v100, v101
	v_add_f32_e32 v78, v98, v99
	v_add_f32_e32 v74, v78, v74
	s_nop 1
	v_add_f32_dpp v74, v74, v74 quad_perm:[1,0,3,2] row_mask:0xf bank_mask:0xf bound_ctrl:1
	s_nop 1
	v_add_f32_dpp v74, v74, v74 quad_perm:[2,3,0,1] row_mask:0xf bank_mask:0xf bound_ctrl:1
	s_nop 1
	v_add_f32_dpp v74, v74, v74 row_half_mirror row_mask:0xf bank_mask:0xf bound_ctrl:1
	s_nop 1
	v_mov_b32_dpp v78, v74 row_mirror row_mask:0xf bank_mask:0xf bound_ctrl:1
	s_and_saveexec_b64 s[10:11], s[4:5]
	s_cbranch_execz .LBB0_727
	v_lshlrev_b32_e32 v98, 4, v163
	v_ashrrev_i32_e32 v99, 31, v98
	v_add_f32_e32 v74, v74, v78
	v_lshl_add_u64 v[98:99], v[98:99], 2, v[142:143]
	global_store_dword v[98:99], v74, off offset:3072

; __device__ __forceinline__ unsigned pack2(float a, float b) { return (unsigned)f2bf(a) | ((unsigned)f2bf(b) << 16); }
; template <int EPI, bool HS = false>
; __device__ __forceinline__ void gemm_phase(const Params& p, const GemmCfg& g, char* shm, const int wave_s) {
;     ...
;               xn.x = xv[j][bj].x + gt[bj][0] * acc[ai][bj][m][0][j];
;               xn.y = xv[j][bj].y + gt[bj][1] * acc[ai][bj][m][1][j];
;               const unsigned o = tb + (unsigned)((ai * 128 + m * 16 + j) * 1024 + bj * 128);
;               *(float2*)(xout_t + o) = xn;
;               if (g.has_next) *(unsigned*)(xg_t + o) = pack2(xn.x * gn[bj][0], xn.y * gn[bj][1]);
;               ss += xn.x * xn.x + xn.y * xn.y;
;             }
;             if (g.has_next) {
;               ss = dpp_row_sum16(ss);
;               if (fr == 0) rss_t[(wr * 64 + fq * 4 + ai * 128 + m * 16 + j) * 16] = ss;
;             }
.LBB0_730:
	v_or_b32_e32 v94, 0xc400, v0
	v_mov_b32_e32 v78, v75
	v_mov_b32_e32 v95, v1
	s_waitcnt lgkmcnt(2)
	v_pk_fma_f32 v[78:79], v[154:155], v[78:79], v[90:91]
	v_lshl_add_u64 v[74:75], v[94:95], 2, s[0:1]
	global_store_dwordx2 v[74:75], v[78:79], off
	s_mov_b64 s[10:11], -1
	s_and_b64 vcc, exec, s[6:7]
	v_or_b32_e32 v74, 0xc480, v0
	s_cbranch_vccnz .LBB0_734
	v_pk_mul_f32 v[90:91], v[148:149], v[78:79]
	v_mov_b32_e32 v75, v1
	s_nop 0
	v_and_b32_sdwa v66, v91, v178 dst_sel:DWORD dst_unused:UNUSED_PAD src0_sel:WORD_1 src1_sel:DWORD
	v_cvt_pk_bf16_f32 v70, v90, v90
	v_add3_u32 v66, v91, v66, s81
	v_lshrrev_b32_e32 v70, 16, v70
	v_and_or_b32 v66, v66, s28, v70
	v_lshl_add_u64 v[90:91], v[94:95], 1, s[2:3]
	v_mov_b32_e32 v70, v67
	global_store_dword v[90:91], v66, off
	v_pk_fma_f32 v[90:91], v[150:151], v[70:71], v[92:93]
	v_lshl_add_u64 v[94:95], v[74:75], 2, s[0:1]
	global_store_dwordx2 v[94:95], v[90:91], off
	v_pk_mul_f32 v[94:95], v[152:153], v[90:91]
	v_pk_mul_f32 v[78:79], v[78:79], v[78:79]
	s_nop 0
	v_and_b32_sdwa v66, v95, v178 dst_sel:DWORD dst_unused:UNUSED_PAD src0_sel:WORD_1 src1_sel:DWORD
	v_cvt_pk_bf16_f32 v70, v94, v94
	v_add3_u32 v66, v95, v66, s81
	v_lshrrev_b32_e32 v70, 16, v70
	v_and_or_b32 v66, v66, s28, v70
	v_lshl_add_u64 v[94:95], v[74:75], 1, s[2:3]
	v_pk_mul_f32 v[90:91], v[90:91], v[90:91]
	global_store_dword v[94:95], v66, off
	v_add_f32_e32 v66, v90, v91
	v_add_f32_e32 v70, v78, v79
	v_add_f32_e32 v66, v70, v66
	s_nop 1
	v_add_f32_dpp v66, v66, v66 quad_perm:[1,0,3,2] row_mask:0xf bank_mask:0xf bound_ctrl:1
	s_nop 1
	v_add_f32_dpp v66, v66, v66 quad_perm:[2,3,0,1] row_mask:0xf bank_mask:0xf bound_ctrl:1
	s_nop 1
	v_add_f32_dpp v66, v66, v66 row_half_mirror row_mask:0xf bank_mask:0xf bound_ctrl:1
	s_nop 1
	v_mov_b32_dpp v70, v66 row_mirror row_mask:0xf bank_mask:0xf bound_ctrl:1
	s_and_saveexec_b64 s[10:11], s[4:5]
	s_cbranch_execz .LBB0_733
	v_lshlrev_b32_e32 v78, 4, v163
	v_ashrrev_i32_e32 v79, 31, v78
	v_add_f32_e32 v66, v66, v70
	v_lshl_add_u64 v[78:79], v[78:79], 2, v[142:143]
	global_store_dword v[78:79], v66, off offset:3136

; __device__ __forceinline__ unsigned pack2(float a, float b) { return (unsigned)f2bf(a) | ((unsigned)f2bf(b) << 16); }
; template <int EPI, bool HS = false>
; __device__ __forceinline__ void gemm_phase(const Params& p, const GemmCfg& g, char* shm, const int wave_s) {
;     ...
;               xn.x = xv[j][bj].x + gt[bj][0] * acc[ai][bj][m][0][j];
;               xn.y = xv[j][bj].y + gt[bj][1] * acc[ai][bj][m][1][j];
;               const unsigned o = tb + (unsigned)((ai * 128 + m * 16 + j) * 1024 + bj * 128);
;               *(float2*)(xout_t + o) = xn;
;               if (g.has_next) *(unsigned*)(xg_t + o) = pack2(xn.x * gn[bj][0], xn.y * gn[bj][1]);
;               ss += xn.x * xn.x + xn.y * xn.y;
;             }
;             if (g.has_next) {
;               ss = dpp_row_sum16(ss);
;               if (fr == 0) rss_t[(wr * 64 + fq * 4 + ai * 128 + m * 16 + j) * 16] = ss;
;             }
.LBB0_736:
	v_or_b32_e32 v74, 0xc800, v0
	v_mov_b32_e32 v66, v76
	v_mov_b32_e32 v67, v80
	v_mov_b32_e32 v75, v1
	s_waitcnt lgkmcnt(1)
	v_pk_fma_f32 v[70:71], v[154:155], v[66:67], v[86:87]
	v_lshl_add_u64 v[66:67], v[74:75], 2, s[0:1]
	global_store_dwordx2 v[66:67], v[70:71], off
	s_mov_b64 s[10:11], -1
	s_and_b64 vcc, exec, s[6:7]
	v_or_b32_e32 v66, 0xc880, v0
	s_cbranch_vccnz .LBB0_740
	v_pk_mul_f32 v[78:79], v[148:149], v[70:71]
	v_lshl_add_u64 v[74:75], v[74:75], 1, s[2:3]
	s_nop 0
	v_and_b32_sdwa v67, v79, v178 dst_sel:DWORD dst_unused:UNUSED_PAD src0_sel:WORD_1 src1_sel:DWORD
	v_cvt_pk_bf16_f32 v76, v78, v78
	v_add3_u32 v67, v79, v67, s81
	v_lshrrev_b32_e32 v76, 16, v76
	v_and_or_b32 v67, v67, s28, v76
	global_store_dword v[74:75], v67, off
	v_mov_b32_e32 v74, v68
	v_mov_b32_e32 v75, v72
	v_mov_b32_e32 v67, v1
	v_pk_fma_f32 v[74:75], v[150:151], v[74:75], v[88:89]
	v_lshl_add_u64 v[78:79], v[66:67], 2, s[0:1]
	global_store_dwordx2 v[78:79], v[74:75], off
	v_pk_mul_f32 v[78:79], v[152:153], v[74:75]
	v_pk_mul_f32 v[70:71], v[70:71], v[70:71]
	v_and_b32_sdwa v80, v78, v178 dst_sel:DWORD dst_unused:UNUSED_PAD src0_sel:WORD_1 src1_sel:DWORD
	v_and_b32_sdwa v76, v79, v178 dst_sel:DWORD dst_unused:UNUSED_PAD src0_sel:WORD_1 src1_sel:DWORD
	v_add3_u32 v78, v78, v80, s81
	v_add3_u32 v76, v79, v76, s81
	v_lshrrev_b32_e32 v78, 16, v78
	v_pk_mul_f32 v[74:75], v[74:75], v[74:75]
	v_and_or_b32 v76, v76, s28, v78
	v_lshl_add_u64 v[78:79], v[66:67], 1, s[2:3]
	v_add_f32_e32 v67, v74, v75
	v_add_f32_e32 v70, v70, v71
	v_add_f32_e32 v67, v70, v67
	global_store_dword v[78:79], v76, off
	s_nop 0
	v_add_f32_dpp v67, v67, v67 quad_perm:[1,0,3,2] row_mask:0xf bank_mask:0xf bound_ctrl:1
	s_nop 1
	v_add_f32_dpp v67, v67, v67 quad_perm:[2,3,0,1] row_mask:0xf bank_mask:0xf bound_ctrl:1
	s_nop 1
	v_add_f32_dpp v67, v67, v67 row_half_mirror row_mask:0xf bank_mask:0xf bound_ctrl:1
	s_nop 1
	v_mov_b32_dpp v70, v67 row_mirror row_mask:0xf bank_mask:0xf bound_ctrl:1
	s_and_saveexec_b64 s[10:11], s[4:5]
	s_cbranch_execz .LBB0_739
	v_add_f32_e32 v67, v67, v70
	v_lshlrev_b32_e32 v70, 4, v163
	v_ashrrev_i32_e32 v71, 31, v70
	v_lshl_add_u64 v[70:71], v[70:71], 2, v[142:143]
	global_store_dword v[70:71], v67, off offset:3200

; __device__ __forceinline__ unsigned pack2(float a, float b) { return (unsigned)f2bf(a) | ((unsigned)f2bf(b) << 16); }
; template <int EPI, bool HS = false>
; __device__ __forceinline__ void gemm_phase(const Params& p, const GemmCfg& g, char* shm, const int wave_s) {
;     ...
;               xn.x = xv[j][bj].x + gt[bj][0] * acc[ai][bj][m][0][j];
;               xn.y = xv[j][bj].y + gt[bj][1] * acc[ai][bj][m][1][j];
;               const unsigned o = tb + (unsigned)((ai * 128 + m * 16 + j) * 1024 + bj * 128);
;               *(float2*)(xout_t + o) = xn;
;               if (g.has_next) *(unsigned*)(xg_t + o) = pack2(xn.x * gn[bj][0], xn.y * gn[bj][1]);
;               ss += xn.x * xn.x + xn.y * xn.y;
;             }
;             if (g.has_next) {
;               ss = dpp_row_sum16(ss);
;               if (fr == 0) rss_t[(wr * 64 + fq * 4 + ai * 128 + m * 16 + j) * 16] = ss;
;             }
.LBB0_742:
	v_or_b32_e32 v74, 0xcc00, v0
	v_mov_b32_e32 v80, v77
	v_mov_b32_e32 v75, v1
	s_waitcnt lgkmcnt(0)
	v_pk_fma_f32 v[70:71], v[154:155], v[80:81], v[82:83]
	v_lshl_add_u64 v[66:67], v[74:75], 2, s[0:1]
	global_store_dwordx2 v[66:67], v[70:71], off
	s_mov_b64 s[10:11], -1
	s_and_b64 vcc, exec, s[6:7]
	v_or_b32_e32 v66, 0xcc80, v0
	s_cbranch_vccnz .LBB0_746
	v_pk_mul_f32 v[76:77], v[148:149], v[70:71]
	v_lshl_add_u64 v[74:75], v[74:75], 1, s[2:3]
	s_nop 0
	v_and_b32_sdwa v67, v77, v178 dst_sel:DWORD dst_unused:UNUSED_PAD src0_sel:WORD_1 src1_sel:DWORD
	v_cvt_pk_bf16_f32 v68, v76, v76
	v_add3_u32 v67, v77, v67, s81
	v_lshrrev_b32_e32 v68, 16, v68
	v_and_or_b32 v67, v67, s28, v68
	global_store_dword v[74:75], v67, off
	v_mov_b32_e32 v72, v69
	v_mov_b32_e32 v67, v1
	v_pk_fma_f32 v[74:75], v[150:151], v[72:73], v[84:85]
	v_lshl_add_u64 v[76:77], v[66:67], 2, s[0:1]
	global_store_dwordx2 v[76:77], v[74:75], off
	v_pk_mul_f32 v[76:77], v[152:153], v[74:75]
	v_pk_mul_f32 v[70:71], v[70:71], v[70:71]
	s_nop 0
	v_and_b32_sdwa v68, v77, v178 dst_sel:DWORD dst_unused:UNUSED_PAD src0_sel:WORD_1 src1_sel:DWORD
	v_cvt_pk_bf16_f32 v72, v76, v76
	v_add3_u32 v68, v77, v68, s81
	v_lshrrev_b32_e32 v72, 16, v72
	v_and_or_b32 v68, v68, s28, v72
	v_lshl_add_u64 v[76:77], v[66:67], 1, s[2:3]
	v_pk_mul_f32 v[74:75], v[74:75], v[74:75]
	global_store_dword v[76:77], v68, off
	v_add_f32_e32 v67, v74, v75
	v_add_f32_e32 v68, v70, v71
	v_add_f32_e32 v67, v68, v67
	s_nop 1
	v_add_f32_dpp v67, v67, v67 quad_perm:[1,0,3,2] row_mask:0xf bank_mask:0xf bound_ctrl:1
	s_nop 1
	v_add_f32_dpp v67, v67, v67 quad_perm:[2,3,0,1] row_mask:0xf bank_mask:0xf bound_ctrl:1
	s_nop 1
	v_add_f32_dpp v67, v67, v67 row_half_mirror row_mask:0xf bank_mask:0xf bound_ctrl:1
	s_nop 1
	v_mov_b32_dpp v68, v67 row_mirror row_mask:0xf bank_mask:0xf bound_ctrl:1
	s_and_saveexec_b64 s[10:11], s[4:5]
	s_cbranch_execz .LBB0_745
	v_lshlrev_b32_e32 v70, 4, v163
	v_ashrrev_i32_e32 v71, 31, v70
	v_add_f32_e32 v67, v67, v68
	v_lshl_add_u64 v[70:71], v[70:71], 2, v[142:143]
	global_store_dword v[70:71], v67, off offset:3264

; __device__ __forceinline__ unsigned pack2(float a, float b) { return (unsigned)f2bf(a) | ((unsigned)f2bf(b) << 16); }
; #define WAIT_V(n) asm volatile("s_waitcnt vmcnt(" #n ")" ::: "memory")
; template <int EPI, bool HS = false>
; __device__ __forceinline__ void gemm_phase(const Params& p, const GemmCfg& g, char* shm, const int wave_s) {
;     ...
; #pragma unroll
;       for (int ai = 0; ai < 2; ++ai) {
; #pragma unroll
;         for (int i = 0; i < 16; ++i) {
;           const int r = wv_s * 16 + i;
;           glds_row(xin_t + (size_t)(ai * 128 + r) * 1024, (unsigned)lane * 16u, ldsb + (unsigned)(r * XROW));
;         }
;         WAIT_V(0);
;         __syncthreads();
; #pragma unroll
;         for (int m = 0; m < 4; ++m) {
;           float2 xv[4][2];
; #pragma unroll
;           for (int j = 0; j < 4; ++j)
; #pragma unroll
;             for (int bj = 0; bj < 2; ++bj) xv[j][bj] = *(const float2*)(xl + (m * 16 + j) * XROW + bj * 512);
; #pragma unroll
;           for (int j = 0; j < 4; ++j) {
;             float ss = 0.f;
; #pragma unroll
;             for (int bj = 0; bj < 2; ++bj) {
;               float2 xn;
;               xn.x = xv[j][bj].x + gt[bj][0] * acc[ai][bj][m][0][j];
;               xn.y = xv[j][bj].y + gt[bj][1] * acc[ai][bj][m][1][j];
;               const unsigned o = tb + (unsigned)((ai * 128 + m * 16 + j) * 1024 + bj * 128);
;               *(float2*)(xout_t + o) = xn;
;               if (g.has_next) *(unsigned*)(xg_t + o) = pack2(xn.x * gn[bj][0], xn.y * gn[bj][1]);
;               ss += xn.x * xn.x + xn.y * xn.y;
;             }
;             if (g.has_next) {
;               ss = dpp_row_sum16(ss);
;               if (fr == 0) rss_t[(wr * 64 + fq * 4 + ai * 128 + m * 16 + j) * 16] = ss;
;             }
.LBB0_748:
	s_lshl_b64 s[8:9], s[8:9], 12
	s_add_u32 s10, s71, s8
	s_addc_u32 s11, s72, s9
	s_add_u32 s8, s10, 0x80000
	s_addc_u32 s9, s11, 0
	s_waitcnt vmcnt(63) expcnt(7) lgkmcnt(15)
	s_barrier
	s_mov_b32 m0, s73
	s_nop 0
	global_load_lds_dwordx4 v167, s[8:9]
	s_add_u32 s8, s10, 0x81000
	s_addc_u32 s9, s11, 0
	s_mov_b32 m0, s74
	s_nop 0
	global_load_lds_dwordx4 v167, s[8:9]
	s_add_u32 s8, s10, 0x82000
	s_addc_u32 s9, s11, 0
	s_mov_b32 m0, s12
	s_nop 0
	global_load_lds_dwordx4 v167, s[8:9]
	s_add_u32 s8, s10, 0x83000
	s_addc_u32 s9, s11, 0
	s_mov_b32 m0, s13
	s_nop 0
	global_load_lds_dwordx4 v167, s[8:9]
	s_add_u32 s8, s10, 0x84000
	s_addc_u32 s9, s11, 0
	s_mov_b32 m0, s14
	s_nop 0
	global_load_lds_dwordx4 v167, s[8:9]
	s_add_u32 s8, s10, 0x85000
	s_addc_u32 s9, s11, 0
	s_mov_b32 m0, s15
	s_nop 0
	global_load_lds_dwordx4 v167, s[8:9]
	s_add_u32 s8, s10, 0x86000
	s_addc_u32 s9, s11, 0
	s_mov_b32 m0, s16
	s_nop 0
	global_load_lds_dwordx4 v167, s[8:9]
	s_add_u32 s8, s10, 0x87000
	s_addc_u32 s9, s11, 0
	s_mov_b32 m0, s17
	s_nop 0
	global_load_lds_dwordx4 v167, s[8:9]
	s_add_u32 s8, s10, 0x88000
	s_addc_u32 s9, s11, 0
	s_mov_b32 m0, s18
	s_nop 0
	global_load_lds_dwordx4 v167, s[8:9]
	s_add_u32 s8, s10, 0x89000
	s_addc_u32 s9, s11, 0
	s_mov_b32 m0, s19
	s_nop 0
	global_load_lds_dwordx4 v167, s[8:9]
	s_add_u32 s8, s10, 0x8a000
	s_addc_u32 s9, s11, 0
	s_mov_b32 m0, s20
	s_nop 0
	global_load_lds_dwordx4 v167, s[8:9]
	s_add_u32 s8, s10, 0x8b000
	s_addc_u32 s9, s11, 0
	s_mov_b32 m0, s21
	s_nop 0
	global_load_lds_dwordx4 v167, s[8:9]
	s_add_u32 s8, s10, 0x8c000
	s_addc_u32 s9, s11, 0
	s_mov_b32 m0, s22
	s_nop 0
	global_load_lds_dwordx4 v167, s[8:9]
	s_add_u32 s8, s10, 0x8d000
	s_addc_u32 s9, s11, 0
	s_mov_b32 m0, s23
	s_nop 0
	global_load_lds_dwordx4 v167, s[8:9]
	s_add_u32 s8, s10, 0x8e000
	s_addc_u32 s9, s11, 0
	s_mov_b32 m0, s24
	s_nop 0
	global_load_lds_dwordx4 v167, s[8:9]
	s_add_u32 s8, s10, 0x8f000
	s_addc_u32 s9, s11, 0
	s_mov_b32 m0, s25
	s_nop 0
	global_load_lds_dwordx4 v167, s[8:9]
	s_waitcnt vmcnt(0)
	s_barrier
	ds_read2st64_b64 v[78:81], v164 offset1:1
	ds_read2_b64 v[74:77], v164 offset0:130 offset1:194
	ds_read2st64_b64 v[70:73], v165 offset0:4 offset1:5
	ds_read2st64_b64 v[66:69], v166 offset0:6 offset1:7
	v_add_u32_e32 v84, 0x20000, v0
	v_mov_b32_e32 v82, v58
	v_mov_b32_e32 v83, v62
	v_mov_b32_e32 v85, v1
	s_waitcnt lgkmcnt(3)
	v_pk_fma_f32 v[82:83], v[154:155], v[82:83], v[78:79]
	v_lshl_add_u64 v[78:79], v[84:85], 2, s[0:1]
	global_store_dwordx2 v[78:79], v[82:83], off
	s_mov_b64 s[8:9], -1
	s_and_b64 vcc, exec, s[6:7]
	v_add_u32_e32 v78, 0x20080, v0
	s_cbranch_vccnz .LBB0_752
	v_pk_mul_f32 v[86:87], v[148:149], v[82:83]
	v_lshl_add_u64 v[84:85], v[84:85], 1, s[2:3]
	s_nop 0
	v_and_b32_sdwa v58, v87, v178 dst_sel:DWORD dst_unused:UNUSED_PAD src0_sel:WORD_1 src1_sel:DWORD
	v_cvt_pk_bf16_f32 v62, v86, v86
	v_add3_u32 v58, v87, v58, s81
	v_lshrrev_b32_e32 v62, 16, v62
	v_and_or_b32 v58, v58, s28, v62
	global_store_dword v[84:85], v58, off
	v_mov_b32_e32 v84, v50
	v_mov_b32_e32 v85, v54
	v_mov_b32_e32 v79, v1
	v_pk_fma_f32 v[84:85], v[150:151], v[84:85], v[80:81]
	v_lshl_add_u64 v[86:87], v[78:79], 2, s[0:1]
	global_store_dwordx2 v[86:87], v[84:85], off
	v_pk_mul_f32 v[86:87], v[152:153], v[84:85]
	v_pk_mul_f32 v[82:83], v[82:83], v[82:83]
	s_nop 0
	v_and_b32_sdwa v58, v87, v178 dst_sel:DWORD dst_unused:UNUSED_PAD src0_sel:WORD_1 src1_sel:DWORD
	v_cvt_pk_bf16_f32 v62, v86, v86
	v_add3_u32 v58, v87, v58, s81
	v_lshrrev_b32_e32 v62, 16, v62
	v_and_or_b32 v58, v58, s28, v62
	v_lshl_add_u64 v[86:87], v[78:79], 1, s[2:3]
	v_pk_mul_f32 v[84:85], v[84:85], v[84:85]
	global_store_dword v[86:87], v58, off
	v_add_f32_e32 v58, v84, v85
	v_add_f32_e32 v62, v82, v83
	v_add_f32_e32 v58, v62, v58
	s_nop 1
	v_add_f32_dpp v58, v58, v58 quad_perm:[1,0,3,2] row_mask:0xf bank_mask:0xf bound_ctrl:1
	s_nop 1
	v_add_f32_dpp v58, v58, v58 quad_perm:[2,3,0,1] row_mask:0xf bank_mask:0xf bound_ctrl:1
	s_nop 1
	v_add_f32_dpp v58, v58, v58 row_half_mirror row_mask:0xf bank_mask:0xf bound_ctrl:1
	s_nop 1
	v_mov_b32_dpp v62, v58 row_mirror row_mask:0xf bank_mask:0xf bound_ctrl:1
	s_and_saveexec_b64 s[8:9], s[4:5]
	s_cbranch_execz .LBB0_751
	v_add_f32_e32 v58, v58, v62
	v_mov_b32_e32 v62, 0x800
	v_lshl_add_u32 v82, v163, 4, v62
	v_ashrrev_i32_e32 v83, 31, v82
	v_lshl_add_u64 v[82:83], v[82:83], 2, v[142:143]
	global_store_dword v[82:83], v58, off

; __device__ __forceinline__ unsigned pack2(float a, float b) { return (unsigned)f2bf(a) | ((unsigned)f2bf(b) << 16); }
; template <int EPI, bool HS = false>
; __device__ __forceinline__ void gemm_phase(const Params& p, const GemmCfg& g, char* shm, const int wave_s) {
;     ...
;               xn.x = xv[j][bj].x + gt[bj][0] * acc[ai][bj][m][0][j];
;               xn.y = xv[j][bj].y + gt[bj][1] * acc[ai][bj][m][1][j];
;               const unsigned o = tb + (unsigned)((ai * 128 + m * 16 + j) * 1024 + bj * 128);
;               *(float2*)(xout_t + o) = xn;
;               if (g.has_next) *(unsigned*)(xg_t + o) = pack2(xn.x * gn[bj][0], xn.y * gn[bj][1]);
;               ss += xn.x * xn.x + xn.y * xn.y;
;             }
;             if (g.has_next) {
;               ss = dpp_row_sum16(ss);
;               if (fr == 0) rss_t[(wr * 64 + fq * 4 + ai * 128 + m * 16 + j) * 16] = ss;
;             }
.LBB0_754:
	v_add_u32_e32 v78, 0x20400, v0
	v_mov_b32_e32 v62, v59
	v_mov_b32_e32 v79, v1
	s_waitcnt lgkmcnt(2)
	v_pk_fma_f32 v[62:63], v[154:155], v[62:63], v[74:75]
	v_lshl_add_u64 v[58:59], v[78:79], 2, s[0:1]
	global_store_dwordx2 v[58:59], v[62:63], off
	s_mov_b64 s[8:9], -1
	s_and_b64 vcc, exec, s[6:7]
	v_add_u32_e32 v58, 0x20480, v0
	s_cbranch_vccnz .LBB0_758
	v_pk_mul_f32 v[74:75], v[148:149], v[62:63]
	v_mov_b32_e32 v59, v1
	s_nop 0
	v_and_b32_sdwa v50, v75, v178 dst_sel:DWORD dst_unused:UNUSED_PAD src0_sel:WORD_1 src1_sel:DWORD
	v_cvt_pk_bf16_f32 v54, v74, v74
	v_add3_u32 v50, v75, v50, s81
	v_lshrrev_b32_e32 v54, 16, v54
	v_and_or_b32 v50, v50, s28, v54
	v_lshl_add_u64 v[74:75], v[78:79], 1, s[2:3]
	v_mov_b32_e32 v54, v51
	global_store_dword v[74:75], v50, off
	v_pk_fma_f32 v[74:75], v[150:151], v[54:55], v[76:77]
	v_lshl_add_u64 v[78:79], v[58:59], 2, s[0:1]
	global_store_dwordx2 v[78:79], v[74:75], off
	v_pk_mul_f32 v[78:79], v[152:153], v[74:75]
	v_pk_mul_f32 v[62:63], v[62:63], v[62:63]
	s_nop 0
	v_and_b32_sdwa v50, v79, v178 dst_sel:DWORD dst_unused:UNUSED_PAD src0_sel:WORD_1 src1_sel:DWORD
	v_cvt_pk_bf16_f32 v54, v78, v78
	v_add3_u32 v50, v79, v50, s81
	v_lshrrev_b32_e32 v54, 16, v54
	v_and_or_b32 v50, v50, s28, v54
	v_lshl_add_u64 v[78:79], v[58:59], 1, s[2:3]
	v_pk_mul_f32 v[74:75], v[74:75], v[74:75]
	global_store_dword v[78:79], v50, off
	v_add_f32_e32 v50, v74, v75
	v_add_f32_e32 v54, v62, v63
	v_add_f32_e32 v50, v54, v50
	s_nop 1
	v_add_f32_dpp v50, v50, v50 quad_perm:[1,0,3,2] row_mask:0xf bank_mask:0xf bound_ctrl:1
	s_nop 1
	v_add_f32_dpp v50, v50, v50 quad_perm:[2,3,0,1] row_mask:0xf bank_mask:0xf bound_ctrl:1
	s_nop 1
	v_add_f32_dpp v50, v50, v50 row_half_mirror row_mask:0xf bank_mask:0xf bound_ctrl:1
	s_nop 1
	v_mov_b32_dpp v54, v50 row_mirror row_mask:0xf bank_mask:0xf bound_ctrl:1
	s_and_saveexec_b64 s[8:9], s[4:5]
	s_cbranch_execz .LBB0_757
	v_add_f32_e32 v50, v50, v54
	v_mov_b32_e32 v54, 0x810
	v_lshl_add_u32 v62, v163, 4, v54
	v_ashrrev_i32_e32 v63, 31, v62
	v_lshl_add_u64 v[62:63], v[62:63], 2, v[142:143]
	global_store_dword v[62:63], v50, off

; __device__ __forceinline__ unsigned pack2(float a, float b) { return (unsigned)f2bf(a) | ((unsigned)f2bf(b) << 16); }
; template <int EPI, bool HS = false>
; __device__ __forceinline__ void gemm_phase(const Params& p, const GemmCfg& g, char* shm, const int wave_s) {
;     ...
;               xn.x = xv[j][bj].x + gt[bj][0] * acc[ai][bj][m][0][j];
;               xn.y = xv[j][bj].y + gt[bj][1] * acc[ai][bj][m][1][j];
;               const unsigned o = tb + (unsigned)((ai * 128 + m * 16 + j) * 1024 + bj * 128);
;               *(float2*)(xout_t + o) = xn;
;               if (g.has_next) *(unsigned*)(xg_t + o) = pack2(xn.x * gn[bj][0], xn.y * gn[bj][1]);
;               ss += xn.x * xn.x + xn.y * xn.y;
;             }
;             if (g.has_next) {
;               ss = dpp_row_sum16(ss);
;               if (fr == 0) rss_t[(wr * 64 + fq * 4 + ai * 128 + m * 16 + j) * 16] = ss;
;             }
.LBB0_760:
	v_add_u32_e32 v58, 0x20800, v0
	v_mov_b32_e32 v50, v60
	v_mov_b32_e32 v51, v64
	v_mov_b32_e32 v59, v1
	s_waitcnt lgkmcnt(1)
	v_pk_fma_f32 v[54:55], v[154:155], v[50:51], v[70:71]
	v_lshl_add_u64 v[50:51], v[58:59], 2, s[0:1]
	global_store_dwordx2 v[50:51], v[54:55], off
	s_mov_b64 s[8:9], -1
	s_and_b64 vcc, exec, s[6:7]
	v_add_u32_e32 v50, 0x20880, v0
	s_cbranch_vccnz .LBB0_764
	v_pk_mul_f32 v[62:63], v[148:149], v[54:55]
	v_lshl_add_u64 v[58:59], v[58:59], 1, s[2:3]
	s_nop 0
	v_and_b32_sdwa v51, v63, v178 dst_sel:DWORD dst_unused:UNUSED_PAD src0_sel:WORD_1 src1_sel:DWORD
	v_cvt_pk_bf16_f32 v60, v62, v62
	v_add3_u32 v51, v63, v51, s81
	v_lshrrev_b32_e32 v60, 16, v60
	v_and_or_b32 v51, v51, s28, v60
	global_store_dword v[58:59], v51, off
	v_mov_b32_e32 v58, v52
	v_mov_b32_e32 v59, v56
	v_mov_b32_e32 v51, v1
	v_pk_fma_f32 v[58:59], v[150:151], v[58:59], v[72:73]
	v_lshl_add_u64 v[62:63], v[50:51], 2, s[0:1]
	global_store_dwordx2 v[62:63], v[58:59], off
	v_pk_mul_f32 v[62:63], v[152:153], v[58:59]
	v_pk_mul_f32 v[54:55], v[54:55], v[54:55]
	v_and_b32_sdwa v64, v62, v178 dst_sel:DWORD dst_unused:UNUSED_PAD src0_sel:WORD_1 src1_sel:DWORD
	v_and_b32_sdwa v60, v63, v178 dst_sel:DWORD dst_unused:UNUSED_PAD src0_sel:WORD_1 src1_sel:DWORD
	v_add3_u32 v62, v62, v64, s81
	v_add3_u32 v60, v63, v60, s81
	v_lshrrev_b32_e32 v62, 16, v62
	v_pk_mul_f32 v[58:59], v[58:59], v[58:59]
	v_and_or_b32 v60, v60, s28, v62
	v_lshl_add_u64 v[62:63], v[50:51], 1, s[2:3]
	v_add_f32_e32 v51, v58, v59
	v_add_f32_e32 v54, v54, v55
	v_add_f32_e32 v51, v54, v51
	global_store_dword v[62:63], v60, off
	s_nop 0
	v_add_f32_dpp v51, v51, v51 quad_perm:[1,0,3,2] row_mask:0xf bank_mask:0xf bound_ctrl:1
	s_nop 1
	v_add_f32_dpp v51, v51, v51 quad_perm:[2,3,0,1] row_mask:0xf bank_mask:0xf bound_ctrl:1
	s_nop 1
	v_add_f32_dpp v51, v51, v51 row_half_mirror row_mask:0xf bank_mask:0xf bound_ctrl:1
	s_nop 1
	v_mov_b32_dpp v54, v51 row_mirror row_mask:0xf bank_mask:0xf bound_ctrl:1
	s_and_saveexec_b64 s[8:9], s[4:5]
	s_cbranch_execz .LBB0_763
	v_add_f32_e32 v51, v51, v54
	v_mov_b32_e32 v54, 0x820
	v_lshl_add_u32 v54, v163, 4, v54
	v_ashrrev_i32_e32 v55, 31, v54
	v_lshl_add_u64 v[54:55], v[54:55], 2, v[142:143]
	global_store_dword v[54:55], v51, off

; __device__ __forceinline__ unsigned pack2(float a, float b) { return (unsigned)f2bf(a) | ((unsigned)f2bf(b) << 16); }
; template <int EPI, bool HS = false>
; __device__ __forceinline__ void gemm_phase(const Params& p, const GemmCfg& g, char* shm, const int wave_s) {
;     ...
;               xn.x = xv[j][bj].x + gt[bj][0] * acc[ai][bj][m][0][j];
;               xn.y = xv[j][bj].y + gt[bj][1] * acc[ai][bj][m][1][j];
;               const unsigned o = tb + (unsigned)((ai * 128 + m * 16 + j) * 1024 + bj * 128);
;               *(float2*)(xout_t + o) = xn;
;               if (g.has_next) *(unsigned*)(xg_t + o) = pack2(xn.x * gn[bj][0], xn.y * gn[bj][1]);
;               ss += xn.x * xn.x + xn.y * xn.y;
;             }
;             if (g.has_next) {
;               ss = dpp_row_sum16(ss);
;               if (fr == 0) rss_t[(wr * 64 + fq * 4 + ai * 128 + m * 16 + j) * 16] = ss;
;             }
.LBB0_766:
	v_add_u32_e32 v58, 0x20c00, v0
	v_mov_b32_e32 v64, v61
	v_mov_b32_e32 v59, v1
	s_waitcnt lgkmcnt(0)
	v_pk_fma_f32 v[54:55], v[154:155], v[64:65], v[66:67]
	v_lshl_add_u64 v[50:51], v[58:59], 2, s[0:1]
	global_store_dwordx2 v[50:51], v[54:55], off
	s_mov_b64 s[8:9], -1
	s_and_b64 vcc, exec, s[6:7]
	v_add_u32_e32 v50, 0x20c80, v0
	s_cbranch_vccnz .LBB0_770
	v_pk_mul_f32 v[60:61], v[148:149], v[54:55]
	v_lshl_add_u64 v[58:59], v[58:59], 1, s[2:3]
	s_nop 0
	v_and_b32_sdwa v51, v61, v178 dst_sel:DWORD dst_unused:UNUSED_PAD src0_sel:WORD_1 src1_sel:DWORD
	v_cvt_pk_bf16_f32 v52, v60, v60
	v_add3_u32 v51, v61, v51, s81
	v_lshrrev_b32_e32 v52, 16, v52
	v_and_or_b32 v51, v51, s28, v52
	global_store_dword v[58:59], v51, off
	v_mov_b32_e32 v56, v53
	v_mov_b32_e32 v51, v1
	v_pk_fma_f32 v[58:59], v[150:151], v[56:57], v[68:69]
	v_lshl_add_u64 v[60:61], v[50:51], 2, s[0:1]
	global_store_dwordx2 v[60:61], v[58:59], off
	v_pk_mul_f32 v[60:61], v[152:153], v[58:59]
	v_pk_mul_f32 v[54:55], v[54:55], v[54:55]
	s_nop 0
	v_and_b32_sdwa v52, v61, v178 dst_sel:DWORD dst_unused:UNUSED_PAD src0_sel:WORD_1 src1_sel:DWORD
	v_cvt_pk_bf16_f32 v56, v60, v60
	v_add3_u32 v52, v61, v52, s81
	v_lshrrev_b32_e32 v56, 16, v56
	v_and_or_b32 v52, v52, s28, v56
	v_lshl_add_u64 v[60:61], v[50:51], 1, s[2:3]
	v_pk_mul_f32 v[58:59], v[58:59], v[58:59]
	global_store_dword v[60:61], v52, off
	v_add_f32_e32 v51, v58, v59
	v_add_f32_e32 v52, v54, v55
	v_add_f32_e32 v51, v52, v51
	s_nop 1
	v_add_f32_dpp v51, v51, v51 quad_perm:[1,0,3,2] row_mask:0xf bank_mask:0xf bound_ctrl:1
	s_nop 1
	v_add_f32_dpp v51, v51, v51 quad_perm:[2,3,0,1] row_mask:0xf bank_mask:0xf bound_ctrl:1
	s_nop 1
	v_add_f32_dpp v51, v51, v51 row_half_mirror row_mask:0xf bank_mask:0xf bound_ctrl:1
	s_nop 1
	v_mov_b32_dpp v52, v51 row_mirror row_mask:0xf bank_mask:0xf bound_ctrl:1
	s_and_saveexec_b64 s[8:9], s[4:5]
	s_cbranch_execz .LBB0_769
	v_add_f32_e32 v51, v51, v52
	v_mov_b32_e32 v52, 0x830
	v_lshl_add_u32 v54, v163, 4, v52
	v_ashrrev_i32_e32 v55, 31, v54
	v_lshl_add_u64 v[54:55], v[54:55], 2, v[142:143]
	global_store_dword v[54:55], v51, off

; __device__ __forceinline__ unsigned pack2(float a, float b) { return (unsigned)f2bf(a) | ((unsigned)f2bf(b) << 16); }
; template <int EPI, bool HS = false>
; __device__ __forceinline__ void gemm_phase(const Params& p, const GemmCfg& g, char* shm, const int wave_s) {
;     ...
;         for (int m = 0; m < 4; ++m) {
;           float2 xv[4][2];
; #pragma unroll
;           for (int j = 0; j < 4; ++j)
; #pragma unroll
;             for (int bj = 0; bj < 2; ++bj) xv[j][bj] = *(const float2*)(xl + (m * 16 + j) * XROW + bj * 512);
; #pragma unroll
;           for (int j = 0; j < 4; ++j) {
;             float ss = 0.f;
; #pragma unroll
;             for (int bj = 0; bj < 2; ++bj) {
;               float2 xn;
;               xn.x = xv[j][bj].x + gt[bj][0] * acc[ai][bj][m][0][j];
;               xn.y = xv[j][bj].y + gt[bj][1] * acc[ai][bj][m][1][j];
;               const unsigned o = tb + (unsigned)((ai * 128 + m * 16 + j) * 1024 + bj * 128);
;               *(float2*)(xout_t + o) = xn;
;               if (g.has_next) *(unsigned*)(xg_t + o) = pack2(xn.x * gn[bj][0], xn.y * gn[bj][1]);
;               ss += xn.x * xn.x + xn.y * xn.y;
;             }
;             if (g.has_next) {
;               ss = dpp_row_sum16(ss);
;               if (fr == 0) rss_t[(wr * 64 + fq * 4 + ai * 128 + m * 16 + j) * 16] = ss;
;             }
.LBB0_772:
	ds_read2st64_b64 v[62:65], v134 offset0:32 offset1:33
	ds_read2st64_b64 v[58:61], v135 offset0:34 offset1:35
	ds_read2st64_b64 v[54:57], v136 offset0:36 offset1:37
	ds_read2st64_b64 v[50:53], v137 offset0:38 offset1:39
	v_add_u32_e32 v68, 0x24000, v0
	v_mov_b32_e32 v66, v42
	v_mov_b32_e32 v67, v46
	v_mov_b32_e32 v69, v1
	s_waitcnt lgkmcnt(3)
	v_pk_fma_f32 v[66:67], v[154:155], v[66:67], v[62:63]
	v_lshl_add_u64 v[62:63], v[68:69], 2, s[0:1]
	global_store_dwordx2 v[62:63], v[66:67], off
	s_mov_b64 s[8:9], -1
	s_and_b64 vcc, exec, s[6:7]
	v_add_u32_e32 v62, 0x24080, v0
	s_cbranch_vccnz .LBB0_776
	v_pk_mul_f32 v[70:71], v[148:149], v[66:67]
	v_lshl_add_u64 v[68:69], v[68:69], 1, s[2:3]
	s_nop 0
	v_and_b32_sdwa v42, v71, v178 dst_sel:DWORD dst_unused:UNUSED_PAD src0_sel:WORD_1 src1_sel:DWORD
	v_cvt_pk_bf16_f32 v46, v70, v70
	v_add3_u32 v42, v71, v42, s81
	v_lshrrev_b32_e32 v46, 16, v46
	v_and_or_b32 v42, v42, s28, v46
	global_store_dword v[68:69], v42, off
	v_mov_b32_e32 v68, v34
	v_mov_b32_e32 v69, v38
	v_mov_b32_e32 v63, v1
	v_pk_fma_f32 v[68:69], v[150:151], v[68:69], v[64:65]
	v_lshl_add_u64 v[70:71], v[62:63], 2, s[0:1]
	global_store_dwordx2 v[70:71], v[68:69], off
	v_pk_mul_f32 v[70:71], v[152:153], v[68:69]
	v_pk_mul_f32 v[66:67], v[66:67], v[66:67]
	s_nop 0
	v_and_b32_sdwa v42, v71, v178 dst_sel:DWORD dst_unused:UNUSED_PAD src0_sel:WORD_1 src1_sel:DWORD
	v_cvt_pk_bf16_f32 v46, v70, v70
	v_add3_u32 v42, v71, v42, s81
	v_lshrrev_b32_e32 v46, 16, v46
	v_and_or_b32 v42, v42, s28, v46
	v_lshl_add_u64 v[70:71], v[62:63], 1, s[2:3]
	v_pk_mul_f32 v[68:69], v[68:69], v[68:69]
	global_store_dword v[70:71], v42, off
	v_add_f32_e32 v42, v68, v69
	v_add_f32_e32 v46, v66, v67
	v_add_f32_e32 v42, v46, v42
	s_nop 1
	v_add_f32_dpp v42, v42, v42 quad_perm:[1,0,3,2] row_mask:0xf bank_mask:0xf bound_ctrl:1
	s_nop 1
	v_add_f32_dpp v42, v42, v42 quad_perm:[2,3,0,1] row_mask:0xf bank_mask:0xf bound_ctrl:1
	s_nop 1
	v_add_f32_dpp v42, v42, v42 row_half_mirror row_mask:0xf bank_mask:0xf bound_ctrl:1
	s_nop 1
	v_mov_b32_dpp v46, v42 row_mirror row_mask:0xf bank_mask:0xf bound_ctrl:1
	s_and_saveexec_b64 s[8:9], s[4:5]
	s_cbranch_execz .LBB0_775
	v_add_f32_e32 v42, v42, v46
	v_mov_b32_e32 v46, 0x900
	v_lshl_add_u32 v66, v163, 4, v46
	v_ashrrev_i32_e32 v67, 31, v66
	v_lshl_add_u64 v[66:67], v[66:67], 2, v[142:143]
	global_store_dword v[66:67], v42, off

; __device__ __forceinline__ unsigned pack2(float a, float b) { return (unsigned)f2bf(a) | ((unsigned)f2bf(b) << 16); }
; template <int EPI, bool HS = false>
; __device__ __forceinline__ void gemm_phase(const Params& p, const GemmCfg& g, char* shm, const int wave_s) {
;     ...
;               xn.x = xv[j][bj].x + gt[bj][0] * acc[ai][bj][m][0][j];
;               xn.y = xv[j][bj].y + gt[bj][1] * acc[ai][bj][m][1][j];
;               const unsigned o = tb + (unsigned)((ai * 128 + m * 16 + j) * 1024 + bj * 128);
;               *(float2*)(xout_t + o) = xn;
;               if (g.has_next) *(unsigned*)(xg_t + o) = pack2(xn.x * gn[bj][0], xn.y * gn[bj][1]);
;               ss += xn.x * xn.x + xn.y * xn.y;
;             }
;             if (g.has_next) {
;               ss = dpp_row_sum16(ss);
;               if (fr == 0) rss_t[(wr * 64 + fq * 4 + ai * 128 + m * 16 + j) * 16] = ss;
;             }
.LBB0_778:
	v_add_u32_e32 v62, 0x24400, v0
	v_mov_b32_e32 v46, v43
	v_mov_b32_e32 v63, v1
	s_waitcnt lgkmcnt(2)
	v_pk_fma_f32 v[46:47], v[154:155], v[46:47], v[58:59]
	v_lshl_add_u64 v[42:43], v[62:63], 2, s[0:1]
	global_store_dwordx2 v[42:43], v[46:47], off
	s_mov_b64 s[8:9], -1
	s_and_b64 vcc, exec, s[6:7]
	v_add_u32_e32 v42, 0x24480, v0
	s_cbranch_vccnz .LBB0_782
	v_pk_mul_f32 v[58:59], v[148:149], v[46:47]
	v_mov_b32_e32 v43, v1
	s_nop 0
	v_and_b32_sdwa v34, v59, v178 dst_sel:DWORD dst_unused:UNUSED_PAD src0_sel:WORD_1 src1_sel:DWORD
	v_cvt_pk_bf16_f32 v38, v58, v58
	v_add3_u32 v34, v59, v34, s81
	v_lshrrev_b32_e32 v38, 16, v38
	v_and_or_b32 v34, v34, s28, v38
	v_lshl_add_u64 v[58:59], v[62:63], 1, s[2:3]
	v_mov_b32_e32 v38, v35
	global_store_dword v[58:59], v34, off
	v_pk_fma_f32 v[58:59], v[150:151], v[38:39], v[60:61]
	v_lshl_add_u64 v[62:63], v[42:43], 2, s[0:1]
	global_store_dwordx2 v[62:63], v[58:59], off
	v_pk_mul_f32 v[62:63], v[152:153], v[58:59]
	v_pk_mul_f32 v[46:47], v[46:47], v[46:47]
	s_nop 0
	v_and_b32_sdwa v34, v63, v178 dst_sel:DWORD dst_unused:UNUSED_PAD src0_sel:WORD_1 src1_sel:DWORD
	v_cvt_pk_bf16_f32 v38, v62, v62
	v_add3_u32 v34, v63, v34, s81
	v_lshrrev_b32_e32 v38, 16, v38
	v_and_or_b32 v34, v34, s28, v38
	v_lshl_add_u64 v[62:63], v[42:43], 1, s[2:3]
	v_pk_mul_f32 v[58:59], v[58:59], v[58:59]
	global_store_dword v[62:63], v34, off
	v_add_f32_e32 v34, v58, v59
	v_add_f32_e32 v38, v46, v47
	v_add_f32_e32 v34, v38, v34
	s_nop 1
	v_add_f32_dpp v34, v34, v34 quad_perm:[1,0,3,2] row_mask:0xf bank_mask:0xf bound_ctrl:1
	s_nop 1
	v_add_f32_dpp v34, v34, v34 quad_perm:[2,3,0,1] row_mask:0xf bank_mask:0xf bound_ctrl:1
	s_nop 1
	v_add_f32_dpp v34, v34, v34 row_half_mirror row_mask:0xf bank_mask:0xf bound_ctrl:1
	s_nop 1
	v_mov_b32_dpp v38, v34 row_mirror row_mask:0xf bank_mask:0xf bound_ctrl:1
	s_and_saveexec_b64 s[8:9], s[4:5]
	s_cbranch_execz .LBB0_781
	v_add_f32_e32 v34, v34, v38
	v_mov_b32_e32 v38, 0x910
	v_lshl_add_u32 v46, v163, 4, v38
	v_ashrrev_i32_e32 v47, 31, v46
	v_lshl_add_u64 v[46:47], v[46:47], 2, v[142:143]
	global_store_dword v[46:47], v34, off

; __device__ __forceinline__ unsigned pack2(float a, float b) { return (unsigned)f2bf(a) | ((unsigned)f2bf(b) << 16); }
; template <int EPI, bool HS = false>
; __device__ __forceinline__ void gemm_phase(const Params& p, const GemmCfg& g, char* shm, const int wave_s) {
;     ...
;               xn.x = xv[j][bj].x + gt[bj][0] * acc[ai][bj][m][0][j];
;               xn.y = xv[j][bj].y + gt[bj][1] * acc[ai][bj][m][1][j];
;               const unsigned o = tb + (unsigned)((ai * 128 + m * 16 + j) * 1024 + bj * 128);
;               *(float2*)(xout_t + o) = xn;
;               if (g.has_next) *(unsigned*)(xg_t + o) = pack2(xn.x * gn[bj][0], xn.y * gn[bj][1]);
;               ss += xn.x * xn.x + xn.y * xn.y;
;             }
;             if (g.has_next) {
;               ss = dpp_row_sum16(ss);
;               if (fr == 0) rss_t[(wr * 64 + fq * 4 + ai * 128 + m * 16 + j) * 16] = ss;
;             }
.LBB0_784:
	v_add_u32_e32 v42, 0x24800, v0
	v_mov_b32_e32 v34, v44
	v_mov_b32_e32 v35, v48
	v_mov_b32_e32 v43, v1
	s_waitcnt lgkmcnt(1)
	v_pk_fma_f32 v[38:39], v[154:155], v[34:35], v[54:55]
	v_lshl_add_u64 v[34:35], v[42:43], 2, s[0:1]
	global_store_dwordx2 v[34:35], v[38:39], off
	s_mov_b64 s[8:9], -1
	s_and_b64 vcc, exec, s[6:7]
	v_add_u32_e32 v34, 0x24880, v0
	s_cbranch_vccnz .LBB0_788
	v_pk_mul_f32 v[46:47], v[148:149], v[38:39]
	v_lshl_add_u64 v[42:43], v[42:43], 1, s[2:3]
	s_nop 0
	v_and_b32_sdwa v35, v47, v178 dst_sel:DWORD dst_unused:UNUSED_PAD src0_sel:WORD_1 src1_sel:DWORD
	v_cvt_pk_bf16_f32 v44, v46, v46
	v_add3_u32 v35, v47, v35, s81
	v_lshrrev_b32_e32 v44, 16, v44
	v_and_or_b32 v35, v35, s28, v44
	global_store_dword v[42:43], v35, off
	v_mov_b32_e32 v42, v36
	v_mov_b32_e32 v43, v40
	v_mov_b32_e32 v35, v1
	v_pk_fma_f32 v[42:43], v[150:151], v[42:43], v[56:57]
	v_lshl_add_u64 v[46:47], v[34:35], 2, s[0:1]
	global_store_dwordx2 v[46:47], v[42:43], off
	v_pk_mul_f32 v[46:47], v[152:153], v[42:43]
	v_pk_mul_f32 v[38:39], v[38:39], v[38:39]
	v_and_b32_sdwa v48, v46, v178 dst_sel:DWORD dst_unused:UNUSED_PAD src0_sel:WORD_1 src1_sel:DWORD
	v_and_b32_sdwa v44, v47, v178 dst_sel:DWORD dst_unused:UNUSED_PAD src0_sel:WORD_1 src1_sel:DWORD
	v_add3_u32 v46, v46, v48, s81
	v_add3_u32 v44, v47, v44, s81
	v_lshrrev_b32_e32 v46, 16, v46
	v_pk_mul_f32 v[42:43], v[42:43], v[42:43]
	v_and_or_b32 v44, v44, s28, v46
	v_lshl_add_u64 v[46:47], v[34:35], 1, s[2:3]
	v_add_f32_e32 v35, v42, v43
	v_add_f32_e32 v38, v38, v39
	v_add_f32_e32 v35, v38, v35
	global_store_dword v[46:47], v44, off
	s_nop 0
	v_add_f32_dpp v35, v35, v35 quad_perm:[1,0,3,2] row_mask:0xf bank_mask:0xf bound_ctrl:1
	s_nop 1
	v_add_f32_dpp v35, v35, v35 quad_perm:[2,3,0,1] row_mask:0xf bank_mask:0xf bound_ctrl:1
	s_nop 1
	v_add_f32_dpp v35, v35, v35 row_half_mirror row_mask:0xf bank_mask:0xf bound_ctrl:1
	s_nop 1
	v_mov_b32_dpp v38, v35 row_mirror row_mask:0xf bank_mask:0xf bound_ctrl:1
	s_and_saveexec_b64 s[8:9], s[4:5]
	s_cbranch_execz .LBB0_787
	v_add_f32_e32 v35, v35, v38
	v_mov_b32_e32 v38, 0x920
	v_lshl_add_u32 v38, v163, 4, v38
	v_ashrrev_i32_e32 v39, 31, v38
	v_lshl_add_u64 v[38:39], v[38:39], 2, v[142:143]
	global_store_dword v[38:39], v35, off

; __device__ __forceinline__ unsigned pack2(float a, float b) { return (unsigned)f2bf(a) | ((unsigned)f2bf(b) << 16); }
; template <int EPI, bool HS = false>
; __device__ __forceinline__ void gemm_phase(const Params& p, const GemmCfg& g, char* shm, const int wave_s) {
;     ...
;           for (int j = 0; j < 4; ++j) {
;             float ss = 0.f;
; #pragma unroll
;             for (int bj = 0; bj < 2; ++bj) {
;               float2 xn;
;               xn.x = xv[j][bj].x + gt[bj][0] * acc[ai][bj][m][0][j];
;               xn.y = xv[j][bj].y + gt[bj][1] * acc[ai][bj][m][1][j];
;               const unsigned o = tb + (unsigned)((ai * 128 + m * 16 + j) * 1024 + bj * 128);
;               *(float2*)(xout_t + o) = xn;
;               if (g.has_next) *(unsigned*)(xg_t + o) = pack2(xn.x * gn[bj][0], xn.y * gn[bj][1]);
;               ss += xn.x * xn.x + xn.y * xn.y;
;             }
;             if (g.has_next) {
;               ss = dpp_row_sum16(ss);
;               if (fr == 0) rss_t[(wr * 64 + fq * 4 + ai * 128 + m * 16 + j) * 16] = ss;
;             }
.LBB0_790:
	v_add_u32_e32 v42, 0x24c00, v0
	v_mov_b32_e32 v48, v45
	v_mov_b32_e32 v43, v1
	s_waitcnt lgkmcnt(0)
	v_pk_fma_f32 v[38:39], v[154:155], v[48:49], v[50:51]
	v_lshl_add_u64 v[34:35], v[42:43], 2, s[0:1]
	global_store_dwordx2 v[34:35], v[38:39], off
	s_mov_b64 s[8:9], -1
	s_and_b64 vcc, exec, s[6:7]
	v_add_u32_e32 v34, 0x24c80, v0
	s_cbranch_vccnz .LBB0_794
	v_pk_mul_f32 v[44:45], v[148:149], v[38:39]
	v_lshl_add_u64 v[42:43], v[42:43], 1, s[2:3]
	s_nop 0
	v_and_b32_sdwa v35, v45, v178 dst_sel:DWORD dst_unused:UNUSED_PAD src0_sel:WORD_1 src1_sel:DWORD
	v_cvt_pk_bf16_f32 v36, v44, v44
	v_add3_u32 v35, v45, v35, s81
	v_lshrrev_b32_e32 v36, 16, v36
	v_and_or_b32 v35, v35, s28, v36
	global_store_dword v[42:43], v35, off
	v_mov_b32_e32 v40, v37
	v_mov_b32_e32 v35, v1
	v_pk_fma_f32 v[42:43], v[150:151], v[40:41], v[52:53]
	v_lshl_add_u64 v[44:45], v[34:35], 2, s[0:1]
	global_store_dwordx2 v[44:45], v[42:43], off
	v_pk_mul_f32 v[44:45], v[152:153], v[42:43]
	v_pk_mul_f32 v[38:39], v[38:39], v[38:39]
	s_nop 0
	v_and_b32_sdwa v36, v45, v178 dst_sel:DWORD dst_unused:UNUSED_PAD src0_sel:WORD_1 src1_sel:DWORD
	v_cvt_pk_bf16_f32 v40, v44, v44
	v_add3_u32 v36, v45, v36, s81
	v_lshrrev_b32_e32 v40, 16, v40
	v_and_or_b32 v36, v36, s28, v40
	v_lshl_add_u64 v[44:45], v[34:35], 1, s[2:3]
	v_pk_mul_f32 v[42:43], v[42:43], v[42:43]
	global_store_dword v[44:45], v36, off
	v_add_f32_e32 v35, v42, v43
	v_add_f32_e32 v36, v38, v39
	v_add_f32_e32 v35, v36, v35
	s_nop 1
	v_add_f32_dpp v35, v35, v35 quad_perm:[1,0,3,2] row_mask:0xf bank_mask:0xf bound_ctrl:1
	s_nop 1
	v_add_f32_dpp v35, v35, v35 quad_perm:[2,3,0,1] row_mask:0xf bank_mask:0xf bound_ctrl:1
	s_nop 1
	v_add_f32_dpp v35, v35, v35 row_half_mirror row_mask:0xf bank_mask:0xf bound_ctrl:1
	s_nop 1
	v_mov_b32_dpp v36, v35 row_mirror row_mask:0xf bank_mask:0xf bound_ctrl:1
	s_and_saveexec_b64 s[8:9], s[4:5]
	s_cbranch_execz .LBB0_793
	v_add_f32_e32 v35, v35, v36
	v_mov_b32_e32 v36, 0x930
	v_lshl_add_u32 v38, v163, 4, v36
	v_ashrrev_i32_e32 v39, 31, v38
	v_lshl_add_u64 v[38:39], v[38:39], 2, v[142:143]
	global_store_dword v[38:39], v35, off

; __device__ __forceinline__ unsigned pack2(float a, float b) { return (unsigned)f2bf(a) | ((unsigned)f2bf(b) << 16); }
; template <int EPI, bool HS = false>
; __device__ __forceinline__ void gemm_phase(const Params& p, const GemmCfg& g, char* shm, const int wave_s) {
;     ...
;           for (int j = 0; j < 4; ++j) {
;             float ss = 0.f;
; #pragma unroll
;             for (int bj = 0; bj < 2; ++bj) {
;               float2 xn;
;               xn.x = xv[j][bj].x + gt[bj][0] * acc[ai][bj][m][0][j];
;               xn.y = xv[j][bj].y + gt[bj][1] * acc[ai][bj][m][1][j];
;               const unsigned o = tb + (unsigned)((ai * 128 + m * 16 + j) * 1024 + bj * 128);
;               *(float2*)(xout_t + o) = xn;
;               if (g.has_next) *(unsigned*)(xg_t + o) = pack2(xn.x * gn[bj][0], xn.y * gn[bj][1]);
;               ss += xn.x * xn.x + xn.y * xn.y;
;             }
;             if (g.has_next) {
;               ss = dpp_row_sum16(ss);
;               if (fr == 0) rss_t[(wr * 64 + fq * 4 + ai * 128 + m * 16 + j) * 16] = ss;
;             }
.LBB0_796:
	ds_read2st64_b64 v[46:49], v164 offset0:65 offset1:66
	ds_read2st64_b64 v[42:45], v118 offset0:67 offset1:68
	ds_read2st64_b64 v[38:41], v165 offset0:69 offset1:70
	ds_read2st64_b64 v[34:37], v166 offset0:71 offset1:72
	v_add_u32_e32 v52, 0x28000, v0
	v_mov_b32_e32 v50, v26
	v_mov_b32_e32 v51, v30
	v_mov_b32_e32 v53, v1
	s_waitcnt lgkmcnt(3)
	v_pk_fma_f32 v[50:51], v[154:155], v[50:51], v[46:47]
	v_lshl_add_u64 v[46:47], v[52:53], 2, s[0:1]
	global_store_dwordx2 v[46:47], v[50:51], off
	s_mov_b64 s[8:9], -1
	s_and_b64 vcc, exec, s[6:7]
	v_add_u32_e32 v46, 0x28080, v0
	s_cbranch_vccnz .LBB0_800
	v_pk_mul_f32 v[54:55], v[148:149], v[50:51]
	v_lshl_add_u64 v[52:53], v[52:53], 1, s[2:3]
	s_nop 0
	v_and_b32_sdwa v26, v55, v178 dst_sel:DWORD dst_unused:UNUSED_PAD src0_sel:WORD_1 src1_sel:DWORD
	v_cvt_pk_bf16_f32 v30, v54, v54
	v_add3_u32 v26, v55, v26, s81
	v_lshrrev_b32_e32 v30, 16, v30
	v_and_or_b32 v26, v26, s28, v30
	global_store_dword v[52:53], v26, off
	v_mov_b32_e32 v52, v18
	v_mov_b32_e32 v53, v22
	v_mov_b32_e32 v47, v1
	v_pk_fma_f32 v[52:53], v[150:151], v[52:53], v[48:49]
	v_lshl_add_u64 v[54:55], v[46:47], 2, s[0:1]
	global_store_dwordx2 v[54:55], v[52:53], off
	v_pk_mul_f32 v[54:55], v[152:153], v[52:53]
	v_pk_mul_f32 v[50:51], v[50:51], v[50:51]
	s_nop 0
	v_and_b32_sdwa v26, v55, v178 dst_sel:DWORD dst_unused:UNUSED_PAD src0_sel:WORD_1 src1_sel:DWORD
	v_cvt_pk_bf16_f32 v30, v54, v54
	v_add3_u32 v26, v55, v26, s81
	v_lshrrev_b32_e32 v30, 16, v30
	v_and_or_b32 v26, v26, s28, v30
	v_lshl_add_u64 v[54:55], v[46:47], 1, s[2:3]
	v_pk_mul_f32 v[52:53], v[52:53], v[52:53]
	global_store_dword v[54:55], v26, off
	v_add_f32_e32 v26, v52, v53
	v_add_f32_e32 v30, v50, v51
	v_add_f32_e32 v26, v30, v26
	s_nop 1
	v_add_f32_dpp v26, v26, v26 quad_perm:[1,0,3,2] row_mask:0xf bank_mask:0xf bound_ctrl:1
	s_nop 1
	v_add_f32_dpp v26, v26, v26 quad_perm:[2,3,0,1] row_mask:0xf bank_mask:0xf bound_ctrl:1
	s_nop 1
	v_add_f32_dpp v26, v26, v26 row_half_mirror row_mask:0xf bank_mask:0xf bound_ctrl:1
	s_nop 1
	v_mov_b32_dpp v30, v26 row_mirror row_mask:0xf bank_mask:0xf bound_ctrl:1
	s_and_saveexec_b64 s[8:9], s[4:5]
	s_cbranch_execz .LBB0_799
	v_add_f32_e32 v26, v26, v30
	v_mov_b32_e32 v30, 0xa00
	v_lshl_add_u32 v50, v163, 4, v30
	v_ashrrev_i32_e32 v51, 31, v50
	v_lshl_add_u64 v[50:51], v[50:51], 2, v[142:143]
	global_store_dword v[50:51], v26, off

; __device__ __forceinline__ unsigned pack2(float a, float b) { return (unsigned)f2bf(a) | ((unsigned)f2bf(b) << 16); }
; template <int EPI, bool HS = false>
; __device__ __forceinline__ void gemm_phase(const Params& p, const GemmCfg& g, char* shm, const int wave_s) {
;     ...
;           for (int j = 0; j < 4; ++j) {
;             float ss = 0.f;
; #pragma unroll
;             for (int bj = 0; bj < 2; ++bj) {
;               float2 xn;
;               xn.x = xv[j][bj].x + gt[bj][0] * acc[ai][bj][m][0][j];
;               xn.y = xv[j][bj].y + gt[bj][1] * acc[ai][bj][m][1][j];
;               const unsigned o = tb + (unsigned)((ai * 128 + m * 16 + j) * 1024 + bj * 128);
;               *(float2*)(xout_t + o) = xn;
;               if (g.has_next) *(unsigned*)(xg_t + o) = pack2(xn.x * gn[bj][0], xn.y * gn[bj][1]);
;               ss += xn.x * xn.x + xn.y * xn.y;
;             }
;             if (g.has_next) {
;               ss = dpp_row_sum16(ss);
;               if (fr == 0) rss_t[(wr * 64 + fq * 4 + ai * 128 + m * 16 + j) * 16] = ss;
;             }
.LBB0_802:
	v_add_u32_e32 v46, 0x28400, v0
	v_mov_b32_e32 v30, v27
	v_mov_b32_e32 v47, v1
	s_waitcnt lgkmcnt(2)
	v_pk_fma_f32 v[30:31], v[154:155], v[30:31], v[42:43]
	v_lshl_add_u64 v[26:27], v[46:47], 2, s[0:1]
	global_store_dwordx2 v[26:27], v[30:31], off
	s_mov_b64 s[8:9], -1
	s_and_b64 vcc, exec, s[6:7]
	v_add_u32_e32 v26, 0x28480, v0
	s_cbranch_vccnz .LBB0_806
	v_pk_mul_f32 v[42:43], v[148:149], v[30:31]
	v_mov_b32_e32 v27, v1
	s_nop 0
	v_and_b32_sdwa v18, v43, v178 dst_sel:DWORD dst_unused:UNUSED_PAD src0_sel:WORD_1 src1_sel:DWORD
	v_cvt_pk_bf16_f32 v22, v42, v42
	v_add3_u32 v18, v43, v18, s81
	v_lshrrev_b32_e32 v22, 16, v22
	v_and_or_b32 v18, v18, s28, v22
	v_lshl_add_u64 v[42:43], v[46:47], 1, s[2:3]
	v_mov_b32_e32 v22, v19
	global_store_dword v[42:43], v18, off
	v_pk_fma_f32 v[42:43], v[150:151], v[22:23], v[44:45]
	v_lshl_add_u64 v[46:47], v[26:27], 2, s[0:1]
	global_store_dwordx2 v[46:47], v[42:43], off
	v_pk_mul_f32 v[46:47], v[152:153], v[42:43]
	v_pk_mul_f32 v[30:31], v[30:31], v[30:31]
	s_nop 0
	v_and_b32_sdwa v18, v47, v178 dst_sel:DWORD dst_unused:UNUSED_PAD src0_sel:WORD_1 src1_sel:DWORD
	v_cvt_pk_bf16_f32 v22, v46, v46
	v_add3_u32 v18, v47, v18, s81
	v_lshrrev_b32_e32 v22, 16, v22
	v_and_or_b32 v18, v18, s28, v22
	v_lshl_add_u64 v[46:47], v[26:27], 1, s[2:3]
	v_pk_mul_f32 v[42:43], v[42:43], v[42:43]
	global_store_dword v[46:47], v18, off
	v_add_f32_e32 v18, v42, v43
	v_add_f32_e32 v22, v30, v31
	v_add_f32_e32 v18, v22, v18
	s_nop 1
	v_add_f32_dpp v18, v18, v18 quad_perm:[1,0,3,2] row_mask:0xf bank_mask:0xf bound_ctrl:1
	s_nop 1
	v_add_f32_dpp v18, v18, v18 quad_perm:[2,3,0,1] row_mask:0xf bank_mask:0xf bound_ctrl:1
	s_nop 1
	v_add_f32_dpp v18, v18, v18 row_half_mirror row_mask:0xf bank_mask:0xf bound_ctrl:1
	s_nop 1
	v_mov_b32_dpp v22, v18 row_mirror row_mask:0xf bank_mask:0xf bound_ctrl:1
	s_and_saveexec_b64 s[8:9], s[4:5]
	s_cbranch_execz .LBB0_805
	v_add_f32_e32 v18, v18, v22
	v_mov_b32_e32 v22, 0xa10
	v_lshl_add_u32 v30, v163, 4, v22
	v_ashrrev_i32_e32 v31, 31, v30
	v_lshl_add_u64 v[30:31], v[30:31], 2, v[142:143]
	global_store_dword v[30:31], v18, off

; __device__ __forceinline__ unsigned pack2(float a, float b) { return (unsigned)f2bf(a) | ((unsigned)f2bf(b) << 16); }
; template <int EPI, bool HS = false>
; __device__ __forceinline__ void gemm_phase(const Params& p, const GemmCfg& g, char* shm, const int wave_s) {
;     ...
;           for (int j = 0; j < 4; ++j) {
;             float ss = 0.f;
; #pragma unroll
;             for (int bj = 0; bj < 2; ++bj) {
;               float2 xn;
;               xn.x = xv[j][bj].x + gt[bj][0] * acc[ai][bj][m][0][j];
;               xn.y = xv[j][bj].y + gt[bj][1] * acc[ai][bj][m][1][j];
;               const unsigned o = tb + (unsigned)((ai * 128 + m * 16 + j) * 1024 + bj * 128);
;               *(float2*)(xout_t + o) = xn;
;               if (g.has_next) *(unsigned*)(xg_t + o) = pack2(xn.x * gn[bj][0], xn.y * gn[bj][1]);
;               ss += xn.x * xn.x + xn.y * xn.y;
;             }
;             if (g.has_next) {
;               ss = dpp_row_sum16(ss);
;               if (fr == 0) rss_t[(wr * 64 + fq * 4 + ai * 128 + m * 16 + j) * 16] = ss;
;             }
.LBB0_808:
	v_add_u32_e32 v26, 0x28800, v0
	v_mov_b32_e32 v18, v28
	v_mov_b32_e32 v19, v32
	v_mov_b32_e32 v27, v1
	s_waitcnt lgkmcnt(1)
	v_pk_fma_f32 v[22:23], v[154:155], v[18:19], v[38:39]
	v_lshl_add_u64 v[18:19], v[26:27], 2, s[0:1]
	global_store_dwordx2 v[18:19], v[22:23], off
	s_mov_b64 s[8:9], -1
	s_and_b64 vcc, exec, s[6:7]
	v_add_u32_e32 v18, 0x28880, v0
	s_cbranch_vccnz .LBB0_812
	v_pk_mul_f32 v[30:31], v[148:149], v[22:23]
	v_lshl_add_u64 v[26:27], v[26:27], 1, s[2:3]
	s_nop 0
	v_and_b32_sdwa v19, v31, v178 dst_sel:DWORD dst_unused:UNUSED_PAD src0_sel:WORD_1 src1_sel:DWORD
	v_cvt_pk_bf16_f32 v28, v30, v30
	v_add3_u32 v19, v31, v19, s81
	v_lshrrev_b32_e32 v28, 16, v28
	v_and_or_b32 v19, v19, s28, v28
	global_store_dword v[26:27], v19, off
	v_mov_b32_e32 v26, v20
	v_mov_b32_e32 v27, v24
	v_mov_b32_e32 v19, v1
	v_pk_fma_f32 v[26:27], v[150:151], v[26:27], v[40:41]
	v_lshl_add_u64 v[30:31], v[18:19], 2, s[0:1]
	global_store_dwordx2 v[30:31], v[26:27], off
	v_pk_mul_f32 v[30:31], v[152:153], v[26:27]
	v_pk_mul_f32 v[22:23], v[22:23], v[22:23]
	v_and_b32_sdwa v32, v30, v178 dst_sel:DWORD dst_unused:UNUSED_PAD src0_sel:WORD_1 src1_sel:DWORD
	v_and_b32_sdwa v28, v31, v178 dst_sel:DWORD dst_unused:UNUSED_PAD src0_sel:WORD_1 src1_sel:DWORD
	v_add3_u32 v30, v30, v32, s81
	v_add3_u32 v28, v31, v28, s81
	v_lshrrev_b32_e32 v30, 16, v30
	v_pk_mul_f32 v[26:27], v[26:27], v[26:27]
	v_and_or_b32 v28, v28, s28, v30
	v_lshl_add_u64 v[30:31], v[18:19], 1, s[2:3]
	v_add_f32_e32 v19, v26, v27
	v_add_f32_e32 v22, v22, v23
	v_add_f32_e32 v19, v22, v19
	global_store_dword v[30:31], v28, off
	s_nop 0
	v_add_f32_dpp v19, v19, v19 quad_perm:[1,0,3,2] row_mask:0xf bank_mask:0xf bound_ctrl:1
	s_nop 1
	v_add_f32_dpp v19, v19, v19 quad_perm:[2,3,0,1] row_mask:0xf bank_mask:0xf bound_ctrl:1
	s_nop 1
	v_add_f32_dpp v19, v19, v19 row_half_mirror row_mask:0xf bank_mask:0xf bound_ctrl:1
	s_nop 1
	v_mov_b32_dpp v22, v19 row_mirror row_mask:0xf bank_mask:0xf bound_ctrl:1
	s_and_saveexec_b64 s[8:9], s[4:5]
	s_cbranch_execz .LBB0_811
	v_add_f32_e32 v19, v19, v22
	v_mov_b32_e32 v22, 0xa20
	v_lshl_add_u32 v22, v163, 4, v22
	v_ashrrev_i32_e32 v23, 31, v22
	v_lshl_add_u64 v[22:23], v[22:23], 2, v[142:143]
	global_store_dword v[22:23], v19, off

; __device__ __forceinline__ unsigned pack2(float a, float b) { return (unsigned)f2bf(a) | ((unsigned)f2bf(b) << 16); }
; template <int EPI, bool HS = false>
; __device__ __forceinline__ void gemm_phase(const Params& p, const GemmCfg& g, char* shm, const int wave_s) {
;     ...
;           for (int j = 0; j < 4; ++j) {
;             float ss = 0.f;
; #pragma unroll
;             for (int bj = 0; bj < 2; ++bj) {
;               float2 xn;
;               xn.x = xv[j][bj].x + gt[bj][0] * acc[ai][bj][m][0][j];
;               xn.y = xv[j][bj].y + gt[bj][1] * acc[ai][bj][m][1][j];
;               const unsigned o = tb + (unsigned)((ai * 128 + m * 16 + j) * 1024 + bj * 128);
;               *(float2*)(xout_t + o) = xn;
;               if (g.has_next) *(unsigned*)(xg_t + o) = pack2(xn.x * gn[bj][0], xn.y * gn[bj][1]);
;               ss += xn.x * xn.x + xn.y * xn.y;
;             }
;             if (g.has_next) {
;               ss = dpp_row_sum16(ss);
;               if (fr == 0) rss_t[(wr * 64 + fq * 4 + ai * 128 + m * 16 + j) * 16] = ss;
;             }
.LBB0_814:
	v_add_u32_e32 v26, 0x28c00, v0
	v_mov_b32_e32 v32, v29
	v_mov_b32_e32 v27, v1
	s_waitcnt lgkmcnt(0)
	v_pk_fma_f32 v[22:23], v[154:155], v[32:33], v[34:35]
	v_lshl_add_u64 v[18:19], v[26:27], 2, s[0:1]
	global_store_dwordx2 v[18:19], v[22:23], off
	s_mov_b64 s[8:9], -1
	s_and_b64 vcc, exec, s[6:7]
	v_add_u32_e32 v18, 0x28c80, v0
	s_cbranch_vccnz .LBB0_818
	v_pk_mul_f32 v[28:29], v[148:149], v[22:23]
	v_lshl_add_u64 v[26:27], v[26:27], 1, s[2:3]
	s_nop 0
	v_and_b32_sdwa v19, v29, v178 dst_sel:DWORD dst_unused:UNUSED_PAD src0_sel:WORD_1 src1_sel:DWORD
	v_cvt_pk_bf16_f32 v20, v28, v28
	v_add3_u32 v19, v29, v19, s81
	v_lshrrev_b32_e32 v20, 16, v20
	v_and_or_b32 v19, v19, s28, v20
	global_store_dword v[26:27], v19, off
	v_mov_b32_e32 v24, v21
	v_mov_b32_e32 v19, v1
	v_pk_fma_f32 v[26:27], v[150:151], v[24:25], v[36:37]
	v_lshl_add_u64 v[28:29], v[18:19], 2, s[0:1]
	global_store_dwordx2 v[28:29], v[26:27], off
	v_pk_mul_f32 v[28:29], v[152:153], v[26:27]
	v_pk_mul_f32 v[22:23], v[22:23], v[22:23]
	s_nop 0
	v_and_b32_sdwa v20, v29, v178 dst_sel:DWORD dst_unused:UNUSED_PAD src0_sel:WORD_1 src1_sel:DWORD
	v_cvt_pk_bf16_f32 v24, v28, v28
	v_add3_u32 v20, v29, v20, s81
	v_lshrrev_b32_e32 v24, 16, v24
	v_and_or_b32 v20, v20, s28, v24
	v_lshl_add_u64 v[28:29], v[18:19], 1, s[2:3]
	v_pk_mul_f32 v[26:27], v[26:27], v[26:27]
	global_store_dword v[28:29], v20, off
	v_add_f32_e32 v19, v26, v27
	v_add_f32_e32 v20, v22, v23
	v_add_f32_e32 v19, v20, v19
	s_nop 1
	v_add_f32_dpp v19, v19, v19 quad_perm:[1,0,3,2] row_mask:0xf bank_mask:0xf bound_ctrl:1
	s_nop 1
	v_add_f32_dpp v19, v19, v19 quad_perm:[2,3,0,1] row_mask:0xf bank_mask:0xf bound_ctrl:1
	s_nop 1
	v_add_f32_dpp v19, v19, v19 row_half_mirror row_mask:0xf bank_mask:0xf bound_ctrl:1
	s_nop 1
	v_mov_b32_dpp v20, v19 row_mirror row_mask:0xf bank_mask:0xf bound_ctrl:1
	s_and_saveexec_b64 s[8:9], s[4:5]
	s_cbranch_execz .LBB0_817
	v_add_f32_e32 v19, v19, v20
	v_mov_b32_e32 v20, 0xa30
	v_lshl_add_u32 v22, v163, 4, v20
	v_ashrrev_i32_e32 v23, 31, v22
	v_lshl_add_u64 v[22:23], v[22:23], 2, v[142:143]
	global_store_dword v[22:23], v19, off

; __device__ __forceinline__ unsigned pack2(float a, float b) { return (unsigned)f2bf(a) | ((unsigned)f2bf(b) << 16); }
; template <int EPI, bool HS = false>
; __device__ __forceinline__ void gemm_phase(const Params& p, const GemmCfg& g, char* shm, const int wave_s) {
;     ...
;           for (int j = 0; j < 4; ++j) {
;             float ss = 0.f;
; #pragma unroll
;             for (int bj = 0; bj < 2; ++bj) {
;               float2 xn;
;               xn.x = xv[j][bj].x + gt[bj][0] * acc[ai][bj][m][0][j];
;               xn.y = xv[j][bj].y + gt[bj][1] * acc[ai][bj][m][1][j];
;               const unsigned o = tb + (unsigned)((ai * 128 + m * 16 + j) * 1024 + bj * 128);
;               *(float2*)(xout_t + o) = xn;
;               if (g.has_next) *(unsigned*)(xg_t + o) = pack2(xn.x * gn[bj][0], xn.y * gn[bj][1]);
;               ss += xn.x * xn.x + xn.y * xn.y;
;             }
;             if (g.has_next) {
;               ss = dpp_row_sum16(ss);
;               if (fr == 0) rss_t[(wr * 64 + fq * 4 + ai * 128 + m * 16 + j) * 16] = ss;
;             }
.LBB0_820:
	ds_read2st64_b64 v[30:33], v134 offset0:97 offset1:98
	ds_read2st64_b64 v[26:29], v135 offset0:99 offset1:100
	ds_read2st64_b64 v[22:25], v136 offset0:101 offset1:102
	ds_read2st64_b64 v[18:21], v137 offset0:103 offset1:104
	v_add_u32_e32 v36, 0x2c000, v0
	v_mov_b32_e32 v34, v10
	v_mov_b32_e32 v35, v14
	v_mov_b32_e32 v37, v1
	s_waitcnt lgkmcnt(3)
	v_pk_fma_f32 v[34:35], v[154:155], v[34:35], v[30:31]
	v_lshl_add_u64 v[30:31], v[36:37], 2, s[0:1]
	global_store_dwordx2 v[30:31], v[34:35], off
	s_mov_b64 s[8:9], -1
	s_and_b64 vcc, exec, s[6:7]
	v_add_u32_e32 v30, 0x2c080, v0
	s_cbranch_vccnz .LBB0_824
	v_pk_mul_f32 v[38:39], v[148:149], v[34:35]
	v_lshl_add_u64 v[36:37], v[36:37], 1, s[2:3]
	s_nop 0
	v_and_b32_sdwa v10, v39, v178 dst_sel:DWORD dst_unused:UNUSED_PAD src0_sel:WORD_1 src1_sel:DWORD
	v_cvt_pk_bf16_f32 v14, v38, v38
	v_add3_u32 v10, v39, v10, s81
	v_lshrrev_b32_e32 v14, 16, v14
	v_and_or_b32 v10, v10, s28, v14
	global_store_dword v[36:37], v10, off
	v_mov_b32_e32 v36, v2
	v_mov_b32_e32 v37, v6
	v_mov_b32_e32 v31, v1
	v_pk_fma_f32 v[36:37], v[150:151], v[36:37], v[32:33]
	v_lshl_add_u64 v[38:39], v[30:31], 2, s[0:1]
	global_store_dwordx2 v[38:39], v[36:37], off
	v_pk_mul_f32 v[38:39], v[152:153], v[36:37]
	v_pk_mul_f32 v[34:35], v[34:35], v[34:35]
	s_nop 0
	v_and_b32_sdwa v10, v39, v178 dst_sel:DWORD dst_unused:UNUSED_PAD src0_sel:WORD_1 src1_sel:DWORD
	v_cvt_pk_bf16_f32 v14, v38, v38
	v_add3_u32 v10, v39, v10, s81
	v_lshrrev_b32_e32 v14, 16, v14
	v_and_or_b32 v10, v10, s28, v14
	v_lshl_add_u64 v[38:39], v[30:31], 1, s[2:3]
	v_pk_mul_f32 v[36:37], v[36:37], v[36:37]
	global_store_dword v[38:39], v10, off
	v_add_f32_e32 v10, v36, v37
	v_add_f32_e32 v14, v34, v35
	v_add_f32_e32 v10, v14, v10
	s_nop 1
	v_add_f32_dpp v10, v10, v10 quad_perm:[1,0,3,2] row_mask:0xf bank_mask:0xf bound_ctrl:1
	s_nop 1
	v_add_f32_dpp v10, v10, v10 quad_perm:[2,3,0,1] row_mask:0xf bank_mask:0xf bound_ctrl:1
	s_nop 1
	v_add_f32_dpp v10, v10, v10 row_half_mirror row_mask:0xf bank_mask:0xf bound_ctrl:1
	s_nop 1
	v_mov_b32_dpp v14, v10 row_mirror row_mask:0xf bank_mask:0xf bound_ctrl:1
	s_and_saveexec_b64 s[8:9], s[4:5]
	s_cbranch_execz .LBB0_823
	v_add_f32_e32 v10, v10, v14
	v_mov_b32_e32 v14, 0xb00
	v_lshl_add_u32 v34, v163, 4, v14
	v_ashrrev_i32_e32 v35, 31, v34
	v_lshl_add_u64 v[34:35], v[34:35], 2, v[142:143]
	global_store_dword v[34:35], v10, off

; __device__ __forceinline__ unsigned pack2(float a, float b) { return (unsigned)f2bf(a) | ((unsigned)f2bf(b) << 16); }
; template <int EPI, bool HS = false>
; __device__ __forceinline__ void gemm_phase(const Params& p, const GemmCfg& g, char* shm, const int wave_s) {
;     ...
;           for (int j = 0; j < 4; ++j) {
;             float ss = 0.f;
; #pragma unroll
;             for (int bj = 0; bj < 2; ++bj) {
;               float2 xn;
;               xn.x = xv[j][bj].x + gt[bj][0] * acc[ai][bj][m][0][j];
;               xn.y = xv[j][bj].y + gt[bj][1] * acc[ai][bj][m][1][j];
;               const unsigned o = tb + (unsigned)((ai * 128 + m * 16 + j) * 1024 + bj * 128);
;               *(float2*)(xout_t + o) = xn;
;               if (g.has_next) *(unsigned*)(xg_t + o) = pack2(xn.x * gn[bj][0], xn.y * gn[bj][1]);
;               ss += xn.x * xn.x + xn.y * xn.y;
;             }
;             if (g.has_next) {
;               ss = dpp_row_sum16(ss);
;               if (fr == 0) rss_t[(wr * 64 + fq * 4 + ai * 128 + m * 16 + j) * 16] = ss;
;             }
.LBB0_826:
	v_add_u32_e32 v30, 0x2c400, v0
	v_mov_b32_e32 v14, v11
	v_mov_b32_e32 v31, v1
	s_waitcnt lgkmcnt(2)
	v_pk_fma_f32 v[14:15], v[154:155], v[14:15], v[26:27]
	v_lshl_add_u64 v[10:11], v[30:31], 2, s[0:1]
	global_store_dwordx2 v[10:11], v[14:15], off
	s_mov_b64 s[8:9], -1
	s_and_b64 vcc, exec, s[6:7]
	v_add_u32_e32 v10, 0x2c480, v0
	s_cbranch_vccnz .LBB0_830
	v_pk_mul_f32 v[26:27], v[148:149], v[14:15]
	v_mov_b32_e32 v11, v1
	s_nop 0
	v_and_b32_sdwa v2, v27, v178 dst_sel:DWORD dst_unused:UNUSED_PAD src0_sel:WORD_1 src1_sel:DWORD
	v_cvt_pk_bf16_f32 v6, v26, v26
	v_add3_u32 v2, v27, v2, s81
	v_lshrrev_b32_e32 v6, 16, v6
	v_and_or_b32 v2, v2, s28, v6
	v_lshl_add_u64 v[26:27], v[30:31], 1, s[2:3]
	v_mov_b32_e32 v6, v3
	global_store_dword v[26:27], v2, off
	v_pk_fma_f32 v[26:27], v[150:151], v[6:7], v[28:29]
	v_lshl_add_u64 v[30:31], v[10:11], 2, s[0:1]
	global_store_dwordx2 v[30:31], v[26:27], off
	v_pk_mul_f32 v[30:31], v[152:153], v[26:27]
	v_pk_mul_f32 v[14:15], v[14:15], v[14:15]
	s_nop 0
	v_and_b32_sdwa v2, v31, v178 dst_sel:DWORD dst_unused:UNUSED_PAD src0_sel:WORD_1 src1_sel:DWORD
	v_cvt_pk_bf16_f32 v6, v30, v30
	v_add3_u32 v2, v31, v2, s81
	v_lshrrev_b32_e32 v6, 16, v6
	v_and_or_b32 v2, v2, s28, v6
	v_lshl_add_u64 v[30:31], v[10:11], 1, s[2:3]
	v_pk_mul_f32 v[26:27], v[26:27], v[26:27]
	global_store_dword v[30:31], v2, off
	v_add_f32_e32 v2, v26, v27
	v_add_f32_e32 v6, v14, v15
	v_add_f32_e32 v2, v6, v2
	s_nop 1
	v_add_f32_dpp v2, v2, v2 quad_perm:[1,0,3,2] row_mask:0xf bank_mask:0xf bound_ctrl:1
	s_nop 1
	v_add_f32_dpp v2, v2, v2 quad_perm:[2,3,0,1] row_mask:0xf bank_mask:0xf bound_ctrl:1
	s_nop 1
	v_add_f32_dpp v2, v2, v2 row_half_mirror row_mask:0xf bank_mask:0xf bound_ctrl:1
	s_nop 1
	v_mov_b32_dpp v6, v2 row_mirror row_mask:0xf bank_mask:0xf bound_ctrl:1
	s_and_saveexec_b64 s[8:9], s[4:5]
	s_cbranch_execz .LBB0_829
	v_add_f32_e32 v2, v2, v6
	v_mov_b32_e32 v6, 0xb10
	v_lshl_add_u32 v14, v163, 4, v6
	v_ashrrev_i32_e32 v15, 31, v14
	v_lshl_add_u64 v[14:15], v[14:15], 2, v[142:143]
	global_store_dword v[14:15], v2, off

; __device__ __forceinline__ unsigned pack2(float a, float b) { return (unsigned)f2bf(a) | ((unsigned)f2bf(b) << 16); }
; template <int EPI, bool HS = false>
; __device__ __forceinline__ void gemm_phase(const Params& p, const GemmCfg& g, char* shm, const int wave_s) {
;     ...
;           for (int j = 0; j < 4; ++j) {
;             float ss = 0.f;
; #pragma unroll
;             for (int bj = 0; bj < 2; ++bj) {
;               float2 xn;
;               xn.x = xv[j][bj].x + gt[bj][0] * acc[ai][bj][m][0][j];
;               xn.y = xv[j][bj].y + gt[bj][1] * acc[ai][bj][m][1][j];
;               const unsigned o = tb + (unsigned)((ai * 128 + m * 16 + j) * 1024 + bj * 128);
;               *(float2*)(xout_t + o) = xn;
;               if (g.has_next) *(unsigned*)(xg_t + o) = pack2(xn.x * gn[bj][0], xn.y * gn[bj][1]);
;               ss += xn.x * xn.x + xn.y * xn.y;
;             }
;             if (g.has_next) {
;               ss = dpp_row_sum16(ss);
;               if (fr == 0) rss_t[(wr * 64 + fq * 4 + ai * 128 + m * 16 + j) * 16] = ss;
;             }
.LBB0_832:
	v_add_u32_e32 v10, 0x2c800, v0
	v_mov_b32_e32 v2, v12
	v_mov_b32_e32 v3, v16
	v_mov_b32_e32 v11, v1
	s_waitcnt lgkmcnt(1)
	v_pk_fma_f32 v[6:7], v[154:155], v[2:3], v[22:23]
	v_lshl_add_u64 v[2:3], v[10:11], 2, s[0:1]
	global_store_dwordx2 v[2:3], v[6:7], off
	s_mov_b64 s[8:9], -1
	s_and_b64 vcc, exec, s[6:7]
	v_add_u32_e32 v2, 0x2c880, v0
	s_cbranch_vccnz .LBB0_836
	v_pk_mul_f32 v[14:15], v[148:149], v[6:7]
	v_lshl_add_u64 v[10:11], v[10:11], 1, s[2:3]
	s_nop 0
	v_and_b32_sdwa v3, v15, v178 dst_sel:DWORD dst_unused:UNUSED_PAD src0_sel:WORD_1 src1_sel:DWORD
	v_cvt_pk_bf16_f32 v12, v14, v14
	v_add3_u32 v3, v15, v3, s81
	v_lshrrev_b32_e32 v12, 16, v12
	v_and_or_b32 v3, v3, s28, v12
	global_store_dword v[10:11], v3, off
	v_mov_b32_e32 v10, v4
	v_mov_b32_e32 v11, v8
	v_mov_b32_e32 v3, v1
	v_pk_fma_f32 v[10:11], v[150:151], v[10:11], v[24:25]
	v_lshl_add_u64 v[14:15], v[2:3], 2, s[0:1]
	global_store_dwordx2 v[14:15], v[10:11], off
	v_pk_mul_f32 v[14:15], v[152:153], v[10:11]
	v_pk_mul_f32 v[6:7], v[6:7], v[6:7]
	v_and_b32_sdwa v16, v14, v178 dst_sel:DWORD dst_unused:UNUSED_PAD src0_sel:WORD_1 src1_sel:DWORD
	v_and_b32_sdwa v12, v15, v178 dst_sel:DWORD dst_unused:UNUSED_PAD src0_sel:WORD_1 src1_sel:DWORD
	v_add3_u32 v14, v14, v16, s81
	v_add3_u32 v12, v15, v12, s81
	v_lshrrev_b32_e32 v14, 16, v14
	v_pk_mul_f32 v[10:11], v[10:11], v[10:11]
	v_and_or_b32 v12, v12, s28, v14
	v_lshl_add_u64 v[14:15], v[2:3], 1, s[2:3]
	v_add_f32_e32 v3, v10, v11
	v_add_f32_e32 v6, v6, v7
	v_add_f32_e32 v3, v6, v3
	global_store_dword v[14:15], v12, off
	s_nop 0
	v_add_f32_dpp v3, v3, v3 quad_perm:[1,0,3,2] row_mask:0xf bank_mask:0xf bound_ctrl:1
	s_nop 1
	v_add_f32_dpp v3, v3, v3 quad_perm:[2,3,0,1] row_mask:0xf bank_mask:0xf bound_ctrl:1
	s_nop 1
	v_add_f32_dpp v3, v3, v3 row_half_mirror row_mask:0xf bank_mask:0xf bound_ctrl:1
	s_nop 1
	v_mov_b32_dpp v6, v3 row_mirror row_mask:0xf bank_mask:0xf bound_ctrl:1
	s_and_saveexec_b64 s[8:9], s[4:5]
	s_cbranch_execz .LBB0_835
	v_add_f32_e32 v3, v3, v6
	v_mov_b32_e32 v6, 0xb20
	v_lshl_add_u32 v6, v163, 4, v6
	v_ashrrev_i32_e32 v7, 31, v6
	v_lshl_add_u64 v[6:7], v[6:7], 2, v[142:143]
	global_store_dword v[6:7], v3, off

; __device__ __forceinline__ unsigned pack2(float a, float b) { return (unsigned)f2bf(a) | ((unsigned)f2bf(b) << 16); }
; template <int EPI, bool HS = false>
; __device__ __forceinline__ void gemm_phase(const Params& p, const GemmCfg& g, char* shm, const int wave_s) {
;     ...
;           for (int j = 0; j < 4; ++j) {
;             float ss = 0.f;
; #pragma unroll
;             for (int bj = 0; bj < 2; ++bj) {
;               float2 xn;
;               xn.x = xv[j][bj].x + gt[bj][0] * acc[ai][bj][m][0][j];
;               xn.y = xv[j][bj].y + gt[bj][1] * acc[ai][bj][m][1][j];
;               const unsigned o = tb + (unsigned)((ai * 128 + m * 16 + j) * 1024 + bj * 128);
;               *(float2*)(xout_t + o) = xn;
;               if (g.has_next) *(unsigned*)(xg_t + o) = pack2(xn.x * gn[bj][0], xn.y * gn[bj][1]);
;               ss += xn.x * xn.x + xn.y * xn.y;
;             }
;             if (g.has_next) {
;               ss = dpp_row_sum16(ss);
;               if (fr == 0) rss_t[(wr * 64 + fq * 4 + ai * 128 + m * 16 + j) * 16] = ss;
;             }
.LBB0_838:
	v_add_u32_e32 v6, 0x2cc00, v0
	v_mov_b32_e32 v16, v13
	v_mov_b32_e32 v7, v1
	s_waitcnt lgkmcnt(0)
	v_pk_fma_f32 v[2:3], v[154:155], v[16:17], v[18:19]
	v_lshl_add_u64 v[10:11], v[6:7], 2, s[0:1]
	s_mov_b64 s[8:9], -1
	s_and_b64 vcc, exec, s[6:7]
	v_add_u32_e32 v0, 0x2cc80, v0
	global_store_dwordx2 v[10:11], v[2:3], off
	s_cbranch_vccnz .LBB0_842
	v_pk_mul_f32 v[10:11], v[148:149], v[2:3]
	v_lshl_add_u64 v[6:7], v[6:7], 1, s[2:3]
	s_nop 0
	v_and_b32_sdwa v4, v11, v178 dst_sel:DWORD dst_unused:UNUSED_PAD src0_sel:WORD_1 src1_sel:DWORD
	v_cvt_pk_bf16_f32 v8, v10, v10
	v_add3_u32 v4, v11, v4, s81
	v_lshrrev_b32_e32 v8, 16, v8
	v_and_or_b32 v4, v4, s28, v8
	v_mov_b32_e32 v8, v5
	global_store_dword v[6:7], v4, off
	v_pk_fma_f32 v[6:7], v[150:151], v[8:9], v[20:21]
	v_lshl_add_u64 v[10:11], v[0:1], 2, s[0:1]
	global_store_dwordx2 v[10:11], v[6:7], off
	v_pk_mul_f32 v[10:11], v[152:153], v[6:7]
	v_pk_mul_f32 v[2:3], v[2:3], v[2:3]
	s_nop 0
	v_and_b32_sdwa v4, v11, v178 dst_sel:DWORD dst_unused:UNUSED_PAD src0_sel:WORD_1 src1_sel:DWORD
	v_cvt_pk_bf16_f32 v8, v10, v10
	v_add3_u32 v4, v11, v4, s81
	v_lshrrev_b32_e32 v8, 16, v8
	v_and_or_b32 v4, v4, s28, v8
	v_lshl_add_u64 v[10:11], v[0:1], 1, s[2:3]
	v_pk_mul_f32 v[6:7], v[6:7], v[6:7]
	global_store_dword v[10:11], v4, off
	v_add_f32_e32 v4, v6, v7
	v_add_f32_e32 v2, v2, v3
	v_add_f32_e32 v2, v2, v4
	s_nop 1
	v_add_f32_dpp v2, v2, v2 quad_perm:[1,0,3,2] row_mask:0xf bank_mask:0xf bound_ctrl:1
	s_nop 1
	v_add_f32_dpp v2, v2, v2 quad_perm:[2,3,0,1] row_mask:0xf bank_mask:0xf bound_ctrl:1
	s_nop 1
	v_add_f32_dpp v2, v2, v2 row_half_mirror row_mask:0xf bank_mask:0xf bound_ctrl:1
	s_nop 1
	v_mov_b32_dpp v3, v2 row_mirror row_mask:0xf bank_mask:0xf bound_ctrl:1
	s_and_saveexec_b64 s[2:3], s[4:5]
	s_cbranch_execz .LBB0_841
	v_add_f32_e32 v4, v2, v3
	v_mov_b32_e32 v2, 0xb30
	v_lshl_add_u32 v2, v163, 4, v2
	v_ashrrev_i32_e32 v3, 31, v2
	v_lshl_add_u64 v[2:3], v[2:3], 2, v[142:143]
	global_store_dword v[2:3], v4, off

; #define STG_A(b, h, kt) stage_half_s(lds0 + ((b) * 2 + (h)) * HT_B, ((h) ? A1 : Ap) + (kt) * BK, off0, off1)
; #define STG_B(b, h, kt) stage_half_s(lds0 + (4 + (b) * 2 + (h)) * HT_B, ((h) ? B1p : Bp) + (kt) * BK, off0, off1)
; #define STG_A(b, h, kt) stage_half_s(lds0 + ((b) * 2 + (h)) * HT_B, ((h) ? A1 : Ap) + (kt) * BK, off0, off1)
; #define STG_B(b, h, kt) stage_half_s(lds0 + (4 + (b) * 2 + (h)) * HT_B, ((h) ? B1p : Bp) + (kt) * BK, off0, off1)
; __device__ __forceinline__ void gemm8_prefetch(const u16* __restrict__ Ap, const u16* __restrict__ Bp, int K, char* shm, const int tid) {
;   int r0, c0, r1, c1;
;   stage_rc(tid * 16, r0, c0);
;   stage_rc(tid * 16 + 8192, r1, c1);
;   const unsigned off0 = (unsigned)(r0 * K + c0) * 2u, off1 = (unsigned)(r1 * K + c1) * 2u;
;   const int wvoff = __builtin_amdgcn_readfirstlane(tid >> 6) * 1024;
;   const u16* A1 = Ap + (size_t)128 * K;
;   const u16* B1p = Bp + (size_t)128 * K;
;   const unsigned lds0 = (unsigned)(size_t)(__attribute__((address_space(3))) char*)shm + (unsigned)wvoff;
;     ...
;   STG_B(0, 0, 0); STG_A(0, 0, 0); STG_B(0, 1, 0); STG_A(0, 1, 0);
;   STG_B(1, 0, 1); STG_A(1, 0, 1); STG_B(1, 1, 1);
;     ...
; }
; template <int EPI, bool HS = false>
; __device__ __forceinline__ void gemm_phase(const Params& p, const GemmCfg& g, char* shm, const int wave_s) {
;     ...
;   if ((int)blockIdx.x < nwg) {
;     int mt, pn, arow0, orow0;
;     tile_coords(blockIdx.x, mt, pn, arow0, orow0);
;     gemm8_prefetch(g.A + (size_t)arow0 * g.K, g.Bt + (size_t)pn * 256 * g.K, g.K, shm, fresh_tid(wave_s));
;   }
.LBB0_850:
	s_andn2_b64 vcc, exec, s[0:1]
	s_cbranch_vccnz .LBB0_864
	v_readlane_b32 s0, v253, 6
	v_readlane_b32 s1, v253, 7
	s_andn2_b64 vcc, exec, s[0:1]
	s_cbranch_vccnz .LBB0_864
	s_mov_b32 s0, 0xb00000
	v_mul_hi_i32 v3, v162, s0
	v_mul_lo_u32 v2, v162, s0
	v_readlane_b32 s0, v253, 25
	v_readlane_b32 s1, v253, 26
	v_readlane_b32 s2, v253, 27
	v_readlane_b32 s3, v253, 28
	v_readlane_b32 s4, v253, 29
	v_readlane_b32 s5, v253, 30
	v_readlane_b32 s6, v253, 31
	v_readlane_b32 s7, v253, 32
	v_readlane_b32 s14, v253, 39
	v_readlane_b32 s15, v253, 40
	s_mov_b32 s0, 0x16000
	v_readlane_b32 s8, v253, 33
	v_lshl_add_u64 v[134:135], s[14:15], 0, v[2:3]
	v_mul_lo_u32 v2, v162, s0
	v_readlane_b32 s0, v252, 0
	v_readlane_b32 s1, v252, 1
	v_ashrrev_i32_e32 v3, 31, v2
	v_readlane_b32 s0, v253, 8
	v_lshlrev_b64 v[2:3], 2, v[2:3]
	v_readlane_b32 s4, v252, 4
	v_readlane_b32 s5, v252, 5
	v_readlane_b32 s1, v253, 9
	v_readlane_b32 s2, v252, 2
	v_lshl_add_u64 v[136:137], s[4:5], 0, v[2:3]
	v_lshl_add_u64 v[2:3], v[134:135], 0, s[0:1]
	s_mov_b32 s0, s82
	s_mov_b32 s1, -1
	v_readlane_b32 s3, v252, 3
	v_mbcnt_lo_u32_b32 v0, s1, 0
	v_mbcnt_hi_u32_b32 v0, s1, v0
	v_lshl_add_u32 v0, s0, 6, v0
	s_mov_b64 s[0:1], 0x40000
	v_bfe_i32 v6, v0, 27, 1
	v_lshlrev_b32_e32 v4, 4, v0
	v_lshrrev_b32_e32 v6, 22, v6
	v_add_u32_e32 v6, v4, v6
	v_and_b32_e32 v6, 0xfffffc00, v6
	v_ashrrev_i32_e32 v5, 31, v0
	v_sub_u32_e32 v6, v4, v6
	v_lshrrev_b32_e32 v5, 26, v5
	v_lshrrev_b32_e32 v7, 4, v6
	v_add_u32_e32 v5, v0, v5
	v_bitop3_b32 v7, v7, v6, 32 bitop3:0x6c
	v_ashrrev_i32_e32 v6, 31, v6
	v_ashrrev_i32_e32 v5, 6, v5
	v_lshrrev_b32_e32 v6, 26, v6
	v_lshlrev_b32_e32 v8, 3, v5
	v_add_u32_e32 v6, v7, v6
	v_and_b32_e32 v8, 0x1ffff0, v8
	v_ashrrev_i32_e32 v6, 6, v6
	v_add_u32_e32 v8, v6, v8
	v_mul_i32_i24_e32 v6, 64, v6
	v_add_u32_e32 v4, 0x2000, v4
	v_sub_u32_e32 v6, v7, v6
	v_ashrrev_i32_e32 v7, 31, v4
	v_lshrrev_b32_e32 v7, 22, v7
	v_add_u32_e32 v7, v4, v7
	v_ashrrev_i32_e32 v7, 10, v7
	v_mul_i32_i24_e32 v9, 0x400, v7
	v_sub_u32_e32 v4, v4, v9
	v_lshrrev_b32_e32 v9, 4, v4
	v_bitop3_b32 v4, v9, v4, 32 bitop3:0x6c
	v_ashrrev_i32_e32 v10, 31, v4
	v_lshrrev_b32_e32 v10, 26, v10
	v_add_u32_e32 v10, v4, v10
	v_lshlrev_b32_e32 v5, 5, v5
	v_lshlrev_b32_e32 v9, 3, v7
	v_lshrrev_b32_e32 v11, 6, v10
	v_and_b32_e32 v10, 0xc0, v10
	v_readfirstlane_b32 s2, v0
	v_and_b32_e32 v5, 32, v5
	v_ashrrev_i16_sdwa v6, v178, sext(v6) dst_sel:DWORD dst_unused:UNUSED_PAD src0_sel:DWORD src1_sel:BYTE_0
	v_and_b32_e32 v9, 0x1ffff0, v9
	v_lshlrev_b32_e32 v7, 5, v7
	v_sub_u32_e32 v4, v4, v10
	s_lshl_b32 s2, s2, 4
	v_bfe_i32 v6, v6, 0, 16
	v_add_u32_e32 v9, v11, v9
	v_and_b32_e32 v7, 32, v7
	v_ashrrev_i16_sdwa v4, v178, sext(v4) dst_sel:DWORD dst_unused:UNUSED_PAD src0_sel:DWORD src1_sel:BYTE_0
	v_lshl_or_b32 v5, v8, 10, v5
	s_and_b32 s2, s2, 0xfffffc00
	v_bfe_i32 v4, v4, 0, 16
	v_add_lshl_u32 v6, v5, v6, 1
	v_lshl_or_b32 v5, v9, 10, v7
	s_add_i32 s2, s2, 0
	v_add_lshl_u32 v7, v5, v4, 1
	v_lshl_add_u64 v[4:5], v[2:3], 0, s[0:1]
	v_readfirstlane_b32 s1, v3
	v_readfirstlane_b32 s0, v2
	s_add_i32 s3, s2, 0x10000
	s_mov_b32 m0, s3
	s_nop 2
	global_load_lds_dwordx4 v6, s[0:1]
	s_add_i32 s3, s2, 0x12000
	s_mov_b32 m0, s3
	s_nop 0
	global_load_lds_dwordx4 v7, s[0:1]
	s_add_i32 s3, s2, 0x14000
	v_readlane_b32 s4, v253, 12
	v_readlane_b32 s5, v253, 13
	s_mov_b32 m0, s2
	s_nop 3
	global_load_lds_dwordx4 v6, s[4:5]
	s_add_i32 s0, s2, 0x2000
	s_mov_b32 m0, s0
	s_nop 0
	global_load_lds_dwordx4 v7, s[4:5]
	v_readfirstlane_b32 s0, v4
	v_readfirstlane_b32 s1, v5
	s_mov_b32 m0, s3
	s_nop 3
	global_load_lds_dwordx4 v6, s[0:1]
	s_add_i32 s3, s2, 0x16000
	s_mov_b32 m0, s3
	s_nop 0
	global_load_lds_dwordx4 v7, s[0:1]
	s_add_i32 s0, s2, 0x4000
	v_readlane_b32 s4, v253, 10
	v_readlane_b32 s5, v253, 11
	s_mov_b32 m0, s0
	s_nop 3
	global_load_lds_dwordx4 v6, s[4:5]
	s_add_i32 s0, s2, 0x6000
	s_mov_b32 m0, s0
	s_nop 0
	global_load_lds_dwordx4 v7, s[4:5]
	s_mov_b64 s[0:1], 0x80
	v_lshl_add_u64 v[4:5], v[2:3], 0, s[0:1]
	s_add_i32 s3, s2, 0x18000
	v_readfirstlane_b32 s1, v5
	v_readfirstlane_b32 s0, v4
	s_mov_b32 m0, s3
	s_nop 3
	global_load_lds_dwordx4 v6, s[0:1]
	s_add_i32 s3, s2, 0x1a000
	s_mov_b32 m0, s3
	s_nop 0
	global_load_lds_dwordx4 v7, s[0:1]
	s_add_i32 s0, s2, 0x8000
	v_readlane_b32 s4, v253, 14
	v_readlane_b32 s5, v253, 15
	s_mov_b32 m0, s0
	s_nop 3
	global_load_lds_dwordx4 v6, s[4:5]
	s_add_i32 s0, s2, 0xa000
	s_mov_b32 m0, s0
	s_nop 0
	global_load_lds_dwordx4 v7, s[4:5]
	s_mov_b64 s[0:1], 0x40080
	v_lshl_add_u64 v[2:3], v[2:3], 0, s[0:1]
	s_add_i32 s3, s2, 0x1c000
	v_readfirstlane_b32 s1, v3
	v_readfirstlane_b32 s0, v2
	s_mov_b32 m0, s3
	s_nop 3
	global_load_lds_dwordx4 v6, s[0:1]
	s_add_i32 s2, s2, 0x1e000
	s_mov_b32 m0, s2
	s_nop 0
	global_load_lds_dwordx4 v7, s[0:1]
	s_mov_b32 s8, s45
	v_readlane_b32 s9, v253, 34
	v_readlane_b32 s10, v253, 35
	v_readlane_b32 s11, v253, 36
	v_readlane_b32 s12, v253, 37
	v_readlane_b32 s13, v253, 38
	v_readlane_b32 s6, v252, 6
	v_readlane_b32 s7, v252, 7
; template <int EPI, bool HS = false>
; __device__ __forceinline__ void gemm_phase(const Params& p, const GemmCfg& g, char* shm, const int wave_s) {
;     ...
;   for (int tile = blockIdx.x; tile < nwg; tile += gridDim.x) {
;     int mt, pn, arow0, orow0;
;     tile_coords(tile, mt, pn, arow0, orow0);
;     float* rs = (float*)(shm + 131072) + (((tile - (int)blockIdx.x) / (int)gridDim.x) & 1) * 256;
;     float swv[2][2] = {{0.f, 0.f}, {0.f, 0.f}};
;     float gt[2][2] = {{0.f, 0.f}, {0.f, 0.f}}, gn[2][2] = {{0.f, 0.f}, {0.f, 0.f}};
;     {
;       const int t1 = fresh_tid(wave_s);
;       const int cix = pn * 256 + ((t1 >> 6) & 3) * 32 + (t1 & 15);
;       if constexpr (EPI != EPI_RESID) {
;         const float* swp = g.sw + (size_t)(arow0 >> 12) * g.N + cix;
; #pragma unroll
;         for (int bj = 0; bj < 2; ++bj)
; #pragma unroll
;           for (int n = 0; n < 2; ++n) swv[bj][n] = swp[bj * 128 + n * 16];
;       } else if constexpr (!HS) {
;         const int b = orow0 >> 12;
;         const int cix2 = pn * 256 + ((t1 >> 6) & 3) * 32 + 2 * (t1 & 15);
;         const float* gate = g.modl + (size_t)b * 9216 + g.sub * 3072 + 2048 + cix2;
; #pragma unroll
;         for (int bj = 0; bj < 2; ++bj)
; #pragma unroll
;           for (int n = 0; n < 2; ++n) {
;             gt[bj][n] = g.coef * gate[bj * 128 + n];
;             if (g.has_next) gn[bj][n] = g.gnext[cix2 + bj * 128 + n] * (1.0f + g.scnext[(size_t)b * 9216 + cix2 + bj * 128 + n]);
;           }
;       }
;     }
;     float* hs = (float*)(shm + 131072 + 2048) + (((tile - (int)blockIdx.x) / (int)gridDim.x) & 1) * 1024;
;     if constexpr (HS) {
;       const int t0 = fresh_tid(wave_s);
;       if (t0 < 256) {
;         const f32x4* pp = (const f32x4*)(p.sspart + (size_t)(arow0 + t0) * 32);
;         float rr[4];
; #pragma unroll
;         for (int h = 0; h < 4; ++h) {
;           f32x4 a = pp[2 * h], b4 = pp[2 * h + 1];
;           float ss = (a[0] + a[1] + a[2] + a[3]) + (b4[0] + b4[1] + b4[2] + b4[3]);
;           rr[h] = rsqrtf(ss * (1.0f / 512.0f) + 1e-6f);
;         }
;         hs[t0] = rr[0] / rr[1]; hs[256 + t0] = rr[1] / rr[2]; hs[512 + t0] = rr[2] / rr[3]; hs[768 + t0] = rr[3];
;       }
;     }
;     if constexpr (EPI != EPI_RESID) {
;       const int t0 = fresh_tid(wave_s);
;       if (t0 < 256) {
;         const f32x4* pp = (const f32x4*)(p.rowss + (size_t)(arow0 + t0) * 16);
.Lffn_in_first:
	s_ashr_i32 s0, s8, 31
	s_lshr_b32 s0, s0, 29
	s_add_i32 s0, s8, s0
	s_ashr_i32 s1, s0, 3
	s_and_b32 s0, s0, -8
	s_sub_i32 s0, s8, s0
	s_cmp_lt_i32 s0, 0
	s_movk_i32 s2, 0x2c1
	s_cselect_b32 s2, s2, 0x2c0
	s_mul_i32 s0, s2, s0
	s_add_i32 s0, s0, s1
	s_mul_hi_i32 s1, s0, 0x2e8ba2e9
	s_lshr_b32 s2, s1, 31
	s_ashr_i32 s1, s1, 5
	s_add_i32 s1, s1, s2
	s_mul_i32 s2, s1, 0xb0
	s_sub_i32 s0, s0, s2
	s_sext_i32_i16 s2, s0
	s_bfe_u32 s2, s2, 0x3001c
	s_add_i32 s2, s0, s2
	s_sext_i32_i16 s3, s2
	s_and_b32 s2, s2, 0xfff8
	s_sub_i32 s0, s0, s2
	s_sext_i32_i16 s0, s0
	s_lshl_b32 s1, s1, 11
	s_lshl_b32 s0, s0, 8
	s_add_i32 s4, s0, s1
	s_sub_i32 s0, s8, s45
	s_ashr_i32 s2, s3, 3
	s_ashr_i32 s1, s0, 31
	v_readlane_b32 s3, v254, 31
	s_xor_b32 s3, s1, s3
	s_abs_i32 s0, s0
	v_readlane_b32 s1, v254, 28
	s_mul_hi_u32 s1, s0, s1
	v_readlane_b32 s7, v254, 27
	s_mul_i32 s5, s1, s7
	s_sub_i32 s0, s0, s5
	s_add_i32 s5, s1, 1
	s_sub_i32 s6, s0, s7
	s_cmp_ge_u32 s0, s7
	s_cselect_b32 s1, s5, s1
	s_cselect_b32 s0, s6, s0
	s_add_i32 s5, s1, 1
	s_cmp_ge_u32 s0, s7
	s_cselect_b32 s5, s5, s1
	s_mov_b32 s0, -1
	s_mov_b32 s1, s82
	s_nop 0
	v_mbcnt_lo_u32_b32 v0, s0, 0
	v_mbcnt_hi_u32_b32 v0, s0, v0
	v_lshl_add_u32 v0, s1, 6, v0
	s_lshl_b32 s0, s2, 8
	v_lshrrev_b32_e32 v2, 1, v0
	v_and_b32_e32 v2, 0x60, v2
	v_and_b32_e32 v0, 15, v0
	v_or3_b32 v2, s0, v2, v0
	s_ashr_i32 s0, s4, 12
	s_mul_hi_i32 s1, s0, 0x5800
	s_mulk_i32 s0, 0x5800
	v_lshl_add_u64 v[4:5], v[136:137], 0, s[0:1]
	v_ashrrev_i32_e32 v3, 31, v2
	v_lshl_add_u64 v[2:3], v[2:3], 2, v[4:5]
	global_load_dword v140, v[2:3], off
	global_load_dword v141, v[2:3], off offset:64
	global_load_dword v138, v[2:3], off offset:512
	global_load_dword v139, v[2:3], off offset:576
	s_xor_b32 s0, s5, s3
	s_sub_i32 s0, s0, s3
	s_lshl_b32 s0, s0, 10
	s_and_b32 s0, s0, 0x400
	s_add_i32 s9, s0, 0
	s_mov_b32 s0, s82
	s_mov_b32 s1, -1
	s_add_i32 s9, s9, 0x20000
	v_mbcnt_lo_u32_b32 v0, s1, 0
	v_mbcnt_hi_u32_b32 v0, s1, v0
	v_lshl_add_u32 v0, s0, 6, v0
	s_movk_i32 s0, 0x100
	s_nop 0
	v_cmp_gt_i32_e32 vcc, s0, v0
	s_and_saveexec_b64 s[0:1], vcc
	s_cbranch_execz .Lf_856
	v_add_u32_e32 v2, s4, v0
	v_ashrrev_i32_e32 v3, 31, v2
	v_readlane_b32 s12, v252, 0
	v_lshlrev_b64 v[2:3], 6, v[2:3]
	v_readlane_b32 s18, v252, 6
	v_readlane_b32 s19, v252, 7
	v_lshl_add_u32 v0, v0, 2, s9
	v_readlane_b32 s13, v252, 1
	v_lshl_add_u64 v[14:15], s[18:19], 0, v[2:3]
	global_load_dwordx4 v[2:5], v[14:15], off
	global_load_dwordx4 v[6:9], v[14:15], off offset:16
	global_load_dwordx4 v[10:13], v[14:15], off offset:32
	s_nop 0
	global_load_dwordx4 v[14:17], v[14:15], off offset:48
	v_readlane_b32 s14, v252, 2
	v_readlane_b32 s15, v252, 3
	v_readlane_b32 s16, v252, 4
	v_readlane_b32 s17, v252, 5
	s_waitcnt vmcnt(3)
	v_mov_b32_e32 v18, v2
	s_waitcnt vmcnt(2)
	v_mov_b32_e32 v19, v6
	v_mov_b32_e32 v6, v3
	v_mov_b32_e32 v2, v4
	v_mov_b32_e32 v3, v8
	v_mov_b32_e32 v8, v5
	s_waitcnt vmcnt(1)
	v_mov_b32_e32 v4, v10
	s_waitcnt vmcnt(0)
	v_mov_b32_e32 v5, v14
	v_mov_b32_e32 v14, v11
	v_pk_add_f32 v[6:7], v[18:19], v[6:7]
	v_mov_b32_e32 v10, v12
	v_mov_b32_e32 v11, v16
	v_pk_add_f32 v[4:5], v[4:5], v[14:15]
	v_pk_add_f32 v[2:3], v[2:3], v[6:7]
	v_mov_b32_e32 v16, v13
	v_pk_add_f32 v[4:5], v[10:11], v[4:5]
	v_pk_add_f32 v[2:3], v[8:9], v[2:3]
	v_pk_add_f32 v[4:5], v[16:17], v[4:5]
	v_add_f32_e32 v2, v2, v3
	v_add_f32_e32 v2, v2, v4
	v_add_f32_e32 v2, v2, v5
	v_mov_b32_e32 v4, 0x358637bd
	v_fmamk_f32 v2, v2, 0x3a800000, v4
	v_mul_f32_e32 v3, 0x4b800000, v2
	v_cmp_gt_f32_e32 vcc, s42, v2
	s_nop 1
	v_cndmask_b32_e32 v2, v2, v3, vcc
	v_rsq_f32_e32 v2, v2
	s_nop 0
	v_mul_f32_e32 v3, 0x45800000, v2
	v_cndmask_b32_e32 v2, v2, v3, vcc
	ds_write_b32 v0, v2

; template <bool HS>
; __device__ __forceinline__ void gemm_tile8(const u16* __restrict__ Ap, const u16* __restrict__ Bp, int K,
;                                            f32x4 (&acc)[2][2][4][2], char* shm, const int tid, const float* hsr = nullptr) {
;   const int wid = tid >> 6, lane = tid & 63, wr = wid >> 2, wc = wid & 3, fr = lane & 15, fq = lane >> 4;
;   int r0, c0, r1, c1;
;   stage_rc(tid * 16, r0, c0);
;   stage_rc(tid * 16 + 8192, r1, c1);
;   const unsigned off0 = (unsigned)(r0 * K + c0) * 2u, off1 = (unsigned)(r1 * K + c1) * 2u;
;   const int wvoff = __builtin_amdgcn_readfirstlane(tid >> 6) * 1024;
;   const u16* A1 = Ap + (size_t)128 * K;
;   const u16* B1p = Bp + (size_t)128 * K;
; #pragma unroll
;   for (int a = 0; a < 2; ++a)
; #pragma unroll
;     for (int b = 0; b < 2; ++b)
; #pragma unroll
;       for (int m = 0; m < 4; ++m)
; #pragma unroll
;         for (int n = 0; n < 2; ++n) acc[a][b][m][n] = f32x4{0.f, 0.f, 0.f, 0.f};
;   const int abase = lds_byte(wr * 64 + fr, fq * 8), bbase = lds_byte(wc * 32 + fr, fq * 8);
;   bf16x8 At[4][2], B0[2][2], B1[2][2];
;   const unsigned lds0 = (unsigned)(size_t)(__attribute__((address_space(3))) char*)shm + (unsigned)wvoff;
.Lf_858:
	s_or_b64 exec, exec, s[0:1]
	v_bfe_i32 v6, v0, 27, 1
	v_lshlrev_b32_e32 v4, 4, v0
	v_lshrrev_b32_e32 v6, 22, v6
	v_add_u32_e32 v6, v4, v6
	v_and_b32_e32 v6, 0xfffffc00, v6
	v_ashrrev_i32_e32 v5, 31, v0
	v_sub_u32_e32 v6, v4, v6
	v_lshrrev_b32_e32 v5, 26, v5
	v_lshrrev_b32_e32 v7, 4, v6
	v_add_u32_e32 v5, v0, v5
	v_bitop3_b32 v7, v7, v6, 32 bitop3:0x6c
	v_ashrrev_i32_e32 v6, 31, v6
	v_ashrrev_i32_e32 v5, 6, v5
	v_lshrrev_b32_e32 v6, 26, v6
	v_lshlrev_b32_e32 v8, 3, v5
	v_add_u32_e32 v6, v7, v6
	v_and_b32_e32 v8, 0x1ffff0, v8
	v_ashrrev_i32_e32 v6, 6, v6
	v_add_u32_e32 v8, v6, v8
	v_mul_i32_i24_e32 v6, 64, v6
	v_add_u32_e32 v4, 0x2000, v4
	v_sub_u32_e32 v6, v7, v6
	v_ashrrev_i32_e32 v7, 31, v4
	v_lshrrev_b32_e32 v7, 22, v7
	v_add_u32_e32 v7, v4, v7
	v_ashrrev_i32_e32 v7, 10, v7
	v_mul_i32_i24_e32 v9, 0x400, v7
	v_sub_u32_e32 v4, v4, v9
	v_lshrrev_b32_e32 v9, 4, v4
	v_bitop3_b32 v4, v9, v4, 32 bitop3:0x6c
	v_ashrrev_i32_e32 v10, 31, v4
	v_lshrrev_b32_e32 v10, 26, v10
	v_add_u32_e32 v10, v4, v10
	v_lshlrev_b32_e32 v9, 3, v7
	v_lshrrev_b32_e32 v11, 6, v10
	v_and_b32_e32 v10, 0xc0, v10
	v_and_b32_e32 v9, 0x1ffff0, v9
	v_lshlrev_b32_e32 v7, 5, v7
	v_sub_u32_e32 v4, v4, v10
	s_ashr_i32 s5, s4, 31
	v_lshlrev_b32_e32 v5, 5, v5
	v_add_u32_e32 v9, v11, v9
	v_and_b32_e32 v7, 32, v7
	v_ashrrev_i16_sdwa v4, v178, sext(v4) dst_sel:DWORD dst_unused:UNUSED_PAD src0_sel:DWORD src1_sel:BYTE_0
	s_lshl_b64 s[0:1], s[4:5], 11
	v_and_b32_e32 v5, 32, v5
	v_ashrrev_i16_sdwa v6, v178, sext(v6) dst_sel:DWORD dst_unused:UNUSED_PAD src0_sel:DWORD src1_sel:BYTE_0
	v_bfe_i32 v4, v4, 0, 16
	v_lshl_or_b32 v7, v9, 10, v7
	s_add_u32 s5, s88, s0
	v_bfe_i32 v6, v6, 0, 16
	v_lshl_or_b32 v5, v8, 10, v5
	v_and_b32_e32 v8, 15, v0
	v_add_lshl_u32 v143, v7, v4, 1
	v_lshlrev_b32_e32 v7, 2, v0
	s_addc_u32 s6, s89, s1
	s_ashr_i32 s3, s2, 31
	v_add_lshl_u32 v144, v5, v6, 1
	v_and_b32_e32 v4, 48, v0
	v_lshlrev_b32_e32 v5, 6, v8
	v_and_b32_e32 v7, 32, v7
	s_lshl_b64 s[10:11], s[2:3], 19
	s_lshl_b32 s3, s7, 10
	v_or_b32_e32 v6, v5, v4
	v_bitop3_b32 v4, v5, v7, v4 bitop3:0x36
	v_lshlrev_b32_e32 v2, 12, v2
	s_movk_i32 s7, 0x3000
	v_lshl_add_u64 v[130:131], v[134:135], 0, s[10:11]
	s_mov_b64 s[10:11], 0x40000
	v_and_or_b32 v145, v2, s7, v4
	s_add_i32 s7, s3, 0
	v_lshl_add_u64 v[132:133], v[130:131], 0, s[10:11]
	s_add_u32 s10, s5, 0x40100
	v_lshlrev_b32_e32 v3, 13, v3
	s_addc_u32 s11, s6, 0
	v_readlane_b32 s12, v254, 34
	v_bitop3_b32 v3, v6, v3, v7 bitop3:0xde
	s_add_u32 s12, s12, s0
	v_readlane_b32 s0, v254, 35
	v_mov_b32_e32 v2, 0
	s_addc_u32 s13, s0, s1
	s_mov_b32 s14, -2
	s_mov_b64 s[0:1], 0
	v_add_u32_e32 v142, 0, v3
	s_waitcnt lgkmcnt(0)
	v_mov_b32_e32 v240, v143
	v_mov_b32_e32 v241, v144
	v_mov_b32_e32 v242, v145
	v_mov_b32_e32 v243, v142
	s_branch .Lffn_in_kinit

; #define WAIT_V(n) asm volatile("s_waitcnt vmcnt(" #n ")" ::: "memory")
; #define WAIT_L(n) asm volatile("s_waitcnt lgkmcnt(" #n ")" ::: "memory")
; #define BAR __builtin_amdgcn_s_barrier()
; #define SCHED __builtin_amdgcn_sched_barrier(0)
; #define STG_A(b, h, kt) stage_half_s(lds0 + ((b) * 2 + (h)) * HT_B, ((h) ? A1 : Ap) + (kt) * BK, off0, off1)
; #define STG_B(b, h, kt) stage_half_s(lds0 + (4 + (b) * 2 + (h)) * HT_B, ((h) ? B1p : Bp) + (kt) * BK, off0, off1)
; #define STG_A(b, h, kt) stage_half_s(lds0 + ((b) * 2 + (h)) * HT_B, ((h) ? A1 : Ap) + (kt) * BK, off0, off1)
; #define STG_B(b, h, kt) stage_half_s(lds0 + (4 + (b) * 2 + (h)) * HT_B, ((h) ? B1p : Bp) + (kt) * BK, off0, off1)
; #define LDA8(b, h) _Pragma("unroll") for (int m = 0; m < 4; ++m) _Pragma("unroll") for (int k = 0; k < 2; ++k) \
;     At[m][k] = *(const bf16x8*)(SA_(shm, b, h) + abase + (m * 2 + k) * 1024)
; template <bool HS>
; __device__ __forceinline__ void gemm_tile8(const u16* __restrict__ Ap, const u16* __restrict__ Bp, int K,
;                                            f32x4 (&acc)[2][2][4][2], char* shm, const int tid, const float* hsr = nullptr) {
;     ...
;   const int abase = lds_byte(wr * 64 + fr, fq * 8), bbase = lds_byte(wc * 32 + fr, fq * 8);
;   bf16x8 At[4][2], B0[2][2], B1[2][2];
;   const unsigned lds0 = (unsigned)(size_t)(__attribute__((address_space(3))) char*)shm + (unsigned)wvoff;
;     ...
;   const int nt = K / BK;
;   WAIT_V(0);
;   if (wr == 1) BAR;
;   BAR;
;   BAR;
;   for (int t = 0; t < nt - 2; t += 2) {
;     if constexpr (HS) {
;       if (t > 0 && (t & 7) == 0) {
;         const float* rt = hsr + ((t >> 3) - 1) * 256 + wr * 64 + fq * 4;
; #pragma unroll
;         for (int ai = 0; ai < 2; ++ai)
; #pragma unroll
;           for (int m = 0; m < 4; ++m) {
;             const f32x4 q4 = *(const f32x4*)(rt + ai * 128 + m * 16);
; #pragma unroll
;             for (int bj = 0; bj < 2; ++bj)
; #pragma unroll
;               for (int n = 0; n < 2; ++n) acc[ai][bj][m][n] *= q4;
;             SCHED;
;           }
;       }
;     }
;     LDB8(B0, 0, 0); SCHED; LDA8(0, 0); STG_A(1, 1, t + 1);
;     WAIT_L(8); BAR; WAIT_L(0); MMA8(0, 0, B0); BAR; SCHED;
;     LDB8(B1, 0, 1); STG_B(0, 0, t + 2);
;     BAR; WAIT_L(0); MMA8(0, 1, B1); BAR;
;     LDA8(0, 1); STG_A(0, 0, t + 2);
;     BAR; WAIT_L(0); MMA8(1, 0, B0); BAR; SCHED;
.LBB0_858:
	s_or_b64 exec, exec, s[0:1]
	s_ashr_i32 s5, s4, 31
	s_lshl_b64 s[0:1], s[4:5], 11
	s_add_u32 s5, s88, s0
	s_addc_u32 s6, s89, s1
	s_ashr_i32 s3, s2, 31
	s_lshl_b64 s[10:11], s[2:3], 19
	s_lshl_b32 s3, s7, 10
	s_movk_i32 s7, 0x3000
	v_lshl_add_u64 v[130:131], v[134:135], 0, s[10:11]
	s_mov_b64 s[10:11], 0x40000
	s_add_i32 s7, s3, 0
	v_lshl_add_u64 v[132:133], v[130:131], 0, s[10:11]
	s_add_u32 s10, s5, 0x40100
	s_addc_u32 s11, s6, 0
	v_readlane_b32 s12, v254, 34
	s_add_u32 s12, s12, s0
	v_readlane_b32 s0, v254, 35
	v_mov_b32_e32 v2, 0
	s_addc_u32 s13, s0, s1
	s_mov_b32 s14, -2
	s_mov_b64 s[0:1], 0
	s_waitcnt lgkmcnt(0)
	v_mov_b32_e32 v143, v240
	v_mov_b32_e32 v144, v241
	v_mov_b32_e32 v145, v242
	v_mov_b32_e32 v142, v243
.Lffn_in_kinit:
	v_readfirstlane_b32 s20, v130
	v_readfirstlane_b32 s21, v131
	v_readfirstlane_b32 s22, v132
	v_readfirstlane_b32 s23, v133
	s_mov_b32 s16, s5
	s_mov_b32 s17, s6
	s_mov_b32 s18, s12
	s_mov_b32 s19, s13
	s_barrier
	s_barrier
	v_add_u32_e32 v158, 0x10000, v145
	ds_read_b128 v[146:149], v158
	ds_read_b128 v[150:153], v158 offset:1024
	ds_read_b128 v[154:157], v158 offset:2048
	ds_read_b128 v[158:161], v158 offset:3072
	ds_read_b128 v[162:165], v142
	ds_read_b128 v[166:169], v142 offset:1024
	ds_read_b128 v[170:173], v142 offset:2048
	ds_read_b128 v[174:177], v142 offset:3072
	ds_read_b128 v[180:183], v142 offset:4096
	ds_read_b128 v[184:187], v142 offset:5120
	ds_read_b128 v[188:191], v142 offset:6144
	ds_read_b128 v[192:195], v142 offset:7168
	v_add_u32_e32 v208, 0x14000, v145
	ds_read_b128 v[196:199], v208
	ds_read_b128 v[200:203], v208 offset:1024
	ds_read_b128 v[204:207], v208 offset:2048
	ds_read_b128 v[208:211], v208 offset:3072
	s_add_u32 s0, s18, 0x80
	s_addc_u32 s1, s19, 0
	s_add_i32 s3, s7, 0xc000
	s_mov_b32 m0, s3
	s_nop 0
	global_load_lds_dwordx4 v144, s[0:1]
	s_add_i32 s3, s7, 0xe000
	s_mov_b32 m0, s3
	s_nop 0
	global_load_lds_dwordx4 v143, s[0:1]
	s_waitcnt vmcnt(8) lgkmcnt(0)
	s_barrier
	s_setprio 1
	v_mfma_f32_16x16x32_bf16 v[126:129], v[162:165], v[146:149], 0
	v_mfma_f32_16x16x32_bf16 v[122:125], v[162:165], v[154:157], 0
	v_mfma_f32_16x16x32_bf16 v[118:121], v[170:173], v[146:149], 0
	v_mfma_f32_16x16x32_bf16 v[114:117], v[170:173], v[154:157], 0
	v_mfma_f32_16x16x32_bf16 v[110:113], v[180:183], v[146:149], 0
	v_mfma_f32_16x16x32_bf16 v[106:109], v[180:183], v[154:157], 0
	v_mfma_f32_16x16x32_bf16 v[102:105], v[188:191], v[146:149], 0
	v_mfma_f32_16x16x32_bf16 v[98:101], v[188:191], v[154:157], 0
	v_mfma_f32_16x16x32_bf16 v[126:129], v[166:169], v[150:153], v[126:129]
	v_mfma_f32_16x16x32_bf16 v[122:125], v[166:169], v[158:161], v[122:125]
	v_mfma_f32_16x16x32_bf16 v[118:121], v[174:177], v[150:153], v[118:121]
	v_mfma_f32_16x16x32_bf16 v[114:117], v[174:177], v[158:161], v[114:117]
	v_mfma_f32_16x16x32_bf16 v[110:113], v[184:187], v[150:153], v[110:113]
	v_mfma_f32_16x16x32_bf16 v[106:109], v[184:187], v[158:161], v[106:109]
	v_mfma_f32_16x16x32_bf16 v[102:105], v[192:195], v[150:153], v[102:105]
	v_mfma_f32_16x16x32_bf16 v[98:101], v[192:195], v[158:161], v[98:101]
	v_mfma_f32_16x16x32_bf16 v[94:97], v[162:165], v[196:199], 0
	v_mfma_f32_16x16x32_bf16 v[90:93], v[162:165], v[204:207], 0
	v_mfma_f32_16x16x32_bf16 v[86:89], v[170:173], v[196:199], 0
	v_mfma_f32_16x16x32_bf16 v[82:85], v[170:173], v[204:207], 0
	v_mfma_f32_16x16x32_bf16 v[78:81], v[180:183], v[196:199], 0
	v_mfma_f32_16x16x32_bf16 v[74:77], v[180:183], v[204:207], 0
	v_mfma_f32_16x16x32_bf16 v[70:73], v[188:191], v[196:199], 0
	v_mfma_f32_16x16x32_bf16 v[66:69], v[188:191], v[204:207], 0
	v_mfma_f32_16x16x32_bf16 v[94:97], v[166:169], v[200:203], v[94:97]
	v_mfma_f32_16x16x32_bf16 v[90:93], v[166:169], v[208:211], v[90:93]
	v_mfma_f32_16x16x32_bf16 v[86:89], v[174:177], v[200:203], v[86:89]
	v_mfma_f32_16x16x32_bf16 v[82:85], v[174:177], v[208:211], v[82:85]
	v_mfma_f32_16x16x32_bf16 v[78:81], v[184:187], v[200:203], v[78:81]
	v_mfma_f32_16x16x32_bf16 v[74:77], v[184:187], v[208:211], v[74:77]
	v_mfma_f32_16x16x32_bf16 v[70:73], v[192:195], v[200:203], v[70:73]
	v_mfma_f32_16x16x32_bf16 v[66:69], v[192:195], v[208:211], v[66:69]
	s_setprio 0
	s_barrier
	ds_read_b128 v[162:165], v142 offset:16384
	ds_read_b128 v[166:169], v142 offset:17408
	ds_read_b128 v[170:173], v142 offset:18432
	ds_read_b128 v[174:177], v142 offset:19456
	ds_read_b128 v[180:183], v142 offset:20480
	ds_read_b128 v[184:187], v142 offset:21504
	ds_read_b128 v[188:191], v142 offset:22528
	ds_read_b128 v[192:195], v142 offset:23552
	s_add_u32 s0, s20, 0x100
	s_addc_u32 s1, s21, 0
	s_add_i32 s3, s7, 0x10000
	s_mov_b32 m0, s3
	s_nop 0
	global_load_lds_dwordx4 v144, s[0:1]
	s_add_i32 s3, s7, 0x12000
	s_mov_b32 m0, s3
	s_nop 0
	global_load_lds_dwordx4 v143, s[0:1]
	s_add_u32 s0, s16, 0x100
	s_addc_u32 s1, s17, 0
	s_mov_b32 m0, s7
	s_nop 0
	global_load_lds_dwordx4 v144, s[0:1]
	s_add_i32 s3, s7, 0x2000
	s_mov_b32 m0, s3
	s_nop 0
	global_load_lds_dwordx4 v143, s[0:1]
	s_add_u32 s0, s22, 0x100
	s_addc_u32 s1, s23, 0
	s_add_i32 s3, s7, 0x14000
	s_mov_b32 m0, s3
	s_nop 0
	global_load_lds_dwordx4 v144, s[0:1]
	s_add_i32 s3, s7, 0x16000
	s_mov_b32 m0, s3
	s_nop 0
	global_load_lds_dwordx4 v143, s[0:1]
	s_waitcnt vmcnt(8) lgkmcnt(0)
	s_barrier
; #define WAIT_V(n) asm volatile("s_waitcnt vmcnt(" #n ")" ::: "memory")
; #define WAIT_L(n) asm volatile("s_waitcnt lgkmcnt(" #n ")" ::: "memory")
; #define BAR __builtin_amdgcn_s_barrier()
; #define SCHED __builtin_amdgcn_sched_barrier(0)
; #define STG_A(b, h, kt) stage_half_s(lds0 + ((b) * 2 + (h)) * HT_B, ((h) ? A1 : Ap) + (kt) * BK, off0, off1)
; #define STG_B(b, h, kt) stage_half_s(lds0 + (4 + (b) * 2 + (h)) * HT_B, ((h) ? B1p : Bp) + (kt) * BK, off0, off1)
; #define STG_A(b, h, kt) stage_half_s(lds0 + ((b) * 2 + (h)) * HT_B, ((h) ? A1 : Ap) + (kt) * BK, off0, off1)
; #define STG_B(b, h, kt) stage_half_s(lds0 + (4 + (b) * 2 + (h)) * HT_B, ((h) ? B1p : Bp) + (kt) * BK, off0, off1)
; #define LDA8(b, h) _Pragma("unroll") for (int m = 0; m < 4; ++m) _Pragma("unroll") for (int k = 0; k < 2; ++k) \
;     At[m][k] = *(const bf16x8*)(SA_(shm, b, h) + abase + (m * 2 + k) * 1024)
; #define LDB8(dst, b, h) _Pragma("unroll") for (int n = 0; n < 2; ++n) _Pragma("unroll") for (int k = 0; k < 2; ++k) \
;     dst[n][k] = *(const bf16x8*)(SB_(shm, b, h) + bbase + (n * 2 + k) * 1024)
; template <bool HS>
; __device__ __forceinline__ void gemm_tile8(const u16* __restrict__ Ap, const u16* __restrict__ Bp, int K,
;                                            f32x4 (&acc)[2][2][4][2], char* shm, const int tid, const float* hsr = nullptr) {
;     ...
;     LDB8(B0, 0, 0); SCHED; LDA8(0, 0); STG_A(1, 1, t + 1);
;     WAIT_L(8); BAR; WAIT_L(0); MMA8(0, 0, B0); BAR; SCHED;
;     LDB8(B1, 0, 1); STG_B(0, 0, t + 2);
;     BAR; WAIT_L(0); MMA8(0, 1, B1); BAR;
;     LDA8(0, 1); STG_A(0, 0, t + 2);
;     BAR; WAIT_L(0); MMA8(1, 0, B0); BAR; SCHED;
;     STG_B(0, 1, t + 2);
;     WAIT_V(6); BAR; MMA8(1, 1, B1); BAR;
;     LDB8(B0, 1, 0); SCHED; LDA8(1, 0); STG_A(0, 1, t + 2);
;     WAIT_L(8); BAR; WAIT_L(0); MMA8(0, 0, B0); BAR; SCHED;
;     LDB8(B1, 1, 1); STG_B(1, 0, t + 3);
;     BAR; WAIT_L(0); MMA8(0, 1, B1); BAR;
;     LDA8(1, 1); STG_A(1, 0, t + 3);
;     BAR; WAIT_L(0); MMA8(1, 0, B0); BAR; SCHED;
;     STG_B(1, 1, t + 3);
;     WAIT_V(6); BAR; MMA8(1, 1, B1); BAR;
;   }
	s_setprio 1
	v_mfma_f32_16x16x32_bf16 v[62:65], v[162:165], v[146:149], 0
	v_mfma_f32_16x16x32_bf16 v[58:61], v[162:165], v[154:157], 0
	v_mfma_f32_16x16x32_bf16 v[54:57], v[170:173], v[146:149], 0
	v_mfma_f32_16x16x32_bf16 v[50:53], v[170:173], v[154:157], 0
	v_mfma_f32_16x16x32_bf16 v[46:49], v[180:183], v[146:149], 0
	v_mfma_f32_16x16x32_bf16 v[42:45], v[180:183], v[154:157], 0
	v_mfma_f32_16x16x32_bf16 v[38:41], v[188:191], v[146:149], 0
	v_mfma_f32_16x16x32_bf16 v[34:37], v[188:191], v[154:157], 0
	v_mfma_f32_16x16x32_bf16 v[62:65], v[166:169], v[150:153], v[62:65]
	v_mfma_f32_16x16x32_bf16 v[58:61], v[166:169], v[158:161], v[58:61]
	v_mfma_f32_16x16x32_bf16 v[54:57], v[174:177], v[150:153], v[54:57]
	v_mfma_f32_16x16x32_bf16 v[50:53], v[174:177], v[158:161], v[50:53]
	v_mfma_f32_16x16x32_bf16 v[46:49], v[184:187], v[150:153], v[46:49]
	v_mfma_f32_16x16x32_bf16 v[42:45], v[184:187], v[158:161], v[42:45]
	v_mfma_f32_16x16x32_bf16 v[38:41], v[192:195], v[150:153], v[38:41]
	v_mfma_f32_16x16x32_bf16 v[34:37], v[192:195], v[158:161], v[34:37]
	v_mfma_f32_16x16x32_bf16 v[30:33], v[162:165], v[196:199], 0
	v_mfma_f32_16x16x32_bf16 v[26:29], v[162:165], v[204:207], 0
	v_mfma_f32_16x16x32_bf16 v[22:25], v[170:173], v[196:199], 0
	v_mfma_f32_16x16x32_bf16 v[18:21], v[170:173], v[204:207], 0
	v_mfma_f32_16x16x32_bf16 v[14:17], v[180:183], v[196:199], 0
	v_mfma_f32_16x16x32_bf16 v[10:13], v[180:183], v[204:207], 0
	v_mfma_f32_16x16x32_bf16 v[6:9], v[188:191], v[196:199], 0
	v_mfma_f32_16x16x32_bf16 v[2:5], v[188:191], v[204:207], 0
	v_mfma_f32_16x16x32_bf16 v[30:33], v[166:169], v[200:203], v[30:33]
	v_mfma_f32_16x16x32_bf16 v[26:29], v[166:169], v[208:211], v[26:29]
	v_mfma_f32_16x16x32_bf16 v[22:25], v[174:177], v[200:203], v[22:25]
	v_mfma_f32_16x16x32_bf16 v[18:21], v[174:177], v[208:211], v[18:21]
	v_mfma_f32_16x16x32_bf16 v[14:17], v[184:187], v[200:203], v[14:17]
	v_mfma_f32_16x16x32_bf16 v[10:13], v[184:187], v[208:211], v[10:13]
	v_mfma_f32_16x16x32_bf16 v[6:9], v[192:195], v[200:203], v[6:9]
	v_mfma_f32_16x16x32_bf16 v[2:5], v[192:195], v[208:211], v[2:5]
	s_setprio 0
	s_barrier
	v_add_u32_e32 v158, 0x18000, v145
	ds_read_b128 v[146:149], v158
	ds_read_b128 v[150:153], v158 offset:1024
	ds_read_b128 v[154:157], v158 offset:2048
	ds_read_b128 v[158:161], v158 offset:3072
	ds_read_b128 v[162:165], v142 offset:32768
	ds_read_b128 v[166:169], v142 offset:33792
	ds_read_b128 v[170:173], v142 offset:34816
	ds_read_b128 v[174:177], v142 offset:35840
	ds_read_b128 v[180:183], v142 offset:36864
	ds_read_b128 v[184:187], v142 offset:37888
	ds_read_b128 v[188:191], v142 offset:38912
	ds_read_b128 v[192:195], v142 offset:39936
	v_add_u32_e32 v208, 0x1c000, v145
	ds_read_b128 v[196:199], v208
	ds_read_b128 v[200:203], v208 offset:1024
	ds_read_b128 v[204:207], v208 offset:2048
	ds_read_b128 v[208:211], v208 offset:3072
	s_add_u32 s0, s18, 0x100
	s_addc_u32 s1, s19, 0
	s_add_i32 s3, s7, 0x4000
	s_mov_b32 m0, s3
	s_nop 0
	global_load_lds_dwordx4 v144, s[0:1]
	s_add_i32 s3, s7, 0x6000
	s_mov_b32 m0, s3
	s_nop 0
	global_load_lds_dwordx4 v143, s[0:1]
	s_waitcnt vmcnt(8) lgkmcnt(0)
	s_barrier
	s_setprio 1
	v_mfma_f32_16x16x32_bf16 v[126:129], v[162:165], v[146:149], v[126:129]
	v_mfma_f32_16x16x32_bf16 v[122:125], v[162:165], v[154:157], v[122:125]
	v_mfma_f32_16x16x32_bf16 v[118:121], v[170:173], v[146:149], v[118:121]
	v_mfma_f32_16x16x32_bf16 v[114:117], v[170:173], v[154:157], v[114:117]
	v_mfma_f32_16x16x32_bf16 v[110:113], v[180:183], v[146:149], v[110:113]
	v_mfma_f32_16x16x32_bf16 v[106:109], v[180:183], v[154:157], v[106:109]
	v_mfma_f32_16x16x32_bf16 v[102:105], v[188:191], v[146:149], v[102:105]
	v_mfma_f32_16x16x32_bf16 v[98:101], v[188:191], v[154:157], v[98:101]
	v_mfma_f32_16x16x32_bf16 v[126:129], v[166:169], v[150:153], v[126:129]
	v_mfma_f32_16x16x32_bf16 v[122:125], v[166:169], v[158:161], v[122:125]
	v_mfma_f32_16x16x32_bf16 v[118:121], v[174:177], v[150:153], v[118:121]
	v_mfma_f32_16x16x32_bf16 v[114:117], v[174:177], v[158:161], v[114:117]
	v_mfma_f32_16x16x32_bf16 v[110:113], v[184:187], v[150:153], v[110:113]
	v_mfma_f32_16x16x32_bf16 v[106:109], v[184:187], v[158:161], v[106:109]
	v_mfma_f32_16x16x32_bf16 v[102:105], v[192:195], v[150:153], v[102:105]
	v_mfma_f32_16x16x32_bf16 v[98:101], v[192:195], v[158:161], v[98:101]
	v_mfma_f32_16x16x32_bf16 v[94:97], v[162:165], v[196:199], v[94:97]
	v_mfma_f32_16x16x32_bf16 v[90:93], v[162:165], v[204:207], v[90:93]
	v_mfma_f32_16x16x32_bf16 v[86:89], v[170:173], v[196:199], v[86:89]
	v_mfma_f32_16x16x32_bf16 v[82:85], v[170:173], v[204:207], v[82:85]
	v_mfma_f32_16x16x32_bf16 v[78:81], v[180:183], v[196:199], v[78:81]
	v_mfma_f32_16x16x32_bf16 v[74:77], v[180:183], v[204:207], v[74:77]
	v_mfma_f32_16x16x32_bf16 v[70:73], v[188:191], v[196:199], v[70:73]
	v_mfma_f32_16x16x32_bf16 v[66:69], v[188:191], v[204:207], v[66:69]
	v_mfma_f32_16x16x32_bf16 v[94:97], v[166:169], v[200:203], v[94:97]
	v_mfma_f32_16x16x32_bf16 v[90:93], v[166:169], v[208:211], v[90:93]
	v_mfma_f32_16x16x32_bf16 v[86:89], v[174:177], v[200:203], v[86:89]
	v_mfma_f32_16x16x32_bf16 v[82:85], v[174:177], v[208:211], v[82:85]
	v_mfma_f32_16x16x32_bf16 v[78:81], v[184:187], v[200:203], v[78:81]
	v_mfma_f32_16x16x32_bf16 v[74:77], v[184:187], v[208:211], v[74:77]
	v_mfma_f32_16x16x32_bf16 v[70:73], v[192:195], v[200:203], v[70:73]
	v_mfma_f32_16x16x32_bf16 v[66:69], v[192:195], v[208:211], v[66:69]
	s_setprio 0
	s_barrier
; #define WAIT_V(n) asm volatile("s_waitcnt vmcnt(" #n ")" ::: "memory")
; #define WAIT_L(n) asm volatile("s_waitcnt lgkmcnt(" #n ")" ::: "memory")
; #define BAR __builtin_amdgcn_s_barrier()
; #define SCHED __builtin_amdgcn_sched_barrier(0)
; #define STG_A(b, h, kt) stage_half_s(lds0 + ((b) * 2 + (h)) * HT_B, ((h) ? A1 : Ap) + (kt) * BK, off0, off1)
; #define STG_B(b, h, kt) stage_half_s(lds0 + (4 + (b) * 2 + (h)) * HT_B, ((h) ? B1p : Bp) + (kt) * BK, off0, off1)
; #define STG_A(b, h, kt) stage_half_s(lds0 + ((b) * 2 + (h)) * HT_B, ((h) ? A1 : Ap) + (kt) * BK, off0, off1)
; #define STG_B(b, h, kt) stage_half_s(lds0 + (4 + (b) * 2 + (h)) * HT_B, ((h) ? B1p : Bp) + (kt) * BK, off0, off1)
; #define LDA8(b, h) _Pragma("unroll") for (int m = 0; m < 4; ++m) _Pragma("unroll") for (int k = 0; k < 2; ++k) \
;     At[m][k] = *(const bf16x8*)(SA_(shm, b, h) + abase + (m * 2 + k) * 1024)
; #define LDB8(dst, b, h) _Pragma("unroll") for (int n = 0; n < 2; ++n) _Pragma("unroll") for (int k = 0; k < 2; ++k) \
;     dst[n][k] = *(const bf16x8*)(SB_(shm, b, h) + bbase + (n * 2 + k) * 1024)
; template <bool HS>
; __device__ __forceinline__ void gemm_tile8(const u16* __restrict__ Ap, const u16* __restrict__ Bp, int K,
;                                            f32x4 (&acc)[2][2][4][2], char* shm, const int tid, const float* hsr = nullptr) {
;     ...
;     LDB8(B0, 0, 0); SCHED; LDA8(0, 0); STG_A(1, 1, t + 1);
;     WAIT_L(8); BAR; WAIT_L(0); MMA8(0, 0, B0); BAR; SCHED;
;     LDB8(B1, 0, 1); STG_B(0, 0, t + 2);
;     BAR; WAIT_L(0); MMA8(0, 1, B1); BAR;
;     LDA8(0, 1); STG_A(0, 0, t + 2);
;     BAR; WAIT_L(0); MMA8(1, 0, B0); BAR; SCHED;
;     STG_B(0, 1, t + 2);
;     WAIT_V(6); BAR; MMA8(1, 1, B1); BAR;
;     LDB8(B0, 1, 0); SCHED; LDA8(1, 0); STG_A(0, 1, t + 2);
;     WAIT_L(8); BAR; WAIT_L(0); MMA8(0, 0, B0); BAR; SCHED;
;     LDB8(B1, 1, 1); STG_B(1, 0, t + 3);
;     BAR; WAIT_L(0); MMA8(0, 1, B1); BAR;
;     LDA8(1, 1); STG_A(1, 0, t + 3);
;     BAR; WAIT_L(0); MMA8(1, 0, B0); BAR; SCHED;
;     STG_B(1, 1, t + 3);
;     WAIT_V(6); BAR; MMA8(1, 1, B1); BAR;
;   }
	ds_read_b128 v[162:165], v142 offset:49152
	ds_read_b128 v[166:169], v142 offset:50176
	ds_read_b128 v[170:173], v142 offset:51200
	ds_read_b128 v[174:177], v142 offset:52224
	ds_read_b128 v[180:183], v142 offset:53248
	ds_read_b128 v[184:187], v142 offset:54272
	ds_read_b128 v[188:191], v142 offset:55296
	ds_read_b128 v[192:195], v142 offset:56320
	s_add_u32 s0, s20, 0x180
	s_addc_u32 s1, s21, 0
	s_add_i32 s3, s7, 0x18000
	s_mov_b32 m0, s3
	s_nop 0
	global_load_lds_dwordx4 v144, s[0:1]
	s_add_i32 s3, s7, 0x1a000
	s_mov_b32 m0, s3
	s_nop 0
	global_load_lds_dwordx4 v143, s[0:1]
	s_add_u32 s0, s16, 0x180
	s_addc_u32 s1, s17, 0
	s_add_i32 s3, s7, 0x8000
	s_mov_b32 m0, s3
	s_nop 0
	global_load_lds_dwordx4 v144, s[0:1]
	s_add_i32 s3, s7, 0xa000
	s_mov_b32 m0, s3
	s_nop 0
	global_load_lds_dwordx4 v143, s[0:1]
	s_add_u32 s0, s22, 0x180
	s_addc_u32 s1, s23, 0
	s_add_i32 s3, s7, 0x1c000
	s_mov_b32 m0, s3
	s_nop 0
	global_load_lds_dwordx4 v144, s[0:1]
	s_add_i32 s3, s7, 0x1e000
	s_mov_b32 m0, s3
	s_nop 0
	global_load_lds_dwordx4 v143, s[0:1]
	s_waitcnt vmcnt(8) lgkmcnt(0)
	s_barrier
	s_setprio 1
	v_mfma_f32_16x16x32_bf16 v[62:65], v[162:165], v[146:149], v[62:65]
	v_mfma_f32_16x16x32_bf16 v[58:61], v[162:165], v[154:157], v[58:61]
	v_mfma_f32_16x16x32_bf16 v[54:57], v[170:173], v[146:149], v[54:57]
	v_mfma_f32_16x16x32_bf16 v[50:53], v[170:173], v[154:157], v[50:53]
	v_mfma_f32_16x16x32_bf16 v[46:49], v[180:183], v[146:149], v[46:49]
	v_mfma_f32_16x16x32_bf16 v[42:45], v[180:183], v[154:157], v[42:45]
	v_mfma_f32_16x16x32_bf16 v[38:41], v[188:191], v[146:149], v[38:41]
	v_mfma_f32_16x16x32_bf16 v[34:37], v[188:191], v[154:157], v[34:37]
	v_mfma_f32_16x16x32_bf16 v[62:65], v[166:169], v[150:153], v[62:65]
	v_mfma_f32_16x16x32_bf16 v[58:61], v[166:169], v[158:161], v[58:61]
	v_mfma_f32_16x16x32_bf16 v[54:57], v[174:177], v[150:153], v[54:57]
	v_mfma_f32_16x16x32_bf16 v[50:53], v[174:177], v[158:161], v[50:53]
	v_mfma_f32_16x16x32_bf16 v[46:49], v[184:187], v[150:153], v[46:49]
	v_mfma_f32_16x16x32_bf16 v[42:45], v[184:187], v[158:161], v[42:45]
	v_mfma_f32_16x16x32_bf16 v[38:41], v[192:195], v[150:153], v[38:41]
	v_mfma_f32_16x16x32_bf16 v[34:37], v[192:195], v[158:161], v[34:37]
	v_mfma_f32_16x16x32_bf16 v[30:33], v[162:165], v[196:199], v[30:33]
	v_mfma_f32_16x16x32_bf16 v[26:29], v[162:165], v[204:207], v[26:29]
	v_mfma_f32_16x16x32_bf16 v[22:25], v[170:173], v[196:199], v[22:25]
	v_mfma_f32_16x16x32_bf16 v[18:21], v[170:173], v[204:207], v[18:21]
	v_mfma_f32_16x16x32_bf16 v[14:17], v[180:183], v[196:199], v[14:17]
	v_mfma_f32_16x16x32_bf16 v[10:13], v[180:183], v[204:207], v[10:13]
	v_mfma_f32_16x16x32_bf16 v[6:9], v[188:191], v[196:199], v[6:9]
	v_mfma_f32_16x16x32_bf16 v[2:5], v[188:191], v[204:207], v[2:5]
	v_mfma_f32_16x16x32_bf16 v[30:33], v[166:169], v[200:203], v[30:33]
	v_mfma_f32_16x16x32_bf16 v[26:29], v[166:169], v[208:211], v[26:29]
	v_mfma_f32_16x16x32_bf16 v[22:25], v[174:177], v[200:203], v[22:25]
	v_mfma_f32_16x16x32_bf16 v[18:21], v[174:177], v[208:211], v[18:21]
	v_mfma_f32_16x16x32_bf16 v[14:17], v[184:187], v[200:203], v[14:17]
	v_mfma_f32_16x16x32_bf16 v[10:13], v[184:187], v[208:211], v[10:13]
	v_mfma_f32_16x16x32_bf16 v[6:9], v[192:195], v[200:203], v[6:9]
	v_mfma_f32_16x16x32_bf16 v[2:5], v[192:195], v[208:211], v[2:5]
	s_setprio 0
	s_add_u32 s16, s16, 0x100
	s_addc_u32 s17, s17, 0
	s_add_u32 s18, s18, 0x100
	s_addc_u32 s19, s19, 0
	s_add_u32 s20, s20, 0x100
	s_addc_u32 s21, s21, 0
	s_add_u32 s22, s22, 0x100
	s_addc_u32 s23, s23, 0
	s_mov_b32 s14, 6
	s_barrier

; #define STG_A(b, h, kt) stage_half_s(lds0 + ((b) * 2 + (h)) * HT_B, ((h) ? A1 : Ap) + (kt) * BK, off0, off1)
; #define STG_B(b, h, kt) stage_half_s(lds0 + (4 + (b) * 2 + (h)) * HT_B, ((h) ? B1p : Bp) + (kt) * BK, off0, off1)
; #define STG_A(b, h, kt) stage_half_s(lds0 + ((b) * 2 + (h)) * HT_B, ((h) ? A1 : Ap) + (kt) * BK, off0, off1)
; #define STG_B(b, h, kt) stage_half_s(lds0 + (4 + (b) * 2 + (h)) * HT_B, ((h) ? B1p : Bp) + (kt) * BK, off0, off1)
; __device__ __forceinline__ void gemm8_prefetch(const u16* __restrict__ Ap, const u16* __restrict__ Bp, int K, char* shm, const int tid) {
;   int r0, c0, r1, c1;
;   stage_rc(tid * 16, r0, c0);
;   stage_rc(tid * 16 + 8192, r1, c1);
;   const unsigned off0 = (unsigned)(r0 * K + c0) * 2u, off1 = (unsigned)(r1 * K + c1) * 2u;
;   const int wvoff = __builtin_amdgcn_readfirstlane(tid >> 6) * 1024;
;   const u16* A1 = Ap + (size_t)128 * K;
;   const u16* B1p = Bp + (size_t)128 * K;
;   const unsigned lds0 = (unsigned)(size_t)(__attribute__((address_space(3))) char*)shm + (unsigned)wvoff;
;     ...
;   STG_B(0, 0, 0); STG_A(0, 0, 0); STG_B(0, 1, 0); STG_A(0, 1, 0);
;   STG_B(1, 0, 1); STG_A(1, 0, 1); STG_B(1, 1, 1);
;     ...
; }
; template <int EPI, bool HS = false>
; __device__ __forceinline__ void gemm_phase(const Params& p, const GemmCfg& g, char* shm, const int wave_s) {
;     ...
;     if (!defer_pf && tile + (int)gridDim.x < nwg) {
;       int mt2, pn2, arow2, orow2;
;       tile_coords(tile + gridDim.x, mt2, pn2, arow2, orow2);
;       gemm8_prefetch(g.A + (size_t)arow2 * g.K, g.Bt + (size_t)pn2 * 256 * g.K, g.K, shm, fresh_tid(wave_s));
;     }
.LBB0_862:
	s_or_b64 exec, exec, s[0:1]
	s_add_i32 s8, s8, s44
	s_cmpk_gt_i32 s8, 0x15ff
	s_cselect_b64 s[0:1], -1, 0
	s_and_b64 vcc, exec, s[0:1]
	s_cbranch_vccnz .LBB0_853
	s_ashr_i32 s3, s8, 31
	s_lshr_b32 s3, s3, 29
	s_add_i32 s3, s8, s3
	s_ashr_i32 s5, s3, 3
	s_and_b32 s3, s3, -8
	s_sub_i32 s3, s8, s3
	s_cmp_lt_i32 s3, 0
	s_movk_i32 s6, 0x2c1
	s_cselect_b32 s6, s6, 0x2c0
	s_mul_i32 s3, s6, s3
	s_add_i32 s3, s3, s5
	s_mul_hi_i32 s5, s3, 0x2e8ba2e9
	s_lshr_b32 s6, s5, 31
	s_ashr_i32 s5, s5, 5
	s_add_i32 s5, s5, s6
	s_mul_i32 s6, s5, 0xb0
	s_sub_i32 s3, s3, s6
	s_bfe_u32 s6, s3, 0x3001c
	s_add_i32 s6, s3, s6
	s_sext_i32_i16 s7, s6
	s_and_b32 s6, s6, 0xfff8
	s_sub_i32 s3, s3, s6
	s_sext_i32_i16 s3, s3
	s_lshl_b32 s5, s5, 11
	s_lshl_b32 s3, s3, 8
	s_add_i32 s6, s3, s5
	s_mov_b32 s3, s82
	s_mov_b32 s5, -1
	s_lshr_b32 s10, s7, 3
	v_mbcnt_lo_u32_b32 v0, s5, 0
	v_mbcnt_hi_u32_b32 v0, s5, v0
	v_lshl_add_u32 v0, s3, 6, v0
	s_ashr_i32 s7, s6, 31
	s_lshl_b64 s[6:7], s[6:7], 11
	s_add_u32 s6, s88, s6
	s_addc_u32 s7, s89, s7
	s_bfe_i64 s[10:11], s[10:11], 0x100000
	s_lshl_b64 s[10:11], s[10:11], 19
	v_lshl_add_u64 v[130:131], v[134:135], 0, s[10:11]
	v_readfirstlane_b32 s3, v0
	s_add_u32 s10, s6, 0x40000
	s_addc_u32 s11, s7, 0
	s_lshl_b32 s3, s3, 4
	s_and_b32 s3, s3, 0xfffffc00
	s_mov_b64 s[12:13], 0x40000
	s_add_i32 s3, s3, 0
	v_lshl_add_u64 v[132:133], v[130:131], 0, s[12:13]
	v_readfirstlane_b32 s13, v131
	v_readfirstlane_b32 s12, v130
	s_add_i32 s5, s3, 0x10000
	s_mov_b32 m0, s5
	s_nop 2
	global_load_lds_dwordx4 v241, s[12:13]
	s_add_i32 s5, s3, 0x12000
	s_mov_b32 m0, s5
	s_nop 0
	global_load_lds_dwordx4 v240, s[12:13]
	s_mov_b32 m0, s3
	s_nop 0
	global_load_lds_dwordx4 v241, s[6:7]
	s_add_i32 s5, s3, 0x2000
	s_mov_b32 m0, s5
	s_nop 0
	global_load_lds_dwordx4 v240, s[6:7]
	v_readfirstlane_b32 s13, v133
	v_readfirstlane_b32 s12, v132
	s_add_i32 s5, s3, 0x14000
	s_mov_b32 m0, s5
	s_nop 2
	global_load_lds_dwordx4 v241, s[12:13]
	s_add_i32 s5, s3, 0x16000
	s_mov_b32 m0, s5
	s_nop 0
	global_load_lds_dwordx4 v240, s[12:13]
	s_add_i32 s5, s3, 0x4000
	s_mov_b32 m0, s5
	s_nop 0
	global_load_lds_dwordx4 v241, s[10:11]
	s_add_i32 s5, s3, 0x6000
	s_mov_b32 m0, s5
	s_nop 0
	global_load_lds_dwordx4 v240, s[10:11]
	s_mov_b64 s[10:11], 0x80
	v_lshl_add_u64 v[132:133], v[130:131], 0, s[10:11]
	s_add_i32 s5, s3, 0x18000
	v_readfirstlane_b32 s11, v133
	v_readfirstlane_b32 s10, v132
	s_mov_b32 m0, s5
	s_nop 3
	global_load_lds_dwordx4 v241, s[10:11]
	s_add_i32 s5, s3, 0x1a000
	s_mov_b32 m0, s5
	s_nop 0
	global_load_lds_dwordx4 v240, s[10:11]
	s_add_u32 s6, s6, 0x80
	s_addc_u32 s7, s7, 0
	s_add_i32 s5, s3, 0x8000
	s_mov_b32 m0, s5
	s_nop 0
	global_load_lds_dwordx4 v241, s[6:7]
	s_add_i32 s5, s3, 0xa000
	s_mov_b32 m0, s5
	s_nop 0
	global_load_lds_dwordx4 v240, s[6:7]
	s_mov_b64 s[6:7], 0x40080
	v_lshl_add_u64 v[130:131], v[130:131], 0, s[6:7]
	s_add_i32 s5, s3, 0x1c000
	v_readfirstlane_b32 s7, v131
	v_readfirstlane_b32 s6, v130
	s_mov_b32 m0, s5
	s_nop 3
	global_load_lds_dwordx4 v241, s[6:7]
	s_add_i32 s3, s3, 0x1e000
	s_mov_b32 m0, s3
	s_nop 0
	global_load_lds_dwordx4 v240, s[6:7]
	s_branch .LBB0_853

; __device__ __forceinline__ unsigned pack2(float a, float b) { return (unsigned)f2bf(a) | ((unsigned)f2bf(b) << 16); }
; __device__ __forceinline__ void prep_phase(const Params& p, char* shm, const int tid) {
;     ...
;       char* shb = (char*)shl;
;       const float* mp = p.mod + (size_t)l * 16 * 9216 + sub * 3072;
;       for (int pi = tid; pi < 16 * 512; pi += 512) {
;         int b = pi >> 9, k = (pi & 511) * 2;
;         float2 mv = *(const float2*)(mp + (size_t)b * 9216 + k);
;         *(unsigned*)(shb + b * 2064 + k * 2) = pack2(mv.x, mv.y);
;       }
.LBB0_880:
	v_ashrrev_i32_e32 v11, 9, v2
	v_lshlrev_b32_e32 v12, 1, v2
	v_ashrrev_i32_e32 v5, 9, v3
	v_lshlrev_b32_e32 v0, 1, v3
	v_and_b32_e32 v17, 0x3fe, v12
	v_mul_hi_i32_i24_e32 v13, 0x9000, v11
	v_mul_i32_i24_e32 v12, 0x9000, v11
	v_and_b32_e32 v16, 0x3fe, v0
	v_mul_hi_i32_i24_e32 v15, 0x9000, v5
	v_mul_i32_i24_e32 v14, 0x9000, v5
	v_lshl_add_u64 v[12:13], s[68:69], 0, v[12:13]
	v_lshlrev_b32_e32 v0, 2, v17
	v_lshl_add_u64 v[14:15], s[68:69], 0, v[14:15]
	v_lshl_add_u64 v[12:13], v[12:13], 0, v[0:1]
	v_lshlrev_b32_e32 v0, 2, v16
	global_load_dwordx2 v[12:13], v[12:13], off
	v_lshl_add_u64 v[14:15], v[14:15], 0, v[0:1]
	global_load_dwordx2 v[14:15], v[14:15], off
	v_mul_i32_i24_e32 v0, 0x810, v11
	v_mul_i32_i24_e32 v5, 0x810, v5
	v_lshlrev_b32_e32 v11, 1, v16
	v_lshlrev_b32_e32 v16, 1, v17
	v_add3_u32 v0, 0, v0, v16
	v_add3_u32 v5, 0, v5, v11
	v_add_u32_e32 v4, -2, v4
	v_cmp_eq_u32_e32 vcc, 0, v4
	v_add_u32_e32 v3, 0x400, v3
	v_add_u32_e32 v2, 0x400, v2
	s_or_b64 s[72:73], vcc, s[72:73]
	s_waitcnt vmcnt(1)
	s_nop 0
	v_and_b32_sdwa v16, v13, v178 dst_sel:DWORD dst_unused:UNUSED_PAD src0_sel:WORD_1 src1_sel:DWORD
	v_cvt_pk_bf16_f32 v11, v12, v12
	s_waitcnt vmcnt(0)
	s_nop 0
	v_add3_u32 v13, v13, v16, s81
	v_and_b32_sdwa v17, v14, v178 dst_sel:DWORD dst_unused:UNUSED_PAD src0_sel:WORD_1 src1_sel:DWORD
	v_cvt_pk_bf16_f32 v12, v15, v15
	v_and_b32_e32 v13, 0xffff0000, v13
	v_add3_u32 v14, v14, v17, s81
	v_and_b32_e32 v12, 0xffff0000, v12
	v_or_b32_sdwa v11, v13, v11 dst_sel:DWORD dst_unused:UNUSED_PAD src0_sel:DWORD src1_sel:WORD_1
	v_or_b32_sdwa v12, v12, v14 dst_sel:DWORD dst_unused:UNUSED_PAD src0_sel:DWORD src1_sel:WORD_1
	ds_write_b32 v0, v11
	ds_write_b32 v5, v12
	s_andn2_b64 exec, exec, s[72:73]
	s_cbranch_execnz .LBB0_880
	s_or_b64 exec, exec, s[72:73]
	s_orn2_b64 s[72:73], s[6:7], exec
	v_mov_b32_e32 v2, v26

; __device__ __forceinline__ unsigned pack2(float a, float b) { return (unsigned)f2bf(a) | ((unsigned)f2bf(b) << 16); }
; __device__ __forceinline__ void prep_phase(const Params& p, char* shm, const int tid) {
;     ...
; #pragma unroll
;       for (int i = 0; i < 4; ++i) {
;         int col = (lane + 64 * i) * 4;
;         f32x4 gg = *(const f32x4*)(g + col), s4 = *(const f32x4*)(sc + col);
;         uint2 pk;
;         pk.x = pack2(v[q][i][0] * gg[0] * (1.0f + s4[0]), v[q][i][1] * gg[1] * (1.0f + s4[1]));
;         pk.y = pack2(v[q][i][2] * gg[2] * (1.0f + s4[2]), v[q][i][3] * gg[3] * (1.0f + s4[3]));
;         *(uint2*)(p.h + (size_t)row * 1024 + col) = pk;
;       }
.LBB0_892:
	s_or_b64 exec, exec, s[8:9]
	global_load_dwordx4 v[18:21], v[36:37], off
	s_nop 0
	global_load_dwordx4 v[50:53], v[50:51], off
	v_lshlrev_b64 v[24:25], 11, v[24:25]
	v_lshl_add_u64 v[24:25], v[42:43], 0, v[24:25]
	v_readlane_b32 s8, v253, 18
	s_waitcnt vmcnt(1)
	v_pk_mul_f32 v[16:17], v[16:17], v[20:21]
	v_pk_mul_f32 v[14:15], v[14:15], v[18:19]
	s_waitcnt vmcnt(0)
	v_mov_b32_e32 v19, v52
	v_mov_b32_e32 v52, v51
	v_mov_b32_e32 v18, v50
	v_mov_b32_e32 v20, v14
	v_mov_b32_e32 v21, v16
	v_mov_b32_e32 v16, v15
	v_pk_add_f32 v[14:15], v[52:53], 1.0 op_sel_hi:[1,0]
	v_pk_add_f32 v[18:19], v[18:19], 1.0 op_sel_hi:[1,0]
	v_pk_mul_f32 v[14:15], v[16:17], v[14:15]
	v_pk_mul_f32 v[18:19], v[20:21], v[18:19]
	s_nop 0
	s_nop 0
	s_nop 0
	s_nop 0
	v_cvt_pk_bf16_f32 v15, v15, v15
	v_cvt_pk_bf16_f32 v14, v14, v14
	v_cvt_pk_bf16_f32 v17, v18, v18
	v_cvt_pk_bf16_f32 v16, v19, v19
	v_and_b32_e32 v15, 0xffff0000, v15
	v_and_b32_e32 v14, 0xffff0000, v14
	v_or_b32_sdwa v15, v15, v16 dst_sel:DWORD dst_unused:UNUSED_PAD src0_sel:DWORD src1_sel:WORD_1
	v_or_b32_sdwa v14, v14, v17 dst_sel:DWORD dst_unused:UNUSED_PAD src0_sel:DWORD src1_sel:WORD_1
	global_store_dwordx2 v[24:25], v[14:15], off
	global_load_dwordx4 v[14:17], v[36:37], off offset:1024
	s_nop 0
	global_load_dwordx4 v[18:21], v[30:31], off
	v_add_u32_e32 v34, s8, v34
	s_mov_b32 s8, 0xffff
	v_cmp_lt_i32_e32 vcc, s8, v34
	s_or_b64 s[2:3], vcc, s[2:3]
	s_waitcnt vmcnt(1)
	v_pk_mul_f32 v[12:13], v[12:13], v[16:17]
	v_pk_mul_f32 v[10:11], v[10:11], v[14:15]
	s_waitcnt vmcnt(0)
	v_mov_b32_e32 v15, v20
	v_mov_b32_e32 v20, v19
	v_mov_b32_e32 v14, v18
	v_mov_b32_e32 v16, v10
	v_mov_b32_e32 v17, v12
	v_mov_b32_e32 v12, v11
	v_pk_add_f32 v[10:11], v[20:21], 1.0 op_sel_hi:[1,0]
	v_pk_add_f32 v[14:15], v[14:15], 1.0 op_sel_hi:[1,0]
	v_pk_mul_f32 v[10:11], v[12:13], v[10:11]
	v_pk_mul_f32 v[14:15], v[16:17], v[14:15]
	s_nop 0
	s_nop 0
	s_nop 0
	s_nop 0
	v_cvt_pk_bf16_f32 v11, v11, v11
	v_cvt_pk_bf16_f32 v10, v10, v10
	v_cvt_pk_bf16_f32 v13, v14, v14
	v_cvt_pk_bf16_f32 v12, v15, v15
	v_and_b32_e32 v11, 0xffff0000, v11
	v_and_b32_e32 v10, 0xffff0000, v10
	v_or_b32_sdwa v11, v11, v12 dst_sel:DWORD dst_unused:UNUSED_PAD src0_sel:DWORD src1_sel:WORD_1
	v_or_b32_sdwa v10, v10, v13 dst_sel:DWORD dst_unused:UNUSED_PAD src0_sel:DWORD src1_sel:WORD_1
	global_store_dwordx2 v[24:25], v[10:11], off offset:512
	global_load_dwordx4 v[10:13], v[36:37], off offset:2048
	s_nop 0
	global_load_dwordx4 v[14:17], v[26:27], off
	s_waitcnt vmcnt(1)
	v_pk_mul_f32 v[8:9], v[8:9], v[12:13]
	v_pk_mul_f32 v[6:7], v[6:7], v[10:11]
	s_waitcnt vmcnt(0)
	v_mov_b32_e32 v11, v16
	v_mov_b32_e32 v16, v15
	v_mov_b32_e32 v10, v14
	v_mov_b32_e32 v12, v6
	v_mov_b32_e32 v13, v8
	v_mov_b32_e32 v8, v7
	v_pk_add_f32 v[6:7], v[16:17], 1.0 op_sel_hi:[1,0]
	v_pk_add_f32 v[10:11], v[10:11], 1.0 op_sel_hi:[1,0]
	v_pk_mul_f32 v[6:7], v[8:9], v[6:7]
	v_pk_mul_f32 v[10:11], v[12:13], v[10:11]
	s_nop 0
	s_nop 0
	s_nop 0
	s_nop 0
	v_cvt_pk_bf16_f32 v7, v7, v7
	v_cvt_pk_bf16_f32 v6, v6, v6
	v_cvt_pk_bf16_f32 v9, v10, v10
	v_cvt_pk_bf16_f32 v8, v11, v11
	v_and_b32_e32 v7, 0xffff0000, v7
	v_and_b32_e32 v6, 0xffff0000, v6
	v_or_b32_sdwa v7, v7, v8 dst_sel:DWORD dst_unused:UNUSED_PAD src0_sel:DWORD src1_sel:WORD_1
	v_or_b32_sdwa v6, v6, v9 dst_sel:DWORD dst_unused:UNUSED_PAD src0_sel:DWORD src1_sel:WORD_1
	global_store_dwordx2 v[24:25], v[6:7], off offset:1024
	global_load_dwordx4 v[6:9], v[36:37], off offset:3072
	s_nop 0
	global_load_dwordx4 v[10:13], v[22:23], off
	s_waitcnt vmcnt(1)
	v_pk_mul_f32 v[4:5], v[4:5], v[8:9]
	v_pk_mul_f32 v[2:3], v[2:3], v[6:7]
	s_waitcnt vmcnt(0)
	v_mov_b32_e32 v7, v12
	v_mov_b32_e32 v12, v11
	v_mov_b32_e32 v6, v10
	v_mov_b32_e32 v8, v2
	v_mov_b32_e32 v9, v4
	v_mov_b32_e32 v4, v3
	v_pk_add_f32 v[2:3], v[12:13], 1.0 op_sel_hi:[1,0]
	v_pk_add_f32 v[6:7], v[6:7], 1.0 op_sel_hi:[1,0]
	v_pk_mul_f32 v[2:3], v[4:5], v[2:3]
	v_pk_mul_f32 v[6:7], v[8:9], v[6:7]
	v_and_b32_sdwa v8, v3, v178 dst_sel:DWORD dst_unused:UNUSED_PAD src0_sel:WORD_1 src1_sel:DWORD
	v_and_b32_sdwa v9, v2, v178 dst_sel:DWORD dst_unused:UNUSED_PAD src0_sel:WORD_1 src1_sel:DWORD
	v_and_b32_sdwa v4, v7, v178 dst_sel:DWORD dst_unused:UNUSED_PAD src0_sel:WORD_1 src1_sel:DWORD
	v_and_b32_sdwa v5, v6, v178 dst_sel:DWORD dst_unused:UNUSED_PAD src0_sel:WORD_1 src1_sel:DWORD
	v_add3_u32 v3, v3, v8, s81
	v_add3_u32 v2, v2, v9, s81
	v_add3_u32 v5, v6, v5, s81
	v_add3_u32 v4, v7, v4, s81
	v_and_b32_e32 v3, 0xffff0000, v3
	v_and_b32_e32 v2, 0xffff0000, v2
	v_or_b32_sdwa v3, v3, v4 dst_sel:DWORD dst_unused:UNUSED_PAD src0_sel:DWORD src1_sel:WORD_1
	v_or_b32_sdwa v2, v2, v5 dst_sel:DWORD dst_unused:UNUSED_PAD src0_sel:DWORD src1_sel:WORD_1
	global_store_dwordx2 v[24:25], v[2:3], off offset:1536
	s_andn2_b64 exec, exec, s[2:3]
	s_cbranch_execz .LBB0_897

; __device__ __forceinline__ unsigned pack2(float a, float b) { return (unsigned)f2bf(a) | ((unsigned)f2bf(b) << 16); }
; __device__ __forceinline__ void prep_phase(const Params& p, char* shm, const int tid) {
;     ...
;     for (int q = 0; q < 2; ++q) {
;       const int row = row0 + q;
;       float ss = 0.f;
; #pragma unroll
;       for (int i = 0; i < 4; ++i) ss += v[q][i][0] * v[q][i][0] + v[q][i][1] * v[q][i][1] + v[q][i][2] * v[q][i][2] + v[q][i][3] * v[q][i][3];
;       ss = wave_sum(ss, lane);
;       if (lane < 16) p.rowss[(size_t)row * 16 + lane] = (lane == 0) ? ss : 0.0f;
; #pragma unroll
;       for (int i = 0; i < 4; ++i) {
;         int col = (lane + 64 * i) * 4;
;         f32x4 gg = *(const f32x4*)(g + col), s4 = *(const f32x4*)(sc + col);
;         uint2 pk;
;         pk.x = pack2(v[q][i][0] * gg[0] * (1.0f + s4[0]), v[q][i][1] * gg[1] * (1.0f + s4[1]));
;         pk.y = pack2(v[q][i][2] * gg[2] * (1.0f + s4[2]), v[q][i][3] * gg[3] * (1.0f + s4[3]));
;         *(uint2*)(p.h + (size_t)row * 1024 + col) = pk;
;       }
.LBB0_895:
	s_or_b64 exec, exec, s[8:9]
	v_ashrrev_i32_e32 v45, 12, v34
	v_readlane_b32 s8, v252, 26
	v_mul_hi_i32_i24_e32 v51, 0x9000, v45
	v_mul_i32_i24_e32 v50, 0x9000, v45
	v_readlane_b32 s9, v252, 27
	v_readlane_b32 s18, v252, 36
	v_readlane_b32 s19, v252, 37
	s_mov_b64 s[8:9], 0x1000
	global_load_dwordx4 v[60:63], v[36:37], off
	v_lshl_add_u64 v[50:51], s[18:19], 0, v[50:51]
	v_lshl_add_u64 v[68:69], v[50:51], 0, s[8:9]
	v_lshl_add_u64 v[50:51], v[68:69], 0, v[0:1]
	global_load_dwordx4 v[64:67], v[50:51], off
	v_lshlrev_b64 v[52:53], 11, v[34:35]
	v_mov_b32_e32 v45, v1
	v_lshl_add_u64 v[52:53], v[42:43], 0, v[52:53]
	v_readlane_b32 s10, v252, 28
	v_readlane_b32 s11, v252, 29
	v_readlane_b32 s12, v252, 30
	v_readlane_b32 s13, v252, 31
	v_readlane_b32 s14, v252, 32
	v_readlane_b32 s15, v252, 33
	v_readlane_b32 s16, v252, 34
	v_readlane_b32 s17, v252, 35
	v_readlane_b32 s20, v252, 38
	v_readlane_b32 s21, v252, 39
	v_readlane_b32 s22, v252, 40
	v_readlane_b32 s23, v252, 41
	s_waitcnt vmcnt(1)
	v_pk_mul_f32 v[32:33], v[32:33], v[62:63]
	v_pk_mul_f32 v[30:31], v[30:31], v[60:61]
	v_mov_b32_e32 v61, v32
	v_mov_b32_e32 v32, v31
	s_waitcnt vmcnt(0)
	v_mov_b32_e32 v31, v66
	v_mov_b32_e32 v66, v65
	v_mov_b32_e32 v60, v30
	v_mov_b32_e32 v30, v64
	v_pk_add_f32 v[62:63], v[66:67], 1.0 op_sel_hi:[1,0]
	v_pk_add_f32 v[30:31], v[30:31], 1.0 op_sel_hi:[1,0]
	v_pk_mul_f32 v[32:33], v[32:33], v[62:63]
	v_pk_mul_f32 v[30:31], v[60:61], v[30:31]
	s_nop 0
	s_nop 0
	s_nop 0
	s_waitcnt lgkmcnt(0)
	s_nop 0
	v_cvt_pk_bf16_f32 v33, v33, v33
	v_cvt_pk_bf16_f32 v32, v32, v32
	v_cvt_pk_bf16_f32 v30, v30, v30
	v_cvt_pk_bf16_f32 v31, v31, v31
	v_and_b32_e32 v33, 0xffff0000, v33
	v_and_b32_e32 v32, 0xffff0000, v32
	v_or_b32_sdwa v31, v33, v31 dst_sel:DWORD dst_unused:UNUSED_PAD src0_sel:DWORD src1_sel:WORD_1
	v_or_b32_sdwa v30, v32, v30 dst_sel:DWORD dst_unused:UNUSED_PAD src0_sel:DWORD src1_sel:WORD_1
	global_store_dwordx2 v[52:53], v[30:31], off
	v_lshl_add_u64 v[30:31], v[68:69], 0, v[44:45]
	global_load_dwordx4 v[60:63], v[36:37], off offset:1024
	global_load_dwordx4 v[64:67], v[30:31], off
	v_mov_b32_e32 v47, v1
	v_mov_b32_e32 v49, v1
	s_waitcnt vmcnt(1)
	v_pk_mul_f32 v[28:29], v[28:29], v[62:63]
	v_pk_mul_f32 v[26:27], v[26:27], v[60:61]
	s_waitcnt vmcnt(0)
	v_mov_b32_e32 v33, v66
	v_mov_b32_e32 v66, v65
	v_mov_b32_e32 v32, v64
	v_mov_b32_e32 v60, v26
	v_mov_b32_e32 v61, v28
	v_mov_b32_e32 v28, v27
	v_pk_add_f32 v[26:27], v[66:67], 1.0 op_sel_hi:[1,0]
	v_pk_add_f32 v[32:33], v[32:33], 1.0 op_sel_hi:[1,0]
	v_pk_mul_f32 v[26:27], v[28:29], v[26:27]
	v_pk_mul_f32 v[32:33], v[60:61], v[32:33]
	s_nop 0
	v_and_b32_sdwa v45, v26, v178 dst_sel:DWORD dst_unused:UNUSED_PAD src0_sel:WORD_1 src1_sel:DWORD
	s_nop 0
	s_nop 0
	v_cvt_pk_bf16_f32 v27, v27, v27
	v_add3_u32 v26, v26, v45, s81
	v_cvt_pk_bf16_f32 v29, v32, v32
	v_cvt_pk_bf16_f32 v28, v33, v33
	v_and_b32_e32 v27, 0xffff0000, v27
	v_and_b32_e32 v26, 0xffff0000, v26
	v_or_b32_sdwa v27, v27, v28 dst_sel:DWORD dst_unused:UNUSED_PAD src0_sel:DWORD src1_sel:WORD_1
	v_or_b32_sdwa v26, v26, v29 dst_sel:DWORD dst_unused:UNUSED_PAD src0_sel:DWORD src1_sel:WORD_1
	global_store_dwordx2 v[52:53], v[26:27], off offset:512
	v_lshl_add_u64 v[26:27], v[68:69], 0, v[46:47]
	global_load_dwordx4 v[60:63], v[36:37], off offset:2048
	global_load_dwordx4 v[64:67], v[26:27], off
	s_waitcnt vmcnt(1)
	v_pk_mul_f32 v[24:25], v[24:25], v[62:63]
	v_pk_mul_f32 v[22:23], v[22:23], v[60:61]
	s_waitcnt vmcnt(0)
	v_mov_b32_e32 v29, v66
	v_mov_b32_e32 v66, v65
	v_mov_b32_e32 v28, v64
	v_mov_b32_e32 v32, v22
	v_mov_b32_e32 v33, v24
	v_mov_b32_e32 v24, v23
	v_pk_add_f32 v[22:23], v[66:67], 1.0 op_sel_hi:[1,0]
	v_pk_add_f32 v[28:29], v[28:29], 1.0 op_sel_hi:[1,0]
	v_pk_mul_f32 v[22:23], v[24:25], v[22:23]
	v_pk_mul_f32 v[28:29], v[32:33], v[28:29]
	s_nop 0
	s_nop 0
	s_nop 0
	s_nop 0
	v_cvt_pk_bf16_f32 v23, v23, v23
	v_cvt_pk_bf16_f32 v22, v22, v22
	v_cvt_pk_bf16_f32 v25, v28, v28
	v_cvt_pk_bf16_f32 v24, v29, v29
	v_and_b32_e32 v23, 0xffff0000, v23
	v_and_b32_e32 v22, 0xffff0000, v22
	v_or_b32_sdwa v23, v23, v24 dst_sel:DWORD dst_unused:UNUSED_PAD src0_sel:DWORD src1_sel:WORD_1
	v_or_b32_sdwa v22, v22, v25 dst_sel:DWORD dst_unused:UNUSED_PAD src0_sel:DWORD src1_sel:WORD_1
	global_store_dwordx2 v[52:53], v[22:23], off offset:1024
	v_lshl_add_u64 v[22:23], v[68:69], 0, v[48:49]
	global_load_dwordx4 v[60:63], v[36:37], off offset:3072
	global_load_dwordx4 v[64:67], v[22:23], off
	v_mul_f32_e32 v24, v15, v15
	v_mul_f32_e32 v25, v11, v11
	v_mul_f32_e32 v28, v7, v7
	v_fmac_f32_e32 v24, v14, v14
	v_fmac_f32_e32 v25, v10, v10
	v_mul_f32_e32 v29, v3, v3
	v_fmac_f32_e32 v28, v6, v6
	v_fmac_f32_e32 v24, v16, v16
	v_fmac_f32_e32 v25, v12, v12
	v_fmac_f32_e32 v29, v2, v2
	v_fmac_f32_e32 v28, v8, v8
	v_fmac_f32_e32 v24, v17, v17
	v_fmac_f32_e32 v25, v13, v13
	v_fmac_f32_e32 v29, v4, v4
	v_fmac_f32_e32 v28, v9, v9
	v_add_f32_e32 v24, v24, v25
	v_fmac_f32_e32 v29, v5, v5
	v_add_f32_e32 v24, v24, v28
	v_add_f32_e32 v24, v24, v29
	ds_bpermute_b32 v25, v54, v24
	s_waitcnt lgkmcnt(0)
	v_add_f32_e32 v24, v24, v25
	ds_bpermute_b32 v25, v55, v24
	s_waitcnt lgkmcnt(0)
	v_add_f32_e32 v24, v24, v25
	ds_bpermute_b32 v25, v56, v24
	s_waitcnt lgkmcnt(0)
	v_add_f32_e32 v24, v24, v25
	ds_bpermute_b32 v25, v57, v24
	s_waitcnt lgkmcnt(0)
	v_add_f32_e32 v25, v24, v25
	ds_bpermute_b32 v28, v58, v25
	v_add_u32_e32 v24, 1, v34
	s_waitcnt lgkmcnt(0)
	v_add_f32_e32 v28, v25, v28
	ds_bpermute_b32 v29, v59, v28
	s_waitcnt vmcnt(1)
	v_pk_mul_f32 v[20:21], v[20:21], v[62:63]
	v_pk_mul_f32 v[18:19], v[18:19], v[60:61]
	s_waitcnt vmcnt(0)
	v_mov_b32_e32 v33, v66
	v_mov_b32_e32 v66, v65
	v_mov_b32_e32 v32, v64
	v_mov_b32_e32 v60, v18
	v_mov_b32_e32 v61, v20
	v_mov_b32_e32 v20, v19
	v_pk_add_f32 v[18:19], v[66:67], 1.0 op_sel_hi:[1,0]
	v_pk_add_f32 v[32:33], v[32:33], 1.0 op_sel_hi:[1,0]
	v_pk_mul_f32 v[18:19], v[20:21], v[18:19]
	v_pk_mul_f32 v[32:33], v[60:61], v[32:33]
	s_nop 0
	v_and_b32_sdwa v35, v18, v178 dst_sel:DWORD dst_unused:UNUSED_PAD src0_sel:WORD_1 src1_sel:DWORD
	v_and_b32_sdwa v20, v33, v178 dst_sel:DWORD dst_unused:UNUSED_PAD src0_sel:WORD_1 src1_sel:DWORD
	v_and_b32_sdwa v21, v32, v178 dst_sel:DWORD dst_unused:UNUSED_PAD src0_sel:WORD_1 src1_sel:DWORD
	v_cvt_pk_bf16_f32 v19, v19, v19
	v_add3_u32 v18, v18, v35, s81
	v_add3_u32 v21, v32, v21, s81
	v_add3_u32 v20, v33, v20, s81
	v_and_b32_e32 v19, 0xffff0000, v19
	v_and_b32_e32 v18, 0xffff0000, v18
	v_or_b32_sdwa v19, v19, v20 dst_sel:DWORD dst_unused:UNUSED_PAD src0_sel:DWORD src1_sel:WORD_1
	v_or_b32_sdwa v18, v18, v21 dst_sel:DWORD dst_unused:UNUSED_PAD src0_sel:DWORD src1_sel:WORD_1
	v_ashrrev_i32_e32 v25, 31, v24
	global_store_dwordx2 v[52:53], v[18:19], off offset:1536
	s_and_saveexec_b64 s[8:9], s[6:7]
	s_cbranch_execz .LBB0_892
	v_lshlrev_b64 v[18:19], 6, v[24:25]
	s_waitcnt lgkmcnt(0)
	v_add_f32_e32 v20, v28, v29
	v_lshl_add_u64 v[18:19], v[40:41], 0, v[18:19]
	v_cndmask_b32_e64 v20, 0, v20, s[4:5]
	global_store_dword v[18:19], v20, off
	s_branch .LBB0_892

; __device__ __forceinline__ int srccol(int perm, int n) {
;   if (perm == 1) {
;     int blk = n >> 5, t = (n >> 4) & 1, i = n & 15;
;     int j = blk * 16 + i;
;     return t ? DFF + j : j;
; __device__ __forceinline__ void conv_family(const float* __restrict__ W, u16* __restrict__ Wt, int cnt, int K, int N, int perm,
;                             float* tile, const int tid, const float* __restrict__ kscale = nullptr) {
;     ...
;   for (int t = blockIdx.x; t < total; t += gridDim.x) {
;     int mi = t / per, r = t % per, kt = r / tn, ntile = r % tn;
;     const float* Ws = W + (size_t)mi * K * N;
;     u16* Wd = Wt + (size_t)mi * K * N;
;     int k0 = kt * 64, n0 = ntile * 256;
;     {
;       int n = tid & 255;
;       int sc = srccol(perm, n0 + n);
;       const float* wp = Ws + (size_t)(k0 + (tid >> 8)) * N + sc;
.LBB0_908:
	s_mul_hi_i32 s1, s0, 0x2e8ba2e9
	s_lshr_b32 s2, s1, 31
	s_ashr_i32 s1, s1, 6
	s_add_i32 s1, s1, s2
	s_mul_i32 s6, s1, 0xfffffea0
	s_mul_hi_i32 s3, s1, 0x580000
	s_mul_i32 s2, s1, 0x580000
	s_add_i32 s1, s0, s6
	s_mul_i32 s8, s1, 0xba3
	s_lshr_b32 s9, s8, 31
	s_lshr_b32 s8, s8, 16
	s_add_i32 s8, s8, s9
	s_sext_i32_i16 s9, s8
	s_mul_i32 s8, s8, 22
	s_lshl_b64 s[6:7], s[2:3], 2
	s_sub_i32 s1, s1, s8
	s_add_u32 s6, s18, s6
	s_addc_u32 s7, s19, s7
	s_lshl_b64 s[2:3], s[2:3], 1
	s_sext_i32_i16 s1, s1
	s_add_u32 s8, s66, s2
	s_addc_u32 s10, s67, s3
	s_lshl_b32 s1, s1, 8
	v_or_b32_e32 v11, s1, v3
	v_lshrrev_b32_e32 v13, 5, v3
	v_and_b32_e32 v20, 3, v13
	v_lshrrev_b32_e32 v13, 2, v13
	v_lshl_add_u32 v13, v5, 1, v13
	v_lshl_add_u32 v20, v20, 5, v13
	v_lshrrev_b32_e32 v13, 1, v11
	v_and_b32_e32 v13, 0xffffff80, v13
	v_add_u32_e32 v20, v20, v13
	s_lshl_b32 s2, s9, 6
	v_add_u32_e32 v21, 0xb00, v20
	v_mov_b64_e32 v[8:9], s[6:7]
	v_add_u32_e32 v12, s2, v4
	v_add_u32_e32 v10, s1, v7
	s_movk_i32 s1, 0x5800
	v_cndmask_b32_e64 v20, v21, v20, s[4:5]
	v_mad_i64_i32 v[16:17], s[6:7], v12, s1, v[8:9]
	v_ashrrev_i32_e32 v21, 31, v20
	v_lshl_add_u64 v[48:49], v[20:21], 2, v[16:17]
	v_add_co_u32_e32 v50, vcc, s12, v48
	s_mov_b32 s1, 0x37000
	s_nop 0
	v_addc_co_u32_e32 v51, vcc, 0, v49, vcc
	v_add_co_u32_e32 v52, vcc, s11, v48
	s_ashr_i32 s3, s2, 31
	s_nop 0
	v_addc_co_u32_e32 v53, vcc, 0, v49, vcc
	v_add_co_u32_e32 v54, vcc, s13, v48
	s_lshl_b64 s[2:3], s[2:3], 1
	s_nop 0
	v_addc_co_u32_e32 v55, vcc, 0, v49, vcc
	v_add_co_u32_e32 v56, vcc, s39, v48
	v_add_u32_e32 v8, 64, v10
	s_nop 0
	v_addc_co_u32_e32 v57, vcc, 0, v49, vcc
	v_add_co_u32_e32 v58, vcc, s1, v48
	s_mov_b32 s1, 0x4d000
	s_nop 0
	v_addc_co_u32_e32 v59, vcc, 0, v49, vcc
	v_add_co_u32_e32 v60, vcc, s14, v48
	s_add_u32 s2, s8, s2
	s_nop 0
	v_addc_co_u32_e32 v61, vcc, 0, v49, vcc
	v_add_co_u32_e32 v62, vcc, s1, v48
	s_mov_b32 s1, 0x58000
	s_nop 0
	v_addc_co_u32_e32 v63, vcc, 0, v49, vcc
	v_add_co_u32_e32 v64, vcc, s1, v48
	s_mov_b32 s1, 0x6e000
	s_nop 0
	v_addc_co_u32_e32 v65, vcc, 0, v49, vcc
	v_add_co_u32_e32 v66, vcc, s35, v48
	v_ashrrev_i32_e32 v11, 31, v10
	s_nop 0
	v_addc_co_u32_e32 v67, vcc, 0, v49, vcc
	v_add_co_u32_e32 v68, vcc, s1, v48
	s_mov_b32 s1, 0x79000
	s_nop 0
	v_addc_co_u32_e32 v69, vcc, 0, v49, vcc
	v_add_co_u32_e32 v70, vcc, s1, v48
	s_mov_b32 s1, 0x8f000
	s_nop 0
	v_addc_co_u32_e32 v71, vcc, 0, v49, vcc
	v_add_co_u32_e32 v78, vcc, s15, v48
	v_ashrrev_i32_e32 v9, 31, v8
	s_nop 0
	v_addc_co_u32_e32 v79, vcc, 0, v49, vcc
	v_add_co_u32_e32 v80, vcc, s1, v48
	s_mov_b32 s1, 0x9a000
	s_nop 0
	v_addc_co_u32_e32 v81, vcc, 0, v49, vcc
	v_add_co_u32_e32 v82, vcc, s1, v48
	s_mov_b32 s1, 0xa5000
	s_nop 0
	v_addc_co_u32_e32 v83, vcc, 0, v49, vcc
	v_add_co_u32_e32 v84, vcc, s1, v48
	s_mov_b32 s1, 0xb0000
	s_nop 0
	v_addc_co_u32_e32 v85, vcc, 0, v49, vcc
	v_add_co_u32_e32 v86, vcc, s1, v48
	s_mov_b32 s1, 0xbb000
	s_nop 0
	v_addc_co_u32_e32 v87, vcc, 0, v49, vcc
	v_add_co_u32_e32 v34, vcc, s1, v48
	s_mov_b32 s1, 0xc6000
	s_nop 0
	v_addc_co_u32_e32 v35, vcc, 0, v49, vcc
	v_add_co_u32_e32 v36, vcc, s1, v48
	s_mov_b32 s1, 0xd1000
	s_nop 0
	v_addc_co_u32_e32 v37, vcc, 0, v49, vcc
	v_add_co_u32_e32 v38, vcc, s1, v48
	s_mov_b32 s1, 0xdc000
	s_nop 0
	v_addc_co_u32_e32 v39, vcc, 0, v49, vcc
	v_add_co_u32_e32 v40, vcc, s1, v48
	s_mov_b32 s1, 0xe7000
	s_nop 0
	v_addc_co_u32_e32 v41, vcc, 0, v49, vcc
	v_add_co_u32_e32 v42, vcc, s1, v48
	s_mov_b32 s1, 0xf2000
	s_nop 0
	v_addc_co_u32_e32 v43, vcc, 0, v49, vcc
	v_add_co_u32_e32 v44, vcc, s1, v48
	s_mov_b32 s1, 0xfd000
	s_nop 0
	v_addc_co_u32_e32 v45, vcc, 0, v49, vcc
	s_addc_u32 s3, s10, s3
	v_add_co_u32_e32 v16, vcc, s1, v48
	v_add_u32_e32 v12, 0x80, v10
	v_add_u32_e32 v14, 0xc0, v10
	v_lshlrev_b64 v[10:11], 11, v[10:11]
	v_lshlrev_b64 v[18:19], 11, v[8:9]
	v_lshl_add_u64 v[22:23], s[2:3], 0, v[0:1]
	v_addc_co_u32_e32 v17, vcc, 0, v49, vcc
	v_lshl_add_u64 v[8:9], v[22:23], 0, v[10:11]
	v_lshl_add_u64 v[10:11], v[22:23], 0, v[18:19]
	v_add_co_u32_e32 v18, vcc, s16, v48
	s_mov_b32 s1, 0x113000
	s_nop 0
	v_addc_co_u32_e32 v19, vcc, 0, v49, vcc
	v_ashrrev_i32_e32 v13, 31, v12
	v_ashrrev_i32_e32 v15, 31, v14
	v_add_co_u32_e32 v20, vcc, s1, v48
	v_lshlrev_b64 v[12:13], 11, v[12:13]
	v_lshlrev_b64 v[14:15], 11, v[14:15]
	v_addc_co_u32_e32 v21, vcc, 0, v49, vcc
	s_mov_b32 s1, 0x11e000
	v_lshl_add_u64 v[12:13], v[22:23], 0, v[12:13]
	v_lshl_add_u64 v[14:15], v[22:23], 0, v[14:15]
	v_add_co_u32_e32 v22, vcc, s1, v48
	s_mov_b32 s1, 0x129000
	s_nop 0
	v_addc_co_u32_e32 v23, vcc, 0, v49, vcc
	v_add_co_u32_e32 v24, vcc, s1, v48
	s_mov_b32 s1, 0x134000
	s_nop 0
	v_addc_co_u32_e32 v25, vcc, 0, v49, vcc
	v_add_co_u32_e32 v26, vcc, s1, v48
	s_mov_b32 s1, 0x13f000
	s_nop 0
	v_addc_co_u32_e32 v27, vcc, 0, v49, vcc
	v_add_co_u32_e32 v28, vcc, s1, v48
	s_mov_b32 s1, 0x14a000
	s_waitcnt lgkmcnt(0)
; __device__ __forceinline__ void conv_family(const float* __restrict__ W, u16* __restrict__ Wt, int cnt, int K, int N, int perm,
;                             float* tile, const int tid, const float* __restrict__ kscale = nullptr) {
;     ...
;       float v[32];
; #pragma unroll
;       for (int i = 0; i < 32; ++i) v[i] = wp[(size_t)(2 * i) * N];
;       if (kscale) {
;         const float* ks = kscale + (size_t)mi * K + k0 + (tid >> 8);
; #pragma unroll
;         for (int i = 0; i < 32; ++i) v[i] *= ks[2 * i];
;       }
; #pragma unroll
;       for (int i = 0; i < 32; ++i) tile[(2 * i + (tid >> 8)) * 257 + n] = v[i];
;     }
;     __syncthreads();
	v_addc_co_u32_e32 v29, vcc, 0, v49, vcc
	v_add_co_u32_e32 v30, vcc, s1, v48
	s_mov_b32 s1, 0x155000
	s_nop 0
	v_addc_co_u32_e32 v31, vcc, 0, v49, vcc
	v_add_co_u32_e32 v32, vcc, s1, v48
	s_add_i32 s0, s0, s44
	s_nop 0
	v_addc_co_u32_e32 v33, vcc, 0, v49, vcc
	global_load_dword v48, v[48:49], off
	s_nop 0
	global_load_dword v49, v[50:51], off
	s_nop 0
	global_load_dword v50, v[52:53], off
	global_load_dword v51, v[54:55], off
	s_nop 0
	global_load_dword v52, v[56:57], off
	global_load_dword v53, v[58:59], off
	global_load_dword v54, v[60:61], off
	global_load_dword v55, v[62:63], off
	s_nop 0
	global_load_dword v56, v[64:65], off
	global_load_dword v57, v[66:67], off
	global_load_dword v58, v[68:69], off
	global_load_dword v59, v[70:71], off
	global_load_dword v60, v[78:79], off
	global_load_dword v61, v[80:81], off
	global_load_dword v62, v[82:83], off
	global_load_dword v63, v[84:85], off
	global_load_dword v64, v[86:87], off
	global_load_dword v66, v[34:35], off
	global_load_dword v67, v[36:37], off
	global_load_dword v68, v[38:39], off
	v_add_u32_e32 v65, 4, v46
	global_load_dword v40, v[40:41], off
	v_add_u32_e32 v34, 8, v46
	global_load_dword v41, v[42:43], off
	v_add_u32_e32 v35, 12, v46
	global_load_dword v42, v[44:45], off
	s_nop 0
	global_load_dword v16, v[16:17], off
	s_nop 0
	global_load_dword v17, v[18:19], off
	s_nop 0
	global_load_dword v18, v[20:21], off
	global_load_dword v19, v[22:23], off
	s_nop 0
	global_load_dword v20, v[24:25], off
	global_load_dword v21, v[26:27], off
	global_load_dword v22, v[28:29], off
	global_load_dword v23, v[30:31], off
	s_nop 0
	global_load_dword v24, v[32:33], off
	v_add_u32_e32 v36, 16, v46
	v_add_u32_e32 v37, 20, v46
	v_add_u32_e32 v38, 24, v46
	v_add_u32_e32 v39, 28, v46
	s_waitcnt vmcnt(31)
	ds_write_b32 v47, v48
	s_waitcnt vmcnt(30)
	ds_write_b32 v47, v49 offset:2056
	s_waitcnt vmcnt(29)
	ds_write_b32 v47, v50 offset:4112
	s_waitcnt vmcnt(28)
	ds_write_b32 v47, v51 offset:6168
	s_waitcnt vmcnt(27)
	ds_write_b32 v47, v52 offset:8224
	s_waitcnt vmcnt(26)
	ds_write_b32 v47, v53 offset:10280
	s_waitcnt vmcnt(25)
	ds_write_b32 v47, v54 offset:12336
	s_waitcnt vmcnt(24)
	ds_write_b32 v47, v55 offset:14392
	s_waitcnt vmcnt(23)
	ds_write_b32 v47, v56 offset:16448
	s_waitcnt vmcnt(22)
	ds_write_b32 v47, v57 offset:18504
	s_waitcnt vmcnt(21)
	ds_write_b32 v47, v58 offset:20560
	s_waitcnt vmcnt(20)
	ds_write_b32 v47, v59 offset:22616
	s_waitcnt vmcnt(19)
	ds_write_b32 v47, v60 offset:24672
	s_waitcnt vmcnt(18)
	ds_write_b32 v47, v61 offset:26728
	s_waitcnt vmcnt(17)
	ds_write_b32 v47, v62 offset:28784
	s_waitcnt vmcnt(16)
	ds_write_b32 v47, v63 offset:30840
	s_waitcnt vmcnt(15)
	ds_write_b32 v47, v64 offset:32896
	s_waitcnt vmcnt(14)
	ds_write_b32 v47, v66 offset:34952
	s_waitcnt vmcnt(13)
	ds_write_b32 v47, v67 offset:37008
	s_waitcnt vmcnt(12)
	ds_write_b32 v47, v68 offset:39064
	s_waitcnt vmcnt(11)
	ds_write_b32 v47, v40 offset:41120
	s_waitcnt vmcnt(10)
	ds_write_b32 v47, v41 offset:43176
	s_waitcnt vmcnt(9)
	ds_write_b32 v47, v42 offset:45232
	s_waitcnt vmcnt(8)
	ds_write_b32 v47, v16 offset:47288
	s_waitcnt vmcnt(7)
	ds_write_b32 v47, v17 offset:49344
	s_waitcnt vmcnt(6)
	ds_write_b32 v47, v18 offset:51400
	s_waitcnt vmcnt(5)
	ds_write_b32 v47, v19 offset:53456
	s_waitcnt vmcnt(4)
	ds_write_b32 v47, v20 offset:55512
	s_waitcnt vmcnt(3)
	ds_write_b32 v47, v21 offset:57568
	s_waitcnt vmcnt(2)
	ds_write_b32 v47, v22 offset:59624
	s_waitcnt vmcnt(1)
	ds_write_b32 v47, v23 offset:61680
	s_waitcnt vmcnt(0)
	ds_write_b32 v47, v24 offset:63736
	s_waitcnt lgkmcnt(0)
	s_barrier
; __device__ __forceinline__ unsigned pack2(float a, float b) { return (unsigned)f2bf(a) | ((unsigned)f2bf(b) << 16); }
; __device__ __forceinline__ void conv_family(const float* __restrict__ W, u16* __restrict__ Wt, int cnt, int K, int N, int perm,
;                             float* tile, const int tid, const float* __restrict__ kscale = nullptr) {
;     ...
; #pragma unroll
;     for (int i = 0; i < 4; ++i) {
;       int n = i * 64 + (tid >> 3), ks = (tid & 7) * 8;
;       uint4 pk;
;       pk.x = pack2(tile[(ks + 0) * 257 + n], tile[(ks + 1) * 257 + n]);
;       pk.y = pack2(tile[(ks + 2) * 257 + n], tile[(ks + 3) * 257 + n]);
;       pk.z = pack2(tile[(ks + 4) * 257 + n], tile[(ks + 5) * 257 + n]);
;       pk.w = pack2(tile[(ks + 6) * 257 + n], tile[(ks + 7) * 257 + n]);
;       *(uint4*)(Wd + (size_t)(n0 + n) * K + k0 + ks) = pk;
;     }
;     __syncthreads();
;   }
	ds_read2st64_b32 v[16:17], v46 offset1:1
	ds_read2st64_b32 v[18:19], v46 offset0:2 offset1:3
	ds_read2st64_b32 v[20:21], v65 offset0:4 offset1:5
	ds_read2st64_b32 v[22:23], v65 offset0:6 offset1:7
	ds_read2st64_b32 v[24:25], v34 offset0:8 offset1:9
	ds_read2st64_b32 v[26:27], v34 offset0:10 offset1:11
	ds_read2st64_b32 v[28:29], v35 offset0:12 offset1:13
	ds_read2st64_b32 v[30:31], v35 offset0:14 offset1:15
	ds_read2st64_b32 v[32:33], v36 offset0:16 offset1:17
	ds_read2st64_b32 v[34:35], v36 offset0:18 offset1:19
	ds_read2st64_b32 v[40:41], v37 offset0:20 offset1:21
	ds_read2st64_b32 v[36:37], v37 offset0:22 offset1:23
	ds_read2st64_b32 v[42:43], v38 offset0:24 offset1:25
	ds_read2st64_b32 v[44:45], v38 offset0:26 offset1:27
	ds_read2st64_b32 v[48:49], v39 offset0:28 offset1:29
	ds_read2st64_b32 v[38:39], v39 offset0:30 offset1:31
	s_waitcnt lgkmcnt(11)
	s_nop 0
	s_nop 0
	s_waitcnt lgkmcnt(9)
	s_nop 0
	s_nop 0
	s_waitcnt lgkmcnt(3)
	v_and_b32_sdwa v54, v42, v178 dst_sel:DWORD dst_unused:UNUSED_PAD src0_sel:WORD_1 src1_sel:DWORD
	v_and_b32_sdwa v55, v32, v178 dst_sel:DWORD dst_unused:UNUSED_PAD src0_sel:WORD_1 src1_sel:DWORD
	s_waitcnt lgkmcnt(1)
	s_nop 0
	s_nop 0
	s_nop 0
	v_and_b32_sdwa v59, v17, v178 dst_sel:DWORD dst_unused:UNUSED_PAD src0_sel:WORD_1 src1_sel:DWORD
	s_nop 0
	s_nop 0
	v_and_b32_sdwa v62, v43, v178 dst_sel:DWORD dst_unused:UNUSED_PAD src0_sel:WORD_1 src1_sel:DWORD
	v_and_b32_sdwa v63, v33, v178 dst_sel:DWORD dst_unused:UNUSED_PAD src0_sel:WORD_1 src1_sel:DWORD
	s_nop 0
	s_nop 0
	v_cvt_pk_bf16_f32 v16, v16, v16
	v_add3_u32 v51, v17, v59, s81
	s_nop 0
	v_and_b32_sdwa v59, v18, v178 dst_sel:DWORD dst_unused:UNUSED_PAD src0_sel:WORD_1 src1_sel:DWORD
	v_cvt_pk_bf16_f32 v24, v24, v24
	v_cvt_pk_bf16_f32 v25, v25, v25
	s_nop 0
	v_and_b32_sdwa v58, v22, v178 dst_sel:DWORD dst_unused:UNUSED_PAD src0_sel:WORD_1 src1_sel:DWORD
	v_cvt_pk_bf16_f32 v28, v28, v28
	v_cvt_pk_bf16_f32 v29, v29, v29
	v_and_b32_sdwa v52, v44, v178 dst_sel:DWORD dst_unused:UNUSED_PAD src0_sel:WORD_1 src1_sel:DWORD
	v_and_b32_sdwa v60, v34, v178 dst_sel:DWORD dst_unused:UNUSED_PAD src0_sel:WORD_1 src1_sel:DWORD
	v_cvt_pk_bf16_f32 v20, v20, v20
	v_cvt_pk_bf16_f32 v21, v21, v21
	s_waitcnt lgkmcnt(0)
	s_nop 0
	v_and_b32_sdwa v61, v36, v178 dst_sel:DWORD dst_unused:UNUSED_PAD src0_sel:WORD_1 src1_sel:DWORD
	v_add3_u32 v32, v32, v55, s81
	v_add3_u32 v33, v33, v63, s81
	v_and_b32_sdwa v55, v27, v178 dst_sel:DWORD dst_unused:UNUSED_PAD src0_sel:WORD_1 src1_sel:DWORD
	v_and_b32_sdwa v63, v19, v178 dst_sel:DWORD dst_unused:UNUSED_PAD src0_sel:WORD_1 src1_sel:DWORD
	v_add3_u32 v42, v42, v54, s81
	v_add3_u32 v43, v43, v62, s81
	s_nop 0
	v_and_b32_sdwa v62, v23, v178 dst_sel:DWORD dst_unused:UNUSED_PAD src0_sel:WORD_1 src1_sel:DWORD
	v_cvt_pk_bf16_f32 v48, v48, v48
	v_cvt_pk_bf16_f32 v40, v40, v40
	v_cvt_pk_bf16_f32 v41, v41, v41
	v_and_b32_sdwa v57, v39, v178 dst_sel:DWORD dst_unused:UNUSED_PAD src0_sel:WORD_1 src1_sel:DWORD
	v_and_b32_sdwa v65, v37, v178 dst_sel:DWORD dst_unused:UNUSED_PAD src0_sel:WORD_1 src1_sel:DWORD
	v_cvt_pk_bf16_f32 v49, v49, v49
	v_and_b32_sdwa v56, v45, v178 dst_sel:DWORD dst_unused:UNUSED_PAD src0_sel:WORD_1 src1_sel:DWORD
	v_and_b32_sdwa v64, v35, v178 dst_sel:DWORD dst_unused:UNUSED_PAD src0_sel:WORD_1 src1_sel:DWORD
	v_add3_u32 v59, v18, v59, s81
	v_cvt_pk_bf16_f32 v26, v26, v26
	v_cvt_pk_bf16_f32 v17, v30, v30
	v_add3_u32 v18, v22, v58, s81
	v_add3_u32 v30, v34, v60, s81
	v_add3_u32 v34, v44, v52, s81
	v_cvt_pk_bf16_f32 v22, v38, v38
	v_add3_u32 v36, v36, v61, s81
	v_add3_u32 v38, v19, v63, s81
	v_add3_u32 v44, v27, v55, s81
	v_cvt_pk_bf16_f32 v19, v31, v31
	v_add3_u32 v23, v23, v62, s81
	v_add3_u32 v27, v39, v57, s81
	v_add3_u32 v37, v37, v65, s81
	v_and_b32_e32 v28, 0xffff0000, v28
	v_and_b32_e32 v20, 0xffff0000, v20
	v_and_b32_e32 v39, 0xffff0000, v48
	v_and_b32_e32 v40, 0xffff0000, v40
	s_cmpk_lt_i32 s0, 0xb00
	v_add3_u32 v35, v35, v64, s81
	v_add3_u32 v31, v45, v56, s81
	v_and_b32_e32 v29, 0xffff0000, v29
	v_and_b32_e32 v45, 0xffff0000, v21
	v_and_b32_e32 v48, 0xffff0000, v49
	v_and_b32_e32 v41, 0xffff0000, v41
	v_and_b32_e32 v49, 0xffff0000, v17
	v_and_b32_e32 v50, 0xffff0000, v18
	v_and_b32_e32 v52, 0xffff0000, v22
	v_and_b32_e32 v36, 0xffff0000, v36
	v_and_b32_e32 v53, 0xffff0000, v19
	v_and_b32_e32 v54, 0xffff0000, v23
	v_and_b32_e32 v55, 0xffff0000, v27
	v_and_b32_e32 v37, 0xffff0000, v37
	v_or_b32_sdwa v17, v28, v24 dst_sel:DWORD dst_unused:UNUSED_PAD src0_sel:DWORD src1_sel:WORD_1
	v_or_b32_sdwa v16, v20, v16 dst_sel:DWORD dst_unused:UNUSED_PAD src0_sel:DWORD src1_sel:WORD_1
	v_or_b32_sdwa v19, v39, v42 dst_sel:DWORD dst_unused:UNUSED_PAD src0_sel:DWORD src1_sel:WORD_1
	v_or_b32_sdwa v18, v40, v32 dst_sel:DWORD dst_unused:UNUSED_PAD src0_sel:DWORD src1_sel:WORD_1
	v_or_b32_sdwa v21, v29, v25 dst_sel:DWORD dst_unused:UNUSED_PAD src0_sel:DWORD src1_sel:WORD_1
	v_or_b32_sdwa v20, v45, v51 dst_sel:DWORD dst_unused:UNUSED_PAD src0_sel:DWORD src1_sel:WORD_1
	v_or_b32_sdwa v23, v48, v43 dst_sel:DWORD dst_unused:UNUSED_PAD src0_sel:DWORD src1_sel:WORD_1
	v_or_b32_sdwa v22, v41, v33 dst_sel:DWORD dst_unused:UNUSED_PAD src0_sel:DWORD src1_sel:WORD_1
	v_or_b32_sdwa v25, v49, v26 dst_sel:DWORD dst_unused:UNUSED_PAD src0_sel:DWORD src1_sel:WORD_1
	v_or_b32_sdwa v24, v50, v59 dst_sel:DWORD dst_unused:UNUSED_PAD src0_sel:DWORD src1_sel:WORD_1
	v_or_b32_sdwa v27, v52, v34 dst_sel:DWORD dst_unused:UNUSED_PAD src0_sel:DWORD src1_sel:WORD_1
	v_or_b32_sdwa v26, v36, v30 dst_sel:DWORD dst_unused:UNUSED_PAD src0_sel:DWORD src1_sel:WORD_1
	v_or_b32_sdwa v29, v53, v44 dst_sel:DWORD dst_unused:UNUSED_PAD src0_sel:DWORD src1_sel:WORD_1
	v_or_b32_sdwa v28, v54, v38 dst_sel:DWORD dst_unused:UNUSED_PAD src0_sel:DWORD src1_sel:WORD_1
	v_or_b32_sdwa v31, v55, v31 dst_sel:DWORD dst_unused:UNUSED_PAD src0_sel:DWORD src1_sel:WORD_1
	v_or_b32_sdwa v30, v37, v35 dst_sel:DWORD dst_unused:UNUSED_PAD src0_sel:DWORD src1_sel:WORD_1
	global_store_dwordx4 v[8:9], v[16:19], off
	global_store_dwordx4 v[10:11], v[20:23], off
	global_store_dwordx4 v[12:13], v[24:27], off
	global_store_dwordx4 v[14:15], v[28:31], off
	s_barrier
	s_cbranch_scc1 .LBB0_908

; __device__ __forceinline__ void conv_family(const float* __restrict__ W, u16* __restrict__ Wt, int cnt, int K, int N, int perm,
;                             float* tile, const int tid, const float* __restrict__ kscale = nullptr) {
;     ...
;   for (int t = blockIdx.x; t < total; t += gridDim.x) {
;     int mi = t / per, r = t % per, kt = r / tn, ntile = r % tn;
;     const float* Ws = W + (size_t)mi * K * N;
;     u16* Wd = Wt + (size_t)mi * K * N;
;     int k0 = kt * 64, n0 = ntile * 256;
;     {
;       int n = tid & 255;
;       int sc = srccol(perm, n0 + n);
;       const float* wp = Ws + (size_t)(k0 + (tid >> 8)) * N + sc;
;       float v[32];
; #pragma unroll
;       for (int i = 0; i < 32; ++i) v[i] = wp[(size_t)(2 * i) * N];
;       if (kscale) {
;         const float* ks = kscale + (size_t)mi * K + k0 + (tid >> 8);
; #pragma unroll
;         for (int i = 0; i < 32; ++i) v[i] *= ks[2 * i];
;       }
; #pragma unroll
;       for (int i = 0; i < 32; ++i) tile[(2 * i + (tid >> 8)) * 257 + n] = v[i];
;     }
;     __syncthreads();
.LBB0_911:
	s_mul_hi_i32 s0, s4, 0x2e8ba2e9
	s_lshr_b32 s1, s0, 31
	s_ashr_i32 s0, s0, 5
	s_add_i32 s0, s0, s1
	s_mul_i32 s1, s0, 0xffffff50
	s_add_i32 s1, s4, s1
	s_bfe_u32 s2, s1, 0x2001d
	s_add_i32 s2, s1, s2
	s_sext_i32_i16 s5, s2
	s_and_b32 s2, s2, 0xfffc
	s_sub_i32 s1, s1, s2
	s_sext_i32_i16 s8, s1
	s_mul_hi_i32 s1, s0, 0x2c0000
	s_mul_i32 s0, s0, 0x2c0000
	s_lshl_b64 s[2:3], s[0:1], 2
	s_add_u32 s2, s20, s2
	s_addc_u32 s3, s21, s3
	s_lshl_b64 s[0:1], s[0:1], 1
	s_add_u32 s6, s52, s0
	s_addc_u32 s7, s53, s1
	s_lshl_b32 s0, s5, 4
	s_andn2_b32 s0, s0, 63
	s_lshl_b32 s5, s8, 8
	v_lshlrev_b32_e32 v9, 1, v3
	v_add_u32_e32 v10, s0, v4
	v_bitop3_b32 v8, s5, v43, v3 bitop3:0xc8
	v_and_b32_e32 v9, 30, v9
	v_ashrrev_i32_e32 v11, 31, v10
	v_or3_b32 v8, v8, v75, v9
	v_lshlrev_b64 v[10:11], 12, v[10:11]
	v_lshl_add_u64 v[10:11], s[2:3], 0, v[10:11]
	v_ashrrev_i32_e32 v9, 31, v8
	v_lshl_add_u64 v[8:9], v[8:9], 2, v[10:11]
	v_add_co_u32_e32 v10, vcc, s10, v8
	global_load_dword v12, v[8:9], off
	s_nop 0
	v_addc_co_u32_e32 v11, vcc, 0, v9, vcc
	global_load_dword v13, v[10:11], off
	v_add_co_u32_e32 v10, vcc, s14, v8
	s_ashr_i32 s1, s0, 31
	s_nop 0
	v_addc_co_u32_e32 v11, vcc, 0, v9, vcc
	global_load_dword v14, v[10:11], off
	v_add_co_u32_e32 v10, vcc, s15, v8
	s_lshl_b64 s[0:1], s[0:1], 1
	s_nop 0
	v_addc_co_u32_e32 v11, vcc, 0, v9, vcc
	global_load_dword v15, v[10:11], off
	v_add_co_u32_e32 v10, vcc, s84, v8
	s_add_u32 s0, s6, s0
	s_nop 0
	v_addc_co_u32_e32 v11, vcc, 0, v9, vcc
	global_load_dword v16, v[10:11], off
	v_add_co_u32_e32 v10, vcc, s18, v8
	s_addc_u32 s1, s7, s1
	s_nop 0
	v_addc_co_u32_e32 v11, vcc, 0, v9, vcc
	global_load_dword v17, v[10:11], off
	v_add_co_u32_e32 v10, vcc, s22, v8
	s_add_i32 s4, s4, s44
	s_nop 0
	v_addc_co_u32_e32 v11, vcc, 0, v9, vcc
	global_load_dword v18, v[10:11], off
	v_add_co_u32_e32 v10, vcc, s23, v8
	s_cmpk_lt_i32 s4, 0x580
	s_nop 0
	v_addc_co_u32_e32 v11, vcc, 0, v9, vcc
	global_load_dword v19, v[10:11], off
	v_add_co_u32_e32 v10, vcc, s11, v8
	s_nop 1
	v_addc_co_u32_e32 v11, vcc, 0, v9, vcc
	global_load_dword v20, v[10:11], off
	v_add_co_u32_e32 v10, vcc, s95, v8
	s_nop 1
	v_addc_co_u32_e32 v11, vcc, 0, v9, vcc
	global_load_dword v21, v[10:11], off
	v_add_co_u32_e32 v10, vcc, s12, v8
	s_nop 1
	v_addc_co_u32_e32 v11, vcc, 0, v9, vcc
	global_load_dword v22, v[10:11], off
	v_add_co_u32_e32 v10, vcc, s13, v8
	s_nop 1
	v_addc_co_u32_e32 v11, vcc, 0, v9, vcc
	global_load_dword v23, v[10:11], off
	v_add_co_u32_e32 v10, vcc, s16, v8
	s_nop 1
	v_addc_co_u32_e32 v11, vcc, 0, v9, vcc
	global_load_dword v24, v[10:11], off
	v_add_co_u32_e32 v10, vcc, s17, v8
	s_nop 1
	v_addc_co_u32_e32 v11, vcc, 0, v9, vcc
	global_load_dword v25, v[10:11], off
	v_add_co_u32_e32 v10, vcc, s19, v8
	s_nop 1
	v_addc_co_u32_e32 v11, vcc, 0, v9, vcc
	global_load_dword v27, v[10:11], off
	v_add_co_u32_e32 v10, vcc, s38, v8
	s_nop 1
	v_addc_co_u32_e32 v11, vcc, 0, v9, vcc
	global_load_dword v28, v[10:11], off
	v_add_co_u32_e32 v10, vcc, s24, v8
	s_nop 1
	v_addc_co_u32_e32 v11, vcc, 0, v9, vcc
	s_waitcnt lgkmcnt(0)
	global_load_dword v29, v[10:11], off
	v_add_co_u32_e32 v10, vcc, s40, v8
	s_nop 1
	v_addc_co_u32_e32 v11, vcc, 0, v9, vcc
	global_load_dword v30, v[10:11], off
	v_add_co_u32_e32 v10, vcc, s30, v8
	s_nop 1
	v_addc_co_u32_e32 v11, vcc, 0, v9, vcc
	global_load_dword v31, v[10:11], off
	v_add_co_u32_e32 v10, vcc, s41, v8
	s_nop 1
	v_addc_co_u32_e32 v11, vcc, 0, v9, vcc
	global_load_dword v32, v[10:11], off
	v_add_co_u32_e32 v10, vcc, s25, v8
	s_nop 1
	v_addc_co_u32_e32 v11, vcc, 0, v9, vcc
	global_load_dword v33, v[10:11], off
	v_add_co_u32_e32 v10, vcc, s43, v8
	s_nop 1
	v_addc_co_u32_e32 v11, vcc, 0, v9, vcc
	global_load_dword v34, v[10:11], off
	v_add_co_u32_e32 v10, vcc, s39, v8
	s_nop 1
	v_addc_co_u32_e32 v11, vcc, 0, v9, vcc
	global_load_dword v35, v[10:11], off
	v_add_co_u32_e32 v10, vcc, s48, v8
	s_nop 1
	v_addc_co_u32_e32 v11, vcc, 0, v9, vcc
	global_load_dword v36, v[10:11], off
	v_add_co_u32_e32 v10, vcc, s56, v8
	s_nop 1
	v_addc_co_u32_e32 v11, vcc, 0, v9, vcc
	global_load_dword v37, v[10:11], off
	v_add_co_u32_e32 v10, vcc, s54, v8
	s_nop 1
	v_addc_co_u32_e32 v11, vcc, 0, v9, vcc
	global_load_dword v38, v[10:11], off
	v_add_co_u32_e32 v10, vcc, s55, v8
	s_nop 1
	v_addc_co_u32_e32 v11, vcc, 0, v9, vcc
	global_load_dword v39, v[10:11], off
	v_add_co_u32_e32 v10, vcc, s96, v8
	s_nop 1
	v_addc_co_u32_e32 v11, vcc, 0, v9, vcc
	global_load_dword v40, v[10:11], off
	v_add_co_u32_e32 v10, vcc, s57, v8
	s_nop 1
	v_addc_co_u32_e32 v11, vcc, 0, v9, vcc
	global_load_dword v41, v[10:11], off
	v_add_co_u32_e32 v10, vcc, s26, v8
	s_nop 1
	v_addc_co_u32_e32 v11, vcc, 0, v9, vcc
	global_load_dword v42, v[10:11], off
	v_add_co_u32_e32 v10, vcc, s27, v8
	s_nop 1
	v_addc_co_u32_e32 v11, vcc, 0, v9, vcc
	v_add_co_u32_e32 v8, vcc, s36, v8
	global_load_dword v10, v[10:11], off
	s_nop 0
	v_addc_co_u32_e32 v9, vcc, 0, v9, vcc
	global_load_dword v8, v[8:9], off
	s_waitcnt vmcnt(31)
	ds_write_b32 v26, v12
	s_waitcnt vmcnt(30)
	ds_write_b32 v26, v13 offset:2056
	s_waitcnt vmcnt(29)
	ds_write_b32 v26, v14 offset:4112
	s_waitcnt vmcnt(28)
	ds_write_b32 v26, v15 offset:6168
	s_waitcnt vmcnt(27)
	ds_write_b32 v26, v16 offset:8224
	s_waitcnt vmcnt(26)
	ds_write_b32 v26, v17 offset:10280
	s_waitcnt vmcnt(25)
	ds_write_b32 v26, v18 offset:12336
	s_waitcnt vmcnt(24)
	ds_write_b32 v26, v19 offset:14392
	s_waitcnt vmcnt(23)
	ds_write_b32 v26, v20 offset:16448
	s_waitcnt vmcnt(22)
	ds_write_b32 v26, v21 offset:18504
	s_waitcnt vmcnt(21)
	ds_write_b32 v26, v22 offset:20560
	s_waitcnt vmcnt(20)
	ds_write_b32 v26, v23 offset:22616
	s_waitcnt vmcnt(19)
	ds_write_b32 v26, v24 offset:24672
	s_waitcnt vmcnt(18)
	ds_write_b32 v26, v25 offset:26728
	s_waitcnt vmcnt(17)
	ds_write_b32 v26, v27 offset:28784
	s_waitcnt vmcnt(16)
	ds_write_b32 v26, v28 offset:30840
	s_waitcnt vmcnt(15)
	ds_write_b32 v26, v29 offset:32896
	s_waitcnt vmcnt(14)
	ds_write_b32 v26, v30 offset:34952
	s_waitcnt vmcnt(13)
	ds_write_b32 v26, v31 offset:37008
	s_waitcnt vmcnt(12)
	ds_write_b32 v26, v32 offset:39064
	s_waitcnt vmcnt(11)
	ds_write_b32 v26, v33 offset:41120
	s_waitcnt vmcnt(10)
	ds_write_b32 v26, v34 offset:43176
	s_waitcnt vmcnt(9)
	ds_write_b32 v26, v35 offset:45232
	s_waitcnt vmcnt(8)
	ds_write_b32 v26, v36 offset:47288
	s_waitcnt vmcnt(7)
	ds_write_b32 v26, v37 offset:49344
	s_waitcnt vmcnt(6)
	ds_write_b32 v26, v38 offset:51400
	s_waitcnt vmcnt(5)
	ds_write_b32 v26, v39 offset:53456
	s_waitcnt vmcnt(4)
	ds_write_b32 v26, v40 offset:55512
	s_waitcnt vmcnt(3)
	ds_write_b32 v26, v41 offset:57568
	s_waitcnt vmcnt(2)
	ds_write_b32 v26, v42 offset:59624
	s_waitcnt vmcnt(1)
	ds_write_b32 v26, v10 offset:61680
	s_waitcnt vmcnt(0)
	ds_write_b32 v26, v8 offset:63736
	v_add_u32_e32 v34, 8, v5
	s_waitcnt lgkmcnt(0)
	s_barrier
; __device__ __forceinline__ unsigned pack2(float a, float b) { return (unsigned)f2bf(a) | ((unsigned)f2bf(b) << 16); }
; __device__ __forceinline__ void conv_family(const float* __restrict__ W, u16* __restrict__ Wt, int cnt, int K, int N, int perm,
;                             float* tile, const int tid, const float* __restrict__ kscale = nullptr) {
;     ...
; #pragma unroll
;     for (int i = 0; i < 4; ++i) {
;       int n = i * 64 + (tid >> 3), ks = (tid & 7) * 8;
;       uint4 pk;
;       pk.x = pack2(tile[(ks + 0) * 257 + n], tile[(ks + 1) * 257 + n]);
;       pk.y = pack2(tile[(ks + 2) * 257 + n], tile[(ks + 3) * 257 + n]);
;       pk.z = pack2(tile[(ks + 4) * 257 + n], tile[(ks + 5) * 257 + n]);
;       pk.w = pack2(tile[(ks + 6) * 257 + n], tile[(ks + 7) * 257 + n]);
;       *(uint4*)(Wd + (size_t)(n0 + n) * K + k0 + ks) = pk;
;     }
;     __syncthreads();
;   }
	ds_read2st64_b32 v[14:15], v34 offset0:8 offset1:9
	v_add_u32_e32 v35, 12, v5
	ds_read2st64_b32 v[10:11], v5 offset1:1
	v_add_u32_e32 v27, 4, v5
	ds_read2st64_b32 v[16:17], v35 offset0:12 offset1:13
	ds_read2st64_b32 v[12:13], v27 offset0:4 offset1:5
	v_add_u32_e32 v37, 20, v5
	v_add_u32_e32 v36, 16, v5
	ds_read2st64_b32 v[20:21], v37 offset0:20 offset1:21
	v_add_u32_e32 v39, 28, v5
	ds_read2st64_b32 v[18:19], v36 offset0:16 offset1:17
	v_add_u32_e32 v38, 24, v5
	ds_read2st64_b32 v[24:25], v39 offset0:28 offset1:29
	s_waitcnt lgkmcnt(6)
	s_nop 0
	ds_read2st64_b32 v[22:23], v38 offset0:24 offset1:25
	s_waitcnt lgkmcnt(6)
	s_nop 0
	v_cvt_pk_bf16_f32 v14, v14, v14
	s_waitcnt lgkmcnt(5)
	s_nop 0
	v_cvt_pk_bf16_f32 v10, v10, v10
	s_waitcnt lgkmcnt(4)
	s_nop 0
	v_cvt_pk_bf16_f32 v16, v16, v16
	v_cvt_pk_bf16_f32 v12, v12, v12
	v_and_b32_e32 v16, 0xffff0000, v16
	v_and_b32_e32 v12, 0xffff0000, v12
	v_or_b32_sdwa v29, v16, v14 dst_sel:DWORD dst_unused:UNUSED_PAD src0_sel:DWORD src1_sel:WORD_1
	s_waitcnt lgkmcnt(3)
	s_nop 0
	v_or_b32_sdwa v28, v12, v10 dst_sel:DWORD dst_unused:UNUSED_PAD src0_sel:DWORD src1_sel:WORD_1
	s_waitcnt lgkmcnt(2)
	s_nop 0
	s_waitcnt lgkmcnt(1)
	s_nop 0
	v_cvt_pk_bf16_f32 v16, v20, v20
	s_waitcnt lgkmcnt(0)
	s_nop 0
	v_cvt_pk_bf16_f32 v12, v18, v18
	v_cvt_pk_bf16_f32 v14, v24, v24
	v_and_b32_e32 v16, 0xffff0000, v16
	v_lshl_add_u64 v[8:9], s[0:1], 0, v[0:1]
	v_add_u32_e32 v40, s5, v7
	v_cvt_pk_bf16_f32 v10, v22, v22
	v_and_b32_e32 v14, 0xffff0000, v14
	v_or_b32_sdwa v30, v16, v12 dst_sel:DWORD dst_unused:UNUSED_PAD src0_sel:DWORD src1_sel:WORD_1
	s_nop 0
	v_mad_i64_i32 v[32:33], s[0:1], v40, s9, v[8:9]
	v_or_b32_sdwa v31, v14, v10 dst_sel:DWORD dst_unused:UNUSED_PAD src0_sel:DWORD src1_sel:WORD_1
	v_add_u32_e32 v10, 64, v40
	v_cvt_pk_bf16_f32 v12, v11, v11
	s_nop 0
	s_nop 0
	global_store_dwordx4 v[32:33], v[28:31], off
	v_cvt_pk_bf16_f32 v11, v17, v17
	v_cvt_pk_bf16_f32 v13, v13, v13
	v_mad_i64_i32 v[28:29], s[0:1], v10, s9, v[8:9]
	s_nop 0
	v_cvt_pk_bf16_f32 v10, v15, v15
	v_and_b32_e32 v11, 0xffff0000, v11
	v_and_b32_e32 v13, 0xffff0000, v13
	v_or_b32_sdwa v11, v11, v10 dst_sel:DWORD dst_unused:UNUSED_PAD src0_sel:DWORD src1_sel:WORD_1
	v_or_b32_sdwa v10, v13, v12 dst_sel:DWORD dst_unused:UNUSED_PAD src0_sel:DWORD src1_sel:WORD_1
	s_nop 0
	v_cvt_pk_bf16_f32 v14, v19, v19
	s_nop 0
	s_nop 0
	s_nop 0
	v_cvt_pk_bf16_f32 v13, v25, v25
	v_cvt_pk_bf16_f32 v15, v21, v21
	v_cvt_pk_bf16_f32 v12, v23, v23
	v_and_b32_e32 v13, 0xffff0000, v13
	v_and_b32_e32 v15, 0xffff0000, v15
	v_or_b32_sdwa v13, v13, v12 dst_sel:DWORD dst_unused:UNUSED_PAD src0_sel:DWORD src1_sel:WORD_1
	v_or_b32_sdwa v12, v15, v14 dst_sel:DWORD dst_unused:UNUSED_PAD src0_sel:DWORD src1_sel:WORD_1
	global_store_dwordx4 v[28:29], v[10:13], off
	ds_read2st64_b32 v[22:23], v5 offset0:2 offset1:3
	ds_read2st64_b32 v[18:19], v27 offset0:6 offset1:7
	ds_read2st64_b32 v[24:25], v34 offset0:10 offset1:11
	ds_read2st64_b32 v[20:21], v35 offset0:14 offset1:15
	ds_read2st64_b32 v[14:15], v36 offset0:18 offset1:19
	ds_read2st64_b32 v[10:11], v37 offset0:22 offset1:23
	ds_read2st64_b32 v[16:17], v38 offset0:26 offset1:27
	ds_read2st64_b32 v[12:13], v39 offset0:30 offset1:31
	v_add_u32_e32 v27, 0x80, v40
	v_mad_i64_i32 v[32:33], s[0:1], v27, s9, v[8:9]
	s_waitcnt lgkmcnt(5)
	v_and_b32_sdwa v27, v24, v178 dst_sel:DWORD dst_unused:UNUSED_PAD src0_sel:WORD_1 src1_sel:DWORD
	v_and_b32_sdwa v28, v22, v178 dst_sel:DWORD dst_unused:UNUSED_PAD src0_sel:WORD_1 src1_sel:DWORD
	v_add3_u32 v22, v22, v28, s81
	v_add3_u32 v24, v24, v27, s81
	s_waitcnt lgkmcnt(4)
	v_and_b32_sdwa v27, v20, v178 dst_sel:DWORD dst_unused:UNUSED_PAD src0_sel:WORD_1 src1_sel:DWORD
	s_nop 0
	v_add3_u32 v20, v20, v27, s81
	v_cvt_pk_bf16_f32 v18, v18, v18
	v_and_b32_e32 v20, 0xffff0000, v20
	v_and_b32_e32 v18, 0xffff0000, v18
	v_or_b32_sdwa v29, v20, v24 dst_sel:DWORD dst_unused:UNUSED_PAD src0_sel:DWORD src1_sel:WORD_1
	v_or_b32_sdwa v28, v18, v22 dst_sel:DWORD dst_unused:UNUSED_PAD src0_sel:DWORD src1_sel:WORD_1
	s_waitcnt lgkmcnt(1)
	v_and_b32_sdwa v18, v16, v178 dst_sel:DWORD dst_unused:UNUSED_PAD src0_sel:WORD_1 src1_sel:DWORD
	s_nop 0
	v_cvt_pk_bf16_f32 v14, v14, v14
	v_add3_u32 v16, v16, v18, s81
	s_waitcnt lgkmcnt(0)
	v_and_b32_sdwa v18, v12, v178 dst_sel:DWORD dst_unused:UNUSED_PAD src0_sel:WORD_1 src1_sel:DWORD
	v_and_b32_sdwa v20, v10, v178 dst_sel:DWORD dst_unused:UNUSED_PAD src0_sel:WORD_1 src1_sel:DWORD
	v_add3_u32 v12, v12, v18, s81
	v_add3_u32 v10, v10, v20, s81
	v_and_b32_e32 v12, 0xffff0000, v12
	v_and_b32_e32 v10, 0xffff0000, v10
	v_or_b32_sdwa v31, v12, v16 dst_sel:DWORD dst_unused:UNUSED_PAD src0_sel:DWORD src1_sel:WORD_1
	v_or_b32_sdwa v30, v10, v14 dst_sel:DWORD dst_unused:UNUSED_PAD src0_sel:DWORD src1_sel:WORD_1
	v_add_u32_e32 v10, 0xc0, v40
	global_store_dwordx4 v[32:33], v[28:31], off
	s_nop 0
	v_cvt_pk_bf16_f32 v12, v19, v19
	v_mad_i64_i32 v[28:29], s[0:1], v10, s9, v[8:9]
	s_nop 0
	v_cvt_pk_bf16_f32 v10, v23, v23
	s_nop 0
	s_nop 0
	v_cvt_pk_bf16_f32 v9, v21, v21
	v_cvt_pk_bf16_f32 v8, v25, v25
	v_and_b32_e32 v9, 0xffff0000, v9
	v_and_b32_e32 v12, 0xffff0000, v12
	v_or_b32_sdwa v9, v9, v8 dst_sel:DWORD dst_unused:UNUSED_PAD src0_sel:DWORD src1_sel:WORD_1
	v_or_b32_sdwa v8, v12, v10 dst_sel:DWORD dst_unused:UNUSED_PAD src0_sel:DWORD src1_sel:WORD_1
	v_and_b32_sdwa v12, v15, v178 dst_sel:DWORD dst_unused:UNUSED_PAD src0_sel:WORD_1 src1_sel:DWORD
	v_add3_u32 v12, v15, v12, s81
	s_nop 0
	v_and_b32_sdwa v15, v11, v178 dst_sel:DWORD dst_unused:UNUSED_PAD src0_sel:WORD_1 src1_sel:DWORD
	s_nop 0
	v_cvt_pk_bf16_f32 v13, v13, v13
	v_add3_u32 v11, v11, v15, s81
	v_cvt_pk_bf16_f32 v10, v17, v17
	v_and_b32_e32 v13, 0xffff0000, v13
	v_and_b32_e32 v14, 0xffff0000, v11
	v_or_b32_sdwa v11, v13, v10 dst_sel:DWORD dst_unused:UNUSED_PAD src0_sel:DWORD src1_sel:WORD_1
	v_or_b32_sdwa v10, v14, v12 dst_sel:DWORD dst_unused:UNUSED_PAD src0_sel:DWORD src1_sel:WORD_1
	global_store_dwordx4 v[28:29], v[8:11], off
	s_barrier
	s_cbranch_scc1 .LBB0_911
	s_mov_b32 s51, 0x10000

; __device__ __forceinline__ int srccol(int perm, int n) {
;     ...
;   } else if (perm == 2) {
;     if (n < 2048) {
;       int part = n >> 10, hh = (n >> 8) & 3, cp = n & 255;
;       int grp = cp >> 5, t = (cp >> 4) & 1, i = cp & 15;
;       int pp = grp * 16 + i;
;       return part * 1024 + hh * 256 + t * 128 + pp;
;     }
;     return n;
; __device__ __forceinline__ void conv_family(const float* __restrict__ W, u16* __restrict__ Wt, int cnt, int K, int N, int perm,
;                             float* tile, const int tid, const float* __restrict__ kscale = nullptr) {
;     ...
;   for (int t = blockIdx.x; t < total; t += gridDim.x) {
;     int mi = t / per, r = t % per, kt = r / tn, ntile = r % tn;
;     const float* Ws = W + (size_t)mi * K * N;
;     u16* Wd = Wt + (size_t)mi * K * N;
;     int k0 = kt * 64, n0 = ntile * 256;
;     {
;       int n = tid & 255;
;       int sc = srccol(perm, n0 + n);
;       const float* wp = Ws + (size_t)(k0 + (tid >> 8)) * N + sc;
.LBB0_915:
	s_mul_hi_i32 s0, s4, 0x2aaaaaab
	s_lshr_b32 s1, s0, 31
	s_ashr_i32 s0, s0, 6
	s_add_i32 s0, s0, s1
	s_mul_i32 s1, s0, 0xfffffe80
	s_add_i32 s1, s4, s1
	s_mul_i32 s2, s1, 0x2aab
	s_lshr_b32 s3, s2, 31
	s_ashr_i32 s2, s2, 18
	s_add_i32 s5, s2, s3
	s_mul_i32 s2, s5, 24
	s_sub_i32 s1, s1, s2
	s_sext_i32_i16 s8, s1
	s_mul_hi_i32 s1, s0, 0x600000
	s_mul_i32 s0, s0, 0x600000
	s_lshl_b64 s[2:3], s[0:1], 2
	s_add_u32 s2, s22, s2
	s_addc_u32 s3, s23, s3
	s_lshl_b64 s[0:1], s[0:1], 1
	s_add_u32 s6, s54, s0
	s_addc_u32 s7, s55, s1
	s_lshl_b32 s0, s5, 6
	s_lshl_b32 s5, s8, 8
	v_lshlrev_b32_e32 v9, 3, v3
	v_mov_b32_e32 v10, 0xffffff0f
	v_or_b32_e32 v8, s5, v3
	s_movk_i32 s1, 0x800
	v_and_b32_e32 v9, 0x80, v9
	v_bitop3_b32 v10, s5, v10, v3 bitop3:0xc8
	v_cmp_gt_i32_e32 vcc, s1, v8
	v_or3_b32 v9, v10, v5, v9
	v_mov_b64_e32 v[10:11], s[2:3]
	v_cndmask_b32_e32 v8, v8, v9, vcc
	v_bfe_u32 v12, v3, 5, 2
	v_lshlrev_b32_e32 v12, 6, v12
	v_and_b32_e32 v13, 15, v3
	v_lshl_add_u32 v12, v13, 2, v12
	v_bfe_u32 v13, v3, 7, 1
	v_lshl_add_u32 v12, v13, 1, v12
	v_bfe_u32 v13, v3, 4, 1
	v_add3_u32 v12, v12, v13, s5
	v_cmp_lt_u32_e32 vcc, 0xfff, v8
	s_nop 1
	v_cndmask_b32_e32 v8, v8, v12, vcc
	v_add_u32_e32 v9, s0, v4
	v_mad_i64_i32 v[10:11], s[2:3], v9, s10, v[10:11]
	v_ashrrev_i32_e32 v9, 31, v8
	v_lshl_add_u64 v[8:9], v[8:9], 2, v[10:11]
	v_add_co_u32_e32 v10, vcc, s12, v8
	global_load_dword v12, v[8:9], off
	s_nop 0
	v_addc_co_u32_e32 v11, vcc, 0, v9, vcc
	global_load_dword v13, v[10:11], off
	v_add_co_u32_e32 v10, vcc, s11, v8
	s_mov_b32 s1, 0xc0000
	s_nop 0
	v_addc_co_u32_e32 v11, vcc, 0, v9, vcc
	global_load_dword v14, v[10:11], off
	v_add_co_u32_e32 v10, vcc, s30, v8
	s_nop 1
	v_addc_co_u32_e32 v11, vcc, 0, v9, vcc
	global_load_dword v15, v[10:11], off
	v_add_co_u32_e32 v10, vcc, s56, v8
	s_nop 1
	v_addc_co_u32_e32 v11, vcc, 0, v9, vcc
	global_load_dword v16, v[10:11], off
	v_add_co_u32_e32 v10, vcc, s15, v8
	s_nop 1
	v_addc_co_u32_e32 v11, vcc, 0, v9, vcc
	global_load_dword v17, v[10:11], off
	v_add_co_u32_e32 v10, vcc, s34, v8
	s_nop 1
	v_addc_co_u32_e32 v11, vcc, 0, v9, vcc
	global_load_dword v18, v[10:11], off
	v_add_co_u32_e32 v10, vcc, s16, v8
	s_nop 1
	v_addc_co_u32_e32 v11, vcc, 0, v9, vcc
	global_load_dword v19, v[10:11], off
	v_add_co_u32_e32 v10, vcc, s17, v8
	s_nop 1
	v_addc_co_u32_e32 v11, vcc, 0, v9, vcc
	global_load_dword v20, v[10:11], off
	v_add_co_u32_e32 v10, vcc, s97, v8
	s_nop 1
	v_addc_co_u32_e32 v11, vcc, 0, v9, vcc
	global_load_dword v21, v[10:11], off
	v_add_co_u32_e32 v10, vcc, s18, v8
	s_nop 1
	v_addc_co_u32_e32 v11, vcc, 0, v9, vcc
	global_load_dword v22, v[10:11], off
	v_add_co_u32_e32 v10, vcc, s13, v8
	s_nop 1
	v_addc_co_u32_e32 v11, vcc, 0, v9, vcc
	global_load_dword v23, v[10:11], off
	v_add_co_u32_e32 v10, vcc, s9, v8
	s_nop 1
	v_addc_co_u32_e32 v11, vcc, 0, v9, vcc
	global_load_dword v24, v[10:11], off
	v_add_co_u32_e32 v10, vcc, s19, v8
	s_nop 1
	v_addc_co_u32_e32 v11, vcc, 0, v9, vcc
	global_load_dword v25, v[10:11], off
	v_add_co_u32_e32 v10, vcc, s20, v8
	s_nop 1
	v_addc_co_u32_e32 v11, vcc, 0, v9, vcc
	global_load_dword v26, v[10:11], off
	v_add_co_u32_e32 v10, vcc, s21, v8
	s_nop 1
	v_addc_co_u32_e32 v11, vcc, 0, v9, vcc
	global_load_dword v27, v[10:11], off
	v_add_co_u32_e32 v10, vcc, s1, v8
	s_mov_b32 s1, 0xcc000
	s_nop 0
	v_addc_co_u32_e32 v11, vcc, 0, v9, vcc
	global_load_dword v30, v[10:11], off
	v_add_co_u32_e32 v10, vcc, s1, v8
	s_mov_b32 s1, 0xd8000
	s_nop 0
	v_addc_co_u32_e32 v11, vcc, 0, v9, vcc
	global_load_dword v31, v[10:11], off
	v_add_co_u32_e32 v10, vcc, s1, v8
	s_mov_b32 s1, 0xe4000
	s_nop 0
	v_addc_co_u32_e32 v11, vcc, 0, v9, vcc
	global_load_dword v32, v[10:11], off
	v_add_co_u32_e32 v10, vcc, s1, v8
	s_mov_b32 s1, 0xf0000
	s_nop 0
	v_addc_co_u32_e32 v11, vcc, 0, v9, vcc
	global_load_dword v33, v[10:11], off
	v_add_co_u32_e32 v10, vcc, s1, v8
	s_mov_b32 s1, 0xfc000
	s_nop 0
	v_addc_co_u32_e32 v11, vcc, 0, v9, vcc
	global_load_dword v34, v[10:11], off
	v_add_co_u32_e32 v10, vcc, s1, v8
	s_mov_b32 s1, 0x114000
	s_nop 0
	v_addc_co_u32_e32 v11, vcc, 0, v9, vcc
	global_load_dword v35, v[10:11], off
	v_add_co_u32_e32 v10, vcc, s14, v8
	s_nop 1
	v_addc_co_u32_e32 v11, vcc, 0, v9, vcc
	global_load_dword v36, v[10:11], off
	v_add_co_u32_e32 v10, vcc, s1, v8
	s_mov_b32 s1, 0x120000
	s_nop 0
	v_addc_co_u32_e32 v11, vcc, 0, v9, vcc
	global_load_dword v37, v[10:11], off
	v_add_co_u32_e32 v10, vcc, s1, v8
	s_mov_b32 s1, 0x12c000
	s_nop 0
	v_addc_co_u32_e32 v11, vcc, 0, v9, vcc
	global_load_dword v38, v[10:11], off
	v_add_co_u32_e32 v10, vcc, s1, v8
	s_mov_b32 s1, 0x138000
	s_nop 0
	v_addc_co_u32_e32 v11, vcc, 0, v9, vcc
	global_load_dword v39, v[10:11], off
	v_add_co_u32_e32 v10, vcc, s1, v8
	s_mov_b32 s1, 0x144000
	s_nop 0
	v_addc_co_u32_e32 v11, vcc, 0, v9, vcc
	global_load_dword v40, v[10:11], off
	v_add_co_u32_e32 v10, vcc, s1, v8
	s_mov_b32 s1, 0x150000
	s_nop 0
	v_addc_co_u32_e32 v11, vcc, 0, v9, vcc
	global_load_dword v41, v[10:11], off
	v_add_co_u32_e32 v10, vcc, s1, v8
	s_mov_b32 s1, 0x15c000
	s_nop 0
	v_addc_co_u32_e32 v11, vcc, 0, v9, vcc
	global_load_dword v42, v[10:11], off
	v_add_co_u32_e32 v10, vcc, s1, v8
	s_mov_b32 s1, 0x168000
	s_nop 0
	v_addc_co_u32_e32 v11, vcc, 0, v9, vcc
	global_load_dword v43, v[10:11], off
	v_add_co_u32_e32 v10, vcc, s1, v8
	s_mov_b32 s1, 0x174000
	s_nop 0
	v_addc_co_u32_e32 v11, vcc, 0, v9, vcc
	v_add_co_u32_e32 v8, vcc, s1, v8
	global_load_dword v10, v[10:11], off
	s_nop 0
	v_addc_co_u32_e32 v9, vcc, 0, v9, vcc
	global_load_dword v8, v[8:9], off
	s_waitcnt vmcnt(31)
	ds_write_b32 v29, v12
	s_waitcnt vmcnt(30)
	ds_write_b32 v29, v13 offset:2056
	s_waitcnt vmcnt(29)
; __device__ __forceinline__ void conv_family(const float* __restrict__ W, u16* __restrict__ Wt, int cnt, int K, int N, int perm,
;                             float* tile, const int tid, const float* __restrict__ kscale = nullptr) {
;     ...
; #pragma unroll
;       for (int i = 0; i < 32; ++i) tile[(2 * i + (tid >> 8)) * 257 + n] = v[i];
;     }
;     __syncthreads();
	ds_write_b32 v29, v14 offset:4112
	s_waitcnt vmcnt(28)
	ds_write_b32 v29, v15 offset:6168
	s_waitcnt vmcnt(27)
	ds_write_b32 v29, v16 offset:8224
	s_waitcnt vmcnt(26)
	ds_write_b32 v29, v17 offset:10280
	s_waitcnt vmcnt(25)
	ds_write_b32 v29, v18 offset:12336
	s_waitcnt vmcnt(24)
	ds_write_b32 v29, v19 offset:14392
	s_waitcnt vmcnt(23)
	ds_write_b32 v29, v20 offset:16448
	s_waitcnt vmcnt(22)
	ds_write_b32 v29, v21 offset:18504
	s_waitcnt vmcnt(21)
	ds_write_b32 v29, v22 offset:20560
	s_waitcnt vmcnt(20)
	ds_write_b32 v29, v23 offset:22616
	s_waitcnt vmcnt(19)
	ds_write_b32 v29, v24 offset:24672
	s_waitcnt vmcnt(18)
	ds_write_b32 v29, v25 offset:26728
	s_waitcnt vmcnt(17)
	ds_write_b32 v29, v26 offset:28784
	s_waitcnt vmcnt(16)
	ds_write_b32 v29, v27 offset:30840
	s_waitcnt vmcnt(15)
	ds_write_b32 v29, v30 offset:32896
	s_waitcnt vmcnt(14)
	ds_write_b32 v29, v31 offset:34952
	s_waitcnt vmcnt(13)
	ds_write_b32 v29, v32 offset:37008
	s_waitcnt vmcnt(12)
	ds_write_b32 v29, v33 offset:39064
	s_waitcnt vmcnt(11)
	ds_write_b32 v29, v34 offset:41120
	s_waitcnt vmcnt(10)
	ds_write_b32 v29, v35 offset:43176
	s_waitcnt vmcnt(9)
	ds_write_b32 v29, v36 offset:45232
	s_waitcnt vmcnt(8)
	ds_write_b32 v29, v37 offset:47288
	s_waitcnt vmcnt(7)
	ds_write_b32 v29, v38 offset:49344
	s_waitcnt vmcnt(6)
	ds_write_b32 v29, v39 offset:51400
	s_waitcnt vmcnt(5)
	ds_write_b32 v29, v40 offset:53456
	s_waitcnt vmcnt(4)
	ds_write_b32 v29, v41 offset:55512
	s_waitcnt vmcnt(3)
	ds_write_b32 v29, v42 offset:57568
	s_waitcnt vmcnt(2)
	ds_write_b32 v29, v43 offset:59624
	s_waitcnt vmcnt(1)
	ds_write_b32 v29, v10 offset:61680
	s_waitcnt vmcnt(0)
	ds_write_b32 v29, v8 offset:63736
	v_add_u32_e32 v37, 8, v28
	s_waitcnt lgkmcnt(0)
	s_barrier
; __device__ __forceinline__ unsigned pack2(float a, float b) { return (unsigned)f2bf(a) | ((unsigned)f2bf(b) << 16); }
; __device__ __forceinline__ void conv_family(const float* __restrict__ W, u16* __restrict__ Wt, int cnt, int K, int N, int perm,
;                             float* tile, const int tid, const float* __restrict__ kscale = nullptr) {
;     ...
; #pragma unroll
;     for (int i = 0; i < 4; ++i) {
;       int n = i * 64 + (tid >> 3), ks = (tid & 7) * 8;
;       uint4 pk;
;       pk.x = pack2(tile[(ks + 0) * 257 + n], tile[(ks + 1) * 257 + n]);
;       pk.y = pack2(tile[(ks + 2) * 257 + n], tile[(ks + 3) * 257 + n]);
;       pk.z = pack2(tile[(ks + 4) * 257 + n], tile[(ks + 5) * 257 + n]);
;       pk.w = pack2(tile[(ks + 6) * 257 + n], tile[(ks + 7) * 257 + n]);
;       *(uint4*)(Wd + (size_t)(n0 + n) * K + k0 + ks) = pk;
;     }
;     __syncthreads();
;   }
	ds_read2st64_b32 v[16:17], v37 offset0:8 offset1:9
	v_add_u32_e32 v38, 12, v28
	ds_read2st64_b32 v[18:19], v38 offset0:12 offset1:13
	s_ashr_i32 s1, s0, 31
	ds_read2st64_b32 v[10:11], v28 offset1:1
	v_add_u32_e32 v36, 4, v28
	s_lshl_b64 s[0:1], s[0:1], 1
	ds_read2st64_b32 v[14:15], v36 offset0:4 offset1:5
	v_add_u32_e32 v40, 20, v28
	v_add_u32_e32 v12, s5, v7
	s_add_u32 s0, s6, s0
	v_add_u32_e32 v39, 16, v28
	ds_read2st64_b32 v[22:23], v40 offset0:20 offset1:21
	v_ashrrev_i32_e32 v13, 31, v12
	s_addc_u32 s1, s7, s1
	ds_read2st64_b32 v[20:21], v39 offset0:16 offset1:17
	v_add_u32_e32 v42, 28, v28
	v_lshlrev_b64 v[30:31], 11, v[12:13]
	s_waitcnt lgkmcnt(5)
	s_nop 0
	v_lshl_add_u64 v[8:9], s[0:1], 0, v[0:1]
	v_add_u32_e32 v41, 24, v28
	ds_read2st64_b32 v[26:27], v42 offset0:28 offset1:29
	v_cvt_pk_bf16_f32 v13, v16, v16
	s_waitcnt lgkmcnt(5)
	s_nop 0
	ds_read2st64_b32 v[24:25], v41 offset0:24 offset1:25
	v_lshl_add_u64 v[34:35], v[8:9], 0, v[30:31]
	s_waitcnt lgkmcnt(5)
	s_nop 0
	v_cvt_pk_bf16_f32 v16, v18, v18
	v_cvt_pk_bf16_f32 v10, v10, v10
	s_waitcnt lgkmcnt(4)
	s_nop 0
	v_and_b32_e32 v16, 0xffff0000, v16
	v_cvt_pk_bf16_f32 v14, v14, v14
	v_or_b32_sdwa v31, v16, v13 dst_sel:DWORD dst_unused:UNUSED_PAD src0_sel:DWORD src1_sel:WORD_1
	s_waitcnt lgkmcnt(3)
	s_nop 0
	v_and_b32_e32 v14, 0xffff0000, v14
	s_waitcnt lgkmcnt(2)
	s_nop 0
	v_cvt_pk_bf16_f32 v16, v22, v22
	v_or_b32_sdwa v30, v14, v10 dst_sel:DWORD dst_unused:UNUSED_PAD src0_sel:DWORD src1_sel:WORD_1
	v_cvt_pk_bf16_f32 v13, v20, v20
	s_waitcnt lgkmcnt(1)
	s_nop 0
	v_and_b32_e32 v16, 0xffff0000, v16
	s_waitcnt lgkmcnt(0)
	s_nop 0
	v_cvt_pk_bf16_f32 v14, v26, v26
	v_or_b32_sdwa v32, v16, v13 dst_sel:DWORD dst_unused:UNUSED_PAD src0_sel:DWORD src1_sel:WORD_1
	s_nop 0
	v_cvt_pk_bf16_f32 v10, v24, v24
	v_and_b32_e32 v14, 0xffff0000, v14
	v_cvt_pk_bf16_f32 v11, v11, v11
	s_nop 0
	v_or_b32_sdwa v33, v14, v10 dst_sel:DWORD dst_unused:UNUSED_PAD src0_sel:DWORD src1_sel:WORD_1
	s_nop 0
	s_nop 0
	v_cvt_pk_bf16_f32 v13, v19, v19
	v_cvt_pk_bf16_f32 v10, v17, v17
	v_cvt_pk_bf16_f32 v14, v15, v15
	v_and_b32_e32 v13, 0xffff0000, v13
	global_store_dwordx4 v[34:35], v[30:33], off
	v_and_b32_e32 v14, 0xffff0000, v14
	v_or_b32_sdwa v15, v13, v10 dst_sel:DWORD dst_unused:UNUSED_PAD src0_sel:DWORD src1_sel:WORD_1
	v_add_u32_e32 v30, 64, v12
	s_nop 0
	s_nop 0
	v_ashrrev_i32_e32 v31, 31, v30
	v_or_b32_sdwa v14, v14, v11 dst_sel:DWORD dst_unused:UNUSED_PAD src0_sel:DWORD src1_sel:WORD_1
	s_nop 0
	s_nop 0
	v_cvt_pk_bf16_f32 v13, v27, v27
	v_cvt_pk_bf16_f32 v16, v23, v23
	v_lshlrev_b64 v[30:31], 11, v[30:31]
	v_cvt_pk_bf16_f32 v11, v21, v21
	v_cvt_pk_bf16_f32 v10, v25, v25
	v_and_b32_e32 v13, 0xffff0000, v13
	v_and_b32_e32 v16, 0xffff0000, v16
	v_lshl_add_u64 v[30:31], v[8:9], 0, v[30:31]
	v_or_b32_sdwa v17, v13, v10 dst_sel:DWORD dst_unused:UNUSED_PAD src0_sel:DWORD src1_sel:WORD_1
	v_or_b32_sdwa v16, v16, v11 dst_sel:DWORD dst_unused:UNUSED_PAD src0_sel:DWORD src1_sel:WORD_1
	global_store_dwordx4 v[30:31], v[14:17], off
	ds_read2st64_b32 v[24:25], v28 offset0:2 offset1:3
	ds_read2st64_b32 v[20:21], v36 offset0:6 offset1:7
	ds_read2st64_b32 v[26:27], v37 offset0:10 offset1:11
	ds_read2st64_b32 v[22:23], v38 offset0:14 offset1:15
	ds_read2st64_b32 v[16:17], v39 offset0:18 offset1:19
	ds_read2st64_b32 v[10:11], v40 offset0:22 offset1:23
	ds_read2st64_b32 v[18:19], v41 offset0:26 offset1:27
	ds_read2st64_b32 v[14:15], v42 offset0:30 offset1:31
	v_add_u32_e32 v30, 0x80, v12
	s_waitcnt lgkmcnt(5)
	s_nop 0
	v_ashrrev_i32_e32 v31, 31, v30
	v_cvt_pk_bf16_f32 v13, v26, v26
	s_waitcnt lgkmcnt(4)
	v_and_b32_sdwa v26, v22, v178 dst_sel:DWORD dst_unused:UNUSED_PAD src0_sel:WORD_1 src1_sel:DWORD
	v_lshlrev_b64 v[30:31], 11, v[30:31]
	v_add3_u32 v22, v22, v26, s81
	v_lshl_add_u64 v[34:35], v[8:9], 0, v[30:31]
	v_and_b32_sdwa v30, v24, v178 dst_sel:DWORD dst_unused:UNUSED_PAD src0_sel:WORD_1 src1_sel:DWORD
	v_and_b32_e32 v22, 0xffff0000, v22
	v_add3_u32 v24, v24, v30, s81
	s_nop 0
	v_or_b32_sdwa v31, v22, v13 dst_sel:DWORD dst_unused:UNUSED_PAD src0_sel:DWORD src1_sel:WORD_1
	s_waitcnt lgkmcnt(1)
	s_nop 0
	v_cvt_pk_bf16_f32 v20, v20, v20
	v_cvt_pk_bf16_f32 v13, v18, v18
	s_waitcnt lgkmcnt(0)
	v_and_b32_sdwa v18, v14, v178 dst_sel:DWORD dst_unused:UNUSED_PAD src0_sel:WORD_1 src1_sel:DWORD
	v_and_b32_e32 v20, 0xffff0000, v20
	v_add3_u32 v14, v14, v18, s81
	v_or_b32_sdwa v30, v20, v24 dst_sel:DWORD dst_unused:UNUSED_PAD src0_sel:DWORD src1_sel:WORD_1
	s_nop 0
	v_and_b32_e32 v14, 0xffff0000, v14
	v_add_u32_e32 v12, 0xc0, v12
	v_cvt_pk_bf16_f32 v16, v16, v16
	v_and_b32_sdwa v20, v10, v178 dst_sel:DWORD dst_unused:UNUSED_PAD src0_sel:WORD_1 src1_sel:DWORD
	v_or_b32_sdwa v33, v14, v13 dst_sel:DWORD dst_unused:UNUSED_PAD src0_sel:DWORD src1_sel:WORD_1
	v_ashrrev_i32_e32 v13, 31, v12
	v_add3_u32 v10, v10, v20, s81
	v_lshlrev_b64 v[12:13], 11, v[12:13]
	v_and_b32_e32 v10, 0xffff0000, v10
	v_lshl_add_u64 v[12:13], v[8:9], 0, v[12:13]
	s_nop 0
	v_or_b32_sdwa v32, v10, v16 dst_sel:DWORD dst_unused:UNUSED_PAD src0_sel:DWORD src1_sel:WORD_1
	v_cvt_pk_bf16_f32 v10, v25, v25
	s_nop 0
	s_nop 0
	s_nop 0
	v_cvt_pk_bf16_f32 v9, v23, v23
	v_cvt_pk_bf16_f32 v14, v21, v21
	v_cvt_pk_bf16_f32 v8, v27, v27
	v_and_b32_e32 v9, 0xffff0000, v9
	v_and_b32_e32 v14, 0xffff0000, v14
	v_or_b32_sdwa v9, v9, v8 dst_sel:DWORD dst_unused:UNUSED_PAD src0_sel:DWORD src1_sel:WORD_1
	v_or_b32_sdwa v8, v14, v10 dst_sel:DWORD dst_unused:UNUSED_PAD src0_sel:DWORD src1_sel:WORD_1
	v_and_b32_sdwa v14, v17, v178 dst_sel:DWORD dst_unused:UNUSED_PAD src0_sel:WORD_1 src1_sel:DWORD
	v_add3_u32 v14, v17, v14, s81
	s_nop 0
	v_and_b32_sdwa v17, v11, v178 dst_sel:DWORD dst_unused:UNUSED_PAD src0_sel:WORD_1 src1_sel:DWORD
	s_nop 0
	v_cvt_pk_bf16_f32 v15, v15, v15
	v_add3_u32 v11, v11, v17, s81
	v_cvt_pk_bf16_f32 v10, v19, v19
	v_and_b32_e32 v15, 0xffff0000, v15
	v_and_b32_e32 v16, 0xffff0000, v11
	s_add_i32 s4, s4, s44
	v_or_b32_sdwa v11, v15, v10 dst_sel:DWORD dst_unused:UNUSED_PAD src0_sel:DWORD src1_sel:WORD_1
	v_or_b32_sdwa v10, v16, v14 dst_sel:DWORD dst_unused:UNUSED_PAD src0_sel:DWORD src1_sel:WORD_1
	s_cmpk_lt_i32 s4, 0x300
	global_store_dwordx4 v[34:35], v[30:33], off
	global_store_dwordx4 v[12:13], v[8:11], off
	s_barrier
	s_cbranch_scc1 .LBB0_915
	s_mov_b32 s38, 0x1e000
	s_mov_b32 s39, 0x2c000
	s_mov_b32 s40, 0x22000
	s_mov_b32 s41, 0x26000
	s_mov_b32 s43, 0x2a000
	s_mov_b32 s48, 0x2e000
	s_mov_b32 s54, 0x32000
	s_mov_b32 s55, 0x34000
	s_mov_b32 s57, 0x38000

; __device__ __forceinline__ void conv_family(const float* __restrict__ W, u16* __restrict__ Wt, int cnt, int K, int N, int perm,
;                             float* tile, const int tid, const float* __restrict__ kscale = nullptr) {
;     ...
;       if (kscale) {
;         const float* ks = kscale + (size_t)mi * K + k0 + (tid >> 8);
; #pragma unroll
;         for (int i = 0; i < 32; ++i) v[i] *= ks[2 * i];
;       }
; #pragma unroll
;       for (int i = 0; i < 32; ++i) tile[(2 * i + (tid >> 8)) * 257 + n] = v[i];
;     }
;     __syncthreads();
.LBB0_919:
	s_lshl_b64 s[2:3], s[2:3], 21
	v_readlane_b32 s8, v252, 26
	s_lshl_b64 s[2:3], s[2:3], 1
	v_readlane_b32 s12, v252, 30
	v_readlane_b32 s13, v252, 31
	s_add_u32 s2, s12, s2
	ds_write_b32 v78, v70
	ds_write_b32 v78, v71 offset:2056
	ds_write_b32 v78, v68 offset:4112
	ds_write_b32 v78, v69 offset:6168
	ds_write_b32 v78, v66 offset:8224
	ds_write_b32 v78, v67 offset:10280
	ds_write_b32 v78, v64 offset:12336
	ds_write_b32 v78, v65 offset:14392
	ds_write_b32 v78, v62 offset:16448
	ds_write_b32 v78, v63 offset:18504
	ds_write_b32 v78, v60 offset:20560
	ds_write_b32 v78, v61 offset:22616
	ds_write_b32 v78, v58 offset:24672
	ds_write_b32 v78, v59 offset:26728
	ds_write_b32 v78, v56 offset:28784
	ds_write_b32 v78, v57 offset:30840
	ds_write_b32 v78, v54 offset:32896
	ds_write_b32 v78, v55 offset:34952
	ds_write_b32 v78, v52 offset:37008
	ds_write_b32 v78, v53 offset:39064
	ds_write_b32 v78, v50 offset:41120
	ds_write_b32 v78, v51 offset:43176
	ds_write_b32 v78, v48 offset:45232
	ds_write_b32 v78, v49 offset:47288
	ds_write_b32 v78, v46 offset:49344
	ds_write_b32 v78, v47 offset:51400
	ds_write_b32 v78, v44 offset:53456
	ds_write_b32 v78, v45 offset:55512
	ds_write_b32 v78, v42 offset:57568
	ds_write_b32 v78, v43 offset:59624
	ds_write_b32 v78, v40 offset:61680
	ds_write_b32 v78, v41 offset:63736
	s_waitcnt lgkmcnt(0)
	s_barrier
; __device__ __forceinline__ unsigned pack2(float a, float b) { return (unsigned)f2bf(a) | ((unsigned)f2bf(b) << 16); }
; __device__ __forceinline__ void conv_family(const float* __restrict__ W, u16* __restrict__ Wt, int cnt, int K, int N, int perm,
;                             float* tile, const int tid, const float* __restrict__ kscale = nullptr) {
;     ...
; #pragma unroll
;     for (int i = 0; i < 4; ++i) {
;       int n = i * 64 + (tid >> 3), ks = (tid & 7) * 8;
;       uint4 pk;
;       pk.x = pack2(tile[(ks + 0) * 257 + n], tile[(ks + 1) * 257 + n]);
;       pk.y = pack2(tile[(ks + 2) * 257 + n], tile[(ks + 3) * 257 + n]);
;       pk.z = pack2(tile[(ks + 4) * 257 + n], tile[(ks + 5) * 257 + n]);
;       pk.w = pack2(tile[(ks + 6) * 257 + n], tile[(ks + 7) * 257 + n]);
;       *(uint4*)(Wd + (size_t)(n0 + n) * K + k0 + ks) = pk;
;     }
;     __syncthreads();
;   }
	s_waitcnt vmcnt(30)
	ds_read2st64_b32 v[14:15], v77 offset1:1
	s_waitcnt vmcnt(4)
	ds_read2st64_b32 v[36:37], v77 offset0:2 offset1:3
	v_add_u32_e32 v10, 4, v77
	v_add_u32_e32 v38, 12, v77
	s_addc_u32 s3, s13, s3
	s_lshl_b64 s[0:1], s[0:1], 1
	ds_read2st64_b32 v[16:17], v10 offset0:4 offset1:5
	ds_read2st64_b32 v[40:41], v10 offset0:6 offset1:7
	v_add_u32_e32 v11, 8, v77
	ds_read2st64_b32 v[20:21], v38 offset0:12 offset1:13
	s_add_u32 s0, s2, s0
	ds_read2st64_b32 v[18:19], v11 offset0:8 offset1:9
	s_waitcnt vmcnt(2)
	ds_read2st64_b32 v[34:35], v11 offset0:10 offset1:11
	v_add_u32_e32 v30, s7, v7
	s_addc_u32 s1, s3, s1
	v_add_u32_e32 v44, 16, v77
	v_ashrrev_i32_e32 v31, 31, v30
	v_lshl_add_u64 v[12:13], s[0:1], 0, v[0:1]
	ds_read2st64_b32 v[22:23], v44 offset0:16 offset1:17
	v_add_u32_e32 v48, 20, v77
	v_add_u32_e32 v46, 28, v77
	v_lshlrev_b64 v[8:9], 12, v[30:31]
	ds_read2st64_b32 v[24:25], v48 offset0:20 offset1:21
	v_add_u32_e32 v42, 24, v77
	ds_read2st64_b32 v[28:29], v46 offset0:28 offset1:29
	s_waitcnt vmcnt(0)
	v_lshl_add_u64 v[32:33], v[12:13], 0, v[8:9]
	s_waitcnt lgkmcnt(9)
	s_nop 0
	ds_read2st64_b32 v[26:27], v42 offset0:24 offset1:25
	v_cvt_pk_bf16_f32 v11, v14, v14
	s_waitcnt lgkmcnt(6)
	s_nop 0
	s_nop 0
	s_waitcnt lgkmcnt(5)
	s_nop 0
	v_cvt_pk_bf16_f32 v9, v20, v20
	v_cvt_pk_bf16_f32 v10, v16, v16
	v_cvt_pk_bf16_f32 v8, v18, v18
	v_and_b32_e32 v9, 0xffff0000, v9
	v_and_b32_e32 v10, 0xffff0000, v10
	v_or_b32_sdwa v9, v9, v8 dst_sel:DWORD dst_unused:UNUSED_PAD src0_sel:DWORD src1_sel:WORD_1
	v_or_b32_sdwa v8, v10, v11 dst_sel:DWORD dst_unused:UNUSED_PAD src0_sel:DWORD src1_sel:WORD_1
	s_waitcnt lgkmcnt(3)
	s_nop 0
	v_cvt_pk_bf16_f32 v14, v22, v22
	s_waitcnt lgkmcnt(1)
	s_nop 0
	s_nop 0
	s_waitcnt lgkmcnt(0)
	s_nop 0
	v_cvt_pk_bf16_f32 v11, v28, v28
	v_cvt_pk_bf16_f32 v16, v24, v24
	v_cvt_pk_bf16_f32 v10, v26, v26
	v_and_b32_e32 v11, 0xffff0000, v11
	v_and_b32_e32 v16, 0xffff0000, v16
	v_or_b32_sdwa v11, v11, v10 dst_sel:DWORD dst_unused:UNUSED_PAD src0_sel:DWORD src1_sel:WORD_1
	v_or_b32_sdwa v10, v16, v14 dst_sel:DWORD dst_unused:UNUSED_PAD src0_sel:DWORD src1_sel:WORD_1
	global_store_dwordx4 v[32:33], v[8:11], off
	ds_read2st64_b32 v[38:39], v38 offset0:14 offset1:15
	ds_read2st64_b32 v[44:45], v44 offset0:18 offset1:19
	v_add_u32_e32 v8, 64, v30
	v_ashrrev_i32_e32 v9, 31, v8
	v_lshlrev_b64 v[8:9], 12, v[8:9]
	v_lshl_add_u64 v[32:33], v[12:13], 0, v[8:9]
	s_nop 0
	v_cvt_pk_bf16_f32 v10, v15, v15
	s_nop 0
	s_nop 0
	s_nop 0
	v_cvt_pk_bf16_f32 v9, v21, v21
	v_cvt_pk_bf16_f32 v11, v17, v17
	v_cvt_pk_bf16_f32 v8, v19, v19
	v_and_b32_e32 v9, 0xffff0000, v9
	v_and_b32_e32 v11, 0xffff0000, v11
	v_or_b32_sdwa v9, v9, v8 dst_sel:DWORD dst_unused:UNUSED_PAD src0_sel:DWORD src1_sel:WORD_1
	v_or_b32_sdwa v8, v11, v10 dst_sel:DWORD dst_unused:UNUSED_PAD src0_sel:DWORD src1_sel:WORD_1
	s_nop 0
	v_cvt_pk_bf16_f32 v14, v23, v23
	s_nop 0
	s_nop 0
	s_nop 0
	v_cvt_pk_bf16_f32 v11, v29, v29
	v_cvt_pk_bf16_f32 v15, v25, v25
	v_cvt_pk_bf16_f32 v10, v27, v27
	v_and_b32_e32 v11, 0xffff0000, v11
	v_and_b32_e32 v15, 0xffff0000, v15
	v_or_b32_sdwa v11, v11, v10 dst_sel:DWORD dst_unused:UNUSED_PAD src0_sel:DWORD src1_sel:WORD_1
	v_or_b32_sdwa v10, v15, v14 dst_sel:DWORD dst_unused:UNUSED_PAD src0_sel:DWORD src1_sel:WORD_1
	global_store_dwordx4 v[32:33], v[8:11], off
	ds_read2st64_b32 v[46:47], v46 offset0:30 offset1:31
	ds_read2st64_b32 v[48:49], v48 offset0:22 offset1:23
	v_add_u32_e32 v8, 0x80, v30
	v_ashrrev_i32_e32 v9, 31, v8
	v_lshlrev_b64 v[8:9], 12, v[8:9]
	v_lshl_add_u64 v[14:15], v[12:13], 0, v[8:9]
	s_nop 0
	ds_read2st64_b32 v[42:43], v42 offset0:26 offset1:27
	v_cvt_pk_bf16_f32 v10, v36, v36
	s_waitcnt lgkmcnt(4)
	s_nop 0
	s_nop 0
	s_nop 0
	v_cvt_pk_bf16_f32 v9, v38, v38
	v_cvt_pk_bf16_f32 v11, v40, v40
	v_cvt_pk_bf16_f32 v8, v34, v34
	v_and_b32_e32 v9, 0xffff0000, v9
	v_and_b32_e32 v11, 0xffff0000, v11
	v_or_b32_sdwa v9, v9, v8 dst_sel:DWORD dst_unused:UNUSED_PAD src0_sel:DWORD src1_sel:WORD_1
	v_or_b32_sdwa v8, v11, v10 dst_sel:DWORD dst_unused:UNUSED_PAD src0_sel:DWORD src1_sel:WORD_1
	s_waitcnt lgkmcnt(3)
	v_and_b32_sdwa v11, v44, v178 dst_sel:DWORD dst_unused:UNUSED_PAD src0_sel:WORD_1 src1_sel:DWORD
	v_add3_u32 v16, v44, v11, s81
	s_waitcnt lgkmcnt(2)
	s_nop 0
	s_waitcnt lgkmcnt(1)
	s_nop 0
	s_waitcnt lgkmcnt(0)
	s_nop 0
	v_cvt_pk_bf16_f32 v11, v46, v46
	v_cvt_pk_bf16_f32 v17, v48, v48
	v_cvt_pk_bf16_f32 v10, v42, v42
	v_and_b32_e32 v11, 0xffff0000, v11
	v_and_b32_e32 v17, 0xffff0000, v17
	v_or_b32_sdwa v11, v11, v10 dst_sel:DWORD dst_unused:UNUSED_PAD src0_sel:DWORD src1_sel:WORD_1
	v_or_b32_sdwa v10, v17, v16 dst_sel:DWORD dst_unused:UNUSED_PAD src0_sel:DWORD src1_sel:WORD_1
	global_store_dwordx4 v[14:15], v[8:11], off
	s_nop 0
	v_cvt_pk_bf16_f32 v15, v49, v49
	v_add_u32_e32 v8, 0xc0, v30
	v_ashrrev_i32_e32 v9, 31, v8
	v_lshlrev_b64 v[8:9], 12, v[8:9]
	v_lshl_add_u64 v[12:13], v[12:13], 0, v[8:9]
	s_nop 0
	v_cvt_pk_bf16_f32 v10, v37, v37
	s_nop 0
	s_nop 0
	s_nop 0
	v_cvt_pk_bf16_f32 v9, v39, v39
	v_cvt_pk_bf16_f32 v11, v41, v41
	v_cvt_pk_bf16_f32 v8, v35, v35
	v_and_b32_e32 v9, 0xffff0000, v9
	v_and_b32_e32 v11, 0xffff0000, v11
	v_or_b32_sdwa v9, v9, v8 dst_sel:DWORD dst_unused:UNUSED_PAD src0_sel:DWORD src1_sel:WORD_1
	v_or_b32_sdwa v8, v11, v10 dst_sel:DWORD dst_unused:UNUSED_PAD src0_sel:DWORD src1_sel:WORD_1
	v_and_b32_sdwa v11, v45, v178 dst_sel:DWORD dst_unused:UNUSED_PAD src0_sel:WORD_1 src1_sel:DWORD
	v_add3_u32 v14, v45, v11, s81
	s_nop 0
	s_nop 0
	v_cvt_pk_bf16_f32 v11, v47, v47
	v_cvt_pk_bf16_f32 v10, v43, v43
	v_and_b32_e32 v11, 0xffff0000, v11
	v_and_b32_e32 v15, 0xffff0000, v15
	s_add_i32 s6, s6, s44
	v_or_b32_sdwa v11, v11, v10 dst_sel:DWORD dst_unused:UNUSED_PAD src0_sel:DWORD src1_sel:WORD_1
	v_or_b32_sdwa v10, v15, v14 dst_sel:DWORD dst_unused:UNUSED_PAD src0_sel:DWORD src1_sel:WORD_1
	s_cmpk_lt_i32 s6, 0x100
	v_readlane_b32 s9, v252, 27
	v_readlane_b32 s10, v252, 28
	v_readlane_b32 s11, v252, 29
	v_readlane_b32 s14, v252, 32
	v_readlane_b32 s15, v252, 33
	v_readlane_b32 s16, v252, 34
	v_readlane_b32 s17, v252, 35
	v_readlane_b32 s18, v252, 36
	v_readlane_b32 s19, v252, 37
	v_readlane_b32 s20, v252, 38
	v_readlane_b32 s21, v252, 39
	v_readlane_b32 s22, v252, 40
	v_readlane_b32 s23, v252, 41
	global_store_dwordx4 v[12:13], v[8:11], off
	s_barrier
	s_cbranch_scc0 .LBB0_924

; __device__ __forceinline__ int srccol(int perm, int n) {
;     ...
;   } else if (perm == 3) {
;     if (n < 1024) return n;
;     int m = n - 1024;
;     int blk = m >> 5, t = (m >> 4) & 1, i = m & 15;
;     int j = blk * 16 + i;
;     return t ? 2048 + j : 1024 + j;
;   }
; __device__ __forceinline__ void conv_family(const float* __restrict__ W, u16* __restrict__ Wt, int cnt, int K, int N, int perm,
;                             float* tile, const int tid, const float* __restrict__ kscale = nullptr) {
;     ...
;   for (int t = blockIdx.x; t < total; t += gridDim.x) {
;     int mi = t / per, r = t % per, kt = r / tn, ntile = r % tn;
;     const float* Ws = W + (size_t)mi * K * N;
;     u16* Wd = Wt + (size_t)mi * K * N;
;     int k0 = kt * 64, n0 = ntile * 256;
;     {
;       int n = tid & 255;
;       int sc = srccol(perm, n0 + n);
;       const float* wp = Ws + (size_t)(k0 + (tid >> 8)) * N + sc;
;       float v[32];
; #pragma unroll
;       for (int i = 0; i < 32; ++i) v[i] = wp[(size_t)(2 * i) * N];
.LBB0_926:
	s_mul_hi_i32 s1, s0, 0x2aaaaaab
	s_lshr_b32 s2, s1, 31
	s_ashr_i32 s1, s1, 5
	s_add_i32 s1, s1, s2
	s_mul_i32 s4, s1, 0xffffff40
	s_mul_hi_i32 s3, s1, 0x300000
	s_mul_i32 s2, s1, 0x300000
	s_add_i32 s1, s0, s4
	s_mul_i32 s6, s1, 0x2aab
	s_lshr_b32 s7, s6, 31
	s_ashr_i32 s6, s6, 17
	s_add_i32 s6, s6, s7
	s_mul_i32 s7, s6, 12
	s_lshl_b64 s[4:5], s[2:3], 2
	s_sub_i32 s1, s1, s7
	s_add_u32 s4, s12, s4
	s_addc_u32 s5, s13, s5
	s_lshl_b64 s[2:3], s[2:3], 1
	s_sext_i32_i16 s1, s1
	s_add_u32 s7, s58, s2
	s_addc_u32 s8, s59, s3
	s_lshl_b32 s1, s1, 8
	s_lshl_b32 s2, s6, 6
	v_or_b32_e32 v22, s1, v3
	v_mov_b64_e32 v[8:9], s[4:5]
	v_add_u32_e32 v11, s2, v4
	v_add_u32_e32 v10, s1, v7
	v_add_u32_e32 v13, 0xfffffc00, v22
	v_mad_i64_i32 v[16:17], s[4:5], v11, s15, v[8:9]
	v_add_u32_e32 v8, 64, v10
	v_lshrrev_b32_e32 v18, 1, v13
	v_ashrrev_i32_e32 v9, 31, v8
	v_and_b32_e32 v20, 0x7ffffff0, v18
	s_movk_i32 s1, 0x400
	v_lshlrev_b64 v[18:19], 11, v[8:9]
	v_add_u32_e32 v8, v5, v20
	v_cmp_gt_i32_e32 vcc, s1, v22
	s_ashr_i32 s3, s2, 31
	s_lshl_b64 s[2:3], s[2:3], 1
	v_cndmask_b32_e32 v22, v8, v22, vcc
	v_ashrrev_i32_e32 v23, 31, v22
	s_add_u32 s2, s7, s2
	v_lshl_add_u64 v[36:37], v[22:23], 2, v[16:17]
	v_ashrrev_i32_e32 v11, 31, v10
	s_addc_u32 s3, s8, s3
	v_add_co_u32_e32 v16, vcc, s10, v36
	v_add_u32_e32 v12, 0x80, v10
	v_add_u32_e32 v14, 0xc0, v10
	v_lshlrev_b64 v[10:11], 11, v[10:11]
	v_lshl_add_u64 v[20:21], s[2:3], 0, v[0:1]
	v_addc_co_u32_e32 v17, vcc, 0, v37, vcc
	v_ashrrev_i32_e32 v13, 31, v12
	v_ashrrev_i32_e32 v15, 31, v14
	v_lshl_add_u64 v[8:9], v[20:21], 0, v[10:11]
	v_lshl_add_u64 v[10:11], v[20:21], 0, v[18:19]
	v_add_co_u32_e32 v18, vcc, s16, v36
	v_lshlrev_b64 v[12:13], 11, v[12:13]
	v_lshlrev_b64 v[14:15], 11, v[14:15]
	v_addc_co_u32_e32 v19, vcc, 0, v37, vcc
	v_lshl_add_u64 v[12:13], v[20:21], 0, v[12:13]
	v_lshl_add_u64 v[14:15], v[20:21], 0, v[14:15]
	v_add_co_u32_e32 v20, vcc, s95, v36
	s_mov_b32 s1, 0x4e000
	s_nop 0
	v_addc_co_u32_e32 v21, vcc, 0, v37, vcc
	v_add_co_u32_e32 v22, vcc, s11, v36
	v_add_u32_e32 v52, 4, v50
	s_nop 0
	v_addc_co_u32_e32 v23, vcc, 0, v37, vcc
	v_add_co_u32_e32 v24, vcc, s14, v36
	v_add_u32_e32 v53, 8, v50
	s_nop 0
	v_addc_co_u32_e32 v25, vcc, 0, v37, vcc
	v_add_co_u32_e32 v26, vcc, s30, v36
	v_add_u32_e32 v54, 12, v50
	s_nop 0
	v_addc_co_u32_e32 v27, vcc, 0, v37, vcc
	v_add_co_u32_e32 v28, vcc, s19, v36
	v_add_u32_e32 v55, 16, v50
	s_waitcnt lgkmcnt(0)
	v_addc_co_u32_e32 v29, vcc, 0, v37, vcc
	v_add_co_u32_e32 v30, vcc, s20, v36
	v_add_u32_e32 v56, 20, v50
	s_nop 0
	v_addc_co_u32_e32 v31, vcc, 0, v37, vcc
	v_add_co_u32_e32 v32, vcc, s96, v36
	v_add_u32_e32 v57, 24, v50
	s_nop 0
	v_addc_co_u32_e32 v33, vcc, 0, v37, vcc
	v_add_co_u32_e32 v34, vcc, s21, v36
	v_add_u32_e32 v58, 28, v50
	s_nop 0
	v_addc_co_u32_e32 v35, vcc, 0, v37, vcc
	v_add_co_u32_e32 v38, vcc, s17, v36
	s_add_i32 s0, s0, s44
	s_nop 0
	v_addc_co_u32_e32 v39, vcc, 0, v37, vcc
	v_add_co_u32_e32 v40, vcc, s34, v36
	s_cmpk_lt_i32 s0, 0x180
	s_nop 0
	v_addc_co_u32_e32 v41, vcc, 0, v37, vcc
	v_add_co_u32_e32 v42, vcc, s1, v36
	s_mov_b32 s1, 0x66000
	s_nop 0
	v_addc_co_u32_e32 v43, vcc, 0, v37, vcc
	v_add_co_u32_e32 v44, vcc, s22, v36
	s_nop 1
	v_addc_co_u32_e32 v45, vcc, 0, v37, vcc
	v_add_co_u32_e32 v46, vcc, s83, v36
	s_nop 1
	v_addc_co_u32_e32 v47, vcc, 0, v37, vcc
	v_add_co_u32_e32 v48, vcc, s23, v36
	s_nop 1
	v_addc_co_u32_e32 v49, vcc, 0, v37, vcc
	v_add_co_u32_e32 v60, vcc, s1, v36
	s_mov_b32 s1, 0x72000
	s_nop 0
	v_addc_co_u32_e32 v61, vcc, 0, v37, vcc
	v_add_co_u32_e32 v62, vcc, s97, v36
	s_nop 1
	v_addc_co_u32_e32 v63, vcc, 0, v37, vcc
	v_add_co_u32_e32 v64, vcc, s1, v36
	s_mov_b32 s1, 0x8a000
	s_nop 0
	v_addc_co_u32_e32 v65, vcc, 0, v37, vcc
	v_add_co_u32_e32 v66, vcc, s24, v36
	s_nop 1
	v_addc_co_u32_e32 v67, vcc, 0, v37, vcc
	v_add_co_u32_e32 v68, vcc, s33, v36
	s_nop 1
	v_addc_co_u32_e32 v69, vcc, 0, v37, vcc
	v_add_co_u32_e32 v70, vcc, s18, v36
	s_nop 1
	v_addc_co_u32_e32 v71, vcc, 0, v37, vcc
	v_add_co_u32_e32 v76, vcc, s1, v36
	s_mov_b32 s1, 0x96000
	s_nop 0
	v_addc_co_u32_e32 v77, vcc, 0, v37, vcc
	v_add_co_u32_e32 v78, vcc, s9, v36
	s_nop 1
	v_addc_co_u32_e32 v79, vcc, 0, v37, vcc
	v_add_co_u32_e32 v80, vcc, s1, v36
	s_mov_b32 s1, 0xa2000
	s_nop 0
	v_addc_co_u32_e32 v81, vcc, 0, v37, vcc
	v_add_co_u32_e32 v82, vcc, s25, v36
	s_nop 1
	v_addc_co_u32_e32 v83, vcc, 0, v37, vcc
	v_add_co_u32_e32 v84, vcc, s1, v36
	s_mov_b32 s1, 0xae000
	s_nop 0
	v_addc_co_u32_e32 v85, vcc, 0, v37, vcc
	v_add_co_u32_e32 v86, vcc, s26, v36
	s_nop 1
	v_addc_co_u32_e32 v87, vcc, 0, v37, vcc
	v_add_co_u32_e32 v88, vcc, s1, v36
	s_mov_b32 s1, 0xba000
	s_nop 0
	v_addc_co_u32_e32 v89, vcc, 0, v37, vcc
	v_add_co_u32_e32 v90, vcc, s27, v36
	s_nop 1
	v_addc_co_u32_e32 v91, vcc, 0, v37, vcc
	v_add_co_u32_e32 v92, vcc, s1, v36
	s_nop 1
	v_addc_co_u32_e32 v93, vcc, 0, v37, vcc
	global_load_dword v36, v[36:37], off
	s_nop 0
	global_load_dword v16, v[16:17], off
	s_nop 0
	global_load_dword v17, v[18:19], off
	s_nop 0
	global_load_dword v18, v[20:21], off
	global_load_dword v19, v[22:23], off
	s_nop 0
	global_load_dword v20, v[24:25], off
	global_load_dword v21, v[26:27], off
	global_load_dword v22, v[28:29], off
	global_load_dword v23, v[30:31], off
	s_nop 0
	global_load_dword v24, v[32:33], off
	global_load_dword v25, v[34:35], off
	global_load_dword v26, v[38:39], off
	global_load_dword v27, v[40:41], off
	global_load_dword v28, v[42:43], off
	global_load_dword v29, v[44:45], off
	global_load_dword v30, v[46:47], off
	global_load_dword v31, v[48:49], off
	global_load_dword v32, v[60:61], off
	global_load_dword v33, v[62:63], off
	global_load_dword v34, v[64:65], off
	global_load_dword v35, v[66:67], off
	global_load_dword v37, v[68:69], off
	global_load_dword v38, v[70:71], off
	global_load_dword v39, v[76:77], off
	global_load_dword v40, v[78:79], off
	global_load_dword v41, v[80:81], off
	global_load_dword v42, v[82:83], off
	global_load_dword v43, v[84:85], off
	global_load_dword v44, v[86:87], off
	global_load_dword v45, v[88:89], off
	global_load_dword v46, v[90:91], off
	global_load_dword v47, v[92:93], off
	s_waitcnt vmcnt(31)
; __device__ __forceinline__ void conv_family(const float* __restrict__ W, u16* __restrict__ Wt, int cnt, int K, int N, int perm,
;                             float* tile, const int tid, const float* __restrict__ kscale = nullptr) {
;     ...
; #pragma unroll
;       for (int i = 0; i < 32; ++i) tile[(2 * i + (tid >> 8)) * 257 + n] = v[i];
;     }
;     __syncthreads();
	ds_write_b32 v51, v36
	s_waitcnt vmcnt(30)
	ds_write_b32 v51, v16 offset:2056
	s_waitcnt vmcnt(29)
	ds_write_b32 v51, v17 offset:4112
	s_waitcnt vmcnt(28)
	ds_write_b32 v51, v18 offset:6168
	s_waitcnt vmcnt(27)
	ds_write_b32 v51, v19 offset:8224
	s_waitcnt vmcnt(26)
	ds_write_b32 v51, v20 offset:10280
	s_waitcnt vmcnt(25)
	ds_write_b32 v51, v21 offset:12336
	s_waitcnt vmcnt(24)
	ds_write_b32 v51, v22 offset:14392
	s_waitcnt vmcnt(23)
	ds_write_b32 v51, v23 offset:16448
	s_waitcnt vmcnt(22)
	ds_write_b32 v51, v24 offset:18504
	s_waitcnt vmcnt(21)
	ds_write_b32 v51, v25 offset:20560
	s_waitcnt vmcnt(20)
	ds_write_b32 v51, v26 offset:22616
	s_waitcnt vmcnt(19)
	ds_write_b32 v51, v27 offset:24672
	s_waitcnt vmcnt(18)
	ds_write_b32 v51, v28 offset:26728
	s_waitcnt vmcnt(17)
	ds_write_b32 v51, v29 offset:28784
	s_waitcnt vmcnt(16)
	ds_write_b32 v51, v30 offset:30840
	s_waitcnt vmcnt(15)
	ds_write_b32 v51, v31 offset:32896
	s_waitcnt vmcnt(14)
	ds_write_b32 v51, v32 offset:34952
	s_waitcnt vmcnt(13)
	ds_write_b32 v51, v33 offset:37008
	s_waitcnt vmcnt(12)
	ds_write_b32 v51, v34 offset:39064
	s_waitcnt vmcnt(11)
	ds_write_b32 v51, v35 offset:41120
	s_waitcnt vmcnt(10)
	ds_write_b32 v51, v37 offset:43176
	s_waitcnt vmcnt(9)
	ds_write_b32 v51, v38 offset:45232
	s_waitcnt vmcnt(8)
	ds_write_b32 v51, v39 offset:47288
	s_waitcnt vmcnt(7)
	ds_write_b32 v51, v40 offset:49344
	s_waitcnt vmcnt(6)
	ds_write_b32 v51, v41 offset:51400
	s_waitcnt vmcnt(5)
	ds_write_b32 v51, v42 offset:53456
	s_waitcnt vmcnt(4)
	ds_write_b32 v51, v43 offset:55512
	s_waitcnt vmcnt(3)
	ds_write_b32 v51, v44 offset:57568
	s_waitcnt vmcnt(2)
	ds_write_b32 v51, v45 offset:59624
	s_waitcnt vmcnt(1)
	ds_write_b32 v51, v46 offset:61680
	s_waitcnt vmcnt(0)
	ds_write_b32 v51, v47 offset:63736
	s_waitcnt lgkmcnt(0)
	s_barrier
; __device__ __forceinline__ unsigned pack2(float a, float b) { return (unsigned)f2bf(a) | ((unsigned)f2bf(b) << 16); }
; __device__ __forceinline__ void conv_family(const float* __restrict__ W, u16* __restrict__ Wt, int cnt, int K, int N, int perm,
;                             float* tile, const int tid, const float* __restrict__ kscale = nullptr) {
;     ...
; #pragma unroll
;     for (int i = 0; i < 4; ++i) {
;       int n = i * 64 + (tid >> 3), ks = (tid & 7) * 8;
;       uint4 pk;
;       pk.x = pack2(tile[(ks + 0) * 257 + n], tile[(ks + 1) * 257 + n]);
;       pk.y = pack2(tile[(ks + 2) * 257 + n], tile[(ks + 3) * 257 + n]);
;       pk.z = pack2(tile[(ks + 4) * 257 + n], tile[(ks + 5) * 257 + n]);
;       pk.w = pack2(tile[(ks + 6) * 257 + n], tile[(ks + 7) * 257 + n]);
;       *(uint4*)(Wd + (size_t)(n0 + n) * K + k0 + ks) = pk;
;     }
;     __syncthreads();
;   }
	ds_read2st64_b32 v[16:17], v50 offset1:1
	ds_read2st64_b32 v[18:19], v50 offset0:2 offset1:3
	ds_read2st64_b32 v[20:21], v52 offset0:4 offset1:5
	ds_read2st64_b32 v[22:23], v52 offset0:6 offset1:7
	ds_read2st64_b32 v[24:25], v53 offset0:8 offset1:9
	ds_read2st64_b32 v[26:27], v53 offset0:10 offset1:11
	ds_read2st64_b32 v[28:29], v54 offset0:12 offset1:13
	ds_read2st64_b32 v[30:31], v54 offset0:14 offset1:15
	ds_read2st64_b32 v[32:33], v55 offset0:16 offset1:17
	ds_read2st64_b32 v[34:35], v55 offset0:18 offset1:19
	ds_read2st64_b32 v[36:37], v56 offset0:20 offset1:21
	ds_read2st64_b32 v[38:39], v56 offset0:22 offset1:23
	ds_read2st64_b32 v[40:41], v57 offset0:24 offset1:25
	ds_read2st64_b32 v[42:43], v57 offset0:26 offset1:27
	ds_read2st64_b32 v[44:45], v58 offset0:28 offset1:29
	ds_read2st64_b32 v[46:47], v58 offset0:30 offset1:31
	s_waitcnt lgkmcnt(9)
	s_nop 0
	s_nop 0
	s_waitcnt lgkmcnt(5)
	v_and_b32_sdwa v57, v36, v178 dst_sel:DWORD dst_unused:UNUSED_PAD src0_sel:WORD_1 src1_sel:DWORD
	s_waitcnt lgkmcnt(1)
	s_nop 0
	s_nop 0
	s_nop 0
	v_and_b32_sdwa v54, v40, v178 dst_sel:DWORD dst_unused:UNUSED_PAD src0_sel:WORD_1 src1_sel:DWORD
	v_and_b32_sdwa v55, v32, v178 dst_sel:DWORD dst_unused:UNUSED_PAD src0_sel:WORD_1 src1_sel:DWORD
	v_and_b32_sdwa v59, v17, v178 dst_sel:DWORD dst_unused:UNUSED_PAD src0_sel:WORD_1 src1_sel:DWORD
	v_and_b32_sdwa v60, v29, v178 dst_sel:DWORD dst_unused:UNUSED_PAD src0_sel:WORD_1 src1_sel:DWORD
	v_and_b32_sdwa v61, v21, v178 dst_sel:DWORD dst_unused:UNUSED_PAD src0_sel:WORD_1 src1_sel:DWORD
	v_and_b32_sdwa v62, v41, v178 dst_sel:DWORD dst_unused:UNUSED_PAD src0_sel:WORD_1 src1_sel:DWORD
	v_and_b32_sdwa v63, v33, v178 dst_sel:DWORD dst_unused:UNUSED_PAD src0_sel:WORD_1 src1_sel:DWORD
	v_and_b32_sdwa v64, v45, v178 dst_sel:DWORD dst_unused:UNUSED_PAD src0_sel:WORD_1 src1_sel:DWORD
	v_and_b32_sdwa v65, v37, v178 dst_sel:DWORD dst_unused:UNUSED_PAD src0_sel:WORD_1 src1_sel:DWORD
	v_and_b32_sdwa v67, v18, v178 dst_sel:DWORD dst_unused:UNUSED_PAD src0_sel:WORD_1 src1_sel:DWORD
	v_and_b32_sdwa v68, v30, v178 dst_sel:DWORD dst_unused:UNUSED_PAD src0_sel:WORD_1 src1_sel:DWORD
	v_and_b32_sdwa v69, v22, v178 dst_sel:DWORD dst_unused:UNUSED_PAD src0_sel:WORD_1 src1_sel:DWORD
	v_and_b32_sdwa v70, v42, v178 dst_sel:DWORD dst_unused:UNUSED_PAD src0_sel:WORD_1 src1_sel:DWORD
	v_and_b32_sdwa v71, v34, v178 dst_sel:DWORD dst_unused:UNUSED_PAD src0_sel:WORD_1 src1_sel:DWORD
	s_waitcnt lgkmcnt(0)
	v_and_b32_sdwa v76, v46, v178 dst_sel:DWORD dst_unused:UNUSED_PAD src0_sel:WORD_1 src1_sel:DWORD
	v_and_b32_sdwa v77, v38, v178 dst_sel:DWORD dst_unused:UNUSED_PAD src0_sel:WORD_1 src1_sel:DWORD
	v_and_b32_sdwa v78, v27, v178 dst_sel:DWORD dst_unused:UNUSED_PAD src0_sel:WORD_1 src1_sel:DWORD
	v_and_b32_sdwa v79, v19, v178 dst_sel:DWORD dst_unused:UNUSED_PAD src0_sel:WORD_1 src1_sel:DWORD
	v_and_b32_sdwa v80, v31, v178 dst_sel:DWORD dst_unused:UNUSED_PAD src0_sel:WORD_1 src1_sel:DWORD
	v_and_b32_sdwa v81, v23, v178 dst_sel:DWORD dst_unused:UNUSED_PAD src0_sel:WORD_1 src1_sel:DWORD
	v_and_b32_sdwa v82, v43, v178 dst_sel:DWORD dst_unused:UNUSED_PAD src0_sel:WORD_1 src1_sel:DWORD
	v_and_b32_sdwa v84, v47, v178 dst_sel:DWORD dst_unused:UNUSED_PAD src0_sel:WORD_1 src1_sel:DWORD
	v_and_b32_sdwa v85, v39, v178 dst_sel:DWORD dst_unused:UNUSED_PAD src0_sel:WORD_1 src1_sel:DWORD
	v_cvt_pk_bf16_f32 v28, v28, v28
	v_cvt_pk_bf16_f32 v20, v20, v20
	v_cvt_pk_bf16_f32 v44, v44, v44
	v_add3_u32 v36, v36, v57, s81
	v_and_b32_sdwa v58, v25, v178 dst_sel:DWORD dst_unused:UNUSED_PAD src0_sel:WORD_1 src1_sel:DWORD
	v_and_b32_sdwa v66, v26, v178 dst_sel:DWORD dst_unused:UNUSED_PAD src0_sel:WORD_1 src1_sel:DWORD
	v_and_b32_sdwa v83, v35, v178 dst_sel:DWORD dst_unused:UNUSED_PAD src0_sel:WORD_1 src1_sel:DWORD
	v_cvt_pk_bf16_f32 v16, v16, v16
	v_cvt_pk_bf16_f32 v24, v24, v24
	v_add3_u32 v32, v32, v55, s81
	v_add3_u32 v40, v40, v54, s81
	v_add3_u32 v48, v17, v59, s81
	v_add3_u32 v17, v29, v60, s81
	v_add3_u32 v21, v21, v61, s81
	v_add3_u32 v29, v33, v63, s81
	v_add3_u32 v33, v41, v62, s81
	v_add3_u32 v41, v45, v64, s81
	v_add3_u32 v37, v37, v65, s81
	v_add3_u32 v45, v18, v67, s81
	v_add3_u32 v18, v30, v68, s81
	v_add3_u32 v22, v22, v69, s81
	v_add3_u32 v30, v34, v71, s81
	v_add3_u32 v34, v42, v70, s81
	v_add3_u32 v42, v46, v76, s81
	v_add3_u32 v38, v38, v77, s81
	v_add3_u32 v46, v19, v79, s81
	v_add3_u32 v49, v27, v78, s81
	v_add3_u32 v19, v31, v80, s81
	v_add3_u32 v23, v23, v81, s81
	v_add3_u32 v31, v43, v82, s81
	v_add3_u32 v27, v47, v84, s81
	v_add3_u32 v39, v39, v85, s81
	v_and_b32_e32 v28, 0xffff0000, v28
	v_and_b32_e32 v20, 0xffff0000, v20
	v_and_b32_e32 v43, 0xffff0000, v44
	v_and_b32_e32 v36, 0xffff0000, v36
	v_add3_u32 v25, v25, v58, s81
	v_add3_u32 v26, v26, v66, s81
	v_add3_u32 v35, v35, v83, s81
	v_and_b32_e32 v44, 0xffff0000, v17
	v_and_b32_e32 v47, 0xffff0000, v21
	v_and_b32_e32 v41, 0xffff0000, v41
	v_and_b32_e32 v37, 0xffff0000, v37
	v_and_b32_e32 v52, 0xffff0000, v18
	v_and_b32_e32 v53, 0xffff0000, v22
	v_and_b32_e32 v42, 0xffff0000, v42
	v_and_b32_e32 v38, 0xffff0000, v38
	v_and_b32_e32 v54, 0xffff0000, v19
	v_and_b32_e32 v55, 0xffff0000, v23
	v_and_b32_e32 v56, 0xffff0000, v27
	v_and_b32_e32 v39, 0xffff0000, v39
	v_or_b32_sdwa v17, v28, v24 dst_sel:DWORD dst_unused:UNUSED_PAD src0_sel:DWORD src1_sel:WORD_1
	v_or_b32_sdwa v16, v20, v16 dst_sel:DWORD dst_unused:UNUSED_PAD src0_sel:DWORD src1_sel:WORD_1
	v_or_b32_sdwa v19, v43, v40 dst_sel:DWORD dst_unused:UNUSED_PAD src0_sel:DWORD src1_sel:WORD_1
	v_or_b32_sdwa v18, v36, v32 dst_sel:DWORD dst_unused:UNUSED_PAD src0_sel:DWORD src1_sel:WORD_1
	v_or_b32_sdwa v21, v44, v25 dst_sel:DWORD dst_unused:UNUSED_PAD src0_sel:DWORD src1_sel:WORD_1
	v_or_b32_sdwa v20, v47, v48 dst_sel:DWORD dst_unused:UNUSED_PAD src0_sel:DWORD src1_sel:WORD_1
	v_or_b32_sdwa v23, v41, v33 dst_sel:DWORD dst_unused:UNUSED_PAD src0_sel:DWORD src1_sel:WORD_1
	v_or_b32_sdwa v22, v37, v29 dst_sel:DWORD dst_unused:UNUSED_PAD src0_sel:DWORD src1_sel:WORD_1
	v_or_b32_sdwa v25, v52, v26 dst_sel:DWORD dst_unused:UNUSED_PAD src0_sel:DWORD src1_sel:WORD_1
	v_or_b32_sdwa v24, v53, v45 dst_sel:DWORD dst_unused:UNUSED_PAD src0_sel:DWORD src1_sel:WORD_1
	v_or_b32_sdwa v27, v42, v34 dst_sel:DWORD dst_unused:UNUSED_PAD src0_sel:DWORD src1_sel:WORD_1
	v_or_b32_sdwa v26, v38, v30 dst_sel:DWORD dst_unused:UNUSED_PAD src0_sel:DWORD src1_sel:WORD_1
	v_or_b32_sdwa v29, v54, v49 dst_sel:DWORD dst_unused:UNUSED_PAD src0_sel:DWORD src1_sel:WORD_1
	v_or_b32_sdwa v28, v55, v46 dst_sel:DWORD dst_unused:UNUSED_PAD src0_sel:DWORD src1_sel:WORD_1
	v_or_b32_sdwa v31, v56, v31 dst_sel:DWORD dst_unused:UNUSED_PAD src0_sel:DWORD src1_sel:WORD_1
	v_or_b32_sdwa v30, v39, v35 dst_sel:DWORD dst_unused:UNUSED_PAD src0_sel:DWORD src1_sel:WORD_1
	global_store_dwordx4 v[8:9], v[16:19], off
	global_store_dwordx4 v[10:11], v[20:23], off
	global_store_dwordx4 v[12:13], v[24:27], off
	global_store_dwordx4 v[14:15], v[28:31], off
	s_barrier
	s_cbranch_scc1 .LBB0_926

; __device__ __forceinline__ int srccol(int perm, int n) {
;     ...
;   } else if (perm == 4) {
;     int grp = n >> 5, t = (n >> 4) & 1, i = n & 15;
;     return grp * 32 + 2 * i + t;
; __device__ __forceinline__ void conv_family(const float* __restrict__ W, u16* __restrict__ Wt, int cnt, int K, int N, int perm,
;                             float* tile, const int tid, const float* __restrict__ kscale = nullptr) {
;     ...
;   for (int t = blockIdx.x; t < total; t += gridDim.x) {
;     int mi = t / per, r = t % per, kt = r / tn, ntile = r % tn;
;     const float* Ws = W + (size_t)mi * K * N;
;     u16* Wd = Wt + (size_t)mi * K * N;
;     int k0 = kt * 64, n0 = ntile * 256;
;     {
;       int n = tid & 255;
;       int sc = srccol(perm, n0 + n);
;       const float* wp = Ws + (size_t)(k0 + (tid >> 8)) * N + sc;
;       float v[32];
; #pragma unroll
;       for (int i = 0; i < 32; ++i) v[i] = wp[(size_t)(2 * i) * N];
.LBB0_929:
	s_ashr_i32 s0, s4, 31
	s_lshr_b32 s0, s0, 26
	s_add_i32 s0, s4, s0
	s_ashr_i32 s2, s0, 6
	s_and_b32 s0, s0, 0xffc0
	s_sub_i32 s5, s4, s0
	s_bfe_i32 s6, s5, 0x80000
	s_bfe_u32 s6, s6, 0x2000d
	s_add_i32 s6, s5, s6
	s_ashr_i32 s3, s2, 31
	s_sext_i32_i8 s7, s6
	s_and_b32 s6, s6, 0xfc
	s_lshl_b64 s[0:1], s[2:3], 22
	s_sub_i32 s5, s5, s6
	s_add_u32 s0, s16, s0
	s_addc_u32 s1, s17, s1
	s_lshl_b64 s[2:3], s[2:3], 21
	s_add_u32 s6, s60, s2
	s_addc_u32 s8, s61, s3
	s_lshl_b32 s2, s7, 4
	s_sext_i32_i8 s5, s5
	s_andn2_b32 s2, s2, 63
	v_lshlrev_b32_e32 v6, 1, v3
	s_lshl_b32 s3, s5, 8
	v_add_u32_e32 v14, s2, v4
	v_and_b32_e32 v6, 30, v6
	v_bitop3_b32 v11, s3, v99, v3 bitop3:0xc8
	v_ashrrev_i32_e32 v15, 31, v14
	v_or3_b32 v12, v11, v75, v6
	v_lshlrev_b64 v[14:15], 12, v[14:15]
	v_ashrrev_i32_e32 v13, 31, v12
	v_lshl_add_u64 v[14:15], s[0:1], 0, v[14:15]
	v_lshl_add_u64 v[12:13], v[12:13], 2, v[14:15]
	v_add_co_u32_e32 v22, vcc, s9, v12
	v_add_u32_e32 v10, s3, v7
	s_nop 0
	v_addc_co_u32_e32 v23, vcc, 0, v13, vcc
	v_add_co_u32_e32 v24, vcc, s13, v12
	s_ashr_i32 s3, s2, 31
	s_nop 0
	v_addc_co_u32_e32 v25, vcc, 0, v13, vcc
	v_add_co_u32_e32 v26, vcc, s14, v12
	s_lshl_b64 s[2:3], s[2:3], 1
	s_nop 0
	v_addc_co_u32_e32 v27, vcc, 0, v13, vcc
	v_add_co_u32_e32 v28, vcc, s84, v12
	v_add_u32_e32 v16, 64, v10
	s_waitcnt lgkmcnt(0)
	v_addc_co_u32_e32 v29, vcc, 0, v13, vcc
	v_add_co_u32_e32 v30, vcc, s19, v12
	v_add_u32_e32 v18, 0x80, v10
	s_nop 0
	v_addc_co_u32_e32 v31, vcc, 0, v13, vcc
	v_add_co_u32_e32 v32, vcc, s22, v12
	v_add_u32_e32 v20, 0xc0, v10
	s_nop 0
	v_addc_co_u32_e32 v33, vcc, 0, v13, vcc
	v_add_co_u32_e32 v34, vcc, s23, v12
	s_add_u32 s2, s6, s2
	s_nop 0
	v_addc_co_u32_e32 v35, vcc, 0, v13, vcc
	v_add_co_u32_e32 v36, vcc, s10, v12
	v_ashrrev_i32_e32 v11, 31, v10
	s_nop 0
	v_addc_co_u32_e32 v37, vcc, 0, v13, vcc
	v_add_co_u32_e32 v38, vcc, s95, v12
	v_ashrrev_i32_e32 v17, 31, v16
	s_nop 0
	v_addc_co_u32_e32 v39, vcc, 0, v13, vcc
	v_add_co_u32_e32 v40, vcc, s11, v12
	v_ashrrev_i32_e32 v19, 31, v18
	s_nop 0
	v_addc_co_u32_e32 v41, vcc, 0, v13, vcc
	v_add_co_u32_e32 v42, vcc, s12, v12
	v_ashrrev_i32_e32 v21, 31, v20
	s_nop 0
	v_addc_co_u32_e32 v43, vcc, 0, v13, vcc
	v_add_co_u32_e32 v44, vcc, s15, v12
	s_addc_u32 s3, s8, s3
	s_nop 0
	v_addc_co_u32_e32 v45, vcc, 0, v13, vcc
	v_add_co_u32_e32 v46, vcc, s18, v12
	v_lshlrev_b64 v[10:11], 11, v[10:11]
	s_nop 0
	v_addc_co_u32_e32 v47, vcc, 0, v13, vcc
	v_add_co_u32_e32 v48, vcc, s20, v12
	v_lshlrev_b64 v[16:17], 11, v[16:17]
	s_nop 0
	v_addc_co_u32_e32 v49, vcc, 0, v13, vcc
	v_add_co_u32_e32 v50, vcc, s21, v12
	v_lshlrev_b64 v[18:19], 11, v[18:19]
	s_nop 0
	v_addc_co_u32_e32 v51, vcc, 0, v13, vcc
	v_add_co_u32_e32 v52, vcc, s24, v12
	v_lshlrev_b64 v[20:21], 11, v[20:21]
	s_nop 0
	v_addc_co_u32_e32 v53, vcc, 0, v13, vcc
	v_add_co_u32_e32 v54, vcc, s27, v12
	v_lshl_add_u64 v[14:15], s[2:3], 0, v[0:1]
	s_nop 0
	v_addc_co_u32_e32 v55, vcc, 0, v13, vcc
	v_add_co_u32_e32 v56, vcc, s30, v12
	v_lshl_add_u64 v[86:87], v[14:15], 0, v[10:11]
	s_nop 0
	v_addc_co_u32_e32 v57, vcc, 0, v13, vcc
	v_add_co_u32_e32 v58, vcc, s36, v12
	v_lshl_add_u64 v[88:89], v[14:15], 0, v[16:17]
	s_nop 0
	v_addc_co_u32_e32 v59, vcc, 0, v13, vcc
	v_add_co_u32_e32 v60, vcc, s25, v12
	v_lshl_add_u64 v[90:91], v[14:15], 0, v[18:19]
	s_nop 0
	v_addc_co_u32_e32 v61, vcc, 0, v13, vcc
	v_add_co_u32_e32 v62, vcc, s37, v12
	v_lshl_add_u64 v[92:93], v[14:15], 0, v[20:21]
	s_nop 0
	v_addc_co_u32_e32 v63, vcc, 0, v13, vcc
	v_add_co_u32_e32 v64, vcc, s26, v12
	v_add_u32_e32 v9, 4, v5
	s_nop 0
	v_addc_co_u32_e32 v65, vcc, 0, v13, vcc
	v_add_co_u32_e32 v66, vcc, s38, v12
	v_add_u32_e32 v74, 8, v5
	s_nop 0
	v_addc_co_u32_e32 v67, vcc, 0, v13, vcc
	v_add_co_u32_e32 v68, vcc, s39, v12
	v_add_u32_e32 v94, 12, v5
	s_nop 0
	v_addc_co_u32_e32 v69, vcc, 0, v13, vcc
	v_add_co_u32_e32 v70, vcc, s40, v12
	v_add_u32_e32 v95, 16, v5
	s_nop 0
	v_addc_co_u32_e32 v71, vcc, 0, v13, vcc
	v_add_co_u32_e32 v72, vcc, s41, v12
	v_add_u32_e32 v96, 20, v5
	s_nop 0
	v_addc_co_u32_e32 v73, vcc, 0, v13, vcc
	v_add_co_u32_e32 v76, vcc, s96, v12
	v_add_u32_e32 v97, 24, v5
	s_nop 0
	v_addc_co_u32_e32 v77, vcc, 0, v13, vcc
	v_add_co_u32_e32 v78, vcc, s43, v12
	v_add_u32_e32 v98, 28, v5
	s_nop 0
	v_addc_co_u32_e32 v79, vcc, 0, v13, vcc
	v_add_co_u32_e32 v80, vcc, s48, v12
	s_add_i32 s4, s4, s44
	s_nop 0
	v_addc_co_u32_e32 v81, vcc, 0, v13, vcc
	v_add_co_u32_e32 v82, vcc, s50, v12
	s_cmpk_lt_i32 s4, 0x80
	s_nop 0
	v_addc_co_u32_e32 v83, vcc, 0, v13, vcc
	v_add_co_u32_e32 v84, vcc, s51, v12
	s_nop 1
	v_addc_co_u32_e32 v85, vcc, 0, v13, vcc
	global_load_dword v6, v[12:13], off
	global_load_dword v10, v[22:23], off
	global_load_dword v11, v[24:25], off
	s_nop 0
	global_load_dword v12, v[26:27], off
	global_load_dword v13, v[28:29], off
	global_load_dword v14, v[30:31], off
	global_load_dword v15, v[32:33], off
	global_load_dword v16, v[34:35], off
	global_load_dword v17, v[36:37], off
	global_load_dword v18, v[38:39], off
	global_load_dword v19, v[40:41], off
	global_load_dword v20, v[42:43], off
	global_load_dword v21, v[44:45], off
	global_load_dword v22, v[46:47], off
	global_load_dword v23, v[48:49], off
	global_load_dword v24, v[50:51], off
	global_load_dword v25, v[52:53], off
	global_load_dword v26, v[54:55], off
	global_load_dword v27, v[56:57], off
	global_load_dword v28, v[58:59], off
	global_load_dword v29, v[60:61], off
	global_load_dword v30, v[62:63], off
	global_load_dword v31, v[64:65], off
	global_load_dword v32, v[66:67], off
	global_load_dword v33, v[68:69], off
	global_load_dword v34, v[70:71], off
	global_load_dword v35, v[72:73], off
	global_load_dword v36, v[76:77], off
	global_load_dword v37, v[78:79], off
	global_load_dword v38, v[80:81], off
	global_load_dword v39, v[82:83], off
	global_load_dword v40, v[84:85], off
	s_waitcnt vmcnt(31)
; __device__ __forceinline__ void conv_family(const float* __restrict__ W, u16* __restrict__ Wt, int cnt, int K, int N, int perm,
;                             float* tile, const int tid, const float* __restrict__ kscale = nullptr) {
;     ...
; #pragma unroll
;       for (int i = 0; i < 32; ++i) tile[(2 * i + (tid >> 8)) * 257 + n] = v[i];
;     }
;     __syncthreads();
	ds_write_b32 v8, v6
	s_waitcnt vmcnt(30)
	ds_write_b32 v8, v10 offset:2056
	s_waitcnt vmcnt(29)
	ds_write_b32 v8, v11 offset:4112
	s_waitcnt vmcnt(28)
	ds_write_b32 v8, v12 offset:6168
	s_waitcnt vmcnt(27)
	ds_write_b32 v8, v13 offset:8224
	s_waitcnt vmcnt(26)
	ds_write_b32 v8, v14 offset:10280
	s_waitcnt vmcnt(25)
	ds_write_b32 v8, v15 offset:12336
	s_waitcnt vmcnt(24)
	ds_write_b32 v8, v16 offset:14392
	s_waitcnt vmcnt(23)
	ds_write_b32 v8, v17 offset:16448
	s_waitcnt vmcnt(22)
	ds_write_b32 v8, v18 offset:18504
	s_waitcnt vmcnt(21)
	ds_write_b32 v8, v19 offset:20560
	s_waitcnt vmcnt(20)
	ds_write_b32 v8, v20 offset:22616
	s_waitcnt vmcnt(19)
	ds_write_b32 v8, v21 offset:24672
	s_waitcnt vmcnt(18)
	ds_write_b32 v8, v22 offset:26728
	s_waitcnt vmcnt(17)
	ds_write_b32 v8, v23 offset:28784
	s_waitcnt vmcnt(16)
	ds_write_b32 v8, v24 offset:30840
	s_waitcnt vmcnt(15)
	ds_write_b32 v8, v25 offset:32896
	s_waitcnt vmcnt(14)
	ds_write_b32 v8, v26 offset:34952
	s_waitcnt vmcnt(13)
	ds_write_b32 v8, v27 offset:37008
	s_waitcnt vmcnt(12)
	ds_write_b32 v8, v28 offset:39064
	s_waitcnt vmcnt(11)
	ds_write_b32 v8, v29 offset:41120
	s_waitcnt vmcnt(10)
	ds_write_b32 v8, v30 offset:43176
	s_waitcnt vmcnt(9)
	ds_write_b32 v8, v31 offset:45232
	s_waitcnt vmcnt(8)
	ds_write_b32 v8, v32 offset:47288
	s_waitcnt vmcnt(7)
	ds_write_b32 v8, v33 offset:49344
	s_waitcnt vmcnt(6)
	ds_write_b32 v8, v34 offset:51400
	s_waitcnt vmcnt(5)
	ds_write_b32 v8, v35 offset:53456
	s_waitcnt vmcnt(4)
	ds_write_b32 v8, v36 offset:55512
	s_waitcnt vmcnt(3)
	ds_write_b32 v8, v37 offset:57568
	s_waitcnt vmcnt(2)
	ds_write_b32 v8, v38 offset:59624
	s_waitcnt vmcnt(1)
	ds_write_b32 v8, v39 offset:61680
	s_waitcnt vmcnt(0)
	ds_write_b32 v8, v40 offset:63736
	s_waitcnt lgkmcnt(0)
	s_barrier
; __device__ __forceinline__ unsigned pack2(float a, float b) { return (unsigned)f2bf(a) | ((unsigned)f2bf(b) << 16); }
; __device__ __forceinline__ void conv_family(const float* __restrict__ W, u16* __restrict__ Wt, int cnt, int K, int N, int perm,
;                             float* tile, const int tid, const float* __restrict__ kscale = nullptr) {
;     ...
; #pragma unroll
;     for (int i = 0; i < 4; ++i) {
;       int n = i * 64 + (tid >> 3), ks = (tid & 7) * 8;
;       uint4 pk;
;       pk.x = pack2(tile[(ks + 0) * 257 + n], tile[(ks + 1) * 257 + n]);
;       pk.y = pack2(tile[(ks + 2) * 257 + n], tile[(ks + 3) * 257 + n]);
;       pk.z = pack2(tile[(ks + 4) * 257 + n], tile[(ks + 5) * 257 + n]);
;       pk.w = pack2(tile[(ks + 6) * 257 + n], tile[(ks + 7) * 257 + n]);
;       *(uint4*)(Wd + (size_t)(n0 + n) * K + k0 + ks) = pk;
;     }
;     __syncthreads();
;   }
	ds_read2st64_b32 v[10:11], v5 offset1:1
	ds_read2st64_b32 v[12:13], v5 offset0:2 offset1:3
	ds_read2st64_b32 v[14:15], v9 offset0:4 offset1:5
	ds_read2st64_b32 v[16:17], v9 offset0:6 offset1:7
	ds_read2st64_b32 v[18:19], v74 offset0:8 offset1:9
	ds_read2st64_b32 v[20:21], v74 offset0:10 offset1:11
	ds_read2st64_b32 v[22:23], v94 offset0:12 offset1:13
	ds_read2st64_b32 v[24:25], v94 offset0:14 offset1:15
	ds_read2st64_b32 v[26:27], v95 offset0:16 offset1:17
	ds_read2st64_b32 v[28:29], v95 offset0:18 offset1:19
	ds_read2st64_b32 v[30:31], v96 offset0:20 offset1:21
	ds_read2st64_b32 v[32:33], v96 offset0:22 offset1:23
	ds_read2st64_b32 v[34:35], v97 offset0:24 offset1:25
	ds_read2st64_b32 v[36:37], v97 offset0:26 offset1:27
	ds_read2st64_b32 v[38:39], v98 offset0:28 offset1:29
	ds_read2st64_b32 v[40:41], v98 offset0:30 offset1:31
	s_waitcnt lgkmcnt(11)
	v_and_b32_sdwa v6, v18, v178 dst_sel:DWORD dst_unused:UNUSED_PAD src0_sel:WORD_1 src1_sel:DWORD
	v_and_b32_sdwa v9, v10, v178 dst_sel:DWORD dst_unused:UNUSED_PAD src0_sel:WORD_1 src1_sel:DWORD
	s_waitcnt lgkmcnt(9)
	s_nop 0
	s_nop 0
	s_waitcnt lgkmcnt(7)
	s_nop 0
	s_waitcnt lgkmcnt(1)
	s_nop 0
	v_and_b32_sdwa v47, v30, v178 dst_sel:DWORD dst_unused:UNUSED_PAD src0_sel:WORD_1 src1_sel:DWORD
	s_nop 0
	v_and_b32_sdwa v49, v11, v178 dst_sel:DWORD dst_unused:UNUSED_PAD src0_sel:WORD_1 src1_sel:DWORD
	v_and_b32_sdwa v50, v23, v178 dst_sel:DWORD dst_unused:UNUSED_PAD src0_sel:WORD_1 src1_sel:DWORD
	v_and_b32_sdwa v51, v15, v178 dst_sel:DWORD dst_unused:UNUSED_PAD src0_sel:WORD_1 src1_sel:DWORD
	v_and_b32_sdwa v52, v35, v178 dst_sel:DWORD dst_unused:UNUSED_PAD src0_sel:WORD_1 src1_sel:DWORD
	v_and_b32_sdwa v53, v27, v178 dst_sel:DWORD dst_unused:UNUSED_PAD src0_sel:WORD_1 src1_sel:DWORD
	v_and_b32_sdwa v54, v39, v178 dst_sel:DWORD dst_unused:UNUSED_PAD src0_sel:WORD_1 src1_sel:DWORD
	v_and_b32_sdwa v55, v31, v178 dst_sel:DWORD dst_unused:UNUSED_PAD src0_sel:WORD_1 src1_sel:DWORD
	v_and_b32_sdwa v57, v12, v178 dst_sel:DWORD dst_unused:UNUSED_PAD src0_sel:WORD_1 src1_sel:DWORD
	v_and_b32_sdwa v58, v24, v178 dst_sel:DWORD dst_unused:UNUSED_PAD src0_sel:WORD_1 src1_sel:DWORD
	v_and_b32_sdwa v59, v16, v178 dst_sel:DWORD dst_unused:UNUSED_PAD src0_sel:WORD_1 src1_sel:DWORD
	v_and_b32_sdwa v60, v36, v178 dst_sel:DWORD dst_unused:UNUSED_PAD src0_sel:WORD_1 src1_sel:DWORD
	v_and_b32_sdwa v61, v28, v178 dst_sel:DWORD dst_unused:UNUSED_PAD src0_sel:WORD_1 src1_sel:DWORD
	s_waitcnt lgkmcnt(0)
	v_and_b32_sdwa v62, v40, v178 dst_sel:DWORD dst_unused:UNUSED_PAD src0_sel:WORD_1 src1_sel:DWORD
	v_and_b32_sdwa v63, v32, v178 dst_sel:DWORD dst_unused:UNUSED_PAD src0_sel:WORD_1 src1_sel:DWORD
	v_and_b32_sdwa v64, v21, v178 dst_sel:DWORD dst_unused:UNUSED_PAD src0_sel:WORD_1 src1_sel:DWORD
	v_and_b32_sdwa v65, v13, v178 dst_sel:DWORD dst_unused:UNUSED_PAD src0_sel:WORD_1 src1_sel:DWORD
	v_and_b32_sdwa v66, v25, v178 dst_sel:DWORD dst_unused:UNUSED_PAD src0_sel:WORD_1 src1_sel:DWORD
	v_and_b32_sdwa v67, v17, v178 dst_sel:DWORD dst_unused:UNUSED_PAD src0_sel:WORD_1 src1_sel:DWORD
	v_and_b32_sdwa v70, v41, v178 dst_sel:DWORD dst_unused:UNUSED_PAD src0_sel:WORD_1 src1_sel:DWORD
	v_and_b32_sdwa v71, v33, v178 dst_sel:DWORD dst_unused:UNUSED_PAD src0_sel:WORD_1 src1_sel:DWORD
	v_add3_u32 v9, v10, v9, s81
	v_add3_u32 v6, v18, v6, s81
	v_cvt_pk_bf16_f32 v10, v22, v22
	v_cvt_pk_bf16_f32 v14, v14, v14
	v_cvt_pk_bf16_f32 v18, v26, v26
	v_cvt_pk_bf16_f32 v26, v38, v38
	v_add3_u32 v30, v30, v47, s81
	v_and_b32_sdwa v48, v19, v178 dst_sel:DWORD dst_unused:UNUSED_PAD src0_sel:WORD_1 src1_sel:DWORD
	v_and_b32_sdwa v56, v20, v178 dst_sel:DWORD dst_unused:UNUSED_PAD src0_sel:WORD_1 src1_sel:DWORD
	v_and_b32_sdwa v68, v37, v178 dst_sel:DWORD dst_unused:UNUSED_PAD src0_sel:WORD_1 src1_sel:DWORD
	v_and_b32_sdwa v69, v29, v178 dst_sel:DWORD dst_unused:UNUSED_PAD src0_sel:WORD_1 src1_sel:DWORD
	v_cvt_pk_bf16_f32 v22, v34, v34
	v_add3_u32 v34, v11, v49, s81
	v_add3_u32 v11, v23, v50, s81
	v_add3_u32 v15, v15, v51, s81
	v_add3_u32 v23, v27, v53, s81
	v_add3_u32 v27, v35, v52, s81
	v_add3_u32 v35, v39, v54, s81
	v_add3_u32 v31, v31, v55, s81
	v_add3_u32 v38, v12, v57, s81
	v_add3_u32 v12, v24, v58, s81
	v_add3_u32 v16, v16, v59, s81
	v_add3_u32 v24, v28, v61, s81
	v_add3_u32 v28, v36, v60, s81
	v_add3_u32 v36, v40, v62, s81
	v_add3_u32 v32, v32, v63, s81
	v_add3_u32 v39, v13, v65, s81
	v_add3_u32 v40, v21, v64, s81
	v_add3_u32 v13, v25, v66, s81
	v_add3_u32 v17, v17, v67, s81
	v_add3_u32 v21, v41, v70, s81
	v_add3_u32 v33, v33, v71, s81
	v_and_b32_e32 v10, 0xffff0000, v10
	v_and_b32_e32 v14, 0xffff0000, v14
	v_and_b32_e32 v26, 0xffff0000, v26
	v_and_b32_e32 v30, 0xffff0000, v30
	v_add3_u32 v19, v19, v48, s81
	v_add3_u32 v20, v20, v56, s81
	v_add3_u32 v29, v29, v69, s81
	v_add3_u32 v25, v37, v68, s81
	v_and_b32_e32 v37, 0xffff0000, v11
	v_and_b32_e32 v41, 0xffff0000, v15
	v_and_b32_e32 v35, 0xffff0000, v35
	v_and_b32_e32 v31, 0xffff0000, v31
	v_and_b32_e32 v42, 0xffff0000, v12
	v_and_b32_e32 v43, 0xffff0000, v16
	v_and_b32_e32 v36, 0xffff0000, v36
	v_and_b32_e32 v32, 0xffff0000, v32
	v_and_b32_e32 v44, 0xffff0000, v13
	v_and_b32_e32 v45, 0xffff0000, v17
	v_and_b32_e32 v46, 0xffff0000, v21
	v_and_b32_e32 v33, 0xffff0000, v33
	v_or_b32_sdwa v11, v10, v6 dst_sel:DWORD dst_unused:UNUSED_PAD src0_sel:DWORD src1_sel:WORD_1
	v_or_b32_sdwa v10, v14, v9 dst_sel:DWORD dst_unused:UNUSED_PAD src0_sel:DWORD src1_sel:WORD_1
	v_or_b32_sdwa v13, v26, v22 dst_sel:DWORD dst_unused:UNUSED_PAD src0_sel:DWORD src1_sel:WORD_1
	v_or_b32_sdwa v12, v30, v18 dst_sel:DWORD dst_unused:UNUSED_PAD src0_sel:DWORD src1_sel:WORD_1
	v_or_b32_sdwa v15, v37, v19 dst_sel:DWORD dst_unused:UNUSED_PAD src0_sel:DWORD src1_sel:WORD_1
	v_or_b32_sdwa v14, v41, v34 dst_sel:DWORD dst_unused:UNUSED_PAD src0_sel:DWORD src1_sel:WORD_1
	v_or_b32_sdwa v17, v35, v27 dst_sel:DWORD dst_unused:UNUSED_PAD src0_sel:DWORD src1_sel:WORD_1
	v_or_b32_sdwa v16, v31, v23 dst_sel:DWORD dst_unused:UNUSED_PAD src0_sel:DWORD src1_sel:WORD_1
	v_or_b32_sdwa v19, v42, v20 dst_sel:DWORD dst_unused:UNUSED_PAD src0_sel:DWORD src1_sel:WORD_1
	v_or_b32_sdwa v18, v43, v38 dst_sel:DWORD dst_unused:UNUSED_PAD src0_sel:DWORD src1_sel:WORD_1
	v_or_b32_sdwa v21, v36, v28 dst_sel:DWORD dst_unused:UNUSED_PAD src0_sel:DWORD src1_sel:WORD_1
	v_or_b32_sdwa v20, v32, v24 dst_sel:DWORD dst_unused:UNUSED_PAD src0_sel:DWORD src1_sel:WORD_1
	v_or_b32_sdwa v23, v44, v40 dst_sel:DWORD dst_unused:UNUSED_PAD src0_sel:DWORD src1_sel:WORD_1
	v_or_b32_sdwa v22, v45, v39 dst_sel:DWORD dst_unused:UNUSED_PAD src0_sel:DWORD src1_sel:WORD_1
	v_or_b32_sdwa v25, v46, v25 dst_sel:DWORD dst_unused:UNUSED_PAD src0_sel:DWORD src1_sel:WORD_1
	v_or_b32_sdwa v24, v33, v29 dst_sel:DWORD dst_unused:UNUSED_PAD src0_sel:DWORD src1_sel:WORD_1
	global_store_dwordx4 v[86:87], v[10:13], off
	global_store_dwordx4 v[88:89], v[14:17], off
	global_store_dwordx4 v[90:91], v[18:21], off
	global_store_dwordx4 v[92:93], v[22:25], off
	s_barrier
	s_cbranch_scc1 .LBB0_929
	s_mov_b32 s51, 0x10000
